# f32 division expansions (sigmoid/gelu/softmax normalisers) replaced by v_rcp_f32 * numerator; all still f32
# speedup vs baseline: 1.0193x; 1.0193x over previous
; DI float sigmoidf_(float x) { return 1.f / (1.f + __expf(-x)); }
; template <bool SWAP> DI void inproj_tile(const Params& p, int layer, int tm, int tn, bf16_t* smem) {
;     ...
;         const int t = trow0 + i * 16 + l15; const float rs = rstd_from16(ssq + (size_t)t * 16, 1.f / 1024.f);
;         float* gt = (float*)(p.ws + O_GATES) + (size_t)t * 24; float* lf = (float*)(p.ws + O_LOGF) + (size_t)t * 8;
; #pragma unroll
;         for (int r = 0; r < 4; ++r) gt[quad * 4 + r] = sigmoidf_(acc[i][0][r] * rs);
;         if (quad < 2) {
; #pragma unroll
;           for (int r = 0; r < 4; ++r) gt[16 + quad * 4 + r] = sigmoidf_(acc[i][1][r] * rs);
;         } else {
; #pragma unroll
;           for (int r = 0; r < 4; ++r) { const int h = (quad - 2) * 4 + r; const float xx = acc[i][1][r] * rs + p.b_forget[layer * 8 + h]; lf[h] = fminf(xx, 0.f) - log1pf(__expf(-fabsf(xx))); }
.LrcA0_8:
	s_or_b64 exec, exec, s[98:99]
	s_waitcnt vmcnt(0)
	v_cndmask_b32_e64 v130, v249, v130, s[100:101]
	v_mov_b64_e32 v[150:151], s[10:11]
	v_lshlrev_b32_e32 v176, 4, v144
	v_cmp_lt_u32_e64 s[2:3], 31, v145
	v_lshlrev_b32_e32 v131, 2, v144
	v_mad_i64_i32 v[132:133], s[0:1], v128, s63, v[150:151]
	v_mul_f32_e32 v124, v124, v130
	v_mul_f32_e32 v125, v125, v130
	v_mul_f32_e32 v124, 0xbfb8aa3b, v124
	v_mul_f32_e32 v125, 0xbfb8aa3b, v125
	v_mul_f32_e32 v126, v126, v130
	v_mul_f32_e32 v127, v127, v130
	v_exp_f32_e32 v134, v124
	v_exp_f32_e32 v135, v125
	v_mul_f32_e32 v126, 0xbfb8aa3b, v126
	v_mul_f32_e32 v127, 0xbfb8aa3b, v127
	v_exp_f32_e32 v136, v126
	v_exp_f32_e32 v137, v127
	v_lshl_add_u64 v[126:127], v[132:133], 0, v[176:177]
	v_pk_add_f32 v[132:133], v[134:135], 1.0 op_sel_hi:[1,0]
	v_lshlrev_b64 v[124:125], 5, v[128:129]
	v_pk_add_f32 v[134:135], v[136:137], 1.0 op_sel_hi:[1,0]
	v_div_scale_f32 v137, s[0:1], v132, v132, 1.0
	v_div_scale_f32 v139, s[4:5], v135, v135, 1.0
	v_rcp_f32_e32 v145, v137
	v_div_scale_f32 v141, s[6:7], v134, v134, 1.0
	v_rcp_f32_e32 v146, v139
	v_rcp_f32_e32 v147, v141
	v_fma_f32 v149, -v137, v145, 1.0
	v_div_scale_f32 v138, s[0:1], 1.0, v132, 1.0
	v_fma_f32 v150, -v139, v146, 1.0
	v_fmac_f32_e32 v145, v149, v145
	v_div_scale_f32 v140, s[4:5], 1.0, v135, 1.0
	v_fma_f32 v151, -v141, v147, 1.0
	v_fmac_f32_e32 v146, v150, v146
	v_mul_f32_e32 v149, v138, v145
	v_div_scale_f32 v142, s[6:7], 1.0, v134, 1.0
	v_fmac_f32_e32 v147, v151, v147
	v_mul_f32_e32 v150, v140, v146
	v_fma_f32 v153, -v137, v149, v138
	v_mul_f32_e32 v151, v142, v147
	v_fma_f32 v154, -v139, v150, v140
	v_fmac_f32_e32 v149, v153, v145
	v_fma_f32 v155, -v141, v151, v142
	v_fmac_f32_e32 v150, v154, v146
	v_fma_f32 v136, -v137, v149, v138
	s_mov_b64 vcc, s[0:1]
	v_fmac_f32_e32 v151, v155, v147
	v_fma_f32 v137, -v139, v150, v140
	v_rcp_f32_e32 v133, v133
	v_div_fmas_f32 v129, v136, v145, v149
	s_mov_b64 vcc, s[4:5]
	v_fma_f32 v138, -v141, v151, v142
	v_div_fixup_f32 v132, v129, v132, 1.0
	v_div_fmas_f32 v129, v137, v146, v150
	s_mov_b64 vcc, s[6:7]
	v_div_fixup_f32 v135, v129, v135, 1.0
	v_div_fmas_f32 v129, v138, v147, v151
	v_div_fixup_f32 v134, v129, v134, 1.0
	v_lshlrev_b32_e32 v176, 2, v131
	global_store_dwordx4 v[126:127], v[132:135], off
	s_and_saveexec_b64 s[0:1], s[2:3]
	s_xor_b64 s[0:1], exec, s[0:1]
	s_cbranch_execz .LBB0_263
	v_readlane_b32 s72, v241, 8
	v_readlane_b32 s80, v241, 16
	v_readlane_b32 s81, v241, 17
	v_readlane_b32 s73, v241, 9
	v_readlane_b32 s74, v241, 10
	v_readlane_b32 s75, v241, 11
	v_readlane_b32 s76, v241, 12
	v_readlane_b32 s77, v241, 13
	global_load_dword v129, v176, s[80:81] offset:-32
	v_readlane_b32 s78, v241, 14
	v_readlane_b32 s79, v241, 15
	v_readlane_b32 s82, v241, 18
	v_readlane_b32 s83, v241, 19
	v_readlane_b32 s84, v241, 20
	v_readlane_b32 s85, v241, 21
	v_readlane_b32 s86, v241, 22
	v_readlane_b32 s87, v241, 23
	s_waitcnt vmcnt(0)
	v_fmac_f32_e32 v129, v120, v130
	v_mul_f32_e64 v126, |v129|, s64
	v_exp_f32_e32 v134, v126
	v_lshl_add_u64 v[126:127], s[12:13], 0, v[124:125]
	v_min_f32_e32 v129, 0, v129
	v_lshl_add_u64 v[126:127], v[126:127], 0, v[176:177]
	v_add_f32_e32 v135, 1.0, v134
	v_add_f32_e32 v136, -1.0, v135
	v_frexp_mant_f32_e32 v137, v135
	v_cvt_f64_f32_e32 v[132:133], v135
	v_sub_f32_e32 v138, v136, v135
	v_frexp_exp_i32_f64_e32 v132, v[132:133]
	v_cmp_gt_f32_e32 vcc, s65, v137
	v_sub_f32_e32 v136, v134, v136
	v_add_f32_e32 v133, 1.0, v138
	v_subbrev_co_u32_e32 v132, vcc, 0, v132, vcc
	v_add_f32_e32 v133, v136, v133
	v_sub_u32_e32 v136, 0, v132
	v_cvt_f32_i32_e32 v132, v132
	v_ldexp_f32 v135, v135, v136
	v_ldexp_f32 v133, v133, v136
	v_add_f32_e32 v136, -1.0, v135
	v_add_f32_e32 v137, 1.0, v135
	v_add_f32_e32 v138, 1.0, v136
	v_add_f32_e32 v139, -1.0, v137
	v_sub_f32_e32 v138, v135, v138
	v_sub_f32_e32 v135, v135, v139
	v_mul_f32_e32 v139, 0x3f317218, v132
	v_add_f32_e32 v138, v133, v138
	v_add_f32_e32 v133, v133, v135
	v_fma_f32 v135, v132, s66, -v139
	v_add_f32_e32 v140, v136, v138
	v_add_f32_e32 v141, v137, v133
	v_fmac_f32_e32 v135, 0xb102e308, v132
	v_sub_f32_e32 v132, v140, v136
	v_sub_f32_e32 v136, v141, v137
	v_rcp_f32_e32 v137, v141
	v_add_f32_e32 v142, v139, v135
	v_sub_f32_e32 v133, v133, v136
	v_sub_f32_e32 v136, v142, v139
	v_sub_f32_e32 v135, v135, v136
	v_mul_f32_e32 v136, v140, v137
	v_sub_f32_e32 v132, v138, v132
	v_mul_f32_e32 v138, v141, v136
	v_fma_f32 v139, v136, v141, -v138
	v_fmac_f32_e32 v139, v136, v133
	v_add_f32_e32 v143, v138, v139
	v_sub_f32_e32 v145, v140, v143
	v_sub_f32_e32 v138, v143, v138
	v_sub_f32_e32 v140, v140, v145
	v_sub_f32_e32 v138, v138, v139
	v_sub_f32_e32 v139, v140, v143
	v_add_f32_e32 v132, v132, v139
	v_add_f32_e32 v132, v138, v132
	v_add_f32_e32 v138, v145, v132
	v_mul_f32_e32 v139, v137, v138
	v_sub_f32_e32 v140, v145, v138
	v_mul_f32_e32 v143, v141, v139
	v_add_f32_e32 v132, v132, v140
	v_add_f32_e32 v140, v136, v139
	v_fma_f32 v141, v139, v141, -v143
	v_sub_f32_e32 v136, v140, v136
	v_fmac_f32_e32 v141, v139, v133
	v_sub_f32_e32 v133, v139, v136
	v_add_f32_e32 v136, v143, v141
	v_sub_f32_e32 v139, v136, v143
	v_sub_f32_e32 v143, v138, v136
	v_sub_f32_e32 v138, v138, v143
	v_sub_f32_e32 v136, v138, v136
	v_sub_f32_e32 v139, v139, v141
	v_add_f32_e32 v132, v132, v136
	v_add_f32_e32 v132, v139, v132
	v_add_f32_e32 v132, v143, v132
	v_mul_f32_e32 v132, v137, v132
	v_add_f32_e32 v132, v133, v132
	v_add_f32_e32 v133, v140, v132
	v_mul_f32_e32 v136, v133, v133
	v_fmamk_f32 v139, v136, 0x3e9b6dac, v186
	v_sub_f32_e32 v137, v133, v140
	v_ldexp_f32 v138, v133, 1
	v_mul_f32_e32 v133, v133, v136
	v_fmaak_f32 v136, v136, v139, 0x3f2aaada
	v_mul_f32_e32 v133, v133, v136
	v_add_f32_e32 v136, v138, v133
	v_sub_f32_e32 v132, v132, v137
	v_sub_f32_e32 v137, v136, v138
	v_ldexp_f32 v132, v132, 1
	v_sub_f32_e32 v133, v133, v137
	v_add_f32_e32 v132, v132, v133
	v_add_f32_e32 v133, v136, v132
	v_sub_f32_e32 v136, v133, v136
	v_add_f32_e32 v137, v142, v133
	v_sub_f32_e32 v132, v132, v136
	v_sub_f32_e32 v136, v137, v142
	v_sub_f32_e32 v138, v137, v136
	v_sub_f32_e32 v133, v133, v136
	v_add_f32_e32 v136, v135, v132
	v_sub_f32_e32 v138, v142, v138
	v_sub_f32_e32 v139, v136, v135
	v_add_f32_e32 v133, v133, v138
	v_sub_f32_e32 v138, v136, v139
	v_sub_f32_e32 v132, v132, v139
	v_sub_f32_e32 v135, v135, v138
	v_add_f32_e32 v133, v136, v133
	v_add_f32_e32 v132, v132, v135
	v_add_f32_e32 v135, v137, v133
	v_sub_f32_e32 v136, v135, v137
	v_sub_f32_e32 v133, v133, v136
	v_add_f32_e32 v132, v132, v133
	v_add_f32_e32 v132, v135, v132
	v_cmp_neq_f32_e32 vcc, s67, v134
	s_nop 1
	v_cndmask_b32_e32 v132, v194, v132, vcc
	v_cmp_ngt_f32_e32 vcc, -1.0, v134
	s_nop 1
	v_cndmask_b32_e32 v132, v195, v132, vcc
	v_cmp_neq_f32_e32 vcc, -1.0, v134
	s_nop 1
	v_cndmask_b32_e32 v132, v196, v132, vcc
	v_cmp_lt_f32_e64 vcc, |v134|, s68
	s_nop 1
	v_cndmask_b32_e32 v132, v132, v134, vcc
	v_sub_f32_e32 v129, v129, v132
	global_store_dword v[126:127], v129, off offset:-32
	global_load_dword v129, v176, s[80:81] offset:-28
	s_waitcnt vmcnt(0)
; template <bool SWAP> DI void inproj_tile(const Params& p, int layer, int tm, int tn, bf16_t* smem) {
;     ...
; #pragma unroll
;           for (int r = 0; r < 4; ++r) { const int h = (quad - 2) * 4 + r; const float xx = acc[i][1][r] * rs + p.b_forget[layer * 8 + h]; lf[h] = fminf(xx, 0.f) - log1pf(__expf(-fabsf(xx))); }
;         }
	v_fmac_f32_e32 v129, v121, v130
	v_mul_f32_e64 v132, |v129|, s64
	v_exp_f32_e32 v134, v132
	v_min_f32_e32 v129, 0, v129
	v_add_f32_e32 v135, 1.0, v134
	v_add_f32_e32 v136, -1.0, v135
	v_frexp_mant_f32_e32 v137, v135
	v_cvt_f64_f32_e32 v[132:133], v135
	v_sub_f32_e32 v138, v136, v135
	v_frexp_exp_i32_f64_e32 v132, v[132:133]
	v_cmp_gt_f32_e32 vcc, s65, v137
	v_sub_f32_e32 v136, v134, v136
	v_add_f32_e32 v133, 1.0, v138
	v_subbrev_co_u32_e32 v132, vcc, 0, v132, vcc
	v_add_f32_e32 v133, v136, v133
	v_sub_u32_e32 v136, 0, v132
	v_cvt_f32_i32_e32 v132, v132
	v_ldexp_f32 v135, v135, v136
	v_ldexp_f32 v133, v133, v136
	v_add_f32_e32 v136, -1.0, v135
	v_add_f32_e32 v137, 1.0, v135
	v_add_f32_e32 v138, 1.0, v136
	v_add_f32_e32 v139, -1.0, v137
	v_sub_f32_e32 v138, v135, v138
	v_sub_f32_e32 v135, v135, v139
	v_mul_f32_e32 v139, 0x3f317218, v132
	v_add_f32_e32 v138, v133, v138
	v_add_f32_e32 v133, v133, v135
	v_fma_f32 v135, v132, s66, -v139
	v_add_f32_e32 v140, v136, v138
	v_add_f32_e32 v141, v137, v133
	v_fmac_f32_e32 v135, 0xb102e308, v132
	v_sub_f32_e32 v132, v140, v136
	v_sub_f32_e32 v136, v141, v137
	v_rcp_f32_e32 v137, v141
	v_add_f32_e32 v142, v139, v135
	v_sub_f32_e32 v133, v133, v136
	v_sub_f32_e32 v136, v142, v139
	v_sub_f32_e32 v135, v135, v136
	v_mul_f32_e32 v136, v140, v137
	v_sub_f32_e32 v132, v138, v132
	v_mul_f32_e32 v138, v141, v136
	v_fma_f32 v139, v136, v141, -v138
	v_fmac_f32_e32 v139, v136, v133
	v_add_f32_e32 v143, v138, v139
	v_sub_f32_e32 v145, v140, v143
	v_sub_f32_e32 v138, v143, v138
	v_sub_f32_e32 v140, v140, v145
	v_sub_f32_e32 v138, v138, v139
	v_sub_f32_e32 v139, v140, v143
	v_add_f32_e32 v132, v132, v139
	v_add_f32_e32 v132, v138, v132
	v_add_f32_e32 v138, v145, v132
	v_mul_f32_e32 v139, v137, v138
	v_sub_f32_e32 v140, v145, v138
	v_mul_f32_e32 v143, v141, v139
	v_add_f32_e32 v132, v132, v140
	v_add_f32_e32 v140, v136, v139
	v_fma_f32 v141, v139, v141, -v143
	v_sub_f32_e32 v136, v140, v136
	v_fmac_f32_e32 v141, v139, v133
	v_sub_f32_e32 v133, v139, v136
	v_add_f32_e32 v136, v143, v141
	v_sub_f32_e32 v139, v136, v143
	v_sub_f32_e32 v143, v138, v136
	v_sub_f32_e32 v138, v138, v143
	v_sub_f32_e32 v136, v138, v136
	v_sub_f32_e32 v139, v139, v141
	v_add_f32_e32 v132, v132, v136
	v_add_f32_e32 v132, v139, v132
	v_add_f32_e32 v132, v143, v132
	v_mul_f32_e32 v132, v137, v132
	v_add_f32_e32 v132, v133, v132
	v_add_f32_e32 v133, v140, v132
	v_mul_f32_e32 v136, v133, v133
	v_fmamk_f32 v139, v136, 0x3e9b6dac, v186
	v_sub_f32_e32 v137, v133, v140
	v_ldexp_f32 v138, v133, 1
	v_mul_f32_e32 v133, v133, v136
	v_fmaak_f32 v136, v136, v139, 0x3f2aaada
	v_mul_f32_e32 v133, v133, v136
	v_add_f32_e32 v136, v138, v133
	v_sub_f32_e32 v132, v132, v137
	v_sub_f32_e32 v137, v136, v138
	v_ldexp_f32 v132, v132, 1
	v_sub_f32_e32 v133, v133, v137
	v_add_f32_e32 v132, v132, v133
	v_add_f32_e32 v133, v136, v132
	v_sub_f32_e32 v136, v133, v136
	v_add_f32_e32 v137, v142, v133
	v_sub_f32_e32 v132, v132, v136
	v_sub_f32_e32 v136, v137, v142
	v_sub_f32_e32 v138, v137, v136
	v_sub_f32_e32 v133, v133, v136
	v_add_f32_e32 v136, v135, v132
	v_sub_f32_e32 v138, v142, v138
	v_sub_f32_e32 v139, v136, v135
	v_add_f32_e32 v133, v133, v138
	v_sub_f32_e32 v138, v136, v139
	v_sub_f32_e32 v132, v132, v139
	v_sub_f32_e32 v135, v135, v138
	v_add_f32_e32 v133, v136, v133
	v_add_f32_e32 v132, v132, v135
	v_add_f32_e32 v135, v137, v133
	v_sub_f32_e32 v136, v135, v137
	v_sub_f32_e32 v133, v133, v136
	v_add_f32_e32 v132, v132, v133
	v_add_f32_e32 v132, v135, v132
	v_cmp_neq_f32_e32 vcc, s67, v134
	s_nop 1
	v_cndmask_b32_e32 v132, v194, v132, vcc
	v_cmp_ngt_f32_e32 vcc, -1.0, v134
	s_nop 1
	v_cndmask_b32_e32 v132, v195, v132, vcc
	v_cmp_neq_f32_e32 vcc, -1.0, v134
	s_nop 1
	v_cndmask_b32_e32 v132, v196, v132, vcc
	v_cmp_lt_f32_e64 vcc, |v134|, s68
	s_nop 1
	v_cndmask_b32_e32 v132, v132, v134, vcc
	v_sub_f32_e32 v129, v129, v132
	global_store_dword v[126:127], v129, off offset:-28
	global_load_dword v129, v176, s[80:81] offset:-24
	s_waitcnt vmcnt(0)
	v_fmac_f32_e32 v129, v122, v130
	v_mul_f32_e64 v132, |v129|, s64
	v_exp_f32_e32 v134, v132
	v_min_f32_e32 v129, 0, v129
	v_add_f32_e32 v135, 1.0, v134
	v_add_f32_e32 v136, -1.0, v135
	v_frexp_mant_f32_e32 v137, v135
	v_cvt_f64_f32_e32 v[132:133], v135
	v_sub_f32_e32 v138, v136, v135
	v_frexp_exp_i32_f64_e32 v132, v[132:133]
	v_cmp_gt_f32_e32 vcc, s65, v137
	v_sub_f32_e32 v136, v134, v136
	v_add_f32_e32 v133, 1.0, v138
	v_subbrev_co_u32_e32 v132, vcc, 0, v132, vcc
	v_add_f32_e32 v133, v136, v133
	v_sub_u32_e32 v136, 0, v132
	v_cvt_f32_i32_e32 v132, v132
	v_ldexp_f32 v135, v135, v136
	v_ldexp_f32 v133, v133, v136
	v_add_f32_e32 v136, -1.0, v135
	v_add_f32_e32 v137, 1.0, v135
	v_add_f32_e32 v138, 1.0, v136
	v_add_f32_e32 v139, -1.0, v137
	v_sub_f32_e32 v138, v135, v138
	v_sub_f32_e32 v135, v135, v139
	v_mul_f32_e32 v139, 0x3f317218, v132
	v_add_f32_e32 v138, v133, v138
	v_add_f32_e32 v133, v133, v135
	v_fma_f32 v135, v132, s66, -v139
	v_add_f32_e32 v140, v136, v138
	v_add_f32_e32 v141, v137, v133
	v_fmac_f32_e32 v135, 0xb102e308, v132
	v_sub_f32_e32 v132, v140, v136
	v_sub_f32_e32 v136, v141, v137
	v_rcp_f32_e32 v137, v141
	v_add_f32_e32 v142, v139, v135
	v_sub_f32_e32 v133, v133, v136
	v_sub_f32_e32 v136, v142, v139
	v_sub_f32_e32 v135, v135, v136
	v_mul_f32_e32 v136, v140, v137
	v_sub_f32_e32 v132, v138, v132
	v_mul_f32_e32 v138, v141, v136
	v_fma_f32 v139, v136, v141, -v138
	v_fmac_f32_e32 v139, v136, v133
	v_add_f32_e32 v143, v138, v139
	v_sub_f32_e32 v145, v140, v143
	v_sub_f32_e32 v138, v143, v138
	v_sub_f32_e32 v140, v140, v145
	v_sub_f32_e32 v138, v138, v139
	v_sub_f32_e32 v139, v140, v143
	v_add_f32_e32 v132, v132, v139
; template <bool SWAP> DI void inproj_tile(const Params& p, int layer, int tm, int tn, bf16_t* smem) {
;     ...
; #pragma unroll
;           for (int r = 0; r < 4; ++r) { const int h = (quad - 2) * 4 + r; const float xx = acc[i][1][r] * rs + p.b_forget[layer * 8 + h]; lf[h] = fminf(xx, 0.f) - log1pf(__expf(-fabsf(xx))); }
;         }
	v_add_f32_e32 v132, v138, v132
	v_add_f32_e32 v138, v145, v132
	v_mul_f32_e32 v139, v137, v138
	v_sub_f32_e32 v140, v145, v138
	v_mul_f32_e32 v143, v141, v139
	v_add_f32_e32 v132, v132, v140
	v_add_f32_e32 v140, v136, v139
	v_fma_f32 v141, v139, v141, -v143
	v_sub_f32_e32 v136, v140, v136
	v_fmac_f32_e32 v141, v139, v133
	v_sub_f32_e32 v133, v139, v136
	v_add_f32_e32 v136, v143, v141
	v_sub_f32_e32 v139, v136, v143
	v_sub_f32_e32 v143, v138, v136
	v_sub_f32_e32 v138, v138, v143
	v_sub_f32_e32 v136, v138, v136
	v_sub_f32_e32 v139, v139, v141
	v_add_f32_e32 v132, v132, v136
	v_add_f32_e32 v132, v139, v132
	v_add_f32_e32 v132, v143, v132
	v_mul_f32_e32 v132, v137, v132
	v_add_f32_e32 v132, v133, v132
	v_add_f32_e32 v133, v140, v132
	v_mul_f32_e32 v136, v133, v133
	v_fmamk_f32 v139, v136, 0x3e9b6dac, v186
	v_sub_f32_e32 v137, v133, v140
	v_ldexp_f32 v138, v133, 1
	v_mul_f32_e32 v133, v133, v136
	v_fmaak_f32 v136, v136, v139, 0x3f2aaada
	v_mul_f32_e32 v133, v133, v136
	v_add_f32_e32 v136, v138, v133
	v_sub_f32_e32 v132, v132, v137
	v_sub_f32_e32 v137, v136, v138
	v_ldexp_f32 v132, v132, 1
	v_sub_f32_e32 v133, v133, v137
	v_add_f32_e32 v132, v132, v133
	v_add_f32_e32 v133, v136, v132
	v_sub_f32_e32 v136, v133, v136
	v_add_f32_e32 v137, v142, v133
	v_sub_f32_e32 v132, v132, v136
	v_sub_f32_e32 v136, v137, v142
	v_sub_f32_e32 v138, v137, v136
	v_sub_f32_e32 v133, v133, v136
	v_add_f32_e32 v136, v135, v132
	v_sub_f32_e32 v138, v142, v138
	v_sub_f32_e32 v139, v136, v135
	v_add_f32_e32 v133, v133, v138
	v_sub_f32_e32 v138, v136, v139
	v_sub_f32_e32 v132, v132, v139
	v_sub_f32_e32 v135, v135, v138
	v_add_f32_e32 v133, v136, v133
	v_add_f32_e32 v132, v132, v135
	v_add_f32_e32 v135, v137, v133
	v_sub_f32_e32 v136, v135, v137
	v_sub_f32_e32 v133, v133, v136
	v_add_f32_e32 v132, v132, v133
	v_add_f32_e32 v132, v135, v132
	v_cmp_neq_f32_e32 vcc, s67, v134
	s_nop 1
	v_cndmask_b32_e32 v132, v194, v132, vcc
	v_cmp_ngt_f32_e32 vcc, -1.0, v134
	s_nop 1
	v_cndmask_b32_e32 v132, v195, v132, vcc
	v_cmp_neq_f32_e32 vcc, -1.0, v134
	s_nop 1
	v_cndmask_b32_e32 v132, v196, v132, vcc
	v_cmp_lt_f32_e64 vcc, |v134|, s68
	s_nop 1
	v_cndmask_b32_e32 v132, v132, v134, vcc
	v_sub_f32_e32 v129, v129, v132
	global_store_dword v[126:127], v129, off offset:-24
	global_load_dword v129, v176, s[80:81] offset:-20
	s_waitcnt vmcnt(0)
	v_fmac_f32_e32 v129, v123, v130
	v_mul_f32_e64 v132, |v129|, s64
	v_exp_f32_e32 v134, v132
	v_min_f32_e32 v129, 0, v129
	v_add_f32_e32 v135, 1.0, v134
	v_add_f32_e32 v136, -1.0, v135
	v_frexp_mant_f32_e32 v137, v135
	v_cvt_f64_f32_e32 v[132:133], v135
	v_sub_f32_e32 v138, v136, v135
	v_frexp_exp_i32_f64_e32 v132, v[132:133]
	v_cmp_gt_f32_e32 vcc, s65, v137
	v_sub_f32_e32 v136, v134, v136
	v_add_f32_e32 v133, 1.0, v138
	v_subbrev_co_u32_e32 v132, vcc, 0, v132, vcc
	v_add_f32_e32 v133, v136, v133
	v_sub_u32_e32 v136, 0, v132
	v_cvt_f32_i32_e32 v132, v132
	v_ldexp_f32 v135, v135, v136
	v_ldexp_f32 v133, v133, v136
	v_add_f32_e32 v136, -1.0, v135
	v_add_f32_e32 v137, 1.0, v135
	v_add_f32_e32 v138, 1.0, v136
	v_add_f32_e32 v139, -1.0, v137
	v_sub_f32_e32 v138, v135, v138
	v_sub_f32_e32 v135, v135, v139
	v_mul_f32_e32 v139, 0x3f317218, v132
	v_add_f32_e32 v138, v133, v138
	v_add_f32_e32 v133, v133, v135
	v_fma_f32 v135, v132, s66, -v139
	v_add_f32_e32 v140, v136, v138
	v_add_f32_e32 v141, v137, v133
	v_fmac_f32_e32 v135, 0xb102e308, v132
	v_sub_f32_e32 v132, v140, v136
	v_sub_f32_e32 v136, v141, v137
	v_rcp_f32_e32 v137, v141
	v_add_f32_e32 v142, v139, v135
	v_sub_f32_e32 v133, v133, v136
	v_sub_f32_e32 v136, v142, v139
	v_sub_f32_e32 v135, v135, v136
	v_mul_f32_e32 v136, v140, v137
	v_sub_f32_e32 v132, v138, v132
	v_mul_f32_e32 v138, v141, v136
	v_fma_f32 v139, v136, v141, -v138
	v_fmac_f32_e32 v139, v136, v133
	v_add_f32_e32 v143, v138, v139
	v_sub_f32_e32 v145, v140, v143
	v_sub_f32_e32 v138, v143, v138
	v_sub_f32_e32 v140, v140, v145
	v_sub_f32_e32 v138, v138, v139
	v_sub_f32_e32 v139, v140, v143
	v_add_f32_e32 v132, v132, v139
	v_add_f32_e32 v132, v138, v132
	v_add_f32_e32 v138, v145, v132
	v_mul_f32_e32 v139, v137, v138
	v_sub_f32_e32 v140, v145, v138
	v_mul_f32_e32 v143, v141, v139
	v_add_f32_e32 v132, v132, v140
	v_add_f32_e32 v140, v136, v139
	v_fma_f32 v141, v139, v141, -v143
	v_sub_f32_e32 v136, v140, v136
	v_fmac_f32_e32 v141, v139, v133
	v_sub_f32_e32 v133, v139, v136
	v_add_f32_e32 v136, v143, v141
	v_sub_f32_e32 v139, v136, v143
	v_sub_f32_e32 v143, v138, v136
	v_sub_f32_e32 v138, v138, v143
	v_sub_f32_e32 v136, v138, v136
	v_sub_f32_e32 v139, v139, v141
	v_add_f32_e32 v132, v132, v136
	v_add_f32_e32 v132, v139, v132
	v_add_f32_e32 v132, v143, v132
	v_mul_f32_e32 v132, v137, v132
	v_add_f32_e32 v132, v133, v132
	v_add_f32_e32 v133, v140, v132
	v_mul_f32_e32 v136, v133, v133
	v_fmamk_f32 v139, v136, 0x3e9b6dac, v186
	v_sub_f32_e32 v137, v133, v140
	v_ldexp_f32 v138, v133, 1
	v_mul_f32_e32 v133, v133, v136
	v_fmaak_f32 v136, v136, v139, 0x3f2aaada
	v_mul_f32_e32 v133, v133, v136
	v_add_f32_e32 v136, v138, v133
	v_sub_f32_e32 v132, v132, v137
	v_sub_f32_e32 v137, v136, v138
	v_ldexp_f32 v132, v132, 1
	v_sub_f32_e32 v133, v133, v137
	v_add_f32_e32 v132, v132, v133
	v_add_f32_e32 v133, v136, v132
	v_sub_f32_e32 v136, v133, v136
	v_add_f32_e32 v137, v142, v133
	v_sub_f32_e32 v132, v132, v136
	v_sub_f32_e32 v136, v137, v142
	v_sub_f32_e32 v138, v137, v136
	v_sub_f32_e32 v133, v133, v136
	v_add_f32_e32 v136, v135, v132
	v_sub_f32_e32 v138, v142, v138
	v_sub_f32_e32 v139, v136, v135
	v_add_f32_e32 v133, v133, v138
	v_sub_f32_e32 v138, v136, v139
	v_sub_f32_e32 v132, v132, v139
	v_sub_f32_e32 v135, v135, v138
	v_add_f32_e32 v133, v136, v133
	v_add_f32_e32 v132, v132, v135
	v_add_f32_e32 v135, v137, v133
	v_sub_f32_e32 v136, v135, v137
	v_sub_f32_e32 v133, v133, v136
	v_add_f32_e32 v132, v132, v133
	v_add_f32_e32 v132, v135, v132
	v_cmp_neq_f32_e32 vcc, s67, v134
	s_nop 1
	v_cndmask_b32_e32 v132, v194, v132, vcc
	v_cmp_ngt_f32_e32 vcc, -1.0, v134
	s_nop 1
	v_cndmask_b32_e32 v132, v195, v132, vcc
	v_cmp_neq_f32_e32 vcc, -1.0, v134
	s_nop 1
	v_cndmask_b32_e32 v132, v196, v132, vcc
	v_cmp_lt_f32_e64 vcc, |v134|, s68
	s_nop 1
	v_cndmask_b32_e32 v132, v132, v134, vcc
	v_sub_f32_e32 v129, v129, v132
	global_store_dword v[126:127], v129, off offset:-20
; DI unsigned pk2(float lo, float hi) { f32x2 v = {lo, hi}; return __builtin_bit_cast(unsigned, __builtin_convertvector(v, bfx2)); }
; DI float sigmoidf_(float x) { return 1.f / (1.f + __expf(-x)); }
; template <bool SWAP> DI void inproj_tile(const Params& p, int layer, int tm, int tn, bf16_t* smem) {
;     ...
;       for (int i = 0; i < 8; ++i) {
;         const int t = trow0 + i * 16 + l15; const float rs = rstd_from16(ssq + (size_t)t * 16, 1.f / 1024.f);
;         float* gt = (float*)(p.ws + O_GATES) + (size_t)t * 24; float* lf = (float*)(p.ws + O_LOGF) + (size_t)t * 8;
; #pragma unroll
;         for (int r = 0; r < 4; ++r) gt[quad * 4 + r] = sigmoidf_(acc[i][0][r] * rs);
;         if (quad < 2) {
; #pragma unroll
;           for (int r = 0; r < 4; ++r) gt[16 + quad * 4 + r] = sigmoidf_(acc[i][1][r] * rs);
;         } else {
; #pragma unroll
;           for (int r = 0; r < 4; ++r) { const int h = (quad - 2) * 4 + r; const float xx = acc[i][1][r] * rs + p.b_forget[layer * 8 + h]; lf[h] = fminf(xx, 0.f) - log1pf(__expf(-fabsf(xx))); }
;         }
;         const float* rp = (const float*)(p.ws + O_ROPE16) + (size_t)t * 32 + quad * 8; float o1[4], o2[4];
; #pragma unroll
;         for (int r = 0; r < 4; ++r) { const float cs = rp[2 * r], sn = rp[2 * r + 1], x1 = acc[i][2][r] * rs, x2 = acc[i][3][r] * rs; o1[r] = x1 * cs - x2 * sn; o2[r] = x2 * cs + x1 * sn; }
;         bf16_t* kp = (bf16_t*)(p.ws + O_MLAKPE) + (size_t)t * 32 + quad * 4;
;         *(u32x2*)kp = (u32x2){pk2(o1[0], o1[1]), pk2(o1[2], o1[3])}; *(u32x2*)(kp + 16) = (u32x2){pk2(o2[0], o2[1]), pk2(o2[2], o2[3])};
.LBB0_263:
	s_andn2_saveexec_b64 s[0:1], s[0:1]
	s_cbranch_execz .LBB0_265
	v_mul_f32_e32 v120, v120, v130
	v_mul_f32_e32 v121, v121, v130
	v_mul_f32_e32 v120, 0xbfb8aa3b, v120
	v_mul_f32_e32 v121, 0xbfb8aa3b, v121
	v_exp_f32_e32 v120, v120
	v_exp_f32_e32 v121, v121
	v_mul_f32_e32 v122, v122, v130
	v_mul_f32_e32 v123, v123, v130
	v_mul_f32_e32 v122, 0xbfb8aa3b, v122
	v_pk_add_f32 v[120:121], v[120:121], 1.0 op_sel_hi:[1,0]
	v_mul_f32_e32 v123, 0xbfb8aa3b, v123
	v_exp_f32_e32 v122, v122
	v_rcp_f32_e32 v121, v121
	v_exp_f32_e32 v123, v123
	s_nop 0
	v_pk_add_f32 v[122:123], v[122:123], 1.0 op_sel_hi:[1,0]
	v_rcp_f32_e32 v120, v120
	v_rcp_f32_e32 v123, v123
	v_rcp_f32_e32 v122, v122
	global_store_dwordx4 v[126:127], v[120:123], off offset:64
.LBB0_265:
	s_or_b64 exec, exec, s[0:1]
	s_nop 0
	v_lshl_add_u64 v[120:121], v[124:125], 2, s[14:15]
	v_lshlrev_b32_e32 v122, 5, v144
	v_mov_b32_e32 v123, v177
	v_lshl_add_u64 v[126:127], v[120:121], 0, v[122:123]
	global_load_dwordx4 v[120:123], v[126:127], off
	global_load_dwordx4 v[132:135], v[126:127], off offset:16
	v_or_b32_e32 v126, 16, v128
	v_ashrrev_i32_e32 v127, 31, v126
	v_lshlrev_b64 v[136:137], 6, v[126:127]
	v_lshl_add_u64 v[150:151], s[8:9], 0, v[136:137]
	global_load_dwordx4 v[136:139], v[150:151], off
	global_load_dwordx4 v[140:143], v[150:151], off offset:16
	global_load_dwordx4 v[146:149], v[150:151], off offset:32
	s_nop 0
	global_load_dwordx4 v[150:153], v[150:151], off offset:48
	v_pk_mul_f32 v[154:155], v[112:113], v[130:131] op_sel_hi:[1,0]
	v_pk_mul_f32 v[156:157], v[114:115], v[130:131] op_sel_hi:[1,0]
	v_lshl_add_u64 v[114:115], v[124:125], 1, s[16:17]
	v_lshlrev_b32_e32 v112, 1, v131
	v_mov_b32_e32 v113, v177
	v_pk_mul_f32 v[116:117], v[116:117], v[130:131] op_sel_hi:[1,0]
	v_pk_mul_f32 v[158:159], v[118:119], v[130:131] op_sel_hi:[1,0]
	v_mov_b64_e32 v[118:119], s[10:11]
	v_lshl_add_u64 v[124:125], v[114:115], 0, v[112:113]
	v_lshlrev_b64 v[114:115], 5, v[126:127]
	v_mad_i64_i32 v[118:119], s[0:1], v126, s63, v[118:119]
	v_lshl_add_u64 v[118:119], v[118:119], 0, v[176:177]
	s_waitcnt vmcnt(5)
	v_mov_b32_e32 v127, v122
	v_mov_b32_e32 v122, v121
	s_waitcnt vmcnt(4)
	v_mov_b32_e32 v121, v134
	v_mov_b32_e32 v134, v133
	v_mov_b32_e32 v126, v120
	v_mov_b32_e32 v120, v132
	v_pk_mul_f32 v[130:131], v[154:155], v[122:123]
	v_pk_mul_f32 v[122:123], v[116:117], v[122:123]
	v_pk_mul_f32 v[132:133], v[156:157], v[134:135]
	v_pk_fma_f32 v[116:117], v[116:117], v[126:127], v[130:131] neg_lo:[0,0,1] neg_hi:[0,0,1]
	v_pk_fma_f32 v[122:123], v[154:155], v[126:127], v[122:123]
	v_pk_fma_f32 v[126:127], v[158:159], v[120:121], v[132:133] neg_lo:[0,0,1] neg_hi:[0,0,1]
	s_waitcnt vmcnt(3)
	v_mov_b32_e32 v130, v137
	v_mov_b32_e32 v131, v138
	v_mov_b32_e32 v137, v139
	s_waitcnt vmcnt(2)
	v_mov_b32_e32 v132, v141
	v_mov_b32_e32 v133, v142
	v_mov_b32_e32 v141, v143
	v_cvt_pk_bf16_f32 v142, v116, v117
	v_pk_add_f32 v[116:117], v[130:131], v[136:137]
	v_pk_add_f32 v[130:131], v[132:133], v[140:141]
	v_pk_mul_f32 v[134:135], v[158:159], v[134:135]
	v_pk_add_f32 v[116:117], v[116:117], v[116:117] op_sel:[0,1] op_sel_hi:[1,0]
	v_pk_add_f32 v[130:131], v[130:131], v[130:131] op_sel:[0,1] op_sel_hi:[1,0]
	v_pk_fma_f32 v[120:121], v[156:157], v[120:121], v[134:135]
	s_waitcnt vmcnt(1)
	v_add_f32_e32 v134, v146, v147
	v_add_f32_e32 v138, v148, v149
	s_waitcnt vmcnt(0)
	v_mov_b32_e32 v135, v152
	v_mov_b32_e32 v139, v153
	v_mov_b32_e32 v117, v150
	v_mov_b32_e32 v131, v151
	v_pk_add_f32 v[132:133], v[134:135], v[138:139]
	v_pk_add_f32 v[116:117], v[116:117], v[130:131]
	v_cvt_pk_bf16_f32 v143, v126, v127
	v_pk_add_f32 v[116:117], v[116:117], v[132:133]
	v_cvt_pk_bf16_f32 v122, v122, v123
	v_add_f32_e32 v113, v116, v117
	v_fmamk_f32 v113, v113, 0x3a800000, v185
	v_mul_f32_e32 v116, 0x4b800000, v113
	v_cmp_gt_f32_e32 vcc, s60, v113
	v_cvt_pk_bf16_f32 v123, v120, v121
	global_store_dwordx2 v[124:125], v[142:143], off
	global_store_dwordx2 v[124:125], v[122:123], off offset:32
	v_cndmask_b32_e32 v113, v113, v116, vcc
	v_rsq_f32_e32 v113, v113
	s_nop 0
	v_mul_f32_e32 v116, 0x45800000, v113
	v_cndmask_b32_e32 v116, v113, v116, vcc
	v_mul_f32_e32 v108, v108, v116
	v_mul_f32_e32 v109, v109, v116
	v_mul_f32_e32 v108, 0xbfb8aa3b, v108
	v_mul_f32_e32 v109, 0xbfb8aa3b, v109
	v_mul_f32_e32 v110, v110, v116
	v_mul_f32_e32 v111, v111, v116
	v_exp_f32_e32 v108, v108
	v_exp_f32_e32 v109, v109
	v_mul_f32_e32 v110, 0xbfb8aa3b, v110
	v_mul_f32_e32 v111, 0xbfb8aa3b, v111
	v_exp_f32_e32 v110, v110
	v_exp_f32_e32 v111, v111
	v_pk_add_f32 v[108:109], v[108:109], 1.0 op_sel_hi:[1,0]
	v_pk_add_f32 v[110:111], v[110:111], 1.0 op_sel_hi:[1,0]
	v_div_scale_f32 v120, s[0:1], v108, v108, 1.0
	v_rcp_f32_e32 v123, v120
	s_nop 0
	v_fma_f32 v127, -v120, v123, 1.0
	v_div_scale_f32 v125, s[0:1], 1.0, v108, 1.0
	v_fmac_f32_e32 v123, v127, v123
	v_mul_f32_e32 v127, v125, v123
	v_fma_f32 v130, -v120, v127, v125
	v_fmac_f32_e32 v127, v130, v123
	v_fma_f32 v117, -v120, v127, v125
	s_mov_b64 vcc, s[0:1]
	v_rcp_f32_e32 v109, v109
	v_div_fmas_f32 v113, v117, v123, v127
	v_div_fixup_f32 v108, v113, v108, 1.0
	v_rcp_f32_e32 v111, v111
	v_rcp_f32_e32 v110, v110
	global_store_dwordx4 v[118:119], v[108:111], off
	s_and_saveexec_b64 s[0:1], s[2:3]
	s_xor_b64 s[0:1], exec, s[0:1]
	s_cbranch_execz .LBB0_267
; template <bool SWAP> DI void inproj_tile(const Params& p, int layer, int tm, int tn, bf16_t* smem) {
;     ...
; #pragma unroll
;           for (int r = 0; r < 4; ++r) { const int h = (quad - 2) * 4 + r; const float xx = acc[i][1][r] * rs + p.b_forget[layer * 8 + h]; lf[h] = fminf(xx, 0.f) - log1pf(__expf(-fabsf(xx))); }
	v_readlane_b32 s72, v241, 8
	v_readlane_b32 s80, v241, 16
	v_readlane_b32 s81, v241, 17
	v_readlane_b32 s73, v241, 9
	v_readlane_b32 s74, v241, 10
	v_readlane_b32 s75, v241, 11
	v_readlane_b32 s76, v241, 12
	v_readlane_b32 s77, v241, 13
	global_load_dword v110, v176, s[80:81] offset:-32
	v_readlane_b32 s78, v241, 14
	v_readlane_b32 s79, v241, 15
	v_readlane_b32 s82, v241, 18
	v_readlane_b32 s83, v241, 19
	v_readlane_b32 s84, v241, 20
	v_readlane_b32 s85, v241, 21
	v_readlane_b32 s86, v241, 22
	v_readlane_b32 s87, v241, 23
	s_waitcnt vmcnt(0)
	v_fmac_f32_e32 v110, v104, v116
	v_mul_f32_e64 v108, |v110|, s64
	v_exp_f32_e32 v113, v108
	v_min_f32_e32 v117, 0, v110
	v_lshl_add_u64 v[108:109], s[12:13], 0, v[114:115]
	v_lshl_add_u64 v[108:109], v[108:109], 0, v[176:177]
	v_add_f32_e32 v118, 1.0, v113
	v_add_f32_e32 v119, -1.0, v118
	v_frexp_mant_f32_e32 v120, v118
	v_cvt_f64_f32_e32 v[110:111], v118
	v_sub_f32_e32 v121, v119, v118
	v_frexp_exp_i32_f64_e32 v110, v[110:111]
	v_cmp_gt_f32_e32 vcc, s65, v120
	v_sub_f32_e32 v119, v113, v119
	v_add_f32_e32 v111, 1.0, v121
	v_subbrev_co_u32_e32 v110, vcc, 0, v110, vcc
	v_add_f32_e32 v111, v119, v111
	v_sub_u32_e32 v119, 0, v110
	v_cvt_f32_i32_e32 v110, v110
	v_ldexp_f32 v118, v118, v119
	v_ldexp_f32 v111, v111, v119
	v_add_f32_e32 v119, -1.0, v118
	v_add_f32_e32 v120, 1.0, v118
	v_add_f32_e32 v121, 1.0, v119
	v_add_f32_e32 v122, -1.0, v120
	v_sub_f32_e32 v121, v118, v121
	v_sub_f32_e32 v118, v118, v122
	v_mul_f32_e32 v122, 0x3f317218, v110
	v_add_f32_e32 v121, v111, v121
	v_add_f32_e32 v111, v111, v118
	v_fma_f32 v118, v110, s66, -v122
	v_add_f32_e32 v123, v119, v121
	v_add_f32_e32 v124, v120, v111
	v_fmac_f32_e32 v118, 0xb102e308, v110
	v_sub_f32_e32 v110, v123, v119
	v_sub_f32_e32 v119, v124, v120
	v_rcp_f32_e32 v120, v124
	v_add_f32_e32 v125, v122, v118
	v_sub_f32_e32 v111, v111, v119
	v_sub_f32_e32 v119, v125, v122
	v_sub_f32_e32 v118, v118, v119
	v_mul_f32_e32 v119, v123, v120
	v_sub_f32_e32 v110, v121, v110
	v_mul_f32_e32 v121, v124, v119
	v_fma_f32 v122, v119, v124, -v121
	v_fmac_f32_e32 v122, v119, v111
	v_add_f32_e32 v126, v121, v122
	v_sub_f32_e32 v127, v123, v126
	v_sub_f32_e32 v121, v126, v121
	v_sub_f32_e32 v123, v123, v127
	v_sub_f32_e32 v121, v121, v122
	v_sub_f32_e32 v122, v123, v126
	v_add_f32_e32 v110, v110, v122
	v_add_f32_e32 v110, v121, v110
	v_add_f32_e32 v121, v127, v110
	v_mul_f32_e32 v122, v120, v121
	v_sub_f32_e32 v123, v127, v121
	v_mul_f32_e32 v126, v124, v122
	v_add_f32_e32 v110, v110, v123
	v_add_f32_e32 v123, v119, v122
	v_fma_f32 v124, v122, v124, -v126
	v_sub_f32_e32 v119, v123, v119
	v_fmac_f32_e32 v124, v122, v111
	v_sub_f32_e32 v111, v122, v119
	v_add_f32_e32 v119, v126, v124
	v_sub_f32_e32 v122, v119, v126
	v_sub_f32_e32 v126, v121, v119
	v_sub_f32_e32 v121, v121, v126
	v_sub_f32_e32 v119, v121, v119
	v_sub_f32_e32 v122, v122, v124
	v_add_f32_e32 v110, v110, v119
	v_add_f32_e32 v110, v122, v110
	v_add_f32_e32 v110, v126, v110
	v_mul_f32_e32 v110, v120, v110
	v_add_f32_e32 v110, v111, v110
	v_add_f32_e32 v111, v123, v110
	v_mul_f32_e32 v119, v111, v111
	v_fmamk_f32 v122, v119, 0x3e9b6dac, v186
	v_sub_f32_e32 v120, v111, v123
	v_ldexp_f32 v121, v111, 1
	v_mul_f32_e32 v111, v111, v119
	v_fmaak_f32 v119, v119, v122, 0x3f2aaada
	v_mul_f32_e32 v111, v111, v119
	v_add_f32_e32 v119, v121, v111
	v_sub_f32_e32 v110, v110, v120
	v_sub_f32_e32 v120, v119, v121
	v_ldexp_f32 v110, v110, 1
	v_sub_f32_e32 v111, v111, v120
	v_add_f32_e32 v110, v110, v111
	v_add_f32_e32 v111, v119, v110
	v_sub_f32_e32 v119, v111, v119
	v_add_f32_e32 v120, v125, v111
	v_sub_f32_e32 v110, v110, v119
	v_sub_f32_e32 v119, v120, v125
	v_sub_f32_e32 v121, v120, v119
	v_sub_f32_e32 v111, v111, v119
	v_add_f32_e32 v119, v118, v110
	v_sub_f32_e32 v121, v125, v121
	v_sub_f32_e32 v122, v119, v118
	v_add_f32_e32 v111, v111, v121
	v_sub_f32_e32 v121, v119, v122
	v_sub_f32_e32 v110, v110, v122
	v_sub_f32_e32 v118, v118, v121
	v_add_f32_e32 v111, v119, v111
	v_add_f32_e32 v110, v110, v118
	v_add_f32_e32 v118, v120, v111
	v_sub_f32_e32 v119, v118, v120
	v_sub_f32_e32 v111, v111, v119
	v_add_f32_e32 v110, v110, v111
	v_add_f32_e32 v110, v118, v110
	v_cmp_neq_f32_e32 vcc, s67, v113
	s_nop 1
	v_cndmask_b32_e32 v110, v194, v110, vcc
	v_cmp_ngt_f32_e32 vcc, -1.0, v113
	s_nop 1
	v_cndmask_b32_e32 v110, v195, v110, vcc
	v_cmp_neq_f32_e32 vcc, -1.0, v113
	s_nop 1
	v_cndmask_b32_e32 v110, v196, v110, vcc
	v_cmp_lt_f32_e64 vcc, |v113|, s68
	s_nop 1
	v_cndmask_b32_e32 v110, v110, v113, vcc
	v_sub_f32_e32 v110, v117, v110
	global_store_dword v[108:109], v110, off offset:-32
	global_load_dword v110, v176, s[80:81] offset:-28
	s_waitcnt vmcnt(0)
; template <bool SWAP> DI void inproj_tile(const Params& p, int layer, int tm, int tn, bf16_t* smem) {
;     ...
; #pragma unroll
;           for (int r = 0; r < 4; ++r) { const int h = (quad - 2) * 4 + r; const float xx = acc[i][1][r] * rs + p.b_forget[layer * 8 + h]; lf[h] = fminf(xx, 0.f) - log1pf(__expf(-fabsf(xx))); }
	v_fmac_f32_e32 v110, v105, v116
	v_mul_f32_e64 v111, |v110|, s64
	v_exp_f32_e32 v113, v111
	v_min_f32_e32 v117, 0, v110
	v_add_f32_e32 v118, 1.0, v113
	v_add_f32_e32 v119, -1.0, v118
	v_frexp_mant_f32_e32 v120, v118
	v_cvt_f64_f32_e32 v[110:111], v118
	v_sub_f32_e32 v121, v119, v118
	v_frexp_exp_i32_f64_e32 v110, v[110:111]
	v_cmp_gt_f32_e32 vcc, s65, v120
	v_sub_f32_e32 v119, v113, v119
	v_add_f32_e32 v111, 1.0, v121
	v_subbrev_co_u32_e32 v110, vcc, 0, v110, vcc
	v_add_f32_e32 v111, v119, v111
	v_sub_u32_e32 v119, 0, v110
	v_cvt_f32_i32_e32 v110, v110
	v_ldexp_f32 v118, v118, v119
	v_ldexp_f32 v111, v111, v119
	v_add_f32_e32 v119, -1.0, v118
	v_add_f32_e32 v120, 1.0, v118
	v_add_f32_e32 v121, 1.0, v119
	v_add_f32_e32 v122, -1.0, v120
	v_sub_f32_e32 v121, v118, v121
	v_sub_f32_e32 v118, v118, v122
	v_mul_f32_e32 v122, 0x3f317218, v110
	v_add_f32_e32 v121, v111, v121
	v_add_f32_e32 v111, v111, v118
	v_fma_f32 v118, v110, s66, -v122
	v_add_f32_e32 v123, v119, v121
	v_add_f32_e32 v124, v120, v111
	v_fmac_f32_e32 v118, 0xb102e308, v110
	v_sub_f32_e32 v110, v123, v119
	v_sub_f32_e32 v119, v124, v120
	v_rcp_f32_e32 v120, v124
	v_add_f32_e32 v125, v122, v118
	v_sub_f32_e32 v111, v111, v119
	v_sub_f32_e32 v119, v125, v122
	v_sub_f32_e32 v118, v118, v119
	v_mul_f32_e32 v119, v123, v120
	v_sub_f32_e32 v110, v121, v110
	v_mul_f32_e32 v121, v124, v119
	v_fma_f32 v122, v119, v124, -v121
	v_fmac_f32_e32 v122, v119, v111
	v_add_f32_e32 v126, v121, v122
	v_sub_f32_e32 v127, v123, v126
	v_sub_f32_e32 v121, v126, v121
	v_sub_f32_e32 v123, v123, v127
	v_sub_f32_e32 v121, v121, v122
	v_sub_f32_e32 v122, v123, v126
	v_add_f32_e32 v110, v110, v122
	v_add_f32_e32 v110, v121, v110
	v_add_f32_e32 v121, v127, v110
	v_mul_f32_e32 v122, v120, v121
	v_sub_f32_e32 v123, v127, v121
	v_mul_f32_e32 v126, v124, v122
	v_add_f32_e32 v110, v110, v123
	v_add_f32_e32 v123, v119, v122
	v_fma_f32 v124, v122, v124, -v126
	v_sub_f32_e32 v119, v123, v119
	v_fmac_f32_e32 v124, v122, v111
	v_sub_f32_e32 v111, v122, v119
	v_add_f32_e32 v119, v126, v124
	v_sub_f32_e32 v122, v119, v126
	v_sub_f32_e32 v126, v121, v119
	v_sub_f32_e32 v121, v121, v126
	v_sub_f32_e32 v119, v121, v119
	v_sub_f32_e32 v122, v122, v124
	v_add_f32_e32 v110, v110, v119
	v_add_f32_e32 v110, v122, v110
	v_add_f32_e32 v110, v126, v110
	v_mul_f32_e32 v110, v120, v110
	v_add_f32_e32 v110, v111, v110
	v_add_f32_e32 v111, v123, v110
	v_mul_f32_e32 v119, v111, v111
	v_fmamk_f32 v122, v119, 0x3e9b6dac, v186
	v_sub_f32_e32 v120, v111, v123
	v_ldexp_f32 v121, v111, 1
	v_mul_f32_e32 v111, v111, v119
	v_fmaak_f32 v119, v119, v122, 0x3f2aaada
	v_mul_f32_e32 v111, v111, v119
	v_add_f32_e32 v119, v121, v111
	v_sub_f32_e32 v110, v110, v120
	v_sub_f32_e32 v120, v119, v121
	v_ldexp_f32 v110, v110, 1
	v_sub_f32_e32 v111, v111, v120
	v_add_f32_e32 v110, v110, v111
	v_add_f32_e32 v111, v119, v110
	v_sub_f32_e32 v119, v111, v119
	v_add_f32_e32 v120, v125, v111
	v_sub_f32_e32 v110, v110, v119
	v_sub_f32_e32 v119, v120, v125
	v_sub_f32_e32 v121, v120, v119
	v_sub_f32_e32 v111, v111, v119
	v_add_f32_e32 v119, v118, v110
	v_sub_f32_e32 v121, v125, v121
	v_sub_f32_e32 v122, v119, v118
	v_add_f32_e32 v111, v111, v121
	v_sub_f32_e32 v121, v119, v122
	v_sub_f32_e32 v110, v110, v122
	v_sub_f32_e32 v118, v118, v121
	v_add_f32_e32 v111, v119, v111
	v_add_f32_e32 v110, v110, v118
	v_add_f32_e32 v118, v120, v111
	v_sub_f32_e32 v119, v118, v120
	v_sub_f32_e32 v111, v111, v119
	v_add_f32_e32 v110, v110, v111
	v_add_f32_e32 v110, v118, v110
	v_cmp_neq_f32_e32 vcc, s67, v113
	s_nop 1
	v_cndmask_b32_e32 v110, v194, v110, vcc
	v_cmp_ngt_f32_e32 vcc, -1.0, v113
	s_nop 1
	v_cndmask_b32_e32 v110, v195, v110, vcc
	v_cmp_neq_f32_e32 vcc, -1.0, v113
	s_nop 1
	v_cndmask_b32_e32 v110, v196, v110, vcc
	v_cmp_lt_f32_e64 vcc, |v113|, s68
	s_nop 1
	v_cndmask_b32_e32 v110, v110, v113, vcc
	v_sub_f32_e32 v110, v117, v110
	global_store_dword v[108:109], v110, off offset:-28
	global_load_dword v110, v176, s[80:81] offset:-24
	s_waitcnt vmcnt(0)
	v_fmac_f32_e32 v110, v106, v116
	v_mul_f32_e64 v111, |v110|, s64
	v_exp_f32_e32 v113, v111
	v_min_f32_e32 v117, 0, v110
	v_add_f32_e32 v118, 1.0, v113
	v_add_f32_e32 v119, -1.0, v118
	v_frexp_mant_f32_e32 v120, v118
	v_cvt_f64_f32_e32 v[110:111], v118
	v_sub_f32_e32 v121, v119, v118
	v_frexp_exp_i32_f64_e32 v110, v[110:111]
	v_cmp_gt_f32_e32 vcc, s65, v120
	v_sub_f32_e32 v119, v113, v119
	v_add_f32_e32 v111, 1.0, v121
	v_subbrev_co_u32_e32 v110, vcc, 0, v110, vcc
	v_add_f32_e32 v111, v119, v111
	v_sub_u32_e32 v119, 0, v110
	v_cvt_f32_i32_e32 v110, v110
	v_ldexp_f32 v118, v118, v119
	v_ldexp_f32 v111, v111, v119
	v_add_f32_e32 v119, -1.0, v118
	v_add_f32_e32 v120, 1.0, v118
	v_add_f32_e32 v121, 1.0, v119
	v_add_f32_e32 v122, -1.0, v120
	v_sub_f32_e32 v121, v118, v121
	v_sub_f32_e32 v118, v118, v122
	v_mul_f32_e32 v122, 0x3f317218, v110
	v_add_f32_e32 v121, v111, v121
	v_add_f32_e32 v111, v111, v118
	v_fma_f32 v118, v110, s66, -v122
	v_add_f32_e32 v123, v119, v121
	v_add_f32_e32 v124, v120, v111
	v_fmac_f32_e32 v118, 0xb102e308, v110
	v_sub_f32_e32 v110, v123, v119
	v_sub_f32_e32 v119, v124, v120
	v_rcp_f32_e32 v120, v124
	v_add_f32_e32 v125, v122, v118
	v_sub_f32_e32 v111, v111, v119
	v_sub_f32_e32 v119, v125, v122
	v_sub_f32_e32 v118, v118, v119
	v_mul_f32_e32 v119, v123, v120
	v_sub_f32_e32 v110, v121, v110
	v_mul_f32_e32 v121, v124, v119
	v_fma_f32 v122, v119, v124, -v121
	v_fmac_f32_e32 v122, v119, v111
	v_add_f32_e32 v126, v121, v122
	v_sub_f32_e32 v127, v123, v126
	v_sub_f32_e32 v121, v126, v121
	v_sub_f32_e32 v123, v123, v127
	v_sub_f32_e32 v121, v121, v122
	v_sub_f32_e32 v122, v123, v126
	v_add_f32_e32 v110, v110, v122
; template <bool SWAP> DI void inproj_tile(const Params& p, int layer, int tm, int tn, bf16_t* smem) {
;     ...
; #pragma unroll
;           for (int r = 0; r < 4; ++r) { const int h = (quad - 2) * 4 + r; const float xx = acc[i][1][r] * rs + p.b_forget[layer * 8 + h]; lf[h] = fminf(xx, 0.f) - log1pf(__expf(-fabsf(xx))); }
	v_add_f32_e32 v110, v121, v110
	v_add_f32_e32 v121, v127, v110
	v_mul_f32_e32 v122, v120, v121
	v_sub_f32_e32 v123, v127, v121
	v_mul_f32_e32 v126, v124, v122
	v_add_f32_e32 v110, v110, v123
	v_add_f32_e32 v123, v119, v122
	v_fma_f32 v124, v122, v124, -v126
	v_sub_f32_e32 v119, v123, v119
	v_fmac_f32_e32 v124, v122, v111
	v_sub_f32_e32 v111, v122, v119
	v_add_f32_e32 v119, v126, v124
	v_sub_f32_e32 v122, v119, v126
	v_sub_f32_e32 v126, v121, v119
	v_sub_f32_e32 v121, v121, v126
	v_sub_f32_e32 v119, v121, v119
	v_sub_f32_e32 v122, v122, v124
	v_add_f32_e32 v110, v110, v119
	v_add_f32_e32 v110, v122, v110
	v_add_f32_e32 v110, v126, v110
	v_mul_f32_e32 v110, v120, v110
	v_add_f32_e32 v110, v111, v110
	v_add_f32_e32 v111, v123, v110
	v_mul_f32_e32 v119, v111, v111
	v_fmamk_f32 v122, v119, 0x3e9b6dac, v186
	v_sub_f32_e32 v120, v111, v123
	v_ldexp_f32 v121, v111, 1
	v_mul_f32_e32 v111, v111, v119
	v_fmaak_f32 v119, v119, v122, 0x3f2aaada
	v_mul_f32_e32 v111, v111, v119
	v_add_f32_e32 v119, v121, v111
	v_sub_f32_e32 v110, v110, v120
	v_sub_f32_e32 v120, v119, v121
	v_ldexp_f32 v110, v110, 1
	v_sub_f32_e32 v111, v111, v120
	v_add_f32_e32 v110, v110, v111
	v_add_f32_e32 v111, v119, v110
	v_sub_f32_e32 v119, v111, v119
	v_add_f32_e32 v120, v125, v111
	v_sub_f32_e32 v110, v110, v119
	v_sub_f32_e32 v119, v120, v125
	v_sub_f32_e32 v121, v120, v119
	v_sub_f32_e32 v111, v111, v119
	v_add_f32_e32 v119, v118, v110
	v_sub_f32_e32 v121, v125, v121
	v_sub_f32_e32 v122, v119, v118
	v_add_f32_e32 v111, v111, v121
	v_sub_f32_e32 v121, v119, v122
	v_sub_f32_e32 v110, v110, v122
	v_sub_f32_e32 v118, v118, v121
	v_add_f32_e32 v111, v119, v111
	v_add_f32_e32 v110, v110, v118
	v_add_f32_e32 v118, v120, v111
	v_sub_f32_e32 v119, v118, v120
	v_sub_f32_e32 v111, v111, v119
	v_add_f32_e32 v110, v110, v111
	v_add_f32_e32 v110, v118, v110
	v_cmp_neq_f32_e32 vcc, s67, v113
	s_nop 1
	v_cndmask_b32_e32 v110, v194, v110, vcc
	v_cmp_ngt_f32_e32 vcc, -1.0, v113
	s_nop 1
	v_cndmask_b32_e32 v110, v195, v110, vcc
	v_cmp_neq_f32_e32 vcc, -1.0, v113
	s_nop 1
	v_cndmask_b32_e32 v110, v196, v110, vcc
	v_cmp_lt_f32_e64 vcc, |v113|, s68
	s_nop 1
	v_cndmask_b32_e32 v110, v110, v113, vcc
	v_sub_f32_e32 v110, v117, v110
	global_store_dword v[108:109], v110, off offset:-24
	global_load_dword v110, v176, s[80:81] offset:-20
	s_waitcnt vmcnt(0)
	v_fmac_f32_e32 v110, v107, v116
	v_mul_f32_e64 v111, |v110|, s64
	v_exp_f32_e32 v113, v111
	v_min_f32_e32 v117, 0, v110
	v_add_f32_e32 v118, 1.0, v113
	v_add_f32_e32 v119, -1.0, v118
	v_frexp_mant_f32_e32 v120, v118
	v_cvt_f64_f32_e32 v[110:111], v118
	v_sub_f32_e32 v121, v119, v118
	v_frexp_exp_i32_f64_e32 v110, v[110:111]
	v_cmp_gt_f32_e32 vcc, s65, v120
	v_sub_f32_e32 v119, v113, v119
	v_add_f32_e32 v111, 1.0, v121
	v_subbrev_co_u32_e32 v110, vcc, 0, v110, vcc
	v_add_f32_e32 v111, v119, v111
	v_sub_u32_e32 v119, 0, v110
	v_cvt_f32_i32_e32 v110, v110
	v_ldexp_f32 v118, v118, v119
	v_ldexp_f32 v111, v111, v119
	v_add_f32_e32 v119, -1.0, v118
	v_add_f32_e32 v120, 1.0, v118
	v_add_f32_e32 v121, 1.0, v119
	v_add_f32_e32 v122, -1.0, v120
	v_sub_f32_e32 v121, v118, v121
	v_sub_f32_e32 v118, v118, v122
	v_mul_f32_e32 v122, 0x3f317218, v110
	v_add_f32_e32 v121, v111, v121
	v_add_f32_e32 v111, v111, v118
	v_fma_f32 v118, v110, s66, -v122
	v_add_f32_e32 v123, v119, v121
	v_add_f32_e32 v124, v120, v111
	v_fmac_f32_e32 v118, 0xb102e308, v110
	v_sub_f32_e32 v110, v123, v119
	v_sub_f32_e32 v119, v124, v120
	v_rcp_f32_e32 v120, v124
	v_add_f32_e32 v125, v122, v118
	v_sub_f32_e32 v111, v111, v119
	v_sub_f32_e32 v119, v125, v122
	v_sub_f32_e32 v118, v118, v119
	v_mul_f32_e32 v119, v123, v120
	v_sub_f32_e32 v110, v121, v110
	v_mul_f32_e32 v121, v124, v119
	v_fma_f32 v122, v119, v124, -v121
	v_fmac_f32_e32 v122, v119, v111
	v_add_f32_e32 v126, v121, v122
	v_sub_f32_e32 v127, v123, v126
	v_sub_f32_e32 v121, v126, v121
	v_sub_f32_e32 v123, v123, v127
	v_sub_f32_e32 v121, v121, v122
	v_sub_f32_e32 v122, v123, v126
	v_add_f32_e32 v110, v110, v122
	v_add_f32_e32 v110, v121, v110
	v_add_f32_e32 v121, v127, v110
	v_mul_f32_e32 v122, v120, v121
	v_sub_f32_e32 v123, v127, v121
	v_mul_f32_e32 v126, v124, v122
	v_add_f32_e32 v110, v110, v123
	v_add_f32_e32 v123, v119, v122
	v_fma_f32 v124, v122, v124, -v126
	v_sub_f32_e32 v119, v123, v119
	v_fmac_f32_e32 v124, v122, v111
	v_sub_f32_e32 v111, v122, v119
	v_add_f32_e32 v119, v126, v124
	v_sub_f32_e32 v122, v119, v126
	v_sub_f32_e32 v126, v121, v119
	v_sub_f32_e32 v121, v121, v126
	v_sub_f32_e32 v119, v121, v119
	v_sub_f32_e32 v122, v122, v124
	v_add_f32_e32 v110, v110, v119
	v_add_f32_e32 v110, v122, v110
	v_add_f32_e32 v110, v126, v110
	v_mul_f32_e32 v110, v120, v110
	v_add_f32_e32 v110, v111, v110
	v_add_f32_e32 v111, v123, v110
	v_mul_f32_e32 v119, v111, v111
	v_fmamk_f32 v122, v119, 0x3e9b6dac, v186
	v_sub_f32_e32 v120, v111, v123
	v_ldexp_f32 v121, v111, 1
	v_mul_f32_e32 v111, v111, v119
	v_fmaak_f32 v119, v119, v122, 0x3f2aaada
	v_mul_f32_e32 v111, v111, v119
	v_add_f32_e32 v119, v121, v111
	v_sub_f32_e32 v110, v110, v120
	v_sub_f32_e32 v120, v119, v121
	v_ldexp_f32 v110, v110, 1
	v_sub_f32_e32 v111, v111, v120
	v_add_f32_e32 v110, v110, v111
	v_add_f32_e32 v111, v119, v110
	v_sub_f32_e32 v119, v111, v119
	v_add_f32_e32 v120, v125, v111
	v_sub_f32_e32 v110, v110, v119
	v_sub_f32_e32 v119, v120, v125
	v_sub_f32_e32 v121, v120, v119
	v_sub_f32_e32 v111, v111, v119
	v_add_f32_e32 v119, v118, v110
	v_sub_f32_e32 v121, v125, v121
	v_sub_f32_e32 v122, v119, v118
	v_add_f32_e32 v111, v111, v121
	v_sub_f32_e32 v121, v119, v122
	v_sub_f32_e32 v110, v110, v122
	v_sub_f32_e32 v118, v118, v121
	v_add_f32_e32 v111, v119, v111
	v_add_f32_e32 v110, v110, v118
	v_add_f32_e32 v118, v120, v111
	v_sub_f32_e32 v119, v118, v120
	v_sub_f32_e32 v111, v111, v119
	v_add_f32_e32 v110, v110, v111
	v_add_f32_e32 v110, v118, v110
	v_cmp_neq_f32_e32 vcc, s67, v113
	s_nop 1
	v_cndmask_b32_e32 v110, v194, v110, vcc
	v_cmp_ngt_f32_e32 vcc, -1.0, v113
	s_nop 1
	v_cndmask_b32_e32 v110, v195, v110, vcc
	v_cmp_neq_f32_e32 vcc, -1.0, v113
	s_nop 1
	v_cndmask_b32_e32 v110, v196, v110, vcc
	v_cmp_lt_f32_e64 vcc, |v113|, s68
	s_nop 1
	v_cndmask_b32_e32 v110, v110, v113, vcc
	v_sub_f32_e32 v110, v117, v110
	global_store_dword v[108:109], v110, off offset:-20
; DI unsigned pk2(float lo, float hi) { f32x2 v = {lo, hi}; return __builtin_bit_cast(unsigned, __builtin_convertvector(v, bfx2)); }
; DI float sigmoidf_(float x) { return 1.f / (1.f + __expf(-x)); }
; DI float rstd_from16(const float* p, float inv_n) {
;   const f32x4 a = *(const f32x4*)p, b = *(const f32x4*)(p + 4), c = *(const f32x4*)(p + 8), d = *(const f32x4*)(p + 12);
;   const float s = ((a[0] + a[1]) + (a[2] + a[3])) + ((b[0] + b[1]) + (b[2] + b[3])) + ((c[0] + c[1]) + (c[2] + c[3])) + ((d[0] + d[1]) + (d[2] + d[3]));
;   return rsqrtf(s * inv_n + EPS_);
; template <bool SWAP> DI void inproj_tile(const Params& p, int layer, int tm, int tn, bf16_t* smem) {
;     ...
;         const int t = trow0 + i * 16 + l15; const float rs = rstd_from16(ssq + (size_t)t * 16, 1.f / 1024.f);
;         float* gt = (float*)(p.ws + O_GATES) + (size_t)t * 24; float* lf = (float*)(p.ws + O_LOGF) + (size_t)t * 8;
; #pragma unroll
;         for (int r = 0; r < 4; ++r) gt[quad * 4 + r] = sigmoidf_(acc[i][0][r] * rs);
;         if (quad < 2) {
; #pragma unroll
;           for (int r = 0; r < 4; ++r) gt[16 + quad * 4 + r] = sigmoidf_(acc[i][1][r] * rs);
;         } else {
; #pragma unroll
;           for (int r = 0; r < 4; ++r) { const int h = (quad - 2) * 4 + r; const float xx = acc[i][1][r] * rs + p.b_forget[layer * 8 + h]; lf[h] = fminf(xx, 0.f) - log1pf(__expf(-fabsf(xx))); }
;         }
;         const float* rp = (const float*)(p.ws + O_ROPE16) + (size_t)t * 32 + quad * 8; float o1[4], o2[4];
; #pragma unroll
;         for (int r = 0; r < 4; ++r) { const float cs = rp[2 * r], sn = rp[2 * r + 1], x1 = acc[i][2][r] * rs, x2 = acc[i][3][r] * rs; o1[r] = x1 * cs - x2 * sn; o2[r] = x2 * cs + x1 * sn; }
;         bf16_t* kp = (bf16_t*)(p.ws + O_MLAKPE) + (size_t)t * 32 + quad * 4;
;         *(u32x2*)kp = (u32x2){pk2(o1[0], o1[1]), pk2(o1[2], o1[3])}; *(u32x2*)(kp + 16) = (u32x2){pk2(o2[0], o2[1]), pk2(o2[2], o2[3])};
.LBB0_267:
	s_andn2_saveexec_b64 s[0:1], s[0:1]
	s_cbranch_execz .LBB0_269
	v_mul_f32_e32 v104, v104, v116
	v_mul_f32_e32 v105, v105, v116
	v_mul_f32_e32 v104, 0xbfb8aa3b, v104
	v_mul_f32_e32 v105, 0xbfb8aa3b, v105
	v_exp_f32_e32 v104, v104
	v_exp_f32_e32 v105, v105
	v_mul_f32_e32 v106, v106, v116
	v_mul_f32_e32 v107, v107, v116
	v_mul_f32_e32 v106, 0xbfb8aa3b, v106
	v_pk_add_f32 v[104:105], v[104:105], 1.0 op_sel_hi:[1,0]
	v_mul_f32_e32 v107, 0xbfb8aa3b, v107
	v_exp_f32_e32 v106, v106
	v_rcp_f32_e32 v105, v105
	v_exp_f32_e32 v107, v107
	s_nop 0
	v_pk_add_f32 v[106:107], v[106:107], 1.0 op_sel_hi:[1,0]
	v_rcp_f32_e32 v104, v104
	v_rcp_f32_e32 v107, v107
	v_rcp_f32_e32 v106, v106
	global_store_dwordx4 v[118:119], v[104:107], off offset:64
.LBB0_269:
	s_or_b64 exec, exec, s[0:1]
	s_nop 0
	v_lshlrev_b32_e32 v104, 3, v144
	v_lshl_add_u64 v[106:107], v[114:115], 2, s[14:15]
	v_lshlrev_b32_e32 v104, 2, v104
	v_mov_b32_e32 v105, v177
	v_lshl_add_u64 v[110:111], v[106:107], 0, v[104:105]
	global_load_dwordx4 v[106:109], v[110:111], off
	global_load_dwordx4 v[118:121], v[110:111], off offset:16
	v_or_b32_e32 v110, 32, v128
	v_ashrrev_i32_e32 v111, 31, v110
	v_lshlrev_b64 v[122:123], 6, v[110:111]
	v_lshl_add_u64 v[126:127], s[8:9], 0, v[122:123]
	global_load_dwordx4 v[122:125], v[126:127], off
	global_load_dwordx4 v[130:133], v[126:127], off offset:16
	global_load_dwordx4 v[134:137], v[126:127], off offset:32
	global_load_dwordx4 v[138:141], v[126:127], off offset:48
	v_pk_mul_f32 v[126:127], v[96:97], v[116:117] op_sel_hi:[1,0]
	v_lshl_add_u64 v[96:97], v[114:115], 1, s[16:17]
	v_mov_b32_e32 v113, v177
	v_pk_mul_f32 v[142:143], v[100:101], v[116:117] op_sel_hi:[1,0]
	v_pk_mul_f32 v[98:99], v[98:99], v[116:117] op_sel_hi:[1,0]
	v_pk_mul_f32 v[102:103], v[102:103], v[116:117] op_sel_hi:[1,0]
	v_mov_b64_e32 v[100:101], s[10:11]
	v_lshl_add_u64 v[114:115], v[96:97], 0, v[112:113]
	v_lshlrev_b64 v[96:97], 5, v[110:111]
	v_mad_i64_i32 v[100:101], s[0:1], v110, s63, v[100:101]
	v_lshl_add_u64 v[100:101], v[100:101], 0, v[176:177]
	s_waitcnt vmcnt(5)
	v_mov_b32_e32 v111, v108
	v_mov_b32_e32 v108, v107
	s_waitcnt vmcnt(4)
	v_mov_b32_e32 v107, v120
	v_mov_b32_e32 v120, v119
	v_mov_b32_e32 v110, v106
	v_mov_b32_e32 v106, v118
	v_pk_mul_f32 v[116:117], v[126:127], v[108:109]
	v_pk_mul_f32 v[108:109], v[142:143], v[108:109]
	v_pk_mul_f32 v[118:119], v[98:99], v[120:121]
	v_pk_mul_f32 v[120:121], v[102:103], v[120:121]
	s_waitcnt vmcnt(3)
	v_mov_b32_e32 v144, v123
	v_mov_b32_e32 v145, v124
	v_mov_b32_e32 v123, v125
	s_waitcnt vmcnt(2)
	v_mov_b32_e32 v124, v131
	v_mov_b32_e32 v125, v132
	v_mov_b32_e32 v131, v133
	v_pk_fma_f32 v[116:117], v[142:143], v[110:111], v[116:117] neg_lo:[0,0,1] neg_hi:[0,0,1]
	v_pk_fma_f32 v[108:109], v[126:127], v[110:111], v[108:109]
	v_pk_fma_f32 v[102:103], v[102:103], v[106:107], v[118:119] neg_lo:[0,0,1] neg_hi:[0,0,1]
	v_pk_fma_f32 v[98:99], v[98:99], v[106:107], v[120:121]
	v_pk_add_f32 v[106:107], v[144:145], v[122:123]
	v_pk_add_f32 v[110:111], v[124:125], v[130:131]
	v_pk_add_f32 v[106:107], v[106:107], v[106:107] op_sel:[0,1] op_sel_hi:[1,0]
	v_pk_add_f32 v[110:111], v[110:111], v[110:111] op_sel:[0,1] op_sel_hi:[1,0]
	s_waitcnt vmcnt(1)
	v_add_f32_e32 v132, v134, v135
	v_add_f32_e32 v134, v136, v137
	s_waitcnt vmcnt(0)
	v_mov_b32_e32 v133, v140
	v_mov_b32_e32 v135, v141
	v_mov_b32_e32 v107, v138
	v_mov_b32_e32 v111, v139
	v_pk_add_f32 v[118:119], v[132:133], v[134:135]
	v_pk_add_f32 v[106:107], v[106:107], v[110:111]
	v_cvt_pk_bf16_f32 v116, v116, v117
	v_pk_add_f32 v[106:107], v[106:107], v[118:119]
	v_cvt_pk_bf16_f32 v117, v102, v103
	v_add_f32_e32 v105, v106, v107
	v_fmamk_f32 v105, v105, 0x3a800000, v185
	v_mul_f32_e32 v106, 0x4b800000, v105
	v_cmp_gt_f32_e32 vcc, s60, v105
	v_cvt_pk_bf16_f32 v103, v98, v99
	v_cvt_pk_bf16_f32 v102, v108, v109
	v_cndmask_b32_e32 v105, v105, v106, vcc
	v_rsq_f32_e32 v105, v105
	global_store_dwordx2 v[114:115], v[116:117], off
	global_store_dwordx2 v[114:115], v[102:103], off offset:32
	v_mul_f32_e32 v98, 0x45800000, v105
	v_cndmask_b32_e32 v98, v105, v98, vcc
	v_mul_f32_e32 v92, v92, v98
	v_mul_f32_e32 v93, v93, v98
	v_mul_f32_e32 v92, 0xbfb8aa3b, v92
	v_mul_f32_e32 v93, 0xbfb8aa3b, v93
	v_mul_f32_e32 v94, v94, v98
	v_mul_f32_e32 v95, v95, v98
	v_exp_f32_e32 v92, v92
	v_exp_f32_e32 v93, v93
	v_mul_f32_e32 v94, 0xbfb8aa3b, v94
	v_mul_f32_e32 v95, 0xbfb8aa3b, v95
	v_exp_f32_e32 v94, v94
	v_exp_f32_e32 v95, v95
	v_pk_add_f32 v[92:93], v[92:93], 1.0 op_sel_hi:[1,0]
	v_pk_add_f32 v[94:95], v[94:95], 1.0 op_sel_hi:[1,0]
	v_div_scale_f32 v103, s[0:1], v92, v92, 1.0
	v_rcp_f32_e32 v107, v103
	s_nop 0
	v_fma_f32 v111, -v103, v107, 1.0
	v_div_scale_f32 v109, s[0:1], 1.0, v92, 1.0
	v_fmac_f32_e32 v107, v111, v107
	v_mul_f32_e32 v111, v109, v107
	v_fma_f32 v114, -v103, v111, v109
	v_fmac_f32_e32 v111, v114, v107
	v_fma_f32 v102, -v103, v111, v109
	s_mov_b64 vcc, s[0:1]
	v_rcp_f32_e32 v93, v93
	v_div_fmas_f32 v99, v102, v107, v111
	v_div_fixup_f32 v92, v99, v92, 1.0
	v_rcp_f32_e32 v95, v95
	v_rcp_f32_e32 v94, v94
	global_store_dwordx4 v[100:101], v[92:95], off
	s_and_saveexec_b64 s[0:1], s[2:3]
	s_xor_b64 s[0:1], exec, s[0:1]
	s_cbranch_execz .LBB0_271
; template <bool SWAP> DI void inproj_tile(const Params& p, int layer, int tm, int tn, bf16_t* smem) {
;     ...
; #pragma unroll
;           for (int r = 0; r < 4; ++r) { const int h = (quad - 2) * 4 + r; const float xx = acc[i][1][r] * rs + p.b_forget[layer * 8 + h]; lf[h] = fminf(xx, 0.f) - log1pf(__expf(-fabsf(xx))); }
	v_readlane_b32 s72, v241, 8
	v_readlane_b32 s80, v241, 16
	v_readlane_b32 s81, v241, 17
	v_readlane_b32 s73, v241, 9
	v_readlane_b32 s74, v241, 10
	v_readlane_b32 s75, v241, 11
	v_readlane_b32 s76, v241, 12
	v_readlane_b32 s77, v241, 13
	global_load_dword v94, v176, s[80:81] offset:-32
	v_readlane_b32 s78, v241, 14
	v_readlane_b32 s79, v241, 15
	v_readlane_b32 s82, v241, 18
	v_readlane_b32 s83, v241, 19
	v_readlane_b32 s84, v241, 20
	v_readlane_b32 s85, v241, 21
	v_readlane_b32 s86, v241, 22
	v_readlane_b32 s87, v241, 23
	s_waitcnt vmcnt(0)
	v_fmac_f32_e32 v94, v88, v98
	v_mul_f32_e64 v92, |v94|, s64
	v_exp_f32_e32 v99, v92
	v_min_f32_e32 v100, 0, v94
	v_lshl_add_u64 v[92:93], s[12:13], 0, v[96:97]
	v_lshl_add_u64 v[92:93], v[92:93], 0, v[176:177]
	v_add_f32_e32 v101, 1.0, v99
	v_add_f32_e32 v102, -1.0, v101
	v_frexp_mant_f32_e32 v103, v101
	v_cvt_f64_f32_e32 v[94:95], v101
	v_sub_f32_e32 v105, v102, v101
	v_frexp_exp_i32_f64_e32 v94, v[94:95]
	v_cmp_gt_f32_e32 vcc, s65, v103
	v_sub_f32_e32 v102, v99, v102
	v_add_f32_e32 v95, 1.0, v105
	v_subbrev_co_u32_e32 v94, vcc, 0, v94, vcc
	v_add_f32_e32 v95, v102, v95
	v_sub_u32_e32 v102, 0, v94
	v_cvt_f32_i32_e32 v94, v94
	v_ldexp_f32 v101, v101, v102
	v_ldexp_f32 v95, v95, v102
	v_add_f32_e32 v102, -1.0, v101
	v_add_f32_e32 v103, 1.0, v101
	v_add_f32_e32 v105, 1.0, v102
	v_add_f32_e32 v106, -1.0, v103
	v_sub_f32_e32 v105, v101, v105
	v_sub_f32_e32 v101, v101, v106
	v_mul_f32_e32 v106, 0x3f317218, v94
	v_add_f32_e32 v105, v95, v105
	v_add_f32_e32 v95, v95, v101
	v_fma_f32 v101, v94, s66, -v106
	v_add_f32_e32 v107, v102, v105
	v_add_f32_e32 v108, v103, v95
	v_fmac_f32_e32 v101, 0xb102e308, v94
	v_sub_f32_e32 v94, v107, v102
	v_sub_f32_e32 v102, v108, v103
	v_rcp_f32_e32 v103, v108
	v_add_f32_e32 v109, v106, v101
	v_sub_f32_e32 v95, v95, v102
	v_sub_f32_e32 v102, v109, v106
	v_sub_f32_e32 v101, v101, v102
	v_mul_f32_e32 v102, v107, v103
	v_sub_f32_e32 v94, v105, v94
	v_mul_f32_e32 v105, v108, v102
	v_fma_f32 v106, v102, v108, -v105
	v_fmac_f32_e32 v106, v102, v95
	v_add_f32_e32 v110, v105, v106
	v_sub_f32_e32 v111, v107, v110
	v_sub_f32_e32 v105, v110, v105
	v_sub_f32_e32 v107, v107, v111
	v_sub_f32_e32 v105, v105, v106
	v_sub_f32_e32 v106, v107, v110
	v_add_f32_e32 v94, v94, v106
	v_add_f32_e32 v94, v105, v94
	v_add_f32_e32 v105, v111, v94
	v_mul_f32_e32 v106, v103, v105
	v_sub_f32_e32 v107, v111, v105
	v_mul_f32_e32 v110, v108, v106
	v_add_f32_e32 v94, v94, v107
	v_add_f32_e32 v107, v102, v106
	v_fma_f32 v108, v106, v108, -v110
	v_sub_f32_e32 v102, v107, v102
	v_fmac_f32_e32 v108, v106, v95
	v_sub_f32_e32 v95, v106, v102
	v_add_f32_e32 v102, v110, v108
	v_sub_f32_e32 v106, v102, v110
	v_sub_f32_e32 v110, v105, v102
	v_sub_f32_e32 v105, v105, v110
	v_sub_f32_e32 v102, v105, v102
	v_sub_f32_e32 v106, v106, v108
	v_add_f32_e32 v94, v94, v102
	v_add_f32_e32 v94, v106, v94
	v_add_f32_e32 v94, v110, v94
	v_mul_f32_e32 v94, v103, v94
	v_add_f32_e32 v94, v95, v94
	v_add_f32_e32 v95, v107, v94
	v_mul_f32_e32 v102, v95, v95
	v_fmamk_f32 v106, v102, 0x3e9b6dac, v186
	v_sub_f32_e32 v103, v95, v107
	v_ldexp_f32 v105, v95, 1
	v_mul_f32_e32 v95, v95, v102
	v_fmaak_f32 v102, v102, v106, 0x3f2aaada
	v_mul_f32_e32 v95, v95, v102
	v_add_f32_e32 v102, v105, v95
	v_sub_f32_e32 v94, v94, v103
	v_sub_f32_e32 v103, v102, v105
	v_ldexp_f32 v94, v94, 1
	v_sub_f32_e32 v95, v95, v103
	v_add_f32_e32 v94, v94, v95
	v_add_f32_e32 v95, v102, v94
	v_sub_f32_e32 v102, v95, v102
	v_add_f32_e32 v103, v109, v95
	v_sub_f32_e32 v94, v94, v102
	v_sub_f32_e32 v102, v103, v109
	v_sub_f32_e32 v105, v103, v102
	v_sub_f32_e32 v95, v95, v102
	v_add_f32_e32 v102, v101, v94
	v_sub_f32_e32 v105, v109, v105
	v_sub_f32_e32 v106, v102, v101
	v_add_f32_e32 v95, v95, v105
	v_sub_f32_e32 v105, v102, v106
	v_sub_f32_e32 v94, v94, v106
	v_sub_f32_e32 v101, v101, v105
	v_add_f32_e32 v95, v102, v95
	v_add_f32_e32 v94, v94, v101
	v_add_f32_e32 v101, v103, v95
	v_sub_f32_e32 v102, v101, v103
	v_sub_f32_e32 v95, v95, v102
	v_add_f32_e32 v94, v94, v95
	v_add_f32_e32 v94, v101, v94
	v_cmp_neq_f32_e32 vcc, s67, v99
	s_nop 1
	v_cndmask_b32_e32 v94, v194, v94, vcc
	v_cmp_ngt_f32_e32 vcc, -1.0, v99
	s_nop 1
	v_cndmask_b32_e32 v94, v195, v94, vcc
	v_cmp_neq_f32_e32 vcc, -1.0, v99
	s_nop 1
	v_cndmask_b32_e32 v94, v196, v94, vcc
	v_cmp_lt_f32_e64 vcc, |v99|, s68
	s_nop 1
	v_cndmask_b32_e32 v94, v94, v99, vcc
	v_sub_f32_e32 v94, v100, v94
	global_store_dword v[92:93], v94, off offset:-32
	global_load_dword v94, v176, s[80:81] offset:-28
	s_waitcnt vmcnt(0)
; template <bool SWAP> DI void inproj_tile(const Params& p, int layer, int tm, int tn, bf16_t* smem) {
;     ...
; #pragma unroll
;           for (int r = 0; r < 4; ++r) { const int h = (quad - 2) * 4 + r; const float xx = acc[i][1][r] * rs + p.b_forget[layer * 8 + h]; lf[h] = fminf(xx, 0.f) - log1pf(__expf(-fabsf(xx))); }
	v_fmac_f32_e32 v94, v89, v98
	v_mul_f32_e64 v95, |v94|, s64
	v_exp_f32_e32 v99, v95
	v_min_f32_e32 v100, 0, v94
	v_add_f32_e32 v101, 1.0, v99
	v_add_f32_e32 v102, -1.0, v101
	v_frexp_mant_f32_e32 v103, v101
	v_cvt_f64_f32_e32 v[94:95], v101
	v_sub_f32_e32 v105, v102, v101
	v_frexp_exp_i32_f64_e32 v94, v[94:95]
	v_cmp_gt_f32_e32 vcc, s65, v103
	v_sub_f32_e32 v102, v99, v102
	v_add_f32_e32 v95, 1.0, v105
	v_subbrev_co_u32_e32 v94, vcc, 0, v94, vcc
	v_add_f32_e32 v95, v102, v95
	v_sub_u32_e32 v102, 0, v94
	v_cvt_f32_i32_e32 v94, v94
	v_ldexp_f32 v101, v101, v102
	v_ldexp_f32 v95, v95, v102
	v_add_f32_e32 v102, -1.0, v101
	v_add_f32_e32 v103, 1.0, v101
	v_add_f32_e32 v105, 1.0, v102
	v_add_f32_e32 v106, -1.0, v103
	v_sub_f32_e32 v105, v101, v105
	v_sub_f32_e32 v101, v101, v106
	v_mul_f32_e32 v106, 0x3f317218, v94
	v_add_f32_e32 v105, v95, v105
	v_add_f32_e32 v95, v95, v101
	v_fma_f32 v101, v94, s66, -v106
	v_add_f32_e32 v107, v102, v105
	v_add_f32_e32 v108, v103, v95
	v_fmac_f32_e32 v101, 0xb102e308, v94
	v_sub_f32_e32 v94, v107, v102
	v_sub_f32_e32 v102, v108, v103
	v_rcp_f32_e32 v103, v108
	v_add_f32_e32 v109, v106, v101
	v_sub_f32_e32 v95, v95, v102
	v_sub_f32_e32 v102, v109, v106
	v_sub_f32_e32 v101, v101, v102
	v_mul_f32_e32 v102, v107, v103
	v_sub_f32_e32 v94, v105, v94
	v_mul_f32_e32 v105, v108, v102
	v_fma_f32 v106, v102, v108, -v105
	v_fmac_f32_e32 v106, v102, v95
	v_add_f32_e32 v110, v105, v106
	v_sub_f32_e32 v111, v107, v110
	v_sub_f32_e32 v105, v110, v105
	v_sub_f32_e32 v107, v107, v111
	v_sub_f32_e32 v105, v105, v106
	v_sub_f32_e32 v106, v107, v110
	v_add_f32_e32 v94, v94, v106
	v_add_f32_e32 v94, v105, v94
	v_add_f32_e32 v105, v111, v94
	v_mul_f32_e32 v106, v103, v105
	v_sub_f32_e32 v107, v111, v105
	v_mul_f32_e32 v110, v108, v106
	v_add_f32_e32 v94, v94, v107
	v_add_f32_e32 v107, v102, v106
	v_fma_f32 v108, v106, v108, -v110
	v_sub_f32_e32 v102, v107, v102
	v_fmac_f32_e32 v108, v106, v95
	v_sub_f32_e32 v95, v106, v102
	v_add_f32_e32 v102, v110, v108
	v_sub_f32_e32 v106, v102, v110
	v_sub_f32_e32 v110, v105, v102
	v_sub_f32_e32 v105, v105, v110
	v_sub_f32_e32 v102, v105, v102
	v_sub_f32_e32 v106, v106, v108
	v_add_f32_e32 v94, v94, v102
	v_add_f32_e32 v94, v106, v94
	v_add_f32_e32 v94, v110, v94
	v_mul_f32_e32 v94, v103, v94
	v_add_f32_e32 v94, v95, v94
	v_add_f32_e32 v95, v107, v94
	v_mul_f32_e32 v102, v95, v95
	v_fmamk_f32 v106, v102, 0x3e9b6dac, v186
	v_sub_f32_e32 v103, v95, v107
	v_ldexp_f32 v105, v95, 1
	v_mul_f32_e32 v95, v95, v102
	v_fmaak_f32 v102, v102, v106, 0x3f2aaada
	v_mul_f32_e32 v95, v95, v102
	v_add_f32_e32 v102, v105, v95
	v_sub_f32_e32 v94, v94, v103
	v_sub_f32_e32 v103, v102, v105
	v_ldexp_f32 v94, v94, 1
	v_sub_f32_e32 v95, v95, v103
	v_add_f32_e32 v94, v94, v95
	v_add_f32_e32 v95, v102, v94
	v_sub_f32_e32 v102, v95, v102
	v_add_f32_e32 v103, v109, v95
	v_sub_f32_e32 v94, v94, v102
	v_sub_f32_e32 v102, v103, v109
	v_sub_f32_e32 v105, v103, v102
	v_sub_f32_e32 v95, v95, v102
	v_add_f32_e32 v102, v101, v94
	v_sub_f32_e32 v105, v109, v105
	v_sub_f32_e32 v106, v102, v101
	v_add_f32_e32 v95, v95, v105
	v_sub_f32_e32 v105, v102, v106
	v_sub_f32_e32 v94, v94, v106
	v_sub_f32_e32 v101, v101, v105
	v_add_f32_e32 v95, v102, v95
	v_add_f32_e32 v94, v94, v101
	v_add_f32_e32 v101, v103, v95
	v_sub_f32_e32 v102, v101, v103
	v_sub_f32_e32 v95, v95, v102
	v_add_f32_e32 v94, v94, v95
	v_add_f32_e32 v94, v101, v94
	v_cmp_neq_f32_e32 vcc, s67, v99
	s_nop 1
	v_cndmask_b32_e32 v94, v194, v94, vcc
	v_cmp_ngt_f32_e32 vcc, -1.0, v99
	s_nop 1
	v_cndmask_b32_e32 v94, v195, v94, vcc
	v_cmp_neq_f32_e32 vcc, -1.0, v99
	s_nop 1
	v_cndmask_b32_e32 v94, v196, v94, vcc
	v_cmp_lt_f32_e64 vcc, |v99|, s68
	s_nop 1
	v_cndmask_b32_e32 v94, v94, v99, vcc
	v_sub_f32_e32 v94, v100, v94
	global_store_dword v[92:93], v94, off offset:-28
	global_load_dword v94, v176, s[80:81] offset:-24
	s_waitcnt vmcnt(0)
	v_fmac_f32_e32 v94, v90, v98
	v_mul_f32_e64 v95, |v94|, s64
	v_exp_f32_e32 v99, v95
	v_min_f32_e32 v100, 0, v94
	v_add_f32_e32 v101, 1.0, v99
	v_add_f32_e32 v102, -1.0, v101
	v_frexp_mant_f32_e32 v103, v101
	v_cvt_f64_f32_e32 v[94:95], v101
	v_sub_f32_e32 v105, v102, v101
	v_frexp_exp_i32_f64_e32 v94, v[94:95]
	v_cmp_gt_f32_e32 vcc, s65, v103
	v_sub_f32_e32 v102, v99, v102
	v_add_f32_e32 v95, 1.0, v105
	v_subbrev_co_u32_e32 v94, vcc, 0, v94, vcc
	v_add_f32_e32 v95, v102, v95
	v_sub_u32_e32 v102, 0, v94
	v_cvt_f32_i32_e32 v94, v94
	v_ldexp_f32 v101, v101, v102
	v_ldexp_f32 v95, v95, v102
	v_add_f32_e32 v102, -1.0, v101
	v_add_f32_e32 v103, 1.0, v101
	v_add_f32_e32 v105, 1.0, v102
	v_add_f32_e32 v106, -1.0, v103
	v_sub_f32_e32 v105, v101, v105
	v_sub_f32_e32 v101, v101, v106
	v_mul_f32_e32 v106, 0x3f317218, v94
	v_add_f32_e32 v105, v95, v105
	v_add_f32_e32 v95, v95, v101
	v_fma_f32 v101, v94, s66, -v106
	v_add_f32_e32 v107, v102, v105
	v_add_f32_e32 v108, v103, v95
	v_fmac_f32_e32 v101, 0xb102e308, v94
	v_sub_f32_e32 v94, v107, v102
	v_sub_f32_e32 v102, v108, v103
	v_rcp_f32_e32 v103, v108
	v_add_f32_e32 v109, v106, v101
	v_sub_f32_e32 v95, v95, v102
	v_sub_f32_e32 v102, v109, v106
	v_sub_f32_e32 v101, v101, v102
	v_mul_f32_e32 v102, v107, v103
	v_sub_f32_e32 v94, v105, v94
	v_mul_f32_e32 v105, v108, v102
	v_fma_f32 v106, v102, v108, -v105
	v_fmac_f32_e32 v106, v102, v95
	v_add_f32_e32 v110, v105, v106
	v_sub_f32_e32 v111, v107, v110
	v_sub_f32_e32 v105, v110, v105
	v_sub_f32_e32 v107, v107, v111
	v_sub_f32_e32 v105, v105, v106
	v_sub_f32_e32 v106, v107, v110
	v_add_f32_e32 v94, v94, v106
	v_add_f32_e32 v94, v105, v94
	v_add_f32_e32 v105, v111, v94
	v_mul_f32_e32 v106, v103, v105
	v_sub_f32_e32 v107, v111, v105
	v_mul_f32_e32 v110, v108, v106
; template <bool SWAP> DI void inproj_tile(const Params& p, int layer, int tm, int tn, bf16_t* smem) {
;     ...
; #pragma unroll
;           for (int r = 0; r < 4; ++r) { const int h = (quad - 2) * 4 + r; const float xx = acc[i][1][r] * rs + p.b_forget[layer * 8 + h]; lf[h] = fminf(xx, 0.f) - log1pf(__expf(-fabsf(xx))); }
	v_add_f32_e32 v94, v94, v107
	v_add_f32_e32 v107, v102, v106
	v_fma_f32 v108, v106, v108, -v110
	v_sub_f32_e32 v102, v107, v102
	v_fmac_f32_e32 v108, v106, v95
	v_sub_f32_e32 v95, v106, v102
	v_add_f32_e32 v102, v110, v108
	v_sub_f32_e32 v106, v102, v110
	v_sub_f32_e32 v110, v105, v102
	v_sub_f32_e32 v105, v105, v110
	v_sub_f32_e32 v102, v105, v102
	v_sub_f32_e32 v106, v106, v108
	v_add_f32_e32 v94, v94, v102
	v_add_f32_e32 v94, v106, v94
	v_add_f32_e32 v94, v110, v94
	v_mul_f32_e32 v94, v103, v94
	v_add_f32_e32 v94, v95, v94
	v_add_f32_e32 v95, v107, v94
	v_mul_f32_e32 v102, v95, v95
	v_fmamk_f32 v106, v102, 0x3e9b6dac, v186
	v_sub_f32_e32 v103, v95, v107
	v_ldexp_f32 v105, v95, 1
	v_mul_f32_e32 v95, v95, v102
	v_fmaak_f32 v102, v102, v106, 0x3f2aaada
	v_mul_f32_e32 v95, v95, v102
	v_add_f32_e32 v102, v105, v95
	v_sub_f32_e32 v94, v94, v103
	v_sub_f32_e32 v103, v102, v105
	v_ldexp_f32 v94, v94, 1
	v_sub_f32_e32 v95, v95, v103
	v_add_f32_e32 v94, v94, v95
	v_add_f32_e32 v95, v102, v94
	v_sub_f32_e32 v102, v95, v102
	v_add_f32_e32 v103, v109, v95
	v_sub_f32_e32 v94, v94, v102
	v_sub_f32_e32 v102, v103, v109
	v_sub_f32_e32 v105, v103, v102
	v_sub_f32_e32 v95, v95, v102
	v_add_f32_e32 v102, v101, v94
	v_sub_f32_e32 v105, v109, v105
	v_sub_f32_e32 v106, v102, v101
	v_add_f32_e32 v95, v95, v105
	v_sub_f32_e32 v105, v102, v106
	v_sub_f32_e32 v94, v94, v106
	v_sub_f32_e32 v101, v101, v105
	v_add_f32_e32 v95, v102, v95
	v_add_f32_e32 v94, v94, v101
	v_add_f32_e32 v101, v103, v95
	v_sub_f32_e32 v102, v101, v103
	v_sub_f32_e32 v95, v95, v102
	v_add_f32_e32 v94, v94, v95
	v_add_f32_e32 v94, v101, v94
	v_cmp_neq_f32_e32 vcc, s67, v99
	s_nop 1
	v_cndmask_b32_e32 v94, v194, v94, vcc
	v_cmp_ngt_f32_e32 vcc, -1.0, v99
	s_nop 1
	v_cndmask_b32_e32 v94, v195, v94, vcc
	v_cmp_neq_f32_e32 vcc, -1.0, v99
	s_nop 1
	v_cndmask_b32_e32 v94, v196, v94, vcc
	v_cmp_lt_f32_e64 vcc, |v99|, s68
	s_nop 1
	v_cndmask_b32_e32 v94, v94, v99, vcc
	v_sub_f32_e32 v94, v100, v94
	global_store_dword v[92:93], v94, off offset:-24
	global_load_dword v94, v176, s[80:81] offset:-20
	s_waitcnt vmcnt(0)
	v_fmac_f32_e32 v94, v91, v98
	v_mul_f32_e64 v95, |v94|, s64
	v_exp_f32_e32 v99, v95
	v_min_f32_e32 v100, 0, v94
	v_add_f32_e32 v101, 1.0, v99
	v_add_f32_e32 v102, -1.0, v101
	v_frexp_mant_f32_e32 v103, v101
	v_cvt_f64_f32_e32 v[94:95], v101
	v_sub_f32_e32 v105, v102, v101
	v_frexp_exp_i32_f64_e32 v94, v[94:95]
	v_cmp_gt_f32_e32 vcc, s65, v103
	v_sub_f32_e32 v102, v99, v102
	v_add_f32_e32 v95, 1.0, v105
	v_subbrev_co_u32_e32 v94, vcc, 0, v94, vcc
	v_add_f32_e32 v95, v102, v95
	v_sub_u32_e32 v102, 0, v94
	v_cvt_f32_i32_e32 v94, v94
	v_ldexp_f32 v101, v101, v102
	v_ldexp_f32 v95, v95, v102
	v_add_f32_e32 v102, -1.0, v101
	v_add_f32_e32 v103, 1.0, v101
	v_add_f32_e32 v105, 1.0, v102
	v_add_f32_e32 v106, -1.0, v103
	v_sub_f32_e32 v105, v101, v105
	v_sub_f32_e32 v101, v101, v106
	v_mul_f32_e32 v106, 0x3f317218, v94
	v_add_f32_e32 v105, v95, v105
	v_add_f32_e32 v95, v95, v101
	v_fma_f32 v101, v94, s66, -v106
	v_add_f32_e32 v107, v102, v105
	v_add_f32_e32 v108, v103, v95
	v_fmac_f32_e32 v101, 0xb102e308, v94
	v_sub_f32_e32 v94, v107, v102
	v_sub_f32_e32 v102, v108, v103
	v_rcp_f32_e32 v103, v108
	v_add_f32_e32 v109, v106, v101
	v_sub_f32_e32 v95, v95, v102
	v_sub_f32_e32 v102, v109, v106
	v_sub_f32_e32 v101, v101, v102
	v_mul_f32_e32 v102, v107, v103
	v_sub_f32_e32 v94, v105, v94
	v_mul_f32_e32 v105, v108, v102
	v_fma_f32 v106, v102, v108, -v105
	v_fmac_f32_e32 v106, v102, v95
	v_add_f32_e32 v110, v105, v106
	v_sub_f32_e32 v111, v107, v110
	v_sub_f32_e32 v105, v110, v105
	v_sub_f32_e32 v107, v107, v111
	v_sub_f32_e32 v105, v105, v106
	v_sub_f32_e32 v106, v107, v110
	v_add_f32_e32 v94, v94, v106
	v_add_f32_e32 v94, v105, v94
	v_add_f32_e32 v105, v111, v94
	v_mul_f32_e32 v106, v103, v105
	v_sub_f32_e32 v107, v111, v105
	v_mul_f32_e32 v110, v108, v106
	v_add_f32_e32 v94, v94, v107
	v_add_f32_e32 v107, v102, v106
	v_fma_f32 v108, v106, v108, -v110
	v_sub_f32_e32 v102, v107, v102
	v_fmac_f32_e32 v108, v106, v95
	v_sub_f32_e32 v95, v106, v102
	v_add_f32_e32 v102, v110, v108
	v_sub_f32_e32 v106, v102, v110
	v_sub_f32_e32 v110, v105, v102
	v_sub_f32_e32 v105, v105, v110
	v_sub_f32_e32 v102, v105, v102
	v_sub_f32_e32 v106, v106, v108
	v_add_f32_e32 v94, v94, v102
	v_add_f32_e32 v94, v106, v94
	v_add_f32_e32 v94, v110, v94
	v_mul_f32_e32 v94, v103, v94
	v_add_f32_e32 v94, v95, v94
	v_add_f32_e32 v95, v107, v94
	v_mul_f32_e32 v102, v95, v95
	v_fmamk_f32 v106, v102, 0x3e9b6dac, v186
	v_sub_f32_e32 v103, v95, v107
	v_ldexp_f32 v105, v95, 1
	v_mul_f32_e32 v95, v95, v102
	v_fmaak_f32 v102, v102, v106, 0x3f2aaada
	v_mul_f32_e32 v95, v95, v102
	v_add_f32_e32 v102, v105, v95
	v_sub_f32_e32 v94, v94, v103
	v_sub_f32_e32 v103, v102, v105
	v_ldexp_f32 v94, v94, 1
	v_sub_f32_e32 v95, v95, v103
	v_add_f32_e32 v94, v94, v95
	v_add_f32_e32 v95, v102, v94
	v_sub_f32_e32 v102, v95, v102
	v_add_f32_e32 v103, v109, v95
	v_sub_f32_e32 v94, v94, v102
	v_sub_f32_e32 v102, v103, v109
	v_sub_f32_e32 v105, v103, v102
	v_sub_f32_e32 v95, v95, v102
	v_add_f32_e32 v102, v101, v94
	v_sub_f32_e32 v105, v109, v105
	v_sub_f32_e32 v106, v102, v101
	v_add_f32_e32 v95, v95, v105
	v_sub_f32_e32 v105, v102, v106
	v_sub_f32_e32 v94, v94, v106
	v_sub_f32_e32 v101, v101, v105
	v_add_f32_e32 v95, v102, v95
	v_add_f32_e32 v94, v94, v101
	v_add_f32_e32 v101, v103, v95
	v_sub_f32_e32 v102, v101, v103
	v_sub_f32_e32 v95, v95, v102
	v_add_f32_e32 v94, v94, v95
	v_add_f32_e32 v94, v101, v94
	v_cmp_neq_f32_e32 vcc, s67, v99
	s_nop 1
	v_cndmask_b32_e32 v94, v194, v94, vcc
	v_cmp_ngt_f32_e32 vcc, -1.0, v99
	s_nop 1
	v_cndmask_b32_e32 v94, v195, v94, vcc
	v_cmp_neq_f32_e32 vcc, -1.0, v99
	s_nop 1
	v_cndmask_b32_e32 v94, v196, v94, vcc
	v_cmp_lt_f32_e64 vcc, |v99|, s68
	s_nop 1
	v_cndmask_b32_e32 v94, v94, v99, vcc
	v_sub_f32_e32 v94, v100, v94
	global_store_dword v[92:93], v94, off offset:-20
; DI unsigned pk2(float lo, float hi) { f32x2 v = {lo, hi}; return __builtin_bit_cast(unsigned, __builtin_convertvector(v, bfx2)); }
; DI float sigmoidf_(float x) { return 1.f / (1.f + __expf(-x)); }
; DI float rstd_from16(const float* p, float inv_n) {
;   const f32x4 a = *(const f32x4*)p, b = *(const f32x4*)(p + 4), c = *(const f32x4*)(p + 8), d = *(const f32x4*)(p + 12);
;   const float s = ((a[0] + a[1]) + (a[2] + a[3])) + ((b[0] + b[1]) + (b[2] + b[3])) + ((c[0] + c[1]) + (c[2] + c[3])) + ((d[0] + d[1]) + (d[2] + d[3]));
;   return rsqrtf(s * inv_n + EPS_);
; template <bool SWAP> DI void inproj_tile(const Params& p, int layer, int tm, int tn, bf16_t* smem) {
;     ...
;         const int t = trow0 + i * 16 + l15; const float rs = rstd_from16(ssq + (size_t)t * 16, 1.f / 1024.f);
;         float* gt = (float*)(p.ws + O_GATES) + (size_t)t * 24; float* lf = (float*)(p.ws + O_LOGF) + (size_t)t * 8;
; #pragma unroll
;         for (int r = 0; r < 4; ++r) gt[quad * 4 + r] = sigmoidf_(acc[i][0][r] * rs);
;         if (quad < 2) {
; #pragma unroll
;           for (int r = 0; r < 4; ++r) gt[16 + quad * 4 + r] = sigmoidf_(acc[i][1][r] * rs);
;         } else {
; #pragma unroll
;           for (int r = 0; r < 4; ++r) { const int h = (quad - 2) * 4 + r; const float xx = acc[i][1][r] * rs + p.b_forget[layer * 8 + h]; lf[h] = fminf(xx, 0.f) - log1pf(__expf(-fabsf(xx))); }
;         }
;         const float* rp = (const float*)(p.ws + O_ROPE16) + (size_t)t * 32 + quad * 8; float o1[4], o2[4];
; #pragma unroll
;         for (int r = 0; r < 4; ++r) { const float cs = rp[2 * r], sn = rp[2 * r + 1], x1 = acc[i][2][r] * rs, x2 = acc[i][3][r] * rs; o1[r] = x1 * cs - x2 * sn; o2[r] = x2 * cs + x1 * sn; }
;         bf16_t* kp = (bf16_t*)(p.ws + O_MLAKPE) + (size_t)t * 32 + quad * 4;
;         *(u32x2*)kp = (u32x2){pk2(o1[0], o1[1]), pk2(o1[2], o1[3])}; *(u32x2*)(kp + 16) = (u32x2){pk2(o2[0], o2[1]), pk2(o2[2], o2[3])};
.LBB0_271:
	s_andn2_saveexec_b64 s[0:1], s[0:1]
	s_cbranch_execz .LBB0_273
	v_mul_f32_e32 v88, v88, v98
	v_mul_f32_e32 v89, v89, v98
	v_mul_f32_e32 v88, 0xbfb8aa3b, v88
	v_mul_f32_e32 v89, 0xbfb8aa3b, v89
	v_exp_f32_e32 v88, v88
	v_exp_f32_e32 v89, v89
	v_mul_f32_e32 v90, v90, v98
	v_mul_f32_e32 v91, v91, v98
	v_mul_f32_e32 v90, 0xbfb8aa3b, v90
	v_pk_add_f32 v[88:89], v[88:89], 1.0 op_sel_hi:[1,0]
	v_mul_f32_e32 v91, 0xbfb8aa3b, v91
	v_exp_f32_e32 v90, v90
	v_rcp_f32_e32 v89, v89
	v_exp_f32_e32 v91, v91
	s_nop 0
	v_pk_add_f32 v[90:91], v[90:91], 1.0 op_sel_hi:[1,0]
	v_rcp_f32_e32 v88, v88
	v_rcp_f32_e32 v91, v91
	v_rcp_f32_e32 v90, v90
	global_store_dwordx4 v[100:101], v[88:91], off offset:64
.LBB0_273:
	s_or_b64 exec, exec, s[0:1]
	s_nop 0
	v_lshl_add_u64 v[88:89], v[96:97], 2, s[14:15]
	v_mov_b32_e32 v105, v177
	v_lshl_add_u64 v[92:93], v[88:89], 0, v[104:105]
	global_load_dwordx4 v[88:91], v[92:93], off
	s_nop 0
	global_load_dwordx4 v[92:95], v[92:93], off offset:16
	v_or_b32_e32 v110, 48, v128
	v_ashrrev_i32_e32 v111, 31, v110
	v_lshlrev_b64 v[100:101], 6, v[110:111]
	v_lshl_add_u64 v[118:119], s[8:9], 0, v[100:101]
	global_load_dwordx4 v[100:103], v[118:119], off
	global_load_dwordx4 v[106:109], v[118:119], off offset:16
	global_load_dwordx4 v[114:117], v[118:119], off offset:32
	s_nop 0
	global_load_dwordx4 v[118:121], v[118:119], off offset:48
	v_pk_mul_f32 v[122:123], v[80:81], v[98:99] op_sel_hi:[1,0]
	v_pk_mul_f32 v[124:125], v[84:85], v[98:99] op_sel_hi:[1,0]
	v_pk_mul_f32 v[82:83], v[82:83], v[98:99] op_sel_hi:[1,0]
	v_pk_mul_f32 v[86:87], v[86:87], v[98:99] op_sel_hi:[1,0]
	v_lshl_add_u64 v[80:81], v[96:97], 1, s[16:17]
	v_mov_b32_e32 v113, v177
	v_mov_b64_e32 v[84:85], s[10:11]
	v_lshl_add_u64 v[96:97], v[80:81], 0, v[112:113]
	v_mad_i64_i32 v[84:85], s[0:1], v110, s63, v[84:85]
	v_lshlrev_b64 v[80:81], 5, v[110:111]
	v_lshl_add_u64 v[84:85], v[84:85], 0, v[176:177]
	s_waitcnt vmcnt(5)
	v_mov_b32_e32 v99, v90
	v_mov_b32_e32 v90, v89
	s_waitcnt vmcnt(4)
	v_mov_b32_e32 v89, v94
	v_mov_b32_e32 v94, v93
	v_mov_b32_e32 v98, v88
	v_mov_b32_e32 v88, v92
	v_pk_mul_f32 v[110:111], v[82:83], v[94:95]
	v_pk_mul_f32 v[94:95], v[86:87], v[94:95]
	v_pk_fma_f32 v[86:87], v[86:87], v[88:89], v[110:111] neg_lo:[0,0,1] neg_hi:[0,0,1]
	v_pk_fma_f32 v[82:83], v[82:83], v[88:89], v[94:95]
	s_waitcnt vmcnt(3)
	v_mov_b32_e32 v88, v101
	v_mov_b32_e32 v89, v102
	v_mov_b32_e32 v101, v103
	s_waitcnt vmcnt(2)
	v_mov_b32_e32 v94, v107
	v_mov_b32_e32 v95, v108
	v_mov_b32_e32 v107, v109
	v_pk_add_f32 v[88:89], v[88:89], v[100:101]
	v_pk_add_f32 v[94:95], v[94:95], v[106:107]
	v_pk_mul_f32 v[92:93], v[122:123], v[90:91]
	v_pk_mul_f32 v[90:91], v[124:125], v[90:91]
	v_pk_add_f32 v[88:89], v[88:89], v[88:89] op_sel:[0,1] op_sel_hi:[1,0]
	v_pk_add_f32 v[94:95], v[94:95], v[94:95] op_sel:[0,1] op_sel_hi:[1,0]
	v_pk_fma_f32 v[92:93], v[124:125], v[98:99], v[92:93] neg_lo:[0,0,1] neg_hi:[0,0,1]
	v_pk_fma_f32 v[90:91], v[122:123], v[98:99], v[90:91]
	s_waitcnt vmcnt(1)
	v_add_f32_e32 v98, v114, v115
	v_add_f32_e32 v102, v116, v117
	s_waitcnt vmcnt(0)
	v_mov_b32_e32 v99, v120
	v_mov_b32_e32 v103, v121
	v_mov_b32_e32 v89, v118
	v_mov_b32_e32 v95, v119
	v_pk_add_f32 v[98:99], v[98:99], v[102:103]
	v_pk_add_f32 v[88:89], v[88:89], v[94:95]
	v_cvt_pk_bf16_f32 v92, v92, v93
	v_pk_add_f32 v[88:89], v[88:89], v[98:99]
	v_cvt_pk_bf16_f32 v93, v86, v87
	v_add_f32_e32 v88, v88, v89
	v_fmamk_f32 v88, v88, 0x3a800000, v185
	v_mul_f32_e32 v89, 0x4b800000, v88
	v_cmp_gt_f32_e32 vcc, s60, v88
	v_cvt_pk_bf16_f32 v87, v82, v83
	v_cvt_pk_bf16_f32 v86, v90, v91
	v_cndmask_b32_e32 v88, v88, v89, vcc
	v_rsq_f32_e32 v88, v88
	global_store_dwordx2 v[96:97], v[92:93], off
	global_store_dwordx2 v[96:97], v[86:87], off offset:32
	v_mul_f32_e32 v82, 0x45800000, v88
	v_cndmask_b32_e32 v82, v88, v82, vcc
	v_mul_f32_e32 v76, v76, v82
	v_mul_f32_e32 v77, v77, v82
	v_mul_f32_e32 v76, 0xbfb8aa3b, v76
	v_mul_f32_e32 v77, 0xbfb8aa3b, v77
	v_mul_f32_e32 v78, v78, v82
	v_mul_f32_e32 v79, v79, v82
	v_exp_f32_e32 v76, v76
	v_exp_f32_e32 v77, v77
	v_mul_f32_e32 v78, 0xbfb8aa3b, v78
	v_mul_f32_e32 v79, 0xbfb8aa3b, v79
	v_exp_f32_e32 v78, v78
	v_exp_f32_e32 v79, v79
	v_pk_add_f32 v[76:77], v[76:77], 1.0 op_sel_hi:[1,0]
	v_pk_add_f32 v[78:79], v[78:79], 1.0 op_sel_hi:[1,0]
	v_div_scale_f32 v87, s[0:1], v76, v76, 1.0
	v_div_scale_f32 v89, s[4:5], v79, v79, 1.0
	v_rcp_f32_e32 v91, v87
	v_rcp_f32_e32 v92, v89
	v_fma_f32 v95, -v87, v91, 1.0
	v_div_scale_f32 v88, s[0:1], 1.0, v76, 1.0
	v_fma_f32 v96, -v89, v92, 1.0
	v_fmac_f32_e32 v91, v95, v91
	v_fmac_f32_e32 v92, v96, v92
	v_mul_f32_e32 v95, v88, v91
	v_fma_f32 v97, -v87, v95, v88
	v_fmac_f32_e32 v95, v97, v91
	v_fma_f32 v86, -v87, v95, v88
	s_mov_b64 vcc, s[0:1]
	v_div_scale_f32 v93, s[4:5], 1.0, v79, 1.0
	v_rcp_f32_e32 v77, v77
	v_div_fmas_f32 v83, v86, v91, v95
	v_div_fixup_f32 v76, v83, v76, 1.0
	v_mul_f32_e32 v83, v93, v92
	v_fma_f32 v86, -v89, v83, v93
	v_fmac_f32_e32 v83, v86, v92
	v_fma_f32 v86, -v89, v83, v93
	s_mov_b64 vcc, s[4:5]
	v_div_fmas_f32 v83, v86, v92, v83
	v_div_fixup_f32 v79, v83, v79, 1.0
	v_rcp_f32_e32 v78, v78
	global_store_dwordx4 v[84:85], v[76:79], off
	s_and_saveexec_b64 s[0:1], s[2:3]
	s_xor_b64 s[0:1], exec, s[0:1]
	s_cbranch_execz .LBB0_275
; template <bool SWAP> DI void inproj_tile(const Params& p, int layer, int tm, int tn, bf16_t* smem) {
;     ...
; #pragma unroll
;           for (int r = 0; r < 4; ++r) { const int h = (quad - 2) * 4 + r; const float xx = acc[i][1][r] * rs + p.b_forget[layer * 8 + h]; lf[h] = fminf(xx, 0.f) - log1pf(__expf(-fabsf(xx))); }
	v_readlane_b32 s72, v241, 8
	v_readlane_b32 s80, v241, 16
	v_readlane_b32 s81, v241, 17
	v_readlane_b32 s73, v241, 9
	v_readlane_b32 s74, v241, 10
	v_readlane_b32 s75, v241, 11
	v_readlane_b32 s76, v241, 12
	v_readlane_b32 s77, v241, 13
	global_load_dword v78, v176, s[80:81] offset:-32
	v_readlane_b32 s78, v241, 14
	v_readlane_b32 s79, v241, 15
	v_readlane_b32 s82, v241, 18
	v_readlane_b32 s83, v241, 19
	v_readlane_b32 s84, v241, 20
	v_readlane_b32 s85, v241, 21
	v_readlane_b32 s86, v241, 22
	v_readlane_b32 s87, v241, 23
	s_waitcnt vmcnt(0)
	v_fmac_f32_e32 v78, v72, v82
	v_mul_f32_e64 v76, |v78|, s64
	v_exp_f32_e32 v83, v76
	v_min_f32_e32 v84, 0, v78
	v_lshl_add_u64 v[76:77], s[12:13], 0, v[80:81]
	v_lshl_add_u64 v[76:77], v[76:77], 0, v[176:177]
	v_add_f32_e32 v85, 1.0, v83
	v_add_f32_e32 v86, -1.0, v85
	v_frexp_mant_f32_e32 v87, v85
	v_cvt_f64_f32_e32 v[78:79], v85
	v_sub_f32_e32 v88, v86, v85
	v_frexp_exp_i32_f64_e32 v78, v[78:79]
	v_cmp_gt_f32_e32 vcc, s65, v87
	v_sub_f32_e32 v86, v83, v86
	v_add_f32_e32 v79, 1.0, v88
	v_subbrev_co_u32_e32 v78, vcc, 0, v78, vcc
	v_add_f32_e32 v79, v86, v79
	v_sub_u32_e32 v86, 0, v78
	v_cvt_f32_i32_e32 v78, v78
	v_ldexp_f32 v85, v85, v86
	v_ldexp_f32 v79, v79, v86
	v_add_f32_e32 v86, -1.0, v85
	v_add_f32_e32 v87, 1.0, v85
	v_add_f32_e32 v88, 1.0, v86
	v_add_f32_e32 v89, -1.0, v87
	v_sub_f32_e32 v88, v85, v88
	v_sub_f32_e32 v85, v85, v89
	v_mul_f32_e32 v89, 0x3f317218, v78
	v_add_f32_e32 v88, v79, v88
	v_add_f32_e32 v79, v79, v85
	v_fma_f32 v85, v78, s66, -v89
	v_add_f32_e32 v90, v86, v88
	v_add_f32_e32 v91, v87, v79
	v_fmac_f32_e32 v85, 0xb102e308, v78
	v_sub_f32_e32 v78, v90, v86
	v_sub_f32_e32 v86, v91, v87
	v_rcp_f32_e32 v87, v91
	v_add_f32_e32 v92, v89, v85
	v_sub_f32_e32 v79, v79, v86
	v_sub_f32_e32 v86, v92, v89
	v_sub_f32_e32 v85, v85, v86
	v_mul_f32_e32 v86, v90, v87
	v_sub_f32_e32 v78, v88, v78
	v_mul_f32_e32 v88, v91, v86
	v_fma_f32 v89, v86, v91, -v88
	v_fmac_f32_e32 v89, v86, v79
	v_add_f32_e32 v93, v88, v89
	v_sub_f32_e32 v94, v90, v93
	v_sub_f32_e32 v88, v93, v88
	v_sub_f32_e32 v90, v90, v94
	v_sub_f32_e32 v88, v88, v89
	v_sub_f32_e32 v89, v90, v93
	v_add_f32_e32 v78, v78, v89
	v_add_f32_e32 v78, v88, v78
	v_add_f32_e32 v88, v94, v78
	v_mul_f32_e32 v89, v87, v88
	v_sub_f32_e32 v90, v94, v88
	v_mul_f32_e32 v93, v91, v89
	v_add_f32_e32 v78, v78, v90
	v_add_f32_e32 v90, v86, v89
	v_fma_f32 v91, v89, v91, -v93
	v_sub_f32_e32 v86, v90, v86
	v_fmac_f32_e32 v91, v89, v79
	v_sub_f32_e32 v79, v89, v86
	v_add_f32_e32 v86, v93, v91
	v_sub_f32_e32 v89, v86, v93
	v_sub_f32_e32 v93, v88, v86
	v_sub_f32_e32 v88, v88, v93
	v_sub_f32_e32 v86, v88, v86
	v_sub_f32_e32 v89, v89, v91
	v_add_f32_e32 v78, v78, v86
	v_add_f32_e32 v78, v89, v78
	v_add_f32_e32 v78, v93, v78
	v_mul_f32_e32 v78, v87, v78
	v_add_f32_e32 v78, v79, v78
	v_add_f32_e32 v79, v90, v78
	v_mul_f32_e32 v86, v79, v79
	v_fmamk_f32 v89, v86, 0x3e9b6dac, v186
	v_sub_f32_e32 v87, v79, v90
	v_ldexp_f32 v88, v79, 1
	v_mul_f32_e32 v79, v79, v86
	v_fmaak_f32 v86, v86, v89, 0x3f2aaada
	v_mul_f32_e32 v79, v79, v86
	v_add_f32_e32 v86, v88, v79
	v_sub_f32_e32 v78, v78, v87
	v_sub_f32_e32 v87, v86, v88
	v_ldexp_f32 v78, v78, 1
	v_sub_f32_e32 v79, v79, v87
	v_add_f32_e32 v78, v78, v79
	v_add_f32_e32 v79, v86, v78
	v_sub_f32_e32 v86, v79, v86
	v_add_f32_e32 v87, v92, v79
	v_sub_f32_e32 v78, v78, v86
	v_sub_f32_e32 v86, v87, v92
	v_sub_f32_e32 v88, v87, v86
	v_sub_f32_e32 v79, v79, v86
	v_add_f32_e32 v86, v85, v78
	v_sub_f32_e32 v88, v92, v88
	v_sub_f32_e32 v89, v86, v85
	v_add_f32_e32 v79, v79, v88
	v_sub_f32_e32 v88, v86, v89
	v_sub_f32_e32 v78, v78, v89
	v_sub_f32_e32 v85, v85, v88
	v_add_f32_e32 v79, v86, v79
	v_add_f32_e32 v78, v78, v85
	v_add_f32_e32 v85, v87, v79
	v_sub_f32_e32 v86, v85, v87
	v_sub_f32_e32 v79, v79, v86
	v_add_f32_e32 v78, v78, v79
	v_add_f32_e32 v78, v85, v78
	v_cmp_neq_f32_e32 vcc, s67, v83
	s_nop 1
	v_cndmask_b32_e32 v78, v194, v78, vcc
	v_cmp_ngt_f32_e32 vcc, -1.0, v83
	s_nop 1
	v_cndmask_b32_e32 v78, v195, v78, vcc
	v_cmp_neq_f32_e32 vcc, -1.0, v83
	s_nop 1
	v_cndmask_b32_e32 v78, v196, v78, vcc
	v_cmp_lt_f32_e64 vcc, |v83|, s68
	s_nop 1
	v_cndmask_b32_e32 v78, v78, v83, vcc
	v_sub_f32_e32 v78, v84, v78
	global_store_dword v[76:77], v78, off offset:-32
	global_load_dword v78, v176, s[80:81] offset:-28
	s_waitcnt vmcnt(0)
; template <bool SWAP> DI void inproj_tile(const Params& p, int layer, int tm, int tn, bf16_t* smem) {
;     ...
; #pragma unroll
;           for (int r = 0; r < 4; ++r) { const int h = (quad - 2) * 4 + r; const float xx = acc[i][1][r] * rs + p.b_forget[layer * 8 + h]; lf[h] = fminf(xx, 0.f) - log1pf(__expf(-fabsf(xx))); }
	v_fmac_f32_e32 v78, v73, v82
	v_mul_f32_e64 v79, |v78|, s64
	v_exp_f32_e32 v83, v79
	v_min_f32_e32 v84, 0, v78
	v_add_f32_e32 v85, 1.0, v83
	v_add_f32_e32 v86, -1.0, v85
	v_frexp_mant_f32_e32 v87, v85
	v_cvt_f64_f32_e32 v[78:79], v85
	v_sub_f32_e32 v88, v86, v85
	v_frexp_exp_i32_f64_e32 v78, v[78:79]
	v_cmp_gt_f32_e32 vcc, s65, v87
	v_sub_f32_e32 v86, v83, v86
	v_add_f32_e32 v79, 1.0, v88
	v_subbrev_co_u32_e32 v78, vcc, 0, v78, vcc
	v_add_f32_e32 v79, v86, v79
	v_sub_u32_e32 v86, 0, v78
	v_cvt_f32_i32_e32 v78, v78
	v_ldexp_f32 v85, v85, v86
	v_ldexp_f32 v79, v79, v86
	v_add_f32_e32 v86, -1.0, v85
	v_add_f32_e32 v87, 1.0, v85
	v_add_f32_e32 v88, 1.0, v86
	v_add_f32_e32 v89, -1.0, v87
	v_sub_f32_e32 v88, v85, v88
	v_sub_f32_e32 v85, v85, v89
	v_mul_f32_e32 v89, 0x3f317218, v78
	v_add_f32_e32 v88, v79, v88
	v_add_f32_e32 v79, v79, v85
	v_fma_f32 v85, v78, s66, -v89
	v_add_f32_e32 v90, v86, v88
	v_add_f32_e32 v91, v87, v79
	v_fmac_f32_e32 v85, 0xb102e308, v78
	v_sub_f32_e32 v78, v90, v86
	v_sub_f32_e32 v86, v91, v87
	v_rcp_f32_e32 v87, v91
	v_add_f32_e32 v92, v89, v85
	v_sub_f32_e32 v79, v79, v86
	v_sub_f32_e32 v86, v92, v89
	v_sub_f32_e32 v85, v85, v86
	v_mul_f32_e32 v86, v90, v87
	v_sub_f32_e32 v78, v88, v78
	v_mul_f32_e32 v88, v91, v86
	v_fma_f32 v89, v86, v91, -v88
	v_fmac_f32_e32 v89, v86, v79
	v_add_f32_e32 v93, v88, v89
	v_sub_f32_e32 v94, v90, v93
	v_sub_f32_e32 v88, v93, v88
	v_sub_f32_e32 v90, v90, v94
	v_sub_f32_e32 v88, v88, v89
	v_sub_f32_e32 v89, v90, v93
	v_add_f32_e32 v78, v78, v89
	v_add_f32_e32 v78, v88, v78
	v_add_f32_e32 v88, v94, v78
	v_mul_f32_e32 v89, v87, v88
	v_sub_f32_e32 v90, v94, v88
	v_mul_f32_e32 v93, v91, v89
	v_add_f32_e32 v78, v78, v90
	v_add_f32_e32 v90, v86, v89
	v_fma_f32 v91, v89, v91, -v93
	v_sub_f32_e32 v86, v90, v86
	v_fmac_f32_e32 v91, v89, v79
	v_sub_f32_e32 v79, v89, v86
	v_add_f32_e32 v86, v93, v91
	v_sub_f32_e32 v89, v86, v93
	v_sub_f32_e32 v93, v88, v86
	v_sub_f32_e32 v88, v88, v93
	v_sub_f32_e32 v86, v88, v86
	v_sub_f32_e32 v89, v89, v91
	v_add_f32_e32 v78, v78, v86
	v_add_f32_e32 v78, v89, v78
	v_add_f32_e32 v78, v93, v78
	v_mul_f32_e32 v78, v87, v78
	v_add_f32_e32 v78, v79, v78
	v_add_f32_e32 v79, v90, v78
	v_mul_f32_e32 v86, v79, v79
	v_fmamk_f32 v89, v86, 0x3e9b6dac, v186
	v_sub_f32_e32 v87, v79, v90
	v_ldexp_f32 v88, v79, 1
	v_mul_f32_e32 v79, v79, v86
	v_fmaak_f32 v86, v86, v89, 0x3f2aaada
	v_mul_f32_e32 v79, v79, v86
	v_add_f32_e32 v86, v88, v79
	v_sub_f32_e32 v78, v78, v87
	v_sub_f32_e32 v87, v86, v88
	v_ldexp_f32 v78, v78, 1
	v_sub_f32_e32 v79, v79, v87
	v_add_f32_e32 v78, v78, v79
	v_add_f32_e32 v79, v86, v78
	v_sub_f32_e32 v86, v79, v86
	v_add_f32_e32 v87, v92, v79
	v_sub_f32_e32 v78, v78, v86
	v_sub_f32_e32 v86, v87, v92
	v_sub_f32_e32 v88, v87, v86
	v_sub_f32_e32 v79, v79, v86
	v_add_f32_e32 v86, v85, v78
	v_sub_f32_e32 v88, v92, v88
	v_sub_f32_e32 v89, v86, v85
	v_add_f32_e32 v79, v79, v88
	v_sub_f32_e32 v88, v86, v89
	v_sub_f32_e32 v78, v78, v89
	v_sub_f32_e32 v85, v85, v88
	v_add_f32_e32 v79, v86, v79
	v_add_f32_e32 v78, v78, v85
	v_add_f32_e32 v85, v87, v79
	v_sub_f32_e32 v86, v85, v87
	v_sub_f32_e32 v79, v79, v86
	v_add_f32_e32 v78, v78, v79
	v_add_f32_e32 v78, v85, v78
	v_cmp_neq_f32_e32 vcc, s67, v83
	s_nop 1
	v_cndmask_b32_e32 v78, v194, v78, vcc
	v_cmp_ngt_f32_e32 vcc, -1.0, v83
	s_nop 1
	v_cndmask_b32_e32 v78, v195, v78, vcc
	v_cmp_neq_f32_e32 vcc, -1.0, v83
	s_nop 1
	v_cndmask_b32_e32 v78, v196, v78, vcc
	v_cmp_lt_f32_e64 vcc, |v83|, s68
	s_nop 1
	v_cndmask_b32_e32 v78, v78, v83, vcc
	v_sub_f32_e32 v78, v84, v78
	global_store_dword v[76:77], v78, off offset:-28
	global_load_dword v78, v176, s[80:81] offset:-24
	s_waitcnt vmcnt(0)
	v_fmac_f32_e32 v78, v74, v82
	v_mul_f32_e64 v79, |v78|, s64
	v_exp_f32_e32 v83, v79
	v_min_f32_e32 v84, 0, v78
	v_add_f32_e32 v85, 1.0, v83
	v_add_f32_e32 v86, -1.0, v85
	v_frexp_mant_f32_e32 v87, v85
	v_cvt_f64_f32_e32 v[78:79], v85
	v_sub_f32_e32 v88, v86, v85
	v_frexp_exp_i32_f64_e32 v78, v[78:79]
	v_cmp_gt_f32_e32 vcc, s65, v87
	v_sub_f32_e32 v86, v83, v86
	v_add_f32_e32 v79, 1.0, v88
	v_subbrev_co_u32_e32 v78, vcc, 0, v78, vcc
	v_add_f32_e32 v79, v86, v79
	v_sub_u32_e32 v86, 0, v78
	v_cvt_f32_i32_e32 v78, v78
	v_ldexp_f32 v85, v85, v86
	v_ldexp_f32 v79, v79, v86
	v_add_f32_e32 v86, -1.0, v85
	v_add_f32_e32 v87, 1.0, v85
	v_add_f32_e32 v88, 1.0, v86
	v_add_f32_e32 v89, -1.0, v87
	v_sub_f32_e32 v88, v85, v88
	v_sub_f32_e32 v85, v85, v89
	v_mul_f32_e32 v89, 0x3f317218, v78
	v_add_f32_e32 v88, v79, v88
	v_add_f32_e32 v79, v79, v85
	v_fma_f32 v85, v78, s66, -v89
	v_add_f32_e32 v90, v86, v88
	v_add_f32_e32 v91, v87, v79
	v_fmac_f32_e32 v85, 0xb102e308, v78
	v_sub_f32_e32 v78, v90, v86
	v_sub_f32_e32 v86, v91, v87
	v_rcp_f32_e32 v87, v91
	v_add_f32_e32 v92, v89, v85
	v_sub_f32_e32 v79, v79, v86
	v_sub_f32_e32 v86, v92, v89
	v_sub_f32_e32 v85, v85, v86
	v_mul_f32_e32 v86, v90, v87
	v_sub_f32_e32 v78, v88, v78
	v_mul_f32_e32 v88, v91, v86
	v_fma_f32 v89, v86, v91, -v88
	v_fmac_f32_e32 v89, v86, v79
	v_add_f32_e32 v93, v88, v89
	v_sub_f32_e32 v94, v90, v93
	v_sub_f32_e32 v88, v93, v88
	v_sub_f32_e32 v90, v90, v94
	v_sub_f32_e32 v88, v88, v89
	v_sub_f32_e32 v89, v90, v93
	v_add_f32_e32 v78, v78, v89
	v_add_f32_e32 v78, v88, v78
	v_add_f32_e32 v88, v94, v78
	v_mul_f32_e32 v89, v87, v88
	v_sub_f32_e32 v90, v94, v88
	v_mul_f32_e32 v93, v91, v89
	v_add_f32_e32 v78, v78, v90
	v_add_f32_e32 v90, v86, v89
	v_fma_f32 v91, v89, v91, -v93
	v_sub_f32_e32 v86, v90, v86
	v_fmac_f32_e32 v91, v89, v79
	v_sub_f32_e32 v79, v89, v86
	v_add_f32_e32 v86, v93, v91
	v_sub_f32_e32 v89, v86, v93
	v_sub_f32_e32 v93, v88, v86
	v_sub_f32_e32 v88, v88, v93
	v_sub_f32_e32 v86, v88, v86
; DI float sigmoidf_(float x) { return 1.f / (1.f + __expf(-x)); }
; template <bool SWAP> DI void inproj_tile(const Params& p, int layer, int tm, int tn, bf16_t* smem) {
;     ...
;         if (quad < 2) {
; #pragma unroll
;           for (int r = 0; r < 4; ++r) gt[16 + quad * 4 + r] = sigmoidf_(acc[i][1][r] * rs);
;         } else {
; #pragma unroll
;           for (int r = 0; r < 4; ++r) { const int h = (quad - 2) * 4 + r; const float xx = acc[i][1][r] * rs + p.b_forget[layer * 8 + h]; lf[h] = fminf(xx, 0.f) - log1pf(__expf(-fabsf(xx))); }
	v_sub_f32_e32 v89, v89, v91
	v_add_f32_e32 v78, v78, v86
	v_add_f32_e32 v78, v89, v78
	v_add_f32_e32 v78, v93, v78
	v_mul_f32_e32 v78, v87, v78
	v_add_f32_e32 v78, v79, v78
	v_add_f32_e32 v79, v90, v78
	v_mul_f32_e32 v86, v79, v79
	v_fmamk_f32 v89, v86, 0x3e9b6dac, v186
	v_sub_f32_e32 v87, v79, v90
	v_ldexp_f32 v88, v79, 1
	v_mul_f32_e32 v79, v79, v86
	v_fmaak_f32 v86, v86, v89, 0x3f2aaada
	v_mul_f32_e32 v79, v79, v86
	v_add_f32_e32 v86, v88, v79
	v_sub_f32_e32 v78, v78, v87
	v_sub_f32_e32 v87, v86, v88
	v_ldexp_f32 v78, v78, 1
	v_sub_f32_e32 v79, v79, v87
	v_add_f32_e32 v78, v78, v79
	v_add_f32_e32 v79, v86, v78
	v_sub_f32_e32 v86, v79, v86
	v_add_f32_e32 v87, v92, v79
	v_sub_f32_e32 v78, v78, v86
	v_sub_f32_e32 v86, v87, v92
	v_sub_f32_e32 v88, v87, v86
	v_sub_f32_e32 v79, v79, v86
	v_add_f32_e32 v86, v85, v78
	v_sub_f32_e32 v88, v92, v88
	v_sub_f32_e32 v89, v86, v85
	v_add_f32_e32 v79, v79, v88
	v_sub_f32_e32 v88, v86, v89
	v_sub_f32_e32 v78, v78, v89
	v_sub_f32_e32 v85, v85, v88
	v_add_f32_e32 v79, v86, v79
	v_add_f32_e32 v78, v78, v85
	v_add_f32_e32 v85, v87, v79
	v_sub_f32_e32 v86, v85, v87
	v_sub_f32_e32 v79, v79, v86
	v_add_f32_e32 v78, v78, v79
	v_add_f32_e32 v78, v85, v78
	v_cmp_neq_f32_e32 vcc, s67, v83
	s_nop 1
	v_cndmask_b32_e32 v78, v194, v78, vcc
	v_cmp_ngt_f32_e32 vcc, -1.0, v83
	s_nop 1
	v_cndmask_b32_e32 v78, v195, v78, vcc
	v_cmp_neq_f32_e32 vcc, -1.0, v83
	s_nop 1
	v_cndmask_b32_e32 v78, v196, v78, vcc
	v_cmp_lt_f32_e64 vcc, |v83|, s68
	s_nop 1
	v_cndmask_b32_e32 v78, v78, v83, vcc
	v_sub_f32_e32 v78, v84, v78
	global_store_dword v[76:77], v78, off offset:-24
	global_load_dword v78, v176, s[80:81] offset:-20
	s_waitcnt vmcnt(0)
	v_fmac_f32_e32 v78, v75, v82
	v_mul_f32_e64 v79, |v78|, s64
	v_exp_f32_e32 v83, v79
	v_min_f32_e32 v84, 0, v78
	v_add_f32_e32 v85, 1.0, v83
	v_add_f32_e32 v86, -1.0, v85
	v_frexp_mant_f32_e32 v87, v85
	v_cvt_f64_f32_e32 v[78:79], v85
	v_sub_f32_e32 v88, v86, v85
	v_frexp_exp_i32_f64_e32 v78, v[78:79]
	v_cmp_gt_f32_e32 vcc, s65, v87
	v_sub_f32_e32 v86, v83, v86
	v_add_f32_e32 v79, 1.0, v88
	v_subbrev_co_u32_e32 v78, vcc, 0, v78, vcc
	v_add_f32_e32 v79, v86, v79
	v_sub_u32_e32 v86, 0, v78
	v_cvt_f32_i32_e32 v78, v78
	v_ldexp_f32 v85, v85, v86
	v_ldexp_f32 v79, v79, v86
	v_add_f32_e32 v86, -1.0, v85
	v_add_f32_e32 v87, 1.0, v85
	v_add_f32_e32 v88, 1.0, v86
	v_add_f32_e32 v89, -1.0, v87
	v_sub_f32_e32 v88, v85, v88
	v_sub_f32_e32 v85, v85, v89
	v_mul_f32_e32 v89, 0x3f317218, v78
	v_add_f32_e32 v88, v79, v88
	v_add_f32_e32 v79, v79, v85
	v_fma_f32 v85, v78, s66, -v89
	v_add_f32_e32 v90, v86, v88
	v_add_f32_e32 v91, v87, v79
	v_fmac_f32_e32 v85, 0xb102e308, v78
	v_sub_f32_e32 v78, v90, v86
	v_sub_f32_e32 v86, v91, v87
	v_rcp_f32_e32 v87, v91
	v_add_f32_e32 v92, v89, v85
	v_sub_f32_e32 v79, v79, v86
	v_sub_f32_e32 v86, v92, v89
	v_sub_f32_e32 v85, v85, v86
	v_mul_f32_e32 v86, v90, v87
	v_sub_f32_e32 v78, v88, v78
	v_mul_f32_e32 v88, v91, v86
	v_fma_f32 v89, v86, v91, -v88
	v_fmac_f32_e32 v89, v86, v79
	v_add_f32_e32 v93, v88, v89
	v_sub_f32_e32 v94, v90, v93
	v_sub_f32_e32 v88, v93, v88
	v_sub_f32_e32 v90, v90, v94
	v_sub_f32_e32 v88, v88, v89
	v_sub_f32_e32 v89, v90, v93
	v_add_f32_e32 v78, v78, v89
	v_add_f32_e32 v78, v88, v78
	v_add_f32_e32 v88, v94, v78
	v_mul_f32_e32 v89, v87, v88
	v_sub_f32_e32 v90, v94, v88
	v_mul_f32_e32 v93, v91, v89
	v_add_f32_e32 v78, v78, v90
	v_add_f32_e32 v90, v86, v89
	v_fma_f32 v91, v89, v91, -v93
	v_sub_f32_e32 v86, v90, v86
	v_fmac_f32_e32 v91, v89, v79
	v_sub_f32_e32 v79, v89, v86
	v_add_f32_e32 v86, v93, v91
	v_sub_f32_e32 v89, v86, v93
	v_sub_f32_e32 v93, v88, v86
	v_sub_f32_e32 v88, v88, v93
	v_sub_f32_e32 v86, v88, v86
	v_sub_f32_e32 v89, v89, v91
	v_add_f32_e32 v78, v78, v86
	v_add_f32_e32 v78, v89, v78
	v_add_f32_e32 v78, v93, v78
	v_mul_f32_e32 v78, v87, v78
	v_add_f32_e32 v78, v79, v78
	v_add_f32_e32 v79, v90, v78
	v_mul_f32_e32 v86, v79, v79
	v_fmamk_f32 v89, v86, 0x3e9b6dac, v186
	v_sub_f32_e32 v87, v79, v90
	v_ldexp_f32 v88, v79, 1
	v_mul_f32_e32 v79, v79, v86
	v_fmaak_f32 v86, v86, v89, 0x3f2aaada
	v_mul_f32_e32 v79, v79, v86
	v_add_f32_e32 v86, v88, v79
	v_sub_f32_e32 v78, v78, v87
	v_sub_f32_e32 v87, v86, v88
	v_ldexp_f32 v78, v78, 1
	v_sub_f32_e32 v79, v79, v87
	v_add_f32_e32 v78, v78, v79
	v_add_f32_e32 v79, v86, v78
	v_sub_f32_e32 v86, v79, v86
	v_add_f32_e32 v87, v92, v79
	v_sub_f32_e32 v78, v78, v86
	v_sub_f32_e32 v86, v87, v92
	v_sub_f32_e32 v88, v87, v86
	v_sub_f32_e32 v79, v79, v86
	v_add_f32_e32 v86, v85, v78
	v_sub_f32_e32 v88, v92, v88
	v_sub_f32_e32 v89, v86, v85
	v_add_f32_e32 v79, v79, v88
	v_sub_f32_e32 v88, v86, v89
	v_sub_f32_e32 v78, v78, v89
	v_sub_f32_e32 v85, v85, v88
	v_add_f32_e32 v79, v86, v79
	v_add_f32_e32 v78, v78, v85
	v_add_f32_e32 v85, v87, v79
	v_sub_f32_e32 v86, v85, v87
	v_sub_f32_e32 v79, v79, v86
	v_add_f32_e32 v78, v78, v79
	v_add_f32_e32 v78, v85, v78
	v_cmp_neq_f32_e32 vcc, s67, v83
	s_nop 1
	v_cndmask_b32_e32 v78, v194, v78, vcc
	v_cmp_ngt_f32_e32 vcc, -1.0, v83
	s_nop 1
	v_cndmask_b32_e32 v78, v195, v78, vcc
	v_cmp_neq_f32_e32 vcc, -1.0, v83
	s_nop 1
	v_cndmask_b32_e32 v78, v196, v78, vcc
	v_cmp_lt_f32_e64 vcc, |v83|, s68
	s_nop 1
	v_cndmask_b32_e32 v78, v78, v83, vcc
	v_sub_f32_e32 v78, v84, v78
	global_store_dword v[76:77], v78, off offset:-20
.LBB0_275:
	s_andn2_saveexec_b64 s[0:1], s[0:1]
	s_cbranch_execz .LBB0_277
	v_mul_f32_e32 v72, v72, v82
	v_mul_f32_e32 v73, v73, v82
	v_mul_f32_e32 v72, 0xbfb8aa3b, v72
	v_mul_f32_e32 v73, 0xbfb8aa3b, v73
	v_exp_f32_e32 v72, v72
	v_exp_f32_e32 v73, v73
	v_mul_f32_e32 v74, v74, v82
	v_mul_f32_e32 v75, v75, v82
	v_mul_f32_e32 v74, 0xbfb8aa3b, v74
	v_pk_add_f32 v[72:73], v[72:73], 1.0 op_sel_hi:[1,0]
	v_mul_f32_e32 v75, 0xbfb8aa3b, v75
	v_exp_f32_e32 v74, v74
	v_rcp_f32_e32 v73, v73
	v_exp_f32_e32 v75, v75
	s_nop 0
	v_pk_add_f32 v[74:75], v[74:75], 1.0 op_sel_hi:[1,0]
	v_rcp_f32_e32 v72, v72
	v_rcp_f32_e32 v75, v75
	v_rcp_f32_e32 v74, v74
	global_store_dwordx4 v[84:85], v[72:75], off offset:64
; DI unsigned pk2(float lo, float hi) { f32x2 v = {lo, hi}; return __builtin_bit_cast(unsigned, __builtin_convertvector(v, bfx2)); }
; DI float sigmoidf_(float x) { return 1.f / (1.f + __expf(-x)); }
; DI float rstd_from16(const float* p, float inv_n) {
;   const f32x4 a = *(const f32x4*)p, b = *(const f32x4*)(p + 4), c = *(const f32x4*)(p + 8), d = *(const f32x4*)(p + 12);
;   const float s = ((a[0] + a[1]) + (a[2] + a[3])) + ((b[0] + b[1]) + (b[2] + b[3])) + ((c[0] + c[1]) + (c[2] + c[3])) + ((d[0] + d[1]) + (d[2] + d[3]));
;   return rsqrtf(s * inv_n + EPS_);
; template <bool SWAP> DI void inproj_tile(const Params& p, int layer, int tm, int tn, bf16_t* smem) {
;     ...
;         const int t = trow0 + i * 16 + l15; const float rs = rstd_from16(ssq + (size_t)t * 16, 1.f / 1024.f);
;         float* gt = (float*)(p.ws + O_GATES) + (size_t)t * 24; float* lf = (float*)(p.ws + O_LOGF) + (size_t)t * 8;
; #pragma unroll
;         for (int r = 0; r < 4; ++r) gt[quad * 4 + r] = sigmoidf_(acc[i][0][r] * rs);
;         if (quad < 2) {
; #pragma unroll
;           for (int r = 0; r < 4; ++r) gt[16 + quad * 4 + r] = sigmoidf_(acc[i][1][r] * rs);
;         } else {
; #pragma unroll
;           for (int r = 0; r < 4; ++r) { const int h = (quad - 2) * 4 + r; const float xx = acc[i][1][r] * rs + p.b_forget[layer * 8 + h]; lf[h] = fminf(xx, 0.f) - log1pf(__expf(-fabsf(xx))); }
;         }
;         const float* rp = (const float*)(p.ws + O_ROPE16) + (size_t)t * 32 + quad * 8; float o1[4], o2[4];
; #pragma unroll
;         for (int r = 0; r < 4; ++r) { const float cs = rp[2 * r], sn = rp[2 * r + 1], x1 = acc[i][2][r] * rs, x2 = acc[i][3][r] * rs; o1[r] = x1 * cs - x2 * sn; o2[r] = x2 * cs + x1 * sn; }
;         bf16_t* kp = (bf16_t*)(p.ws + O_MLAKPE) + (size_t)t * 32 + quad * 4;
;         *(u32x2*)kp = (u32x2){pk2(o1[0], o1[1]), pk2(o1[2], o1[3])}; *(u32x2*)(kp + 16) = (u32x2){pk2(o2[0], o2[1]), pk2(o2[2], o2[3])};
.LBB0_277:
	s_or_b64 exec, exec, s[0:1]
	s_nop 0
	v_lshl_add_u64 v[72:73], v[80:81], 2, s[14:15]
	v_mov_b32_e32 v105, v177
	v_lshl_add_u64 v[76:77], v[72:73], 0, v[104:105]
	global_load_dwordx4 v[72:75], v[76:77], off
	s_nop 0
	global_load_dwordx4 v[76:79], v[76:77], off offset:16
	v_or_b32_e32 v100, 64, v128
	v_ashrrev_i32_e32 v101, 31, v100
	v_lshlrev_b64 v[84:85], 6, v[100:101]
	v_lshl_add_u64 v[96:97], s[8:9], 0, v[84:85]
	global_load_dwordx4 v[84:87], v[96:97], off
	global_load_dwordx4 v[88:91], v[96:97], off offset:16
	global_load_dwordx4 v[92:95], v[96:97], off offset:32
	s_nop 0
	global_load_dwordx4 v[96:99], v[96:97], off offset:48
	v_pk_mul_f32 v[102:103], v[64:65], v[82:83] op_sel_hi:[1,0]
	v_pk_mul_f32 v[106:107], v[68:69], v[82:83] op_sel_hi:[1,0]
	v_pk_mul_f32 v[66:67], v[66:67], v[82:83] op_sel_hi:[1,0]
	v_pk_mul_f32 v[70:71], v[70:71], v[82:83] op_sel_hi:[1,0]
	v_lshl_add_u64 v[64:65], v[80:81], 1, s[16:17]
	v_mov_b32_e32 v113, v177
	v_mov_b64_e32 v[68:69], s[10:11]
	v_lshl_add_u64 v[80:81], v[64:65], 0, v[112:113]
	v_mad_i64_i32 v[68:69], s[0:1], v100, s63, v[68:69]
	v_lshlrev_b64 v[64:65], 5, v[100:101]
	v_lshl_add_u64 v[68:69], v[68:69], 0, v[176:177]
	s_waitcnt vmcnt(5)
	v_mov_b32_e32 v83, v74
	v_mov_b32_e32 v74, v73
	s_waitcnt vmcnt(4)
	v_mov_b32_e32 v73, v78
	v_mov_b32_e32 v78, v77
	v_mov_b32_e32 v82, v72
	v_mov_b32_e32 v72, v76
	v_pk_mul_f32 v[100:101], v[66:67], v[78:79]
	v_pk_mul_f32 v[78:79], v[70:71], v[78:79]
	v_pk_fma_f32 v[70:71], v[70:71], v[72:73], v[100:101] neg_lo:[0,0,1] neg_hi:[0,0,1]
	v_pk_fma_f32 v[66:67], v[66:67], v[72:73], v[78:79]
	s_waitcnt vmcnt(3)
	v_mov_b32_e32 v72, v85
	v_mov_b32_e32 v73, v86
	v_mov_b32_e32 v85, v87
	s_waitcnt vmcnt(2)
	v_mov_b32_e32 v78, v89
	v_mov_b32_e32 v79, v90
	v_mov_b32_e32 v89, v91
	v_pk_add_f32 v[72:73], v[72:73], v[84:85]
	v_pk_add_f32 v[78:79], v[78:79], v[88:89]
	v_pk_mul_f32 v[76:77], v[102:103], v[74:75]
	v_pk_mul_f32 v[74:75], v[106:107], v[74:75]
	v_pk_add_f32 v[72:73], v[72:73], v[72:73] op_sel:[0,1] op_sel_hi:[1,0]
	v_pk_add_f32 v[78:79], v[78:79], v[78:79] op_sel:[0,1] op_sel_hi:[1,0]
	v_pk_fma_f32 v[76:77], v[106:107], v[82:83], v[76:77] neg_lo:[0,0,1] neg_hi:[0,0,1]
	v_pk_fma_f32 v[74:75], v[102:103], v[82:83], v[74:75]
	s_waitcnt vmcnt(1)
	v_add_f32_e32 v82, v92, v93
	v_add_f32_e32 v86, v94, v95
	s_waitcnt vmcnt(0)
	v_mov_b32_e32 v83, v98
	v_mov_b32_e32 v87, v99
	v_mov_b32_e32 v73, v96
	v_mov_b32_e32 v79, v97
	v_pk_add_f32 v[82:83], v[82:83], v[86:87]
	v_pk_add_f32 v[72:73], v[72:73], v[78:79]
	v_cvt_pk_bf16_f32 v76, v76, v77
	v_pk_add_f32 v[72:73], v[72:73], v[82:83]
	v_cvt_pk_bf16_f32 v77, v70, v71
	v_add_f32_e32 v72, v72, v73
	v_fmamk_f32 v72, v72, 0x3a800000, v185
	v_mul_f32_e32 v73, 0x4b800000, v72
	v_cmp_gt_f32_e32 vcc, s60, v72
	v_cvt_pk_bf16_f32 v71, v66, v67
	v_cvt_pk_bf16_f32 v70, v74, v75
	v_cndmask_b32_e32 v72, v72, v73, vcc
	v_rsq_f32_e32 v72, v72
	global_store_dwordx2 v[80:81], v[76:77], off
	global_store_dwordx2 v[80:81], v[70:71], off offset:32
	v_mul_f32_e32 v66, 0x45800000, v72
	v_cndmask_b32_e32 v66, v72, v66, vcc
	v_mul_f32_e32 v60, v60, v66
	v_mul_f32_e32 v61, v61, v66
	v_mul_f32_e32 v60, 0xbfb8aa3b, v60
	v_mul_f32_e32 v61, 0xbfb8aa3b, v61
	v_mul_f32_e32 v62, v62, v66
	v_mul_f32_e32 v63, v63, v66
	v_exp_f32_e32 v60, v60
	v_exp_f32_e32 v61, v61
	v_mul_f32_e32 v62, 0xbfb8aa3b, v62
	v_mul_f32_e32 v63, 0xbfb8aa3b, v63
	v_exp_f32_e32 v62, v62
	v_exp_f32_e32 v63, v63
	v_pk_add_f32 v[60:61], v[60:61], 1.0 op_sel_hi:[1,0]
	v_pk_add_f32 v[62:63], v[62:63], 1.0 op_sel_hi:[1,0]
	v_div_scale_f32 v71, s[0:1], v60, v60, 1.0
	v_div_scale_f32 v73, s[4:5], v63, v63, 1.0
	v_rcp_f32_e32 v75, v71
	v_rcp_f32_e32 v76, v73
	v_fma_f32 v79, -v71, v75, 1.0
	v_div_scale_f32 v72, s[0:1], 1.0, v60, 1.0
	v_fma_f32 v80, -v73, v76, 1.0
	v_fmac_f32_e32 v75, v79, v75
	v_fmac_f32_e32 v76, v80, v76
	v_mul_f32_e32 v79, v72, v75
	v_fma_f32 v81, -v71, v79, v72
	v_fmac_f32_e32 v79, v81, v75
	v_fma_f32 v70, -v71, v79, v72
	s_mov_b64 vcc, s[0:1]
	v_div_scale_f32 v77, s[4:5], 1.0, v63, 1.0
	v_rcp_f32_e32 v61, v61
	v_div_fmas_f32 v67, v70, v75, v79
	v_div_fixup_f32 v60, v67, v60, 1.0
	v_mul_f32_e32 v67, v77, v76
	v_fma_f32 v70, -v73, v67, v77
	v_fmac_f32_e32 v67, v70, v76
	v_fma_f32 v70, -v73, v67, v77
	s_mov_b64 vcc, s[4:5]
	v_div_fmas_f32 v67, v70, v76, v67
	v_div_fixup_f32 v63, v67, v63, 1.0
	v_rcp_f32_e32 v62, v62
	global_store_dwordx4 v[68:69], v[60:63], off
	s_and_saveexec_b64 s[0:1], s[2:3]
	s_xor_b64 s[0:1], exec, s[0:1]
	s_cbranch_execz .LBB0_279
; template <bool SWAP> DI void inproj_tile(const Params& p, int layer, int tm, int tn, bf16_t* smem) {
;     ...
; #pragma unroll
;           for (int r = 0; r < 4; ++r) { const int h = (quad - 2) * 4 + r; const float xx = acc[i][1][r] * rs + p.b_forget[layer * 8 + h]; lf[h] = fminf(xx, 0.f) - log1pf(__expf(-fabsf(xx))); }
	v_readlane_b32 s72, v241, 8
	v_readlane_b32 s80, v241, 16
	v_readlane_b32 s81, v241, 17
	v_readlane_b32 s73, v241, 9
	v_readlane_b32 s74, v241, 10
	v_readlane_b32 s75, v241, 11
	v_readlane_b32 s76, v241, 12
	v_readlane_b32 s77, v241, 13
	global_load_dword v62, v176, s[80:81] offset:-32
	v_readlane_b32 s78, v241, 14
	v_readlane_b32 s79, v241, 15
	v_readlane_b32 s82, v241, 18
	v_readlane_b32 s83, v241, 19
	v_readlane_b32 s84, v241, 20
	v_readlane_b32 s85, v241, 21
	v_readlane_b32 s86, v241, 22
	v_readlane_b32 s87, v241, 23
	s_waitcnt vmcnt(0)
	v_fmac_f32_e32 v62, v56, v66
	v_mul_f32_e64 v60, |v62|, s64
	v_exp_f32_e32 v67, v60
	v_min_f32_e32 v68, 0, v62
	v_lshl_add_u64 v[60:61], s[12:13], 0, v[64:65]
	v_lshl_add_u64 v[60:61], v[60:61], 0, v[176:177]
	v_add_f32_e32 v69, 1.0, v67
	v_add_f32_e32 v70, -1.0, v69
	v_frexp_mant_f32_e32 v71, v69
	v_cvt_f64_f32_e32 v[62:63], v69
	v_sub_f32_e32 v72, v70, v69
	v_frexp_exp_i32_f64_e32 v62, v[62:63]
	v_cmp_gt_f32_e32 vcc, s65, v71
	v_sub_f32_e32 v70, v67, v70
	v_add_f32_e32 v63, 1.0, v72
	v_subbrev_co_u32_e32 v62, vcc, 0, v62, vcc
	v_add_f32_e32 v63, v70, v63
	v_sub_u32_e32 v70, 0, v62
	v_cvt_f32_i32_e32 v62, v62
	v_ldexp_f32 v69, v69, v70
	v_ldexp_f32 v63, v63, v70
	v_add_f32_e32 v70, -1.0, v69
	v_add_f32_e32 v71, 1.0, v69
	v_add_f32_e32 v72, 1.0, v70
	v_add_f32_e32 v73, -1.0, v71
	v_sub_f32_e32 v72, v69, v72
	v_sub_f32_e32 v69, v69, v73
	v_mul_f32_e32 v73, 0x3f317218, v62
	v_add_f32_e32 v72, v63, v72
	v_add_f32_e32 v63, v63, v69
	v_fma_f32 v69, v62, s66, -v73
	v_add_f32_e32 v74, v70, v72
	v_add_f32_e32 v75, v71, v63
	v_fmac_f32_e32 v69, 0xb102e308, v62
	v_sub_f32_e32 v62, v74, v70
	v_sub_f32_e32 v70, v75, v71
	v_rcp_f32_e32 v71, v75
	v_add_f32_e32 v76, v73, v69
	v_sub_f32_e32 v63, v63, v70
	v_sub_f32_e32 v70, v76, v73
	v_sub_f32_e32 v69, v69, v70
	v_mul_f32_e32 v70, v74, v71
	v_sub_f32_e32 v62, v72, v62
	v_mul_f32_e32 v72, v75, v70
	v_fma_f32 v73, v70, v75, -v72
	v_fmac_f32_e32 v73, v70, v63
	v_add_f32_e32 v77, v72, v73
	v_sub_f32_e32 v78, v74, v77
	v_sub_f32_e32 v72, v77, v72
	v_sub_f32_e32 v74, v74, v78
	v_sub_f32_e32 v72, v72, v73
	v_sub_f32_e32 v73, v74, v77
	v_add_f32_e32 v62, v62, v73
	v_add_f32_e32 v62, v72, v62
	v_add_f32_e32 v72, v78, v62
	v_mul_f32_e32 v73, v71, v72
	v_sub_f32_e32 v74, v78, v72
	v_mul_f32_e32 v77, v75, v73
	v_add_f32_e32 v62, v62, v74
	v_add_f32_e32 v74, v70, v73
	v_fma_f32 v75, v73, v75, -v77
	v_sub_f32_e32 v70, v74, v70
	v_fmac_f32_e32 v75, v73, v63
	v_sub_f32_e32 v63, v73, v70
	v_add_f32_e32 v70, v77, v75
	v_sub_f32_e32 v73, v70, v77
	v_sub_f32_e32 v77, v72, v70
	v_sub_f32_e32 v72, v72, v77
	v_sub_f32_e32 v70, v72, v70
	v_sub_f32_e32 v73, v73, v75
	v_add_f32_e32 v62, v62, v70
	v_add_f32_e32 v62, v73, v62
	v_add_f32_e32 v62, v77, v62
	v_mul_f32_e32 v62, v71, v62
	v_add_f32_e32 v62, v63, v62
	v_add_f32_e32 v63, v74, v62
	v_mul_f32_e32 v70, v63, v63
	v_fmamk_f32 v73, v70, 0x3e9b6dac, v186
	v_sub_f32_e32 v71, v63, v74
	v_ldexp_f32 v72, v63, 1
	v_mul_f32_e32 v63, v63, v70
	v_fmaak_f32 v70, v70, v73, 0x3f2aaada
	v_mul_f32_e32 v63, v63, v70
	v_add_f32_e32 v70, v72, v63
	v_sub_f32_e32 v62, v62, v71
	v_sub_f32_e32 v71, v70, v72
	v_ldexp_f32 v62, v62, 1
	v_sub_f32_e32 v63, v63, v71
	v_add_f32_e32 v62, v62, v63
	v_add_f32_e32 v63, v70, v62
	v_sub_f32_e32 v70, v63, v70
	v_add_f32_e32 v71, v76, v63
	v_sub_f32_e32 v62, v62, v70
	v_sub_f32_e32 v70, v71, v76
	v_sub_f32_e32 v72, v71, v70
	v_sub_f32_e32 v63, v63, v70
	v_add_f32_e32 v70, v69, v62
	v_sub_f32_e32 v72, v76, v72
	v_sub_f32_e32 v73, v70, v69
	v_add_f32_e32 v63, v63, v72
	v_sub_f32_e32 v72, v70, v73
	v_sub_f32_e32 v62, v62, v73
	v_sub_f32_e32 v69, v69, v72
	v_add_f32_e32 v63, v70, v63
	v_add_f32_e32 v62, v62, v69
	v_add_f32_e32 v69, v71, v63
	v_sub_f32_e32 v70, v69, v71
	v_sub_f32_e32 v63, v63, v70
	v_add_f32_e32 v62, v62, v63
	v_add_f32_e32 v62, v69, v62
	v_cmp_neq_f32_e32 vcc, s67, v67
	s_nop 1
	v_cndmask_b32_e32 v62, v194, v62, vcc
	v_cmp_ngt_f32_e32 vcc, -1.0, v67
	s_nop 1
	v_cndmask_b32_e32 v62, v195, v62, vcc
	v_cmp_neq_f32_e32 vcc, -1.0, v67
	s_nop 1
	v_cndmask_b32_e32 v62, v196, v62, vcc
	v_cmp_lt_f32_e64 vcc, |v67|, s68
	s_nop 1
	v_cndmask_b32_e32 v62, v62, v67, vcc
	v_sub_f32_e32 v62, v68, v62
	global_store_dword v[60:61], v62, off offset:-32
	global_load_dword v62, v176, s[80:81] offset:-28
	s_waitcnt vmcnt(0)
; template <bool SWAP> DI void inproj_tile(const Params& p, int layer, int tm, int tn, bf16_t* smem) {
;     ...
; #pragma unroll
;           for (int r = 0; r < 4; ++r) { const int h = (quad - 2) * 4 + r; const float xx = acc[i][1][r] * rs + p.b_forget[layer * 8 + h]; lf[h] = fminf(xx, 0.f) - log1pf(__expf(-fabsf(xx))); }
	v_fmac_f32_e32 v62, v57, v66
	v_mul_f32_e64 v63, |v62|, s64
	v_exp_f32_e32 v67, v63
	v_min_f32_e32 v68, 0, v62
	v_add_f32_e32 v69, 1.0, v67
	v_add_f32_e32 v70, -1.0, v69
	v_frexp_mant_f32_e32 v71, v69
	v_cvt_f64_f32_e32 v[62:63], v69
	v_sub_f32_e32 v72, v70, v69
	v_frexp_exp_i32_f64_e32 v62, v[62:63]
	v_cmp_gt_f32_e32 vcc, s65, v71
	v_sub_f32_e32 v70, v67, v70
	v_add_f32_e32 v63, 1.0, v72
	v_subbrev_co_u32_e32 v62, vcc, 0, v62, vcc
	v_add_f32_e32 v63, v70, v63
	v_sub_u32_e32 v70, 0, v62
	v_cvt_f32_i32_e32 v62, v62
	v_ldexp_f32 v69, v69, v70
	v_ldexp_f32 v63, v63, v70
	v_add_f32_e32 v70, -1.0, v69
	v_add_f32_e32 v71, 1.0, v69
	v_add_f32_e32 v72, 1.0, v70
	v_add_f32_e32 v73, -1.0, v71
	v_sub_f32_e32 v72, v69, v72
	v_sub_f32_e32 v69, v69, v73
	v_mul_f32_e32 v73, 0x3f317218, v62
	v_add_f32_e32 v72, v63, v72
	v_add_f32_e32 v63, v63, v69
	v_fma_f32 v69, v62, s66, -v73
	v_add_f32_e32 v74, v70, v72
	v_add_f32_e32 v75, v71, v63
	v_fmac_f32_e32 v69, 0xb102e308, v62
	v_sub_f32_e32 v62, v74, v70
	v_sub_f32_e32 v70, v75, v71
	v_rcp_f32_e32 v71, v75
	v_add_f32_e32 v76, v73, v69
	v_sub_f32_e32 v63, v63, v70
	v_sub_f32_e32 v70, v76, v73
	v_sub_f32_e32 v69, v69, v70
	v_mul_f32_e32 v70, v74, v71
	v_sub_f32_e32 v62, v72, v62
	v_mul_f32_e32 v72, v75, v70
	v_fma_f32 v73, v70, v75, -v72
	v_fmac_f32_e32 v73, v70, v63
	v_add_f32_e32 v77, v72, v73
	v_sub_f32_e32 v78, v74, v77
	v_sub_f32_e32 v72, v77, v72
	v_sub_f32_e32 v74, v74, v78
	v_sub_f32_e32 v72, v72, v73
	v_sub_f32_e32 v73, v74, v77
	v_add_f32_e32 v62, v62, v73
	v_add_f32_e32 v62, v72, v62
	v_add_f32_e32 v72, v78, v62
	v_mul_f32_e32 v73, v71, v72
	v_sub_f32_e32 v74, v78, v72
	v_mul_f32_e32 v77, v75, v73
	v_add_f32_e32 v62, v62, v74
	v_add_f32_e32 v74, v70, v73
	v_fma_f32 v75, v73, v75, -v77
	v_sub_f32_e32 v70, v74, v70
	v_fmac_f32_e32 v75, v73, v63
	v_sub_f32_e32 v63, v73, v70
	v_add_f32_e32 v70, v77, v75
	v_sub_f32_e32 v73, v70, v77
	v_sub_f32_e32 v77, v72, v70
	v_sub_f32_e32 v72, v72, v77
	v_sub_f32_e32 v70, v72, v70
	v_sub_f32_e32 v73, v73, v75
	v_add_f32_e32 v62, v62, v70
	v_add_f32_e32 v62, v73, v62
	v_add_f32_e32 v62, v77, v62
	v_mul_f32_e32 v62, v71, v62
	v_add_f32_e32 v62, v63, v62
	v_add_f32_e32 v63, v74, v62
	v_mul_f32_e32 v70, v63, v63
	v_fmamk_f32 v73, v70, 0x3e9b6dac, v186
	v_sub_f32_e32 v71, v63, v74
	v_ldexp_f32 v72, v63, 1
	v_mul_f32_e32 v63, v63, v70
	v_fmaak_f32 v70, v70, v73, 0x3f2aaada
	v_mul_f32_e32 v63, v63, v70
	v_add_f32_e32 v70, v72, v63
	v_sub_f32_e32 v62, v62, v71
	v_sub_f32_e32 v71, v70, v72
	v_ldexp_f32 v62, v62, 1
	v_sub_f32_e32 v63, v63, v71
	v_add_f32_e32 v62, v62, v63
	v_add_f32_e32 v63, v70, v62
	v_sub_f32_e32 v70, v63, v70
	v_add_f32_e32 v71, v76, v63
	v_sub_f32_e32 v62, v62, v70
	v_sub_f32_e32 v70, v71, v76
	v_sub_f32_e32 v72, v71, v70
	v_sub_f32_e32 v63, v63, v70
	v_add_f32_e32 v70, v69, v62
	v_sub_f32_e32 v72, v76, v72
	v_sub_f32_e32 v73, v70, v69
	v_add_f32_e32 v63, v63, v72
	v_sub_f32_e32 v72, v70, v73
	v_sub_f32_e32 v62, v62, v73
	v_sub_f32_e32 v69, v69, v72
	v_add_f32_e32 v63, v70, v63
	v_add_f32_e32 v62, v62, v69
	v_add_f32_e32 v69, v71, v63
	v_sub_f32_e32 v70, v69, v71
	v_sub_f32_e32 v63, v63, v70
	v_add_f32_e32 v62, v62, v63
	v_add_f32_e32 v62, v69, v62
	v_cmp_neq_f32_e32 vcc, s67, v67
	s_nop 1
	v_cndmask_b32_e32 v62, v194, v62, vcc
	v_cmp_ngt_f32_e32 vcc, -1.0, v67
	s_nop 1
	v_cndmask_b32_e32 v62, v195, v62, vcc
	v_cmp_neq_f32_e32 vcc, -1.0, v67
	s_nop 1
	v_cndmask_b32_e32 v62, v196, v62, vcc
	v_cmp_lt_f32_e64 vcc, |v67|, s68
	s_nop 1
	v_cndmask_b32_e32 v62, v62, v67, vcc
	v_sub_f32_e32 v62, v68, v62
	global_store_dword v[60:61], v62, off offset:-28
	global_load_dword v62, v176, s[80:81] offset:-24
	s_waitcnt vmcnt(0)
	v_fmac_f32_e32 v62, v58, v66
	v_mul_f32_e64 v63, |v62|, s64
	v_exp_f32_e32 v67, v63
	v_min_f32_e32 v68, 0, v62
	v_add_f32_e32 v69, 1.0, v67
	v_add_f32_e32 v70, -1.0, v69
	v_frexp_mant_f32_e32 v71, v69
	v_cvt_f64_f32_e32 v[62:63], v69
	v_sub_f32_e32 v72, v70, v69
	v_frexp_exp_i32_f64_e32 v62, v[62:63]
	v_cmp_gt_f32_e32 vcc, s65, v71
	v_sub_f32_e32 v70, v67, v70
	v_add_f32_e32 v63, 1.0, v72
	v_subbrev_co_u32_e32 v62, vcc, 0, v62, vcc
	v_add_f32_e32 v63, v70, v63
	v_sub_u32_e32 v70, 0, v62
	v_cvt_f32_i32_e32 v62, v62
	v_ldexp_f32 v69, v69, v70
	v_ldexp_f32 v63, v63, v70
	v_add_f32_e32 v70, -1.0, v69
	v_add_f32_e32 v71, 1.0, v69
	v_add_f32_e32 v72, 1.0, v70
	v_add_f32_e32 v73, -1.0, v71
	v_sub_f32_e32 v72, v69, v72
	v_sub_f32_e32 v69, v69, v73
	v_mul_f32_e32 v73, 0x3f317218, v62
	v_add_f32_e32 v72, v63, v72
	v_add_f32_e32 v63, v63, v69
	v_fma_f32 v69, v62, s66, -v73
	v_add_f32_e32 v74, v70, v72
	v_add_f32_e32 v75, v71, v63
	v_fmac_f32_e32 v69, 0xb102e308, v62
	v_sub_f32_e32 v62, v74, v70
	v_sub_f32_e32 v70, v75, v71
	v_rcp_f32_e32 v71, v75
	v_add_f32_e32 v76, v73, v69
	v_sub_f32_e32 v63, v63, v70
	v_sub_f32_e32 v70, v76, v73
	v_sub_f32_e32 v69, v69, v70
	v_mul_f32_e32 v70, v74, v71
	v_sub_f32_e32 v62, v72, v62
	v_mul_f32_e32 v72, v75, v70
	v_fma_f32 v73, v70, v75, -v72
	v_fmac_f32_e32 v73, v70, v63
	v_add_f32_e32 v77, v72, v73
	v_sub_f32_e32 v78, v74, v77
	v_sub_f32_e32 v72, v77, v72
	v_sub_f32_e32 v74, v74, v78
	v_sub_f32_e32 v72, v72, v73
	v_sub_f32_e32 v73, v74, v77
	v_add_f32_e32 v62, v62, v73
	v_add_f32_e32 v62, v72, v62
	v_add_f32_e32 v72, v78, v62
	v_mul_f32_e32 v73, v71, v72
	v_sub_f32_e32 v74, v78, v72
	v_mul_f32_e32 v77, v75, v73
	v_add_f32_e32 v62, v62, v74
	v_add_f32_e32 v74, v70, v73
	v_fma_f32 v75, v73, v75, -v77
	v_sub_f32_e32 v70, v74, v70
	v_fmac_f32_e32 v75, v73, v63
	v_sub_f32_e32 v63, v73, v70
	v_add_f32_e32 v70, v77, v75
	v_sub_f32_e32 v73, v70, v77
	v_sub_f32_e32 v77, v72, v70
	v_sub_f32_e32 v72, v72, v77
	v_sub_f32_e32 v70, v72, v70
; DI float sigmoidf_(float x) { return 1.f / (1.f + __expf(-x)); }
; template <bool SWAP> DI void inproj_tile(const Params& p, int layer, int tm, int tn, bf16_t* smem) {
;     ...
;         if (quad < 2) {
; #pragma unroll
;           for (int r = 0; r < 4; ++r) gt[16 + quad * 4 + r] = sigmoidf_(acc[i][1][r] * rs);
;         } else {
; #pragma unroll
;           for (int r = 0; r < 4; ++r) { const int h = (quad - 2) * 4 + r; const float xx = acc[i][1][r] * rs + p.b_forget[layer * 8 + h]; lf[h] = fminf(xx, 0.f) - log1pf(__expf(-fabsf(xx))); }
	v_sub_f32_e32 v73, v73, v75
	v_add_f32_e32 v62, v62, v70
	v_add_f32_e32 v62, v73, v62
	v_add_f32_e32 v62, v77, v62
	v_mul_f32_e32 v62, v71, v62
	v_add_f32_e32 v62, v63, v62
	v_add_f32_e32 v63, v74, v62
	v_mul_f32_e32 v70, v63, v63
	v_fmamk_f32 v73, v70, 0x3e9b6dac, v186
	v_sub_f32_e32 v71, v63, v74
	v_ldexp_f32 v72, v63, 1
	v_mul_f32_e32 v63, v63, v70
	v_fmaak_f32 v70, v70, v73, 0x3f2aaada
	v_mul_f32_e32 v63, v63, v70
	v_add_f32_e32 v70, v72, v63
	v_sub_f32_e32 v62, v62, v71
	v_sub_f32_e32 v71, v70, v72
	v_ldexp_f32 v62, v62, 1
	v_sub_f32_e32 v63, v63, v71
	v_add_f32_e32 v62, v62, v63
	v_add_f32_e32 v63, v70, v62
	v_sub_f32_e32 v70, v63, v70
	v_add_f32_e32 v71, v76, v63
	v_sub_f32_e32 v62, v62, v70
	v_sub_f32_e32 v70, v71, v76
	v_sub_f32_e32 v72, v71, v70
	v_sub_f32_e32 v63, v63, v70
	v_add_f32_e32 v70, v69, v62
	v_sub_f32_e32 v72, v76, v72
	v_sub_f32_e32 v73, v70, v69
	v_add_f32_e32 v63, v63, v72
	v_sub_f32_e32 v72, v70, v73
	v_sub_f32_e32 v62, v62, v73
	v_sub_f32_e32 v69, v69, v72
	v_add_f32_e32 v63, v70, v63
	v_add_f32_e32 v62, v62, v69
	v_add_f32_e32 v69, v71, v63
	v_sub_f32_e32 v70, v69, v71
	v_sub_f32_e32 v63, v63, v70
	v_add_f32_e32 v62, v62, v63
	v_add_f32_e32 v62, v69, v62
	v_cmp_neq_f32_e32 vcc, s67, v67
	s_nop 1
	v_cndmask_b32_e32 v62, v194, v62, vcc
	v_cmp_ngt_f32_e32 vcc, -1.0, v67
	s_nop 1
	v_cndmask_b32_e32 v62, v195, v62, vcc
	v_cmp_neq_f32_e32 vcc, -1.0, v67
	s_nop 1
	v_cndmask_b32_e32 v62, v196, v62, vcc
	v_cmp_lt_f32_e64 vcc, |v67|, s68
	s_nop 1
	v_cndmask_b32_e32 v62, v62, v67, vcc
	v_sub_f32_e32 v62, v68, v62
	global_store_dword v[60:61], v62, off offset:-24
	global_load_dword v62, v176, s[80:81] offset:-20
	s_waitcnt vmcnt(0)
	v_fmac_f32_e32 v62, v59, v66
	v_mul_f32_e64 v63, |v62|, s64
	v_exp_f32_e32 v67, v63
	v_min_f32_e32 v68, 0, v62
	v_add_f32_e32 v69, 1.0, v67
	v_add_f32_e32 v70, -1.0, v69
	v_frexp_mant_f32_e32 v71, v69
	v_cvt_f64_f32_e32 v[62:63], v69
	v_sub_f32_e32 v72, v70, v69
	v_frexp_exp_i32_f64_e32 v62, v[62:63]
	v_cmp_gt_f32_e32 vcc, s65, v71
	v_sub_f32_e32 v70, v67, v70
	v_add_f32_e32 v63, 1.0, v72
	v_subbrev_co_u32_e32 v62, vcc, 0, v62, vcc
	v_add_f32_e32 v63, v70, v63
	v_sub_u32_e32 v70, 0, v62
	v_cvt_f32_i32_e32 v62, v62
	v_ldexp_f32 v69, v69, v70
	v_ldexp_f32 v63, v63, v70
	v_add_f32_e32 v70, -1.0, v69
	v_add_f32_e32 v71, 1.0, v69
	v_add_f32_e32 v72, 1.0, v70
	v_add_f32_e32 v73, -1.0, v71
	v_sub_f32_e32 v72, v69, v72
	v_sub_f32_e32 v69, v69, v73
	v_mul_f32_e32 v73, 0x3f317218, v62
	v_add_f32_e32 v72, v63, v72
	v_add_f32_e32 v63, v63, v69
	v_fma_f32 v69, v62, s66, -v73
	v_add_f32_e32 v74, v70, v72
	v_add_f32_e32 v75, v71, v63
	v_fmac_f32_e32 v69, 0xb102e308, v62
	v_sub_f32_e32 v62, v74, v70
	v_sub_f32_e32 v70, v75, v71
	v_rcp_f32_e32 v71, v75
	v_add_f32_e32 v76, v73, v69
	v_sub_f32_e32 v63, v63, v70
	v_sub_f32_e32 v70, v76, v73
	v_sub_f32_e32 v69, v69, v70
	v_mul_f32_e32 v70, v74, v71
	v_sub_f32_e32 v62, v72, v62
	v_mul_f32_e32 v72, v75, v70
	v_fma_f32 v73, v70, v75, -v72
	v_fmac_f32_e32 v73, v70, v63
	v_add_f32_e32 v77, v72, v73
	v_sub_f32_e32 v78, v74, v77
	v_sub_f32_e32 v72, v77, v72
	v_sub_f32_e32 v74, v74, v78
	v_sub_f32_e32 v72, v72, v73
	v_sub_f32_e32 v73, v74, v77
	v_add_f32_e32 v62, v62, v73
	v_add_f32_e32 v62, v72, v62
	v_add_f32_e32 v72, v78, v62
	v_mul_f32_e32 v73, v71, v72
	v_sub_f32_e32 v74, v78, v72
	v_mul_f32_e32 v77, v75, v73
	v_add_f32_e32 v62, v62, v74
	v_add_f32_e32 v74, v70, v73
	v_fma_f32 v75, v73, v75, -v77
	v_sub_f32_e32 v70, v74, v70
	v_fmac_f32_e32 v75, v73, v63
	v_sub_f32_e32 v63, v73, v70
	v_add_f32_e32 v70, v77, v75
	v_sub_f32_e32 v73, v70, v77
	v_sub_f32_e32 v77, v72, v70
	v_sub_f32_e32 v72, v72, v77
	v_sub_f32_e32 v70, v72, v70
	v_sub_f32_e32 v73, v73, v75
	v_add_f32_e32 v62, v62, v70
	v_add_f32_e32 v62, v73, v62
	v_add_f32_e32 v62, v77, v62
	v_mul_f32_e32 v62, v71, v62
	v_add_f32_e32 v62, v63, v62
	v_add_f32_e32 v63, v74, v62
	v_mul_f32_e32 v70, v63, v63
	v_fmamk_f32 v73, v70, 0x3e9b6dac, v186
	v_sub_f32_e32 v71, v63, v74
	v_ldexp_f32 v72, v63, 1
	v_mul_f32_e32 v63, v63, v70
	v_fmaak_f32 v70, v70, v73, 0x3f2aaada
	v_mul_f32_e32 v63, v63, v70
	v_add_f32_e32 v70, v72, v63
	v_sub_f32_e32 v62, v62, v71
	v_sub_f32_e32 v71, v70, v72
	v_ldexp_f32 v62, v62, 1
	v_sub_f32_e32 v63, v63, v71
	v_add_f32_e32 v62, v62, v63
	v_add_f32_e32 v63, v70, v62
	v_sub_f32_e32 v70, v63, v70
	v_add_f32_e32 v71, v76, v63
	v_sub_f32_e32 v62, v62, v70
	v_sub_f32_e32 v70, v71, v76
	v_sub_f32_e32 v72, v71, v70
	v_sub_f32_e32 v63, v63, v70
	v_add_f32_e32 v70, v69, v62
	v_sub_f32_e32 v72, v76, v72
	v_sub_f32_e32 v73, v70, v69
	v_add_f32_e32 v63, v63, v72
	v_sub_f32_e32 v72, v70, v73
	v_sub_f32_e32 v62, v62, v73
	v_sub_f32_e32 v69, v69, v72
	v_add_f32_e32 v63, v70, v63
	v_add_f32_e32 v62, v62, v69
	v_add_f32_e32 v69, v71, v63
	v_sub_f32_e32 v70, v69, v71
	v_sub_f32_e32 v63, v63, v70
	v_add_f32_e32 v62, v62, v63
	v_add_f32_e32 v62, v69, v62
	v_cmp_neq_f32_e32 vcc, s67, v67
	s_nop 1
	v_cndmask_b32_e32 v62, v194, v62, vcc
	v_cmp_ngt_f32_e32 vcc, -1.0, v67
	s_nop 1
	v_cndmask_b32_e32 v62, v195, v62, vcc
	v_cmp_neq_f32_e32 vcc, -1.0, v67
	s_nop 1
	v_cndmask_b32_e32 v62, v196, v62, vcc
	v_cmp_lt_f32_e64 vcc, |v67|, s68
	s_nop 1
	v_cndmask_b32_e32 v62, v62, v67, vcc
	v_sub_f32_e32 v62, v68, v62
	global_store_dword v[60:61], v62, off offset:-20
.LBB0_279:
	s_andn2_saveexec_b64 s[0:1], s[0:1]
	s_cbranch_execz .LBB0_281
	v_mul_f32_e32 v56, v56, v66
	v_mul_f32_e32 v57, v57, v66
	v_mul_f32_e32 v56, 0xbfb8aa3b, v56
	v_mul_f32_e32 v57, 0xbfb8aa3b, v57
	v_exp_f32_e32 v56, v56
	v_exp_f32_e32 v57, v57
	v_mul_f32_e32 v58, v58, v66
	v_mul_f32_e32 v59, v59, v66
	v_mul_f32_e32 v58, 0xbfb8aa3b, v58
	v_pk_add_f32 v[56:57], v[56:57], 1.0 op_sel_hi:[1,0]
	v_mul_f32_e32 v59, 0xbfb8aa3b, v59
	v_exp_f32_e32 v58, v58
	v_rcp_f32_e32 v57, v57
	v_exp_f32_e32 v59, v59
	s_nop 0
	v_pk_add_f32 v[58:59], v[58:59], 1.0 op_sel_hi:[1,0]
	v_rcp_f32_e32 v56, v56
	v_rcp_f32_e32 v59, v59
	v_rcp_f32_e32 v58, v58
	global_store_dwordx4 v[68:69], v[56:59], off offset:64
; DI unsigned pk2(float lo, float hi) { f32x2 v = {lo, hi}; return __builtin_bit_cast(unsigned, __builtin_convertvector(v, bfx2)); }
; DI float sigmoidf_(float x) { return 1.f / (1.f + __expf(-x)); }
; DI float rstd_from16(const float* p, float inv_n) {
;   const f32x4 a = *(const f32x4*)p, b = *(const f32x4*)(p + 4), c = *(const f32x4*)(p + 8), d = *(const f32x4*)(p + 12);
;   const float s = ((a[0] + a[1]) + (a[2] + a[3])) + ((b[0] + b[1]) + (b[2] + b[3])) + ((c[0] + c[1]) + (c[2] + c[3])) + ((d[0] + d[1]) + (d[2] + d[3]));
;   return rsqrtf(s * inv_n + EPS_);
; template <bool SWAP> DI void inproj_tile(const Params& p, int layer, int tm, int tn, bf16_t* smem) {
;     ...
;         const int t = trow0 + i * 16 + l15; const float rs = rstd_from16(ssq + (size_t)t * 16, 1.f / 1024.f);
;         float* gt = (float*)(p.ws + O_GATES) + (size_t)t * 24; float* lf = (float*)(p.ws + O_LOGF) + (size_t)t * 8;
; #pragma unroll
;         for (int r = 0; r < 4; ++r) gt[quad * 4 + r] = sigmoidf_(acc[i][0][r] * rs);
;         if (quad < 2) {
; #pragma unroll
;           for (int r = 0; r < 4; ++r) gt[16 + quad * 4 + r] = sigmoidf_(acc[i][1][r] * rs);
;         } else {
; #pragma unroll
;           for (int r = 0; r < 4; ++r) { const int h = (quad - 2) * 4 + r; const float xx = acc[i][1][r] * rs + p.b_forget[layer * 8 + h]; lf[h] = fminf(xx, 0.f) - log1pf(__expf(-fabsf(xx))); }
;         }
;         const float* rp = (const float*)(p.ws + O_ROPE16) + (size_t)t * 32 + quad * 8; float o1[4], o2[4];
; #pragma unroll
;         for (int r = 0; r < 4; ++r) { const float cs = rp[2 * r], sn = rp[2 * r + 1], x1 = acc[i][2][r] * rs, x2 = acc[i][3][r] * rs; o1[r] = x1 * cs - x2 * sn; o2[r] = x2 * cs + x1 * sn; }
;         bf16_t* kp = (bf16_t*)(p.ws + O_MLAKPE) + (size_t)t * 32 + quad * 4;
;         *(u32x2*)kp = (u32x2){pk2(o1[0], o1[1]), pk2(o1[2], o1[3])}; *(u32x2*)(kp + 16) = (u32x2){pk2(o2[0], o2[1]), pk2(o2[2], o2[3])};
.LBB0_281:
	s_or_b64 exec, exec, s[0:1]
	s_nop 0
	v_lshl_add_u64 v[56:57], v[64:65], 2, s[14:15]
	v_mov_b32_e32 v105, v177
	v_lshl_add_u64 v[60:61], v[56:57], 0, v[104:105]
	global_load_dwordx4 v[56:59], v[60:61], off
	s_nop 0
	global_load_dwordx4 v[60:63], v[60:61], off offset:16
	v_or_b32_e32 v84, 0x50, v128
	v_ashrrev_i32_e32 v85, 31, v84
	v_lshlrev_b64 v[68:69], 6, v[84:85]
	v_lshl_add_u64 v[80:81], s[8:9], 0, v[68:69]
	global_load_dwordx4 v[68:71], v[80:81], off
	global_load_dwordx4 v[72:75], v[80:81], off offset:16
	global_load_dwordx4 v[76:79], v[80:81], off offset:32
	s_nop 0
	global_load_dwordx4 v[80:83], v[80:81], off offset:48
	v_pk_mul_f32 v[86:87], v[48:49], v[66:67] op_sel_hi:[1,0]
	v_pk_mul_f32 v[88:89], v[52:53], v[66:67] op_sel_hi:[1,0]
	v_pk_mul_f32 v[50:51], v[50:51], v[66:67] op_sel_hi:[1,0]
	v_pk_mul_f32 v[54:55], v[54:55], v[66:67] op_sel_hi:[1,0]
	v_lshl_add_u64 v[48:49], v[64:65], 1, s[16:17]
	v_mov_b32_e32 v113, v177
	v_mov_b64_e32 v[52:53], s[10:11]
	v_lshl_add_u64 v[64:65], v[48:49], 0, v[112:113]
	v_mad_i64_i32 v[52:53], s[0:1], v84, s63, v[52:53]
	v_lshlrev_b64 v[48:49], 5, v[84:85]
	v_lshl_add_u64 v[52:53], v[52:53], 0, v[176:177]
	s_waitcnt vmcnt(5)
	v_mov_b32_e32 v67, v58
	v_mov_b32_e32 v58, v57
	s_waitcnt vmcnt(4)
	v_mov_b32_e32 v57, v62
	v_mov_b32_e32 v62, v61
	v_mov_b32_e32 v66, v56
	v_mov_b32_e32 v56, v60
	v_pk_mul_f32 v[84:85], v[50:51], v[62:63]
	v_pk_mul_f32 v[62:63], v[54:55], v[62:63]
	v_pk_fma_f32 v[54:55], v[54:55], v[56:57], v[84:85] neg_lo:[0,0,1] neg_hi:[0,0,1]
	v_pk_fma_f32 v[50:51], v[50:51], v[56:57], v[62:63]
	s_waitcnt vmcnt(3)
	v_mov_b32_e32 v56, v69
	v_mov_b32_e32 v57, v70
	v_mov_b32_e32 v69, v71
	s_waitcnt vmcnt(2)
	v_mov_b32_e32 v62, v73
	v_mov_b32_e32 v63, v74
	v_mov_b32_e32 v73, v75
	v_pk_add_f32 v[56:57], v[56:57], v[68:69]
	v_pk_add_f32 v[62:63], v[62:63], v[72:73]
	v_pk_mul_f32 v[60:61], v[86:87], v[58:59]
	v_pk_mul_f32 v[58:59], v[88:89], v[58:59]
	v_pk_add_f32 v[56:57], v[56:57], v[56:57] op_sel:[0,1] op_sel_hi:[1,0]
	v_pk_add_f32 v[62:63], v[62:63], v[62:63] op_sel:[0,1] op_sel_hi:[1,0]
	v_pk_fma_f32 v[60:61], v[88:89], v[66:67], v[60:61] neg_lo:[0,0,1] neg_hi:[0,0,1]
	v_pk_fma_f32 v[58:59], v[86:87], v[66:67], v[58:59]
	s_waitcnt vmcnt(1)
	v_add_f32_e32 v66, v76, v77
	v_add_f32_e32 v70, v78, v79
	s_waitcnt vmcnt(0)
	v_mov_b32_e32 v67, v82
	v_mov_b32_e32 v71, v83
	v_mov_b32_e32 v57, v80
	v_mov_b32_e32 v63, v81
	v_pk_add_f32 v[66:67], v[66:67], v[70:71]
	v_pk_add_f32 v[56:57], v[56:57], v[62:63]
	v_cvt_pk_bf16_f32 v60, v60, v61
	v_pk_add_f32 v[56:57], v[56:57], v[66:67]
	v_cvt_pk_bf16_f32 v61, v54, v55
	v_add_f32_e32 v56, v56, v57
	v_fmamk_f32 v56, v56, 0x3a800000, v185
	v_mul_f32_e32 v57, 0x4b800000, v56
	v_cmp_gt_f32_e32 vcc, s60, v56
	v_cvt_pk_bf16_f32 v55, v50, v51
	v_cvt_pk_bf16_f32 v54, v58, v59
	v_cndmask_b32_e32 v56, v56, v57, vcc
	v_rsq_f32_e32 v56, v56
	global_store_dwordx2 v[64:65], v[60:61], off
	global_store_dwordx2 v[64:65], v[54:55], off offset:32
	v_mul_f32_e32 v50, 0x45800000, v56
	v_cndmask_b32_e32 v50, v56, v50, vcc
	v_mul_f32_e32 v44, v44, v50
	v_mul_f32_e32 v45, v45, v50
	v_mul_f32_e32 v44, 0xbfb8aa3b, v44
	v_mul_f32_e32 v45, 0xbfb8aa3b, v45
	v_mul_f32_e32 v46, v46, v50
	v_mul_f32_e32 v47, v47, v50
	v_exp_f32_e32 v44, v44
	v_exp_f32_e32 v45, v45
	v_mul_f32_e32 v46, 0xbfb8aa3b, v46
	v_mul_f32_e32 v47, 0xbfb8aa3b, v47
	v_exp_f32_e32 v46, v46
	v_exp_f32_e32 v47, v47
	v_pk_add_f32 v[44:45], v[44:45], 1.0 op_sel_hi:[1,0]
	v_pk_add_f32 v[46:47], v[46:47], 1.0 op_sel_hi:[1,0]
	v_div_scale_f32 v55, s[0:1], v44, v44, 1.0
	v_div_scale_f32 v57, s[4:5], v47, v47, 1.0
	v_rcp_f32_e32 v59, v55
	v_rcp_f32_e32 v60, v57
	v_fma_f32 v63, -v55, v59, 1.0
	v_div_scale_f32 v56, s[0:1], 1.0, v44, 1.0
	v_fma_f32 v64, -v57, v60, 1.0
	v_fmac_f32_e32 v59, v63, v59
	v_fmac_f32_e32 v60, v64, v60
	v_mul_f32_e32 v63, v56, v59
	v_fma_f32 v65, -v55, v63, v56
	v_fmac_f32_e32 v63, v65, v59
	v_fma_f32 v54, -v55, v63, v56
	s_mov_b64 vcc, s[0:1]
	v_div_scale_f32 v61, s[4:5], 1.0, v47, 1.0
	v_rcp_f32_e32 v45, v45
	v_div_fmas_f32 v51, v54, v59, v63
	v_div_fixup_f32 v44, v51, v44, 1.0
	v_mul_f32_e32 v51, v61, v60
	v_fma_f32 v54, -v57, v51, v61
	v_fmac_f32_e32 v51, v54, v60
	v_fma_f32 v54, -v57, v51, v61
	s_mov_b64 vcc, s[4:5]
	v_div_fmas_f32 v51, v54, v60, v51
	v_div_fixup_f32 v47, v51, v47, 1.0
	v_rcp_f32_e32 v46, v46
	global_store_dwordx4 v[52:53], v[44:47], off
	s_and_saveexec_b64 s[0:1], s[2:3]
	s_xor_b64 s[0:1], exec, s[0:1]
	s_cbranch_execz .LBB0_283
; template <bool SWAP> DI void inproj_tile(const Params& p, int layer, int tm, int tn, bf16_t* smem) {
;     ...
; #pragma unroll
;           for (int r = 0; r < 4; ++r) { const int h = (quad - 2) * 4 + r; const float xx = acc[i][1][r] * rs + p.b_forget[layer * 8 + h]; lf[h] = fminf(xx, 0.f) - log1pf(__expf(-fabsf(xx))); }
	v_readlane_b32 s72, v241, 8
	v_readlane_b32 s80, v241, 16
	v_readlane_b32 s81, v241, 17
	v_readlane_b32 s73, v241, 9
	v_readlane_b32 s74, v241, 10
	v_readlane_b32 s75, v241, 11
	v_readlane_b32 s76, v241, 12
	v_readlane_b32 s77, v241, 13
	global_load_dword v46, v176, s[80:81] offset:-32
	v_readlane_b32 s78, v241, 14
	v_readlane_b32 s79, v241, 15
	v_readlane_b32 s82, v241, 18
	v_readlane_b32 s83, v241, 19
	v_readlane_b32 s84, v241, 20
	v_readlane_b32 s85, v241, 21
	v_readlane_b32 s86, v241, 22
	v_readlane_b32 s87, v241, 23
	s_waitcnt vmcnt(0)
	v_fmac_f32_e32 v46, v40, v50
	v_mul_f32_e64 v44, |v46|, s64
	v_exp_f32_e32 v51, v44
	v_min_f32_e32 v52, 0, v46
	v_lshl_add_u64 v[44:45], s[12:13], 0, v[48:49]
	v_lshl_add_u64 v[44:45], v[44:45], 0, v[176:177]
	v_add_f32_e32 v53, 1.0, v51
	v_add_f32_e32 v54, -1.0, v53
	v_frexp_mant_f32_e32 v55, v53
	v_cvt_f64_f32_e32 v[46:47], v53
	v_sub_f32_e32 v56, v54, v53
	v_frexp_exp_i32_f64_e32 v46, v[46:47]
	v_cmp_gt_f32_e32 vcc, s65, v55
	v_sub_f32_e32 v54, v51, v54
	v_add_f32_e32 v47, 1.0, v56
	v_subbrev_co_u32_e32 v46, vcc, 0, v46, vcc
	v_add_f32_e32 v47, v54, v47
	v_sub_u32_e32 v54, 0, v46
	v_cvt_f32_i32_e32 v46, v46
	v_ldexp_f32 v53, v53, v54
	v_ldexp_f32 v47, v47, v54
	v_add_f32_e32 v54, -1.0, v53
	v_add_f32_e32 v55, 1.0, v53
	v_add_f32_e32 v56, 1.0, v54
	v_add_f32_e32 v57, -1.0, v55
	v_sub_f32_e32 v56, v53, v56
	v_sub_f32_e32 v53, v53, v57
	v_mul_f32_e32 v57, 0x3f317218, v46
	v_add_f32_e32 v56, v47, v56
	v_add_f32_e32 v47, v47, v53
	v_fma_f32 v53, v46, s66, -v57
	v_add_f32_e32 v58, v54, v56
	v_add_f32_e32 v59, v55, v47
	v_fmac_f32_e32 v53, 0xb102e308, v46
	v_sub_f32_e32 v46, v58, v54
	v_sub_f32_e32 v54, v59, v55
	v_rcp_f32_e32 v55, v59
	v_add_f32_e32 v60, v57, v53
	v_sub_f32_e32 v47, v47, v54
	v_sub_f32_e32 v54, v60, v57
	v_sub_f32_e32 v53, v53, v54
	v_mul_f32_e32 v54, v58, v55
	v_sub_f32_e32 v46, v56, v46
	v_mul_f32_e32 v56, v59, v54
	v_fma_f32 v57, v54, v59, -v56
	v_fmac_f32_e32 v57, v54, v47
	v_add_f32_e32 v61, v56, v57
	v_sub_f32_e32 v62, v58, v61
	v_sub_f32_e32 v56, v61, v56
	v_sub_f32_e32 v58, v58, v62
	v_sub_f32_e32 v56, v56, v57
	v_sub_f32_e32 v57, v58, v61
	v_add_f32_e32 v46, v46, v57
	v_add_f32_e32 v46, v56, v46
	v_add_f32_e32 v56, v62, v46
	v_mul_f32_e32 v57, v55, v56
	v_sub_f32_e32 v58, v62, v56
	v_mul_f32_e32 v61, v59, v57
	v_add_f32_e32 v46, v46, v58
	v_add_f32_e32 v58, v54, v57
	v_fma_f32 v59, v57, v59, -v61
	v_sub_f32_e32 v54, v58, v54
	v_fmac_f32_e32 v59, v57, v47
	v_sub_f32_e32 v47, v57, v54
	v_add_f32_e32 v54, v61, v59
	v_sub_f32_e32 v57, v54, v61
	v_sub_f32_e32 v61, v56, v54
	v_sub_f32_e32 v56, v56, v61
	v_sub_f32_e32 v54, v56, v54
	v_sub_f32_e32 v57, v57, v59
	v_add_f32_e32 v46, v46, v54
	v_add_f32_e32 v46, v57, v46
	v_add_f32_e32 v46, v61, v46
	v_mul_f32_e32 v46, v55, v46
	v_add_f32_e32 v46, v47, v46
	v_add_f32_e32 v47, v58, v46
	v_mul_f32_e32 v54, v47, v47
	v_fmamk_f32 v57, v54, 0x3e9b6dac, v186
	v_sub_f32_e32 v55, v47, v58
	v_ldexp_f32 v56, v47, 1
	v_mul_f32_e32 v47, v47, v54
	v_fmaak_f32 v54, v54, v57, 0x3f2aaada
	v_mul_f32_e32 v47, v47, v54
	v_add_f32_e32 v54, v56, v47
	v_sub_f32_e32 v46, v46, v55
	v_sub_f32_e32 v55, v54, v56
	v_ldexp_f32 v46, v46, 1
	v_sub_f32_e32 v47, v47, v55
	v_add_f32_e32 v46, v46, v47
	v_add_f32_e32 v47, v54, v46
	v_sub_f32_e32 v54, v47, v54
	v_add_f32_e32 v55, v60, v47
	v_sub_f32_e32 v46, v46, v54
	v_sub_f32_e32 v54, v55, v60
	v_sub_f32_e32 v56, v55, v54
	v_sub_f32_e32 v47, v47, v54
	v_add_f32_e32 v54, v53, v46
	v_sub_f32_e32 v56, v60, v56
	v_sub_f32_e32 v57, v54, v53
	v_add_f32_e32 v47, v47, v56
	v_sub_f32_e32 v56, v54, v57
	v_sub_f32_e32 v46, v46, v57
	v_sub_f32_e32 v53, v53, v56
	v_add_f32_e32 v47, v54, v47
	v_add_f32_e32 v46, v46, v53
	v_add_f32_e32 v53, v55, v47
	v_sub_f32_e32 v54, v53, v55
	v_sub_f32_e32 v47, v47, v54
	v_add_f32_e32 v46, v46, v47
	v_add_f32_e32 v46, v53, v46
	v_cmp_neq_f32_e32 vcc, s67, v51
	s_nop 1
	v_cndmask_b32_e32 v46, v194, v46, vcc
	v_cmp_ngt_f32_e32 vcc, -1.0, v51
	s_nop 1
	v_cndmask_b32_e32 v46, v195, v46, vcc
	v_cmp_neq_f32_e32 vcc, -1.0, v51
	s_nop 1
	v_cndmask_b32_e32 v46, v196, v46, vcc
	v_cmp_lt_f32_e64 vcc, |v51|, s68
	s_nop 1
	v_cndmask_b32_e32 v46, v46, v51, vcc
	v_sub_f32_e32 v46, v52, v46
	global_store_dword v[44:45], v46, off offset:-32
	global_load_dword v46, v176, s[80:81] offset:-28
	s_waitcnt vmcnt(0)
; template <bool SWAP> DI void inproj_tile(const Params& p, int layer, int tm, int tn, bf16_t* smem) {
;     ...
; #pragma unroll
;           for (int r = 0; r < 4; ++r) { const int h = (quad - 2) * 4 + r; const float xx = acc[i][1][r] * rs + p.b_forget[layer * 8 + h]; lf[h] = fminf(xx, 0.f) - log1pf(__expf(-fabsf(xx))); }
	v_fmac_f32_e32 v46, v41, v50
	v_mul_f32_e64 v47, |v46|, s64
	v_exp_f32_e32 v51, v47
	v_min_f32_e32 v52, 0, v46
	v_add_f32_e32 v53, 1.0, v51
	v_add_f32_e32 v54, -1.0, v53
	v_frexp_mant_f32_e32 v55, v53
	v_cvt_f64_f32_e32 v[46:47], v53
	v_sub_f32_e32 v56, v54, v53
	v_frexp_exp_i32_f64_e32 v46, v[46:47]
	v_cmp_gt_f32_e32 vcc, s65, v55
	v_sub_f32_e32 v54, v51, v54
	v_add_f32_e32 v47, 1.0, v56
	v_subbrev_co_u32_e32 v46, vcc, 0, v46, vcc
	v_add_f32_e32 v47, v54, v47
	v_sub_u32_e32 v54, 0, v46
	v_cvt_f32_i32_e32 v46, v46
	v_ldexp_f32 v53, v53, v54
	v_ldexp_f32 v47, v47, v54
	v_add_f32_e32 v54, -1.0, v53
	v_add_f32_e32 v55, 1.0, v53
	v_add_f32_e32 v56, 1.0, v54
	v_add_f32_e32 v57, -1.0, v55
	v_sub_f32_e32 v56, v53, v56
	v_sub_f32_e32 v53, v53, v57
	v_mul_f32_e32 v57, 0x3f317218, v46
	v_add_f32_e32 v56, v47, v56
	v_add_f32_e32 v47, v47, v53
	v_fma_f32 v53, v46, s66, -v57
	v_add_f32_e32 v58, v54, v56
	v_add_f32_e32 v59, v55, v47
	v_fmac_f32_e32 v53, 0xb102e308, v46
	v_sub_f32_e32 v46, v58, v54
	v_sub_f32_e32 v54, v59, v55
	v_rcp_f32_e32 v55, v59
	v_add_f32_e32 v60, v57, v53
	v_sub_f32_e32 v47, v47, v54
	v_sub_f32_e32 v54, v60, v57
	v_sub_f32_e32 v53, v53, v54
	v_mul_f32_e32 v54, v58, v55
	v_sub_f32_e32 v46, v56, v46
	v_mul_f32_e32 v56, v59, v54
	v_fma_f32 v57, v54, v59, -v56
	v_fmac_f32_e32 v57, v54, v47
	v_add_f32_e32 v61, v56, v57
	v_sub_f32_e32 v62, v58, v61
	v_sub_f32_e32 v56, v61, v56
	v_sub_f32_e32 v58, v58, v62
	v_sub_f32_e32 v56, v56, v57
	v_sub_f32_e32 v57, v58, v61
	v_add_f32_e32 v46, v46, v57
	v_add_f32_e32 v46, v56, v46
	v_add_f32_e32 v56, v62, v46
	v_mul_f32_e32 v57, v55, v56
	v_sub_f32_e32 v58, v62, v56
	v_mul_f32_e32 v61, v59, v57
	v_add_f32_e32 v46, v46, v58
	v_add_f32_e32 v58, v54, v57
	v_fma_f32 v59, v57, v59, -v61
	v_sub_f32_e32 v54, v58, v54
	v_fmac_f32_e32 v59, v57, v47
	v_sub_f32_e32 v47, v57, v54
	v_add_f32_e32 v54, v61, v59
	v_sub_f32_e32 v57, v54, v61
	v_sub_f32_e32 v61, v56, v54
	v_sub_f32_e32 v56, v56, v61
	v_sub_f32_e32 v54, v56, v54
	v_sub_f32_e32 v57, v57, v59
	v_add_f32_e32 v46, v46, v54
	v_add_f32_e32 v46, v57, v46
	v_add_f32_e32 v46, v61, v46
	v_mul_f32_e32 v46, v55, v46
	v_add_f32_e32 v46, v47, v46
	v_add_f32_e32 v47, v58, v46
	v_mul_f32_e32 v54, v47, v47
	v_fmamk_f32 v57, v54, 0x3e9b6dac, v186
	v_sub_f32_e32 v55, v47, v58
	v_ldexp_f32 v56, v47, 1
	v_mul_f32_e32 v47, v47, v54
	v_fmaak_f32 v54, v54, v57, 0x3f2aaada
	v_mul_f32_e32 v47, v47, v54
	v_add_f32_e32 v54, v56, v47
	v_sub_f32_e32 v46, v46, v55
	v_sub_f32_e32 v55, v54, v56
	v_ldexp_f32 v46, v46, 1
	v_sub_f32_e32 v47, v47, v55
	v_add_f32_e32 v46, v46, v47
	v_add_f32_e32 v47, v54, v46
	v_sub_f32_e32 v54, v47, v54
	v_add_f32_e32 v55, v60, v47
	v_sub_f32_e32 v46, v46, v54
	v_sub_f32_e32 v54, v55, v60
	v_sub_f32_e32 v56, v55, v54
	v_sub_f32_e32 v47, v47, v54
	v_add_f32_e32 v54, v53, v46
	v_sub_f32_e32 v56, v60, v56
	v_sub_f32_e32 v57, v54, v53
	v_add_f32_e32 v47, v47, v56
	v_sub_f32_e32 v56, v54, v57
	v_sub_f32_e32 v46, v46, v57
	v_sub_f32_e32 v53, v53, v56
	v_add_f32_e32 v47, v54, v47
	v_add_f32_e32 v46, v46, v53
	v_add_f32_e32 v53, v55, v47
	v_sub_f32_e32 v54, v53, v55
	v_sub_f32_e32 v47, v47, v54
	v_add_f32_e32 v46, v46, v47
	v_add_f32_e32 v46, v53, v46
	v_cmp_neq_f32_e32 vcc, s67, v51
	s_nop 1
	v_cndmask_b32_e32 v46, v194, v46, vcc
	v_cmp_ngt_f32_e32 vcc, -1.0, v51
	s_nop 1
	v_cndmask_b32_e32 v46, v195, v46, vcc
	v_cmp_neq_f32_e32 vcc, -1.0, v51
	s_nop 1
	v_cndmask_b32_e32 v46, v196, v46, vcc
	v_cmp_lt_f32_e64 vcc, |v51|, s68
	s_nop 1
	v_cndmask_b32_e32 v46, v46, v51, vcc
	v_sub_f32_e32 v46, v52, v46
	global_store_dword v[44:45], v46, off offset:-28
	global_load_dword v46, v176, s[80:81] offset:-24
	s_waitcnt vmcnt(0)
	v_fmac_f32_e32 v46, v42, v50
	v_mul_f32_e64 v47, |v46|, s64
	v_exp_f32_e32 v51, v47
	v_min_f32_e32 v52, 0, v46
	v_add_f32_e32 v53, 1.0, v51
	v_add_f32_e32 v54, -1.0, v53
	v_frexp_mant_f32_e32 v55, v53
	v_cvt_f64_f32_e32 v[46:47], v53
	v_sub_f32_e32 v56, v54, v53
	v_frexp_exp_i32_f64_e32 v46, v[46:47]
	v_cmp_gt_f32_e32 vcc, s65, v55
	v_sub_f32_e32 v54, v51, v54
	v_add_f32_e32 v47, 1.0, v56
	v_subbrev_co_u32_e32 v46, vcc, 0, v46, vcc
	v_add_f32_e32 v47, v54, v47
	v_sub_u32_e32 v54, 0, v46
	v_cvt_f32_i32_e32 v46, v46
	v_ldexp_f32 v53, v53, v54
	v_ldexp_f32 v47, v47, v54
	v_add_f32_e32 v54, -1.0, v53
	v_add_f32_e32 v55, 1.0, v53
	v_add_f32_e32 v56, 1.0, v54
	v_add_f32_e32 v57, -1.0, v55
	v_sub_f32_e32 v56, v53, v56
	v_sub_f32_e32 v53, v53, v57
	v_mul_f32_e32 v57, 0x3f317218, v46
	v_add_f32_e32 v56, v47, v56
	v_add_f32_e32 v47, v47, v53
	v_fma_f32 v53, v46, s66, -v57
	v_add_f32_e32 v58, v54, v56
	v_add_f32_e32 v59, v55, v47
	v_fmac_f32_e32 v53, 0xb102e308, v46
	v_sub_f32_e32 v46, v58, v54
	v_sub_f32_e32 v54, v59, v55
	v_rcp_f32_e32 v55, v59
	v_add_f32_e32 v60, v57, v53
	v_sub_f32_e32 v47, v47, v54
	v_sub_f32_e32 v54, v60, v57
	v_sub_f32_e32 v53, v53, v54
	v_mul_f32_e32 v54, v58, v55
	v_sub_f32_e32 v46, v56, v46
	v_mul_f32_e32 v56, v59, v54
	v_fma_f32 v57, v54, v59, -v56
	v_fmac_f32_e32 v57, v54, v47
	v_add_f32_e32 v61, v56, v57
	v_sub_f32_e32 v62, v58, v61
	v_sub_f32_e32 v56, v61, v56
	v_sub_f32_e32 v58, v58, v62
	v_sub_f32_e32 v56, v56, v57
	v_sub_f32_e32 v57, v58, v61
	v_add_f32_e32 v46, v46, v57
	v_add_f32_e32 v46, v56, v46
	v_add_f32_e32 v56, v62, v46
	v_mul_f32_e32 v57, v55, v56
	v_sub_f32_e32 v58, v62, v56
	v_mul_f32_e32 v61, v59, v57
	v_add_f32_e32 v46, v46, v58
	v_add_f32_e32 v58, v54, v57
	v_fma_f32 v59, v57, v59, -v61
	v_sub_f32_e32 v54, v58, v54
	v_fmac_f32_e32 v59, v57, v47
	v_sub_f32_e32 v47, v57, v54
	v_add_f32_e32 v54, v61, v59
	v_sub_f32_e32 v57, v54, v61
	v_sub_f32_e32 v61, v56, v54
	v_sub_f32_e32 v56, v56, v61
	v_sub_f32_e32 v54, v56, v54
; DI float sigmoidf_(float x) { return 1.f / (1.f + __expf(-x)); }
; template <bool SWAP> DI void inproj_tile(const Params& p, int layer, int tm, int tn, bf16_t* smem) {
;     ...
;         if (quad < 2) {
; #pragma unroll
;           for (int r = 0; r < 4; ++r) gt[16 + quad * 4 + r] = sigmoidf_(acc[i][1][r] * rs);
;         } else {
; #pragma unroll
;           for (int r = 0; r < 4; ++r) { const int h = (quad - 2) * 4 + r; const float xx = acc[i][1][r] * rs + p.b_forget[layer * 8 + h]; lf[h] = fminf(xx, 0.f) - log1pf(__expf(-fabsf(xx))); }
	v_sub_f32_e32 v57, v57, v59
	v_add_f32_e32 v46, v46, v54
	v_add_f32_e32 v46, v57, v46
	v_add_f32_e32 v46, v61, v46
	v_mul_f32_e32 v46, v55, v46
	v_add_f32_e32 v46, v47, v46
	v_add_f32_e32 v47, v58, v46
	v_mul_f32_e32 v54, v47, v47
	v_fmamk_f32 v57, v54, 0x3e9b6dac, v186
	v_sub_f32_e32 v55, v47, v58
	v_ldexp_f32 v56, v47, 1
	v_mul_f32_e32 v47, v47, v54
	v_fmaak_f32 v54, v54, v57, 0x3f2aaada
	v_mul_f32_e32 v47, v47, v54
	v_add_f32_e32 v54, v56, v47
	v_sub_f32_e32 v46, v46, v55
	v_sub_f32_e32 v55, v54, v56
	v_ldexp_f32 v46, v46, 1
	v_sub_f32_e32 v47, v47, v55
	v_add_f32_e32 v46, v46, v47
	v_add_f32_e32 v47, v54, v46
	v_sub_f32_e32 v54, v47, v54
	v_add_f32_e32 v55, v60, v47
	v_sub_f32_e32 v46, v46, v54
	v_sub_f32_e32 v54, v55, v60
	v_sub_f32_e32 v56, v55, v54
	v_sub_f32_e32 v47, v47, v54
	v_add_f32_e32 v54, v53, v46
	v_sub_f32_e32 v56, v60, v56
	v_sub_f32_e32 v57, v54, v53
	v_add_f32_e32 v47, v47, v56
	v_sub_f32_e32 v56, v54, v57
	v_sub_f32_e32 v46, v46, v57
	v_sub_f32_e32 v53, v53, v56
	v_add_f32_e32 v47, v54, v47
	v_add_f32_e32 v46, v46, v53
	v_add_f32_e32 v53, v55, v47
	v_sub_f32_e32 v54, v53, v55
	v_sub_f32_e32 v47, v47, v54
	v_add_f32_e32 v46, v46, v47
	v_add_f32_e32 v46, v53, v46
	v_cmp_neq_f32_e32 vcc, s67, v51
	s_nop 1
	v_cndmask_b32_e32 v46, v194, v46, vcc
	v_cmp_ngt_f32_e32 vcc, -1.0, v51
	s_nop 1
	v_cndmask_b32_e32 v46, v195, v46, vcc
	v_cmp_neq_f32_e32 vcc, -1.0, v51
	s_nop 1
	v_cndmask_b32_e32 v46, v196, v46, vcc
	v_cmp_lt_f32_e64 vcc, |v51|, s68
	s_nop 1
	v_cndmask_b32_e32 v46, v46, v51, vcc
	v_sub_f32_e32 v46, v52, v46
	global_store_dword v[44:45], v46, off offset:-24
	global_load_dword v46, v176, s[80:81] offset:-20
	s_waitcnt vmcnt(0)
	v_fmac_f32_e32 v46, v43, v50
	v_mul_f32_e64 v47, |v46|, s64
	v_exp_f32_e32 v51, v47
	v_min_f32_e32 v52, 0, v46
	v_add_f32_e32 v53, 1.0, v51
	v_add_f32_e32 v54, -1.0, v53
	v_frexp_mant_f32_e32 v55, v53
	v_cvt_f64_f32_e32 v[46:47], v53
	v_sub_f32_e32 v56, v54, v53
	v_frexp_exp_i32_f64_e32 v46, v[46:47]
	v_cmp_gt_f32_e32 vcc, s65, v55
	v_sub_f32_e32 v54, v51, v54
	v_add_f32_e32 v47, 1.0, v56
	v_subbrev_co_u32_e32 v46, vcc, 0, v46, vcc
	v_add_f32_e32 v47, v54, v47
	v_sub_u32_e32 v54, 0, v46
	v_cvt_f32_i32_e32 v46, v46
	v_ldexp_f32 v53, v53, v54
	v_ldexp_f32 v47, v47, v54
	v_add_f32_e32 v54, -1.0, v53
	v_add_f32_e32 v55, 1.0, v53
	v_add_f32_e32 v56, 1.0, v54
	v_add_f32_e32 v57, -1.0, v55
	v_sub_f32_e32 v56, v53, v56
	v_sub_f32_e32 v53, v53, v57
	v_mul_f32_e32 v57, 0x3f317218, v46
	v_add_f32_e32 v56, v47, v56
	v_add_f32_e32 v47, v47, v53
	v_fma_f32 v53, v46, s66, -v57
	v_add_f32_e32 v58, v54, v56
	v_add_f32_e32 v59, v55, v47
	v_fmac_f32_e32 v53, 0xb102e308, v46
	v_sub_f32_e32 v46, v58, v54
	v_sub_f32_e32 v54, v59, v55
	v_rcp_f32_e32 v55, v59
	v_add_f32_e32 v60, v57, v53
	v_sub_f32_e32 v47, v47, v54
	v_sub_f32_e32 v54, v60, v57
	v_sub_f32_e32 v53, v53, v54
	v_mul_f32_e32 v54, v58, v55
	v_sub_f32_e32 v46, v56, v46
	v_mul_f32_e32 v56, v59, v54
	v_fma_f32 v57, v54, v59, -v56
	v_fmac_f32_e32 v57, v54, v47
	v_add_f32_e32 v61, v56, v57
	v_sub_f32_e32 v62, v58, v61
	v_sub_f32_e32 v56, v61, v56
	v_sub_f32_e32 v58, v58, v62
	v_sub_f32_e32 v56, v56, v57
	v_sub_f32_e32 v57, v58, v61
	v_add_f32_e32 v46, v46, v57
	v_add_f32_e32 v46, v56, v46
	v_add_f32_e32 v56, v62, v46
	v_mul_f32_e32 v57, v55, v56
	v_sub_f32_e32 v58, v62, v56
	v_mul_f32_e32 v61, v59, v57
	v_add_f32_e32 v46, v46, v58
	v_add_f32_e32 v58, v54, v57
	v_fma_f32 v59, v57, v59, -v61
	v_sub_f32_e32 v54, v58, v54
	v_fmac_f32_e32 v59, v57, v47
	v_sub_f32_e32 v47, v57, v54
	v_add_f32_e32 v54, v61, v59
	v_sub_f32_e32 v57, v54, v61
	v_sub_f32_e32 v61, v56, v54
	v_sub_f32_e32 v56, v56, v61
	v_sub_f32_e32 v54, v56, v54
	v_sub_f32_e32 v57, v57, v59
	v_add_f32_e32 v46, v46, v54
	v_add_f32_e32 v46, v57, v46
	v_add_f32_e32 v46, v61, v46
	v_mul_f32_e32 v46, v55, v46
	v_add_f32_e32 v46, v47, v46
	v_add_f32_e32 v47, v58, v46
	v_mul_f32_e32 v54, v47, v47
	v_fmamk_f32 v57, v54, 0x3e9b6dac, v186
	v_sub_f32_e32 v55, v47, v58
	v_ldexp_f32 v56, v47, 1
	v_mul_f32_e32 v47, v47, v54
	v_fmaak_f32 v54, v54, v57, 0x3f2aaada
	v_mul_f32_e32 v47, v47, v54
	v_add_f32_e32 v54, v56, v47
	v_sub_f32_e32 v46, v46, v55
	v_sub_f32_e32 v55, v54, v56
	v_ldexp_f32 v46, v46, 1
	v_sub_f32_e32 v47, v47, v55
	v_add_f32_e32 v46, v46, v47
	v_add_f32_e32 v47, v54, v46
	v_sub_f32_e32 v54, v47, v54
	v_add_f32_e32 v55, v60, v47
	v_sub_f32_e32 v46, v46, v54
	v_sub_f32_e32 v54, v55, v60
	v_sub_f32_e32 v56, v55, v54
	v_sub_f32_e32 v47, v47, v54
	v_add_f32_e32 v54, v53, v46
	v_sub_f32_e32 v56, v60, v56
	v_sub_f32_e32 v57, v54, v53
	v_add_f32_e32 v47, v47, v56
	v_sub_f32_e32 v56, v54, v57
	v_sub_f32_e32 v46, v46, v57
	v_sub_f32_e32 v53, v53, v56
	v_add_f32_e32 v47, v54, v47
	v_add_f32_e32 v46, v46, v53
	v_add_f32_e32 v53, v55, v47
	v_sub_f32_e32 v54, v53, v55
	v_sub_f32_e32 v47, v47, v54
	v_add_f32_e32 v46, v46, v47
	v_add_f32_e32 v46, v53, v46
	v_cmp_neq_f32_e32 vcc, s67, v51
	s_nop 1
	v_cndmask_b32_e32 v46, v194, v46, vcc
	v_cmp_ngt_f32_e32 vcc, -1.0, v51
	s_nop 1
	v_cndmask_b32_e32 v46, v195, v46, vcc
	v_cmp_neq_f32_e32 vcc, -1.0, v51
	s_nop 1
	v_cndmask_b32_e32 v46, v196, v46, vcc
	v_cmp_lt_f32_e64 vcc, |v51|, s68
	s_nop 1
	v_cndmask_b32_e32 v46, v46, v51, vcc
	v_sub_f32_e32 v46, v52, v46
	global_store_dword v[44:45], v46, off offset:-20
.LBB0_283:
	s_andn2_saveexec_b64 s[0:1], s[0:1]
	s_cbranch_execz .LBB0_285
	v_mul_f32_e32 v40, v40, v50
	v_mul_f32_e32 v41, v41, v50
	v_mul_f32_e32 v40, 0xbfb8aa3b, v40
	v_mul_f32_e32 v41, 0xbfb8aa3b, v41
	v_exp_f32_e32 v40, v40
	v_exp_f32_e32 v41, v41
	v_mul_f32_e32 v42, v42, v50
	v_mul_f32_e32 v43, v43, v50
	v_mul_f32_e32 v42, 0xbfb8aa3b, v42
	v_pk_add_f32 v[40:41], v[40:41], 1.0 op_sel_hi:[1,0]
	v_mul_f32_e32 v43, 0xbfb8aa3b, v43
	v_exp_f32_e32 v42, v42
	v_rcp_f32_e32 v41, v41
	v_exp_f32_e32 v43, v43
	s_nop 0
	v_pk_add_f32 v[42:43], v[42:43], 1.0 op_sel_hi:[1,0]
	v_rcp_f32_e32 v40, v40
	v_rcp_f32_e32 v43, v43
	v_rcp_f32_e32 v42, v42
	global_store_dwordx4 v[52:53], v[40:43], off offset:64
; DI unsigned pk2(float lo, float hi) { f32x2 v = {lo, hi}; return __builtin_bit_cast(unsigned, __builtin_convertvector(v, bfx2)); }
; DI float sigmoidf_(float x) { return 1.f / (1.f + __expf(-x)); }
; DI float rstd_from16(const float* p, float inv_n) {
;   const f32x4 a = *(const f32x4*)p, b = *(const f32x4*)(p + 4), c = *(const f32x4*)(p + 8), d = *(const f32x4*)(p + 12);
;   const float s = ((a[0] + a[1]) + (a[2] + a[3])) + ((b[0] + b[1]) + (b[2] + b[3])) + ((c[0] + c[1]) + (c[2] + c[3])) + ((d[0] + d[1]) + (d[2] + d[3]));
;   return rsqrtf(s * inv_n + EPS_);
; template <bool SWAP> DI void inproj_tile(const Params& p, int layer, int tm, int tn, bf16_t* smem) {
;     ...
;         const int t = trow0 + i * 16 + l15; const float rs = rstd_from16(ssq + (size_t)t * 16, 1.f / 1024.f);
;         float* gt = (float*)(p.ws + O_GATES) + (size_t)t * 24; float* lf = (float*)(p.ws + O_LOGF) + (size_t)t * 8;
; #pragma unroll
;         for (int r = 0; r < 4; ++r) gt[quad * 4 + r] = sigmoidf_(acc[i][0][r] * rs);
;         if (quad < 2) {
; #pragma unroll
;           for (int r = 0; r < 4; ++r) gt[16 + quad * 4 + r] = sigmoidf_(acc[i][1][r] * rs);
;         } else {
; #pragma unroll
;           for (int r = 0; r < 4; ++r) { const int h = (quad - 2) * 4 + r; const float xx = acc[i][1][r] * rs + p.b_forget[layer * 8 + h]; lf[h] = fminf(xx, 0.f) - log1pf(__expf(-fabsf(xx))); }
;         }
;         const float* rp = (const float*)(p.ws + O_ROPE16) + (size_t)t * 32 + quad * 8; float o1[4], o2[4];
; #pragma unroll
;         for (int r = 0; r < 4; ++r) { const float cs = rp[2 * r], sn = rp[2 * r + 1], x1 = acc[i][2][r] * rs, x2 = acc[i][3][r] * rs; o1[r] = x1 * cs - x2 * sn; o2[r] = x2 * cs + x1 * sn; }
;         bf16_t* kp = (bf16_t*)(p.ws + O_MLAKPE) + (size_t)t * 32 + quad * 4;
;         *(u32x2*)kp = (u32x2){pk2(o1[0], o1[1]), pk2(o1[2], o1[3])}; *(u32x2*)(kp + 16) = (u32x2){pk2(o2[0], o2[1]), pk2(o2[2], o2[3])};
.LBB0_285:
	s_or_b64 exec, exec, s[0:1]
	s_nop 0
	v_lshl_add_u64 v[40:41], v[48:49], 2, s[14:15]
	v_mov_b32_e32 v105, v177
	v_lshl_add_u64 v[44:45], v[40:41], 0, v[104:105]
	global_load_dwordx4 v[40:43], v[44:45], off
	s_nop 0
	global_load_dwordx4 v[44:47], v[44:45], off offset:16
	v_or_b32_e32 v68, 0x60, v128
	v_ashrrev_i32_e32 v69, 31, v68
	v_lshlrev_b64 v[52:53], 6, v[68:69]
	v_lshl_add_u64 v[64:65], s[8:9], 0, v[52:53]
	global_load_dwordx4 v[52:55], v[64:65], off
	global_load_dwordx4 v[56:59], v[64:65], off offset:16
	global_load_dwordx4 v[60:63], v[64:65], off offset:32
	s_nop 0
	global_load_dwordx4 v[64:67], v[64:65], off offset:48
	v_pk_mul_f32 v[70:71], v[32:33], v[50:51] op_sel_hi:[1,0]
	v_pk_mul_f32 v[72:73], v[36:37], v[50:51] op_sel_hi:[1,0]
	v_pk_mul_f32 v[34:35], v[34:35], v[50:51] op_sel_hi:[1,0]
	v_pk_mul_f32 v[38:39], v[38:39], v[50:51] op_sel_hi:[1,0]
	v_lshl_add_u64 v[32:33], v[48:49], 1, s[16:17]
	v_mov_b32_e32 v113, v177
	v_mov_b64_e32 v[36:37], s[10:11]
	v_lshl_add_u64 v[48:49], v[32:33], 0, v[112:113]
	v_mad_i64_i32 v[36:37], s[0:1], v68, s63, v[36:37]
	v_lshlrev_b64 v[32:33], 5, v[68:69]
	v_lshl_add_u64 v[36:37], v[36:37], 0, v[176:177]
	s_waitcnt vmcnt(5)
	v_mov_b32_e32 v51, v42
	v_mov_b32_e32 v42, v41
	s_waitcnt vmcnt(4)
	v_mov_b32_e32 v41, v46
	v_mov_b32_e32 v46, v45
	v_mov_b32_e32 v50, v40
	v_mov_b32_e32 v40, v44
	v_pk_mul_f32 v[68:69], v[34:35], v[46:47]
	v_pk_mul_f32 v[46:47], v[38:39], v[46:47]
	v_pk_fma_f32 v[38:39], v[38:39], v[40:41], v[68:69] neg_lo:[0,0,1] neg_hi:[0,0,1]
	v_pk_fma_f32 v[34:35], v[34:35], v[40:41], v[46:47]
	s_waitcnt vmcnt(3)
	v_mov_b32_e32 v40, v53
	v_mov_b32_e32 v41, v54
	v_mov_b32_e32 v53, v55
	s_waitcnt vmcnt(2)
	v_mov_b32_e32 v46, v57
	v_mov_b32_e32 v47, v58
	v_mov_b32_e32 v57, v59
	v_pk_add_f32 v[40:41], v[40:41], v[52:53]
	v_pk_add_f32 v[46:47], v[46:47], v[56:57]
	v_pk_mul_f32 v[44:45], v[70:71], v[42:43]
	v_pk_mul_f32 v[42:43], v[72:73], v[42:43]
	v_pk_add_f32 v[40:41], v[40:41], v[40:41] op_sel:[0,1] op_sel_hi:[1,0]
	v_pk_add_f32 v[46:47], v[46:47], v[46:47] op_sel:[0,1] op_sel_hi:[1,0]
	v_pk_fma_f32 v[44:45], v[72:73], v[50:51], v[44:45] neg_lo:[0,0,1] neg_hi:[0,0,1]
	v_pk_fma_f32 v[42:43], v[70:71], v[50:51], v[42:43]
	s_waitcnt vmcnt(1)
	v_add_f32_e32 v50, v60, v61
	v_add_f32_e32 v54, v62, v63
	s_waitcnt vmcnt(0)
	v_mov_b32_e32 v51, v66
	v_mov_b32_e32 v55, v67
	v_mov_b32_e32 v41, v64
	v_mov_b32_e32 v47, v65
	v_pk_add_f32 v[50:51], v[50:51], v[54:55]
	v_pk_add_f32 v[40:41], v[40:41], v[46:47]
	v_cvt_pk_bf16_f32 v44, v44, v45
	v_pk_add_f32 v[40:41], v[40:41], v[50:51]
	v_cvt_pk_bf16_f32 v45, v38, v39
	v_add_f32_e32 v40, v40, v41
	v_fmamk_f32 v40, v40, 0x3a800000, v185
	v_mul_f32_e32 v41, 0x4b800000, v40
	v_cmp_gt_f32_e32 vcc, s60, v40
	v_cvt_pk_bf16_f32 v39, v34, v35
	v_cvt_pk_bf16_f32 v38, v42, v43
	v_cndmask_b32_e32 v40, v40, v41, vcc
	v_rsq_f32_e32 v40, v40
	global_store_dwordx2 v[48:49], v[44:45], off
	global_store_dwordx2 v[48:49], v[38:39], off offset:32
	v_mul_f32_e32 v34, 0x45800000, v40
	v_cndmask_b32_e32 v34, v40, v34, vcc
	v_mul_f32_e32 v28, v28, v34
	v_mul_f32_e32 v29, v29, v34
	v_mul_f32_e32 v28, 0xbfb8aa3b, v28
	v_mul_f32_e32 v29, 0xbfb8aa3b, v29
	v_mul_f32_e32 v30, v30, v34
	v_mul_f32_e32 v31, v31, v34
	v_exp_f32_e32 v28, v28
	v_exp_f32_e32 v29, v29
	v_mul_f32_e32 v30, 0xbfb8aa3b, v30
	v_mul_f32_e32 v31, 0xbfb8aa3b, v31
	v_exp_f32_e32 v30, v30
	v_exp_f32_e32 v31, v31
	v_pk_add_f32 v[28:29], v[28:29], 1.0 op_sel_hi:[1,0]
	v_pk_add_f32 v[30:31], v[30:31], 1.0 op_sel_hi:[1,0]
	v_div_scale_f32 v39, s[0:1], v28, v28, 1.0
	v_div_scale_f32 v41, s[4:5], v31, v31, 1.0
	v_rcp_f32_e32 v43, v39
	v_rcp_f32_e32 v44, v41
	v_fma_f32 v47, -v39, v43, 1.0
	v_div_scale_f32 v40, s[0:1], 1.0, v28, 1.0
	v_fma_f32 v48, -v41, v44, 1.0
	v_fmac_f32_e32 v43, v47, v43
	v_fmac_f32_e32 v44, v48, v44
	v_mul_f32_e32 v47, v40, v43
	v_fma_f32 v49, -v39, v47, v40
	v_fmac_f32_e32 v47, v49, v43
	v_fma_f32 v38, -v39, v47, v40
	s_mov_b64 vcc, s[0:1]
	v_div_scale_f32 v45, s[4:5], 1.0, v31, 1.0
	v_rcp_f32_e32 v29, v29
	v_div_fmas_f32 v35, v38, v43, v47
	v_div_fixup_f32 v28, v35, v28, 1.0
	v_mul_f32_e32 v35, v45, v44
	v_fma_f32 v38, -v41, v35, v45
	v_fmac_f32_e32 v35, v38, v44
	v_fma_f32 v38, -v41, v35, v45
	s_mov_b64 vcc, s[4:5]
	v_div_fmas_f32 v35, v38, v44, v35
	v_div_fixup_f32 v31, v35, v31, 1.0
	v_rcp_f32_e32 v30, v30
	global_store_dwordx4 v[36:37], v[28:31], off
	s_and_saveexec_b64 s[0:1], s[2:3]
	s_xor_b64 s[0:1], exec, s[0:1]
	s_cbranch_execz .LBB0_287
; template <bool SWAP> DI void inproj_tile(const Params& p, int layer, int tm, int tn, bf16_t* smem) {
;     ...
; #pragma unroll
;           for (int r = 0; r < 4; ++r) { const int h = (quad - 2) * 4 + r; const float xx = acc[i][1][r] * rs + p.b_forget[layer * 8 + h]; lf[h] = fminf(xx, 0.f) - log1pf(__expf(-fabsf(xx))); }
	v_readlane_b32 s72, v241, 8
	v_readlane_b32 s80, v241, 16
	v_readlane_b32 s81, v241, 17
	v_readlane_b32 s73, v241, 9
	v_readlane_b32 s74, v241, 10
	v_readlane_b32 s75, v241, 11
	v_readlane_b32 s76, v241, 12
	v_readlane_b32 s77, v241, 13
	global_load_dword v30, v176, s[80:81] offset:-32
	v_readlane_b32 s78, v241, 14
	v_readlane_b32 s79, v241, 15
	v_readlane_b32 s82, v241, 18
	v_readlane_b32 s83, v241, 19
	v_readlane_b32 s84, v241, 20
	v_readlane_b32 s85, v241, 21
	v_readlane_b32 s86, v241, 22
	v_readlane_b32 s87, v241, 23
	s_waitcnt vmcnt(0)
	v_fmac_f32_e32 v30, v24, v34
	v_mul_f32_e64 v28, |v30|, s64
	v_exp_f32_e32 v35, v28
	v_min_f32_e32 v36, 0, v30
	v_lshl_add_u64 v[28:29], s[12:13], 0, v[32:33]
	v_lshl_add_u64 v[28:29], v[28:29], 0, v[176:177]
	v_add_f32_e32 v37, 1.0, v35
	v_add_f32_e32 v38, -1.0, v37
	v_frexp_mant_f32_e32 v39, v37
	v_cvt_f64_f32_e32 v[30:31], v37
	v_sub_f32_e32 v40, v38, v37
	v_frexp_exp_i32_f64_e32 v30, v[30:31]
	v_cmp_gt_f32_e32 vcc, s65, v39
	v_sub_f32_e32 v38, v35, v38
	v_add_f32_e32 v31, 1.0, v40
	v_subbrev_co_u32_e32 v30, vcc, 0, v30, vcc
	v_add_f32_e32 v31, v38, v31
	v_sub_u32_e32 v38, 0, v30
	v_cvt_f32_i32_e32 v30, v30
	v_ldexp_f32 v37, v37, v38
	v_ldexp_f32 v31, v31, v38
	v_add_f32_e32 v38, -1.0, v37
	v_add_f32_e32 v39, 1.0, v37
	v_add_f32_e32 v40, 1.0, v38
	v_add_f32_e32 v41, -1.0, v39
	v_sub_f32_e32 v40, v37, v40
	v_sub_f32_e32 v37, v37, v41
	v_mul_f32_e32 v41, 0x3f317218, v30
	v_add_f32_e32 v40, v31, v40
	v_add_f32_e32 v31, v31, v37
	v_fma_f32 v37, v30, s66, -v41
	v_add_f32_e32 v42, v38, v40
	v_add_f32_e32 v43, v39, v31
	v_fmac_f32_e32 v37, 0xb102e308, v30
	v_sub_f32_e32 v30, v42, v38
	v_sub_f32_e32 v38, v43, v39
	v_rcp_f32_e32 v39, v43
	v_add_f32_e32 v44, v41, v37
	v_sub_f32_e32 v31, v31, v38
	v_sub_f32_e32 v38, v44, v41
	v_sub_f32_e32 v37, v37, v38
	v_mul_f32_e32 v38, v42, v39
	v_sub_f32_e32 v30, v40, v30
	v_mul_f32_e32 v40, v43, v38
	v_fma_f32 v41, v38, v43, -v40
	v_fmac_f32_e32 v41, v38, v31
	v_add_f32_e32 v45, v40, v41
	v_sub_f32_e32 v46, v42, v45
	v_sub_f32_e32 v40, v45, v40
	v_sub_f32_e32 v42, v42, v46
	v_sub_f32_e32 v40, v40, v41
	v_sub_f32_e32 v41, v42, v45
	v_add_f32_e32 v30, v30, v41
	v_add_f32_e32 v30, v40, v30
	v_add_f32_e32 v40, v46, v30
	v_mul_f32_e32 v41, v39, v40
	v_sub_f32_e32 v42, v46, v40
	v_mul_f32_e32 v45, v43, v41
	v_add_f32_e32 v30, v30, v42
	v_add_f32_e32 v42, v38, v41
	v_fma_f32 v43, v41, v43, -v45
	v_sub_f32_e32 v38, v42, v38
	v_fmac_f32_e32 v43, v41, v31
	v_sub_f32_e32 v31, v41, v38
	v_add_f32_e32 v38, v45, v43
	v_sub_f32_e32 v41, v38, v45
	v_sub_f32_e32 v45, v40, v38
	v_sub_f32_e32 v40, v40, v45
	v_sub_f32_e32 v38, v40, v38
	v_sub_f32_e32 v41, v41, v43
	v_add_f32_e32 v30, v30, v38
	v_add_f32_e32 v30, v41, v30
	v_add_f32_e32 v30, v45, v30
	v_mul_f32_e32 v30, v39, v30
	v_add_f32_e32 v30, v31, v30
	v_add_f32_e32 v31, v42, v30
	v_mul_f32_e32 v38, v31, v31
	v_fmamk_f32 v41, v38, 0x3e9b6dac, v186
	v_sub_f32_e32 v39, v31, v42
	v_ldexp_f32 v40, v31, 1
	v_mul_f32_e32 v31, v31, v38
	v_fmaak_f32 v38, v38, v41, 0x3f2aaada
	v_mul_f32_e32 v31, v31, v38
	v_add_f32_e32 v38, v40, v31
	v_sub_f32_e32 v30, v30, v39
	v_sub_f32_e32 v39, v38, v40
	v_ldexp_f32 v30, v30, 1
	v_sub_f32_e32 v31, v31, v39
	v_add_f32_e32 v30, v30, v31
	v_add_f32_e32 v31, v38, v30
	v_sub_f32_e32 v38, v31, v38
	v_add_f32_e32 v39, v44, v31
	v_sub_f32_e32 v30, v30, v38
	v_sub_f32_e32 v38, v39, v44
	v_sub_f32_e32 v40, v39, v38
	v_sub_f32_e32 v31, v31, v38
	v_add_f32_e32 v38, v37, v30
	v_sub_f32_e32 v40, v44, v40
	v_sub_f32_e32 v41, v38, v37
	v_add_f32_e32 v31, v31, v40
	v_sub_f32_e32 v40, v38, v41
	v_sub_f32_e32 v30, v30, v41
	v_sub_f32_e32 v37, v37, v40
	v_add_f32_e32 v31, v38, v31
	v_add_f32_e32 v30, v30, v37
	v_add_f32_e32 v37, v39, v31
	v_sub_f32_e32 v38, v37, v39
	v_sub_f32_e32 v31, v31, v38
	v_add_f32_e32 v30, v30, v31
	v_add_f32_e32 v30, v37, v30
	v_cmp_neq_f32_e32 vcc, s67, v35
	s_nop 1
	v_cndmask_b32_e32 v30, v194, v30, vcc
	v_cmp_ngt_f32_e32 vcc, -1.0, v35
	s_nop 1
	v_cndmask_b32_e32 v30, v195, v30, vcc
	v_cmp_neq_f32_e32 vcc, -1.0, v35
	s_nop 1
	v_cndmask_b32_e32 v30, v196, v30, vcc
	v_cmp_lt_f32_e64 vcc, |v35|, s68
	s_nop 1
	v_cndmask_b32_e32 v30, v30, v35, vcc
	v_sub_f32_e32 v30, v36, v30
	global_store_dword v[28:29], v30, off offset:-32
	global_load_dword v30, v176, s[80:81] offset:-28
	s_waitcnt vmcnt(0)
; template <bool SWAP> DI void inproj_tile(const Params& p, int layer, int tm, int tn, bf16_t* smem) {
;     ...
;         } else {
; #pragma unroll
;           for (int r = 0; r < 4; ++r) { const int h = (quad - 2) * 4 + r; const float xx = acc[i][1][r] * rs + p.b_forget[layer * 8 + h]; lf[h] = fminf(xx, 0.f) - log1pf(__expf(-fabsf(xx))); }
;         }
	v_fmac_f32_e32 v30, v25, v34
	v_mul_f32_e64 v31, |v30|, s64
	v_exp_f32_e32 v35, v31
	v_min_f32_e32 v36, 0, v30
	v_add_f32_e32 v37, 1.0, v35
	v_add_f32_e32 v38, -1.0, v37
	v_frexp_mant_f32_e32 v39, v37
	v_cvt_f64_f32_e32 v[30:31], v37
	v_sub_f32_e32 v40, v38, v37
	v_frexp_exp_i32_f64_e32 v30, v[30:31]
	v_cmp_gt_f32_e32 vcc, s65, v39
	v_sub_f32_e32 v38, v35, v38
	v_add_f32_e32 v31, 1.0, v40
	v_subbrev_co_u32_e32 v30, vcc, 0, v30, vcc
	v_add_f32_e32 v31, v38, v31
	v_sub_u32_e32 v38, 0, v30
	v_cvt_f32_i32_e32 v30, v30
	v_ldexp_f32 v37, v37, v38
	v_ldexp_f32 v31, v31, v38
	v_add_f32_e32 v38, -1.0, v37
	v_add_f32_e32 v39, 1.0, v37
	v_add_f32_e32 v40, 1.0, v38
	v_add_f32_e32 v41, -1.0, v39
	v_sub_f32_e32 v40, v37, v40
	v_sub_f32_e32 v37, v37, v41
	v_mul_f32_e32 v41, 0x3f317218, v30
	v_add_f32_e32 v40, v31, v40
	v_add_f32_e32 v31, v31, v37
	v_fma_f32 v37, v30, s66, -v41
	v_add_f32_e32 v42, v38, v40
	v_add_f32_e32 v43, v39, v31
	v_fmac_f32_e32 v37, 0xb102e308, v30
	v_sub_f32_e32 v30, v42, v38
	v_sub_f32_e32 v38, v43, v39
	v_rcp_f32_e32 v39, v43
	v_add_f32_e32 v44, v41, v37
	v_sub_f32_e32 v31, v31, v38
	v_sub_f32_e32 v38, v44, v41
	v_sub_f32_e32 v37, v37, v38
	v_mul_f32_e32 v38, v42, v39
	v_sub_f32_e32 v30, v40, v30
	v_mul_f32_e32 v40, v43, v38
	v_fma_f32 v41, v38, v43, -v40
	v_fmac_f32_e32 v41, v38, v31
	v_add_f32_e32 v45, v40, v41
	v_sub_f32_e32 v46, v42, v45
	v_sub_f32_e32 v40, v45, v40
	v_sub_f32_e32 v42, v42, v46
	v_sub_f32_e32 v40, v40, v41
	v_sub_f32_e32 v41, v42, v45
	v_add_f32_e32 v30, v30, v41
	v_add_f32_e32 v30, v40, v30
	v_add_f32_e32 v40, v46, v30
	v_mul_f32_e32 v41, v39, v40
	v_sub_f32_e32 v42, v46, v40
	v_mul_f32_e32 v45, v43, v41
	v_add_f32_e32 v30, v30, v42
	v_add_f32_e32 v42, v38, v41
	v_fma_f32 v43, v41, v43, -v45
	v_sub_f32_e32 v38, v42, v38
	v_fmac_f32_e32 v43, v41, v31
	v_sub_f32_e32 v31, v41, v38
	v_add_f32_e32 v38, v45, v43
	v_sub_f32_e32 v41, v38, v45
	v_sub_f32_e32 v45, v40, v38
	v_sub_f32_e32 v40, v40, v45
	v_sub_f32_e32 v38, v40, v38
	v_sub_f32_e32 v41, v41, v43
	v_add_f32_e32 v30, v30, v38
	v_add_f32_e32 v30, v41, v30
	v_add_f32_e32 v30, v45, v30
	v_mul_f32_e32 v30, v39, v30
	v_add_f32_e32 v30, v31, v30
	v_add_f32_e32 v31, v42, v30
	v_mul_f32_e32 v38, v31, v31
	v_fmamk_f32 v41, v38, 0x3e9b6dac, v186
	v_sub_f32_e32 v39, v31, v42
	v_ldexp_f32 v40, v31, 1
	v_mul_f32_e32 v31, v31, v38
	v_fmaak_f32 v38, v38, v41, 0x3f2aaada
	v_mul_f32_e32 v31, v31, v38
	v_add_f32_e32 v38, v40, v31
	v_sub_f32_e32 v30, v30, v39
	v_sub_f32_e32 v39, v38, v40
	v_ldexp_f32 v30, v30, 1
	v_sub_f32_e32 v31, v31, v39
	v_add_f32_e32 v30, v30, v31
	v_add_f32_e32 v31, v38, v30
	v_sub_f32_e32 v38, v31, v38
	v_add_f32_e32 v39, v44, v31
	v_sub_f32_e32 v30, v30, v38
	v_sub_f32_e32 v38, v39, v44
	v_sub_f32_e32 v40, v39, v38
	v_sub_f32_e32 v31, v31, v38
	v_add_f32_e32 v38, v37, v30
	v_sub_f32_e32 v40, v44, v40
	v_sub_f32_e32 v41, v38, v37
	v_add_f32_e32 v31, v31, v40
	v_sub_f32_e32 v40, v38, v41
	v_sub_f32_e32 v30, v30, v41
	v_sub_f32_e32 v37, v37, v40
	v_add_f32_e32 v31, v38, v31
	v_add_f32_e32 v30, v30, v37
	v_add_f32_e32 v37, v39, v31
	v_sub_f32_e32 v38, v37, v39
	v_sub_f32_e32 v31, v31, v38
	v_add_f32_e32 v30, v30, v31
	v_add_f32_e32 v30, v37, v30
	v_cmp_neq_f32_e32 vcc, s67, v35
	s_nop 1
	v_cndmask_b32_e32 v30, v194, v30, vcc
	v_cmp_ngt_f32_e32 vcc, -1.0, v35
	s_nop 1
	v_cndmask_b32_e32 v30, v195, v30, vcc
	v_cmp_neq_f32_e32 vcc, -1.0, v35
	s_nop 1
	v_cndmask_b32_e32 v30, v196, v30, vcc
	v_cmp_lt_f32_e64 vcc, |v35|, s68
	s_nop 1
	v_cndmask_b32_e32 v30, v30, v35, vcc
	v_sub_f32_e32 v30, v36, v30
	global_store_dword v[28:29], v30, off offset:-28
	global_load_dword v30, v176, s[80:81] offset:-24
	s_waitcnt vmcnt(0)
	v_fmac_f32_e32 v30, v26, v34
	v_mul_f32_e64 v31, |v30|, s64
	v_exp_f32_e32 v35, v31
	v_min_f32_e32 v36, 0, v30
	v_add_f32_e32 v37, 1.0, v35
	v_add_f32_e32 v38, -1.0, v37
	v_frexp_mant_f32_e32 v39, v37
	v_cvt_f64_f32_e32 v[30:31], v37
	v_sub_f32_e32 v40, v38, v37
	v_frexp_exp_i32_f64_e32 v30, v[30:31]
	v_cmp_gt_f32_e32 vcc, s65, v39
	v_sub_f32_e32 v38, v35, v38
	v_add_f32_e32 v31, 1.0, v40
	v_subbrev_co_u32_e32 v30, vcc, 0, v30, vcc
	v_add_f32_e32 v31, v38, v31
	v_sub_u32_e32 v38, 0, v30
	v_cvt_f32_i32_e32 v30, v30
	v_ldexp_f32 v37, v37, v38
	v_ldexp_f32 v31, v31, v38
	v_add_f32_e32 v38, -1.0, v37
	v_add_f32_e32 v39, 1.0, v37
	v_add_f32_e32 v40, 1.0, v38
	v_add_f32_e32 v41, -1.0, v39
	v_sub_f32_e32 v40, v37, v40
	v_sub_f32_e32 v37, v37, v41
	v_mul_f32_e32 v41, 0x3f317218, v30
	v_add_f32_e32 v40, v31, v40
	v_add_f32_e32 v31, v31, v37
	v_fma_f32 v37, v30, s66, -v41
	v_add_f32_e32 v42, v38, v40
	v_add_f32_e32 v43, v39, v31
	v_fmac_f32_e32 v37, 0xb102e308, v30
	v_sub_f32_e32 v30, v42, v38
	v_sub_f32_e32 v38, v43, v39
	v_rcp_f32_e32 v39, v43
	v_add_f32_e32 v44, v41, v37
	v_sub_f32_e32 v31, v31, v38
	v_sub_f32_e32 v38, v44, v41
	v_sub_f32_e32 v37, v37, v38
	v_mul_f32_e32 v38, v42, v39
	v_sub_f32_e32 v30, v40, v30
	v_mul_f32_e32 v40, v43, v38
	v_fma_f32 v41, v38, v43, -v40
	v_fmac_f32_e32 v41, v38, v31
	v_add_f32_e32 v45, v40, v41
	v_sub_f32_e32 v46, v42, v45
	v_sub_f32_e32 v40, v45, v40
	v_sub_f32_e32 v42, v42, v46
	v_sub_f32_e32 v40, v40, v41
	v_sub_f32_e32 v41, v42, v45
	v_add_f32_e32 v30, v30, v41
	v_add_f32_e32 v30, v40, v30
	v_add_f32_e32 v40, v46, v30
	v_mul_f32_e32 v41, v39, v40
	v_sub_f32_e32 v42, v46, v40
	v_mul_f32_e32 v45, v43, v41
	v_add_f32_e32 v30, v30, v42
	v_add_f32_e32 v42, v38, v41
	v_fma_f32 v43, v41, v43, -v45
	v_sub_f32_e32 v38, v42, v38
	v_fmac_f32_e32 v43, v41, v31
	v_sub_f32_e32 v31, v41, v38
	v_add_f32_e32 v38, v45, v43
	v_sub_f32_e32 v41, v38, v45
	v_sub_f32_e32 v45, v40, v38
	v_sub_f32_e32 v40, v40, v45
	v_sub_f32_e32 v38, v40, v38
; DI float sigmoidf_(float x) { return 1.f / (1.f + __expf(-x)); }
; template <bool SWAP> DI void inproj_tile(const Params& p, int layer, int tm, int tn, bf16_t* smem) {
;     ...
;         for (int r = 0; r < 4; ++r) gt[quad * 4 + r] = sigmoidf_(acc[i][0][r] * rs);
;         if (quad < 2) {
; #pragma unroll
;           for (int r = 0; r < 4; ++r) gt[16 + quad * 4 + r] = sigmoidf_(acc[i][1][r] * rs);
;         } else {
; #pragma unroll
;           for (int r = 0; r < 4; ++r) { const int h = (quad - 2) * 4 + r; const float xx = acc[i][1][r] * rs + p.b_forget[layer * 8 + h]; lf[h] = fminf(xx, 0.f) - log1pf(__expf(-fabsf(xx))); }
;         }
	v_sub_f32_e32 v41, v41, v43
	v_add_f32_e32 v30, v30, v38
	v_add_f32_e32 v30, v41, v30
	v_add_f32_e32 v30, v45, v30
	v_mul_f32_e32 v30, v39, v30
	v_add_f32_e32 v30, v31, v30
	v_add_f32_e32 v31, v42, v30
	v_mul_f32_e32 v38, v31, v31
	v_fmamk_f32 v41, v38, 0x3e9b6dac, v186
	v_sub_f32_e32 v39, v31, v42
	v_ldexp_f32 v40, v31, 1
	v_mul_f32_e32 v31, v31, v38
	v_fmaak_f32 v38, v38, v41, 0x3f2aaada
	v_mul_f32_e32 v31, v31, v38
	v_add_f32_e32 v38, v40, v31
	v_sub_f32_e32 v30, v30, v39
	v_sub_f32_e32 v39, v38, v40
	v_ldexp_f32 v30, v30, 1
	v_sub_f32_e32 v31, v31, v39
	v_add_f32_e32 v30, v30, v31
	v_add_f32_e32 v31, v38, v30
	v_sub_f32_e32 v38, v31, v38
	v_add_f32_e32 v39, v44, v31
	v_sub_f32_e32 v30, v30, v38
	v_sub_f32_e32 v38, v39, v44
	v_sub_f32_e32 v40, v39, v38
	v_sub_f32_e32 v31, v31, v38
	v_add_f32_e32 v38, v37, v30
	v_sub_f32_e32 v40, v44, v40
	v_sub_f32_e32 v41, v38, v37
	v_add_f32_e32 v31, v31, v40
	v_sub_f32_e32 v40, v38, v41
	v_sub_f32_e32 v30, v30, v41
	v_sub_f32_e32 v37, v37, v40
	v_add_f32_e32 v31, v38, v31
	v_add_f32_e32 v30, v30, v37
	v_add_f32_e32 v37, v39, v31
	v_sub_f32_e32 v38, v37, v39
	v_sub_f32_e32 v31, v31, v38
	v_add_f32_e32 v30, v30, v31
	v_add_f32_e32 v30, v37, v30
	v_cmp_neq_f32_e32 vcc, s67, v35
	s_nop 1
	v_cndmask_b32_e32 v30, v194, v30, vcc
	v_cmp_ngt_f32_e32 vcc, -1.0, v35
	s_nop 1
	v_cndmask_b32_e32 v30, v195, v30, vcc
	v_cmp_neq_f32_e32 vcc, -1.0, v35
	s_nop 1
	v_cndmask_b32_e32 v30, v196, v30, vcc
	v_cmp_lt_f32_e64 vcc, |v35|, s68
	s_nop 1
	v_cndmask_b32_e32 v30, v30, v35, vcc
	v_sub_f32_e32 v30, v36, v30
	global_store_dword v[28:29], v30, off offset:-24
	global_load_dword v30, v176, s[80:81] offset:-20
	s_waitcnt vmcnt(0)
	v_fmac_f32_e32 v30, v27, v34
	v_mul_f32_e64 v31, |v30|, s64
	v_exp_f32_e32 v35, v31
	v_min_f32_e32 v36, 0, v30
	v_add_f32_e32 v37, 1.0, v35
	v_add_f32_e32 v38, -1.0, v37
	v_frexp_mant_f32_e32 v39, v37
	v_cvt_f64_f32_e32 v[30:31], v37
	v_sub_f32_e32 v40, v38, v37
	v_frexp_exp_i32_f64_e32 v30, v[30:31]
	v_cmp_gt_f32_e32 vcc, s65, v39
	v_sub_f32_e32 v38, v35, v38
	v_add_f32_e32 v31, 1.0, v40
	v_subbrev_co_u32_e32 v30, vcc, 0, v30, vcc
	v_add_f32_e32 v31, v38, v31
	v_sub_u32_e32 v38, 0, v30
	v_cvt_f32_i32_e32 v30, v30
	v_ldexp_f32 v37, v37, v38
	v_ldexp_f32 v31, v31, v38
	v_add_f32_e32 v38, -1.0, v37
	v_add_f32_e32 v39, 1.0, v37
	v_add_f32_e32 v40, 1.0, v38
	v_add_f32_e32 v41, -1.0, v39
	v_sub_f32_e32 v40, v37, v40
	v_sub_f32_e32 v37, v37, v41
	v_mul_f32_e32 v41, 0x3f317218, v30
	v_add_f32_e32 v40, v31, v40
	v_add_f32_e32 v31, v31, v37
	v_fma_f32 v37, v30, s66, -v41
	v_add_f32_e32 v42, v38, v40
	v_add_f32_e32 v43, v39, v31
	v_fmac_f32_e32 v37, 0xb102e308, v30
	v_sub_f32_e32 v30, v42, v38
	v_sub_f32_e32 v38, v43, v39
	v_rcp_f32_e32 v39, v43
	v_add_f32_e32 v44, v41, v37
	v_sub_f32_e32 v31, v31, v38
	v_sub_f32_e32 v38, v44, v41
	v_sub_f32_e32 v37, v37, v38
	v_mul_f32_e32 v38, v42, v39
	v_sub_f32_e32 v30, v40, v30
	v_mul_f32_e32 v40, v43, v38
	v_fma_f32 v41, v38, v43, -v40
	v_fmac_f32_e32 v41, v38, v31
	v_add_f32_e32 v45, v40, v41
	v_sub_f32_e32 v46, v42, v45
	v_sub_f32_e32 v40, v45, v40
	v_sub_f32_e32 v42, v42, v46
	v_sub_f32_e32 v40, v40, v41
	v_sub_f32_e32 v41, v42, v45
	v_add_f32_e32 v30, v30, v41
	v_add_f32_e32 v30, v40, v30
	v_add_f32_e32 v40, v46, v30
	v_mul_f32_e32 v41, v39, v40
	v_sub_f32_e32 v42, v46, v40
	v_mul_f32_e32 v45, v43, v41
	v_add_f32_e32 v30, v30, v42
	v_add_f32_e32 v42, v38, v41
	v_fma_f32 v43, v41, v43, -v45
	v_sub_f32_e32 v38, v42, v38
	v_fmac_f32_e32 v43, v41, v31
	v_sub_f32_e32 v31, v41, v38
	v_add_f32_e32 v38, v45, v43
	v_sub_f32_e32 v41, v38, v45
	v_sub_f32_e32 v45, v40, v38
	v_sub_f32_e32 v40, v40, v45
	v_sub_f32_e32 v38, v40, v38
	v_sub_f32_e32 v41, v41, v43
	v_add_f32_e32 v30, v30, v38
	v_add_f32_e32 v30, v41, v30
	v_add_f32_e32 v30, v45, v30
	v_mul_f32_e32 v30, v39, v30
	v_add_f32_e32 v30, v31, v30
	v_add_f32_e32 v31, v42, v30
	v_mul_f32_e32 v38, v31, v31
	v_fmamk_f32 v41, v38, 0x3e9b6dac, v186
	v_sub_f32_e32 v39, v31, v42
	v_ldexp_f32 v40, v31, 1
	v_mul_f32_e32 v31, v31, v38
	v_fmaak_f32 v38, v38, v41, 0x3f2aaada
	v_mul_f32_e32 v31, v31, v38
	v_add_f32_e32 v38, v40, v31
	v_sub_f32_e32 v30, v30, v39
	v_sub_f32_e32 v39, v38, v40
	v_ldexp_f32 v30, v30, 1
	v_sub_f32_e32 v31, v31, v39
	v_add_f32_e32 v30, v30, v31
	v_add_f32_e32 v31, v38, v30
	v_sub_f32_e32 v38, v31, v38
	v_add_f32_e32 v39, v44, v31
	v_sub_f32_e32 v30, v30, v38
	v_sub_f32_e32 v38, v39, v44
	v_sub_f32_e32 v40, v39, v38
	v_sub_f32_e32 v31, v31, v38
	v_add_f32_e32 v38, v37, v30
	v_sub_f32_e32 v40, v44, v40
	v_sub_f32_e32 v41, v38, v37
	v_add_f32_e32 v31, v31, v40
	v_sub_f32_e32 v40, v38, v41
	v_sub_f32_e32 v30, v30, v41
	v_sub_f32_e32 v37, v37, v40
	v_add_f32_e32 v31, v38, v31
	v_add_f32_e32 v30, v30, v37
	v_add_f32_e32 v37, v39, v31
	v_sub_f32_e32 v38, v37, v39
	v_sub_f32_e32 v31, v31, v38
	v_add_f32_e32 v30, v30, v31
	v_add_f32_e32 v30, v37, v30
	v_cmp_neq_f32_e32 vcc, s67, v35
	s_nop 1
	v_cndmask_b32_e32 v30, v194, v30, vcc
	v_cmp_ngt_f32_e32 vcc, -1.0, v35
	s_nop 1
	v_cndmask_b32_e32 v30, v195, v30, vcc
	v_cmp_neq_f32_e32 vcc, -1.0, v35
	s_nop 1
	v_cndmask_b32_e32 v30, v196, v30, vcc
	v_cmp_lt_f32_e64 vcc, |v35|, s68
	s_nop 1
	v_cndmask_b32_e32 v30, v30, v35, vcc
	v_sub_f32_e32 v30, v36, v30
	global_store_dword v[28:29], v30, off offset:-20
.LBB0_287:
	s_andn2_saveexec_b64 s[0:1], s[0:1]
	s_cbranch_execz .LBB0_289
	v_mul_f32_e32 v24, v24, v34
	v_mul_f32_e32 v25, v25, v34
	v_mul_f32_e32 v24, 0xbfb8aa3b, v24
	v_mul_f32_e32 v25, 0xbfb8aa3b, v25
	v_exp_f32_e32 v24, v24
	v_exp_f32_e32 v25, v25
	v_mul_f32_e32 v26, v26, v34
	v_mul_f32_e32 v27, v27, v34
	v_mul_f32_e32 v26, 0xbfb8aa3b, v26
	v_pk_add_f32 v[24:25], v[24:25], 1.0 op_sel_hi:[1,0]
	v_mul_f32_e32 v27, 0xbfb8aa3b, v27
	v_exp_f32_e32 v26, v26
	v_rcp_f32_e32 v25, v25
	v_exp_f32_e32 v27, v27
	s_nop 0
	v_pk_add_f32 v[26:27], v[26:27], 1.0 op_sel_hi:[1,0]
	v_rcp_f32_e32 v24, v24
	v_rcp_f32_e32 v27, v27
	v_rcp_f32_e32 v26, v26
	global_store_dwordx4 v[36:37], v[24:27], off offset:64
; DI unsigned pk2(float lo, float hi) { f32x2 v = {lo, hi}; return __builtin_bit_cast(unsigned, __builtin_convertvector(v, bfx2)); }
; DI float sigmoidf_(float x) { return 1.f / (1.f + __expf(-x)); }
; template <bool SWAP> DI void inproj_tile(const Params& p, int layer, int tm, int tn, bf16_t* smem) {
;     ...
;         const int t = trow0 + i * 16 + l15; const float rs = rstd_from16(ssq + (size_t)t * 16, 1.f / 1024.f);
;         float* gt = (float*)(p.ws + O_GATES) + (size_t)t * 24; float* lf = (float*)(p.ws + O_LOGF) + (size_t)t * 8;
; #pragma unroll
;         for (int r = 0; r < 4; ++r) gt[quad * 4 + r] = sigmoidf_(acc[i][0][r] * rs);
;         if (quad < 2) {
; #pragma unroll
;           for (int r = 0; r < 4; ++r) gt[16 + quad * 4 + r] = sigmoidf_(acc[i][1][r] * rs);
;         } else {
; #pragma unroll
;           for (int r = 0; r < 4; ++r) { const int h = (quad - 2) * 4 + r; const float xx = acc[i][1][r] * rs + p.b_forget[layer * 8 + h]; lf[h] = fminf(xx, 0.f) - log1pf(__expf(-fabsf(xx))); }
;         }
;         const float* rp = (const float*)(p.ws + O_ROPE16) + (size_t)t * 32 + quad * 8; float o1[4], o2[4];
; #pragma unroll
;         for (int r = 0; r < 4; ++r) { const float cs = rp[2 * r], sn = rp[2 * r + 1], x1 = acc[i][2][r] * rs, x2 = acc[i][3][r] * rs; o1[r] = x1 * cs - x2 * sn; o2[r] = x2 * cs + x1 * sn; }
;         bf16_t* kp = (bf16_t*)(p.ws + O_MLAKPE) + (size_t)t * 32 + quad * 4;
;         *(u32x2*)kp = (u32x2){pk2(o1[0], o1[1]), pk2(o1[2], o1[3])}; *(u32x2*)(kp + 16) = (u32x2){pk2(o2[0], o2[1]), pk2(o2[2], o2[3])};
.LBB0_289:
	s_or_b64 exec, exec, s[0:1]
	s_nop 0
	v_lshl_add_u64 v[24:25], v[32:33], 2, s[14:15]
	v_mov_b32_e32 v105, v177
	v_lshl_add_u64 v[28:29], v[24:25], 0, v[104:105]
	global_load_dwordx4 v[24:27], v[28:29], off
	s_nop 0
	global_load_dwordx4 v[28:31], v[28:29], off offset:16
	v_or_b32_e32 v52, 0x70, v128
	v_ashrrev_i32_e32 v53, 31, v52
	v_lshlrev_b64 v[36:37], 6, v[52:53]
	v_lshl_add_u64 v[48:49], s[8:9], 0, v[36:37]
	global_load_dwordx4 v[36:39], v[48:49], off
	global_load_dwordx4 v[40:43], v[48:49], off offset:16
	global_load_dwordx4 v[44:47], v[48:49], off offset:32
	s_nop 0
	global_load_dwordx4 v[48:51], v[48:49], off offset:48
	v_pk_mul_f32 v[54:55], v[16:17], v[34:35] op_sel_hi:[1,0]
	v_pk_mul_f32 v[56:57], v[20:21], v[34:35] op_sel_hi:[1,0]
	v_pk_mul_f32 v[18:19], v[18:19], v[34:35] op_sel_hi:[1,0]
	v_pk_mul_f32 v[22:23], v[22:23], v[34:35] op_sel_hi:[1,0]
	v_lshl_add_u64 v[16:17], v[32:33], 1, s[16:17]
	v_mov_b32_e32 v113, v177
	v_mov_b64_e32 v[20:21], s[10:11]
	v_lshl_add_u64 v[32:33], v[16:17], 0, v[112:113]
	v_mad_i64_i32 v[20:21], s[0:1], v52, s63, v[20:21]
	v_lshlrev_b64 v[16:17], 5, v[52:53]
	v_lshl_add_u64 v[20:21], v[20:21], 0, v[176:177]
	s_waitcnt vmcnt(5)
	v_mov_b32_e32 v35, v26
	v_mov_b32_e32 v26, v25
	s_waitcnt vmcnt(4)
	v_mov_b32_e32 v25, v30
	v_mov_b32_e32 v30, v29
	v_mov_b32_e32 v34, v24
	v_mov_b32_e32 v24, v28
	v_pk_mul_f32 v[52:53], v[18:19], v[30:31]
	v_pk_mul_f32 v[30:31], v[22:23], v[30:31]
	v_pk_fma_f32 v[22:23], v[22:23], v[24:25], v[52:53] neg_lo:[0,0,1] neg_hi:[0,0,1]
	v_pk_fma_f32 v[18:19], v[18:19], v[24:25], v[30:31]
	s_waitcnt vmcnt(3)
	v_mov_b32_e32 v24, v37
	v_mov_b32_e32 v25, v38
	v_mov_b32_e32 v37, v39
	s_waitcnt vmcnt(2)
	v_mov_b32_e32 v30, v41
	v_mov_b32_e32 v31, v42
	v_mov_b32_e32 v41, v43
	v_pk_add_f32 v[24:25], v[24:25], v[36:37]
	v_pk_add_f32 v[30:31], v[30:31], v[40:41]
	v_pk_mul_f32 v[28:29], v[54:55], v[26:27]
	v_pk_mul_f32 v[26:27], v[56:57], v[26:27]
	v_pk_add_f32 v[24:25], v[24:25], v[24:25] op_sel:[0,1] op_sel_hi:[1,0]
	v_pk_add_f32 v[30:31], v[30:31], v[30:31] op_sel:[0,1] op_sel_hi:[1,0]
	v_pk_fma_f32 v[28:29], v[56:57], v[34:35], v[28:29] neg_lo:[0,0,1] neg_hi:[0,0,1]
	v_pk_fma_f32 v[26:27], v[54:55], v[34:35], v[26:27]
	s_waitcnt vmcnt(1)
	v_add_f32_e32 v34, v44, v45
	v_add_f32_e32 v38, v46, v47
	s_waitcnt vmcnt(0)
	v_mov_b32_e32 v35, v50
	v_mov_b32_e32 v39, v51
	v_mov_b32_e32 v25, v48
	v_mov_b32_e32 v31, v49
	v_pk_add_f32 v[34:35], v[34:35], v[38:39]
	v_pk_add_f32 v[24:25], v[24:25], v[30:31]
	v_cvt_pk_bf16_f32 v28, v28, v29
	v_pk_add_f32 v[24:25], v[24:25], v[34:35]
	v_cvt_pk_bf16_f32 v29, v22, v23
	v_add_f32_e32 v24, v24, v25
	v_fmamk_f32 v24, v24, 0x3a800000, v185
	v_mul_f32_e32 v25, 0x4b800000, v24
	v_cmp_gt_f32_e32 vcc, s60, v24
	v_cvt_pk_bf16_f32 v23, v18, v19
	v_cvt_pk_bf16_f32 v22, v26, v27
	v_cndmask_b32_e32 v24, v24, v25, vcc
	v_rsq_f32_e32 v24, v24
	global_store_dwordx2 v[32:33], v[28:29], off
	global_store_dwordx2 v[32:33], v[22:23], off offset:32
	v_mul_f32_e32 v18, 0x45800000, v24
	v_cndmask_b32_e32 v18, v24, v18, vcc
	v_mul_f32_e32 v12, v12, v18
	v_mul_f32_e32 v13, v13, v18
	v_mul_f32_e32 v12, 0xbfb8aa3b, v12
	v_mul_f32_e32 v13, 0xbfb8aa3b, v13
	v_mul_f32_e32 v14, v14, v18
	v_mul_f32_e32 v15, v15, v18
	v_exp_f32_e32 v12, v12
	v_exp_f32_e32 v13, v13
	v_mul_f32_e32 v14, 0xbfb8aa3b, v14
	v_mul_f32_e32 v15, 0xbfb8aa3b, v15
	v_exp_f32_e32 v14, v14
	v_exp_f32_e32 v15, v15
	v_pk_add_f32 v[12:13], v[12:13], 1.0 op_sel_hi:[1,0]
	v_pk_add_f32 v[14:15], v[14:15], 1.0 op_sel_hi:[1,0]
	v_div_scale_f32 v23, s[0:1], v12, v12, 1.0
	v_div_scale_f32 v25, s[4:5], v15, v15, 1.0
	v_rcp_f32_e32 v27, v23
	v_rcp_f32_e32 v28, v25
	v_fma_f32 v31, -v23, v27, 1.0
	v_div_scale_f32 v24, s[0:1], 1.0, v12, 1.0
	v_fma_f32 v32, -v25, v28, 1.0
	v_fmac_f32_e32 v27, v31, v27
	v_fmac_f32_e32 v28, v32, v28
	v_mul_f32_e32 v31, v24, v27
	v_fma_f32 v33, -v23, v31, v24
	v_fmac_f32_e32 v31, v33, v27
	v_fma_f32 v22, -v23, v31, v24
	s_mov_b64 vcc, s[0:1]
	v_div_scale_f32 v29, s[4:5], 1.0, v15, 1.0
	v_rcp_f32_e32 v13, v13
	v_div_fmas_f32 v19, v22, v27, v31
	v_div_fixup_f32 v12, v19, v12, 1.0
	v_mul_f32_e32 v19, v29, v28
	v_fma_f32 v22, -v25, v19, v29
	v_fmac_f32_e32 v19, v22, v28
	v_fma_f32 v22, -v25, v19, v29
	s_mov_b64 vcc, s[4:5]
	v_div_fmas_f32 v19, v22, v28, v19
	v_div_fixup_f32 v15, v19, v15, 1.0
	v_rcp_f32_e32 v14, v14
	global_store_dwordx4 v[20:21], v[12:15], off
	s_and_saveexec_b64 s[0:1], s[2:3]
	s_xor_b64 s[0:1], exec, s[0:1]
	s_cbranch_execz .LBB0_291
; template <bool SWAP> DI void inproj_tile(const Params& p, int layer, int tm, int tn, bf16_t* smem) {
;     ...
;         } else {
; #pragma unroll
;           for (int r = 0; r < 4; ++r) { const int h = (quad - 2) * 4 + r; const float xx = acc[i][1][r] * rs + p.b_forget[layer * 8 + h]; lf[h] = fminf(xx, 0.f) - log1pf(__expf(-fabsf(xx))); }
;         }
	v_readlane_b32 s72, v241, 8
	v_readlane_b32 s80, v241, 16
	v_readlane_b32 s81, v241, 17
	v_readlane_b32 s73, v241, 9
	v_readlane_b32 s74, v241, 10
	v_readlane_b32 s75, v241, 11
	v_readlane_b32 s76, v241, 12
	v_readlane_b32 s77, v241, 13
	global_load_dword v14, v176, s[80:81] offset:-32
	v_readlane_b32 s78, v241, 14
	v_readlane_b32 s79, v241, 15
	v_readlane_b32 s82, v241, 18
	v_readlane_b32 s83, v241, 19
	v_readlane_b32 s84, v241, 20
	v_readlane_b32 s85, v241, 21
	v_readlane_b32 s86, v241, 22
	v_readlane_b32 s87, v241, 23
	s_waitcnt vmcnt(0)
	v_fmac_f32_e32 v14, v8, v18
	v_mul_f32_e64 v12, |v14|, s64
	v_exp_f32_e32 v19, v12
	v_min_f32_e32 v20, 0, v14
	v_lshl_add_u64 v[12:13], s[12:13], 0, v[16:17]
	v_lshl_add_u64 v[12:13], v[12:13], 0, v[176:177]
	v_add_f32_e32 v21, 1.0, v19
	v_add_f32_e32 v22, -1.0, v21
	v_frexp_mant_f32_e32 v23, v21
	v_cvt_f64_f32_e32 v[14:15], v21
	v_sub_f32_e32 v24, v22, v21
	v_frexp_exp_i32_f64_e32 v14, v[14:15]
	v_cmp_gt_f32_e32 vcc, s65, v23
	v_sub_f32_e32 v22, v19, v22
	v_add_f32_e32 v15, 1.0, v24
	v_subbrev_co_u32_e32 v14, vcc, 0, v14, vcc
	v_add_f32_e32 v15, v22, v15
	v_sub_u32_e32 v22, 0, v14
	v_cvt_f32_i32_e32 v14, v14
	v_ldexp_f32 v21, v21, v22
	v_ldexp_f32 v15, v15, v22
	v_add_f32_e32 v22, -1.0, v21
	v_add_f32_e32 v23, 1.0, v21
	v_add_f32_e32 v24, 1.0, v22
	v_add_f32_e32 v25, -1.0, v23
	v_sub_f32_e32 v24, v21, v24
	v_sub_f32_e32 v21, v21, v25
	v_mul_f32_e32 v25, 0x3f317218, v14
	v_add_f32_e32 v24, v15, v24
	v_add_f32_e32 v15, v15, v21
	v_fma_f32 v21, v14, s66, -v25
	v_add_f32_e32 v26, v22, v24
	v_add_f32_e32 v27, v23, v15
	v_fmac_f32_e32 v21, 0xb102e308, v14
	v_sub_f32_e32 v14, v26, v22
	v_sub_f32_e32 v22, v27, v23
	v_rcp_f32_e32 v23, v27
	v_add_f32_e32 v28, v25, v21
	v_sub_f32_e32 v15, v15, v22
	v_sub_f32_e32 v22, v28, v25
	v_sub_f32_e32 v21, v21, v22
	v_mul_f32_e32 v22, v26, v23
	v_sub_f32_e32 v14, v24, v14
	v_mul_f32_e32 v24, v27, v22
	v_fma_f32 v25, v22, v27, -v24
	v_fmac_f32_e32 v25, v22, v15
	v_add_f32_e32 v29, v24, v25
	v_sub_f32_e32 v30, v26, v29
	v_sub_f32_e32 v24, v29, v24
	v_sub_f32_e32 v26, v26, v30
	v_sub_f32_e32 v24, v24, v25
	v_sub_f32_e32 v25, v26, v29
	v_add_f32_e32 v14, v14, v25
	v_add_f32_e32 v14, v24, v14
	v_add_f32_e32 v24, v30, v14
	v_mul_f32_e32 v25, v23, v24
	v_sub_f32_e32 v26, v30, v24
	v_mul_f32_e32 v29, v27, v25
	v_add_f32_e32 v14, v14, v26
	v_add_f32_e32 v26, v22, v25
	v_fma_f32 v27, v25, v27, -v29
	v_sub_f32_e32 v22, v26, v22
	v_fmac_f32_e32 v27, v25, v15
	v_sub_f32_e32 v15, v25, v22
	v_add_f32_e32 v22, v29, v27
	v_sub_f32_e32 v25, v22, v29
	v_sub_f32_e32 v29, v24, v22
	v_sub_f32_e32 v24, v24, v29
	v_sub_f32_e32 v22, v24, v22
	v_sub_f32_e32 v25, v25, v27
	v_add_f32_e32 v14, v14, v22
	v_add_f32_e32 v14, v25, v14
	v_add_f32_e32 v14, v29, v14
	v_mul_f32_e32 v14, v23, v14
	v_add_f32_e32 v14, v15, v14
	v_add_f32_e32 v15, v26, v14
	v_mul_f32_e32 v22, v15, v15
	v_fmamk_f32 v25, v22, 0x3e9b6dac, v186
	v_sub_f32_e32 v23, v15, v26
	v_ldexp_f32 v24, v15, 1
	v_mul_f32_e32 v15, v15, v22
	v_fmaak_f32 v22, v22, v25, 0x3f2aaada
	v_mul_f32_e32 v15, v15, v22
	v_add_f32_e32 v22, v24, v15
	v_sub_f32_e32 v14, v14, v23
	v_sub_f32_e32 v23, v22, v24
	v_ldexp_f32 v14, v14, 1
	v_sub_f32_e32 v15, v15, v23
	v_add_f32_e32 v14, v14, v15
	v_add_f32_e32 v15, v22, v14
	v_sub_f32_e32 v22, v15, v22
	v_add_f32_e32 v23, v28, v15
	v_sub_f32_e32 v14, v14, v22
	v_sub_f32_e32 v22, v23, v28
	v_sub_f32_e32 v24, v23, v22
	v_sub_f32_e32 v15, v15, v22
	v_add_f32_e32 v22, v21, v14
	v_sub_f32_e32 v24, v28, v24
	v_sub_f32_e32 v25, v22, v21
	v_add_f32_e32 v15, v15, v24
	v_sub_f32_e32 v24, v22, v25
	v_sub_f32_e32 v14, v14, v25
	v_sub_f32_e32 v21, v21, v24
	v_add_f32_e32 v15, v22, v15
	v_add_f32_e32 v14, v14, v21
	v_add_f32_e32 v21, v23, v15
	v_sub_f32_e32 v22, v21, v23
	v_sub_f32_e32 v15, v15, v22
	v_add_f32_e32 v14, v14, v15
	v_add_f32_e32 v14, v21, v14
	v_cmp_neq_f32_e32 vcc, s67, v19
	s_nop 1
	v_cndmask_b32_e32 v14, v194, v14, vcc
	v_cmp_ngt_f32_e32 vcc, -1.0, v19
	s_nop 1
	v_cndmask_b32_e32 v14, v195, v14, vcc
	v_cmp_neq_f32_e32 vcc, -1.0, v19
	s_nop 1
	v_cndmask_b32_e32 v14, v196, v14, vcc
	v_cmp_lt_f32_e64 vcc, |v19|, s68
	s_nop 1
	v_cndmask_b32_e32 v14, v14, v19, vcc
	v_sub_f32_e32 v14, v20, v14
	global_store_dword v[12:13], v14, off offset:-32
	global_load_dword v14, v176, s[80:81] offset:-28
	s_waitcnt vmcnt(0)
; template <bool SWAP> DI void inproj_tile(const Params& p, int layer, int tm, int tn, bf16_t* smem) {
;     ...
;         } else {
; #pragma unroll
;           for (int r = 0; r < 4; ++r) { const int h = (quad - 2) * 4 + r; const float xx = acc[i][1][r] * rs + p.b_forget[layer * 8 + h]; lf[h] = fminf(xx, 0.f) - log1pf(__expf(-fabsf(xx))); }
;         }
	v_fmac_f32_e32 v14, v9, v18
	v_mul_f32_e64 v15, |v14|, s64
	v_exp_f32_e32 v19, v15
	v_min_f32_e32 v20, 0, v14
	v_add_f32_e32 v21, 1.0, v19
	v_add_f32_e32 v22, -1.0, v21
	v_frexp_mant_f32_e32 v23, v21
	v_cvt_f64_f32_e32 v[14:15], v21
	v_sub_f32_e32 v24, v22, v21
	v_frexp_exp_i32_f64_e32 v14, v[14:15]
	v_cmp_gt_f32_e32 vcc, s65, v23
	v_sub_f32_e32 v22, v19, v22
	v_add_f32_e32 v15, 1.0, v24
	v_subbrev_co_u32_e32 v14, vcc, 0, v14, vcc
	v_add_f32_e32 v15, v22, v15
	v_sub_u32_e32 v22, 0, v14
	v_cvt_f32_i32_e32 v14, v14
	v_ldexp_f32 v21, v21, v22
	v_ldexp_f32 v15, v15, v22
	v_add_f32_e32 v22, -1.0, v21
	v_add_f32_e32 v23, 1.0, v21
	v_add_f32_e32 v24, 1.0, v22
	v_add_f32_e32 v25, -1.0, v23
	v_sub_f32_e32 v24, v21, v24
	v_sub_f32_e32 v21, v21, v25
	v_mul_f32_e32 v25, 0x3f317218, v14
	v_add_f32_e32 v24, v15, v24
	v_add_f32_e32 v15, v15, v21
	v_fma_f32 v21, v14, s66, -v25
	v_add_f32_e32 v26, v22, v24
	v_add_f32_e32 v27, v23, v15
	v_fmac_f32_e32 v21, 0xb102e308, v14
	v_sub_f32_e32 v14, v26, v22
	v_sub_f32_e32 v22, v27, v23
	v_rcp_f32_e32 v23, v27
	v_add_f32_e32 v28, v25, v21
	v_sub_f32_e32 v15, v15, v22
	v_sub_f32_e32 v22, v28, v25
	v_sub_f32_e32 v21, v21, v22
	v_mul_f32_e32 v22, v26, v23
	v_sub_f32_e32 v14, v24, v14
	v_mul_f32_e32 v24, v27, v22
	v_fma_f32 v25, v22, v27, -v24
	v_fmac_f32_e32 v25, v22, v15
	v_add_f32_e32 v29, v24, v25
	v_sub_f32_e32 v30, v26, v29
	v_sub_f32_e32 v24, v29, v24
	v_sub_f32_e32 v26, v26, v30
	v_sub_f32_e32 v24, v24, v25
	v_sub_f32_e32 v25, v26, v29
	v_add_f32_e32 v14, v14, v25
	v_add_f32_e32 v14, v24, v14
	v_add_f32_e32 v24, v30, v14
	v_mul_f32_e32 v25, v23, v24
	v_sub_f32_e32 v26, v30, v24
	v_mul_f32_e32 v29, v27, v25
	v_add_f32_e32 v14, v14, v26
	v_add_f32_e32 v26, v22, v25
	v_fma_f32 v27, v25, v27, -v29
	v_sub_f32_e32 v22, v26, v22
	v_fmac_f32_e32 v27, v25, v15
	v_sub_f32_e32 v15, v25, v22
	v_add_f32_e32 v22, v29, v27
	v_sub_f32_e32 v25, v22, v29
	v_sub_f32_e32 v29, v24, v22
	v_sub_f32_e32 v24, v24, v29
	v_sub_f32_e32 v22, v24, v22
	v_sub_f32_e32 v25, v25, v27
	v_add_f32_e32 v14, v14, v22
	v_add_f32_e32 v14, v25, v14
	v_add_f32_e32 v14, v29, v14
	v_mul_f32_e32 v14, v23, v14
	v_add_f32_e32 v14, v15, v14
	v_add_f32_e32 v15, v26, v14
	v_mul_f32_e32 v22, v15, v15
	v_fmamk_f32 v25, v22, 0x3e9b6dac, v186
	v_sub_f32_e32 v23, v15, v26
	v_ldexp_f32 v24, v15, 1
	v_mul_f32_e32 v15, v15, v22
	v_fmaak_f32 v22, v22, v25, 0x3f2aaada
	v_mul_f32_e32 v15, v15, v22
	v_add_f32_e32 v22, v24, v15
	v_sub_f32_e32 v14, v14, v23
	v_sub_f32_e32 v23, v22, v24
	v_ldexp_f32 v14, v14, 1
	v_sub_f32_e32 v15, v15, v23
	v_add_f32_e32 v14, v14, v15
	v_add_f32_e32 v15, v22, v14
	v_sub_f32_e32 v22, v15, v22
	v_add_f32_e32 v23, v28, v15
	v_sub_f32_e32 v14, v14, v22
	v_sub_f32_e32 v22, v23, v28
	v_sub_f32_e32 v24, v23, v22
	v_sub_f32_e32 v15, v15, v22
	v_add_f32_e32 v22, v21, v14
	v_sub_f32_e32 v24, v28, v24
	v_sub_f32_e32 v25, v22, v21
	v_add_f32_e32 v15, v15, v24
	v_sub_f32_e32 v24, v22, v25
	v_sub_f32_e32 v14, v14, v25
	v_sub_f32_e32 v21, v21, v24
	v_add_f32_e32 v15, v22, v15
	v_add_f32_e32 v14, v14, v21
	v_add_f32_e32 v21, v23, v15
	v_sub_f32_e32 v22, v21, v23
	v_sub_f32_e32 v15, v15, v22
	v_add_f32_e32 v14, v14, v15
	v_add_f32_e32 v14, v21, v14
	v_cmp_neq_f32_e32 vcc, s67, v19
	s_nop 1
	v_cndmask_b32_e32 v14, v194, v14, vcc
	v_cmp_ngt_f32_e32 vcc, -1.0, v19
	s_nop 1
	v_cndmask_b32_e32 v14, v195, v14, vcc
	v_cmp_neq_f32_e32 vcc, -1.0, v19
	s_nop 1
	v_cndmask_b32_e32 v14, v196, v14, vcc
	v_cmp_lt_f32_e64 vcc, |v19|, s68
	s_nop 1
	v_cndmask_b32_e32 v14, v14, v19, vcc
	v_sub_f32_e32 v14, v20, v14
	global_store_dword v[12:13], v14, off offset:-28
	global_load_dword v14, v176, s[80:81] offset:-24
	s_waitcnt vmcnt(0)
	v_fmac_f32_e32 v14, v10, v18
	v_mul_f32_e64 v15, |v14|, s64
	v_exp_f32_e32 v19, v15
	v_min_f32_e32 v20, 0, v14
	v_add_f32_e32 v21, 1.0, v19
	v_add_f32_e32 v22, -1.0, v21
	v_frexp_mant_f32_e32 v23, v21
	v_cvt_f64_f32_e32 v[14:15], v21
	v_sub_f32_e32 v24, v22, v21
	v_frexp_exp_i32_f64_e32 v14, v[14:15]
	v_cmp_gt_f32_e32 vcc, s65, v23
	v_sub_f32_e32 v22, v19, v22
	v_add_f32_e32 v15, 1.0, v24
	v_subbrev_co_u32_e32 v14, vcc, 0, v14, vcc
	v_add_f32_e32 v15, v22, v15
	v_sub_u32_e32 v22, 0, v14
	v_cvt_f32_i32_e32 v14, v14
	v_ldexp_f32 v21, v21, v22
	v_ldexp_f32 v15, v15, v22
	v_add_f32_e32 v22, -1.0, v21
	v_add_f32_e32 v23, 1.0, v21
	v_add_f32_e32 v24, 1.0, v22
	v_add_f32_e32 v25, -1.0, v23
	v_sub_f32_e32 v24, v21, v24
	v_sub_f32_e32 v21, v21, v25
	v_mul_f32_e32 v25, 0x3f317218, v14
	v_add_f32_e32 v24, v15, v24
	v_add_f32_e32 v15, v15, v21
	v_fma_f32 v21, v14, s66, -v25
	v_add_f32_e32 v26, v22, v24
	v_add_f32_e32 v27, v23, v15
	v_fmac_f32_e32 v21, 0xb102e308, v14
	v_sub_f32_e32 v14, v26, v22
	v_sub_f32_e32 v22, v27, v23
	v_rcp_f32_e32 v23, v27
	v_add_f32_e32 v28, v25, v21
	v_sub_f32_e32 v15, v15, v22
	v_sub_f32_e32 v22, v28, v25
	v_sub_f32_e32 v21, v21, v22
	v_mul_f32_e32 v22, v26, v23
	v_sub_f32_e32 v14, v24, v14
	v_mul_f32_e32 v24, v27, v22
	v_fma_f32 v25, v22, v27, -v24
	v_fmac_f32_e32 v25, v22, v15
	v_add_f32_e32 v29, v24, v25
	v_sub_f32_e32 v30, v26, v29
	v_sub_f32_e32 v24, v29, v24
	v_sub_f32_e32 v26, v26, v30
	v_sub_f32_e32 v24, v24, v25
	v_sub_f32_e32 v25, v26, v29
	v_add_f32_e32 v14, v14, v25
	v_add_f32_e32 v14, v24, v14
	v_add_f32_e32 v24, v30, v14
	v_mul_f32_e32 v25, v23, v24
	v_sub_f32_e32 v26, v30, v24
	v_mul_f32_e32 v29, v27, v25
	v_add_f32_e32 v14, v14, v26
	v_add_f32_e32 v26, v22, v25
	v_fma_f32 v27, v25, v27, -v29
	v_sub_f32_e32 v22, v26, v22
	v_fmac_f32_e32 v27, v25, v15
	v_sub_f32_e32 v15, v25, v22
	v_add_f32_e32 v22, v29, v27
	v_sub_f32_e32 v25, v22, v29
	v_sub_f32_e32 v29, v24, v22
	v_sub_f32_e32 v24, v24, v29
	v_sub_f32_e32 v22, v24, v22
; DI float sigmoidf_(float x) { return 1.f / (1.f + __expf(-x)); }
; template <bool SWAP> DI void inproj_tile(const Params& p, int layer, int tm, int tn, bf16_t* smem) {
;     ...
;         for (int r = 0; r < 4; ++r) gt[quad * 4 + r] = sigmoidf_(acc[i][0][r] * rs);
;         if (quad < 2) {
; #pragma unroll
;           for (int r = 0; r < 4; ++r) gt[16 + quad * 4 + r] = sigmoidf_(acc[i][1][r] * rs);
;         } else {
; #pragma unroll
;           for (int r = 0; r < 4; ++r) { const int h = (quad - 2) * 4 + r; const float xx = acc[i][1][r] * rs + p.b_forget[layer * 8 + h]; lf[h] = fminf(xx, 0.f) - log1pf(__expf(-fabsf(xx))); }
;         }
	v_sub_f32_e32 v25, v25, v27
	v_add_f32_e32 v14, v14, v22
	v_add_f32_e32 v14, v25, v14
	v_add_f32_e32 v14, v29, v14
	v_mul_f32_e32 v14, v23, v14
	v_add_f32_e32 v14, v15, v14
	v_add_f32_e32 v15, v26, v14
	v_mul_f32_e32 v22, v15, v15
	v_fmamk_f32 v25, v22, 0x3e9b6dac, v186
	v_sub_f32_e32 v23, v15, v26
	v_ldexp_f32 v24, v15, 1
	v_mul_f32_e32 v15, v15, v22
	v_fmaak_f32 v22, v22, v25, 0x3f2aaada
	v_mul_f32_e32 v15, v15, v22
	v_add_f32_e32 v22, v24, v15
	v_sub_f32_e32 v14, v14, v23
	v_sub_f32_e32 v23, v22, v24
	v_ldexp_f32 v14, v14, 1
	v_sub_f32_e32 v15, v15, v23
	v_add_f32_e32 v14, v14, v15
	v_add_f32_e32 v15, v22, v14
	v_sub_f32_e32 v22, v15, v22
	v_add_f32_e32 v23, v28, v15
	v_sub_f32_e32 v14, v14, v22
	v_sub_f32_e32 v22, v23, v28
	v_sub_f32_e32 v24, v23, v22
	v_sub_f32_e32 v15, v15, v22
	v_add_f32_e32 v22, v21, v14
	v_sub_f32_e32 v24, v28, v24
	v_sub_f32_e32 v25, v22, v21
	v_add_f32_e32 v15, v15, v24
	v_sub_f32_e32 v24, v22, v25
	v_sub_f32_e32 v14, v14, v25
	v_sub_f32_e32 v21, v21, v24
	v_add_f32_e32 v15, v22, v15
	v_add_f32_e32 v14, v14, v21
	v_add_f32_e32 v21, v23, v15
	v_sub_f32_e32 v22, v21, v23
	v_sub_f32_e32 v15, v15, v22
	v_add_f32_e32 v14, v14, v15
	v_add_f32_e32 v14, v21, v14
	v_cmp_neq_f32_e32 vcc, s67, v19
	s_nop 1
	v_cndmask_b32_e32 v14, v194, v14, vcc
	v_cmp_ngt_f32_e32 vcc, -1.0, v19
	s_nop 1
	v_cndmask_b32_e32 v14, v195, v14, vcc
	v_cmp_neq_f32_e32 vcc, -1.0, v19
	s_nop 1
	v_cndmask_b32_e32 v14, v196, v14, vcc
	v_cmp_lt_f32_e64 vcc, |v19|, s68
	s_nop 1
	v_cndmask_b32_e32 v14, v14, v19, vcc
	v_sub_f32_e32 v14, v20, v14
	global_store_dword v[12:13], v14, off offset:-24
	global_load_dword v14, v176, s[80:81] offset:-20
	s_waitcnt vmcnt(0)
	v_fmac_f32_e32 v14, v11, v18
	v_mul_f32_e64 v15, |v14|, s64
	v_exp_f32_e32 v19, v15
	v_min_f32_e32 v20, 0, v14
	v_add_f32_e32 v21, 1.0, v19
	v_add_f32_e32 v22, -1.0, v21
	v_frexp_mant_f32_e32 v23, v21
	v_cvt_f64_f32_e32 v[14:15], v21
	v_sub_f32_e32 v24, v22, v21
	v_frexp_exp_i32_f64_e32 v14, v[14:15]
	v_cmp_gt_f32_e32 vcc, s65, v23
	v_sub_f32_e32 v22, v19, v22
	v_add_f32_e32 v15, 1.0, v24
	v_subbrev_co_u32_e32 v14, vcc, 0, v14, vcc
	v_add_f32_e32 v15, v22, v15
	v_sub_u32_e32 v22, 0, v14
	v_cvt_f32_i32_e32 v14, v14
	v_ldexp_f32 v21, v21, v22
	v_ldexp_f32 v15, v15, v22
	v_add_f32_e32 v22, -1.0, v21
	v_add_f32_e32 v23, 1.0, v21
	v_add_f32_e32 v24, 1.0, v22
	v_add_f32_e32 v25, -1.0, v23
	v_sub_f32_e32 v24, v21, v24
	v_sub_f32_e32 v21, v21, v25
	v_mul_f32_e32 v25, 0x3f317218, v14
	v_add_f32_e32 v24, v15, v24
	v_add_f32_e32 v15, v15, v21
	v_fma_f32 v21, v14, s66, -v25
	v_add_f32_e32 v26, v22, v24
	v_add_f32_e32 v27, v23, v15
	v_fmac_f32_e32 v21, 0xb102e308, v14
	v_sub_f32_e32 v14, v26, v22
	v_sub_f32_e32 v22, v27, v23
	v_rcp_f32_e32 v23, v27
	v_add_f32_e32 v28, v25, v21
	v_sub_f32_e32 v15, v15, v22
	v_sub_f32_e32 v22, v28, v25
	v_sub_f32_e32 v21, v21, v22
	v_mul_f32_e32 v22, v26, v23
	v_sub_f32_e32 v14, v24, v14
	v_mul_f32_e32 v24, v27, v22
	v_fma_f32 v25, v22, v27, -v24
	v_fmac_f32_e32 v25, v22, v15
	v_add_f32_e32 v29, v24, v25
	v_sub_f32_e32 v30, v26, v29
	v_sub_f32_e32 v24, v29, v24
	v_sub_f32_e32 v26, v26, v30
	v_sub_f32_e32 v24, v24, v25
	v_sub_f32_e32 v25, v26, v29
	v_add_f32_e32 v14, v14, v25
	v_add_f32_e32 v14, v24, v14
	v_add_f32_e32 v24, v30, v14
	v_mul_f32_e32 v25, v23, v24
	v_sub_f32_e32 v26, v30, v24
	v_mul_f32_e32 v29, v27, v25
	v_add_f32_e32 v14, v14, v26
	v_add_f32_e32 v26, v22, v25
	v_fma_f32 v27, v25, v27, -v29
	v_sub_f32_e32 v22, v26, v22
	v_fmac_f32_e32 v27, v25, v15
	v_sub_f32_e32 v15, v25, v22
	v_add_f32_e32 v22, v29, v27
	v_sub_f32_e32 v25, v22, v29
	v_sub_f32_e32 v29, v24, v22
	v_sub_f32_e32 v24, v24, v29
	v_sub_f32_e32 v22, v24, v22
	v_sub_f32_e32 v25, v25, v27
	v_add_f32_e32 v14, v14, v22
	v_add_f32_e32 v14, v25, v14
	v_add_f32_e32 v14, v29, v14
	v_mul_f32_e32 v14, v23, v14
	v_add_f32_e32 v14, v15, v14
	v_add_f32_e32 v15, v26, v14
	v_mul_f32_e32 v22, v15, v15
	v_fmamk_f32 v25, v22, 0x3e9b6dac, v186
	v_sub_f32_e32 v23, v15, v26
	v_ldexp_f32 v24, v15, 1
	v_mul_f32_e32 v15, v15, v22
	v_fmaak_f32 v22, v22, v25, 0x3f2aaada
	v_mul_f32_e32 v15, v15, v22
	v_add_f32_e32 v22, v24, v15
	v_sub_f32_e32 v14, v14, v23
	v_sub_f32_e32 v23, v22, v24
	v_ldexp_f32 v14, v14, 1
	v_sub_f32_e32 v15, v15, v23
	v_add_f32_e32 v14, v14, v15
	v_add_f32_e32 v15, v22, v14
	v_sub_f32_e32 v22, v15, v22
	v_add_f32_e32 v23, v28, v15
	v_sub_f32_e32 v14, v14, v22
	v_sub_f32_e32 v22, v23, v28
	v_sub_f32_e32 v24, v23, v22
	v_sub_f32_e32 v15, v15, v22
	v_add_f32_e32 v22, v21, v14
	v_sub_f32_e32 v24, v28, v24
	v_sub_f32_e32 v25, v22, v21
	v_add_f32_e32 v15, v15, v24
	v_sub_f32_e32 v24, v22, v25
	v_sub_f32_e32 v14, v14, v25
	v_sub_f32_e32 v21, v21, v24
	v_add_f32_e32 v15, v22, v15
	v_add_f32_e32 v14, v14, v21
	v_add_f32_e32 v21, v23, v15
	v_sub_f32_e32 v22, v21, v23
	v_sub_f32_e32 v15, v15, v22
	v_add_f32_e32 v14, v14, v15
	v_add_f32_e32 v14, v21, v14
	v_cmp_neq_f32_e32 vcc, s67, v19
	s_nop 1
	v_cndmask_b32_e32 v14, v194, v14, vcc
	v_cmp_ngt_f32_e32 vcc, -1.0, v19
	s_nop 1
	v_cndmask_b32_e32 v14, v195, v14, vcc
	v_cmp_neq_f32_e32 vcc, -1.0, v19
	s_nop 1
	v_cndmask_b32_e32 v14, v196, v14, vcc
	v_cmp_lt_f32_e64 vcc, |v19|, s68
	s_nop 1
	v_cndmask_b32_e32 v14, v14, v19, vcc
	v_sub_f32_e32 v14, v20, v14
	global_store_dword v[12:13], v14, off offset:-20
.LBB0_291:
	s_andn2_saveexec_b64 s[0:1], s[0:1]
	s_cbranch_execz .LBB0_293
	v_mul_f32_e32 v8, v8, v18
	v_mul_f32_e32 v9, v9, v18
	v_mul_f32_e32 v8, 0xbfb8aa3b, v8
	v_mul_f32_e32 v9, 0xbfb8aa3b, v9
	v_exp_f32_e32 v8, v8
	v_exp_f32_e32 v9, v9
	v_mul_f32_e32 v10, v10, v18
	v_mul_f32_e32 v11, v11, v18
	v_mul_f32_e32 v10, 0xbfb8aa3b, v10
	v_pk_add_f32 v[8:9], v[8:9], 1.0 op_sel_hi:[1,0]
	v_mul_f32_e32 v11, 0xbfb8aa3b, v11
	v_exp_f32_e32 v10, v10
	v_rcp_f32_e32 v9, v9
	v_exp_f32_e32 v11, v11
	s_nop 0
	v_pk_add_f32 v[10:11], v[10:11], 1.0 op_sel_hi:[1,0]
	v_rcp_f32_e32 v8, v8
	v_rcp_f32_e32 v11, v11
	v_rcp_f32_e32 v10, v10
	global_store_dwordx4 v[20:21], v[8:11], off offset:64

; DI int TIDX() { int t = (int)threadIdx.x; asm volatile("" : "+v"(t)); return t; }
; DI void compress_item(const Params& p, int layer, int item, bf16_t* smem) {
;     ...
;   gemm_main<4, 4, true>(acc, ap, 256, bp, 64, 32, smem);
;   const int lane = TIDX() & 63, wid = TIDX() >> 6, wm = wid >> 2, wn = wid & 3, l15 = lane & 15, quad = lane >> 4;
;   constexpr int LDH = 264; bf16_t* H = smem;
;   const float* b1 = (const float*)(p.ws + O_BIAS1) + (size_t)(layer * 2 + kv) * 16 * 256;
; #pragma unroll
;   for (int j = 0; j < 4; ++j) {
;     asm volatile("" ::: "memory");
;     f32x4 bv = {0.f, 0.f, 0.f, 0.f};
;     for (int pc = 0; pc < 16; ++pc) bv += *(const f32x4*)(b1 + pc * 256 + wn * 64 + j * 16 + quad * 4);
.Lcp0_exit:
	v_mfma_f32_16x16x32_bf16 v[52:55], v[140:143], v[132:135], v[52:55]
	v_mfma_f32_16x16x32_bf16 v[48:51], v[140:143], v[136:139], v[48:51]
	v_mfma_f32_16x16x32_bf16 v[36:39], v[148:151], v[132:135], v[36:39]
	v_mfma_f32_16x16x32_bf16 v[32:35], v[148:151], v[136:139], v[32:35]
	v_mfma_f32_16x16x32_bf16 v[20:23], v[152:155], v[132:135], v[20:23]
	v_mfma_f32_16x16x32_bf16 v[16:19], v[152:155], v[136:139], v[16:19]
	v_mfma_f32_16x16x32_bf16 v[4:7], v[242:245], v[132:135], v[4:7]
	v_mfma_f32_16x16x32_bf16 v[0:3], v[242:245], v[136:139], v[0:3]
	s_nop 7
	s_waitcnt vmcnt(5)
	v_mov_b32_e32 v78, v220
	s_waitcnt vmcnt(1)
	v_mov_b32_e32 v81, v220
	s_lshl_b32 s0, s13, 14
	v_ashrrev_i32_e32 v80, 6, v81
	v_readlane_b32 s8, v241, 0
	v_and_b32_e32 v142, 3, v80
	v_readlane_b32 s9, v241, 1
	s_add_u32 s0, s8, s0
	v_bfe_u32 v79, v78, 4, 2
	s_addc_u32 s1, s9, 0
	v_lshlrev_b32_e32 v64, 8, v142
	v_mov_b32_e32 v65, 0
	v_lshl_add_u64 v[66:67], s[0:1], 0, v[64:65]
	v_lshlrev_b32_e32 v64, 4, v79
	v_lshl_add_u64 v[72:73], v[66:67], 0, v[64:65]
	s_mov_b64 s[0:1], 0x4b44000
	v_lshl_add_u64 v[66:67], v[72:73], 0, s[0:1]
	s_mov_b32 s0, 0x4b45000
	v_add_co_u32_e32 v68, vcc, s0, v72
	s_mov_b32 s1, 0x4b47000
	s_nop 0
	v_addc_co_u32_e32 v69, vcc, 0, v73, vcc
	global_load_dwordx4 v[74:77], v[68:69], off offset:-4096
	global_load_dwordx4 v[82:85], v[66:67], off offset:1024
	global_load_dwordx4 v[86:89], v[66:67], off offset:2048
	global_load_dwordx4 v[90:93], v[66:67], off offset:3072
	global_load_dwordx4 v[94:97], v[68:69], off
	global_load_dwordx4 v[98:101], v[68:69], off offset:1024
	global_load_dwordx4 v[102:105], v[68:69], off offset:2048
	v_add_co_u32_e32 v70, vcc, s1, v72
	s_mov_b32 s0, 0x4b46000
	s_nop 0
	v_addc_co_u32_e32 v71, vcc, 0, v73, vcc
	global_load_dwordx4 v[106:109], v[68:69], off offset:3072
	global_load_dwordx4 v[110:113], v[70:71], off offset:-4096
	v_add_co_u32_e32 v72, vcc, s0, v72
	s_mov_b32 s0, 0xfffffc0
	s_nop 0
	v_addc_co_u32_e32 v73, vcc, 0, v73, vcc
	global_load_dwordx4 v[114:117], v[72:73], off offset:1024
	global_load_dwordx4 v[118:121], v[72:73], off offset:2048
	global_load_dwordx4 v[122:125], v[72:73], off offset:3072
	global_load_dwordx4 v[126:129], v[70:71], off
	global_load_dwordx4 v[130:133], v[70:71], off offset:1024
	global_load_dwordx4 v[134:137], v[70:71], off offset:2048
	global_load_dwordx4 v[138:141], v[70:71], off offset:3072
	v_and_b32_e32 v78, 15, v78
	v_lshrrev_b32_e32 v81, 2, v81
	v_and_or_b32 v81, v81, s0, v78
	v_lshlrev_b32_e32 v143, 3, v79
	v_lshl_or_b32 v142, v142, 7, v143
	s_and_b64 s[6:7], s[2:3], exec
	s_waitcnt vmcnt(15)
	v_pk_add_f32 v[76:77], v[76:77], 0 op_sel_hi:[1,0]
	v_pk_add_f32 v[74:75], v[74:75], 0 op_sel_hi:[1,0]
	s_waitcnt vmcnt(14)
	v_pk_add_f32 v[76:77], v[76:77], v[84:85]
	v_pk_add_f32 v[74:75], v[74:75], v[82:83]
	s_waitcnt vmcnt(13)
	v_pk_add_f32 v[76:77], v[76:77], v[88:89]
	v_pk_add_f32 v[74:75], v[74:75], v[86:87]
	s_waitcnt vmcnt(12)
	v_pk_add_f32 v[76:77], v[76:77], v[92:93]
	v_pk_add_f32 v[74:75], v[74:75], v[90:91]
	s_waitcnt vmcnt(11)
	v_pk_add_f32 v[76:77], v[76:77], v[96:97]
	v_pk_add_f32 v[74:75], v[74:75], v[94:95]
	s_waitcnt vmcnt(10)
	v_pk_add_f32 v[76:77], v[76:77], v[100:101]
	v_pk_add_f32 v[74:75], v[74:75], v[98:99]
	s_waitcnt vmcnt(9)
	v_pk_add_f32 v[76:77], v[76:77], v[104:105]
	v_pk_add_f32 v[74:75], v[74:75], v[102:103]
	s_waitcnt vmcnt(8)
	v_pk_add_f32 v[76:77], v[76:77], v[108:109]
	v_pk_add_f32 v[74:75], v[74:75], v[106:107]
	s_waitcnt vmcnt(7)
	v_pk_add_f32 v[76:77], v[76:77], v[112:113]
	v_pk_add_f32 v[74:75], v[74:75], v[110:111]
	s_waitcnt vmcnt(6)
	v_pk_add_f32 v[76:77], v[76:77], v[116:117]
	v_pk_add_f32 v[74:75], v[74:75], v[114:115]
	s_waitcnt vmcnt(5)
	v_pk_add_f32 v[76:77], v[76:77], v[120:121]
	v_pk_add_f32 v[74:75], v[74:75], v[118:119]
	s_waitcnt vmcnt(4)
	v_pk_add_f32 v[76:77], v[76:77], v[124:125]
	v_pk_add_f32 v[74:75], v[74:75], v[122:123]
	s_waitcnt vmcnt(3)
	v_pk_add_f32 v[76:77], v[76:77], v[128:129]
	v_pk_add_f32 v[74:75], v[74:75], v[126:127]
	s_waitcnt vmcnt(2)
	v_pk_add_f32 v[76:77], v[76:77], v[132:133]
	v_pk_add_f32 v[74:75], v[74:75], v[130:131]
	s_waitcnt vmcnt(1)
	v_pk_add_f32 v[76:77], v[76:77], v[136:137]
	v_pk_add_f32 v[82:83], v[74:75], v[134:135]
	s_waitcnt vmcnt(0)
; DI unsigned pk2(float lo, float hi) { f32x2 v = {lo, hi}; return __builtin_bit_cast(unsigned, __builtin_convertvector(v, bfx2)); }
; DI float gelu_tanh(float x) { const float u = 0.7978845608028654f * (x + 0.044715f * x * x * x); return x / (1.f + __expf(-2.f * u)); }
; DI void compress_item(const Params& p, int layer, int item, bf16_t* smem) {
;     ...
;   for (int j = 0; j < 4; ++j) {
;     asm volatile("" ::: "memory");
;     f32x4 bv = {0.f, 0.f, 0.f, 0.f};
;     for (int pc = 0; pc < 16; ++pc) bv += *(const f32x4*)(b1 + pc * 256 + wn * 64 + j * 16 + quad * 4);
; #pragma unroll
;     for (int i = 0; i < 4; ++i) {
;       const int row = wm * 64 + i * 16 + l15, col = wn * 64 + j * 16 + quad * 4;
;       *(u32x2*)(H + row * LDH + col) = (u32x2){pk2(gelu_tanh(acc[i][j][0] + bv[0]), gelu_tanh(acc[i][j][1] + bv[1])), pk2(gelu_tanh(acc[i][j][2] + bv[2]), gelu_tanh(acc[i][j][3] + bv[3]))};
;     }
	v_pk_add_f32 v[74:75], v[76:77], v[140:141]
	v_pk_add_f32 v[76:77], v[82:83], v[138:139]
	v_pk_add_f32 v[62:63], v[62:63], v[74:75]
	v_pk_add_f32 v[60:61], v[60:61], v[76:77]
	v_mul_f32_e32 v84, 0x3d372713, v62
	v_mul_f32_e32 v82, 0x3d372713, v60
	v_mul_f32_e32 v83, 0x3d372713, v61
	v_mul_f32_e32 v82, v60, v82
	v_mul_f32_e32 v83, v61, v83
	v_fma_f32 v82, v60, v82, v60
	v_fma_f32 v83, v61, v83, v61
	v_mul_f32_e32 v82, 0x3f4c422a, v82
	v_mul_f32_e32 v83, 0x3f4c422a, v83
	v_mul_f32_e32 v82, -2.0, v82
	v_mul_f32_e32 v83, -2.0, v83
	v_mul_f32_e32 v82, 0x3fb8aa3b, v82
	v_mul_f32_e32 v83, 0x3fb8aa3b, v83
	v_exp_f32_e32 v82, v82
	v_exp_f32_e32 v83, v83
	v_mul_f32_e32 v84, v62, v84
	v_pk_add_f32 v[58:59], v[58:59], v[74:75]
	v_pk_add_f32 v[52:53], v[52:53], v[76:77]
	v_pk_add_f32 v[82:83], v[82:83], 1.0 op_sel_hi:[1,0]
	v_pk_add_f32 v[54:55], v[54:55], v[74:75]
	v_div_scale_f32 v87, s[0:1], v82, v82, v60
	v_rcp_f32_e32 v85, v83
	s_nop 0
	v_mul_f32_e32 v61, v61, v85
	v_fma_f32 v83, v62, v84, v62
	v_mul_f32_e32 v83, 0x3f4c422a, v83
	v_mul_f32_e32 v83, -2.0, v83
	v_mul_f32_e32 v83, 0x3fb8aa3b, v83
	v_exp_f32_e32 v84, v83
	v_mul_f32_e32 v83, 0x3d372713, v63
	v_mul_f32_e32 v83, v63, v83
	v_fma_f32 v83, v63, v83, v63
	v_rcp_f32_e32 v89, v87
	v_mul_f32_e32 v83, 0x3f4c422a, v83
	v_mul_f32_e32 v83, -2.0, v83
	v_mul_f32_e32 v83, 0x3fb8aa3b, v83
	v_exp_f32_e32 v85, v83
	v_fma_f32 v92, -v87, v89, 1.0
	v_div_scale_f32 v90, s[0:1], v60, v82, v60
	v_fmac_f32_e32 v89, v92, v89
	v_mul_f32_e32 v92, v90, v89
	v_fma_f32 v83, -v87, v92, v90
	v_pk_add_f32 v[84:85], v[84:85], 1.0 op_sel_hi:[1,0]
	v_fmac_f32_e32 v92, v83, v89
	v_fma_f32 v83, -v87, v92, v90
	s_mov_b64 vcc, s[0:1]
	v_div_fmas_f32 v83, v83, v89, v92
	v_div_fixup_f32 v60, v83, v82, v60
	v_cvt_pk_bf16_f32 v60, v60, v61
	v_rcp_f32_e32 v61, v85
	s_nop 0
	v_mul_f32_e32 v61, v63, v61
	s_movk_i32 s0, 0x210
	v_pk_add_f32 v[82:83], v[56:57], v[76:77]
	v_rcp_f32_e32 v63, v84
	s_nop 0
	v_mul_f32_e32 v62, v62, v63
	v_mul_f32_e32 v56, 0x3d372713, v82
	v_mul_f32_e32 v57, 0x3d372713, v83
	v_mul_f32_e32 v56, v82, v56
	v_mul_f32_e32 v57, v83, v57
	v_fma_f32 v56, v82, v56, v82
	v_fma_f32 v57, v83, v57, v83
	v_mul_f32_e32 v56, 0x3f4c422a, v56
	v_mul_f32_e32 v57, 0x3f4c422a, v57
	v_mul_f32_e32 v56, -2.0, v56
	v_mul_f32_e32 v57, -2.0, v57
	v_mul_f32_e32 v56, 0x3fb8aa3b, v56
	v_mul_f32_e32 v57, 0x3fb8aa3b, v57
	v_exp_f32_e32 v56, v56
	v_exp_f32_e32 v57, v57
	v_cvt_pk_bf16_f32 v61, v62, v61
	v_pk_add_f32 v[48:49], v[48:49], v[76:77]
	v_pk_add_f32 v[50:51], v[50:51], v[74:75]
	v_pk_add_f32 v[62:63], v[56:57], 1.0 op_sel_hi:[1,0]
	v_mad_u64_u32 v[56:57], s[6:7], v81, s0, v[142:143]
	ds_write_b64 v56, v[60:61]
	v_mul_f32_e32 v61, 0x3d372713, v59
	v_mul_f32_e32 v61, v59, v61
	v_mul_f32_e32 v60, 0x3d372713, v58
	v_mul_f32_e32 v60, v58, v60
	v_fma_f32 v60, v58, v60, v58
	v_fma_f32 v61, v59, v61, v59
	v_mul_f32_e32 v60, 0x3f4c422a, v60
	v_mul_f32_e32 v61, 0x3f4c422a, v61
	v_mul_f32_e32 v60, -2.0, v60
	v_mul_f32_e32 v61, -2.0, v61
	v_mul_f32_e32 v60, 0x3fb8aa3b, v60
	v_mul_f32_e32 v61, 0x3fb8aa3b, v61
	v_exp_f32_e32 v60, v60
	v_exp_f32_e32 v61, v61
	v_rcp_f32_e32 v57, v63
	s_nop 0
	v_mul_f32_e32 v57, v83, v57
	v_pk_add_f32 v[60:61], v[60:61], 1.0 op_sel_hi:[1,0]
	v_rcp_f32_e32 v63, v62
	s_nop 0
	v_mul_f32_e32 v62, v82, v63
	v_cvt_pk_bf16_f32 v62, v62, v57
	v_rcp_f32_e32 v57, v61
	s_nop 0
	v_mul_f32_e32 v57, v59, v57
	s_mov_b32 s1, 0xf00000
	v_mul_f32_e32 v63, 0x3d372713, v52
	v_mul_f32_e32 v63, v52, v63
	v_fma_f32 v63, v52, v63, v52
	v_mul_f32_e32 v63, 0x3f4c422a, v63
	v_mul_f32_e32 v63, -2.0, v63
	v_mul_f32_e32 v63, 0x3fb8aa3b, v63
	v_exp_f32_e32 v82, v63
	v_mul_f32_e32 v63, 0x3d372713, v53
	v_mul_f32_e32 v63, v53, v63
	v_fma_f32 v63, v53, v63, v53
	v_mul_f32_e32 v63, 0x3f4c422a, v63
	v_mul_f32_e32 v63, -2.0, v63
	v_mul_f32_e32 v63, 0x3fb8aa3b, v63
	v_exp_f32_e32 v83, v63
	v_rcp_f32_e32 v59, v60
	s_nop 0
	v_mul_f32_e32 v60, v58, v59
	v_pk_add_f32 v[58:59], v[82:83], 1.0 op_sel_hi:[1,0]
	v_cvt_pk_bf16_f32 v63, v60, v57
	ds_write_b64 v56, v[62:63] offset:8448
	s_cselect_b32 s1, s1, 0xf08000
	v_mul_f32_e32 v60, 0x3d372713, v54
	v_mul_f32_e32 v61, 0x3d372713, v55
	v_mul_f32_e32 v60, v54, v60
	v_mul_f32_e32 v61, v55, v61
	v_fma_f32 v60, v54, v60, v54
	v_fma_f32 v61, v55, v61, v55
	v_mul_f32_e32 v60, 0x3f4c422a, v60
	v_mul_f32_e32 v61, 0x3f4c422a, v61
	v_mul_f32_e32 v60, -2.0, v60
	v_mul_f32_e32 v61, -2.0, v61
	v_mul_f32_e32 v60, 0x3fb8aa3b, v60
	v_mul_f32_e32 v61, 0x3fb8aa3b, v61
	v_rcp_f32_e32 v57, v59
	s_nop 0
	v_mul_f32_e32 v53, v53, v57
	v_exp_f32_e32 v60, v60
	v_exp_f32_e32 v61, v61
	s_nop 0
	v_pk_add_f32 v[60:61], v[60:61], 1.0 op_sel_hi:[1,0]
	v_rcp_f32_e32 v57, v58
	s_nop 0
	v_mul_f32_e32 v52, v52, v57
	v_cvt_pk_bf16_f32 v52, v52, v53
	v_rcp_f32_e32 v53, v61
	s_nop 0
	v_mul_f32_e32 v53, v55, v53
	v_mul_f32_e32 v58, 0x3d372713, v48
	v_mul_f32_e32 v59, 0x3d372713, v49
	v_mul_f32_e32 v58, v48, v58
	v_mul_f32_e32 v59, v49, v59
	v_fma_f32 v58, v48, v58, v48
	v_fma_f32 v59, v49, v59, v49
	v_mul_f32_e32 v58, 0x3f4c422a, v58
	v_mul_f32_e32 v59, 0x3f4c422a, v59
	v_mul_f32_e32 v58, -2.0, v58
	v_mul_f32_e32 v59, -2.0, v59
	v_mul_f32_e32 v58, 0x3fb8aa3b, v58
	v_mul_f32_e32 v59, 0x3fb8aa3b, v59
	v_exp_f32_e32 v58, v58
	v_exp_f32_e32 v59, v59
	v_rcp_f32_e32 v55, v60
	s_nop 0
	v_mul_f32_e32 v57, v54, v55
	v_cvt_pk_bf16_f32 v53, v57, v53
	v_pk_add_f32 v[54:55], v[58:59], 1.0 op_sel_hi:[1,0]
	ds_write_b64 v56, v[52:53] offset:16896
	s_nop 0
	v_rcp_f32_e32 v52, v55
	s_nop 0
	v_mul_f32_e32 v49, v49, v52
	v_mul_f32_e32 v53, 0x3d372713, v51
	v_mul_f32_e32 v52, 0x3d372713, v50
	v_mul_f32_e32 v52, v50, v52
	v_mul_f32_e32 v53, v51, v53
	v_fma_f32 v52, v50, v52, v50
; DI unsigned pk2(float lo, float hi) { f32x2 v = {lo, hi}; return __builtin_bit_cast(unsigned, __builtin_convertvector(v, bfx2)); }
; DI float gelu_tanh(float x) { const float u = 0.7978845608028654f * (x + 0.044715f * x * x * x); return x / (1.f + __expf(-2.f * u)); }
; DI void compress_item(const Params& p, int layer, int item, bf16_t* smem) {
;     ...
;   for (int j = 0; j < 4; ++j) {
;     asm volatile("" ::: "memory");
;     f32x4 bv = {0.f, 0.f, 0.f, 0.f};
;     for (int pc = 0; pc < 16; ++pc) bv += *(const f32x4*)(b1 + pc * 256 + wn * 64 + j * 16 + quad * 4);
; #pragma unroll
;     for (int i = 0; i < 4; ++i) {
;       const int row = wm * 64 + i * 16 + l15, col = wn * 64 + j * 16 + quad * 4;
;       *(u32x2*)(H + row * LDH + col) = (u32x2){pk2(gelu_tanh(acc[i][j][0] + bv[0]), gelu_tanh(acc[i][j][1] + bv[1])), pk2(gelu_tanh(acc[i][j][2] + bv[2]), gelu_tanh(acc[i][j][3] + bv[3]))};
;     }
	v_fma_f32 v53, v51, v53, v51
	v_mul_f32_e32 v52, 0x3f4c422a, v52
	v_mul_f32_e32 v53, 0x3f4c422a, v53
	v_mul_f32_e32 v52, -2.0, v52
	v_mul_f32_e32 v53, -2.0, v53
	v_mul_f32_e32 v52, 0x3fb8aa3b, v52
	v_mul_f32_e32 v53, 0x3fb8aa3b, v53
	v_exp_f32_e32 v52, v52
	v_exp_f32_e32 v53, v53
	s_nop 0
	v_pk_add_f32 v[52:53], v[52:53], 1.0 op_sel_hi:[1,0]
	v_rcp_f32_e32 v55, v54
	s_nop 0
	v_mul_f32_e32 v48, v48, v55
	v_cvt_pk_bf16_f32 v48, v48, v49
	v_rcp_f32_e32 v49, v53
	s_nop 0
	v_mul_f32_e32 v49, v51, v49
	v_rcp_f32_e32 v51, v52
	s_nop 0
	v_mul_f32_e32 v50, v50, v51
	v_cvt_pk_bf16_f32 v49, v50, v49
	ds_write_b64 v56, v[48:49] offset:25344
	global_load_dwordx4 v[48:51], v[66:67], off offset:64
	global_load_dwordx4 v[52:55], v[66:67], off offset:1088
	global_load_dwordx4 v[58:61], v[66:67], off offset:2112
	global_load_dwordx4 v[74:77], v[66:67], off offset:3136
	global_load_dwordx4 v[82:85], v[68:69], off offset:64
	global_load_dwordx4 v[86:89], v[68:69], off offset:1088
	global_load_dwordx4 v[90:93], v[68:69], off offset:2112
	global_load_dwordx4 v[94:97], v[68:69], off offset:3136
	global_load_dwordx4 v[98:101], v[72:73], off offset:64
	global_load_dwordx4 v[102:105], v[72:73], off offset:1088
	global_load_dwordx4 v[106:109], v[72:73], off offset:2112
	global_load_dwordx4 v[110:113], v[72:73], off offset:3136
	global_load_dwordx4 v[114:117], v[70:71], off offset:64
	global_load_dwordx4 v[118:121], v[70:71], off offset:1088
	global_load_dwordx4 v[122:125], v[70:71], off offset:2112
	global_load_dwordx4 v[126:129], v[70:71], off offset:3136
	s_waitcnt vmcnt(15)
	v_pk_add_f32 v[48:49], v[48:49], 0 op_sel_hi:[1,0]
	s_waitcnt vmcnt(14)
	v_pk_add_f32 v[48:49], v[48:49], v[52:53]
	v_pk_add_f32 v[50:51], v[50:51], 0 op_sel_hi:[1,0]
	s_waitcnt vmcnt(13)
	v_pk_add_f32 v[48:49], v[48:49], v[58:59]
	v_pk_add_f32 v[50:51], v[50:51], v[54:55]
	s_waitcnt vmcnt(12)
	v_pk_add_f32 v[48:49], v[48:49], v[74:75]
	v_pk_add_f32 v[50:51], v[50:51], v[60:61]
	s_waitcnt vmcnt(11)
	v_pk_add_f32 v[48:49], v[48:49], v[82:83]
	v_pk_add_f32 v[50:51], v[50:51], v[76:77]
	s_waitcnt vmcnt(10)
	v_pk_add_f32 v[48:49], v[48:49], v[86:87]
	v_pk_add_f32 v[50:51], v[50:51], v[84:85]
	s_waitcnt vmcnt(9)
	v_pk_add_f32 v[48:49], v[48:49], v[90:91]
	v_pk_add_f32 v[50:51], v[50:51], v[88:89]
	s_waitcnt vmcnt(8)
	v_pk_add_f32 v[48:49], v[48:49], v[94:95]
	v_pk_add_f32 v[50:51], v[50:51], v[92:93]
	s_waitcnt vmcnt(7)
	v_pk_add_f32 v[48:49], v[48:49], v[98:99]
	v_pk_add_f32 v[50:51], v[50:51], v[96:97]
	s_waitcnt vmcnt(6)
	v_pk_add_f32 v[48:49], v[48:49], v[102:103]
	v_pk_add_f32 v[50:51], v[50:51], v[100:101]
	s_waitcnt vmcnt(5)
	v_pk_add_f32 v[48:49], v[48:49], v[106:107]
	v_pk_add_f32 v[50:51], v[50:51], v[104:105]
	s_waitcnt vmcnt(4)
	v_pk_add_f32 v[48:49], v[48:49], v[110:111]
	v_pk_add_f32 v[50:51], v[50:51], v[108:109]
	s_waitcnt vmcnt(3)
	v_pk_add_f32 v[48:49], v[48:49], v[114:115]
	v_pk_add_f32 v[50:51], v[50:51], v[112:113]
	s_waitcnt vmcnt(2)
	v_pk_add_f32 v[48:49], v[48:49], v[118:119]
	v_pk_add_f32 v[50:51], v[50:51], v[116:117]
	s_waitcnt vmcnt(1)
	v_pk_add_f32 v[48:49], v[48:49], v[122:123]
	v_pk_add_f32 v[50:51], v[50:51], v[120:121]
	s_waitcnt vmcnt(0)
	v_pk_add_f32 v[48:49], v[48:49], v[126:127]
	s_nop 0
	v_pk_add_f32 v[52:53], v[44:45], v[48:49]
	v_pk_add_f32 v[40:41], v[40:41], v[48:49]
	v_mul_f32_e32 v44, 0x3d372713, v52
	v_mul_f32_e32 v45, 0x3d372713, v53
	v_mul_f32_e32 v44, v52, v44
	v_mul_f32_e32 v45, v53, v45
	v_fma_f32 v44, v52, v44, v52
	v_fma_f32 v45, v53, v45, v53
	v_mul_f32_e32 v44, 0x3f4c422a, v44
	v_mul_f32_e32 v45, 0x3f4c422a, v45
	v_mul_f32_e32 v44, -2.0, v44
	v_mul_f32_e32 v45, -2.0, v45
	v_mul_f32_e32 v44, 0x3fb8aa3b, v44
	v_mul_f32_e32 v45, 0x3fb8aa3b, v45
	v_exp_f32_e32 v44, v44
	v_exp_f32_e32 v45, v45
	v_pk_add_f32 v[36:37], v[36:37], v[48:49]
	v_pk_add_f32 v[32:33], v[32:33], v[48:49]
	v_pk_add_f32 v[54:55], v[44:45], 1.0 op_sel_hi:[1,0]
	s_nop 0
	v_pk_add_f32 v[44:45], v[50:51], v[124:125]
	v_pk_add_f32 v[44:45], v[44:45], v[128:129]
	v_pk_add_f32 v[46:47], v[46:47], v[44:45]
	v_rcp_f32_e32 v50, v55
	s_nop 0
	v_mul_f32_e32 v53, v53, v50
	v_mul_f32_e32 v50, 0x3d372713, v46
	v_mul_f32_e32 v51, 0x3d372713, v47
	v_mul_f32_e32 v50, v46, v50
	v_mul_f32_e32 v51, v47, v51
	v_fma_f32 v50, v46, v50, v46
	v_fma_f32 v51, v47, v51, v47
	v_mul_f32_e32 v50, 0x3f4c422a, v50
	v_mul_f32_e32 v51, 0x3f4c422a, v51
	v_mul_f32_e32 v50, -2.0, v50
	v_mul_f32_e32 v51, -2.0, v51
	v_mul_f32_e32 v50, 0x3fb8aa3b, v50
	v_mul_f32_e32 v51, 0x3fb8aa3b, v51
	v_exp_f32_e32 v50, v50
	v_exp_f32_e32 v51, v51
	s_nop 0
	v_pk_add_f32 v[50:51], v[50:51], 1.0 op_sel_hi:[1,0]
	v_rcp_f32_e32 v55, v54
	s_nop 0
	v_mul_f32_e32 v52, v52, v55
	v_cvt_pk_bf16_f32 v52, v52, v53
	v_rcp_f32_e32 v53, v51
	s_nop 0
	v_mul_f32_e32 v51, v47, v53
	v_pk_add_f32 v[42:43], v[42:43], v[44:45]
	v_mul_f32_e32 v54, 0x3d372713, v40
	v_mul_f32_e32 v55, 0x3d372713, v41
	v_mul_f32_e32 v54, v40, v54
	v_mul_f32_e32 v55, v41, v55
	v_fma_f32 v54, v40, v54, v40
	v_fma_f32 v55, v41, v55, v41
	v_mul_f32_e32 v54, 0x3f4c422a, v54
	v_mul_f32_e32 v55, 0x3f4c422a, v55
	v_mul_f32_e32 v54, -2.0, v54
	v_mul_f32_e32 v55, -2.0, v55
	v_mul_f32_e32 v54, 0x3fb8aa3b, v54
	v_mul_f32_e32 v55, 0x3fb8aa3b, v55
	v_exp_f32_e32 v54, v54
	v_exp_f32_e32 v55, v55
	v_rcp_f32_e32 v47, v50
	s_nop 0
	v_mul_f32_e32 v50, v46, v47
	v_cvt_pk_bf16_f32 v53, v50, v51
	v_pk_add_f32 v[46:47], v[54:55], 1.0 op_sel_hi:[1,0]
	ds_write_b64 v56, v[52:53] offset:32
	v_pk_add_f32 v[38:39], v[38:39], v[44:45]
	v_pk_add_f32 v[34:35], v[34:35], v[44:45]
	v_rcp_f32_e32 v50, v47
	s_nop 0
	v_mul_f32_e32 v41, v41, v50
	v_mul_f32_e32 v50, 0x3d372713, v42
	v_mul_f32_e32 v51, 0x3d372713, v43
; DI unsigned pk2(float lo, float hi) { f32x2 v = {lo, hi}; return __builtin_bit_cast(unsigned, __builtin_convertvector(v, bfx2)); }
; DI float gelu_tanh(float x) { const float u = 0.7978845608028654f * (x + 0.044715f * x * x * x); return x / (1.f + __expf(-2.f * u)); }
; DI void compress_item(const Params& p, int layer, int item, bf16_t* smem) {
;     ...
;   for (int j = 0; j < 4; ++j) {
;     asm volatile("" ::: "memory");
;     f32x4 bv = {0.f, 0.f, 0.f, 0.f};
;     for (int pc = 0; pc < 16; ++pc) bv += *(const f32x4*)(b1 + pc * 256 + wn * 64 + j * 16 + quad * 4);
; #pragma unroll
;     for (int i = 0; i < 4; ++i) {
;       const int row = wm * 64 + i * 16 + l15, col = wn * 64 + j * 16 + quad * 4;
;       *(u32x2*)(H + row * LDH + col) = (u32x2){pk2(gelu_tanh(acc[i][j][0] + bv[0]), gelu_tanh(acc[i][j][1] + bv[1])), pk2(gelu_tanh(acc[i][j][2] + bv[2]), gelu_tanh(acc[i][j][3] + bv[3]))};
;     }
	v_mul_f32_e32 v50, v42, v50
	v_mul_f32_e32 v51, v43, v51
	v_fma_f32 v50, v42, v50, v42
	v_fma_f32 v51, v43, v51, v43
	v_mul_f32_e32 v50, 0x3f4c422a, v50
	v_mul_f32_e32 v51, 0x3f4c422a, v51
	v_mul_f32_e32 v50, -2.0, v50
	v_mul_f32_e32 v51, -2.0, v51
	v_mul_f32_e32 v50, 0x3fb8aa3b, v50
	v_mul_f32_e32 v51, 0x3fb8aa3b, v51
	v_exp_f32_e32 v50, v50
	v_exp_f32_e32 v51, v51
	s_nop 0
	v_pk_add_f32 v[50:51], v[50:51], 1.0 op_sel_hi:[1,0]
	v_rcp_f32_e32 v47, v46
	s_nop 0
	v_mul_f32_e32 v40, v40, v47
	v_cvt_pk_bf16_f32 v40, v40, v41
	v_rcp_f32_e32 v41, v51
	s_nop 0
	v_mul_f32_e32 v41, v43, v41
	v_mul_f32_e32 v46, 0x3d372713, v36
	v_mul_f32_e32 v47, 0x3d372713, v37
	v_mul_f32_e32 v46, v36, v46
	v_mul_f32_e32 v47, v37, v47
	v_fma_f32 v46, v36, v46, v36
	v_fma_f32 v47, v37, v47, v37
	v_mul_f32_e32 v46, 0x3f4c422a, v46
	v_mul_f32_e32 v47, 0x3f4c422a, v47
	v_mul_f32_e32 v46, -2.0, v46
	v_mul_f32_e32 v47, -2.0, v47
	v_mul_f32_e32 v46, 0x3fb8aa3b, v46
	v_mul_f32_e32 v47, 0x3fb8aa3b, v47
	v_exp_f32_e32 v46, v46
	v_exp_f32_e32 v47, v47
	v_rcp_f32_e32 v43, v50
	s_nop 0
	v_mul_f32_e32 v50, v42, v43
	v_cvt_pk_bf16_f32 v41, v50, v41
	v_pk_add_f32 v[42:43], v[46:47], 1.0 op_sel_hi:[1,0]
	ds_write_b64 v56, v[40:41] offset:8480
	s_nop 0
	v_rcp_f32_e32 v40, v43
	s_nop 0
	v_mul_f32_e32 v37, v37, v40
	v_mul_f32_e32 v41, 0x3d372713, v39
	v_mul_f32_e32 v40, 0x3d372713, v38
	v_mul_f32_e32 v40, v38, v40
	v_mul_f32_e32 v41, v39, v41
	v_fma_f32 v40, v38, v40, v38
	v_fma_f32 v41, v39, v41, v39
	v_mul_f32_e32 v40, 0x3f4c422a, v40
	v_mul_f32_e32 v41, 0x3f4c422a, v41
	v_mul_f32_e32 v40, -2.0, v40
	v_mul_f32_e32 v41, -2.0, v41
	v_mul_f32_e32 v40, 0x3fb8aa3b, v40
	v_mul_f32_e32 v41, 0x3fb8aa3b, v41
	v_exp_f32_e32 v40, v40
	v_exp_f32_e32 v41, v41
	s_nop 0
	v_pk_add_f32 v[40:41], v[40:41], 1.0 op_sel_hi:[1,0]
	v_rcp_f32_e32 v43, v42
	s_nop 0
	v_mul_f32_e32 v36, v36, v43
	v_cvt_pk_bf16_f32 v36, v36, v37
	v_rcp_f32_e32 v37, v41
	s_nop 0
	v_mul_f32_e32 v37, v39, v37
	v_mul_f32_e32 v42, 0x3d372713, v32
	v_mul_f32_e32 v43, 0x3d372713, v33
	v_mul_f32_e32 v42, v32, v42
	v_mul_f32_e32 v43, v33, v43
	v_fma_f32 v42, v32, v42, v32
	v_fma_f32 v43, v33, v43, v33
	v_mul_f32_e32 v42, 0x3f4c422a, v42
	v_mul_f32_e32 v43, 0x3f4c422a, v43
	v_mul_f32_e32 v42, -2.0, v42
	v_mul_f32_e32 v43, -2.0, v43
	v_mul_f32_e32 v42, 0x3fb8aa3b, v42
	v_mul_f32_e32 v43, 0x3fb8aa3b, v43
	v_exp_f32_e32 v42, v42
	v_exp_f32_e32 v43, v43
	v_rcp_f32_e32 v39, v40
	s_nop 0
	v_mul_f32_e32 v40, v38, v39
	v_cvt_pk_bf16_f32 v37, v40, v37
	v_pk_add_f32 v[38:39], v[42:43], 1.0 op_sel_hi:[1,0]
	ds_write_b64 v56, v[36:37] offset:16928
	s_nop 0
	v_rcp_f32_e32 v36, v39
	s_nop 0
	v_mul_f32_e32 v33, v33, v36
	v_mul_f32_e32 v37, 0x3d372713, v35
	v_mul_f32_e32 v36, 0x3d372713, v34
	v_mul_f32_e32 v36, v34, v36
	v_mul_f32_e32 v37, v35, v37
	v_fma_f32 v36, v34, v36, v34
	v_fma_f32 v37, v35, v37, v35
	v_mul_f32_e32 v36, 0x3f4c422a, v36
	v_mul_f32_e32 v37, 0x3f4c422a, v37
	v_mul_f32_e32 v36, -2.0, v36
	v_mul_f32_e32 v37, -2.0, v37
	v_mul_f32_e32 v36, 0x3fb8aa3b, v36
	v_mul_f32_e32 v37, 0x3fb8aa3b, v37
	v_exp_f32_e32 v36, v36
	v_exp_f32_e32 v37, v37
	s_nop 0
	v_pk_add_f32 v[36:37], v[36:37], 1.0 op_sel_hi:[1,0]
	v_rcp_f32_e32 v39, v38
	s_nop 0
	v_mul_f32_e32 v32, v32, v39
	v_cvt_pk_bf16_f32 v32, v32, v33
	v_rcp_f32_e32 v33, v37
	s_nop 0
	v_mul_f32_e32 v33, v35, v33
	v_rcp_f32_e32 v35, v36
	s_nop 0
	v_mul_f32_e32 v34, v34, v35
	v_cvt_pk_bf16_f32 v33, v34, v33
	ds_write_b64 v56, v[32:33] offset:25376
	global_load_dwordx4 v[32:35], v[66:67], off offset:128
	global_load_dwordx4 v[36:39], v[66:67], off offset:1152
	global_load_dwordx4 v[40:43], v[66:67], off offset:2176
	global_load_dwordx4 v[44:47], v[66:67], off offset:3200
	global_load_dwordx4 v[48:51], v[68:69], off offset:128
	global_load_dwordx4 v[52:55], v[68:69], off offset:1152
	global_load_dwordx4 v[58:61], v[68:69], off offset:2176
	global_load_dwordx4 v[74:77], v[68:69], off offset:3200
	global_load_dwordx4 v[82:85], v[72:73], off offset:128
	global_load_dwordx4 v[86:89], v[72:73], off offset:1152
	global_load_dwordx4 v[90:93], v[72:73], off offset:2176
	global_load_dwordx4 v[94:97], v[72:73], off offset:3200
	global_load_dwordx4 v[98:101], v[70:71], off offset:128
	global_load_dwordx4 v[102:105], v[70:71], off offset:1152
	global_load_dwordx4 v[106:109], v[70:71], off offset:2176
	global_load_dwordx4 v[110:113], v[70:71], off offset:3200
	s_waitcnt vmcnt(15)
	v_pk_add_f32 v[32:33], v[32:33], 0 op_sel_hi:[1,0]
	s_waitcnt vmcnt(14)
	v_pk_add_f32 v[32:33], v[32:33], v[36:37]
	v_pk_add_f32 v[34:35], v[34:35], 0 op_sel_hi:[1,0]
	s_waitcnt vmcnt(13)
	v_pk_add_f32 v[32:33], v[32:33], v[40:41]
	v_pk_add_f32 v[34:35], v[34:35], v[38:39]
	s_waitcnt vmcnt(12)
	v_pk_add_f32 v[32:33], v[32:33], v[44:45]
	v_pk_add_f32 v[34:35], v[34:35], v[42:43]
	s_waitcnt vmcnt(11)
	v_pk_add_f32 v[32:33], v[32:33], v[48:49]
	v_pk_add_f32 v[34:35], v[34:35], v[46:47]
	s_waitcnt vmcnt(10)
	v_pk_add_f32 v[32:33], v[32:33], v[52:53]
	v_pk_add_f32 v[34:35], v[34:35], v[50:51]
	s_waitcnt vmcnt(9)
	v_pk_add_f32 v[32:33], v[32:33], v[58:59]
	v_pk_add_f32 v[34:35], v[34:35], v[54:55]
	s_waitcnt vmcnt(8)
	v_pk_add_f32 v[32:33], v[32:33], v[74:75]
	v_pk_add_f32 v[34:35], v[34:35], v[60:61]
	s_waitcnt vmcnt(7)
	v_pk_add_f32 v[32:33], v[32:33], v[82:83]
	v_pk_add_f32 v[34:35], v[34:35], v[76:77]
	s_waitcnt vmcnt(6)
	v_pk_add_f32 v[32:33], v[32:33], v[86:87]
	v_pk_add_f32 v[34:35], v[34:35], v[84:85]
	s_waitcnt vmcnt(5)
	v_pk_add_f32 v[32:33], v[32:33], v[90:91]
	v_pk_add_f32 v[34:35], v[34:35], v[88:89]
	s_waitcnt vmcnt(4)
	v_pk_add_f32 v[32:33], v[32:33], v[94:95]
	v_pk_add_f32 v[34:35], v[34:35], v[92:93]
	s_waitcnt vmcnt(3)
; DI unsigned pk2(float lo, float hi) { f32x2 v = {lo, hi}; return __builtin_bit_cast(unsigned, __builtin_convertvector(v, bfx2)); }
; DI float gelu_tanh(float x) { const float u = 0.7978845608028654f * (x + 0.044715f * x * x * x); return x / (1.f + __expf(-2.f * u)); }
; DI void compress_item(const Params& p, int layer, int item, bf16_t* smem) {
;     ...
;   for (int j = 0; j < 4; ++j) {
;     asm volatile("" ::: "memory");
;     f32x4 bv = {0.f, 0.f, 0.f, 0.f};
;     for (int pc = 0; pc < 16; ++pc) bv += *(const f32x4*)(b1 + pc * 256 + wn * 64 + j * 16 + quad * 4);
; #pragma unroll
;     for (int i = 0; i < 4; ++i) {
;       const int row = wm * 64 + i * 16 + l15, col = wn * 64 + j * 16 + quad * 4;
;       *(u32x2*)(H + row * LDH + col) = (u32x2){pk2(gelu_tanh(acc[i][j][0] + bv[0]), gelu_tanh(acc[i][j][1] + bv[1])), pk2(gelu_tanh(acc[i][j][2] + bv[2]), gelu_tanh(acc[i][j][3] + bv[3]))};
;     }
	v_pk_add_f32 v[32:33], v[32:33], v[98:99]
	v_pk_add_f32 v[34:35], v[34:35], v[96:97]
	s_waitcnt vmcnt(2)
	v_pk_add_f32 v[32:33], v[32:33], v[102:103]
	v_pk_add_f32 v[34:35], v[34:35], v[100:101]
	s_waitcnt vmcnt(1)
	v_pk_add_f32 v[32:33], v[32:33], v[106:107]
	v_pk_add_f32 v[34:35], v[34:35], v[104:105]
	s_waitcnt vmcnt(0)
	v_pk_add_f32 v[32:33], v[32:33], v[110:111]
	s_nop 0
	v_pk_add_f32 v[36:37], v[28:29], v[32:33]
	v_pk_add_f32 v[24:25], v[24:25], v[32:33]
	v_mul_f32_e32 v28, 0x3d372713, v36
	v_mul_f32_e32 v29, 0x3d372713, v37
	v_mul_f32_e32 v28, v36, v28
	v_mul_f32_e32 v29, v37, v29
	v_fma_f32 v28, v36, v28, v36
	v_fma_f32 v29, v37, v29, v37
	v_mul_f32_e32 v28, 0x3f4c422a, v28
	v_mul_f32_e32 v29, 0x3f4c422a, v29
	v_mul_f32_e32 v28, -2.0, v28
	v_mul_f32_e32 v29, -2.0, v29
	v_mul_f32_e32 v28, 0x3fb8aa3b, v28
	v_mul_f32_e32 v29, 0x3fb8aa3b, v29
	v_exp_f32_e32 v28, v28
	v_exp_f32_e32 v29, v29
	v_pk_add_f32 v[20:21], v[20:21], v[32:33]
	v_pk_add_f32 v[16:17], v[16:17], v[32:33]
	v_pk_add_f32 v[38:39], v[28:29], 1.0 op_sel_hi:[1,0]
	s_nop 0
	v_pk_add_f32 v[28:29], v[34:35], v[108:109]
	v_pk_add_f32 v[28:29], v[28:29], v[112:113]
	v_pk_add_f32 v[30:31], v[30:31], v[28:29]
	v_rcp_f32_e32 v34, v39
	s_nop 0
	v_mul_f32_e32 v37, v37, v34
	v_mul_f32_e32 v34, 0x3d372713, v30
	v_mul_f32_e32 v35, 0x3d372713, v31
	v_mul_f32_e32 v34, v30, v34
	v_mul_f32_e32 v35, v31, v35
	v_fma_f32 v34, v30, v34, v30
	v_fma_f32 v35, v31, v35, v31
	v_mul_f32_e32 v34, 0x3f4c422a, v34
	v_mul_f32_e32 v35, 0x3f4c422a, v35
	v_mul_f32_e32 v34, -2.0, v34
	v_mul_f32_e32 v35, -2.0, v35
	v_mul_f32_e32 v34, 0x3fb8aa3b, v34
	v_mul_f32_e32 v35, 0x3fb8aa3b, v35
	v_exp_f32_e32 v34, v34
	v_exp_f32_e32 v35, v35
	s_nop 0
	v_pk_add_f32 v[34:35], v[34:35], 1.0 op_sel_hi:[1,0]
	v_rcp_f32_e32 v39, v38
	s_nop 0
	v_mul_f32_e32 v36, v36, v39
	v_cvt_pk_bf16_f32 v36, v36, v37
	v_rcp_f32_e32 v37, v35
	s_nop 0
	v_mul_f32_e32 v35, v31, v37
	v_pk_add_f32 v[26:27], v[26:27], v[28:29]
	v_mul_f32_e32 v38, 0x3d372713, v24
	v_mul_f32_e32 v39, 0x3d372713, v25
	v_mul_f32_e32 v38, v24, v38
	v_mul_f32_e32 v39, v25, v39
	v_fma_f32 v38, v24, v38, v24
	v_fma_f32 v39, v25, v39, v25
	v_mul_f32_e32 v38, 0x3f4c422a, v38
	v_mul_f32_e32 v39, 0x3f4c422a, v39
	v_mul_f32_e32 v38, -2.0, v38
	v_mul_f32_e32 v39, -2.0, v39
	v_mul_f32_e32 v38, 0x3fb8aa3b, v38
	v_mul_f32_e32 v39, 0x3fb8aa3b, v39
	v_exp_f32_e32 v38, v38
	v_exp_f32_e32 v39, v39
	v_rcp_f32_e32 v31, v34
	s_nop 0
	v_mul_f32_e32 v34, v30, v31
	v_cvt_pk_bf16_f32 v37, v34, v35
	v_pk_add_f32 v[30:31], v[38:39], 1.0 op_sel_hi:[1,0]
	ds_write_b64 v56, v[36:37] offset:64
	v_pk_add_f32 v[22:23], v[22:23], v[28:29]
	v_pk_add_f32 v[18:19], v[18:19], v[28:29]
	v_rcp_f32_e32 v34, v31
	s_nop 0
	v_mul_f32_e32 v25, v25, v34
	v_mul_f32_e32 v34, 0x3d372713, v26
	v_mul_f32_e32 v35, 0x3d372713, v27
	v_mul_f32_e32 v34, v26, v34
	v_mul_f32_e32 v35, v27, v35
	v_fma_f32 v34, v26, v34, v26
	v_fma_f32 v35, v27, v35, v27
	v_mul_f32_e32 v34, 0x3f4c422a, v34
	v_mul_f32_e32 v35, 0x3f4c422a, v35
	v_mul_f32_e32 v34, -2.0, v34
	v_mul_f32_e32 v35, -2.0, v35
	v_mul_f32_e32 v34, 0x3fb8aa3b, v34
	v_mul_f32_e32 v35, 0x3fb8aa3b, v35
	v_exp_f32_e32 v34, v34
	v_exp_f32_e32 v35, v35
	s_nop 0
	v_pk_add_f32 v[34:35], v[34:35], 1.0 op_sel_hi:[1,0]
	v_rcp_f32_e32 v31, v30
	s_nop 0
	v_mul_f32_e32 v24, v24, v31
	v_cvt_pk_bf16_f32 v24, v24, v25
	v_rcp_f32_e32 v25, v35
	s_nop 0
	v_mul_f32_e32 v25, v27, v25
	v_mul_f32_e32 v30, 0x3d372713, v20
	v_mul_f32_e32 v31, 0x3d372713, v21
	v_mul_f32_e32 v30, v20, v30
	v_mul_f32_e32 v31, v21, v31
	v_fma_f32 v30, v20, v30, v20
	v_fma_f32 v31, v21, v31, v21
	v_mul_f32_e32 v30, 0x3f4c422a, v30
	v_mul_f32_e32 v31, 0x3f4c422a, v31
	v_mul_f32_e32 v30, -2.0, v30
	v_mul_f32_e32 v31, -2.0, v31
	v_mul_f32_e32 v30, 0x3fb8aa3b, v30
	v_mul_f32_e32 v31, 0x3fb8aa3b, v31
	v_exp_f32_e32 v30, v30
	v_exp_f32_e32 v31, v31
	v_rcp_f32_e32 v27, v34
	s_nop 0
	v_mul_f32_e32 v34, v26, v27
	v_cvt_pk_bf16_f32 v25, v34, v25
	v_pk_add_f32 v[26:27], v[30:31], 1.0 op_sel_hi:[1,0]
	ds_write_b64 v56, v[24:25] offset:8512
	s_nop 0
	v_rcp_f32_e32 v24, v27
	s_nop 0
	v_mul_f32_e32 v21, v21, v24
	v_mul_f32_e32 v25, 0x3d372713, v23
	v_mul_f32_e32 v24, 0x3d372713, v22
	v_mul_f32_e32 v24, v22, v24
	v_mul_f32_e32 v25, v23, v25
	v_fma_f32 v24, v22, v24, v22
	v_fma_f32 v25, v23, v25, v23
	v_mul_f32_e32 v24, 0x3f4c422a, v24
	v_mul_f32_e32 v25, 0x3f4c422a, v25
	v_mul_f32_e32 v24, -2.0, v24
	v_mul_f32_e32 v25, -2.0, v25
	v_mul_f32_e32 v24, 0x3fb8aa3b, v24
	v_mul_f32_e32 v25, 0x3fb8aa3b, v25
	v_exp_f32_e32 v24, v24
	v_exp_f32_e32 v25, v25
	s_nop 0
	v_pk_add_f32 v[24:25], v[24:25], 1.0 op_sel_hi:[1,0]
	v_rcp_f32_e32 v27, v26
	s_nop 0
	v_mul_f32_e32 v20, v20, v27
	v_cvt_pk_bf16_f32 v20, v20, v21
	v_rcp_f32_e32 v21, v25
	s_nop 0
	v_mul_f32_e32 v21, v23, v21
	v_mul_f32_e32 v26, 0x3d372713, v16
	v_mul_f32_e32 v27, 0x3d372713, v17
	v_mul_f32_e32 v26, v16, v26
	v_mul_f32_e32 v27, v17, v27
	v_fma_f32 v26, v16, v26, v16
	v_fma_f32 v27, v17, v27, v17
	v_mul_f32_e32 v26, 0x3f4c422a, v26
	v_mul_f32_e32 v27, 0x3f4c422a, v27
	v_mul_f32_e32 v26, -2.0, v26
	v_mul_f32_e32 v27, -2.0, v27
	v_mul_f32_e32 v26, 0x3fb8aa3b, v26
	v_mul_f32_e32 v27, 0x3fb8aa3b, v27
	v_exp_f32_e32 v26, v26
	v_exp_f32_e32 v27, v27
	v_rcp_f32_e32 v23, v24
	s_nop 0
	v_mul_f32_e32 v24, v22, v23
	v_cvt_pk_bf16_f32 v21, v24, v21
	v_pk_add_f32 v[22:23], v[26:27], 1.0 op_sel_hi:[1,0]
	ds_write_b64 v56, v[20:21] offset:16960
	s_nop 0
	v_rcp_f32_e32 v20, v23
	s_nop 0
	v_mul_f32_e32 v17, v17, v20
	v_mul_f32_e32 v21, 0x3d372713, v19
	v_mul_f32_e32 v20, 0x3d372713, v18
	v_mul_f32_e32 v20, v18, v20
	v_mul_f32_e32 v21, v19, v21
	v_fma_f32 v20, v18, v20, v18
	v_fma_f32 v21, v19, v21, v19
; DI unsigned pk2(float lo, float hi) { f32x2 v = {lo, hi}; return __builtin_bit_cast(unsigned, __builtin_convertvector(v, bfx2)); }
; DI float gelu_tanh(float x) { const float u = 0.7978845608028654f * (x + 0.044715f * x * x * x); return x / (1.f + __expf(-2.f * u)); }
; DI void compress_item(const Params& p, int layer, int item, bf16_t* smem) {
;     ...
;   for (int j = 0; j < 4; ++j) {
;     asm volatile("" ::: "memory");
;     f32x4 bv = {0.f, 0.f, 0.f, 0.f};
;     for (int pc = 0; pc < 16; ++pc) bv += *(const f32x4*)(b1 + pc * 256 + wn * 64 + j * 16 + quad * 4);
; #pragma unroll
;     for (int i = 0; i < 4; ++i) {
;       const int row = wm * 64 + i * 16 + l15, col = wn * 64 + j * 16 + quad * 4;
;       *(u32x2*)(H + row * LDH + col) = (u32x2){pk2(gelu_tanh(acc[i][j][0] + bv[0]), gelu_tanh(acc[i][j][1] + bv[1])), pk2(gelu_tanh(acc[i][j][2] + bv[2]), gelu_tanh(acc[i][j][3] + bv[3]))};
;     }
	v_mul_f32_e32 v20, 0x3f4c422a, v20
	v_mul_f32_e32 v21, 0x3f4c422a, v21
	v_mul_f32_e32 v20, -2.0, v20
	v_mul_f32_e32 v21, -2.0, v21
	v_mul_f32_e32 v20, 0x3fb8aa3b, v20
	v_mul_f32_e32 v21, 0x3fb8aa3b, v21
	v_exp_f32_e32 v20, v20
	v_exp_f32_e32 v21, v21
	s_nop 0
	v_pk_add_f32 v[20:21], v[20:21], 1.0 op_sel_hi:[1,0]
	v_rcp_f32_e32 v23, v22
	s_nop 0
	v_mul_f32_e32 v16, v16, v23
	v_cvt_pk_bf16_f32 v16, v16, v17
	v_rcp_f32_e32 v17, v21
	s_nop 0
	v_mul_f32_e32 v17, v19, v17
	v_rcp_f32_e32 v19, v20
	s_nop 0
	v_mul_f32_e32 v18, v18, v19
	v_cvt_pk_bf16_f32 v17, v18, v17
	ds_write_b64 v56, v[16:17] offset:25408
	global_load_dwordx4 v[16:19], v[66:67], off offset:192
	global_load_dwordx4 v[20:23], v[66:67], off offset:1216
	global_load_dwordx4 v[24:27], v[66:67], off offset:2240
	global_load_dwordx4 v[28:31], v[66:67], off offset:3264
	global_load_dwordx4 v[32:35], v[68:69], off offset:192
	global_load_dwordx4 v[36:39], v[68:69], off offset:1216
	global_load_dwordx4 v[40:43], v[68:69], off offset:2240
	global_load_dwordx4 v[44:47], v[68:69], off offset:3264
	global_load_dwordx4 v[48:51], v[72:73], off offset:192
	global_load_dwordx4 v[52:55], v[72:73], off offset:1216
	global_load_dwordx4 v[58:61], v[72:73], off offset:2240
	global_load_dwordx4 v[74:77], v[72:73], off offset:3264
	global_load_dwordx4 v[82:85], v[70:71], off offset:192
	global_load_dwordx4 v[86:89], v[70:71], off offset:1216
	global_load_dwordx4 v[90:93], v[70:71], off offset:2240
	global_load_dwordx4 v[66:69], v[70:71], off offset:3264
	s_waitcnt vmcnt(15)
	v_pk_add_f32 v[16:17], v[16:17], 0 op_sel_hi:[1,0]
	s_waitcnt vmcnt(14)
	v_pk_add_f32 v[16:17], v[16:17], v[20:21]
	v_pk_add_f32 v[18:19], v[18:19], 0 op_sel_hi:[1,0]
	s_waitcnt vmcnt(13)
	v_pk_add_f32 v[16:17], v[16:17], v[24:25]
	v_pk_add_f32 v[18:19], v[18:19], v[22:23]
	s_waitcnt vmcnt(12)
	v_pk_add_f32 v[16:17], v[16:17], v[28:29]
	v_pk_add_f32 v[18:19], v[18:19], v[26:27]
	s_waitcnt vmcnt(11)
	v_pk_add_f32 v[16:17], v[16:17], v[32:33]
	v_pk_add_f32 v[18:19], v[18:19], v[30:31]
	s_waitcnt vmcnt(10)
	v_pk_add_f32 v[16:17], v[16:17], v[36:37]
	v_pk_add_f32 v[18:19], v[18:19], v[34:35]
	s_waitcnt vmcnt(9)
	v_pk_add_f32 v[16:17], v[16:17], v[40:41]
	v_pk_add_f32 v[18:19], v[18:19], v[38:39]
	s_waitcnt vmcnt(8)
	v_pk_add_f32 v[16:17], v[16:17], v[44:45]
	v_pk_add_f32 v[18:19], v[18:19], v[42:43]
	s_waitcnt vmcnt(7)
	v_pk_add_f32 v[16:17], v[16:17], v[48:49]
	v_pk_add_f32 v[18:19], v[18:19], v[46:47]
	s_waitcnt vmcnt(6)
	v_pk_add_f32 v[16:17], v[16:17], v[52:53]
	v_pk_add_f32 v[18:19], v[18:19], v[50:51]
	s_waitcnt vmcnt(5)
	v_pk_add_f32 v[16:17], v[16:17], v[58:59]
	v_pk_add_f32 v[18:19], v[18:19], v[54:55]
	s_waitcnt vmcnt(4)
	v_pk_add_f32 v[16:17], v[16:17], v[74:75]
	v_pk_add_f32 v[18:19], v[18:19], v[60:61]
	s_waitcnt vmcnt(3)
	v_pk_add_f32 v[16:17], v[16:17], v[82:83]
	v_pk_add_f32 v[18:19], v[18:19], v[76:77]
	s_waitcnt vmcnt(2)
	v_pk_add_f32 v[16:17], v[16:17], v[86:87]
	v_pk_add_f32 v[18:19], v[18:19], v[84:85]
	s_waitcnt vmcnt(1)
	v_pk_add_f32 v[16:17], v[16:17], v[90:91]
	v_pk_add_f32 v[18:19], v[18:19], v[88:89]
	s_waitcnt vmcnt(0)
	v_pk_add_f32 v[16:17], v[16:17], v[66:67]
	v_lshlrev_b32_e32 v48, 4, v80
	v_pk_add_f32 v[20:21], v[12:13], v[16:17]
	v_pk_add_f32 v[8:9], v[8:9], v[16:17]
	v_mul_f32_e32 v12, 0x3d372713, v20
	v_mul_f32_e32 v13, 0x3d372713, v21
	v_mul_f32_e32 v12, v20, v12
	v_mul_f32_e32 v13, v21, v13
	v_fma_f32 v12, v20, v12, v20
	v_fma_f32 v13, v21, v13, v21
	v_mul_f32_e32 v12, 0x3f4c422a, v12
	v_mul_f32_e32 v13, 0x3f4c422a, v13
	v_mul_f32_e32 v12, -2.0, v12
	v_mul_f32_e32 v13, -2.0, v13
	v_mul_f32_e32 v12, 0x3fb8aa3b, v12
	v_mul_f32_e32 v13, 0x3fb8aa3b, v13
	v_exp_f32_e32 v12, v12
	v_exp_f32_e32 v13, v13
	v_pk_add_f32 v[4:5], v[4:5], v[16:17]
	v_pk_add_f32 v[0:1], v[0:1], v[16:17]
	v_mov_b32_e32 v43, v65
	v_pk_add_f32 v[22:23], v[12:13], 1.0 op_sel_hi:[1,0]
	v_pk_add_f32 v[12:13], v[18:19], v[92:93]
	v_pk_add_f32 v[12:13], v[12:13], v[68:69]
	v_mov_b32_e32 v45, v65
	v_pk_add_f32 v[14:15], v[14:15], v[12:13]
	v_rcp_f32_e32 v18, v23
	s_nop 0
	v_mul_f32_e32 v21, v21, v18
	v_mul_f32_e32 v19, 0x3d372713, v15
	v_mul_f32_e32 v18, 0x3d372713, v14
	v_mul_f32_e32 v18, v14, v18
	v_mul_f32_e32 v19, v15, v19
	v_fma_f32 v18, v14, v18, v14
	v_fma_f32 v19, v15, v19, v15
	v_mul_f32_e32 v18, 0x3f4c422a, v18
	v_mul_f32_e32 v19, 0x3f4c422a, v19
	v_mul_f32_e32 v18, -2.0, v18
	v_mul_f32_e32 v19, -2.0, v19
	v_mul_f32_e32 v18, 0x3fb8aa3b, v18
	v_mul_f32_e32 v19, 0x3fb8aa3b, v19
	v_exp_f32_e32 v18, v18
	v_exp_f32_e32 v19, v19
	s_nop 0
	v_pk_add_f32 v[18:19], v[18:19], 1.0 op_sel_hi:[1,0]
	v_rcp_f32_e32 v23, v22
	s_nop 0
	v_mul_f32_e32 v20, v20, v23
	v_cvt_pk_bf16_f32 v20, v20, v21
	v_rcp_f32_e32 v21, v19
	s_nop 0
	v_mul_f32_e32 v19, v15, v21
	v_pk_add_f32 v[10:11], v[10:11], v[12:13]
	v_mul_f32_e32 v22, 0x3d372713, v8
	v_mul_f32_e32 v23, 0x3d372713, v9
	v_mul_f32_e32 v22, v8, v22
	v_mul_f32_e32 v23, v9, v23
	v_fma_f32 v22, v8, v22, v8
	v_fma_f32 v23, v9, v23, v9
	v_mul_f32_e32 v22, 0x3f4c422a, v22
	v_mul_f32_e32 v23, 0x3f4c422a, v23
	v_mul_f32_e32 v22, -2.0, v22
	v_mul_f32_e32 v23, -2.0, v23
	v_mul_f32_e32 v22, 0x3fb8aa3b, v22
	v_mul_f32_e32 v23, 0x3fb8aa3b, v23
	v_exp_f32_e32 v22, v22
	v_exp_f32_e32 v23, v23
	v_rcp_f32_e32 v15, v18
	s_nop 0
	v_mul_f32_e32 v18, v14, v15
	v_cvt_pk_bf16_f32 v21, v18, v19
	v_pk_add_f32 v[14:15], v[22:23], 1.0 op_sel_hi:[1,0]
	ds_write_b64 v56, v[20:21] offset:96
	v_pk_add_f32 v[6:7], v[6:7], v[12:13]
	v_pk_add_f32 v[2:3], v[2:3], v[12:13]
	v_rcp_f32_e32 v18, v15
	s_nop 0
	v_mul_f32_e32 v9, v9, v18
	v_mul_f32_e32 v18, 0x3d372713, v10
	v_mul_f32_e32 v19, 0x3d372713, v11
	v_mul_f32_e32 v18, v10, v18
; DI unsigned pk2(float lo, float hi) { f32x2 v = {lo, hi}; return __builtin_bit_cast(unsigned, __builtin_convertvector(v, bfx2)); }
; DI float gelu_tanh(float x) { const float u = 0.7978845608028654f * (x + 0.044715f * x * x * x); return x / (1.f + __expf(-2.f * u)); }
; DI f32x4 mfma16(bf16x8 a, bf16x8 b, f32x4 c) { return __builtin_amdgcn_mfma_f32_16x16x32_bf16(a, b, c, 0, 0, 0); }
; DI void compress_item(const Params& p, int layer, int item, bf16_t* smem) {
;     ...
; #pragma unroll
;     for (int i = 0; i < 4; ++i) {
;       const int row = wm * 64 + i * 16 + l15, col = wn * 64 + j * 16 + quad * 4;
;       *(u32x2*)(H + row * LDH + col) = (u32x2){pk2(gelu_tanh(acc[i][j][0] + bv[0]), gelu_tanh(acc[i][j][1] + bv[1])), pk2(gelu_tanh(acc[i][j][2] + bv[2]), gelu_tanh(acc[i][j][3] + bv[3]))};
;     }
;   }
;   __syncthreads();
;   f32x4 a2[4];
; #pragma unroll
;   for (int j = 0; j < 4; ++j) a2[j] = (f32x4){0.f, 0.f, 0.f, 0.f};
;   const bf16_t* w2 = wl + (kv ? W_2V : W_2K);
; #pragma unroll
;   for (int ks = 0; ks < 8; ++ks) {
;     const bf16x8 a = *(const bf16x8*)(H + (wid * 16 + l15) * LDH + ks * 32 + quad * 8);
; #pragma unroll
;     for (int j = 0; j < 4; ++j) a2[j] = mfma16(a, *(const bf16x8*)(w2 + (size_t)(j * 16 + l15) * 256 + ks * 32 + quad * 8), a2[j]);
;   }
	v_mul_f32_e32 v19, v11, v19
	v_fma_f32 v18, v10, v18, v10
	v_fma_f32 v19, v11, v19, v11
	v_mul_f32_e32 v18, 0x3f4c422a, v18
	v_mul_f32_e32 v19, 0x3f4c422a, v19
	v_mul_f32_e32 v18, -2.0, v18
	v_mul_f32_e32 v19, -2.0, v19
	v_mul_f32_e32 v18, 0x3fb8aa3b, v18
	v_mul_f32_e32 v19, 0x3fb8aa3b, v19
	v_exp_f32_e32 v18, v18
	v_exp_f32_e32 v19, v19
	s_nop 0
	v_pk_add_f32 v[18:19], v[18:19], 1.0 op_sel_hi:[1,0]
	v_rcp_f32_e32 v15, v14
	s_nop 0
	v_mul_f32_e32 v8, v8, v15
	v_cvt_pk_bf16_f32 v8, v8, v9
	v_rcp_f32_e32 v9, v19
	s_nop 0
	v_mul_f32_e32 v9, v11, v9
	v_mul_f32_e32 v14, 0x3d372713, v4
	v_mul_f32_e32 v15, 0x3d372713, v5
	v_mul_f32_e32 v14, v4, v14
	v_mul_f32_e32 v15, v5, v15
	v_fma_f32 v14, v4, v14, v4
	v_fma_f32 v15, v5, v15, v5
	v_mul_f32_e32 v14, 0x3f4c422a, v14
	v_mul_f32_e32 v15, 0x3f4c422a, v15
	v_mul_f32_e32 v14, -2.0, v14
	v_mul_f32_e32 v15, -2.0, v15
	v_mul_f32_e32 v14, 0x3fb8aa3b, v14
	v_mul_f32_e32 v15, 0x3fb8aa3b, v15
	v_exp_f32_e32 v14, v14
	v_exp_f32_e32 v15, v15
	v_rcp_f32_e32 v11, v18
	s_nop 0
	v_mul_f32_e32 v18, v10, v11
	v_cvt_pk_bf16_f32 v9, v18, v9
	v_pk_add_f32 v[10:11], v[14:15], 1.0 op_sel_hi:[1,0]
	ds_write_b64 v56, v[8:9] offset:8544
	s_nop 0
	v_rcp_f32_e32 v8, v11
	s_nop 0
	v_mul_f32_e32 v5, v5, v8
	v_mul_f32_e32 v9, 0x3d372713, v7
	v_mul_f32_e32 v8, 0x3d372713, v6
	v_mul_f32_e32 v8, v6, v8
	v_mul_f32_e32 v9, v7, v9
	v_fma_f32 v8, v6, v8, v6
	v_fma_f32 v9, v7, v9, v7
	v_mul_f32_e32 v8, 0x3f4c422a, v8
	v_mul_f32_e32 v9, 0x3f4c422a, v9
	v_mul_f32_e32 v8, -2.0, v8
	v_mul_f32_e32 v9, -2.0, v9
	v_mul_f32_e32 v8, 0x3fb8aa3b, v8
	v_mul_f32_e32 v9, 0x3fb8aa3b, v9
	v_exp_f32_e32 v8, v8
	v_exp_f32_e32 v9, v9
	s_nop 0
	v_pk_add_f32 v[8:9], v[8:9], 1.0 op_sel_hi:[1,0]
	v_rcp_f32_e32 v11, v10
	s_nop 0
	v_mul_f32_e32 v4, v4, v11
	v_cvt_pk_bf16_f32 v4, v4, v5
	v_rcp_f32_e32 v5, v9
	s_nop 0
	v_mul_f32_e32 v5, v7, v5
	v_mul_f32_e32 v10, 0x3d372713, v0
	v_mul_f32_e32 v11, 0x3d372713, v1
	v_mul_f32_e32 v10, v0, v10
	v_mul_f32_e32 v11, v1, v11
	v_fma_f32 v10, v0, v10, v0
	v_fma_f32 v11, v1, v11, v1
	v_mul_f32_e32 v10, 0x3f4c422a, v10
	v_mul_f32_e32 v11, 0x3f4c422a, v11
	v_mul_f32_e32 v10, -2.0, v10
	v_mul_f32_e32 v11, -2.0, v11
	v_mul_f32_e32 v10, 0x3fb8aa3b, v10
	v_mul_f32_e32 v11, 0x3fb8aa3b, v11
	v_exp_f32_e32 v10, v10
	v_exp_f32_e32 v11, v11
	v_rcp_f32_e32 v7, v8
	s_nop 0
	v_mul_f32_e32 v8, v6, v7
	v_cvt_pk_bf16_f32 v5, v8, v5
	v_pk_add_f32 v[6:7], v[10:11], 1.0 op_sel_hi:[1,0]
	ds_write_b64 v56, v[4:5] offset:16992
	s_nop 0
	v_rcp_f32_e32 v4, v7
	s_nop 0
	v_mul_f32_e32 v1, v1, v4
	v_mul_f32_e32 v5, 0x3d372713, v3
	v_mul_f32_e32 v4, 0x3d372713, v2
	v_mul_f32_e32 v4, v2, v4
	v_mul_f32_e32 v5, v3, v5
	v_fma_f32 v4, v2, v4, v2
	v_fma_f32 v5, v3, v5, v3
	v_mul_f32_e32 v4, 0x3f4c422a, v4
	v_mul_f32_e32 v5, 0x3f4c422a, v5
	v_mul_f32_e32 v4, -2.0, v4
	v_mul_f32_e32 v5, -2.0, v5
	v_mul_f32_e32 v4, 0x3fb8aa3b, v4
	v_mul_f32_e32 v5, 0x3fb8aa3b, v5
	v_exp_f32_e32 v4, v4
	v_exp_f32_e32 v5, v5
	s_nop 0
	v_pk_add_f32 v[4:5], v[4:5], 1.0 op_sel_hi:[1,0]
	v_rcp_f32_e32 v7, v6
	s_nop 0
	v_mul_f32_e32 v0, v0, v7
	v_cvt_pk_bf16_f32 v0, v0, v1
	v_rcp_f32_e32 v1, v5
	s_nop 0
	v_mul_f32_e32 v1, v3, v1
	s_add_u32 s6, s11, s1
	v_rcp_f32_e32 v3, v4
	s_nop 0
	v_mul_f32_e32 v2, v2, v3
	v_cvt_pk_bf16_f32 v1, v2, v1
	ds_write_b64 v56, v[0:1] offset:25440
	s_addc_u32 s7, s12, 0
	v_or_b32_e32 v0, v48, v78
	v_mad_u64_u32 v[36:37], s[0:1], v0, s0, v[64:65]
	v_lshl_add_u64 v[38:39], s[6:7], 0, v[64:65]
	v_lshlrev_b32_e32 v64, 9, v78
	v_lshl_add_u64 v[40:41], v[38:39], 0, v[64:65]
	s_waitcnt lgkmcnt(0)
	s_barrier
	global_load_dwordx4 v[0:3], v[40:41], off
	v_or_b32_e32 v42, 0x2000, v64
	v_lshl_add_u64 v[4:5], v[38:39], 0, v[42:43]
	global_load_dwordx4 v[4:7], v[4:5], off
	ds_read_b128 v[8:11], v36
	ds_read_b128 v[12:15], v36 offset:64
	global_load_dwordx4 v[16:19], v[40:41], off offset:64
	v_or_b32_e32 v44, 0x4000, v64
	s_waitcnt vmcnt(2) lgkmcnt(1)
	v_mfma_f32_16x16x32_bf16 v[0:3], v[8:11], v[0:3], 0
	v_lshl_add_u64 v[20:21], v[38:39], 0, v[44:45]
	global_load_dwordx4 v[20:23], v[20:21], off
	v_or_b32_e32 v64, 0x6000, v64
	v_lshl_add_u64 v[32:33], v[38:39], 0, 64
	v_lshl_add_u64 v[24:25], v[38:39], 0, v[64:65]
	v_lshl_add_u64 v[28:29], v[32:33], 0, v[42:43]
	global_load_dwordx4 v[24:27], v[24:25], off
	s_waitcnt vmcnt(2) lgkmcnt(0)
	v_mfma_f32_16x16x32_bf16 v[0:3], v[12:15], v[16:19], v[0:3]
	global_load_dwordx4 v[28:31], v[28:29], off
	v_lshl_add_u64 v[16:17], v[32:33], 0, v[44:45]
	global_load_dwordx4 v[16:19], v[16:17], off
	v_mfma_f32_16x16x32_bf16 v[4:7], v[8:11], v[4:7], 0
	v_lshl_add_u64 v[32:33], v[32:33], 0, v[64:65]
	s_mov_b64 s[0:1], 0x80
	v_lshl_add_u64 v[46:47], v[38:39], 0, s[0:1]
	s_waitcnt vmcnt(3)
	v_mfma_f32_16x16x32_bf16 v[20:23], v[8:11], v[20:23], 0
	s_mov_b64 s[0:1], 0xc0
	s_add_u32 s6, s8, 0x1e454000
	s_addc_u32 s7, s9, 0
	s_waitcnt vmcnt(2)
	v_mfma_f32_16x16x32_bf16 v[8:11], v[8:11], v[24:27], 0
	s_add_u32 s8, s8, 0x1e4d4000
	s_addc_u32 s9, s9, 0
	s_waitcnt vmcnt(1)
	v_mfma_f32_16x16x32_bf16 v[4:7], v[12:15], v[28:31], v[4:7]
	global_load_dwordx4 v[24:27], v[32:33], off
	global_load_dwordx4 v[28:31], v[40:41], off offset:128
	s_waitcnt vmcnt(2)
	v_mfma_f32_16x16x32_bf16 v[16:19], v[12:15], v[16:19], v[20:23]
	s_nop 2
	v_lshl_add_u64 v[20:21], v[46:47], 0, v[42:43]
	global_load_dwordx4 v[20:23], v[20:21], off
	s_waitcnt vmcnt(2)
; DI bf16_t f2bf(float x) { return (bf16_t)(pk2(x, 0.f) & 0xffffu); }
; DI f32x4 mfma16(bf16x8 a, bf16x8 b, f32x4 c) { return __builtin_amdgcn_mfma_f32_16x16x32_bf16(a, b, c, 0, 0, 0); }
; DI void compress_item(const Params& p, int layer, int item, bf16_t* smem) {
;     ...
;   for (int ks = 0; ks < 8; ++ks) {
;     const bf16x8 a = *(const bf16x8*)(H + (wid * 16 + l15) * LDH + ks * 32 + quad * 8);
; #pragma unroll
;     for (int j = 0; j < 4; ++j) a2[j] = mfma16(a, *(const bf16x8*)(w2 + (size_t)(j * 16 + l15) * 256 + ks * 32 + quad * 8), a2[j]);
;   }
;   bf16_t* kc = (bf16_t*)(p.ws + O_KC); bf16_t* vct = (bf16_t*)(p.ws + O_VCT);
; #pragma unroll
;   for (int r = 0; r < 4; ++r) {
;     const int R = tm * 128 + wid * 16 + quad * 4 + r;
;     if (R < 4080) {
;       const int b = R / 510, rem = R - b * 510, n = rem >> 1, g = rem & 1;
; #pragma unroll
;       for (int j = 0; j < 4; ++j) {
;         const int d = j * 16 + l15; const bf16_t v = f2bf(a2[j][r]);
;         if (kv == 0) kc[((size_t)(b * 2 + g) * 256 + n) * 64 + d] = v; else vct[((size_t)(b * 2 + g) * 64 + d) * 256 + n] = v;
	v_mfma_f32_16x16x32_bf16 v[8:11], v[12:15], v[24:27], v[8:11]
	ds_read_b128 v[12:15], v36 offset:128
	ds_read_b128 v[24:27], v36 offset:192
	global_load_dwordx4 v[32:35], v[40:41], off offset:192
	s_waitcnt vmcnt(2) lgkmcnt(1)
	v_mfma_f32_16x16x32_bf16 v[0:3], v[12:15], v[28:31], v[0:3]
	v_lshl_add_u64 v[28:29], v[46:47], 0, v[44:45]
	global_load_dwordx4 v[28:31], v[28:29], off
	s_waitcnt vmcnt(2)
	v_mfma_f32_16x16x32_bf16 v[4:7], v[12:15], v[20:23], v[4:7]
	v_lshl_add_u64 v[20:21], v[46:47], 0, v[64:65]
	global_load_dwordx4 v[20:23], v[20:21], off
	v_lshl_add_u64 v[46:47], v[38:39], 0, s[0:1]
	s_waitcnt vmcnt(1)
	v_mfma_f32_16x16x32_bf16 v[16:19], v[12:15], v[28:31], v[16:19]
	v_lshl_add_u64 v[28:29], v[46:47], 0, v[42:43]
	global_load_dwordx4 v[28:31], v[28:29], off
	s_mov_b64 s[0:1], 0x100
	s_waitcnt vmcnt(1)
	v_mfma_f32_16x16x32_bf16 v[8:11], v[12:15], v[20:23], v[8:11]
	v_lshl_add_u64 v[12:13], v[46:47], 0, v[44:45]
	global_load_dwordx4 v[12:15], v[12:13], off
	v_lshl_add_u64 v[20:21], v[46:47], 0, v[64:65]
	global_load_dwordx4 v[20:23], v[20:21], off
	v_lshl_add_u64 v[46:47], v[38:39], 0, s[0:1]
	s_waitcnt vmcnt(1) lgkmcnt(0)
	v_mfma_f32_16x16x32_bf16 v[12:15], v[24:27], v[12:15], v[16:19]
	s_nop 2
	v_lshl_add_u64 v[16:17], v[46:47], 0, v[42:43]
	global_load_dwordx4 v[16:19], v[16:17], off
	s_mov_b64 s[0:1], 0x140
	v_mfma_f32_16x16x32_bf16 v[4:7], v[24:27], v[28:31], v[4:7]
	global_load_dwordx4 v[28:31], v[40:41], off offset:256
	v_mfma_f32_16x16x32_bf16 v[0:3], v[24:27], v[32:35], v[0:3]
	s_waitcnt vmcnt(2)
	v_mfma_f32_16x16x32_bf16 v[8:11], v[24:27], v[20:23], v[8:11]
	ds_read_b128 v[20:23], v36 offset:256
	ds_read_b128 v[24:27], v36 offset:320
	global_load_dwordx4 v[32:35], v[40:41], off offset:320
	s_waitcnt vmcnt(1) lgkmcnt(1)
	v_mfma_f32_16x16x32_bf16 v[0:3], v[20:23], v[28:31], v[0:3]
	v_lshl_add_u64 v[28:29], v[46:47], 0, v[44:45]
	global_load_dwordx4 v[28:31], v[28:29], off
	v_mfma_f32_16x16x32_bf16 v[4:7], v[20:23], v[16:19], v[4:7]
	v_lshl_add_u64 v[16:17], v[46:47], 0, v[64:65]
	global_load_dwordx4 v[16:19], v[16:17], off
	v_lshl_add_u64 v[46:47], v[38:39], 0, s[0:1]
	s_waitcnt vmcnt(0)
	v_mfma_f32_16x16x32_bf16 v[8:11], v[20:23], v[16:19], v[8:11]
	v_lshl_add_u64 v[16:17], v[46:47], 0, v[44:45]
	global_load_dwordx4 v[16:19], v[16:17], off
	s_mov_b64 s[0:1], 0x180
	v_mfma_f32_16x16x32_bf16 v[12:15], v[20:23], v[28:31], v[12:15]
	v_lshl_add_u64 v[28:29], v[46:47], 0, v[42:43]
	global_load_dwordx4 v[28:31], v[28:29], off
	v_lshl_add_u64 v[20:21], v[46:47], 0, v[64:65]
	global_load_dwordx4 v[20:23], v[20:21], off
	s_waitcnt vmcnt(2) lgkmcnt(0)
	v_mfma_f32_16x16x32_bf16 v[12:15], v[24:27], v[16:19], v[12:15]
	global_load_dwordx4 v[16:19], v[40:41], off offset:384
	v_lshl_add_u64 v[46:47], v[38:39], 0, s[0:1]
	s_mov_b64 s[0:1], 0x1c0
	s_waitcnt vmcnt(2)
	v_mfma_f32_16x16x32_bf16 v[4:7], v[24:27], v[28:31], v[4:7]
	ds_read_b128 v[28:31], v36 offset:384
	v_mfma_f32_16x16x32_bf16 v[0:3], v[24:27], v[32:35], v[0:3]
	global_load_dwordx4 v[32:35], v[40:41], off offset:448
	s_waitcnt vmcnt(2)
	v_mfma_f32_16x16x32_bf16 v[8:11], v[24:27], v[20:23], v[8:11]
	ds_read_b128 v[24:27], v36 offset:448
	v_lshl_add_u64 v[20:21], v[46:47], 0, v[42:43]
	global_load_dwordx4 v[20:23], v[20:21], off
	s_waitcnt vmcnt(2) lgkmcnt(1)
	v_mfma_f32_16x16x32_bf16 v[0:3], v[28:31], v[16:19], v[0:3]
	v_lshl_add_u64 v[16:17], v[46:47], 0, v[44:45]
	global_load_dwordx4 v[16:19], v[16:17], off
	v_lshl_add_u64 v[40:41], v[38:39], 0, s[0:1]
	s_waitcnt vmcnt(0)
	v_mfma_f32_16x16x32_bf16 v[16:19], v[28:31], v[16:19], v[12:15]
	s_nop 2
	v_lshl_add_u64 v[12:13], v[40:41], 0, v[42:43]
	global_load_dwordx4 v[36:39], v[12:13], off
	s_movk_i32 s0, 0xff0
	v_mfma_f32_16x16x32_bf16 v[4:7], v[28:31], v[20:23], v[4:7]
	v_lshl_add_u64 v[20:21], v[46:47], 0, v[64:65]
	global_load_dwordx4 v[20:23], v[20:21], off
	s_waitcnt vmcnt(0)
	v_mfma_f32_16x16x32_bf16 v[28:31], v[28:31], v[20:23], v[8:11]
	v_lshlrev_b32_e32 v22, 8, v78
	s_waitcnt lgkmcnt(0)
	v_mfma_f32_16x16x32_bf16 v[12:15], v[24:27], v[32:35], v[0:3]
	s_nop 2
	v_lshl_add_u64 v[0:1], v[40:41], 0, v[44:45]
	v_mfma_f32_16x16x32_bf16 v[8:11], v[24:27], v[36:39], v[4:7]
	global_load_dwordx4 v[0:3], v[0:1], off
	s_nop 1
	v_lshl_add_u64 v[4:5], v[40:41], 0, v[64:65]
	global_load_dwordx4 v[32:35], v[4:5], off
	s_waitcnt vmcnt(1)
	v_mfma_f32_16x16x32_bf16 v[4:7], v[24:27], v[0:3], v[16:19]
	s_nop 2
	v_add_u32_e32 v16, s10, v48
	v_lshl_or_b32 v23, v79, 2, v16
	v_cmp_gt_i32_e32 vcc, s0, v23
	s_waitcnt vmcnt(0)
	v_mfma_f32_16x16x32_bf16 v[0:3], v[24:27], v[32:35], v[28:31]
	s_and_saveexec_b64 s[0:1], vcc
	s_cbranch_execz .LBB0_412
	s_mov_b32 s10, 0x80808081
	v_mul_hi_i32 v16, v23, s10
	v_add_u32_e32 v16, v16, v23
	v_lshrrev_b32_e32 v17, 31, v16
	v_ashrrev_i32_e32 v16, 8, v16
	v_add_u32_e32 v16, v16, v17
	s_movk_i32 s10, 0xfe02
	v_mad_i32_i24 v17, v16, s10, v23
	v_lshlrev_b32_e32 v16, 1, v16
	v_ashrrev_i32_e32 v18, 1, v17
	v_ashrrev_i32_e32 v17, 31, v16
	v_ashrrev_i32_e32 v19, 31, v18
	v_lshlrev_b64 v[20:21], 15, v[16:17]
	v_cvt_pk_bf16_f32 v12, v12, s0
	s_and_b64 vcc, exec, s[4:5]
	s_cbranch_vccz .LBB0_409
	v_lshl_add_u64 v[16:17], s[8:9], 0, v[20:21]
	v_lshl_add_u64 v[16:17], v[18:19], 1, v[16:17]
	v_lshlrev_b32_e32 v24, 1, v22
	v_mov_b32_e32 v25, 0
	v_lshl_add_u64 v[24:25], v[16:17], 0, v[24:25]
	global_store_short v[24:25], v12, off
	s_cbranch_execz .LBB0_410
	s_branch .LBB0_411

; DI unsigned pk2(float lo, float hi) { f32x2 v = {lo, hi}; return __builtin_bit_cast(unsigned, __builtin_convertvector(v, bfx2)); }
; DI float ex2(float x) { return __builtin_amdgcn_exp2f(x); }
; DI void cmp_item(const Params& p, int item, unsigned char* smem_) {
;     ...
;     for (int s = 0; s < nsub; ++s) { const f32x4 a = score(s); sum += (ex2(a[0] - mx) + ex2(a[1] - mx)) + (ex2(a[2] - mx) + ex2(a[3] - mx)); }
;     sum += __shfl_xor(sum, 16); sum += __shfl_xor(sum, 32);
;     const float inv = 1.f / fmaxf(sum, 1e-30f);
;     f32x4 oacc[4];
; #pragma unroll
;     for (int j = 0; j < 4; ++j) oacc[j] = (f32x4){0.f, 0.f, 0.f, 0.f};
; #pragma unroll
;     for (int c = 0; c < 8; ++c) {
;       asm volatile("" ::: "memory");
;       if (2 * c < nsub) {
;         f32x4 pa = score(2 * c), pb = {-INFINITY, -INFINITY, -INFINITY, -INFINITY};
;         if (2 * c + 1 < nsub) pb = score(2 * c + 1);
; #pragma unroll
;         for (int r = 0; r < 4; ++r) { pa[r] = ex2(pa[r] - mx) * inv; pb[r] = ex2(pb[r] - mx) * inv; }
;         impa[2 * c] += pa[0] + pa[1] + pa[2] + 0.5f * pa[3]; p3a[2 * c] += pa[3];
;         impa[2 * c + 1] += pb[0] + pb[1] + pb[2] + 0.5f * pb[3]; p3a[2 * c + 1] += pb[3];
;         const u32x4 pw = {pk2(pa[0], pa[1]), pk2(pa[2], pa[3]), pk2(pb[0], pb[1]), pk2(pb[2], pb[3])};
.LBB0_502:
	s_waitcnt lgkmcnt(0)
	v_add_f32_e32 v12, v12, v13
	v_max_f32_e32 v12, 0xda24260, v12
	v_cndmask_b32_e64 v8, v8, v84, s[2:3]
	v_sub_f32_e32 v8, v8, v28
	v_rcp_f32_e32 v82, v12
	v_cndmask_b32_e64 v9, v9, v84, s[4:5]
	v_exp_f32_e32 v12, v8
	v_sub_f32_e32 v8, v14, v28
	v_exp_f32_e32 v14, v8
	v_sub_f32_e32 v8, v9, v28
	v_cndmask_b32_e64 v10, v10, v84, s[6:7]
	v_exp_f32_e32 v13, v8
	v_sub_f32_e32 v8, v15, v28
	v_exp_f32_e32 v15, v8
	v_sub_f32_e32 v8, v10, v28
	v_exp_f32_e32 v18, v8
	v_sub_f32_e32 v8, v17, v28
	v_exp_f32_e32 v19, v8
	v_cndmask_b32_e64 v11, v11, v84, s[8:9]
	v_sub_f32_e32 v8, v11, v28
	v_mov_b32_e32 v83, v82
	v_exp_f32_e32 v110, v8
	v_sub_f32_e32 v8, v16, v28
	v_exp_f32_e32 v111, v8
	ds_read2_b64 v[8:11], v105 offset1:4
	v_pk_mul_f32 v[76:77], v[82:83], v[12:13] op_sel_hi:[0,1]
	v_pk_mul_f32 v[78:79], v[82:83], v[14:15] op_sel_hi:[0,1]
	v_pk_mul_f32 v[80:81], v[82:83], v[18:19] op_sel_hi:[0,1]
	ds_read2_b64 v[12:15], v106 offset1:4
	ds_read2_b64 v[16:19], v107 offset0:64 offset1:68
	ds_read2_b64 v[24:27], v108 offset0:96 offset1:100
	v_pk_mul_f32 v[74:75], v[82:83], v[110:111] op_sel_hi:[0,1]
	v_cvt_pk_bf16_f32 v20, v76, v77
	v_cvt_pk_bf16_f32 v21, v80, v74
	v_cvt_pk_bf16_f32 v22, v78, v79
	v_cvt_pk_bf16_f32 v23, v81, v75
	v_pk_fma_f32 v[38:39], v[82:83], v[110:111], v[38:39] op_sel_hi:[0,1,1]
	s_andn2_b64 vcc, exec, s[96:97]
	s_waitcnt lgkmcnt(3)
	v_mfma_f32_16x16x32_bf16 v[8:11], v[8:11], v[20:23], 0
	s_waitcnt lgkmcnt(2)
	v_mfma_f32_16x16x32_bf16 v[12:15], v[12:15], v[20:23], 0
	s_waitcnt lgkmcnt(1)
	v_mfma_f32_16x16x32_bf16 v[16:19], v[16:19], v[20:23], 0
	s_waitcnt lgkmcnt(0)
	v_mfma_f32_16x16x32_bf16 v[20:23], v[24:27], v[20:23], 0
	s_cbranch_vccnz .LBB0_506
	ds_read_b128 v[24:27], v102 offset:4608
	ds_read_b128 v[110:113], v102 offset:4672
	v_mov_b32_e32 v109, 0xff800000
	s_andn2_b64 vcc, exec, s[0:1]
	s_waitcnt lgkmcnt(1)
	v_mfma_f32_16x16x32_bf16 v[24:27], v[24:27], v[4:7], 0
	s_waitcnt lgkmcnt(0)
	v_mfma_f32_16x16x32_bf16 v[24:27], v[110:113], v[0:3], v[24:27]
	v_mov_b32_e32 v111, 0xff800000
	v_mov_b32_e32 v112, 0xff800000
	v_mov_b32_e32 v110, 0xff800000
	s_cbranch_vccnz .LBB0_505
	ds_read_b128 v[110:113], v102 offset:6912
	ds_read_b128 v[114:117], v102 offset:6976
	v_readlane_b32 vcc_lo, v241, 56
	v_readlane_b32 vcc_hi, v241, 57
	s_waitcnt lgkmcnt(1)
	v_mfma_f32_16x16x32_bf16 v[110:113], v[110:113], v[4:7], 0
	s_waitcnt lgkmcnt(0)
	v_mfma_f32_16x16x32_bf16 v[110:113], v[114:117], v[0:3], v[110:113]
	s_nop 7
	v_cndmask_b32_e32 v109, v110, v84, vcc
	v_readlane_b32 vcc_lo, v241, 44
	v_readlane_b32 vcc_hi, v241, 45
	s_nop 1
	v_cndmask_b32_e32 v111, v111, v84, vcc
	v_readlane_b32 vcc_lo, v241, 46
	v_readlane_b32 vcc_hi, v241, 47
	s_nop 1
	v_cndmask_b32_e32 v112, v112, v84, vcc
	v_readlane_b32 vcc_lo, v241, 48
	v_readlane_b32 vcc_hi, v241, 49
	s_nop 1
	v_cndmask_b32_e32 v110, v113, v84, vcc

; DI unsigned pk2(float lo, float hi) { f32x2 v = {lo, hi}; return __builtin_bit_cast(unsigned, __builtin_convertvector(v, bfx2)); }
; DI float bf2f(bf16_t h) { return __uint_as_float(((unsigned)h) << 16); }
; DI void nsa_attn_item(const Params& p, int b, int g, int qt, bf16_t* smem) {
;     ...
;     const float l = st.l + __shfl_xor(st.l, 32), sc = gts[2] / fmaxf(l, 1e-30f);
; #pragma unroll
;     for (int r = 0; r < 16; ++r) { res[0][r] = st.o[0][r] * sc; res[1][r] = st.o[1][r] * sc; }
;   }
;   {
;     AState st; astate_init(st);
;     const u64* selp = (const u64*)(p.ws + O_SEL) + (size_t)(b * 2 + g) * S_;
;     const u64 mysel = selp[tq];
;     const u64 m64 = selp[t0 + lane];
;     unsigned lo = (unsigned)m64, hi = (unsigned)(m64 >> 32);
; #pragma unroll
;     for (int o = 32; o >= 1; o >>= 1) { lo |= __shfl_xor(lo, o); hi |= __shfl_xor(hi, o); }
;     const u64 um = (((u64)(unsigned)__builtin_amdgcn_readfirstlane(hi) << 32) | (u64)(unsigned)__builtin_amdgcn_readfirstlane(lo)) & lowbits(cur + 1);
;     flash_pass<M_SLC>(st, qf, um, um, (const bf16_t*)(p.ws + O_KSLC) + (size_t)b * S_ * 128 + g * 64, 128, nullptr,
;                       (const bf16_t*)(p.ws + O_VSLCT) + (size_t)(b * 2 + g) * 64 * S_, nullptr, tq, mysel, smem);
;     const float l = st.l + __shfl_xor(st.l, 32), sc = gts[1] / fmaxf(l, 1e-30f);
; #pragma unroll
;     for (int r = 0; r < 16; ++r) { res[0][r] += st.o[0][r] * sc; res[1][r] += st.o[1][r] * sc; }
;   }
;   bf16_t* op = (bf16_t*)(p.ws + O_ONSA) + trow * 512 + head * 64;
; #pragma unroll
;   for (int dt = 0; dt < 2; ++dt)
; #pragma unroll
;     for (int g4 = 0; g4 < 4; ++g4) {
;       const int d = dt * 32 + g4 * 8 + half * 4;
;       const u32x2 oc = *(const u32x2*)(op + d);
;       const float c0 = bf2f((bf16_t)(oc[0] & 0xffffu)), c1 = bf2f((bf16_t)(oc[0] >> 16)), c2 = bf2f((bf16_t)(oc[1] & 0xffffu)), c3 = bf2f((bf16_t)(oc[1] >> 16));
;       *(u32x2*)(op + d) = (u32x2){pk2(res[dt][4 * g4] + c0, res[dt][4 * g4 + 1] + c1), pk2(res[dt][4 * g4 + 2] + c2, res[dt][4 * g4 + 3] + c3)};
;     }
.LBB0_663:
	global_load_dword v94, v[164:165], off offset:4
	v_readlane_b32 s0, v240, 23
	v_readlane_b32 s1, v240, 24
	v_lshlrev_b32_e32 v0, 1, v180
	ds_bpermute_b32 v84, v176, v169
	v_lshl_add_u64 v[2:3], v[162:163], 1, s[0:1]
	v_lshl_add_u64 v[2:3], v[2:3], 0, v[0:1]
	v_lshlrev_b32_e32 v0, 3, v177
	v_lshl_add_u64 v[2:3], v[2:3], 0, v[0:1]
	global_load_dwordx2 v[4:5], v[2:3], off
	global_load_dwordx2 v[6:7], v[2:3], off offset:16
	global_load_dwordx2 v[8:9], v[2:3], off offset:32
	global_load_dwordx2 v[10:11], v[2:3], off offset:48
	global_load_dwordx2 v[12:13], v[2:3], off offset:64
	global_load_dwordx2 v[14:15], v[2:3], off offset:80
	global_load_dwordx2 v[80:81], v[2:3], off offset:96
	global_load_dwordx2 v[82:83], v[2:3], off offset:112
	v_add_f32_e32 v0, v178, v179
	v_max_f32_e32 v0, 0xda24260, v0
	s_waitcnt vmcnt(10)
	s_waitcnt lgkmcnt(0)
	v_add_f32_e32 v84, v169, v84
	v_max_f32_e32 v95, 0xda24260, v84
	v_rcp_f32_e32 v84, v0
	s_nop 0
	v_mul_f32_e32 v0, v161, v84
	s_waitcnt vmcnt(8)
	v_div_scale_f32 v96, s[0:1], v95, v95, v94
	v_rcp_f32_e32 v98, v96
	v_div_scale_f32 v97, vcc, v94, v95, v94
	s_mov_b64 s[0:1], 0
	s_waitcnt vmcnt(7)
	v_and_b32_e32 v85, 0xffff0000, v4
	v_lshlrev_b32_e32 v84, 16, v4
	v_and_b32_e32 v87, 0xffff0000, v5
	v_lshlrev_b32_e32 v86, 16, v5
	s_waitcnt vmcnt(6)
	v_and_b32_e32 v5, 0xffff0000, v6
	v_lshlrev_b32_e32 v4, 16, v6
	v_and_b32_e32 v89, 0xffff0000, v7
	v_lshlrev_b32_e32 v88, 16, v7
	s_waitcnt vmcnt(5)
	v_and_b32_e32 v7, 0xffff0000, v8
	v_lshlrev_b32_e32 v6, 16, v8
	v_and_b32_e32 v91, 0xffff0000, v9
	v_lshlrev_b32_e32 v90, 16, v9
	s_waitcnt vmcnt(4)
	v_and_b32_e32 v9, 0xffff0000, v10
	v_lshlrev_b32_e32 v8, 16, v10
	v_fma_f32 v10, -v96, v98, 1.0
	v_fmac_f32_e32 v98, v10, v98
	v_mul_f32_e32 v10, v97, v98
	v_and_b32_e32 v93, 0xffff0000, v11
	v_lshlrev_b32_e32 v92, 16, v11
	v_fma_f32 v11, -v96, v10, v97
	v_fmac_f32_e32 v10, v11, v98
	v_fma_f32 v11, -v96, v10, v97
	v_div_fmas_f32 v10, v11, v98, v10
	v_div_fixup_f32 v10, v10, v95, v94
	v_pk_mul_f32 v[64:65], v[64:65], v[10:11] op_sel_hi:[1,0]
	v_pk_mul_f32 v[66:67], v[66:67], v[10:11] op_sel_hi:[1,0]
	v_pk_mul_f32 v[68:69], v[68:69], v[10:11] op_sel_hi:[1,0]
	v_pk_mul_f32 v[70:71], v[70:71], v[10:11] op_sel_hi:[1,0]
	v_pk_mul_f32 v[72:73], v[72:73], v[10:11] op_sel_hi:[1,0]
	v_pk_mul_f32 v[74:75], v[74:75], v[10:11] op_sel_hi:[1,0]
	v_pk_mul_f32 v[76:77], v[76:77], v[10:11] op_sel_hi:[1,0]
	v_pk_mul_f32 v[78:79], v[78:79], v[10:11] op_sel_hi:[1,0]
	v_pk_fma_f32 v[32:33], v[32:33], v[0:1], v[64:65] op_sel_hi:[1,0,1]
	v_pk_fma_f32 v[34:35], v[34:35], v[0:1], v[66:67] op_sel_hi:[1,0,1]
	v_pk_fma_f32 v[36:37], v[36:37], v[0:1], v[68:69] op_sel_hi:[1,0,1]
	v_pk_fma_f32 v[38:39], v[38:39], v[0:1], v[70:71] op_sel_hi:[1,0,1]
	v_pk_fma_f32 v[40:41], v[40:41], v[0:1], v[72:73] op_sel_hi:[1,0,1]
	v_pk_fma_f32 v[42:43], v[42:43], v[0:1], v[74:75] op_sel_hi:[1,0,1]
	v_pk_fma_f32 v[44:45], v[44:45], v[0:1], v[76:77] op_sel_hi:[1,0,1]
	v_pk_fma_f32 v[46:47], v[46:47], v[0:1], v[78:79] op_sel_hi:[1,0,1]
	v_pk_add_f32 v[32:33], v[32:33], v[84:85]
	v_pk_add_f32 v[34:35], v[34:35], v[86:87]
	v_pk_add_f32 v[4:5], v[36:37], v[4:5]
	v_pk_add_f32 v[36:37], v[38:39], v[88:89]
	v_pk_add_f32 v[6:7], v[40:41], v[6:7]
	v_pk_add_f32 v[38:39], v[42:43], v[90:91]
	v_pk_add_f32 v[8:9], v[44:45], v[8:9]
	v_pk_add_f32 v[40:41], v[46:47], v[92:93]
	v_cvt_pk_bf16_f32 v32, v32, v33
	v_cvt_pk_bf16_f32 v33, v34, v35
	v_cvt_pk_bf16_f32 v4, v4, v5
	v_cvt_pk_bf16_f32 v5, v36, v37
	v_cvt_pk_bf16_f32 v6, v6, v7
	v_cvt_pk_bf16_f32 v7, v38, v39
	v_cvt_pk_bf16_f32 v8, v8, v9
	v_cvt_pk_bf16_f32 v9, v40, v41
	global_store_dwordx2 v[2:3], v[32:33], off
	global_store_dwordx2 v[2:3], v[4:5], off offset:16
	global_store_dwordx2 v[2:3], v[6:7], off offset:32
	global_store_dwordx2 v[2:3], v[8:9], off offset:48
	v_pk_mul_f32 v[4:5], v[48:49], v[10:11] op_sel_hi:[1,0]
	s_waitcnt vmcnt(7)
	v_and_b32_e32 v7, 0xffff0000, v12
	v_pk_fma_f32 v[4:5], v[16:17], v[0:1], v[4:5] op_sel_hi:[1,0,1]
	v_lshlrev_b32_e32 v6, 16, v12
	v_pk_add_f32 v[4:5], v[4:5], v[6:7]
	v_pk_mul_f32 v[6:7], v[50:51], v[10:11] op_sel_hi:[1,0]
	v_and_b32_e32 v9, 0xffff0000, v13
	v_pk_fma_f32 v[6:7], v[18:19], v[0:1], v[6:7] op_sel_hi:[1,0,1]
	v_lshlrev_b32_e32 v8, 16, v13
	v_pk_add_f32 v[6:7], v[6:7], v[8:9]
	v_cvt_pk_bf16_f32 v4, v4, v5
	v_cvt_pk_bf16_f32 v5, v6, v7
	global_store_dwordx2 v[2:3], v[4:5], off offset:64
	v_pk_mul_f32 v[4:5], v[52:53], v[10:11] op_sel_hi:[1,0]
	s_waitcnt vmcnt(7)
	v_and_b32_e32 v7, 0xffff0000, v14
	v_pk_fma_f32 v[4:5], v[20:21], v[0:1], v[4:5] op_sel_hi:[1,0,1]
	v_lshlrev_b32_e32 v6, 16, v14
	v_pk_add_f32 v[4:5], v[4:5], v[6:7]
	v_pk_mul_f32 v[6:7], v[54:55], v[10:11] op_sel_hi:[1,0]
	v_and_b32_e32 v9, 0xffff0000, v15
	v_pk_fma_f32 v[6:7], v[22:23], v[0:1], v[6:7] op_sel_hi:[1,0,1]
	v_lshlrev_b32_e32 v8, 16, v15
	v_pk_add_f32 v[6:7], v[6:7], v[8:9]
	v_cvt_pk_bf16_f32 v4, v4, v5
	v_cvt_pk_bf16_f32 v5, v6, v7
	global_store_dwordx2 v[2:3], v[4:5], off offset:80
	v_pk_mul_f32 v[4:5], v[56:57], v[10:11] op_sel_hi:[1,0]
	s_waitcnt vmcnt(7)
	v_and_b32_e32 v7, 0xffff0000, v80
	v_pk_fma_f32 v[4:5], v[24:25], v[0:1], v[4:5] op_sel_hi:[1,0,1]
	v_lshlrev_b32_e32 v6, 16, v80
	v_pk_add_f32 v[4:5], v[4:5], v[6:7]
	v_pk_mul_f32 v[6:7], v[58:59], v[10:11] op_sel_hi:[1,0]
	v_and_b32_e32 v9, 0xffff0000, v81
	v_pk_fma_f32 v[6:7], v[26:27], v[0:1], v[6:7] op_sel_hi:[1,0,1]
	v_lshlrev_b32_e32 v8, 16, v81
	v_pk_add_f32 v[6:7], v[6:7], v[8:9]
	v_cvt_pk_bf16_f32 v4, v4, v5
	v_cvt_pk_bf16_f32 v5, v6, v7
	global_store_dwordx2 v[2:3], v[4:5], off offset:96
	v_pk_mul_f32 v[4:5], v[60:61], v[10:11] op_sel_hi:[1,0]
	s_waitcnt vmcnt(7)
	v_and_b32_e32 v7, 0xffff0000, v82
	v_pk_fma_f32 v[4:5], v[28:29], v[0:1], v[4:5] op_sel_hi:[1,0,1]
	v_lshlrev_b32_e32 v6, 16, v82
	v_pk_add_f32 v[4:5], v[4:5], v[6:7]
	v_pk_mul_f32 v[6:7], v[62:63], v[10:11] op_sel_hi:[1,0]
	v_and_b32_e32 v9, 0xffff0000, v83
	v_pk_fma_f32 v[6:7], v[30:31], v[0:1], v[6:7] op_sel_hi:[1,0,1]
	v_lshlrev_b32_e32 v8, 16, v83
	v_pk_add_f32 v[6:7], v[6:7], v[8:9]
	v_cvt_pk_bf16_f32 v4, v4, v5
	v_cvt_pk_bf16_f32 v5, v6, v7
	global_store_dwordx2 v[2:3], v[4:5], off offset:112

; DI int TIDX() { int t = (int)threadIdx.x; asm volatile("" : "+v"(t)); return t; }
; DI float sigmoidf_(float x) { return 1.f / (1.f + __expf(-x)); }
; DI void merge_tile(const Params& p, int layer, int tm, int tn, bf16_t* smem) {
;     ...
;     if ((sg & 1) == 0) {
;       const int t2 = TIDX(), row0 = tm * 256 + ((t2 >> 8) & 1) * 128 + (t2 & 15);
; #pragma unroll
;       for (int i = 0; i < 8; ++i) {
;         asm volatile("" ::: "memory");
;         const float rs = rstd_from16((const float*)(p.ws + O_SSQ) + (size_t)(row0 + i * 16) * 16, 1.f / 1024.f);
; #pragma unroll
;         for (int j = 0; j < 2; ++j) {
;           unsigned w = 0;
; #pragma unroll
;           for (int r = 0; r < 4; ++r) w |= (unsigned)__float2int_rn(sigmoidf_(acc[i][j][r] * rs) * 255.f) << (8 * r);
;           gsp[(i * 2 + j) * NTHR] = w;
.LrcE0_0:
	s_or_b64 exec, exec, s[98:99]
	s_waitcnt vmcnt(0)
	v_cndmask_b32_e64 v153, v249, v153, s[100:101]
	v_mov_b64_e32 v[210:211], v[30:31]
	v_mov_b64_e32 v[206:207], v[34:35]
	v_mov_b64_e32 v[202:203], v[38:39]
	v_mov_b64_e32 v[198:199], v[42:43]
	v_mov_b64_e32 v[194:195], v[46:47]
	v_mov_b64_e32 v[190:191], v[50:51]
	v_mov_b64_e32 v[186:187], v[54:55]
	v_mov_b64_e32 v[182:183], v[58:59]
	v_mov_b64_e32 v[178:179], v[62:63]
	v_mov_b64_e32 v[174:175], v[66:67]
	v_mov_b64_e32 v[212:213], v[24:25]
	v_mov_b64_e32 v[208:209], v[28:29]
	v_mov_b64_e32 v[204:205], v[32:33]
	v_mov_b64_e32 v[200:201], v[36:37]
	v_mov_b64_e32 v[196:197], v[40:41]
	v_mov_b64_e32 v[192:193], v[44:45]
	v_mov_b64_e32 v[188:189], v[48:49]
	v_mov_b64_e32 v[184:185], v[52:53]
	v_mov_b64_e32 v[180:181], v[56:57]
	v_mov_b64_e32 v[176:177], v[60:61]
	v_mov_b64_e32 v[172:173], v[64:65]
	v_mov_b64_e32 v[170:171], v[70:71]
	v_mov_b64_e32 v[166:167], v[74:75]
	v_mov_b64_e32 v[168:169], v[68:69]
	v_mov_b64_e32 v[164:165], v[72:73]
	v_mul_f32_e32 v148, v148, v153
	v_mul_f32_e32 v148, 0xbfb8aa3b, v148
	v_exp_f32_e32 v148, v148
	v_mul_f32_e32 v149, v149, v153
	v_mul_f32_e32 v149, 0xbfb8aa3b, v149
	v_exp_f32_e32 v149, v149
	v_add_f32_e32 v148, 1.0, v148
	v_add_f32_e32 v149, 1.0, v149
	v_mul_f32_e32 v144, v144, v153
	v_mul_f32_e32 v144, 0xbfb8aa3b, v144
	v_rcp_f32_e32 v148, v148
	s_nop 0
	v_mul_f32_e32 v148, 0x437f0000, v148
	v_rndne_f32_e32 v148, v148
	v_cvt_i32_f32_e32 v148, v148
	v_rcp_f32_e32 v149, v149
	s_nop 0
	v_mul_f32_e32 v149, 0x437f0000, v149
	v_rndne_f32_e32 v149, v149
	v_cvt_i32_f32_e32 v149, v149
	v_exp_f32_e32 v144, v144
	v_mul_f32_e32 v145, v145, v153
	v_mul_f32_e32 v145, 0xbfb8aa3b, v145
	v_lshl_or_b32 v148, v149, 8, v148
	v_mul_f32_e32 v149, v150, v153
	v_mul_f32_e32 v149, 0xbfb8aa3b, v149
	v_exp_f32_e32 v149, v149
	v_add_f32_e32 v144, 1.0, v144
	v_exp_f32_e32 v145, v145
	v_add_f32_e32 v149, 1.0, v149
	v_add_f32_e32 v145, 1.0, v145
	v_rcp_f32_e32 v149, v149
	v_mul_f32_e32 v150, v151, v153
	v_mul_f32_e32 v150, 0xbfb8aa3b, v150
	v_exp_f32_e32 v150, v150
	v_mul_f32_e32 v149, 0x437f0000, v149
	v_rndne_f32_e32 v149, v149
	v_cvt_i32_f32_sdwa v149, v149 dst_sel:WORD_1 dst_unused:UNUSED_PAD src0_sel:DWORD
	v_add_f32_e32 v150, 1.0, v150
	s_nop 0
	v_rcp_f32_e32 v150, v150
	s_nop 0
	v_mul_f32_e32 v150, 0x437f0000, v150
	v_rndne_f32_e32 v150, v150
	v_cvt_i32_f32_sdwa v150, v150 dst_sel:BYTE_3 dst_unused:UNUSED_PAD src0_sel:DWORD
	s_nop 0
	v_or3_b32 v148, v148, v149, v150
	s_nop 0
	v_rcp_f32_e32 v144, v144
	s_nop 0
	v_mul_f32_e32 v144, 0x437f0000, v144
	v_rndne_f32_e32 v144, v144
	v_cvt_i32_f32_e32 v144, v144
	v_rcp_f32_e32 v145, v145
	s_nop 0
	v_mul_f32_e32 v145, 0x437f0000, v145
	v_rndne_f32_e32 v145, v145
	v_cvt_i32_f32_e32 v145, v145
	v_lshl_or_b32 v144, v145, 8, v144
	v_mul_f32_e32 v145, v146, v153
	v_mul_f32_e32 v145, 0xbfb8aa3b, v145
	v_exp_f32_e32 v145, v145
	s_nop 0
	v_add_f32_e32 v145, 1.0, v145
	s_nop 0
	v_rcp_f32_e32 v145, v145
	v_mul_f32_e32 v146, v147, v153
	v_mul_f32_e32 v146, 0xbfb8aa3b, v146
	v_exp_f32_e32 v146, v146
	v_mul_f32_e32 v145, 0x437f0000, v145
	v_rndne_f32_e32 v145, v145
	v_cvt_i32_f32_sdwa v145, v145 dst_sel:WORD_1 dst_unused:UNUSED_PAD src0_sel:DWORD
	v_add_f32_e32 v146, 1.0, v146
	s_nop 0
	v_rcp_f32_e32 v146, v146
	s_nop 0
	v_mul_f32_e32 v146, 0x437f0000, v146
	v_rndne_f32_e32 v146, v146
	v_cvt_i32_f32_sdwa v146, v146 dst_sel:BYTE_3 dst_unused:UNUSED_PAD src0_sel:DWORD
	s_nop 0
	v_or3_b32 v144, v144, v145, v146
	ds_write2st64_b32 v228, v148, v144 offset1:8
	v_or_b32_e32 v144, 16, v152
	v_ashrrev_i32_e32 v145, 31, v144
	v_lshlrev_b64 v[144:145], 6, v[144:145]
	v_lshl_add_u64 v[158:159], s[0:1], 0, v[144:145]
	v_bfe_u32 v244, v158, 6, 8
	v_lshlrev_b32_e32 v244, 3, v244
	v_add_u32_e32 v244, 0x24010, v244
	v_or_b32_e32 v246, 1, v158
	ds_read_b64 v[248:249], v244
	s_waitcnt lgkmcnt(0)
	v_cmp_ne_u32_e64 s[100:101], v248, v246
	s_nop 1
	s_and_saveexec_b64 s[98:99], s[100:101]
	s_cbranch_execz .LrcE0_1
	global_load_dwordx4 v[144:147], v[158:159], off offset:48
	global_load_dwordx4 v[148:151], v[158:159], off offset:32
	global_load_dwordx4 v[154:157], v[158:159], off offset:16
	s_nop 0
	global_load_dwordx4 v[158:161], v[158:159], off
	s_waitcnt vmcnt(2)
	v_add_f32_e32 v148, v148, v149
	v_add_f32_e32 v150, v150, v151
	s_waitcnt vmcnt(0)
	v_mov_b32_e32 v162, v159
	v_mov_b32_e32 v163, v160
	v_mov_b32_e32 v159, v161
	v_mov_b32_e32 v160, v155
	v_mov_b32_e32 v161, v156
	v_mov_b32_e32 v155, v157
	v_pk_add_f32 v[158:159], v[162:163], v[158:159]
	v_pk_add_f32 v[154:155], v[160:161], v[154:155]
	v_pk_add_f32 v[158:159], v[158:159], v[158:159] op_sel:[0,1] op_sel_hi:[1,0]
	v_pk_add_f32 v[154:155], v[154:155], v[154:155] op_sel:[0,1] op_sel_hi:[1,0]
	v_mov_b32_e32 v159, v144
	v_mov_b32_e32 v155, v145
	v_mov_b32_e32 v149, v146
	v_mov_b32_e32 v151, v147
	v_pk_add_f32 v[144:145], v[158:159], v[154:155]
	v_pk_add_f32 v[146:147], v[148:149], v[150:151]
	v_pk_add_f32 v[144:145], v[144:145], v[146:147]
	v_add_f32_e32 v144, v144, v145
	v_fmamk_f32 v144, v144, 0x3a800000, v225
	v_cmp_gt_f32_e32 vcc, s35, v144
	v_mul_f32_e32 v145, 0x4b800000, v144
	v_cndmask_b32_e32 v144, v144, v145, vcc
	v_rsq_f32_e32 v144, v144
	v_mul_f32_e32 v145, 0x45800000, v144
	v_cndmask_b32_e32 v144, v144, v145, vcc
	s_nop 0
	v_mov_b32_e32 v247, v144
	ds_write_b64 v244, v[246:247]
; DI int TIDX() { int t = (int)threadIdx.x; asm volatile("" : "+v"(t)); return t; }
; DI float sigmoidf_(float x) { return 1.f / (1.f + __expf(-x)); }
; DI void merge_tile(const Params& p, int layer, int tm, int tn, bf16_t* smem) {
;     ...
;     if ((sg & 1) == 0) {
;       const int t2 = TIDX(), row0 = tm * 256 + ((t2 >> 8) & 1) * 128 + (t2 & 15);
; #pragma unroll
;       for (int i = 0; i < 8; ++i) {
;         asm volatile("" ::: "memory");
;         const float rs = rstd_from16((const float*)(p.ws + O_SSQ) + (size_t)(row0 + i * 16) * 16, 1.f / 1024.f);
; #pragma unroll
;         for (int j = 0; j < 2; ++j) {
;           unsigned w = 0;
; #pragma unroll
;           for (int r = 0; r < 4; ++r) w |= (unsigned)__float2int_rn(sigmoidf_(acc[i][j][r] * rs) * 255.f) << (8 * r);
;           gsp[(i * 2 + j) * NTHR] = w;
;         }
;       }
.LrcE0_1:
	s_or_b64 exec, exec, s[98:99]
	s_waitcnt vmcnt(0)
	v_cndmask_b32_e64 v144, v249, v144, s[100:101]
	v_mov_b64_e32 v[162:163], v[78:79]
	v_mov_b64_e32 v[158:159], v[82:83]
	v_mov_b64_e32 v[160:161], v[76:77]
	v_mov_b64_e32 v[156:157], v[80:81]
	v_mul_f32_e32 v140, v140, v144
	v_mul_f32_e32 v140, 0xbfb8aa3b, v140
	v_exp_f32_e32 v140, v140
	v_mul_f32_e32 v141, v141, v144
	v_mul_f32_e32 v141, 0xbfb8aa3b, v141
	v_exp_f32_e32 v141, v141
	v_add_f32_e32 v140, 1.0, v140
	v_add_f32_e32 v141, 1.0, v141
	v_mul_f32_e32 v136, v136, v144
	v_mul_f32_e32 v136, 0xbfb8aa3b, v136
	v_rcp_f32_e32 v140, v140
	s_nop 0
	v_mul_f32_e32 v140, 0x437f0000, v140
	v_rndne_f32_e32 v140, v140
	v_cvt_i32_f32_e32 v140, v140
	v_rcp_f32_e32 v141, v141
	s_nop 0
	v_mul_f32_e32 v141, 0x437f0000, v141
	v_rndne_f32_e32 v141, v141
	v_cvt_i32_f32_e32 v141, v141
	v_exp_f32_e32 v136, v136
	v_mul_f32_e32 v137, v137, v144
	v_mul_f32_e32 v137, 0xbfb8aa3b, v137
	v_lshl_or_b32 v140, v141, 8, v140
	v_mul_f32_e32 v141, v142, v144
	v_mul_f32_e32 v141, 0xbfb8aa3b, v141
	v_exp_f32_e32 v141, v141
	v_add_f32_e32 v136, 1.0, v136
	v_exp_f32_e32 v137, v137
	v_add_f32_e32 v141, 1.0, v141
	v_add_f32_e32 v137, 1.0, v137
	v_rcp_f32_e32 v141, v141
	v_mul_f32_e32 v142, v143, v144
	v_mul_f32_e32 v142, 0xbfb8aa3b, v142
	v_exp_f32_e32 v142, v142
	v_mul_f32_e32 v141, 0x437f0000, v141
	v_rndne_f32_e32 v141, v141
	v_cvt_i32_f32_sdwa v141, v141 dst_sel:WORD_1 dst_unused:UNUSED_PAD src0_sel:DWORD
	v_add_f32_e32 v142, 1.0, v142
	s_nop 0
	v_rcp_f32_e32 v142, v142
	s_nop 0
	v_mul_f32_e32 v142, 0x437f0000, v142
	v_rndne_f32_e32 v142, v142
	v_cvt_i32_f32_sdwa v142, v142 dst_sel:BYTE_3 dst_unused:UNUSED_PAD src0_sel:DWORD
	s_nop 0
	v_or3_b32 v140, v140, v141, v142
	s_nop 0
	v_rcp_f32_e32 v136, v136
	s_nop 0
	v_mul_f32_e32 v136, 0x437f0000, v136
	v_rndne_f32_e32 v136, v136
	v_cvt_i32_f32_e32 v136, v136
	v_rcp_f32_e32 v137, v137
	s_nop 0
	v_mul_f32_e32 v137, 0x437f0000, v137
	v_rndne_f32_e32 v137, v137
	v_cvt_i32_f32_e32 v137, v137
	v_lshl_or_b32 v136, v137, 8, v136
	v_mul_f32_e32 v137, v138, v144
	v_mul_f32_e32 v137, 0xbfb8aa3b, v137
	v_exp_f32_e32 v137, v137
	s_nop 0
	v_add_f32_e32 v137, 1.0, v137
	s_nop 0
	v_rcp_f32_e32 v137, v137
	v_mul_f32_e32 v138, v139, v144
	v_mul_f32_e32 v138, 0xbfb8aa3b, v138
	v_exp_f32_e32 v138, v138
	v_mul_f32_e32 v137, 0x437f0000, v137
	v_rndne_f32_e32 v137, v137
	v_cvt_i32_f32_sdwa v137, v137 dst_sel:WORD_1 dst_unused:UNUSED_PAD src0_sel:DWORD
	v_add_f32_e32 v138, 1.0, v138
	s_nop 0
	v_rcp_f32_e32 v138, v138
	s_nop 0
	v_mul_f32_e32 v138, 0x437f0000, v138
	v_rndne_f32_e32 v138, v138
	v_cvt_i32_f32_sdwa v138, v138 dst_sel:BYTE_3 dst_unused:UNUSED_PAD src0_sel:DWORD
	s_nop 0
	v_or3_b32 v136, v136, v137, v138
	ds_write2st64_b32 v228, v140, v136 offset0:16 offset1:24
	v_or_b32_e32 v136, 32, v152
	v_ashrrev_i32_e32 v137, 31, v136
	v_lshlrev_b64 v[136:137], 6, v[136:137]
	v_lshl_add_u64 v[148:149], s[0:1], 0, v[136:137]
	v_bfe_u32 v244, v148, 6, 8
	v_lshlrev_b32_e32 v244, 3, v244
	v_add_u32_e32 v244, 0x24010, v244
	v_or_b32_e32 v246, 1, v148
	ds_read_b64 v[248:249], v244
	s_waitcnt lgkmcnt(0)
	v_cmp_ne_u32_e64 s[100:101], v248, v246
	s_nop 1
	s_and_saveexec_b64 s[98:99], s[100:101]
	s_cbranch_execz .LrcE0_2
	global_load_dwordx4 v[136:139], v[148:149], off offset:48
	global_load_dwordx4 v[140:143], v[148:149], off offset:32
	global_load_dwordx4 v[144:147], v[148:149], off offset:16
	s_nop 0
	global_load_dwordx4 v[148:151], v[148:149], off
	s_waitcnt vmcnt(2)
	v_add_f32_e32 v140, v140, v141
	v_add_f32_e32 v142, v142, v143
	s_waitcnt vmcnt(0)
	v_mov_b32_e32 v154, v149
	v_mov_b32_e32 v155, v150
	v_mov_b32_e32 v149, v151
	v_mov_b32_e32 v150, v145
	v_mov_b32_e32 v151, v146
	v_mov_b32_e32 v145, v147
	v_pk_add_f32 v[148:149], v[154:155], v[148:149]
	v_pk_add_f32 v[144:145], v[150:151], v[144:145]
	v_pk_add_f32 v[148:149], v[148:149], v[148:149] op_sel:[0,1] op_sel_hi:[1,0]
	v_pk_add_f32 v[144:145], v[144:145], v[144:145] op_sel:[0,1] op_sel_hi:[1,0]
	v_mov_b32_e32 v149, v136
	v_mov_b32_e32 v145, v137
	v_mov_b32_e32 v141, v138
	v_mov_b32_e32 v143, v139
	v_pk_add_f32 v[136:137], v[148:149], v[144:145]
	v_pk_add_f32 v[138:139], v[140:141], v[142:143]
	s_nop 0
	v_pk_add_f32 v[136:137], v[136:137], v[138:139]
	s_nop 0
	v_add_f32_e32 v136, v136, v137
	v_fmamk_f32 v136, v136, 0x3a800000, v225
	v_cmp_gt_f32_e32 vcc, s35, v136
	v_mul_f32_e32 v137, 0x4b800000, v136
	s_nop 0
	v_cndmask_b32_e32 v136, v136, v137, vcc
	v_rsq_f32_e32 v136, v136
	s_nop 0
	v_mul_f32_e32 v137, 0x45800000, v136
	v_cndmask_b32_e32 v136, v136, v137, vcc
	s_nop 0
	v_mov_b32_e32 v247, v136
	ds_write_b64 v244, v[246:247]
; DI int TIDX() { int t = (int)threadIdx.x; asm volatile("" : "+v"(t)); return t; }
; DI float sigmoidf_(float x) { return 1.f / (1.f + __expf(-x)); }
; DI void merge_tile(const Params& p, int layer, int tm, int tn, bf16_t* smem) {
;     ...
;     if ((sg & 1) == 0) {
;       const int t2 = TIDX(), row0 = tm * 256 + ((t2 >> 8) & 1) * 128 + (t2 & 15);
; #pragma unroll
;       for (int i = 0; i < 8; ++i) {
;         asm volatile("" ::: "memory");
;         const float rs = rstd_from16((const float*)(p.ws + O_SSQ) + (size_t)(row0 + i * 16) * 16, 1.f / 1024.f);
; #pragma unroll
;         for (int j = 0; j < 2; ++j) {
;           unsigned w = 0;
; #pragma unroll
;           for (int r = 0; r < 4; ++r) w |= (unsigned)__float2int_rn(sigmoidf_(acc[i][j][r] * rs) * 255.f) << (8 * r);
;           gsp[(i * 2 + j) * NTHR] = w;
;         }
;       }
.LrcE0_2:
	s_or_b64 exec, exec, s[98:99]
	s_waitcnt vmcnt(0)
	v_cndmask_b32_e64 v136, v249, v136, s[100:101]
	v_mul_f32_e32 v132, v132, v136
	v_mul_f32_e32 v132, 0xbfb8aa3b, v132
	v_exp_f32_e32 v132, v132
	v_mul_f32_e32 v133, v133, v136
	v_mul_f32_e32 v133, 0xbfb8aa3b, v133
	v_exp_f32_e32 v133, v133
	v_add_f32_e32 v132, 1.0, v132
	v_add_f32_e32 v133, 1.0, v133
	v_mul_f32_e32 v128, v128, v136
	v_mul_f32_e32 v128, 0xbfb8aa3b, v128
	v_rcp_f32_e32 v132, v132
	s_nop 0
	v_mul_f32_e32 v132, 0x437f0000, v132
	v_rndne_f32_e32 v132, v132
	v_cvt_i32_f32_e32 v132, v132
	v_rcp_f32_e32 v133, v133
	s_nop 0
	v_mul_f32_e32 v133, 0x437f0000, v133
	v_rndne_f32_e32 v133, v133
	v_cvt_i32_f32_e32 v133, v133
	v_exp_f32_e32 v128, v128
	v_mul_f32_e32 v129, v129, v136
	v_mul_f32_e32 v129, 0xbfb8aa3b, v129
	v_lshl_or_b32 v132, v133, 8, v132
	v_mul_f32_e32 v133, v134, v136
	v_mul_f32_e32 v133, 0xbfb8aa3b, v133
	v_exp_f32_e32 v133, v133
	v_add_f32_e32 v128, 1.0, v128
	v_exp_f32_e32 v129, v129
	v_add_f32_e32 v133, 1.0, v133
	v_add_f32_e32 v129, 1.0, v129
	v_rcp_f32_e32 v133, v133
	v_mul_f32_e32 v134, v135, v136
	v_mul_f32_e32 v134, 0xbfb8aa3b, v134
	v_exp_f32_e32 v134, v134
	v_mul_f32_e32 v133, 0x437f0000, v133
	v_rndne_f32_e32 v133, v133
	v_cvt_i32_f32_sdwa v133, v133 dst_sel:WORD_1 dst_unused:UNUSED_PAD src0_sel:DWORD
	v_add_f32_e32 v134, 1.0, v134
	s_nop 0
	v_rcp_f32_e32 v134, v134
	s_nop 0
	v_mul_f32_e32 v134, 0x437f0000, v134
	v_rndne_f32_e32 v134, v134
	v_cvt_i32_f32_sdwa v134, v134 dst_sel:BYTE_3 dst_unused:UNUSED_PAD src0_sel:DWORD
	s_nop 0
	v_or3_b32 v132, v132, v133, v134
	s_nop 0
	v_rcp_f32_e32 v128, v128
	s_nop 0
	v_mul_f32_e32 v128, 0x437f0000, v128
	v_rndne_f32_e32 v128, v128
	v_cvt_i32_f32_e32 v128, v128
	v_rcp_f32_e32 v129, v129
	s_nop 0
	v_mul_f32_e32 v129, 0x437f0000, v129
	v_rndne_f32_e32 v129, v129
	v_cvt_i32_f32_e32 v129, v129
	v_lshl_or_b32 v128, v129, 8, v128
	v_mul_f32_e32 v129, v130, v136
	v_mul_f32_e32 v129, 0xbfb8aa3b, v129
	v_exp_f32_e32 v129, v129
	s_nop 0
	v_add_f32_e32 v129, 1.0, v129
	s_nop 0
	v_rcp_f32_e32 v129, v129
	v_mul_f32_e32 v130, v131, v136
	v_mul_f32_e32 v130, 0xbfb8aa3b, v130
	v_exp_f32_e32 v130, v130
	v_mul_f32_e32 v129, 0x437f0000, v129
	v_rndne_f32_e32 v129, v129
	v_cvt_i32_f32_sdwa v129, v129 dst_sel:WORD_1 dst_unused:UNUSED_PAD src0_sel:DWORD
	v_add_f32_e32 v130, 1.0, v130
	s_nop 0
	v_rcp_f32_e32 v130, v130
	s_nop 0
	v_mul_f32_e32 v130, 0x437f0000, v130
	v_rndne_f32_e32 v130, v130
	v_cvt_i32_f32_sdwa v130, v130 dst_sel:BYTE_3 dst_unused:UNUSED_PAD src0_sel:DWORD
	s_nop 0
	v_or3_b32 v128, v128, v129, v130
	ds_write2st64_b32 v228, v132, v128 offset0:32 offset1:40
	v_or_b32_e32 v128, 48, v152
	v_ashrrev_i32_e32 v129, 31, v128
	v_lshlrev_b64 v[128:129], 6, v[128:129]
	v_lshl_add_u64 v[140:141], s[0:1], 0, v[128:129]
	v_bfe_u32 v244, v140, 6, 8
	v_lshlrev_b32_e32 v244, 3, v244
	v_add_u32_e32 v244, 0x24010, v244
	v_or_b32_e32 v246, 1, v140
	ds_read_b64 v[248:249], v244
	s_waitcnt lgkmcnt(0)
	v_cmp_ne_u32_e64 s[100:101], v248, v246
	s_nop 1
	s_and_saveexec_b64 s[98:99], s[100:101]
	s_cbranch_execz .LrcE0_3
	global_load_dwordx4 v[128:131], v[140:141], off offset:48
	global_load_dwordx4 v[132:135], v[140:141], off offset:32
	global_load_dwordx4 v[136:139], v[140:141], off offset:16
	s_nop 0
	global_load_dwordx4 v[140:143], v[140:141], off
	s_waitcnt vmcnt(2)
	v_add_f32_e32 v132, v132, v133
	v_add_f32_e32 v134, v134, v135
	s_waitcnt vmcnt(0)
	v_mov_b32_e32 v144, v141
	v_mov_b32_e32 v145, v142
	v_mov_b32_e32 v141, v143
	v_mov_b32_e32 v142, v137
	v_mov_b32_e32 v143, v138
	v_mov_b32_e32 v137, v139
	v_pk_add_f32 v[140:141], v[144:145], v[140:141]
	v_pk_add_f32 v[136:137], v[142:143], v[136:137]
	v_pk_add_f32 v[140:141], v[140:141], v[140:141] op_sel:[0,1] op_sel_hi:[1,0]
	v_pk_add_f32 v[136:137], v[136:137], v[136:137] op_sel:[0,1] op_sel_hi:[1,0]
	v_mov_b32_e32 v141, v128
	v_mov_b32_e32 v137, v129
	v_mov_b32_e32 v133, v130
	v_mov_b32_e32 v135, v131
	v_pk_add_f32 v[128:129], v[140:141], v[136:137]
	v_pk_add_f32 v[130:131], v[132:133], v[134:135]
	s_nop 0
	v_pk_add_f32 v[128:129], v[128:129], v[130:131]
	s_nop 0
	v_add_f32_e32 v128, v128, v129
	v_fmamk_f32 v128, v128, 0x3a800000, v225
	v_cmp_gt_f32_e32 vcc, s35, v128
	v_mul_f32_e32 v129, 0x4b800000, v128
	s_nop 0
	v_cndmask_b32_e32 v128, v128, v129, vcc
	v_rsq_f32_e32 v128, v128
	s_nop 0
	v_mul_f32_e32 v129, 0x45800000, v128
	v_cndmask_b32_e32 v128, v128, v129, vcc
	s_nop 0
	v_mov_b32_e32 v247, v128
	ds_write_b64 v244, v[246:247]
; DI int TIDX() { int t = (int)threadIdx.x; asm volatile("" : "+v"(t)); return t; }
; DI float sigmoidf_(float x) { return 1.f / (1.f + __expf(-x)); }
; DI void merge_tile(const Params& p, int layer, int tm, int tn, bf16_t* smem) {
;     ...
;     if ((sg & 1) == 0) {
;       const int t2 = TIDX(), row0 = tm * 256 + ((t2 >> 8) & 1) * 128 + (t2 & 15);
; #pragma unroll
;       for (int i = 0; i < 8; ++i) {
;         asm volatile("" ::: "memory");
;         const float rs = rstd_from16((const float*)(p.ws + O_SSQ) + (size_t)(row0 + i * 16) * 16, 1.f / 1024.f);
; #pragma unroll
;         for (int j = 0; j < 2; ++j) {
;           unsigned w = 0;
; #pragma unroll
;           for (int r = 0; r < 4; ++r) w |= (unsigned)__float2int_rn(sigmoidf_(acc[i][j][r] * rs) * 255.f) << (8 * r);
;           gsp[(i * 2 + j) * NTHR] = w;
;         }
;       }
.LrcE0_3:
	s_or_b64 exec, exec, s[98:99]
	s_waitcnt vmcnt(0)
	v_cndmask_b32_e64 v128, v249, v128, s[100:101]
	v_mul_f32_e32 v124, v124, v128
	v_mul_f32_e32 v124, 0xbfb8aa3b, v124
	v_exp_f32_e32 v124, v124
	v_mul_f32_e32 v125, v125, v128
	v_mul_f32_e32 v125, 0xbfb8aa3b, v125
	v_exp_f32_e32 v125, v125
	v_add_f32_e32 v124, 1.0, v124
	v_add_f32_e32 v125, 1.0, v125
	v_mul_f32_e32 v120, v120, v128
	v_mul_f32_e32 v120, 0xbfb8aa3b, v120
	v_rcp_f32_e32 v124, v124
	s_nop 0
	v_mul_f32_e32 v124, 0x437f0000, v124
	v_rndne_f32_e32 v124, v124
	v_cvt_i32_f32_e32 v124, v124
	v_rcp_f32_e32 v125, v125
	s_nop 0
	v_mul_f32_e32 v125, 0x437f0000, v125
	v_rndne_f32_e32 v125, v125
	v_cvt_i32_f32_e32 v125, v125
	v_exp_f32_e32 v120, v120
	v_mul_f32_e32 v121, v121, v128
	v_mul_f32_e32 v121, 0xbfb8aa3b, v121
	v_lshl_or_b32 v124, v125, 8, v124
	v_mul_f32_e32 v125, v126, v128
	v_mul_f32_e32 v125, 0xbfb8aa3b, v125
	v_exp_f32_e32 v125, v125
	v_add_f32_e32 v120, 1.0, v120
	v_exp_f32_e32 v121, v121
	v_add_f32_e32 v125, 1.0, v125
	v_add_f32_e32 v121, 1.0, v121
	v_rcp_f32_e32 v125, v125
	v_mul_f32_e32 v126, v127, v128
	v_mul_f32_e32 v126, 0xbfb8aa3b, v126
	v_exp_f32_e32 v126, v126
	v_mul_f32_e32 v125, 0x437f0000, v125
	v_rndne_f32_e32 v125, v125
	v_cvt_i32_f32_sdwa v125, v125 dst_sel:WORD_1 dst_unused:UNUSED_PAD src0_sel:DWORD
	v_add_f32_e32 v126, 1.0, v126
	s_nop 0
	v_rcp_f32_e32 v126, v126
	s_nop 0
	v_mul_f32_e32 v126, 0x437f0000, v126
	v_rndne_f32_e32 v126, v126
	v_cvt_i32_f32_sdwa v126, v126 dst_sel:BYTE_3 dst_unused:UNUSED_PAD src0_sel:DWORD
	s_nop 0
	v_or3_b32 v124, v124, v125, v126
	s_nop 0
	v_rcp_f32_e32 v120, v120
	s_nop 0
	v_mul_f32_e32 v120, 0x437f0000, v120
	v_rndne_f32_e32 v120, v120
	v_cvt_i32_f32_e32 v120, v120
	v_rcp_f32_e32 v121, v121
	s_nop 0
	v_mul_f32_e32 v121, 0x437f0000, v121
	v_rndne_f32_e32 v121, v121
	v_cvt_i32_f32_e32 v121, v121
	v_lshl_or_b32 v120, v121, 8, v120
	v_mul_f32_e32 v121, v122, v128
	v_mul_f32_e32 v121, 0xbfb8aa3b, v121
	v_exp_f32_e32 v121, v121
	s_nop 0
	v_add_f32_e32 v121, 1.0, v121
	s_nop 0
	v_rcp_f32_e32 v121, v121
	v_mul_f32_e32 v122, v123, v128
	v_mul_f32_e32 v122, 0xbfb8aa3b, v122
	v_exp_f32_e32 v122, v122
	v_mul_f32_e32 v121, 0x437f0000, v121
	v_rndne_f32_e32 v121, v121
	v_cvt_i32_f32_sdwa v121, v121 dst_sel:WORD_1 dst_unused:UNUSED_PAD src0_sel:DWORD
	v_add_f32_e32 v122, 1.0, v122
	s_nop 0
	v_rcp_f32_e32 v122, v122
	s_nop 0
	v_mul_f32_e32 v122, 0x437f0000, v122
	v_rndne_f32_e32 v122, v122
	v_cvt_i32_f32_sdwa v122, v122 dst_sel:BYTE_3 dst_unused:UNUSED_PAD src0_sel:DWORD
	s_nop 0
	v_or3_b32 v120, v120, v121, v122
	ds_write2st64_b32 v228, v124, v120 offset0:48 offset1:56
	v_or_b32_e32 v120, 64, v152
	v_ashrrev_i32_e32 v121, 31, v120
	v_lshlrev_b64 v[120:121], 6, v[120:121]
	v_lshl_add_u64 v[132:133], s[0:1], 0, v[120:121]
	v_bfe_u32 v244, v132, 6, 8
	v_lshlrev_b32_e32 v244, 3, v244
	v_add_u32_e32 v244, 0x24010, v244
	v_or_b32_e32 v246, 1, v132
	ds_read_b64 v[248:249], v244
	s_waitcnt lgkmcnt(0)
	v_cmp_ne_u32_e64 s[100:101], v248, v246
	s_nop 1
	s_and_saveexec_b64 s[98:99], s[100:101]
	s_cbranch_execz .LrcE0_4
	global_load_dwordx4 v[120:123], v[132:133], off offset:48
	global_load_dwordx4 v[124:127], v[132:133], off offset:32
	global_load_dwordx4 v[128:131], v[132:133], off offset:16
	s_nop 0
	global_load_dwordx4 v[132:135], v[132:133], off
	s_waitcnt vmcnt(2)
	v_add_f32_e32 v124, v124, v125
	v_add_f32_e32 v126, v126, v127
	s_waitcnt vmcnt(0)
	v_mov_b32_e32 v136, v133
	v_mov_b32_e32 v137, v134
	v_mov_b32_e32 v133, v135
	v_mov_b32_e32 v134, v129
	v_mov_b32_e32 v135, v130
	v_mov_b32_e32 v129, v131
	v_pk_add_f32 v[132:133], v[136:137], v[132:133]
	v_pk_add_f32 v[128:129], v[134:135], v[128:129]
	v_pk_add_f32 v[132:133], v[132:133], v[132:133] op_sel:[0,1] op_sel_hi:[1,0]
	v_pk_add_f32 v[128:129], v[128:129], v[128:129] op_sel:[0,1] op_sel_hi:[1,0]
	v_mov_b32_e32 v133, v120
	v_mov_b32_e32 v129, v121
	v_mov_b32_e32 v125, v122
	v_mov_b32_e32 v127, v123
	v_pk_add_f32 v[120:121], v[132:133], v[128:129]
	v_pk_add_f32 v[122:123], v[124:125], v[126:127]
	s_nop 0
	v_pk_add_f32 v[120:121], v[120:121], v[122:123]
	s_nop 0
	v_add_f32_e32 v120, v120, v121
	v_fmamk_f32 v120, v120, 0x3a800000, v225
	v_cmp_gt_f32_e32 vcc, s35, v120
	v_mul_f32_e32 v121, 0x4b800000, v120
	s_nop 0
	v_cndmask_b32_e32 v120, v120, v121, vcc
	v_rsq_f32_e32 v120, v120
	s_nop 0
	v_mul_f32_e32 v121, 0x45800000, v120
	v_cndmask_b32_e32 v120, v120, v121, vcc
	s_nop 0
	v_mov_b32_e32 v247, v120
	ds_write_b64 v244, v[246:247]
; DI int TIDX() { int t = (int)threadIdx.x; asm volatile("" : "+v"(t)); return t; }
; DI float sigmoidf_(float x) { return 1.f / (1.f + __expf(-x)); }
; DI void merge_tile(const Params& p, int layer, int tm, int tn, bf16_t* smem) {
;     ...
;     if ((sg & 1) == 0) {
;       const int t2 = TIDX(), row0 = tm * 256 + ((t2 >> 8) & 1) * 128 + (t2 & 15);
; #pragma unroll
;       for (int i = 0; i < 8; ++i) {
;         asm volatile("" ::: "memory");
;         const float rs = rstd_from16((const float*)(p.ws + O_SSQ) + (size_t)(row0 + i * 16) * 16, 1.f / 1024.f);
; #pragma unroll
;         for (int j = 0; j < 2; ++j) {
;           unsigned w = 0;
; #pragma unroll
;           for (int r = 0; r < 4; ++r) w |= (unsigned)__float2int_rn(sigmoidf_(acc[i][j][r] * rs) * 255.f) << (8 * r);
;           gsp[(i * 2 + j) * NTHR] = w;
;         }
;       }
.LrcE0_4:
	s_or_b64 exec, exec, s[98:99]
	s_waitcnt vmcnt(0)
	v_cndmask_b32_e64 v120, v249, v120, s[100:101]
	v_mul_f32_e32 v116, v116, v120
	v_mul_f32_e32 v116, 0xbfb8aa3b, v116
	v_exp_f32_e32 v116, v116
	v_mul_f32_e32 v117, v117, v120
	v_mul_f32_e32 v117, 0xbfb8aa3b, v117
	v_exp_f32_e32 v117, v117
	v_add_f32_e32 v116, 1.0, v116
	v_add_f32_e32 v117, 1.0, v117
	v_mul_f32_e32 v112, v112, v120
	v_mul_f32_e32 v112, 0xbfb8aa3b, v112
	v_rcp_f32_e32 v116, v116
	s_nop 0
	v_mul_f32_e32 v116, 0x437f0000, v116
	v_rndne_f32_e32 v116, v116
	v_cvt_i32_f32_e32 v116, v116
	v_rcp_f32_e32 v117, v117
	s_nop 0
	v_mul_f32_e32 v117, 0x437f0000, v117
	v_rndne_f32_e32 v117, v117
	v_cvt_i32_f32_e32 v117, v117
	v_exp_f32_e32 v112, v112
	v_mul_f32_e32 v113, v113, v120
	v_mul_f32_e32 v113, 0xbfb8aa3b, v113
	v_lshl_or_b32 v116, v117, 8, v116
	v_mul_f32_e32 v117, v118, v120
	v_mul_f32_e32 v117, 0xbfb8aa3b, v117
	v_exp_f32_e32 v117, v117
	v_add_f32_e32 v112, 1.0, v112
	v_exp_f32_e32 v113, v113
	v_add_f32_e32 v117, 1.0, v117
	v_add_f32_e32 v113, 1.0, v113
	v_rcp_f32_e32 v117, v117
	v_mul_f32_e32 v118, v119, v120
	v_mul_f32_e32 v118, 0xbfb8aa3b, v118
	v_exp_f32_e32 v118, v118
	v_mul_f32_e32 v117, 0x437f0000, v117
	v_rndne_f32_e32 v117, v117
	v_cvt_i32_f32_sdwa v117, v117 dst_sel:WORD_1 dst_unused:UNUSED_PAD src0_sel:DWORD
	v_add_f32_e32 v118, 1.0, v118
	s_nop 0
	v_rcp_f32_e32 v118, v118
	s_nop 0
	v_mul_f32_e32 v118, 0x437f0000, v118
	v_rndne_f32_e32 v118, v118
	v_cvt_i32_f32_sdwa v118, v118 dst_sel:BYTE_3 dst_unused:UNUSED_PAD src0_sel:DWORD
	s_nop 0
	v_or3_b32 v116, v116, v117, v118
	s_nop 0
	v_rcp_f32_e32 v112, v112
	s_nop 0
	v_mul_f32_e32 v112, 0x437f0000, v112
	v_rndne_f32_e32 v112, v112
	v_cvt_i32_f32_e32 v112, v112
	v_rcp_f32_e32 v113, v113
	s_nop 0
	v_mul_f32_e32 v113, 0x437f0000, v113
	v_rndne_f32_e32 v113, v113
	v_cvt_i32_f32_e32 v113, v113
	v_lshl_or_b32 v112, v113, 8, v112
	v_mul_f32_e32 v113, v114, v120
	v_mul_f32_e32 v113, 0xbfb8aa3b, v113
	v_exp_f32_e32 v113, v113
	s_nop 0
	v_add_f32_e32 v113, 1.0, v113
	s_nop 0
	v_rcp_f32_e32 v113, v113
	v_mul_f32_e32 v114, v115, v120
	v_mul_f32_e32 v114, 0xbfb8aa3b, v114
	v_exp_f32_e32 v114, v114
	v_mul_f32_e32 v113, 0x437f0000, v113
	v_rndne_f32_e32 v113, v113
	v_cvt_i32_f32_sdwa v113, v113 dst_sel:WORD_1 dst_unused:UNUSED_PAD src0_sel:DWORD
	v_add_f32_e32 v114, 1.0, v114
	s_nop 0
	v_rcp_f32_e32 v114, v114
	s_nop 0
	v_mul_f32_e32 v114, 0x437f0000, v114
	v_rndne_f32_e32 v114, v114
	v_cvt_i32_f32_sdwa v114, v114 dst_sel:BYTE_3 dst_unused:UNUSED_PAD src0_sel:DWORD
	s_nop 0
	v_or3_b32 v112, v112, v113, v114
	ds_write2st64_b32 v228, v116, v112 offset0:64 offset1:72
	v_or_b32_e32 v112, 0x50, v152
	v_ashrrev_i32_e32 v113, 31, v112
	v_lshlrev_b64 v[112:113], 6, v[112:113]
	v_lshl_add_u64 v[124:125], s[0:1], 0, v[112:113]
	v_bfe_u32 v244, v124, 6, 8
	v_lshlrev_b32_e32 v244, 3, v244
	v_add_u32_e32 v244, 0x24010, v244
	v_or_b32_e32 v246, 1, v124
	ds_read_b64 v[248:249], v244
	s_waitcnt lgkmcnt(0)
	v_cmp_ne_u32_e64 s[100:101], v248, v246
	s_nop 1
	s_and_saveexec_b64 s[98:99], s[100:101]
	s_cbranch_execz .LrcE0_5
	global_load_dwordx4 v[112:115], v[124:125], off offset:48
	global_load_dwordx4 v[116:119], v[124:125], off offset:32
	global_load_dwordx4 v[120:123], v[124:125], off offset:16
	s_nop 0
	global_load_dwordx4 v[124:127], v[124:125], off
	s_waitcnt vmcnt(2)
	v_add_f32_e32 v116, v116, v117
	v_add_f32_e32 v118, v118, v119
	s_waitcnt vmcnt(0)
	v_mov_b32_e32 v128, v125
	v_mov_b32_e32 v129, v126
	v_mov_b32_e32 v125, v127
	v_mov_b32_e32 v126, v121
	v_mov_b32_e32 v127, v122
	v_mov_b32_e32 v121, v123
	v_pk_add_f32 v[124:125], v[128:129], v[124:125]
	v_pk_add_f32 v[120:121], v[126:127], v[120:121]
	v_pk_add_f32 v[124:125], v[124:125], v[124:125] op_sel:[0,1] op_sel_hi:[1,0]
	v_pk_add_f32 v[120:121], v[120:121], v[120:121] op_sel:[0,1] op_sel_hi:[1,0]
	v_mov_b32_e32 v125, v112
	v_mov_b32_e32 v121, v113
	v_mov_b32_e32 v117, v114
	v_mov_b32_e32 v119, v115
	v_pk_add_f32 v[112:113], v[124:125], v[120:121]
	v_pk_add_f32 v[114:115], v[116:117], v[118:119]
	s_nop 0
	v_pk_add_f32 v[112:113], v[112:113], v[114:115]
	s_nop 0
	v_add_f32_e32 v112, v112, v113
	v_fmamk_f32 v112, v112, 0x3a800000, v225
	v_cmp_gt_f32_e32 vcc, s35, v112
	v_mul_f32_e32 v113, 0x4b800000, v112
	s_nop 0
	v_cndmask_b32_e32 v112, v112, v113, vcc
	v_rsq_f32_e32 v112, v112
	s_nop 0
	v_mul_f32_e32 v113, 0x45800000, v112
	v_cndmask_b32_e32 v112, v112, v113, vcc
	s_nop 0
	v_mov_b32_e32 v247, v112
	ds_write_b64 v244, v[246:247]
; DI int TIDX() { int t = (int)threadIdx.x; asm volatile("" : "+v"(t)); return t; }
; DI float sigmoidf_(float x) { return 1.f / (1.f + __expf(-x)); }
; DI void merge_tile(const Params& p, int layer, int tm, int tn, bf16_t* smem) {
;     ...
;     if ((sg & 1) == 0) {
;       const int t2 = TIDX(), row0 = tm * 256 + ((t2 >> 8) & 1) * 128 + (t2 & 15);
; #pragma unroll
;       for (int i = 0; i < 8; ++i) {
;         asm volatile("" ::: "memory");
;         const float rs = rstd_from16((const float*)(p.ws + O_SSQ) + (size_t)(row0 + i * 16) * 16, 1.f / 1024.f);
; #pragma unroll
;         for (int j = 0; j < 2; ++j) {
;           unsigned w = 0;
; #pragma unroll
;           for (int r = 0; r < 4; ++r) w |= (unsigned)__float2int_rn(sigmoidf_(acc[i][j][r] * rs) * 255.f) << (8 * r);
;           gsp[(i * 2 + j) * NTHR] = w;
;         }
;       }
.LrcE0_5:
	s_or_b64 exec, exec, s[98:99]
	s_waitcnt vmcnt(0)
	v_cndmask_b32_e64 v112, v249, v112, s[100:101]
	v_mul_f32_e32 v108, v108, v112
	v_mul_f32_e32 v108, 0xbfb8aa3b, v108
	v_exp_f32_e32 v108, v108
	v_mul_f32_e32 v109, v109, v112
	v_mul_f32_e32 v109, 0xbfb8aa3b, v109
	v_exp_f32_e32 v109, v109
	v_add_f32_e32 v108, 1.0, v108
	v_add_f32_e32 v109, 1.0, v109
	v_mul_f32_e32 v104, v104, v112
	v_mul_f32_e32 v104, 0xbfb8aa3b, v104
	v_rcp_f32_e32 v108, v108
	s_nop 0
	v_mul_f32_e32 v108, 0x437f0000, v108
	v_rndne_f32_e32 v108, v108
	v_cvt_i32_f32_e32 v108, v108
	v_rcp_f32_e32 v109, v109
	s_nop 0
	v_mul_f32_e32 v109, 0x437f0000, v109
	v_rndne_f32_e32 v109, v109
	v_cvt_i32_f32_e32 v109, v109
	v_exp_f32_e32 v104, v104
	v_mul_f32_e32 v105, v105, v112
	v_mul_f32_e32 v105, 0xbfb8aa3b, v105
	v_lshl_or_b32 v108, v109, 8, v108
	v_mul_f32_e32 v109, v110, v112
	v_mul_f32_e32 v109, 0xbfb8aa3b, v109
	v_exp_f32_e32 v109, v109
	v_add_f32_e32 v104, 1.0, v104
	v_exp_f32_e32 v105, v105
	v_add_f32_e32 v109, 1.0, v109
	v_add_f32_e32 v105, 1.0, v105
	v_rcp_f32_e32 v109, v109
	v_mul_f32_e32 v110, v111, v112
	v_mul_f32_e32 v110, 0xbfb8aa3b, v110
	v_exp_f32_e32 v110, v110
	v_mul_f32_e32 v109, 0x437f0000, v109
	v_rndne_f32_e32 v109, v109
	v_cvt_i32_f32_sdwa v109, v109 dst_sel:WORD_1 dst_unused:UNUSED_PAD src0_sel:DWORD
	v_add_f32_e32 v110, 1.0, v110
	s_nop 0
	v_rcp_f32_e32 v110, v110
	s_nop 0
	v_mul_f32_e32 v110, 0x437f0000, v110
	v_rndne_f32_e32 v110, v110
	v_cvt_i32_f32_sdwa v110, v110 dst_sel:BYTE_3 dst_unused:UNUSED_PAD src0_sel:DWORD
	s_nop 0
	v_or3_b32 v108, v108, v109, v110
	s_nop 0
	v_rcp_f32_e32 v104, v104
	s_nop 0
	v_mul_f32_e32 v104, 0x437f0000, v104
	v_rndne_f32_e32 v104, v104
	v_cvt_i32_f32_e32 v104, v104
	v_rcp_f32_e32 v105, v105
	s_nop 0
	v_mul_f32_e32 v105, 0x437f0000, v105
	v_rndne_f32_e32 v105, v105
	v_cvt_i32_f32_e32 v105, v105
	v_lshl_or_b32 v104, v105, 8, v104
	v_mul_f32_e32 v105, v106, v112
	v_mul_f32_e32 v105, 0xbfb8aa3b, v105
	v_exp_f32_e32 v105, v105
	s_nop 0
	v_add_f32_e32 v105, 1.0, v105
	s_nop 0
	v_rcp_f32_e32 v105, v105
	v_mul_f32_e32 v106, v107, v112
	v_mul_f32_e32 v106, 0xbfb8aa3b, v106
	v_exp_f32_e32 v106, v106
	v_mul_f32_e32 v105, 0x437f0000, v105
	v_rndne_f32_e32 v105, v105
	v_cvt_i32_f32_sdwa v105, v105 dst_sel:WORD_1 dst_unused:UNUSED_PAD src0_sel:DWORD
	v_add_f32_e32 v106, 1.0, v106
	s_nop 0
	v_rcp_f32_e32 v106, v106
	s_nop 0
	v_mul_f32_e32 v106, 0x437f0000, v106
	v_rndne_f32_e32 v106, v106
	v_cvt_i32_f32_sdwa v106, v106 dst_sel:BYTE_3 dst_unused:UNUSED_PAD src0_sel:DWORD
	s_nop 0
	v_or3_b32 v104, v104, v105, v106
	ds_write2st64_b32 v228, v108, v104 offset0:80 offset1:88
	v_or_b32_e32 v104, 0x60, v152
	v_ashrrev_i32_e32 v105, 31, v104
	v_lshlrev_b64 v[104:105], 6, v[104:105]
	v_lshl_add_u64 v[116:117], s[0:1], 0, v[104:105]
	v_bfe_u32 v244, v116, 6, 8
	v_lshlrev_b32_e32 v244, 3, v244
	v_add_u32_e32 v244, 0x24010, v244
	v_or_b32_e32 v246, 1, v116
	ds_read_b64 v[248:249], v244
	s_waitcnt lgkmcnt(0)
	v_cmp_ne_u32_e64 s[100:101], v248, v246
	s_nop 1
	s_and_saveexec_b64 s[98:99], s[100:101]
	s_cbranch_execz .LrcE0_6
	global_load_dwordx4 v[104:107], v[116:117], off offset:48
	global_load_dwordx4 v[108:111], v[116:117], off offset:32
	global_load_dwordx4 v[112:115], v[116:117], off offset:16
	s_nop 0
	global_load_dwordx4 v[116:119], v[116:117], off
	s_waitcnt vmcnt(2)
	v_add_f32_e32 v108, v108, v109
	v_add_f32_e32 v110, v110, v111
	s_waitcnt vmcnt(0)
	v_mov_b32_e32 v120, v117
	v_mov_b32_e32 v121, v118
	v_mov_b32_e32 v117, v119
	v_mov_b32_e32 v118, v113
	v_mov_b32_e32 v119, v114
	v_mov_b32_e32 v113, v115
	v_pk_add_f32 v[116:117], v[120:121], v[116:117]
	v_pk_add_f32 v[112:113], v[118:119], v[112:113]
	v_pk_add_f32 v[116:117], v[116:117], v[116:117] op_sel:[0,1] op_sel_hi:[1,0]
	v_pk_add_f32 v[112:113], v[112:113], v[112:113] op_sel:[0,1] op_sel_hi:[1,0]
	v_mov_b32_e32 v117, v104
	v_mov_b32_e32 v113, v105
	v_mov_b32_e32 v109, v106
	v_mov_b32_e32 v111, v107
	v_pk_add_f32 v[104:105], v[116:117], v[112:113]
	v_pk_add_f32 v[106:107], v[108:109], v[110:111]
	s_nop 0
	v_pk_add_f32 v[104:105], v[104:105], v[106:107]
	s_nop 0
	v_add_f32_e32 v104, v104, v105
	v_fmamk_f32 v104, v104, 0x3a800000, v225
	v_cmp_gt_f32_e32 vcc, s35, v104
	v_mul_f32_e32 v105, 0x4b800000, v104
	s_nop 0
	v_cndmask_b32_e32 v104, v104, v105, vcc
	v_rsq_f32_e32 v104, v104
	s_nop 0
	v_mul_f32_e32 v105, 0x45800000, v104
	v_cndmask_b32_e32 v104, v104, v105, vcc
	s_nop 0
	v_mov_b32_e32 v247, v104
	ds_write_b64 v244, v[246:247]
; DI int TIDX() { int t = (int)threadIdx.x; asm volatile("" : "+v"(t)); return t; }
; DI float sigmoidf_(float x) { return 1.f / (1.f + __expf(-x)); }
; DI void merge_tile(const Params& p, int layer, int tm, int tn, bf16_t* smem) {
;     ...
;     if ((sg & 1) == 0) {
;       const int t2 = TIDX(), row0 = tm * 256 + ((t2 >> 8) & 1) * 128 + (t2 & 15);
; #pragma unroll
;       for (int i = 0; i < 8; ++i) {
;         asm volatile("" ::: "memory");
;         const float rs = rstd_from16((const float*)(p.ws + O_SSQ) + (size_t)(row0 + i * 16) * 16, 1.f / 1024.f);
; #pragma unroll
;         for (int j = 0; j < 2; ++j) {
;           unsigned w = 0;
; #pragma unroll
;           for (int r = 0; r < 4; ++r) w |= (unsigned)__float2int_rn(sigmoidf_(acc[i][j][r] * rs) * 255.f) << (8 * r);
;           gsp[(i * 2 + j) * NTHR] = w;
;         }
;       }
.LrcE0_6:
	s_or_b64 exec, exec, s[98:99]
	s_waitcnt vmcnt(0)
	v_cndmask_b32_e64 v104, v249, v104, s[100:101]
	v_mul_f32_e32 v100, v100, v104
	v_mul_f32_e32 v100, 0xbfb8aa3b, v100
	v_exp_f32_e32 v100, v100
	v_mul_f32_e32 v101, v101, v104
	v_mul_f32_e32 v101, 0xbfb8aa3b, v101
	v_exp_f32_e32 v101, v101
	v_add_f32_e32 v100, 1.0, v100
	v_add_f32_e32 v101, 1.0, v101
	v_mul_f32_e32 v96, v96, v104
	v_mul_f32_e32 v96, 0xbfb8aa3b, v96
	v_rcp_f32_e32 v100, v100
	s_nop 0
	v_mul_f32_e32 v100, 0x437f0000, v100
	v_rndne_f32_e32 v100, v100
	v_cvt_i32_f32_e32 v100, v100
	v_rcp_f32_e32 v101, v101
	s_nop 0
	v_mul_f32_e32 v101, 0x437f0000, v101
	v_rndne_f32_e32 v101, v101
	v_cvt_i32_f32_e32 v101, v101
	v_exp_f32_e32 v96, v96
	v_mul_f32_e32 v97, v97, v104
	v_mul_f32_e32 v97, 0xbfb8aa3b, v97
	v_lshl_or_b32 v100, v101, 8, v100
	v_mul_f32_e32 v101, v102, v104
	v_mul_f32_e32 v101, 0xbfb8aa3b, v101
	v_exp_f32_e32 v101, v101
	v_add_f32_e32 v96, 1.0, v96
	v_exp_f32_e32 v97, v97
	v_add_f32_e32 v101, 1.0, v101
	v_add_f32_e32 v97, 1.0, v97
	v_rcp_f32_e32 v101, v101
	v_mul_f32_e32 v102, v103, v104
	v_mul_f32_e32 v102, 0xbfb8aa3b, v102
	v_exp_f32_e32 v102, v102
	v_mul_f32_e32 v101, 0x437f0000, v101
	v_rndne_f32_e32 v101, v101
	v_cvt_i32_f32_sdwa v101, v101 dst_sel:WORD_1 dst_unused:UNUSED_PAD src0_sel:DWORD
	v_add_f32_e32 v102, 1.0, v102
	s_nop 0
	v_rcp_f32_e32 v102, v102
	s_nop 0
	v_mul_f32_e32 v102, 0x437f0000, v102
	v_rndne_f32_e32 v102, v102
	v_cvt_i32_f32_sdwa v102, v102 dst_sel:BYTE_3 dst_unused:UNUSED_PAD src0_sel:DWORD
	s_nop 0
	v_or3_b32 v100, v100, v101, v102
	s_nop 0
	v_rcp_f32_e32 v96, v96
	s_nop 0
	v_mul_f32_e32 v96, 0x437f0000, v96
	v_rndne_f32_e32 v96, v96
	v_cvt_i32_f32_e32 v96, v96
	v_rcp_f32_e32 v97, v97
	s_nop 0
	v_mul_f32_e32 v97, 0x437f0000, v97
	v_rndne_f32_e32 v97, v97
	v_cvt_i32_f32_e32 v97, v97
	v_lshl_or_b32 v96, v97, 8, v96
	v_mul_f32_e32 v97, v98, v104
	v_mul_f32_e32 v97, 0xbfb8aa3b, v97
	v_exp_f32_e32 v97, v97
	s_nop 0
	v_add_f32_e32 v97, 1.0, v97
	s_nop 0
	v_rcp_f32_e32 v97, v97
	v_mul_f32_e32 v98, v99, v104
	v_mul_f32_e32 v98, 0xbfb8aa3b, v98
	v_exp_f32_e32 v98, v98
	v_mul_f32_e32 v97, 0x437f0000, v97
	v_rndne_f32_e32 v97, v97
	v_cvt_i32_f32_sdwa v97, v97 dst_sel:WORD_1 dst_unused:UNUSED_PAD src0_sel:DWORD
	v_add_f32_e32 v98, 1.0, v98
	s_nop 0
	v_rcp_f32_e32 v98, v98
	s_nop 0
	v_mul_f32_e32 v98, 0x437f0000, v98
	v_rndne_f32_e32 v98, v98
	v_cvt_i32_f32_sdwa v98, v98 dst_sel:BYTE_3 dst_unused:UNUSED_PAD src0_sel:DWORD
	s_nop 0
	v_or3_b32 v96, v96, v97, v98
	ds_write2st64_b32 v228, v100, v96 offset0:96 offset1:104
	v_or_b32_e32 v96, 0x70, v152
	v_ashrrev_i32_e32 v97, 31, v96
	v_lshlrev_b64 v[96:97], 6, v[96:97]
	v_lshl_add_u64 v[108:109], s[0:1], 0, v[96:97]
	v_mov_b64_e32 v[154:155], v[86:87]
	v_mov_b64_e32 v[152:153], v[84:85]
	v_bfe_u32 v244, v108, 6, 8
	v_lshlrev_b32_e32 v244, 3, v244
	v_add_u32_e32 v244, 0x24010, v244
	v_or_b32_e32 v246, 1, v108
	ds_read_b64 v[248:249], v244
	s_waitcnt lgkmcnt(0)
	v_cmp_ne_u32_e64 s[100:101], v248, v246
	s_nop 1
	s_and_saveexec_b64 s[98:99], s[100:101]
	s_cbranch_execz .LrcE0_7
	global_load_dwordx4 v[96:99], v[108:109], off offset:48
	global_load_dwordx4 v[100:103], v[108:109], off offset:32
	global_load_dwordx4 v[104:107], v[108:109], off offset:16
	s_nop 0
	global_load_dwordx4 v[108:111], v[108:109], off
	s_waitcnt vmcnt(2)
	v_add_f32_e32 v100, v100, v101
	v_add_f32_e32 v102, v102, v103
	s_waitcnt vmcnt(0)
	v_mov_b32_e32 v112, v109
	v_mov_b32_e32 v113, v110
	v_mov_b32_e32 v109, v111
	v_mov_b32_e32 v110, v105
	v_mov_b32_e32 v111, v106
	v_mov_b32_e32 v105, v107
	v_pk_add_f32 v[108:109], v[112:113], v[108:109]
	v_pk_add_f32 v[104:105], v[110:111], v[104:105]
	v_pk_add_f32 v[108:109], v[108:109], v[108:109] op_sel:[0,1] op_sel_hi:[1,0]
	v_pk_add_f32 v[104:105], v[104:105], v[104:105] op_sel:[0,1] op_sel_hi:[1,0]
	v_mov_b32_e32 v109, v96
	v_mov_b32_e32 v105, v97
	v_mov_b32_e32 v101, v98
	v_mov_b32_e32 v103, v99
	v_pk_add_f32 v[96:97], v[108:109], v[104:105]
	v_pk_add_f32 v[98:99], v[100:101], v[102:103]
	s_nop 0
	v_pk_add_f32 v[96:97], v[96:97], v[98:99]
	s_nop 0
	v_add_f32_e32 v96, v96, v97
	v_fmamk_f32 v96, v96, 0x3a800000, v225
	v_cmp_gt_f32_e32 vcc, s35, v96
	v_mul_f32_e32 v97, 0x4b800000, v96
	s_nop 0
	v_cndmask_b32_e32 v96, v96, v97, vcc
	v_rsq_f32_e32 v96, v96
	s_nop 0
	v_mul_f32_e32 v97, 0x45800000, v96
	v_cndmask_b32_e32 v96, v96, v97, vcc
	s_nop 0
	v_mov_b32_e32 v247, v96
	ds_write_b64 v244, v[246:247]
.LrcE0_7:
	s_or_b64 exec, exec, s[98:99]
	s_waitcnt vmcnt(0)
	v_cndmask_b32_e64 v96, v249, v96, s[100:101]
	v_mul_f32_e32 v92, v92, v96
	v_mul_f32_e32 v92, 0xbfb8aa3b, v92
	v_exp_f32_e32 v92, v92
	v_mul_f32_e32 v93, v93, v96
	v_mul_f32_e32 v93, 0xbfb8aa3b, v93
	v_exp_f32_e32 v93, v93
	v_add_f32_e32 v92, 1.0, v92
	v_add_f32_e32 v93, 1.0, v93
	v_mul_f32_e32 v88, v88, v96
	v_mul_f32_e32 v88, 0xbfb8aa3b, v88
	v_rcp_f32_e32 v92, v92
	s_nop 0
	v_mul_f32_e32 v92, 0x437f0000, v92
	v_rndne_f32_e32 v92, v92
	v_cvt_i32_f32_e32 v92, v92
	v_rcp_f32_e32 v93, v93
	s_nop 0
	v_mul_f32_e32 v93, 0x437f0000, v93
	v_rndne_f32_e32 v93, v93
	v_cvt_i32_f32_e32 v93, v93
	v_exp_f32_e32 v88, v88
	v_mul_f32_e32 v89, v89, v96
	v_mul_f32_e32 v89, 0xbfb8aa3b, v89
	v_lshl_or_b32 v92, v93, 8, v92
	v_mul_f32_e32 v93, v94, v96
	v_mul_f32_e32 v93, 0xbfb8aa3b, v93
	v_exp_f32_e32 v93, v93
	v_add_f32_e32 v88, 1.0, v88
	v_exp_f32_e32 v89, v89
	v_add_f32_e32 v93, 1.0, v93
	v_add_f32_e32 v89, 1.0, v89
	v_rcp_f32_e32 v93, v93
	v_mul_f32_e32 v94, v95, v96
	v_mul_f32_e32 v94, 0xbfb8aa3b, v94
	v_exp_f32_e32 v94, v94
	v_mul_f32_e32 v93, 0x437f0000, v93
	v_rndne_f32_e32 v93, v93
	v_cvt_i32_f32_sdwa v93, v93 dst_sel:WORD_1 dst_unused:UNUSED_PAD src0_sel:DWORD
	v_add_f32_e32 v94, 1.0, v94
	s_nop 0
	v_rcp_f32_e32 v94, v94
	s_nop 0
	v_mul_f32_e32 v94, 0x437f0000, v94
	v_rndne_f32_e32 v94, v94
	v_cvt_i32_f32_sdwa v94, v94 dst_sel:BYTE_3 dst_unused:UNUSED_PAD src0_sel:DWORD
	s_nop 0
	v_or3_b32 v92, v92, v93, v94
	s_nop 0
	v_rcp_f32_e32 v88, v88
	s_nop 0
	v_mul_f32_e32 v88, 0x437f0000, v88
	v_rndne_f32_e32 v88, v88
	v_cvt_i32_f32_e32 v88, v88
	v_rcp_f32_e32 v89, v89
	s_nop 0
	v_mul_f32_e32 v89, 0x437f0000, v89
	v_rndne_f32_e32 v89, v89
	v_cvt_i32_f32_e32 v89, v89
	v_lshl_or_b32 v88, v89, 8, v88
	v_mul_f32_e32 v89, v90, v96
	v_mul_f32_e32 v89, 0xbfb8aa3b, v89
	v_exp_f32_e32 v89, v89
	s_nop 0
	v_add_f32_e32 v89, 1.0, v89
	s_nop 0
	v_rcp_f32_e32 v89, v89
	v_mul_f32_e32 v90, v91, v96
	v_mul_f32_e32 v90, 0xbfb8aa3b, v90
	v_exp_f32_e32 v90, v90
	v_mul_f32_e32 v89, 0x437f0000, v89
	v_rndne_f32_e32 v89, v89
	v_cvt_i32_f32_sdwa v89, v89 dst_sel:WORD_1 dst_unused:UNUSED_PAD src0_sel:DWORD
	v_add_f32_e32 v90, 1.0, v90
	s_nop 0
	v_rcp_f32_e32 v90, v90
	s_nop 0
	v_mul_f32_e32 v90, 0x437f0000, v90
	v_rndne_f32_e32 v90, v90
	v_cvt_i32_f32_sdwa v90, v90 dst_sel:BYTE_3 dst_unused:UNUSED_PAD src0_sel:DWORD
	s_nop 0
	v_or3_b32 v88, v88, v89, v90
	ds_write2st64_b32 v228, v92, v88 offset0:112 offset1:120
	s_add_i32 s40, s40, 1
	s_cmp_lg_u32 s40, 6
	s_cbranch_scc0 .LBB0_833

; DI unsigned pk2(float lo, float hi) { f32x2 v = {lo, hi}; return __builtin_bit_cast(unsigned, __builtin_convertvector(v, bfx2)); }
; DI float bf2f(bf16_t h) { return __uint_as_float(((unsigned)h) << 16); }
; DI float sigmoidf_(float x) { return 1.f / (1.f + __expf(-x)); }
; DI void ffnup_tile(const Params& p, int layer, int b, int mt, int tn, bf16_t* smem) {
;     ...
;     for (int it = 0; it < 8; ++it) {
;       const int row = it * 32 + (tid >> 4), s = s0 + row;
;       if (row >= 2 && s < S_) {
;         const u32x4 u0 = *(const u32x4*)(U + (row - 2) * LDU + cc * 8), u1 = *(const u32x4*)(U + (row - 1) * LDU + cc * 8), u2 = *(const u32x4*)(U + row * LDU + cc * 8), vv = *(const u32x4*)(V + row * LDU + cc * 8);
;         unsigned o[4];
; #pragma unroll
;         for (int e = 0; e < 4; ++e) {
;           float r2[2];
; #pragma unroll
;           for (int h = 0; h < 2; ++h) {
;             const int k = 2 * e + h;
;             const float a0 = bf2f((bf16_t)(h ? u0[e] >> 16 : u0[e] & 0xffffu)), a1 = bf2f((bf16_t)(h ? u1[e] >> 16 : u1[e] & 0xffffu)), a2 = bf2f((bf16_t)(h ? u2[e] >> 16 : u2[e] & 0xffffu)), vx = bf2f((bf16_t)(h ? vv[e] >> 16 : vv[e] & 0xffffu));
;             const float uc = w0[k] * a0 + w1[k] * a1 + w2[k] * a2 + cb[k];
;             r2[h] = uc * sigmoidf_(uc) * vx;
;           }
;           o[e] = pk2(r2[0], r2[1]);
;         }
;         __builtin_nontemporal_store((u32x4){o[0], o[1], o[2], o[3]}, (u32x4*)(act + ((size_t)b * S_ + s) * DFF_ + cg0));
;       }
.LBB0_1068:
	v_add_u32_e32 v40, s4, v38
	v_add_u32_e32 v39, s4, v36
	v_add_u32_e32 v34, -2, v40
	v_cmp_lt_i32_e32 vcc, 1, v39
	v_cmp_gt_i32_e64 s[0:1], s22, v34
	s_and_b64 s[10:11], vcc, s[0:1]
	s_and_saveexec_b64 s[0:1], s[10:11]
	s_cbranch_execz .LBB0_1070
	v_add_u32_e32 v41, 0xfffecbe0, v37
	ds_read_b128 v[42:45], v41
	v_add_u32_e32 v41, 0xfffeccf0, v37
	v_add_u32_e32 v35, 0xfffece00, v37
	ds_read_b128 v[46:49], v41
	ds_read_b128 v[50:53], v35
	v_add_u32_e32 v35, 0xffffde00, v37
	s_waitcnt lgkmcnt(2)
	v_lshlrev_b32_e32 v58, 16, v42
	v_and_b32_e32 v59, 0xffff0000, v42
	s_waitcnt lgkmcnt(1)
	v_lshlrev_b32_e32 v60, 16, v46
	v_and_b32_e32 v61, 0xffff0000, v46
	v_pk_mul_f32 v[60:61], v[8:9], v[60:61]
	s_waitcnt lgkmcnt(0)
	v_lshlrev_b32_e32 v62, 16, v50
	v_and_b32_e32 v63, 0xffff0000, v50
	v_pk_fma_f32 v[58:59], v[4:5], v[58:59], v[60:61]
	ds_read_b128 v[54:57], v35
	v_pk_fma_f32 v[58:59], v[12:13], v[62:63], v[58:59]
	v_lshlrev_b32_e32 v64, 16, v52
	v_pk_add_f32 v[58:59], v[28:29], v[58:59]
	v_and_b32_e32 v65, 0xffff0000, v52
	v_mul_f32_e32 v35, 0xbfb8aa3b, v58
	v_exp_f32_e32 v60, v35
	v_mul_f32_e32 v35, 0xbfb8aa3b, v59
	v_exp_f32_e32 v61, v35
	s_waitcnt lgkmcnt(0)
	v_lshlrev_b32_e32 v62, 16, v54
	v_and_b32_e32 v63, 0xffff0000, v54
	v_pk_add_f32 v[60:61], v[60:61], 1.0 op_sel_hi:[1,0]
	s_nop 0
	s_nop 0
	v_rcp_f32_e32 v61, v61
	v_lshlrev_b32_e32 v46, 16, v47
	v_and_b32_e32 v47, 0xffff0000, v47
	v_lshlrev_b32_e32 v42, 16, v43
	v_and_b32_e32 v43, 0xffff0000, v43
	v_pk_mul_f32 v[46:47], v[10:11], v[46:47]
	v_lshlrev_b32_e32 v50, 16, v51
	v_and_b32_e32 v51, 0xffff0000, v51
	v_pk_fma_f32 v[42:43], v[6:7], v[42:43], v[46:47]
	v_rcp_f32_e32 v60, v60
	v_pk_fma_f32 v[42:43], v[14:15], v[50:51], v[42:43]
	v_pk_mul_f32 v[50:51], v[58:59], v[60:61]
	v_pk_add_f32 v[46:47], v[30:31], v[42:43]
	v_pk_mul_f32 v[50:51], v[50:51], v[62:63]
	v_mul_f32_e32 v41, 0xbfb8aa3b, v46
	v_exp_f32_e32 v42, v41
	v_mul_f32_e32 v41, 0xbfb8aa3b, v47
	v_exp_f32_e32 v43, v41
	v_lshlrev_b32_e32 v62, 16, v48
	v_and_b32_e32 v63, 0xffff0000, v48
	v_and_b32_e32 v61, 0xffff0000, v44
	v_pk_add_f32 v[58:59], v[42:43], 1.0 op_sel_hi:[1,0]
	v_cvt_pk_bf16_f32 v42, v50, v51
	v_lshlrev_b32_e32 v50, 16, v55
	v_and_b32_e32 v51, 0xffff0000, v55
	v_pk_mul_f32 v[62:63], v[16:17], v[62:63]
	v_rcp_f32_e32 v55, v59
	v_lshlrev_b32_e32 v60, 16, v44
	v_pk_fma_f32 v[60:61], v[0:1], v[60:61], v[62:63]
	v_rcp_f32_e32 v54, v58
	v_pk_fma_f32 v[60:61], v[20:21], v[64:65], v[60:61]
	v_pk_mul_f32 v[46:47], v[46:47], v[54:55]
	v_pk_add_f32 v[60:61], v[24:25], v[60:61]
	v_pk_mul_f32 v[46:47], v[46:47], v[50:51]
	v_mul_f32_e32 v41, 0xbfb8aa3b, v60
	v_exp_f32_e32 v62, v41
	v_mul_f32_e32 v41, 0xbfb8aa3b, v61
	v_exp_f32_e32 v63, v41
	v_cvt_pk_bf16_f32 v43, v46, v47
	v_lshlrev_b32_e32 v46, 16, v56
	v_and_b32_e32 v47, 0xffff0000, v56
	v_pk_add_f32 v[50:51], v[62:63], 1.0 op_sel_hi:[1,0]
	s_nop 0
	s_nop 0
	v_rcp_f32_e32 v51, v51
	v_lshlrev_b32_e32 v48, 16, v49
	v_and_b32_e32 v49, 0xffff0000, v49
	v_lshlrev_b32_e32 v44, 16, v45
	v_and_b32_e32 v45, 0xffff0000, v45
	v_pk_mul_f32 v[48:49], v[18:19], v[48:49]
	v_lshlrev_b32_e32 v52, 16, v53
	v_and_b32_e32 v53, 0xffff0000, v53
	v_pk_fma_f32 v[44:45], v[2:3], v[44:45], v[48:49]
	v_rcp_f32_e32 v50, v50
	v_pk_fma_f32 v[44:45], v[22:23], v[52:53], v[44:45]
	v_pk_mul_f32 v[50:51], v[60:61], v[50:51]
	v_pk_add_f32 v[48:49], v[26:27], v[44:45]
	v_pk_mul_f32 v[46:47], v[50:51], v[46:47]
	v_mul_f32_e32 v41, 0xbfb8aa3b, v48
	v_exp_f32_e32 v44, v41
	v_mul_f32_e32 v41, 0xbfb8aa3b, v49
	v_exp_f32_e32 v45, v41
	s_nop 0
	v_pk_add_f32 v[50:51], v[44:45], 1.0 op_sel_hi:[1,0]
	s_nop 0
	v_cvt_pk_bf16_f32 v44, v46, v47
	v_lshlrev_b32_e32 v46, 16, v57
	v_and_b32_e32 v47, 0xffff0000, v57
	v_rcp_f32_e32 v51, v51
	v_rcp_f32_e32 v50, v50
	s_nop 0
	v_pk_mul_f32 v[48:49], v[48:49], v[50:51]
	v_ashrrev_i32_e32 v35, 31, v34
	v_pk_mul_f32 v[46:47], v[48:49], v[46:47]
	v_lshl_add_u64 v[34:35], s[2:3], 0, v[34:35]
	v_cvt_pk_bf16_f32 v45, v46, v47
	v_mad_u64_u32 v[46:47], s[10:11], v34, s26, v[32:33]
	v_mad_i32_i24 v47, v35, s26, v47
	global_store_dwordx4 v[46:47], v[42:45], off nt
; DI unsigned pk2(float lo, float hi) { f32x2 v = {lo, hi}; return __builtin_bit_cast(unsigned, __builtin_convertvector(v, bfx2)); }
; DI float bf2f(bf16_t h) { return __uint_as_float(((unsigned)h) << 16); }
; DI float sigmoidf_(float x) { return 1.f / (1.f + __expf(-x)); }
; DI void ffnup_tile(const Params& p, int layer, int b, int mt, int tn, bf16_t* smem) {
;     ...
;     for (int it = 0; it < 8; ++it) {
;       const int row = it * 32 + (tid >> 4), s = s0 + row;
;       if (row >= 2 && s < S_) {
;         const u32x4 u0 = *(const u32x4*)(U + (row - 2) * LDU + cc * 8), u1 = *(const u32x4*)(U + (row - 1) * LDU + cc * 8), u2 = *(const u32x4*)(U + row * LDU + cc * 8), vv = *(const u32x4*)(V + row * LDU + cc * 8);
;         unsigned o[4];
; #pragma unroll
;         for (int e = 0; e < 4; ++e) {
;           float r2[2];
; #pragma unroll
;           for (int h = 0; h < 2; ++h) {
;             const int k = 2 * e + h;
;             const float a0 = bf2f((bf16_t)(h ? u0[e] >> 16 : u0[e] & 0xffffu)), a1 = bf2f((bf16_t)(h ? u1[e] >> 16 : u1[e] & 0xffffu)), a2 = bf2f((bf16_t)(h ? u2[e] >> 16 : u2[e] & 0xffffu)), vx = bf2f((bf16_t)(h ? vv[e] >> 16 : vv[e] & 0xffffu));
;             const float uc = w0[k] * a0 + w1[k] * a1 + w2[k] * a2 + cb[k];
;             r2[h] = uc * sigmoidf_(uc) * vx;
;           }
;           o[e] = pk2(r2[0], r2[1]);
;         }
;         __builtin_nontemporal_store((u32x4){o[0], o[1], o[2], o[3]}, (u32x4*)(act + ((size_t)b * S_ + s) * DFF_ + cg0));
;       }
.LBB0_1070:
	s_or_b64 exec, exec, s[0:1]
	v_add_u32_e32 v35, 32, v39
	v_add_u32_e32 v34, 30, v40
	v_cmp_lt_i32_e32 vcc, 1, v35
	v_cmp_gt_i32_e64 s[0:1], s22, v34
	s_and_b64 s[10:11], vcc, s[0:1]
	s_and_saveexec_b64 s[0:1], s[10:11]
	s_cbranch_execz .LBB0_1067
	v_add_u32_e32 v39, 0xfffeede0, v37
	ds_read_b128 v[40:43], v39
	v_add_u32_e32 v39, 0xfffeeef0, v37
	v_add_u32_e32 v35, 0xfffef000, v37
	ds_read_b128 v[44:47], v39
	ds_read_b128 v[48:51], v35
	ds_read_b128 v[52:55], v37
	s_waitcnt lgkmcnt(3)
	v_lshlrev_b32_e32 v56, 16, v40
	s_waitcnt lgkmcnt(2)
	v_lshlrev_b32_e32 v58, 16, v44
	v_and_b32_e32 v59, 0xffff0000, v44
	v_and_b32_e32 v57, 0xffff0000, v40
	v_pk_mul_f32 v[58:59], v[8:9], v[58:59]
	s_waitcnt lgkmcnt(1)
	v_lshlrev_b32_e32 v60, 16, v48
	v_and_b32_e32 v61, 0xffff0000, v48
	v_pk_fma_f32 v[56:57], v[4:5], v[56:57], v[58:59]
	v_lshlrev_b32_e32 v62, 16, v50
	v_pk_fma_f32 v[56:57], v[12:13], v[60:61], v[56:57]
	s_waitcnt lgkmcnt(0)
	v_lshlrev_b32_e32 v60, 16, v52
	v_pk_add_f32 v[56:57], v[28:29], v[56:57]
	v_and_b32_e32 v61, 0xffff0000, v52
	v_mul_f32_e32 v35, 0xbfb8aa3b, v56
	v_exp_f32_e32 v58, v35
	v_mul_f32_e32 v35, 0xbfb8aa3b, v57
	v_exp_f32_e32 v59, v35
	v_and_b32_e32 v63, 0xffff0000, v50
	v_pk_add_f32 v[58:59], v[58:59], 1.0 op_sel_hi:[1,0]
	s_nop 0
	s_nop 0
	v_rcp_f32_e32 v59, v59
	v_lshlrev_b32_e32 v44, 16, v45
	v_and_b32_e32 v45, 0xffff0000, v45
	v_lshlrev_b32_e32 v40, 16, v41
	v_and_b32_e32 v41, 0xffff0000, v41
	v_pk_mul_f32 v[44:45], v[10:11], v[44:45]
	v_lshlrev_b32_e32 v48, 16, v49
	v_and_b32_e32 v49, 0xffff0000, v49
	v_pk_fma_f32 v[40:41], v[6:7], v[40:41], v[44:45]
	v_rcp_f32_e32 v58, v58
	v_pk_fma_f32 v[40:41], v[14:15], v[48:49], v[40:41]
	v_pk_mul_f32 v[48:49], v[56:57], v[58:59]
	v_pk_add_f32 v[44:45], v[30:31], v[40:41]
	v_pk_mul_f32 v[48:49], v[48:49], v[60:61]
	v_mul_f32_e32 v39, 0xbfb8aa3b, v44
	v_exp_f32_e32 v40, v39
	v_mul_f32_e32 v39, 0xbfb8aa3b, v45
	v_exp_f32_e32 v41, v39
	v_lshlrev_b32_e32 v60, 16, v46
	v_and_b32_e32 v61, 0xffff0000, v46
	v_and_b32_e32 v59, 0xffff0000, v42
	v_pk_add_f32 v[56:57], v[40:41], 1.0 op_sel_hi:[1,0]
	v_cvt_pk_bf16_f32 v40, v48, v49
	v_lshlrev_b32_e32 v48, 16, v53
	v_and_b32_e32 v49, 0xffff0000, v53
	v_pk_mul_f32 v[60:61], v[16:17], v[60:61]
	v_rcp_f32_e32 v53, v57
	v_lshlrev_b32_e32 v58, 16, v42
	v_pk_fma_f32 v[58:59], v[0:1], v[58:59], v[60:61]
	v_rcp_f32_e32 v52, v56
	v_pk_fma_f32 v[58:59], v[20:21], v[62:63], v[58:59]
	v_pk_mul_f32 v[44:45], v[44:45], v[52:53]
	v_pk_add_f32 v[58:59], v[24:25], v[58:59]
	v_pk_mul_f32 v[44:45], v[44:45], v[48:49]
	v_mul_f32_e32 v39, 0xbfb8aa3b, v58
	v_exp_f32_e32 v60, v39
	v_mul_f32_e32 v39, 0xbfb8aa3b, v59
	v_exp_f32_e32 v61, v39
	v_cvt_pk_bf16_f32 v41, v44, v45
	v_lshlrev_b32_e32 v44, 16, v54
	v_and_b32_e32 v45, 0xffff0000, v54
	v_pk_add_f32 v[48:49], v[60:61], 1.0 op_sel_hi:[1,0]
	s_nop 0
	s_nop 0
	v_rcp_f32_e32 v49, v49
	v_lshlrev_b32_e32 v46, 16, v47
	v_and_b32_e32 v47, 0xffff0000, v47
	v_lshlrev_b32_e32 v42, 16, v43
	v_and_b32_e32 v43, 0xffff0000, v43
	v_pk_mul_f32 v[46:47], v[18:19], v[46:47]
	v_lshlrev_b32_e32 v50, 16, v51
	v_and_b32_e32 v51, 0xffff0000, v51
	v_pk_fma_f32 v[42:43], v[2:3], v[42:43], v[46:47]
	v_rcp_f32_e32 v48, v48
	v_pk_fma_f32 v[42:43], v[22:23], v[50:51], v[42:43]
	v_pk_mul_f32 v[48:49], v[58:59], v[48:49]
	v_pk_add_f32 v[46:47], v[26:27], v[42:43]
	v_pk_mul_f32 v[44:45], v[48:49], v[44:45]
	v_mul_f32_e32 v39, 0xbfb8aa3b, v46
	v_exp_f32_e32 v42, v39
	v_mul_f32_e32 v39, 0xbfb8aa3b, v47
	v_exp_f32_e32 v43, v39
	s_nop 0
	v_pk_add_f32 v[48:49], v[42:43], 1.0 op_sel_hi:[1,0]
	s_nop 0
	v_cvt_pk_bf16_f32 v42, v44, v45
	v_lshlrev_b32_e32 v44, 16, v55
	v_and_b32_e32 v45, 0xffff0000, v55
	v_rcp_f32_e32 v49, v49
	v_rcp_f32_e32 v48, v48
	s_nop 0
	v_pk_mul_f32 v[46:47], v[46:47], v[48:49]
	v_ashrrev_i32_e32 v35, 31, v34
	v_pk_mul_f32 v[44:45], v[46:47], v[44:45]
	v_lshl_add_u64 v[34:35], s[2:3], 0, v[34:35]
	v_cvt_pk_bf16_f32 v43, v44, v45
	v_mad_u64_u32 v[44:45], s[10:11], v34, s26, v[32:33]
	v_mad_i32_i24 v45, v35, s26, v45
	global_store_dwordx4 v[44:45], v[40:43], off nt
	s_branch .LBB0_1067

; DI float sigmoidf_(float x) { return 1.f / (1.f + __expf(-x)); }
; template <bool SWAP> DI void inproj_tile(const Params& p, int layer, int tm, int tn, bf16_t* smem) {
;     ...
;       for (int i = 0; i < 8; ++i) {
;         const int t = trow0 + i * 16 + l15; const float rs = rstd_from16(ssq + (size_t)t * 16, 1.f / 1024.f);
;         float* gt = (float*)(p.ws + O_GATES) + (size_t)t * 24; float* lf = (float*)(p.ws + O_LOGF) + (size_t)t * 8;
; #pragma unroll
;         for (int r = 0; r < 4; ++r) gt[quad * 4 + r] = sigmoidf_(acc[i][0][r] * rs);
;         if (quad < 2) {
; #pragma unroll
;           for (int r = 0; r < 4; ++r) gt[16 + quad * 4 + r] = sigmoidf_(acc[i][1][r] * rs);
;         } else {
; #pragma unroll
;           for (int r = 0; r < 4; ++r) { const int h = (quad - 2) * 4 + r; const float xx = acc[i][1][r] * rs + p.b_forget[layer * 8 + h]; lf[h] = fminf(xx, 0.f) - log1pf(__expf(-fabsf(xx))); }
;         }
.LrcA1_8:
	s_or_b64 exec, exec, s[98:99]
	s_waitcnt vmcnt(0)
	v_cndmask_b32_e64 v130, v249, v130, s[100:101]
	v_mul_f32_e32 v124, v124, v130
	v_mul_f32_e32 v125, v125, v130
	v_mul_f32_e32 v124, 0xbfb8aa3b, v124
	v_mul_f32_e32 v125, 0xbfb8aa3b, v125
	v_exp_f32_e32 v124, v124
	v_exp_f32_e32 v125, v125
	v_mov_b64_e32 v[132:133], s[2:3]
	v_mad_i64_i32 v[134:135], s[2:3], v128, s45, v[132:133]
	v_pk_add_f32 v[124:125], v[124:125], 1.0 op_sel_hi:[1,0]
	v_lshlrev_b64 v[132:133], 5, v[128:129]
	v_mul_f32_e32 v126, v126, v130
	v_mul_f32_e32 v127, v127, v130
	v_mul_f32_e32 v126, 0xbfb8aa3b, v126
	v_rcp_f32_e32 v125, v125
	v_mul_f32_e32 v127, 0xbfb8aa3b, v127
	v_exp_f32_e32 v126, v126
	v_exp_f32_e32 v127, v127
	s_nop 0
	v_pk_add_f32 v[126:127], v[126:127], 1.0 op_sel_hi:[1,0]
	v_rcp_f32_e32 v124, v124
	v_lshl_add_u64 v[134:135], v[134:135], 0, v[160:161]
	v_lshlrev_b32_e32 v160, 2, v131
	v_rcp_f32_e32 v127, v127
	s_nop 0
	v_rcp_f32_e32 v126, v126
	global_store_dwordx4 v[134:135], v[124:127], off
	s_and_saveexec_b64 s[2:3], s[4:5]
	s_xor_b64 s[2:3], exec, s[2:3]
	s_cbranch_execz .LBB0_1297
	v_readlane_b32 s52, v241, 8
	v_readlane_b32 s60, v241, 16
	v_readlane_b32 s61, v241, 17
	v_lshl_add_u64 v[124:125], s[8:9], 0, v[132:133]
	v_lshl_add_u64 v[124:125], v[124:125], 0, v[160:161]
	v_readlane_b32 s53, v241, 9
	v_readlane_b32 s54, v241, 10
	v_readlane_b32 s55, v241, 11
	global_load_dword v126, v160, s[60:61]
	v_readlane_b32 s56, v241, 12
	v_readlane_b32 s57, v241, 13
	v_readlane_b32 s58, v241, 14
	v_readlane_b32 s59, v241, 15
	v_readlane_b32 s62, v241, 18
	v_readlane_b32 s63, v241, 19
	v_readlane_b32 s64, v241, 20
	v_readlane_b32 s65, v241, 21
	v_readlane_b32 s66, v241, 22
	v_readlane_b32 s67, v241, 23
	s_waitcnt vmcnt(0)
	v_fmac_f32_e32 v126, v120, v130
	v_min_f32_e32 v129, 0, v126
	v_mul_f32_e64 v126, |v126|, s46
	v_exp_f32_e32 v134, v126
	s_nop 0
	v_add_f32_e32 v135, 1.0, v134
	v_add_f32_e32 v126, -1.0, v135
	v_sub_f32_e32 v127, v126, v135
	v_add_f32_e32 v127, 1.0, v127
	v_sub_f32_e32 v126, v134, v126
	v_add_f32_e32 v136, v126, v127
	v_frexp_mant_f32_e32 v126, v135
	v_cmp_gt_f32_e32 vcc, s47, v126
	v_cvt_f64_f32_e32 v[126:127], v135
	v_frexp_exp_i32_f64_e32 v126, v[126:127]
	v_subbrev_co_u32_e32 v126, vcc, 0, v126, vcc
	v_sub_u32_e32 v127, 0, v126
	v_ldexp_f32 v135, v135, v127
	v_ldexp_f32 v127, v136, v127
	v_add_f32_e32 v136, -1.0, v135
	v_add_f32_e32 v137, 1.0, v136
	v_sub_f32_e32 v137, v135, v137
	v_add_f32_e32 v137, v127, v137
	v_add_f32_e32 v138, v136, v137
	v_sub_f32_e32 v136, v138, v136
	v_sub_f32_e32 v136, v137, v136
	v_add_f32_e32 v137, 1.0, v135
	v_add_f32_e32 v139, -1.0, v137
	v_sub_f32_e32 v135, v135, v139
	v_add_f32_e32 v127, v127, v135
	v_add_f32_e32 v135, v137, v127
	v_sub_f32_e32 v137, v135, v137
	v_sub_f32_e32 v127, v127, v137
	v_rcp_f32_e32 v137, v135
	v_cvt_f32_i32_e32 v126, v126
	v_cmp_neq_f32_e32 vcc, s49, v134
	v_mul_f32_e32 v139, v138, v137
	v_mul_f32_e32 v140, v135, v139
	v_fma_f32 v141, v139, v135, -v140
	v_fmac_f32_e32 v141, v139, v127
	v_add_f32_e32 v142, v140, v141
	v_sub_f32_e32 v143, v138, v142
	v_sub_f32_e32 v138, v138, v143
	v_sub_f32_e32 v140, v142, v140
	v_sub_f32_e32 v138, v138, v142
	v_add_f32_e32 v136, v136, v138
	v_sub_f32_e32 v138, v140, v141
	v_add_f32_e32 v136, v138, v136
	v_add_f32_e32 v138, v143, v136
	v_mul_f32_e32 v140, v137, v138
	v_mul_f32_e32 v141, v135, v140
	v_fma_f32 v135, v140, v135, -v141
	v_fmac_f32_e32 v135, v140, v127
	v_sub_f32_e32 v127, v143, v138
	v_add_f32_e32 v127, v136, v127
	v_add_f32_e32 v136, v141, v135
	v_sub_f32_e32 v142, v138, v136
	v_sub_f32_e32 v138, v138, v142
	v_sub_f32_e32 v141, v136, v141
	v_sub_f32_e32 v136, v138, v136
	v_add_f32_e32 v127, v127, v136
	v_sub_f32_e32 v135, v141, v135
	v_add_f32_e32 v127, v135, v127
	v_add_f32_e32 v135, v139, v140
	v_add_f32_e32 v127, v142, v127
	v_sub_f32_e32 v136, v135, v139
	v_mul_f32_e32 v127, v137, v127
	v_sub_f32_e32 v136, v140, v136
	v_add_f32_e32 v127, v136, v127
	v_mul_f32_e32 v139, 0x3f317218, v126
	v_add_f32_e32 v136, v135, v127
	v_fma_f32 v140, v126, s48, -v139
	v_mul_f32_e32 v137, v136, v136
	v_fmac_f32_e32 v140, 0xb102e308, v126
	v_sub_f32_e32 v126, v136, v135
	v_fmamk_f32 v138, v137, 0x3e9b6dac, v171
	v_sub_f32_e32 v126, v127, v126
	v_add_f32_e32 v127, v139, v140
	v_fmaak_f32 v138, v137, v138, 0x3f2aaada
	v_sub_f32_e32 v135, v127, v139
	v_ldexp_f32 v139, v136, 1
	v_mul_f32_e32 v136, v136, v137
	v_mul_f32_e32 v136, v136, v138
	v_add_f32_e32 v137, v139, v136
	v_sub_f32_e32 v138, v137, v139
	v_ldexp_f32 v126, v126, 1
	v_sub_f32_e32 v136, v136, v138
	v_add_f32_e32 v126, v126, v136
	v_add_f32_e32 v136, v137, v126
	v_sub_f32_e32 v137, v136, v137
	v_sub_f32_e32 v126, v126, v137
	v_add_f32_e32 v137, v127, v136
	v_sub_f32_e32 v138, v137, v127
	v_sub_f32_e32 v139, v137, v138
	v_sub_f32_e32 v135, v140, v135
	v_sub_f32_e32 v127, v127, v139
	v_sub_f32_e32 v136, v136, v138
	v_add_f32_e32 v127, v136, v127
	v_add_f32_e32 v136, v135, v126
	v_sub_f32_e32 v138, v136, v135
	v_sub_f32_e32 v139, v136, v138
	v_sub_f32_e32 v135, v135, v139
	v_sub_f32_e32 v126, v126, v138
	v_add_f32_e32 v127, v136, v127
	v_add_f32_e32 v126, v126, v135
	v_add_f32_e32 v135, v137, v127
	v_sub_f32_e32 v136, v135, v137
	v_sub_f32_e32 v127, v127, v136
	v_add_f32_e32 v126, v126, v127
	v_add_f32_e32 v126, v135, v126
	v_cndmask_b32_e32 v126, v178, v126, vcc
	v_cmp_ngt_f32_e32 vcc, -1.0, v134
	s_nop 1
	v_cndmask_b32_e32 v126, v179, v126, vcc
	v_cmp_neq_f32_e32 vcc, -1.0, v134
	s_nop 1
	v_cndmask_b32_e32 v126, v180, v126, vcc
	v_cmp_lt_f32_e64 vcc, |v134|, s50
	s_nop 1
	v_cndmask_b32_e32 v126, v126, v134, vcc
	v_sub_f32_e32 v126, v129, v126
	global_store_dword v[124:125], v126, off offset:-32
	global_load_dword v127, v160, s[60:61] offset:4
	s_waitcnt vmcnt(0)
; template <bool SWAP> DI void inproj_tile(const Params& p, int layer, int tm, int tn, bf16_t* smem) {
;     ...
;           for (int r = 0; r < 4; ++r) { const int h = (quad - 2) * 4 + r; const float xx = acc[i][1][r] * rs + p.b_forget[layer * 8 + h]; lf[h] = fminf(xx, 0.f) - log1pf(__expf(-fabsf(xx))); }
	v_fmac_f32_e32 v127, v121, v130
	v_min_f32_e32 v126, 0, v127
	v_mul_f32_e64 v127, |v127|, s46
	v_exp_f32_e32 v127, v127
	s_nop 0
	v_add_f32_e32 v129, 1.0, v127
	v_add_f32_e32 v134, -1.0, v129
	v_sub_f32_e32 v135, v134, v129
	v_add_f32_e32 v135, 1.0, v135
	v_sub_f32_e32 v134, v127, v134
	v_add_f32_e32 v136, v134, v135
	v_frexp_mant_f32_e32 v134, v129
	v_cmp_gt_f32_e32 vcc, s47, v134
	v_cvt_f64_f32_e32 v[134:135], v129
	v_frexp_exp_i32_f64_e32 v134, v[134:135]
	v_subbrev_co_u32_e32 v134, vcc, 0, v134, vcc
	v_sub_u32_e32 v135, 0, v134
	v_ldexp_f32 v129, v129, v135
	v_ldexp_f32 v135, v136, v135
	v_add_f32_e32 v136, -1.0, v129
	v_add_f32_e32 v137, 1.0, v136
	v_sub_f32_e32 v137, v129, v137
	v_add_f32_e32 v137, v135, v137
	v_add_f32_e32 v138, v136, v137
	v_sub_f32_e32 v136, v138, v136
	v_sub_f32_e32 v136, v137, v136
	v_add_f32_e32 v137, 1.0, v129
	v_add_f32_e32 v139, -1.0, v137
	v_sub_f32_e32 v129, v129, v139
	v_add_f32_e32 v129, v135, v129
	v_add_f32_e32 v135, v137, v129
	v_sub_f32_e32 v137, v135, v137
	v_sub_f32_e32 v129, v129, v137
	v_rcp_f32_e32 v137, v135
	v_cvt_f32_i32_e32 v134, v134
	v_cmp_neq_f32_e32 vcc, s49, v127
	v_mul_f32_e32 v139, v138, v137
	v_mul_f32_e32 v140, v135, v139
	v_fma_f32 v141, v139, v135, -v140
	v_fmac_f32_e32 v141, v139, v129
	v_add_f32_e32 v142, v140, v141
	v_sub_f32_e32 v143, v138, v142
	v_sub_f32_e32 v138, v138, v143
	v_sub_f32_e32 v140, v142, v140
	v_sub_f32_e32 v138, v138, v142
	v_add_f32_e32 v136, v136, v138
	v_sub_f32_e32 v138, v140, v141
	v_add_f32_e32 v136, v138, v136
	v_add_f32_e32 v138, v143, v136
	v_mul_f32_e32 v140, v137, v138
	v_mul_f32_e32 v141, v135, v140
	v_fma_f32 v135, v140, v135, -v141
	v_fmac_f32_e32 v135, v140, v129
	v_sub_f32_e32 v129, v143, v138
	v_add_f32_e32 v129, v136, v129
	v_add_f32_e32 v136, v141, v135
	v_sub_f32_e32 v142, v138, v136
	v_sub_f32_e32 v138, v138, v142
	v_sub_f32_e32 v141, v136, v141
	v_sub_f32_e32 v136, v138, v136
	v_add_f32_e32 v129, v129, v136
	v_sub_f32_e32 v135, v141, v135
	v_add_f32_e32 v129, v135, v129
	v_add_f32_e32 v135, v139, v140
	v_add_f32_e32 v129, v142, v129
	v_sub_f32_e32 v136, v135, v139
	v_mul_f32_e32 v129, v137, v129
	v_sub_f32_e32 v136, v140, v136
	v_add_f32_e32 v129, v136, v129
	v_mul_f32_e32 v139, 0x3f317218, v134
	v_add_f32_e32 v136, v135, v129
	v_fma_f32 v140, v134, s48, -v139
	v_mul_f32_e32 v137, v136, v136
	v_fmac_f32_e32 v140, 0xb102e308, v134
	v_sub_f32_e32 v134, v136, v135
	v_fmamk_f32 v138, v137, 0x3e9b6dac, v171
	v_sub_f32_e32 v129, v129, v134
	v_add_f32_e32 v134, v139, v140
	v_fmaak_f32 v138, v137, v138, 0x3f2aaada
	v_sub_f32_e32 v135, v134, v139
	v_ldexp_f32 v139, v136, 1
	v_mul_f32_e32 v136, v136, v137
	v_mul_f32_e32 v136, v136, v138
	v_add_f32_e32 v137, v139, v136
	v_sub_f32_e32 v138, v137, v139
	v_ldexp_f32 v129, v129, 1
	v_sub_f32_e32 v136, v136, v138
	v_add_f32_e32 v129, v129, v136
	v_add_f32_e32 v136, v137, v129
	v_sub_f32_e32 v137, v136, v137
	v_sub_f32_e32 v129, v129, v137
	v_add_f32_e32 v137, v134, v136
	v_sub_f32_e32 v138, v137, v134
	v_sub_f32_e32 v139, v137, v138
	v_sub_f32_e32 v135, v140, v135
	v_sub_f32_e32 v134, v134, v139
	v_sub_f32_e32 v136, v136, v138
	v_add_f32_e32 v134, v136, v134
	v_add_f32_e32 v136, v135, v129
	v_sub_f32_e32 v138, v136, v135
	v_sub_f32_e32 v139, v136, v138
	v_sub_f32_e32 v135, v135, v139
	v_sub_f32_e32 v129, v129, v138
	v_add_f32_e32 v134, v136, v134
	v_add_f32_e32 v129, v129, v135
	v_add_f32_e32 v135, v137, v134
	v_sub_f32_e32 v136, v135, v137
	v_sub_f32_e32 v134, v134, v136
	v_add_f32_e32 v129, v129, v134
	v_add_f32_e32 v129, v135, v129
	v_cndmask_b32_e32 v129, v178, v129, vcc
	v_cmp_ngt_f32_e32 vcc, -1.0, v127
	s_nop 1
	v_cndmask_b32_e32 v129, v179, v129, vcc
	v_cmp_neq_f32_e32 vcc, -1.0, v127
	s_nop 1
	v_cndmask_b32_e32 v129, v180, v129, vcc
	v_cmp_lt_f32_e64 vcc, |v127|, s50
	s_nop 1
	v_cndmask_b32_e32 v127, v129, v127, vcc
	v_sub_f32_e32 v126, v126, v127
	global_store_dword v[124:125], v126, off offset:-28
	global_load_dword v127, v160, s[60:61] offset:8
	s_waitcnt vmcnt(0)
	v_fmac_f32_e32 v127, v122, v130
	v_min_f32_e32 v126, 0, v127
	v_mul_f32_e64 v127, |v127|, s46
	v_exp_f32_e32 v127, v127
	s_nop 0
	v_add_f32_e32 v129, 1.0, v127
	v_add_f32_e32 v134, -1.0, v129
	v_sub_f32_e32 v135, v134, v129
	v_add_f32_e32 v135, 1.0, v135
	v_sub_f32_e32 v134, v127, v134
	v_add_f32_e32 v136, v134, v135
	v_frexp_mant_f32_e32 v134, v129
	v_cmp_gt_f32_e32 vcc, s47, v134
	v_cvt_f64_f32_e32 v[134:135], v129
	v_frexp_exp_i32_f64_e32 v134, v[134:135]
	v_subbrev_co_u32_e32 v134, vcc, 0, v134, vcc
	v_sub_u32_e32 v135, 0, v134
	v_ldexp_f32 v129, v129, v135
	v_ldexp_f32 v135, v136, v135
	v_add_f32_e32 v136, -1.0, v129
	v_add_f32_e32 v137, 1.0, v136
	v_sub_f32_e32 v137, v129, v137
	v_add_f32_e32 v137, v135, v137
	v_add_f32_e32 v138, v136, v137
	v_sub_f32_e32 v136, v138, v136
	v_sub_f32_e32 v136, v137, v136
	v_add_f32_e32 v137, 1.0, v129
	v_add_f32_e32 v139, -1.0, v137
	v_sub_f32_e32 v129, v129, v139
	v_add_f32_e32 v129, v135, v129
	v_add_f32_e32 v135, v137, v129
	v_sub_f32_e32 v137, v135, v137
	v_sub_f32_e32 v129, v129, v137
	v_rcp_f32_e32 v137, v135
	v_cvt_f32_i32_e32 v134, v134
	v_cmp_neq_f32_e32 vcc, s49, v127
	v_mul_f32_e32 v139, v138, v137
	v_mul_f32_e32 v140, v135, v139
	v_fma_f32 v141, v139, v135, -v140
	v_fmac_f32_e32 v141, v139, v129
	v_add_f32_e32 v142, v140, v141
	v_sub_f32_e32 v143, v138, v142
	v_sub_f32_e32 v138, v138, v143
	v_sub_f32_e32 v140, v142, v140
	v_sub_f32_e32 v138, v138, v142
	v_add_f32_e32 v136, v136, v138
	v_sub_f32_e32 v138, v140, v141
	v_add_f32_e32 v136, v138, v136
	v_add_f32_e32 v138, v143, v136
	v_mul_f32_e32 v140, v137, v138
	v_mul_f32_e32 v141, v135, v140
	v_fma_f32 v135, v140, v135, -v141
; DI float sigmoidf_(float x) { return 1.f / (1.f + __expf(-x)); }
; template <bool SWAP> DI void inproj_tile(const Params& p, int layer, int tm, int tn, bf16_t* smem) {
;     ...
;         if (quad < 2) {
; #pragma unroll
;           for (int r = 0; r < 4; ++r) gt[16 + quad * 4 + r] = sigmoidf_(acc[i][1][r] * rs);
;         } else {
;     ...
;           for (int r = 0; r < 4; ++r) { const int h = (quad - 2) * 4 + r; const float xx = acc[i][1][r] * rs + p.b_forget[layer * 8 + h]; lf[h] = fminf(xx, 0.f) - log1pf(__expf(-fabsf(xx))); }
	v_fmac_f32_e32 v135, v140, v129
	v_sub_f32_e32 v129, v143, v138
	v_add_f32_e32 v129, v136, v129
	v_add_f32_e32 v136, v141, v135
	v_sub_f32_e32 v142, v138, v136
	v_sub_f32_e32 v138, v138, v142
	v_sub_f32_e32 v141, v136, v141
	v_sub_f32_e32 v136, v138, v136
	v_add_f32_e32 v129, v129, v136
	v_sub_f32_e32 v135, v141, v135
	v_add_f32_e32 v129, v135, v129
	v_add_f32_e32 v135, v139, v140
	v_add_f32_e32 v129, v142, v129
	v_sub_f32_e32 v136, v135, v139
	v_mul_f32_e32 v129, v137, v129
	v_sub_f32_e32 v136, v140, v136
	v_add_f32_e32 v129, v136, v129
	v_mul_f32_e32 v139, 0x3f317218, v134
	v_add_f32_e32 v136, v135, v129
	v_fma_f32 v140, v134, s48, -v139
	v_mul_f32_e32 v137, v136, v136
	v_fmac_f32_e32 v140, 0xb102e308, v134
	v_sub_f32_e32 v134, v136, v135
	v_fmamk_f32 v138, v137, 0x3e9b6dac, v171
	v_sub_f32_e32 v129, v129, v134
	v_add_f32_e32 v134, v139, v140
	v_fmaak_f32 v138, v137, v138, 0x3f2aaada
	v_sub_f32_e32 v135, v134, v139
	v_ldexp_f32 v139, v136, 1
	v_mul_f32_e32 v136, v136, v137
	v_mul_f32_e32 v136, v136, v138
	v_add_f32_e32 v137, v139, v136
	v_sub_f32_e32 v138, v137, v139
	v_ldexp_f32 v129, v129, 1
	v_sub_f32_e32 v136, v136, v138
	v_add_f32_e32 v129, v129, v136
	v_add_f32_e32 v136, v137, v129
	v_sub_f32_e32 v137, v136, v137
	v_sub_f32_e32 v129, v129, v137
	v_add_f32_e32 v137, v134, v136
	v_sub_f32_e32 v138, v137, v134
	v_sub_f32_e32 v139, v137, v138
	v_sub_f32_e32 v135, v140, v135
	v_sub_f32_e32 v134, v134, v139
	v_sub_f32_e32 v136, v136, v138
	v_add_f32_e32 v134, v136, v134
	v_add_f32_e32 v136, v135, v129
	v_sub_f32_e32 v138, v136, v135
	v_sub_f32_e32 v139, v136, v138
	v_sub_f32_e32 v135, v135, v139
	v_sub_f32_e32 v129, v129, v138
	v_add_f32_e32 v134, v136, v134
	v_add_f32_e32 v129, v129, v135
	v_add_f32_e32 v135, v137, v134
	v_sub_f32_e32 v136, v135, v137
	v_sub_f32_e32 v134, v134, v136
	v_add_f32_e32 v129, v129, v134
	v_add_f32_e32 v129, v135, v129
	v_cndmask_b32_e32 v129, v178, v129, vcc
	v_cmp_ngt_f32_e32 vcc, -1.0, v127
	s_nop 1
	v_cndmask_b32_e32 v129, v179, v129, vcc
	v_cmp_neq_f32_e32 vcc, -1.0, v127
	s_nop 1
	v_cndmask_b32_e32 v129, v180, v129, vcc
	v_cmp_lt_f32_e64 vcc, |v127|, s50
	s_nop 1
	v_cndmask_b32_e32 v127, v129, v127, vcc
	v_sub_f32_e32 v126, v126, v127
	global_store_dword v[124:125], v126, off offset:-24
	global_load_dword v127, v160, s[60:61] offset:12
	s_waitcnt vmcnt(0)
	v_fmac_f32_e32 v127, v123, v130
	v_min_f32_e32 v126, 0, v127
	v_mul_f32_e64 v127, |v127|, s46
	v_exp_f32_e32 v127, v127
	s_nop 0
	v_add_f32_e32 v129, 1.0, v127
	v_add_f32_e32 v134, -1.0, v129
	v_sub_f32_e32 v135, v134, v129
	v_add_f32_e32 v135, 1.0, v135
	v_sub_f32_e32 v134, v127, v134
	v_add_f32_e32 v136, v134, v135
	v_frexp_mant_f32_e32 v134, v129
	v_cmp_gt_f32_e32 vcc, s47, v134
	v_cvt_f64_f32_e32 v[134:135], v129
	v_frexp_exp_i32_f64_e32 v134, v[134:135]
	v_subbrev_co_u32_e32 v134, vcc, 0, v134, vcc
	v_sub_u32_e32 v135, 0, v134
	v_ldexp_f32 v129, v129, v135
	v_ldexp_f32 v135, v136, v135
	v_add_f32_e32 v136, -1.0, v129
	v_add_f32_e32 v137, 1.0, v136
	v_sub_f32_e32 v137, v129, v137
	v_add_f32_e32 v137, v135, v137
	v_add_f32_e32 v138, v136, v137
	v_sub_f32_e32 v136, v138, v136
	v_sub_f32_e32 v136, v137, v136
	v_add_f32_e32 v137, 1.0, v129
	v_add_f32_e32 v139, -1.0, v137
	v_sub_f32_e32 v129, v129, v139
	v_add_f32_e32 v129, v135, v129
	v_add_f32_e32 v135, v137, v129
	v_sub_f32_e32 v137, v135, v137
	v_sub_f32_e32 v129, v129, v137
	v_rcp_f32_e32 v137, v135
	v_cvt_f32_i32_e32 v134, v134
	v_cmp_neq_f32_e32 vcc, s49, v127
	v_mul_f32_e32 v139, v138, v137
	v_mul_f32_e32 v140, v135, v139
	v_fma_f32 v141, v139, v135, -v140
	v_fmac_f32_e32 v141, v139, v129
	v_add_f32_e32 v142, v140, v141
	v_sub_f32_e32 v143, v138, v142
	v_sub_f32_e32 v138, v138, v143
	v_sub_f32_e32 v140, v142, v140
	v_sub_f32_e32 v138, v138, v142
	v_add_f32_e32 v136, v136, v138
	v_sub_f32_e32 v138, v140, v141
	v_add_f32_e32 v136, v138, v136
	v_add_f32_e32 v138, v143, v136
	v_mul_f32_e32 v140, v137, v138
	v_mul_f32_e32 v141, v135, v140
	v_fma_f32 v135, v140, v135, -v141
	v_fmac_f32_e32 v135, v140, v129
	v_sub_f32_e32 v129, v143, v138
	v_add_f32_e32 v129, v136, v129
	v_add_f32_e32 v136, v141, v135
	v_sub_f32_e32 v142, v138, v136
	v_sub_f32_e32 v138, v138, v142
	v_sub_f32_e32 v141, v136, v141
	v_sub_f32_e32 v136, v138, v136
	v_add_f32_e32 v129, v129, v136
	v_sub_f32_e32 v135, v141, v135
	v_add_f32_e32 v129, v135, v129
	v_add_f32_e32 v135, v139, v140
	v_add_f32_e32 v129, v142, v129
	v_sub_f32_e32 v136, v135, v139
	v_mul_f32_e32 v129, v137, v129
	v_sub_f32_e32 v136, v140, v136
	v_add_f32_e32 v129, v136, v129
	v_mul_f32_e32 v139, 0x3f317218, v134
	v_add_f32_e32 v136, v135, v129
	v_fma_f32 v140, v134, s48, -v139
	v_mul_f32_e32 v137, v136, v136
	v_fmac_f32_e32 v140, 0xb102e308, v134
	v_sub_f32_e32 v134, v136, v135
	v_fmamk_f32 v138, v137, 0x3e9b6dac, v171
	v_sub_f32_e32 v129, v129, v134
	v_add_f32_e32 v134, v139, v140
	v_fmaak_f32 v138, v137, v138, 0x3f2aaada
	v_sub_f32_e32 v135, v134, v139
	v_ldexp_f32 v139, v136, 1
	v_mul_f32_e32 v136, v136, v137
	v_mul_f32_e32 v136, v136, v138
	v_add_f32_e32 v137, v139, v136
	v_sub_f32_e32 v138, v137, v139
	v_ldexp_f32 v129, v129, 1
	v_sub_f32_e32 v136, v136, v138
	v_add_f32_e32 v129, v129, v136
	v_add_f32_e32 v136, v137, v129
	v_sub_f32_e32 v137, v136, v137
	v_sub_f32_e32 v129, v129, v137
	v_add_f32_e32 v137, v134, v136
	v_sub_f32_e32 v138, v137, v134
	v_sub_f32_e32 v139, v137, v138
	v_sub_f32_e32 v135, v140, v135
	v_sub_f32_e32 v134, v134, v139
	v_sub_f32_e32 v136, v136, v138
	v_add_f32_e32 v134, v136, v134
	v_add_f32_e32 v136, v135, v129
	v_sub_f32_e32 v138, v136, v135
	v_sub_f32_e32 v139, v136, v138
	v_sub_f32_e32 v135, v135, v139
	v_sub_f32_e32 v129, v129, v138
	v_add_f32_e32 v134, v136, v134
	v_add_f32_e32 v129, v129, v135
	v_add_f32_e32 v135, v137, v134
	v_sub_f32_e32 v136, v135, v137
	v_sub_f32_e32 v134, v134, v136
	v_add_f32_e32 v129, v129, v134
	v_add_f32_e32 v129, v135, v129
	v_cndmask_b32_e32 v129, v178, v129, vcc
	v_cmp_ngt_f32_e32 vcc, -1.0, v127
	s_nop 1
	v_cndmask_b32_e32 v129, v179, v129, vcc
	v_cmp_neq_f32_e32 vcc, -1.0, v127
	s_nop 1
	v_cndmask_b32_e32 v129, v180, v129, vcc
	v_cmp_lt_f32_e64 vcc, |v127|, s50
	s_nop 1
	v_cndmask_b32_e32 v127, v129, v127, vcc
	v_sub_f32_e32 v126, v126, v127
	global_store_dword v[124:125], v126, off offset:-20
.LBB0_1297:
	s_andn2_saveexec_b64 s[2:3], s[2:3]
	s_cbranch_execz .LBB0_1299
	v_mul_f32_e32 v120, v120, v130
	v_mul_f32_e32 v121, v121, v130
	v_mul_f32_e32 v120, 0xbfb8aa3b, v120
	v_mul_f32_e32 v121, 0xbfb8aa3b, v121
	v_exp_f32_e32 v120, v120
	v_exp_f32_e32 v121, v121
	v_mul_f32_e32 v122, v122, v130
	v_mul_f32_e32 v123, v123, v130
	v_mul_f32_e32 v122, 0xbfb8aa3b, v122
	v_pk_add_f32 v[120:121], v[120:121], 1.0 op_sel_hi:[1,0]
	v_mul_f32_e32 v123, 0xbfb8aa3b, v123
	v_exp_f32_e32 v122, v122
	v_exp_f32_e32 v123, v123
	v_rcp_f32_e32 v121, v121
	v_pk_add_f32 v[122:123], v[122:123], 1.0 op_sel_hi:[1,0]
	v_rcp_f32_e32 v120, v120
	s_nop 0
	v_rcp_f32_e32 v123, v123
	s_nop 0
	v_rcp_f32_e32 v122, v122
	global_store_dwordx4 v[134:135], v[120:123], off offset:64

; DI float sigmoidf_(float x) { return 1.f / (1.f + __expf(-x)); }
; template <bool SWAP> DI void inproj_tile(const Params& p, int layer, int tm, int tn, bf16_t* smem) {
;     ...
;       for (int i = 0; i < 8; ++i) {
;         const int t = trow0 + i * 16 + l15; const float rs = rstd_from16(ssq + (size_t)t * 16, 1.f / 1024.f);
;         float* gt = (float*)(p.ws + O_GATES) + (size_t)t * 24; float* lf = (float*)(p.ws + O_LOGF) + (size_t)t * 8;
; #pragma unroll
;         for (int r = 0; r < 4; ++r) gt[quad * 4 + r] = sigmoidf_(acc[i][0][r] * rs);
;         if (quad < 2) {
; #pragma unroll
;           for (int r = 0; r < 4; ++r) gt[16 + quad * 4 + r] = sigmoidf_(acc[i][1][r] * rs);
;         } else {
; #pragma unroll
;           for (int r = 0; r < 4; ++r) { const int h = (quad - 2) * 4 + r; const float xx = acc[i][1][r] * rs + p.b_forget[layer * 8 + h]; lf[h] = fminf(xx, 0.f) - log1pf(__expf(-fabsf(xx))); }
;         }
.LrcA1_9:
	s_or_b64 exec, exec, s[98:99]
	s_waitcnt vmcnt(0)
	v_cndmask_b32_e64 v114, v249, v114, s[100:101]
	v_readlane_b32 s2, v240, 35
	v_readlane_b32 s3, v240, 36
	s_nop 1
	v_mov_b64_e32 v[116:117], s[2:3]
	v_mad_i64_i32 v[118:119], s[2:3], v126, s45, v[116:117]
	v_lshlrev_b64 v[116:117], 5, v[126:127]
	v_lshl_add_u64 v[118:119], v[118:119], 0, v[160:161]
	v_mul_f32_e32 v108, v108, v114
	v_mul_f32_e32 v109, v109, v114
	v_mul_f32_e32 v108, 0xbfb8aa3b, v108
	v_mul_f32_e32 v109, 0xbfb8aa3b, v109
	v_exp_f32_e32 v108, v108
	v_exp_f32_e32 v109, v109
	v_mul_f32_e32 v110, v110, v114
	v_mul_f32_e32 v111, v111, v114
	v_mul_f32_e32 v110, 0xbfb8aa3b, v110
	v_pk_add_f32 v[108:109], v[108:109], 1.0 op_sel_hi:[1,0]
	v_mul_f32_e32 v111, 0xbfb8aa3b, v111
	v_exp_f32_e32 v110, v110
	v_exp_f32_e32 v111, v111
	v_rcp_f32_e32 v109, v109
	v_pk_add_f32 v[110:111], v[110:111], 1.0 op_sel_hi:[1,0]
	v_rcp_f32_e32 v108, v108
	s_nop 0
	v_rcp_f32_e32 v111, v111
	s_nop 0
	v_rcp_f32_e32 v110, v110
	global_store_dwordx4 v[118:119], v[108:111], off
	s_and_saveexec_b64 s[2:3], s[4:5]
	s_xor_b64 s[2:3], exec, s[2:3]
	s_cbranch_execz .LBB0_1301
	v_readlane_b32 s52, v241, 8
	v_readlane_b32 s60, v241, 16
	v_readlane_b32 s61, v241, 17
	v_lshl_add_u64 v[108:109], s[8:9], 0, v[116:117]
	v_lshl_add_u64 v[108:109], v[108:109], 0, v[160:161]
	v_readlane_b32 s53, v241, 9
	v_readlane_b32 s54, v241, 10
	v_readlane_b32 s55, v241, 11
	global_load_dword v110, v160, s[60:61]
	v_readlane_b32 s56, v241, 12
	v_readlane_b32 s57, v241, 13
	v_readlane_b32 s58, v241, 14
	v_readlane_b32 s59, v241, 15
	v_readlane_b32 s62, v241, 18
	v_readlane_b32 s63, v241, 19
	v_readlane_b32 s64, v241, 20
	v_readlane_b32 s65, v241, 21
	v_readlane_b32 s66, v241, 22
	v_readlane_b32 s67, v241, 23
	s_waitcnt vmcnt(0)
	v_fmac_f32_e32 v110, v104, v114
	v_min_f32_e32 v113, 0, v110
	v_mul_f32_e64 v110, |v110|, s46
	v_exp_f32_e32 v115, v110
	s_nop 0
	v_add_f32_e32 v118, 1.0, v115
	v_add_f32_e32 v110, -1.0, v118
	v_sub_f32_e32 v111, v110, v118
	v_add_f32_e32 v111, 1.0, v111
	v_sub_f32_e32 v110, v115, v110
	v_add_f32_e32 v119, v110, v111
	v_frexp_mant_f32_e32 v110, v118
	v_cmp_gt_f32_e32 vcc, s47, v110
	v_cvt_f64_f32_e32 v[110:111], v118
	v_frexp_exp_i32_f64_e32 v110, v[110:111]
	v_subbrev_co_u32_e32 v110, vcc, 0, v110, vcc
	v_sub_u32_e32 v111, 0, v110
	v_ldexp_f32 v118, v118, v111
	v_ldexp_f32 v111, v119, v111
	v_add_f32_e32 v119, -1.0, v118
	v_add_f32_e32 v120, 1.0, v119
	v_sub_f32_e32 v120, v118, v120
	v_add_f32_e32 v120, v111, v120
	v_add_f32_e32 v121, v119, v120
	v_sub_f32_e32 v119, v121, v119
	v_sub_f32_e32 v119, v120, v119
	v_add_f32_e32 v120, 1.0, v118
	v_add_f32_e32 v122, -1.0, v120
	v_sub_f32_e32 v118, v118, v122
	v_add_f32_e32 v111, v111, v118
	v_add_f32_e32 v118, v120, v111
	v_sub_f32_e32 v120, v118, v120
	v_sub_f32_e32 v111, v111, v120
	v_rcp_f32_e32 v120, v118
	v_cvt_f32_i32_e32 v110, v110
	v_cmp_neq_f32_e32 vcc, s49, v115
	v_mul_f32_e32 v122, v121, v120
	v_mul_f32_e32 v123, v118, v122
	v_fma_f32 v124, v122, v118, -v123
	v_fmac_f32_e32 v124, v122, v111
	v_add_f32_e32 v125, v123, v124
	v_sub_f32_e32 v126, v121, v125
	v_sub_f32_e32 v121, v121, v126
	v_sub_f32_e32 v123, v125, v123
	v_sub_f32_e32 v121, v121, v125
	v_add_f32_e32 v119, v119, v121
	v_sub_f32_e32 v121, v123, v124
	v_add_f32_e32 v119, v121, v119
	v_add_f32_e32 v121, v126, v119
	v_mul_f32_e32 v123, v120, v121
	v_mul_f32_e32 v124, v118, v123
	v_fma_f32 v118, v123, v118, -v124
	v_fmac_f32_e32 v118, v123, v111
	v_sub_f32_e32 v111, v126, v121
	v_add_f32_e32 v111, v119, v111
	v_add_f32_e32 v119, v124, v118
	v_sub_f32_e32 v125, v121, v119
	v_sub_f32_e32 v121, v121, v125
	v_sub_f32_e32 v124, v119, v124
	v_sub_f32_e32 v119, v121, v119
	v_add_f32_e32 v111, v111, v119
	v_sub_f32_e32 v118, v124, v118
	v_add_f32_e32 v111, v118, v111
	v_add_f32_e32 v118, v122, v123
	v_add_f32_e32 v111, v125, v111
	v_sub_f32_e32 v119, v118, v122
	v_mul_f32_e32 v111, v120, v111
	v_sub_f32_e32 v119, v123, v119
	v_add_f32_e32 v111, v119, v111
	v_mul_f32_e32 v122, 0x3f317218, v110
	v_add_f32_e32 v119, v118, v111
	v_fma_f32 v123, v110, s48, -v122
	v_mul_f32_e32 v120, v119, v119
	v_fmac_f32_e32 v123, 0xb102e308, v110
	v_sub_f32_e32 v110, v119, v118
	v_fmamk_f32 v121, v120, 0x3e9b6dac, v171
	v_sub_f32_e32 v110, v111, v110
	v_add_f32_e32 v111, v122, v123
	v_fmaak_f32 v121, v120, v121, 0x3f2aaada
	v_sub_f32_e32 v118, v111, v122
	v_ldexp_f32 v122, v119, 1
	v_mul_f32_e32 v119, v119, v120
	v_mul_f32_e32 v119, v119, v121
	v_add_f32_e32 v120, v122, v119
	v_sub_f32_e32 v121, v120, v122
	v_ldexp_f32 v110, v110, 1
	v_sub_f32_e32 v119, v119, v121
	v_add_f32_e32 v110, v110, v119
	v_add_f32_e32 v119, v120, v110
	v_sub_f32_e32 v120, v119, v120
	v_sub_f32_e32 v110, v110, v120
	v_add_f32_e32 v120, v111, v119
	v_sub_f32_e32 v121, v120, v111
	v_sub_f32_e32 v122, v120, v121
	v_sub_f32_e32 v118, v123, v118
	v_sub_f32_e32 v111, v111, v122
	v_sub_f32_e32 v119, v119, v121
	v_add_f32_e32 v111, v119, v111
	v_add_f32_e32 v119, v118, v110
	v_sub_f32_e32 v121, v119, v118
	v_sub_f32_e32 v122, v119, v121
	v_sub_f32_e32 v118, v118, v122
	v_sub_f32_e32 v110, v110, v121
	v_add_f32_e32 v111, v119, v111
	v_add_f32_e32 v110, v110, v118
	v_add_f32_e32 v118, v120, v111
	v_sub_f32_e32 v119, v118, v120
	v_sub_f32_e32 v111, v111, v119
	v_add_f32_e32 v110, v110, v111
	v_add_f32_e32 v110, v118, v110
	v_cndmask_b32_e32 v110, v178, v110, vcc
	v_cmp_ngt_f32_e32 vcc, -1.0, v115
	s_nop 1
	v_cndmask_b32_e32 v110, v179, v110, vcc
	v_cmp_neq_f32_e32 vcc, -1.0, v115
	s_nop 1
	v_cndmask_b32_e32 v110, v180, v110, vcc
	v_cmp_lt_f32_e64 vcc, |v115|, s50
	s_nop 1
	v_cndmask_b32_e32 v110, v110, v115, vcc
	v_sub_f32_e32 v110, v113, v110
	global_store_dword v[108:109], v110, off offset:-32
	global_load_dword v111, v160, s[60:61] offset:4
	s_waitcnt vmcnt(0)
; template <bool SWAP> DI void inproj_tile(const Params& p, int layer, int tm, int tn, bf16_t* smem) {
;     ...
;           for (int r = 0; r < 4; ++r) { const int h = (quad - 2) * 4 + r; const float xx = acc[i][1][r] * rs + p.b_forget[layer * 8 + h]; lf[h] = fminf(xx, 0.f) - log1pf(__expf(-fabsf(xx))); }
	v_fmac_f32_e32 v111, v105, v114
	v_min_f32_e32 v110, 0, v111
	v_mul_f32_e64 v111, |v111|, s46
	v_exp_f32_e32 v111, v111
	s_nop 0
	v_add_f32_e32 v113, 1.0, v111
	v_add_f32_e32 v115, -1.0, v113
	v_sub_f32_e32 v118, v115, v113
	v_add_f32_e32 v118, 1.0, v118
	v_sub_f32_e32 v115, v111, v115
	v_add_f32_e32 v115, v115, v118
	v_frexp_mant_f32_e32 v118, v113
	v_cmp_gt_f32_e32 vcc, s47, v118
	v_cvt_f64_f32_e32 v[118:119], v113
	v_frexp_exp_i32_f64_e32 v118, v[118:119]
	v_subbrev_co_u32_e32 v118, vcc, 0, v118, vcc
	v_sub_u32_e32 v119, 0, v118
	v_ldexp_f32 v113, v113, v119
	v_ldexp_f32 v115, v115, v119
	v_add_f32_e32 v119, -1.0, v113
	v_add_f32_e32 v120, 1.0, v119
	v_sub_f32_e32 v120, v113, v120
	v_add_f32_e32 v120, v115, v120
	v_add_f32_e32 v121, v119, v120
	v_sub_f32_e32 v119, v121, v119
	v_sub_f32_e32 v119, v120, v119
	v_add_f32_e32 v120, 1.0, v113
	v_add_f32_e32 v122, -1.0, v120
	v_sub_f32_e32 v113, v113, v122
	v_add_f32_e32 v113, v115, v113
	v_add_f32_e32 v115, v120, v113
	v_sub_f32_e32 v120, v115, v120
	v_sub_f32_e32 v113, v113, v120
	v_rcp_f32_e32 v120, v115
	v_cvt_f32_i32_e32 v118, v118
	v_cmp_neq_f32_e32 vcc, s49, v111
	v_mul_f32_e32 v122, v121, v120
	v_mul_f32_e32 v123, v115, v122
	v_fma_f32 v124, v122, v115, -v123
	v_fmac_f32_e32 v124, v122, v113
	v_add_f32_e32 v125, v123, v124
	v_sub_f32_e32 v126, v121, v125
	v_sub_f32_e32 v121, v121, v126
	v_sub_f32_e32 v123, v125, v123
	v_sub_f32_e32 v121, v121, v125
	v_add_f32_e32 v119, v119, v121
	v_sub_f32_e32 v121, v123, v124
	v_add_f32_e32 v119, v121, v119
	v_add_f32_e32 v121, v126, v119
	v_mul_f32_e32 v123, v120, v121
	v_mul_f32_e32 v124, v115, v123
	v_fma_f32 v115, v123, v115, -v124
	v_fmac_f32_e32 v115, v123, v113
	v_sub_f32_e32 v113, v126, v121
	v_add_f32_e32 v113, v119, v113
	v_add_f32_e32 v119, v124, v115
	v_sub_f32_e32 v125, v121, v119
	v_sub_f32_e32 v121, v121, v125
	v_sub_f32_e32 v124, v119, v124
	v_sub_f32_e32 v119, v121, v119
	v_add_f32_e32 v113, v113, v119
	v_sub_f32_e32 v115, v124, v115
	v_add_f32_e32 v113, v115, v113
	v_add_f32_e32 v115, v122, v123
	v_add_f32_e32 v113, v125, v113
	v_sub_f32_e32 v119, v115, v122
	v_mul_f32_e32 v113, v120, v113
	v_sub_f32_e32 v119, v123, v119
	v_add_f32_e32 v113, v119, v113
	v_mul_f32_e32 v122, 0x3f317218, v118
	v_add_f32_e32 v119, v115, v113
	v_fma_f32 v123, v118, s48, -v122
	v_mul_f32_e32 v120, v119, v119
	v_fmac_f32_e32 v123, 0xb102e308, v118
	v_sub_f32_e32 v115, v119, v115
	v_fmamk_f32 v121, v120, 0x3e9b6dac, v171
	v_sub_f32_e32 v113, v113, v115
	v_add_f32_e32 v115, v122, v123
	v_fmaak_f32 v121, v120, v121, 0x3f2aaada
	v_sub_f32_e32 v118, v115, v122
	v_ldexp_f32 v122, v119, 1
	v_mul_f32_e32 v119, v119, v120
	v_mul_f32_e32 v119, v119, v121
	v_add_f32_e32 v120, v122, v119
	v_sub_f32_e32 v121, v120, v122
	v_ldexp_f32 v113, v113, 1
	v_sub_f32_e32 v119, v119, v121
	v_add_f32_e32 v113, v113, v119
	v_add_f32_e32 v119, v120, v113
	v_sub_f32_e32 v120, v119, v120
	v_sub_f32_e32 v113, v113, v120
	v_add_f32_e32 v120, v115, v119
	v_sub_f32_e32 v121, v120, v115
	v_sub_f32_e32 v122, v120, v121
	v_sub_f32_e32 v118, v123, v118
	v_sub_f32_e32 v115, v115, v122
	v_sub_f32_e32 v119, v119, v121
	v_add_f32_e32 v115, v119, v115
	v_add_f32_e32 v119, v118, v113
	v_sub_f32_e32 v121, v119, v118
	v_sub_f32_e32 v122, v119, v121
	v_sub_f32_e32 v118, v118, v122
	v_sub_f32_e32 v113, v113, v121
	v_add_f32_e32 v115, v119, v115
	v_add_f32_e32 v113, v113, v118
	v_add_f32_e32 v118, v120, v115
	v_sub_f32_e32 v119, v118, v120
	v_sub_f32_e32 v115, v115, v119
	v_add_f32_e32 v113, v113, v115
	v_add_f32_e32 v113, v118, v113
	v_cndmask_b32_e32 v113, v178, v113, vcc
	v_cmp_ngt_f32_e32 vcc, -1.0, v111
	s_nop 1
	v_cndmask_b32_e32 v113, v179, v113, vcc
	v_cmp_neq_f32_e32 vcc, -1.0, v111
	s_nop 1
	v_cndmask_b32_e32 v113, v180, v113, vcc
	v_cmp_lt_f32_e64 vcc, |v111|, s50
	s_nop 1
	v_cndmask_b32_e32 v111, v113, v111, vcc
	v_sub_f32_e32 v110, v110, v111
	global_store_dword v[108:109], v110, off offset:-28
	global_load_dword v111, v160, s[60:61] offset:8
	s_waitcnt vmcnt(0)
	v_fmac_f32_e32 v111, v106, v114
	v_min_f32_e32 v110, 0, v111
	v_mul_f32_e64 v111, |v111|, s46
	v_exp_f32_e32 v111, v111
	s_nop 0
	v_add_f32_e32 v113, 1.0, v111
	v_add_f32_e32 v115, -1.0, v113
	v_sub_f32_e32 v118, v115, v113
	v_add_f32_e32 v118, 1.0, v118
	v_sub_f32_e32 v115, v111, v115
	v_add_f32_e32 v115, v115, v118
	v_frexp_mant_f32_e32 v118, v113
	v_cmp_gt_f32_e32 vcc, s47, v118
	v_cvt_f64_f32_e32 v[118:119], v113
	v_frexp_exp_i32_f64_e32 v118, v[118:119]
	v_subbrev_co_u32_e32 v118, vcc, 0, v118, vcc
	v_sub_u32_e32 v119, 0, v118
	v_ldexp_f32 v113, v113, v119
	v_ldexp_f32 v115, v115, v119
	v_add_f32_e32 v119, -1.0, v113
	v_add_f32_e32 v120, 1.0, v119
	v_sub_f32_e32 v120, v113, v120
	v_add_f32_e32 v120, v115, v120
	v_add_f32_e32 v121, v119, v120
	v_sub_f32_e32 v119, v121, v119
	v_sub_f32_e32 v119, v120, v119
	v_add_f32_e32 v120, 1.0, v113
	v_add_f32_e32 v122, -1.0, v120
	v_sub_f32_e32 v113, v113, v122
	v_add_f32_e32 v113, v115, v113
	v_add_f32_e32 v115, v120, v113
	v_sub_f32_e32 v120, v115, v120
	v_sub_f32_e32 v113, v113, v120
	v_rcp_f32_e32 v120, v115
	v_cvt_f32_i32_e32 v118, v118
	v_cmp_neq_f32_e32 vcc, s49, v111
	v_mul_f32_e32 v122, v121, v120
	v_mul_f32_e32 v123, v115, v122
	v_fma_f32 v124, v122, v115, -v123
	v_fmac_f32_e32 v124, v122, v113
	v_add_f32_e32 v125, v123, v124
	v_sub_f32_e32 v126, v121, v125
	v_sub_f32_e32 v121, v121, v126
	v_sub_f32_e32 v123, v125, v123
	v_sub_f32_e32 v121, v121, v125
	v_add_f32_e32 v119, v119, v121
	v_sub_f32_e32 v121, v123, v124
	v_add_f32_e32 v119, v121, v119
	v_add_f32_e32 v121, v126, v119
	v_mul_f32_e32 v123, v120, v121
	v_mul_f32_e32 v124, v115, v123
	v_fma_f32 v115, v123, v115, -v124
; DI float sigmoidf_(float x) { return 1.f / (1.f + __expf(-x)); }
; template <bool SWAP> DI void inproj_tile(const Params& p, int layer, int tm, int tn, bf16_t* smem) {
;     ...
;         if (quad < 2) {
; #pragma unroll
;           for (int r = 0; r < 4; ++r) gt[16 + quad * 4 + r] = sigmoidf_(acc[i][1][r] * rs);
;         } else {
;     ...
;           for (int r = 0; r < 4; ++r) { const int h = (quad - 2) * 4 + r; const float xx = acc[i][1][r] * rs + p.b_forget[layer * 8 + h]; lf[h] = fminf(xx, 0.f) - log1pf(__expf(-fabsf(xx))); }
	v_fmac_f32_e32 v115, v123, v113
	v_sub_f32_e32 v113, v126, v121
	v_add_f32_e32 v113, v119, v113
	v_add_f32_e32 v119, v124, v115
	v_sub_f32_e32 v125, v121, v119
	v_sub_f32_e32 v121, v121, v125
	v_sub_f32_e32 v124, v119, v124
	v_sub_f32_e32 v119, v121, v119
	v_add_f32_e32 v113, v113, v119
	v_sub_f32_e32 v115, v124, v115
	v_add_f32_e32 v113, v115, v113
	v_add_f32_e32 v115, v122, v123
	v_add_f32_e32 v113, v125, v113
	v_sub_f32_e32 v119, v115, v122
	v_mul_f32_e32 v113, v120, v113
	v_sub_f32_e32 v119, v123, v119
	v_add_f32_e32 v113, v119, v113
	v_mul_f32_e32 v122, 0x3f317218, v118
	v_add_f32_e32 v119, v115, v113
	v_fma_f32 v123, v118, s48, -v122
	v_mul_f32_e32 v120, v119, v119
	v_fmac_f32_e32 v123, 0xb102e308, v118
	v_sub_f32_e32 v115, v119, v115
	v_fmamk_f32 v121, v120, 0x3e9b6dac, v171
	v_sub_f32_e32 v113, v113, v115
	v_add_f32_e32 v115, v122, v123
	v_fmaak_f32 v121, v120, v121, 0x3f2aaada
	v_sub_f32_e32 v118, v115, v122
	v_ldexp_f32 v122, v119, 1
	v_mul_f32_e32 v119, v119, v120
	v_mul_f32_e32 v119, v119, v121
	v_add_f32_e32 v120, v122, v119
	v_sub_f32_e32 v121, v120, v122
	v_ldexp_f32 v113, v113, 1
	v_sub_f32_e32 v119, v119, v121
	v_add_f32_e32 v113, v113, v119
	v_add_f32_e32 v119, v120, v113
	v_sub_f32_e32 v120, v119, v120
	v_sub_f32_e32 v113, v113, v120
	v_add_f32_e32 v120, v115, v119
	v_sub_f32_e32 v121, v120, v115
	v_sub_f32_e32 v122, v120, v121
	v_sub_f32_e32 v118, v123, v118
	v_sub_f32_e32 v115, v115, v122
	v_sub_f32_e32 v119, v119, v121
	v_add_f32_e32 v115, v119, v115
	v_add_f32_e32 v119, v118, v113
	v_sub_f32_e32 v121, v119, v118
	v_sub_f32_e32 v122, v119, v121
	v_sub_f32_e32 v118, v118, v122
	v_sub_f32_e32 v113, v113, v121
	v_add_f32_e32 v115, v119, v115
	v_add_f32_e32 v113, v113, v118
	v_add_f32_e32 v118, v120, v115
	v_sub_f32_e32 v119, v118, v120
	v_sub_f32_e32 v115, v115, v119
	v_add_f32_e32 v113, v113, v115
	v_add_f32_e32 v113, v118, v113
	v_cndmask_b32_e32 v113, v178, v113, vcc
	v_cmp_ngt_f32_e32 vcc, -1.0, v111
	s_nop 1
	v_cndmask_b32_e32 v113, v179, v113, vcc
	v_cmp_neq_f32_e32 vcc, -1.0, v111
	s_nop 1
	v_cndmask_b32_e32 v113, v180, v113, vcc
	v_cmp_lt_f32_e64 vcc, |v111|, s50
	s_nop 1
	v_cndmask_b32_e32 v111, v113, v111, vcc
	v_sub_f32_e32 v110, v110, v111
	global_store_dword v[108:109], v110, off offset:-24
	global_load_dword v111, v160, s[60:61] offset:12
	s_waitcnt vmcnt(0)
	v_fmac_f32_e32 v111, v107, v114
	v_min_f32_e32 v110, 0, v111
	v_mul_f32_e64 v111, |v111|, s46
	v_exp_f32_e32 v111, v111
	s_nop 0
	v_add_f32_e32 v113, 1.0, v111
	v_add_f32_e32 v115, -1.0, v113
	v_sub_f32_e32 v118, v115, v113
	v_add_f32_e32 v118, 1.0, v118
	v_sub_f32_e32 v115, v111, v115
	v_add_f32_e32 v115, v115, v118
	v_frexp_mant_f32_e32 v118, v113
	v_cmp_gt_f32_e32 vcc, s47, v118
	v_cvt_f64_f32_e32 v[118:119], v113
	v_frexp_exp_i32_f64_e32 v118, v[118:119]
	v_subbrev_co_u32_e32 v118, vcc, 0, v118, vcc
	v_sub_u32_e32 v119, 0, v118
	v_ldexp_f32 v113, v113, v119
	v_ldexp_f32 v115, v115, v119
	v_add_f32_e32 v119, -1.0, v113
	v_add_f32_e32 v120, 1.0, v119
	v_sub_f32_e32 v120, v113, v120
	v_add_f32_e32 v120, v115, v120
	v_add_f32_e32 v121, v119, v120
	v_sub_f32_e32 v119, v121, v119
	v_sub_f32_e32 v119, v120, v119
	v_add_f32_e32 v120, 1.0, v113
	v_add_f32_e32 v122, -1.0, v120
	v_sub_f32_e32 v113, v113, v122
	v_add_f32_e32 v113, v115, v113
	v_add_f32_e32 v115, v120, v113
	v_sub_f32_e32 v120, v115, v120
	v_sub_f32_e32 v113, v113, v120
	v_rcp_f32_e32 v120, v115
	v_cvt_f32_i32_e32 v118, v118
	v_cmp_neq_f32_e32 vcc, s49, v111
	v_mul_f32_e32 v122, v121, v120
	v_mul_f32_e32 v123, v115, v122
	v_fma_f32 v124, v122, v115, -v123
	v_fmac_f32_e32 v124, v122, v113
	v_add_f32_e32 v125, v123, v124
	v_sub_f32_e32 v126, v121, v125
	v_sub_f32_e32 v121, v121, v126
	v_sub_f32_e32 v123, v125, v123
	v_sub_f32_e32 v121, v121, v125
	v_add_f32_e32 v119, v119, v121
	v_sub_f32_e32 v121, v123, v124
	v_add_f32_e32 v119, v121, v119
	v_add_f32_e32 v121, v126, v119
	v_mul_f32_e32 v123, v120, v121
	v_mul_f32_e32 v124, v115, v123
	v_fma_f32 v115, v123, v115, -v124
	v_fmac_f32_e32 v115, v123, v113
	v_sub_f32_e32 v113, v126, v121
	v_add_f32_e32 v113, v119, v113
	v_add_f32_e32 v119, v124, v115
	v_sub_f32_e32 v125, v121, v119
	v_sub_f32_e32 v121, v121, v125
	v_sub_f32_e32 v124, v119, v124
	v_sub_f32_e32 v119, v121, v119
	v_add_f32_e32 v113, v113, v119
	v_sub_f32_e32 v115, v124, v115
	v_add_f32_e32 v113, v115, v113
	v_add_f32_e32 v115, v122, v123
	v_add_f32_e32 v113, v125, v113
	v_sub_f32_e32 v119, v115, v122
	v_mul_f32_e32 v113, v120, v113
	v_sub_f32_e32 v119, v123, v119
	v_add_f32_e32 v113, v119, v113
	v_mul_f32_e32 v122, 0x3f317218, v118
	v_add_f32_e32 v119, v115, v113
	v_fma_f32 v123, v118, s48, -v122
	v_mul_f32_e32 v120, v119, v119
	v_fmac_f32_e32 v123, 0xb102e308, v118
	v_sub_f32_e32 v115, v119, v115
	v_fmamk_f32 v121, v120, 0x3e9b6dac, v171
	v_sub_f32_e32 v113, v113, v115
	v_add_f32_e32 v115, v122, v123
	v_fmaak_f32 v121, v120, v121, 0x3f2aaada
	v_sub_f32_e32 v118, v115, v122
	v_ldexp_f32 v122, v119, 1
	v_mul_f32_e32 v119, v119, v120
	v_mul_f32_e32 v119, v119, v121
	v_add_f32_e32 v120, v122, v119
	v_sub_f32_e32 v121, v120, v122
	v_ldexp_f32 v113, v113, 1
	v_sub_f32_e32 v119, v119, v121
	v_add_f32_e32 v113, v113, v119
	v_add_f32_e32 v119, v120, v113
	v_sub_f32_e32 v120, v119, v120
	v_sub_f32_e32 v113, v113, v120
	v_add_f32_e32 v120, v115, v119
	v_sub_f32_e32 v121, v120, v115
	v_sub_f32_e32 v122, v120, v121
	v_sub_f32_e32 v118, v123, v118
	v_sub_f32_e32 v115, v115, v122
	v_sub_f32_e32 v119, v119, v121
	v_add_f32_e32 v115, v119, v115
	v_add_f32_e32 v119, v118, v113
	v_sub_f32_e32 v121, v119, v118
	v_sub_f32_e32 v122, v119, v121
	v_sub_f32_e32 v118, v118, v122
	v_sub_f32_e32 v113, v113, v121
	v_add_f32_e32 v115, v119, v115
	v_add_f32_e32 v113, v113, v118
	v_add_f32_e32 v118, v120, v115
	v_sub_f32_e32 v119, v118, v120
	v_sub_f32_e32 v115, v115, v119
	v_add_f32_e32 v113, v113, v115
	v_add_f32_e32 v113, v118, v113
	v_cndmask_b32_e32 v113, v178, v113, vcc
	v_cmp_ngt_f32_e32 vcc, -1.0, v111
	s_nop 1
	v_cndmask_b32_e32 v113, v179, v113, vcc
	v_cmp_neq_f32_e32 vcc, -1.0, v111
	s_nop 1
	v_cndmask_b32_e32 v113, v180, v113, vcc
	v_cmp_lt_f32_e64 vcc, |v111|, s50
	s_nop 1
	v_cndmask_b32_e32 v111, v113, v111, vcc
	v_sub_f32_e32 v110, v110, v111
	global_store_dword v[108:109], v110, off offset:-20
.LBB0_1301:
	s_andn2_saveexec_b64 s[2:3], s[2:3]
	s_cbranch_execz .LBB0_1303
	v_mul_f32_e32 v104, v104, v114
	v_mul_f32_e32 v105, v105, v114
	v_mul_f32_e32 v104, 0xbfb8aa3b, v104
	v_mul_f32_e32 v105, 0xbfb8aa3b, v105
	v_exp_f32_e32 v104, v104
	v_exp_f32_e32 v105, v105
	v_mul_f32_e32 v106, v106, v114
	v_mul_f32_e32 v107, v107, v114
	v_mul_f32_e32 v106, 0xbfb8aa3b, v106
	v_pk_add_f32 v[104:105], v[104:105], 1.0 op_sel_hi:[1,0]
	v_mul_f32_e32 v107, 0xbfb8aa3b, v107
	v_exp_f32_e32 v106, v106
	v_exp_f32_e32 v107, v107
	v_rcp_f32_e32 v105, v105
	v_pk_add_f32 v[106:107], v[106:107], 1.0 op_sel_hi:[1,0]
	v_rcp_f32_e32 v104, v104
	s_nop 0
	v_rcp_f32_e32 v107, v107
	s_nop 0
	v_rcp_f32_e32 v106, v106
	global_store_dwordx4 v[118:119], v[104:107], off offset:64

; DI float sigmoidf_(float x) { return 1.f / (1.f + __expf(-x)); }
; template <bool SWAP> DI void inproj_tile(const Params& p, int layer, int tm, int tn, bf16_t* smem) {
;     ...
;       for (int i = 0; i < 8; ++i) {
;         const int t = trow0 + i * 16 + l15; const float rs = rstd_from16(ssq + (size_t)t * 16, 1.f / 1024.f);
;         float* gt = (float*)(p.ws + O_GATES) + (size_t)t * 24; float* lf = (float*)(p.ws + O_LOGF) + (size_t)t * 8;
; #pragma unroll
;         for (int r = 0; r < 4; ++r) gt[quad * 4 + r] = sigmoidf_(acc[i][0][r] * rs);
;         if (quad < 2) {
; #pragma unroll
;           for (int r = 0; r < 4; ++r) gt[16 + quad * 4 + r] = sigmoidf_(acc[i][1][r] * rs);
;         } else {
; #pragma unroll
;           for (int r = 0; r < 4; ++r) { const int h = (quad - 2) * 4 + r; const float xx = acc[i][1][r] * rs + p.b_forget[layer * 8 + h]; lf[h] = fminf(xx, 0.f) - log1pf(__expf(-fabsf(xx))); }
;         }
.LrcA1_10:
	s_or_b64 exec, exec, s[98:99]
	s_waitcnt vmcnt(0)
	v_cndmask_b32_e64 v96, v249, v96, s[100:101]
	v_readlane_b32 s2, v240, 35
	v_readlane_b32 s3, v240, 36
	s_nop 1
	v_mov_b64_e32 v[98:99], s[2:3]
	v_mad_i64_i32 v[100:101], s[2:3], v110, s45, v[98:99]
	v_lshlrev_b64 v[98:99], 5, v[110:111]
	v_lshl_add_u64 v[100:101], v[100:101], 0, v[160:161]
	v_mul_f32_e32 v92, v92, v96
	v_mul_f32_e32 v93, v93, v96
	v_mul_f32_e32 v92, 0xbfb8aa3b, v92
	v_mul_f32_e32 v93, 0xbfb8aa3b, v93
	v_exp_f32_e32 v92, v92
	v_exp_f32_e32 v93, v93
	v_mul_f32_e32 v94, v94, v96
	v_mul_f32_e32 v95, v95, v96
	v_mul_f32_e32 v94, 0xbfb8aa3b, v94
	v_pk_add_f32 v[92:93], v[92:93], 1.0 op_sel_hi:[1,0]
	v_mul_f32_e32 v95, 0xbfb8aa3b, v95
	v_exp_f32_e32 v94, v94
	v_exp_f32_e32 v95, v95
	v_rcp_f32_e32 v93, v93
	v_pk_add_f32 v[94:95], v[94:95], 1.0 op_sel_hi:[1,0]
	v_rcp_f32_e32 v92, v92
	s_nop 0
	v_rcp_f32_e32 v95, v95
	s_nop 0
	v_rcp_f32_e32 v94, v94
	global_store_dwordx4 v[100:101], v[92:95], off
	s_and_saveexec_b64 s[2:3], s[4:5]
	s_xor_b64 s[2:3], exec, s[2:3]
	s_cbranch_execz .LBB0_1305
	v_readlane_b32 s52, v241, 8
	v_readlane_b32 s60, v241, 16
	v_readlane_b32 s61, v241, 17
	v_lshl_add_u64 v[92:93], s[8:9], 0, v[98:99]
	v_lshl_add_u64 v[92:93], v[92:93], 0, v[160:161]
	v_readlane_b32 s53, v241, 9
	v_readlane_b32 s54, v241, 10
	v_readlane_b32 s55, v241, 11
	global_load_dword v94, v160, s[60:61]
	v_readlane_b32 s56, v241, 12
	v_readlane_b32 s57, v241, 13
	v_readlane_b32 s58, v241, 14
	v_readlane_b32 s59, v241, 15
	v_readlane_b32 s62, v241, 18
	v_readlane_b32 s63, v241, 19
	v_readlane_b32 s64, v241, 20
	v_readlane_b32 s65, v241, 21
	v_readlane_b32 s66, v241, 22
	v_readlane_b32 s67, v241, 23
	s_waitcnt vmcnt(0)
	v_fmac_f32_e32 v94, v88, v96
	v_min_f32_e32 v97, 0, v94
	v_mul_f32_e64 v94, |v94|, s46
	v_exp_f32_e32 v100, v94
	s_nop 0
	v_add_f32_e32 v101, 1.0, v100
	v_add_f32_e32 v94, -1.0, v101
	v_sub_f32_e32 v95, v94, v101
	v_add_f32_e32 v95, 1.0, v95
	v_sub_f32_e32 v94, v100, v94
	v_add_f32_e32 v102, v94, v95
	v_frexp_mant_f32_e32 v94, v101
	v_cmp_gt_f32_e32 vcc, s47, v94
	v_cvt_f64_f32_e32 v[94:95], v101
	v_frexp_exp_i32_f64_e32 v94, v[94:95]
	v_subbrev_co_u32_e32 v94, vcc, 0, v94, vcc
	v_sub_u32_e32 v95, 0, v94
	v_ldexp_f32 v101, v101, v95
	v_ldexp_f32 v95, v102, v95
	v_add_f32_e32 v102, -1.0, v101
	v_add_f32_e32 v103, 1.0, v102
	v_sub_f32_e32 v103, v101, v103
	v_add_f32_e32 v103, v95, v103
	v_add_f32_e32 v105, v102, v103
	v_sub_f32_e32 v102, v105, v102
	v_sub_f32_e32 v102, v103, v102
	v_add_f32_e32 v103, 1.0, v101
	v_add_f32_e32 v106, -1.0, v103
	v_sub_f32_e32 v101, v101, v106
	v_add_f32_e32 v95, v95, v101
	v_add_f32_e32 v101, v103, v95
	v_sub_f32_e32 v103, v101, v103
	v_sub_f32_e32 v95, v95, v103
	v_rcp_f32_e32 v103, v101
	v_cvt_f32_i32_e32 v94, v94
	v_cmp_neq_f32_e32 vcc, s49, v100
	v_mul_f32_e32 v106, v105, v103
	v_mul_f32_e32 v107, v101, v106
	v_fma_f32 v108, v106, v101, -v107
	v_fmac_f32_e32 v108, v106, v95
	v_add_f32_e32 v109, v107, v108
	v_sub_f32_e32 v110, v105, v109
	v_sub_f32_e32 v105, v105, v110
	v_sub_f32_e32 v107, v109, v107
	v_sub_f32_e32 v105, v105, v109
	v_add_f32_e32 v102, v102, v105
	v_sub_f32_e32 v105, v107, v108
	v_add_f32_e32 v102, v105, v102
	v_add_f32_e32 v105, v110, v102
	v_mul_f32_e32 v107, v103, v105
	v_mul_f32_e32 v108, v101, v107
	v_fma_f32 v101, v107, v101, -v108
	v_fmac_f32_e32 v101, v107, v95
	v_sub_f32_e32 v95, v110, v105
	v_add_f32_e32 v95, v102, v95
	v_add_f32_e32 v102, v108, v101
	v_sub_f32_e32 v109, v105, v102
	v_sub_f32_e32 v105, v105, v109
	v_sub_f32_e32 v108, v102, v108
	v_sub_f32_e32 v102, v105, v102
	v_add_f32_e32 v95, v95, v102
	v_sub_f32_e32 v101, v108, v101
	v_add_f32_e32 v95, v101, v95
	v_add_f32_e32 v101, v106, v107
	v_add_f32_e32 v95, v109, v95
	v_sub_f32_e32 v102, v101, v106
	v_mul_f32_e32 v95, v103, v95
	v_sub_f32_e32 v102, v107, v102
	v_add_f32_e32 v95, v102, v95
	v_mul_f32_e32 v106, 0x3f317218, v94
	v_add_f32_e32 v102, v101, v95
	v_fma_f32 v107, v94, s48, -v106
	v_mul_f32_e32 v103, v102, v102
	v_fmac_f32_e32 v107, 0xb102e308, v94
	v_sub_f32_e32 v94, v102, v101
	v_fmamk_f32 v105, v103, 0x3e9b6dac, v171
	v_sub_f32_e32 v94, v95, v94
	v_add_f32_e32 v95, v106, v107
	v_fmaak_f32 v105, v103, v105, 0x3f2aaada
	v_sub_f32_e32 v101, v95, v106
	v_ldexp_f32 v106, v102, 1
	v_mul_f32_e32 v102, v102, v103
	v_mul_f32_e32 v102, v102, v105
	v_add_f32_e32 v103, v106, v102
	v_sub_f32_e32 v105, v103, v106
	v_ldexp_f32 v94, v94, 1
	v_sub_f32_e32 v102, v102, v105
	v_add_f32_e32 v94, v94, v102
	v_add_f32_e32 v102, v103, v94
	v_sub_f32_e32 v103, v102, v103
	v_sub_f32_e32 v94, v94, v103
	v_add_f32_e32 v103, v95, v102
	v_sub_f32_e32 v105, v103, v95
	v_sub_f32_e32 v106, v103, v105
	v_sub_f32_e32 v101, v107, v101
	v_sub_f32_e32 v95, v95, v106
	v_sub_f32_e32 v102, v102, v105
	v_add_f32_e32 v95, v102, v95
	v_add_f32_e32 v102, v101, v94
	v_sub_f32_e32 v105, v102, v101
	v_sub_f32_e32 v106, v102, v105
	v_sub_f32_e32 v101, v101, v106
	v_sub_f32_e32 v94, v94, v105
	v_add_f32_e32 v95, v102, v95
	v_add_f32_e32 v94, v94, v101
	v_add_f32_e32 v101, v103, v95
	v_sub_f32_e32 v102, v101, v103
	v_sub_f32_e32 v95, v95, v102
	v_add_f32_e32 v94, v94, v95
	v_add_f32_e32 v94, v101, v94
	v_cndmask_b32_e32 v94, v178, v94, vcc
	v_cmp_ngt_f32_e32 vcc, -1.0, v100
	s_nop 1
	v_cndmask_b32_e32 v94, v179, v94, vcc
	v_cmp_neq_f32_e32 vcc, -1.0, v100
	s_nop 1
	v_cndmask_b32_e32 v94, v180, v94, vcc
	v_cmp_lt_f32_e64 vcc, |v100|, s50
	s_nop 1
	v_cndmask_b32_e32 v94, v94, v100, vcc
	v_sub_f32_e32 v94, v97, v94
	global_store_dword v[92:93], v94, off offset:-32
	global_load_dword v95, v160, s[60:61] offset:4
	s_waitcnt vmcnt(0)
; template <bool SWAP> DI void inproj_tile(const Params& p, int layer, int tm, int tn, bf16_t* smem) {
;     ...
;           for (int r = 0; r < 4; ++r) { const int h = (quad - 2) * 4 + r; const float xx = acc[i][1][r] * rs + p.b_forget[layer * 8 + h]; lf[h] = fminf(xx, 0.f) - log1pf(__expf(-fabsf(xx))); }
	v_fmac_f32_e32 v95, v89, v96
	v_min_f32_e32 v94, 0, v95
	v_mul_f32_e64 v95, |v95|, s46
	v_exp_f32_e32 v95, v95
	s_nop 0
	v_add_f32_e32 v97, 1.0, v95
	v_add_f32_e32 v100, -1.0, v97
	v_sub_f32_e32 v101, v100, v97
	v_add_f32_e32 v101, 1.0, v101
	v_sub_f32_e32 v100, v95, v100
	v_add_f32_e32 v102, v100, v101
	v_frexp_mant_f32_e32 v100, v97
	v_cmp_gt_f32_e32 vcc, s47, v100
	v_cvt_f64_f32_e32 v[100:101], v97
	v_frexp_exp_i32_f64_e32 v100, v[100:101]
	v_subbrev_co_u32_e32 v100, vcc, 0, v100, vcc
	v_sub_u32_e32 v101, 0, v100
	v_ldexp_f32 v97, v97, v101
	v_ldexp_f32 v101, v102, v101
	v_add_f32_e32 v102, -1.0, v97
	v_add_f32_e32 v103, 1.0, v102
	v_sub_f32_e32 v103, v97, v103
	v_add_f32_e32 v103, v101, v103
	v_add_f32_e32 v105, v102, v103
	v_sub_f32_e32 v102, v105, v102
	v_sub_f32_e32 v102, v103, v102
	v_add_f32_e32 v103, 1.0, v97
	v_add_f32_e32 v106, -1.0, v103
	v_sub_f32_e32 v97, v97, v106
	v_add_f32_e32 v97, v101, v97
	v_add_f32_e32 v101, v103, v97
	v_sub_f32_e32 v103, v101, v103
	v_sub_f32_e32 v97, v97, v103
	v_rcp_f32_e32 v103, v101
	v_cvt_f32_i32_e32 v100, v100
	v_cmp_neq_f32_e32 vcc, s49, v95
	v_mul_f32_e32 v106, v105, v103
	v_mul_f32_e32 v107, v101, v106
	v_fma_f32 v108, v106, v101, -v107
	v_fmac_f32_e32 v108, v106, v97
	v_add_f32_e32 v109, v107, v108
	v_sub_f32_e32 v110, v105, v109
	v_sub_f32_e32 v105, v105, v110
	v_sub_f32_e32 v107, v109, v107
	v_sub_f32_e32 v105, v105, v109
	v_add_f32_e32 v102, v102, v105
	v_sub_f32_e32 v105, v107, v108
	v_add_f32_e32 v102, v105, v102
	v_add_f32_e32 v105, v110, v102
	v_mul_f32_e32 v107, v103, v105
	v_mul_f32_e32 v108, v101, v107
	v_fma_f32 v101, v107, v101, -v108
	v_fmac_f32_e32 v101, v107, v97
	v_sub_f32_e32 v97, v110, v105
	v_add_f32_e32 v97, v102, v97
	v_add_f32_e32 v102, v108, v101
	v_sub_f32_e32 v109, v105, v102
	v_sub_f32_e32 v105, v105, v109
	v_sub_f32_e32 v108, v102, v108
	v_sub_f32_e32 v102, v105, v102
	v_add_f32_e32 v97, v97, v102
	v_sub_f32_e32 v101, v108, v101
	v_add_f32_e32 v97, v101, v97
	v_add_f32_e32 v101, v106, v107
	v_add_f32_e32 v97, v109, v97
	v_sub_f32_e32 v102, v101, v106
	v_mul_f32_e32 v97, v103, v97
	v_sub_f32_e32 v102, v107, v102
	v_add_f32_e32 v97, v102, v97
	v_mul_f32_e32 v106, 0x3f317218, v100
	v_add_f32_e32 v102, v101, v97
	v_fma_f32 v107, v100, s48, -v106
	v_mul_f32_e32 v103, v102, v102
	v_fmac_f32_e32 v107, 0xb102e308, v100
	v_sub_f32_e32 v100, v102, v101
	v_fmamk_f32 v105, v103, 0x3e9b6dac, v171
	v_sub_f32_e32 v97, v97, v100
	v_add_f32_e32 v100, v106, v107
	v_fmaak_f32 v105, v103, v105, 0x3f2aaada
	v_sub_f32_e32 v101, v100, v106
	v_ldexp_f32 v106, v102, 1
	v_mul_f32_e32 v102, v102, v103
	v_mul_f32_e32 v102, v102, v105
	v_add_f32_e32 v103, v106, v102
	v_sub_f32_e32 v105, v103, v106
	v_ldexp_f32 v97, v97, 1
	v_sub_f32_e32 v102, v102, v105
	v_add_f32_e32 v97, v97, v102
	v_add_f32_e32 v102, v103, v97
	v_sub_f32_e32 v103, v102, v103
	v_sub_f32_e32 v97, v97, v103
	v_add_f32_e32 v103, v100, v102
	v_sub_f32_e32 v105, v103, v100
	v_sub_f32_e32 v106, v103, v105
	v_sub_f32_e32 v101, v107, v101
	v_sub_f32_e32 v100, v100, v106
	v_sub_f32_e32 v102, v102, v105
	v_add_f32_e32 v100, v102, v100
	v_add_f32_e32 v102, v101, v97
	v_sub_f32_e32 v105, v102, v101
	v_sub_f32_e32 v106, v102, v105
	v_sub_f32_e32 v101, v101, v106
	v_sub_f32_e32 v97, v97, v105
	v_add_f32_e32 v100, v102, v100
	v_add_f32_e32 v97, v97, v101
	v_add_f32_e32 v101, v103, v100
	v_sub_f32_e32 v102, v101, v103
	v_sub_f32_e32 v100, v100, v102
	v_add_f32_e32 v97, v97, v100
	v_add_f32_e32 v97, v101, v97
	v_cndmask_b32_e32 v97, v178, v97, vcc
	v_cmp_ngt_f32_e32 vcc, -1.0, v95
	s_nop 1
	v_cndmask_b32_e32 v97, v179, v97, vcc
	v_cmp_neq_f32_e32 vcc, -1.0, v95
	s_nop 1
	v_cndmask_b32_e32 v97, v180, v97, vcc
	v_cmp_lt_f32_e64 vcc, |v95|, s50
	s_nop 1
	v_cndmask_b32_e32 v95, v97, v95, vcc
	v_sub_f32_e32 v94, v94, v95
	global_store_dword v[92:93], v94, off offset:-28
	global_load_dword v95, v160, s[60:61] offset:8
	s_waitcnt vmcnt(0)
	v_fmac_f32_e32 v95, v90, v96
	v_min_f32_e32 v94, 0, v95
	v_mul_f32_e64 v95, |v95|, s46
	v_exp_f32_e32 v95, v95
	s_nop 0
	v_add_f32_e32 v97, 1.0, v95
	v_add_f32_e32 v100, -1.0, v97
	v_sub_f32_e32 v101, v100, v97
	v_add_f32_e32 v101, 1.0, v101
	v_sub_f32_e32 v100, v95, v100
	v_add_f32_e32 v102, v100, v101
	v_frexp_mant_f32_e32 v100, v97
	v_cmp_gt_f32_e32 vcc, s47, v100
	v_cvt_f64_f32_e32 v[100:101], v97
	v_frexp_exp_i32_f64_e32 v100, v[100:101]
	v_subbrev_co_u32_e32 v100, vcc, 0, v100, vcc
	v_sub_u32_e32 v101, 0, v100
	v_ldexp_f32 v97, v97, v101
	v_ldexp_f32 v101, v102, v101
	v_add_f32_e32 v102, -1.0, v97
	v_add_f32_e32 v103, 1.0, v102
	v_sub_f32_e32 v103, v97, v103
	v_add_f32_e32 v103, v101, v103
	v_add_f32_e32 v105, v102, v103
	v_sub_f32_e32 v102, v105, v102
	v_sub_f32_e32 v102, v103, v102
	v_add_f32_e32 v103, 1.0, v97
	v_add_f32_e32 v106, -1.0, v103
	v_sub_f32_e32 v97, v97, v106
	v_add_f32_e32 v97, v101, v97
	v_add_f32_e32 v101, v103, v97
	v_sub_f32_e32 v103, v101, v103
	v_sub_f32_e32 v97, v97, v103
	v_rcp_f32_e32 v103, v101
	v_cvt_f32_i32_e32 v100, v100
	v_cmp_neq_f32_e32 vcc, s49, v95
	v_mul_f32_e32 v106, v105, v103
	v_mul_f32_e32 v107, v101, v106
	v_fma_f32 v108, v106, v101, -v107
	v_fmac_f32_e32 v108, v106, v97
	v_add_f32_e32 v109, v107, v108
	v_sub_f32_e32 v110, v105, v109
	v_sub_f32_e32 v105, v105, v110
	v_sub_f32_e32 v107, v109, v107
	v_sub_f32_e32 v105, v105, v109
	v_add_f32_e32 v102, v102, v105
	v_sub_f32_e32 v105, v107, v108
	v_add_f32_e32 v102, v105, v102
	v_add_f32_e32 v105, v110, v102
	v_mul_f32_e32 v107, v103, v105
	v_mul_f32_e32 v108, v101, v107
	v_fma_f32 v101, v107, v101, -v108
	v_fmac_f32_e32 v101, v107, v97
	v_sub_f32_e32 v97, v110, v105
	v_add_f32_e32 v97, v102, v97
	v_add_f32_e32 v102, v108, v101
; DI float sigmoidf_(float x) { return 1.f / (1.f + __expf(-x)); }
; template <bool SWAP> DI void inproj_tile(const Params& p, int layer, int tm, int tn, bf16_t* smem) {
;     ...
;       for (int i = 0; i < 8; ++i) {
;         const int t = trow0 + i * 16 + l15; const float rs = rstd_from16(ssq + (size_t)t * 16, 1.f / 1024.f);
;         float* gt = (float*)(p.ws + O_GATES) + (size_t)t * 24; float* lf = (float*)(p.ws + O_LOGF) + (size_t)t * 8;
; #pragma unroll
;         for (int r = 0; r < 4; ++r) gt[quad * 4 + r] = sigmoidf_(acc[i][0][r] * rs);
;         if (quad < 2) {
; #pragma unroll
;           for (int r = 0; r < 4; ++r) gt[16 + quad * 4 + r] = sigmoidf_(acc[i][1][r] * rs);
;         } else {
; #pragma unroll
;           for (int r = 0; r < 4; ++r) { const int h = (quad - 2) * 4 + r; const float xx = acc[i][1][r] * rs + p.b_forget[layer * 8 + h]; lf[h] = fminf(xx, 0.f) - log1pf(__expf(-fabsf(xx))); }
;         }
	v_sub_f32_e32 v109, v105, v102
	v_sub_f32_e32 v105, v105, v109
	v_sub_f32_e32 v108, v102, v108
	v_sub_f32_e32 v102, v105, v102
	v_add_f32_e32 v97, v97, v102
	v_sub_f32_e32 v101, v108, v101
	v_add_f32_e32 v97, v101, v97
	v_add_f32_e32 v101, v106, v107
	v_add_f32_e32 v97, v109, v97
	v_sub_f32_e32 v102, v101, v106
	v_mul_f32_e32 v97, v103, v97
	v_sub_f32_e32 v102, v107, v102
	v_add_f32_e32 v97, v102, v97
	v_mul_f32_e32 v106, 0x3f317218, v100
	v_add_f32_e32 v102, v101, v97
	v_fma_f32 v107, v100, s48, -v106
	v_mul_f32_e32 v103, v102, v102
	v_fmac_f32_e32 v107, 0xb102e308, v100
	v_sub_f32_e32 v100, v102, v101
	v_fmamk_f32 v105, v103, 0x3e9b6dac, v171
	v_sub_f32_e32 v97, v97, v100
	v_add_f32_e32 v100, v106, v107
	v_fmaak_f32 v105, v103, v105, 0x3f2aaada
	v_sub_f32_e32 v101, v100, v106
	v_ldexp_f32 v106, v102, 1
	v_mul_f32_e32 v102, v102, v103
	v_mul_f32_e32 v102, v102, v105
	v_add_f32_e32 v103, v106, v102
	v_sub_f32_e32 v105, v103, v106
	v_ldexp_f32 v97, v97, 1
	v_sub_f32_e32 v102, v102, v105
	v_add_f32_e32 v97, v97, v102
	v_add_f32_e32 v102, v103, v97
	v_sub_f32_e32 v103, v102, v103
	v_sub_f32_e32 v97, v97, v103
	v_add_f32_e32 v103, v100, v102
	v_sub_f32_e32 v105, v103, v100
	v_sub_f32_e32 v106, v103, v105
	v_sub_f32_e32 v101, v107, v101
	v_sub_f32_e32 v100, v100, v106
	v_sub_f32_e32 v102, v102, v105
	v_add_f32_e32 v100, v102, v100
	v_add_f32_e32 v102, v101, v97
	v_sub_f32_e32 v105, v102, v101
	v_sub_f32_e32 v106, v102, v105
	v_sub_f32_e32 v101, v101, v106
	v_sub_f32_e32 v97, v97, v105
	v_add_f32_e32 v100, v102, v100
	v_add_f32_e32 v97, v97, v101
	v_add_f32_e32 v101, v103, v100
	v_sub_f32_e32 v102, v101, v103
	v_sub_f32_e32 v100, v100, v102
	v_add_f32_e32 v97, v97, v100
	v_add_f32_e32 v97, v101, v97
	v_cndmask_b32_e32 v97, v178, v97, vcc
	v_cmp_ngt_f32_e32 vcc, -1.0, v95
	s_nop 1
	v_cndmask_b32_e32 v97, v179, v97, vcc
	v_cmp_neq_f32_e32 vcc, -1.0, v95
	s_nop 1
	v_cndmask_b32_e32 v97, v180, v97, vcc
	v_cmp_lt_f32_e64 vcc, |v95|, s50
	s_nop 1
	v_cndmask_b32_e32 v95, v97, v95, vcc
	v_sub_f32_e32 v94, v94, v95
	global_store_dword v[92:93], v94, off offset:-24
	global_load_dword v95, v160, s[60:61] offset:12
	s_waitcnt vmcnt(0)
	v_fmac_f32_e32 v95, v91, v96
	v_min_f32_e32 v94, 0, v95
	v_mul_f32_e64 v95, |v95|, s46
	v_exp_f32_e32 v95, v95
	s_nop 0
	v_add_f32_e32 v97, 1.0, v95
	v_add_f32_e32 v100, -1.0, v97
	v_sub_f32_e32 v101, v100, v97
	v_add_f32_e32 v101, 1.0, v101
	v_sub_f32_e32 v100, v95, v100
	v_add_f32_e32 v102, v100, v101
	v_frexp_mant_f32_e32 v100, v97
	v_cmp_gt_f32_e32 vcc, s47, v100
	v_cvt_f64_f32_e32 v[100:101], v97
	v_frexp_exp_i32_f64_e32 v100, v[100:101]
	v_subbrev_co_u32_e32 v100, vcc, 0, v100, vcc
	v_sub_u32_e32 v101, 0, v100
	v_ldexp_f32 v97, v97, v101
	v_ldexp_f32 v101, v102, v101
	v_add_f32_e32 v102, -1.0, v97
	v_add_f32_e32 v103, 1.0, v102
	v_sub_f32_e32 v103, v97, v103
	v_add_f32_e32 v103, v101, v103
	v_add_f32_e32 v105, v102, v103
	v_sub_f32_e32 v102, v105, v102
	v_sub_f32_e32 v102, v103, v102
	v_add_f32_e32 v103, 1.0, v97
	v_add_f32_e32 v106, -1.0, v103
	v_sub_f32_e32 v97, v97, v106
	v_add_f32_e32 v97, v101, v97
	v_add_f32_e32 v101, v103, v97
	v_sub_f32_e32 v103, v101, v103
	v_sub_f32_e32 v97, v97, v103
	v_rcp_f32_e32 v103, v101
	v_cvt_f32_i32_e32 v100, v100
	v_cmp_neq_f32_e32 vcc, s49, v95
	v_mul_f32_e32 v106, v105, v103
	v_mul_f32_e32 v107, v101, v106
	v_fma_f32 v108, v106, v101, -v107
	v_fmac_f32_e32 v108, v106, v97
	v_add_f32_e32 v109, v107, v108
	v_sub_f32_e32 v110, v105, v109
	v_sub_f32_e32 v105, v105, v110
	v_sub_f32_e32 v107, v109, v107
	v_sub_f32_e32 v105, v105, v109
	v_add_f32_e32 v102, v102, v105
	v_sub_f32_e32 v105, v107, v108
	v_add_f32_e32 v102, v105, v102
	v_add_f32_e32 v105, v110, v102
	v_mul_f32_e32 v107, v103, v105
	v_mul_f32_e32 v108, v101, v107
	v_fma_f32 v101, v107, v101, -v108
	v_fmac_f32_e32 v101, v107, v97
	v_sub_f32_e32 v97, v110, v105
	v_add_f32_e32 v97, v102, v97
	v_add_f32_e32 v102, v108, v101
	v_sub_f32_e32 v109, v105, v102
	v_sub_f32_e32 v105, v105, v109
	v_sub_f32_e32 v108, v102, v108
	v_sub_f32_e32 v102, v105, v102
	v_add_f32_e32 v97, v97, v102
	v_sub_f32_e32 v101, v108, v101
	v_add_f32_e32 v97, v101, v97
	v_add_f32_e32 v101, v106, v107
	v_add_f32_e32 v97, v109, v97
	v_sub_f32_e32 v102, v101, v106
	v_mul_f32_e32 v97, v103, v97
	v_sub_f32_e32 v102, v107, v102
	v_add_f32_e32 v97, v102, v97
	v_mul_f32_e32 v106, 0x3f317218, v100
	v_add_f32_e32 v102, v101, v97
	v_fma_f32 v107, v100, s48, -v106
	v_mul_f32_e32 v103, v102, v102
	v_fmac_f32_e32 v107, 0xb102e308, v100
	v_sub_f32_e32 v100, v102, v101
	v_fmamk_f32 v105, v103, 0x3e9b6dac, v171
	v_sub_f32_e32 v97, v97, v100
	v_add_f32_e32 v100, v106, v107
	v_fmaak_f32 v105, v103, v105, 0x3f2aaada
	v_sub_f32_e32 v101, v100, v106
	v_ldexp_f32 v106, v102, 1
	v_mul_f32_e32 v102, v102, v103
	v_mul_f32_e32 v102, v102, v105
	v_add_f32_e32 v103, v106, v102
	v_sub_f32_e32 v105, v103, v106
	v_ldexp_f32 v97, v97, 1
	v_sub_f32_e32 v102, v102, v105
	v_add_f32_e32 v97, v97, v102
	v_add_f32_e32 v102, v103, v97
	v_sub_f32_e32 v103, v102, v103
	v_sub_f32_e32 v97, v97, v103
	v_add_f32_e32 v103, v100, v102
	v_sub_f32_e32 v105, v103, v100
	v_sub_f32_e32 v106, v103, v105
	v_sub_f32_e32 v101, v107, v101
	v_sub_f32_e32 v100, v100, v106
	v_sub_f32_e32 v102, v102, v105
	v_add_f32_e32 v100, v102, v100
	v_add_f32_e32 v102, v101, v97
	v_sub_f32_e32 v105, v102, v101
	v_sub_f32_e32 v106, v102, v105
	v_sub_f32_e32 v101, v101, v106
	v_sub_f32_e32 v97, v97, v105
	v_add_f32_e32 v100, v102, v100
	v_add_f32_e32 v97, v97, v101
	v_add_f32_e32 v101, v103, v100
	v_sub_f32_e32 v102, v101, v103
	v_sub_f32_e32 v100, v100, v102
	v_add_f32_e32 v97, v97, v100
	v_add_f32_e32 v97, v101, v97
	v_cndmask_b32_e32 v97, v178, v97, vcc
	v_cmp_ngt_f32_e32 vcc, -1.0, v95
	s_nop 1
	v_cndmask_b32_e32 v97, v179, v97, vcc
	v_cmp_neq_f32_e32 vcc, -1.0, v95
	s_nop 1
	v_cndmask_b32_e32 v97, v180, v97, vcc
	v_cmp_lt_f32_e64 vcc, |v95|, s50
	s_nop 1
	v_cndmask_b32_e32 v95, v97, v95, vcc
	v_sub_f32_e32 v94, v94, v95
	global_store_dword v[92:93], v94, off offset:-20
.LBB0_1305:
	s_andn2_saveexec_b64 s[2:3], s[2:3]
	s_cbranch_execz .LBB0_1307
	v_mul_f32_e32 v88, v88, v96
	v_mul_f32_e32 v89, v89, v96
	v_mul_f32_e32 v88, 0xbfb8aa3b, v88
	v_mul_f32_e32 v89, 0xbfb8aa3b, v89
	v_exp_f32_e32 v88, v88
	v_exp_f32_e32 v89, v89
	v_mul_f32_e32 v90, v90, v96
	v_mul_f32_e32 v91, v91, v96
	v_mul_f32_e32 v90, 0xbfb8aa3b, v90
	v_pk_add_f32 v[88:89], v[88:89], 1.0 op_sel_hi:[1,0]
	v_mul_f32_e32 v91, 0xbfb8aa3b, v91
	v_exp_f32_e32 v90, v90
	v_exp_f32_e32 v91, v91
	v_rcp_f32_e32 v89, v89
	v_pk_add_f32 v[90:91], v[90:91], 1.0 op_sel_hi:[1,0]
	v_rcp_f32_e32 v88, v88
	s_nop 0
	v_rcp_f32_e32 v91, v91
	s_nop 0
	v_rcp_f32_e32 v90, v90
	global_store_dwordx4 v[100:101], v[88:91], off offset:64

; DI float sigmoidf_(float x) { return 1.f / (1.f + __expf(-x)); }
; template <bool SWAP> DI void inproj_tile(const Params& p, int layer, int tm, int tn, bf16_t* smem) {
;     ...
;       for (int i = 0; i < 8; ++i) {
;         const int t = trow0 + i * 16 + l15; const float rs = rstd_from16(ssq + (size_t)t * 16, 1.f / 1024.f);
;         float* gt = (float*)(p.ws + O_GATES) + (size_t)t * 24; float* lf = (float*)(p.ws + O_LOGF) + (size_t)t * 8;
; #pragma unroll
;         for (int r = 0; r < 4; ++r) gt[quad * 4 + r] = sigmoidf_(acc[i][0][r] * rs);
;         if (quad < 2) {
; #pragma unroll
;           for (int r = 0; r < 4; ++r) gt[16 + quad * 4 + r] = sigmoidf_(acc[i][1][r] * rs);
;         } else {
; #pragma unroll
;           for (int r = 0; r < 4; ++r) { const int h = (quad - 2) * 4 + r; const float xx = acc[i][1][r] * rs + p.b_forget[layer * 8 + h]; lf[h] = fminf(xx, 0.f) - log1pf(__expf(-fabsf(xx))); }
;         }
.LrcA1_11:
	s_or_b64 exec, exec, s[98:99]
	s_waitcnt vmcnt(0)
	v_cndmask_b32_e64 v80, v249, v80, s[100:101]
	v_readlane_b32 s2, v240, 35
	v_readlane_b32 s3, v240, 36
	s_nop 1
	v_mov_b64_e32 v[82:83], s[2:3]
	v_mad_i64_i32 v[84:85], s[2:3], v96, s45, v[82:83]
	v_lshlrev_b64 v[82:83], 5, v[96:97]
	v_lshl_add_u64 v[84:85], v[84:85], 0, v[160:161]
	v_mul_f32_e32 v76, v76, v80
	v_mul_f32_e32 v77, v77, v80
	v_mul_f32_e32 v76, 0xbfb8aa3b, v76
	v_mul_f32_e32 v77, 0xbfb8aa3b, v77
	v_exp_f32_e32 v76, v76
	v_exp_f32_e32 v77, v77
	v_mul_f32_e32 v78, v78, v80
	v_mul_f32_e32 v79, v79, v80
	v_mul_f32_e32 v78, 0xbfb8aa3b, v78
	v_pk_add_f32 v[76:77], v[76:77], 1.0 op_sel_hi:[1,0]
	v_mul_f32_e32 v79, 0xbfb8aa3b, v79
	v_exp_f32_e32 v78, v78
	v_exp_f32_e32 v79, v79
	v_rcp_f32_e32 v77, v77
	v_pk_add_f32 v[78:79], v[78:79], 1.0 op_sel_hi:[1,0]
	v_rcp_f32_e32 v76, v76
	s_nop 0
	v_rcp_f32_e32 v79, v79
	s_nop 0
	v_rcp_f32_e32 v78, v78
	global_store_dwordx4 v[84:85], v[76:79], off
	s_and_saveexec_b64 s[2:3], s[4:5]
	s_xor_b64 s[2:3], exec, s[2:3]
	s_cbranch_execz .LBB0_1309
	v_readlane_b32 s52, v241, 8
	v_readlane_b32 s60, v241, 16
	v_readlane_b32 s61, v241, 17
	v_lshl_add_u64 v[76:77], s[8:9], 0, v[82:83]
	v_lshl_add_u64 v[76:77], v[76:77], 0, v[160:161]
	v_readlane_b32 s53, v241, 9
	v_readlane_b32 s54, v241, 10
	v_readlane_b32 s55, v241, 11
	global_load_dword v78, v160, s[60:61]
	v_readlane_b32 s56, v241, 12
	v_readlane_b32 s57, v241, 13
	v_readlane_b32 s58, v241, 14
	v_readlane_b32 s59, v241, 15
	v_readlane_b32 s62, v241, 18
	v_readlane_b32 s63, v241, 19
	v_readlane_b32 s64, v241, 20
	v_readlane_b32 s65, v241, 21
	v_readlane_b32 s66, v241, 22
	v_readlane_b32 s67, v241, 23
	s_waitcnt vmcnt(0)
	v_fmac_f32_e32 v78, v72, v80
	v_min_f32_e32 v81, 0, v78
	v_mul_f32_e64 v78, |v78|, s46
	v_exp_f32_e32 v84, v78
	s_nop 0
	v_add_f32_e32 v85, 1.0, v84
	v_add_f32_e32 v78, -1.0, v85
	v_sub_f32_e32 v79, v78, v85
	v_add_f32_e32 v79, 1.0, v79
	v_sub_f32_e32 v78, v84, v78
	v_add_f32_e32 v86, v78, v79
	v_frexp_mant_f32_e32 v78, v85
	v_cmp_gt_f32_e32 vcc, s47, v78
	v_cvt_f64_f32_e32 v[78:79], v85
	v_frexp_exp_i32_f64_e32 v78, v[78:79]
	v_subbrev_co_u32_e32 v78, vcc, 0, v78, vcc
	v_sub_u32_e32 v79, 0, v78
	v_ldexp_f32 v85, v85, v79
	v_ldexp_f32 v79, v86, v79
	v_add_f32_e32 v86, -1.0, v85
	v_add_f32_e32 v87, 1.0, v86
	v_sub_f32_e32 v87, v85, v87
	v_add_f32_e32 v87, v79, v87
	v_add_f32_e32 v88, v86, v87
	v_sub_f32_e32 v86, v88, v86
	v_sub_f32_e32 v86, v87, v86
	v_add_f32_e32 v87, 1.0, v85
	v_add_f32_e32 v89, -1.0, v87
	v_sub_f32_e32 v85, v85, v89
	v_add_f32_e32 v79, v79, v85
	v_add_f32_e32 v85, v87, v79
	v_sub_f32_e32 v87, v85, v87
	v_sub_f32_e32 v79, v79, v87
	v_rcp_f32_e32 v87, v85
	v_cvt_f32_i32_e32 v78, v78
	v_cmp_neq_f32_e32 vcc, s49, v84
	v_mul_f32_e32 v89, v88, v87
	v_mul_f32_e32 v90, v85, v89
	v_fma_f32 v91, v89, v85, -v90
	v_fmac_f32_e32 v91, v89, v79
	v_add_f32_e32 v92, v90, v91
	v_sub_f32_e32 v93, v88, v92
	v_sub_f32_e32 v88, v88, v93
	v_sub_f32_e32 v90, v92, v90
	v_sub_f32_e32 v88, v88, v92
	v_add_f32_e32 v86, v86, v88
	v_sub_f32_e32 v88, v90, v91
	v_add_f32_e32 v86, v88, v86
	v_add_f32_e32 v88, v93, v86
	v_mul_f32_e32 v90, v87, v88
	v_mul_f32_e32 v91, v85, v90
	v_fma_f32 v85, v90, v85, -v91
	v_fmac_f32_e32 v85, v90, v79
	v_sub_f32_e32 v79, v93, v88
	v_add_f32_e32 v79, v86, v79
	v_add_f32_e32 v86, v91, v85
	v_sub_f32_e32 v92, v88, v86
	v_sub_f32_e32 v88, v88, v92
	v_sub_f32_e32 v91, v86, v91
	v_sub_f32_e32 v86, v88, v86
	v_add_f32_e32 v79, v79, v86
	v_sub_f32_e32 v85, v91, v85
	v_add_f32_e32 v79, v85, v79
	v_add_f32_e32 v85, v89, v90
	v_add_f32_e32 v79, v92, v79
	v_sub_f32_e32 v86, v85, v89
	v_mul_f32_e32 v79, v87, v79
	v_sub_f32_e32 v86, v90, v86
	v_add_f32_e32 v79, v86, v79
	v_mul_f32_e32 v89, 0x3f317218, v78
	v_add_f32_e32 v86, v85, v79
	v_fma_f32 v90, v78, s48, -v89
	v_mul_f32_e32 v87, v86, v86
	v_fmac_f32_e32 v90, 0xb102e308, v78
	v_sub_f32_e32 v78, v86, v85
	v_fmamk_f32 v88, v87, 0x3e9b6dac, v171
	v_sub_f32_e32 v78, v79, v78
	v_add_f32_e32 v79, v89, v90
	v_fmaak_f32 v88, v87, v88, 0x3f2aaada
	v_sub_f32_e32 v85, v79, v89
	v_ldexp_f32 v89, v86, 1
	v_mul_f32_e32 v86, v86, v87
	v_mul_f32_e32 v86, v86, v88
	v_add_f32_e32 v87, v89, v86
	v_sub_f32_e32 v88, v87, v89
	v_ldexp_f32 v78, v78, 1
	v_sub_f32_e32 v86, v86, v88
	v_add_f32_e32 v78, v78, v86
	v_add_f32_e32 v86, v87, v78
	v_sub_f32_e32 v87, v86, v87
	v_sub_f32_e32 v78, v78, v87
	v_add_f32_e32 v87, v79, v86
	v_sub_f32_e32 v88, v87, v79
	v_sub_f32_e32 v89, v87, v88
	v_sub_f32_e32 v85, v90, v85
	v_sub_f32_e32 v79, v79, v89
	v_sub_f32_e32 v86, v86, v88
	v_add_f32_e32 v79, v86, v79
	v_add_f32_e32 v86, v85, v78
	v_sub_f32_e32 v88, v86, v85
	v_sub_f32_e32 v89, v86, v88
	v_sub_f32_e32 v85, v85, v89
	v_sub_f32_e32 v78, v78, v88
	v_add_f32_e32 v79, v86, v79
	v_add_f32_e32 v78, v78, v85
	v_add_f32_e32 v85, v87, v79
	v_sub_f32_e32 v86, v85, v87
	v_sub_f32_e32 v79, v79, v86
	v_add_f32_e32 v78, v78, v79
	v_add_f32_e32 v78, v85, v78
	v_cndmask_b32_e32 v78, v178, v78, vcc
	v_cmp_ngt_f32_e32 vcc, -1.0, v84
	s_nop 1
	v_cndmask_b32_e32 v78, v179, v78, vcc
	v_cmp_neq_f32_e32 vcc, -1.0, v84
	s_nop 1
	v_cndmask_b32_e32 v78, v180, v78, vcc
	v_cmp_lt_f32_e64 vcc, |v84|, s50
	s_nop 1
	v_cndmask_b32_e32 v78, v78, v84, vcc
	v_sub_f32_e32 v78, v81, v78
	global_store_dword v[76:77], v78, off offset:-32
	global_load_dword v79, v160, s[60:61] offset:4
	s_waitcnt vmcnt(0)
; template <bool SWAP> DI void inproj_tile(const Params& p, int layer, int tm, int tn, bf16_t* smem) {
;     ...
;           for (int r = 0; r < 4; ++r) { const int h = (quad - 2) * 4 + r; const float xx = acc[i][1][r] * rs + p.b_forget[layer * 8 + h]; lf[h] = fminf(xx, 0.f) - log1pf(__expf(-fabsf(xx))); }
	v_fmac_f32_e32 v79, v73, v80
	v_min_f32_e32 v78, 0, v79
	v_mul_f32_e64 v79, |v79|, s46
	v_exp_f32_e32 v79, v79
	s_nop 0
	v_add_f32_e32 v81, 1.0, v79
	v_add_f32_e32 v84, -1.0, v81
	v_sub_f32_e32 v85, v84, v81
	v_add_f32_e32 v85, 1.0, v85
	v_sub_f32_e32 v84, v79, v84
	v_add_f32_e32 v86, v84, v85
	v_frexp_mant_f32_e32 v84, v81
	v_cmp_gt_f32_e32 vcc, s47, v84
	v_cvt_f64_f32_e32 v[84:85], v81
	v_frexp_exp_i32_f64_e32 v84, v[84:85]
	v_subbrev_co_u32_e32 v84, vcc, 0, v84, vcc
	v_sub_u32_e32 v85, 0, v84
	v_ldexp_f32 v81, v81, v85
	v_ldexp_f32 v85, v86, v85
	v_add_f32_e32 v86, -1.0, v81
	v_add_f32_e32 v87, 1.0, v86
	v_sub_f32_e32 v87, v81, v87
	v_add_f32_e32 v87, v85, v87
	v_add_f32_e32 v88, v86, v87
	v_sub_f32_e32 v86, v88, v86
	v_sub_f32_e32 v86, v87, v86
	v_add_f32_e32 v87, 1.0, v81
	v_add_f32_e32 v89, -1.0, v87
	v_sub_f32_e32 v81, v81, v89
	v_add_f32_e32 v81, v85, v81
	v_add_f32_e32 v85, v87, v81
	v_sub_f32_e32 v87, v85, v87
	v_sub_f32_e32 v81, v81, v87
	v_rcp_f32_e32 v87, v85
	v_cvt_f32_i32_e32 v84, v84
	v_cmp_neq_f32_e32 vcc, s49, v79
	v_mul_f32_e32 v89, v88, v87
	v_mul_f32_e32 v90, v85, v89
	v_fma_f32 v91, v89, v85, -v90
	v_fmac_f32_e32 v91, v89, v81
	v_add_f32_e32 v92, v90, v91
	v_sub_f32_e32 v93, v88, v92
	v_sub_f32_e32 v88, v88, v93
	v_sub_f32_e32 v90, v92, v90
	v_sub_f32_e32 v88, v88, v92
	v_add_f32_e32 v86, v86, v88
	v_sub_f32_e32 v88, v90, v91
	v_add_f32_e32 v86, v88, v86
	v_add_f32_e32 v88, v93, v86
	v_mul_f32_e32 v90, v87, v88
	v_mul_f32_e32 v91, v85, v90
	v_fma_f32 v85, v90, v85, -v91
	v_fmac_f32_e32 v85, v90, v81
	v_sub_f32_e32 v81, v93, v88
	v_add_f32_e32 v81, v86, v81
	v_add_f32_e32 v86, v91, v85
	v_sub_f32_e32 v92, v88, v86
	v_sub_f32_e32 v88, v88, v92
	v_sub_f32_e32 v91, v86, v91
	v_sub_f32_e32 v86, v88, v86
	v_add_f32_e32 v81, v81, v86
	v_sub_f32_e32 v85, v91, v85
	v_add_f32_e32 v81, v85, v81
	v_add_f32_e32 v85, v89, v90
	v_add_f32_e32 v81, v92, v81
	v_sub_f32_e32 v86, v85, v89
	v_mul_f32_e32 v81, v87, v81
	v_sub_f32_e32 v86, v90, v86
	v_add_f32_e32 v81, v86, v81
	v_mul_f32_e32 v89, 0x3f317218, v84
	v_add_f32_e32 v86, v85, v81
	v_fma_f32 v90, v84, s48, -v89
	v_mul_f32_e32 v87, v86, v86
	v_fmac_f32_e32 v90, 0xb102e308, v84
	v_sub_f32_e32 v84, v86, v85
	v_fmamk_f32 v88, v87, 0x3e9b6dac, v171
	v_sub_f32_e32 v81, v81, v84
	v_add_f32_e32 v84, v89, v90
	v_fmaak_f32 v88, v87, v88, 0x3f2aaada
	v_sub_f32_e32 v85, v84, v89
	v_ldexp_f32 v89, v86, 1
	v_mul_f32_e32 v86, v86, v87
	v_mul_f32_e32 v86, v86, v88
	v_add_f32_e32 v87, v89, v86
	v_sub_f32_e32 v88, v87, v89
	v_ldexp_f32 v81, v81, 1
	v_sub_f32_e32 v86, v86, v88
	v_add_f32_e32 v81, v81, v86
	v_add_f32_e32 v86, v87, v81
	v_sub_f32_e32 v87, v86, v87
	v_sub_f32_e32 v81, v81, v87
	v_add_f32_e32 v87, v84, v86
	v_sub_f32_e32 v88, v87, v84
	v_sub_f32_e32 v89, v87, v88
	v_sub_f32_e32 v85, v90, v85
	v_sub_f32_e32 v84, v84, v89
	v_sub_f32_e32 v86, v86, v88
	v_add_f32_e32 v84, v86, v84
	v_add_f32_e32 v86, v85, v81
	v_sub_f32_e32 v88, v86, v85
	v_sub_f32_e32 v89, v86, v88
	v_sub_f32_e32 v85, v85, v89
	v_sub_f32_e32 v81, v81, v88
	v_add_f32_e32 v84, v86, v84
	v_add_f32_e32 v81, v81, v85
	v_add_f32_e32 v85, v87, v84
	v_sub_f32_e32 v86, v85, v87
	v_sub_f32_e32 v84, v84, v86
	v_add_f32_e32 v81, v81, v84
	v_add_f32_e32 v81, v85, v81
	v_cndmask_b32_e32 v81, v178, v81, vcc
	v_cmp_ngt_f32_e32 vcc, -1.0, v79
	s_nop 1
	v_cndmask_b32_e32 v81, v179, v81, vcc
	v_cmp_neq_f32_e32 vcc, -1.0, v79
	s_nop 1
	v_cndmask_b32_e32 v81, v180, v81, vcc
	v_cmp_lt_f32_e64 vcc, |v79|, s50
	s_nop 1
	v_cndmask_b32_e32 v79, v81, v79, vcc
	v_sub_f32_e32 v78, v78, v79
	global_store_dword v[76:77], v78, off offset:-28
	global_load_dword v79, v160, s[60:61] offset:8
	s_waitcnt vmcnt(0)
	v_fmac_f32_e32 v79, v74, v80
	v_min_f32_e32 v78, 0, v79
	v_mul_f32_e64 v79, |v79|, s46
	v_exp_f32_e32 v79, v79
	s_nop 0
	v_add_f32_e32 v81, 1.0, v79
	v_add_f32_e32 v84, -1.0, v81
	v_sub_f32_e32 v85, v84, v81
	v_add_f32_e32 v85, 1.0, v85
	v_sub_f32_e32 v84, v79, v84
	v_add_f32_e32 v86, v84, v85
	v_frexp_mant_f32_e32 v84, v81
	v_cmp_gt_f32_e32 vcc, s47, v84
	v_cvt_f64_f32_e32 v[84:85], v81
	v_frexp_exp_i32_f64_e32 v84, v[84:85]
	v_subbrev_co_u32_e32 v84, vcc, 0, v84, vcc
	v_sub_u32_e32 v85, 0, v84
	v_ldexp_f32 v81, v81, v85
	v_ldexp_f32 v85, v86, v85
	v_add_f32_e32 v86, -1.0, v81
	v_add_f32_e32 v87, 1.0, v86
	v_sub_f32_e32 v87, v81, v87
	v_add_f32_e32 v87, v85, v87
	v_add_f32_e32 v88, v86, v87
	v_sub_f32_e32 v86, v88, v86
	v_sub_f32_e32 v86, v87, v86
	v_add_f32_e32 v87, 1.0, v81
	v_add_f32_e32 v89, -1.0, v87
	v_sub_f32_e32 v81, v81, v89
	v_add_f32_e32 v81, v85, v81
	v_add_f32_e32 v85, v87, v81
	v_sub_f32_e32 v87, v85, v87
	v_sub_f32_e32 v81, v81, v87
	v_rcp_f32_e32 v87, v85
	v_cvt_f32_i32_e32 v84, v84
	v_cmp_neq_f32_e32 vcc, s49, v79
	v_mul_f32_e32 v89, v88, v87
	v_mul_f32_e32 v90, v85, v89
	v_fma_f32 v91, v89, v85, -v90
	v_fmac_f32_e32 v91, v89, v81
	v_add_f32_e32 v92, v90, v91
	v_sub_f32_e32 v93, v88, v92
	v_sub_f32_e32 v88, v88, v93
	v_sub_f32_e32 v90, v92, v90
	v_sub_f32_e32 v88, v88, v92
	v_add_f32_e32 v86, v86, v88
	v_sub_f32_e32 v88, v90, v91
	v_add_f32_e32 v86, v88, v86
	v_add_f32_e32 v88, v93, v86
	v_mul_f32_e32 v90, v87, v88
	v_mul_f32_e32 v91, v85, v90
	v_fma_f32 v85, v90, v85, -v91
	v_fmac_f32_e32 v85, v90, v81
	v_sub_f32_e32 v81, v93, v88
	v_add_f32_e32 v81, v86, v81
	v_add_f32_e32 v86, v91, v85
	v_sub_f32_e32 v92, v88, v86
	v_sub_f32_e32 v88, v88, v92
	v_sub_f32_e32 v91, v86, v91
	v_sub_f32_e32 v86, v88, v86
	v_add_f32_e32 v81, v81, v86
	v_sub_f32_e32 v85, v91, v85
	v_add_f32_e32 v81, v85, v81
	v_add_f32_e32 v85, v89, v90
	v_add_f32_e32 v81, v92, v81
	v_sub_f32_e32 v86, v85, v89
	v_mul_f32_e32 v81, v87, v81
	v_sub_f32_e32 v86, v90, v86
; DI float sigmoidf_(float x) { return 1.f / (1.f + __expf(-x)); }
; template <bool SWAP> DI void inproj_tile(const Params& p, int layer, int tm, int tn, bf16_t* smem) {
;     ...
;       for (int i = 0; i < 8; ++i) {
;         const int t = trow0 + i * 16 + l15; const float rs = rstd_from16(ssq + (size_t)t * 16, 1.f / 1024.f);
;         float* gt = (float*)(p.ws + O_GATES) + (size_t)t * 24; float* lf = (float*)(p.ws + O_LOGF) + (size_t)t * 8;
; #pragma unroll
;         for (int r = 0; r < 4; ++r) gt[quad * 4 + r] = sigmoidf_(acc[i][0][r] * rs);
;         if (quad < 2) {
; #pragma unroll
;           for (int r = 0; r < 4; ++r) gt[16 + quad * 4 + r] = sigmoidf_(acc[i][1][r] * rs);
;         } else {
; #pragma unroll
;           for (int r = 0; r < 4; ++r) { const int h = (quad - 2) * 4 + r; const float xx = acc[i][1][r] * rs + p.b_forget[layer * 8 + h]; lf[h] = fminf(xx, 0.f) - log1pf(__expf(-fabsf(xx))); }
;         }
	v_add_f32_e32 v81, v86, v81
	v_mul_f32_e32 v89, 0x3f317218, v84
	v_add_f32_e32 v86, v85, v81
	v_fma_f32 v90, v84, s48, -v89
	v_mul_f32_e32 v87, v86, v86
	v_fmac_f32_e32 v90, 0xb102e308, v84
	v_sub_f32_e32 v84, v86, v85
	v_fmamk_f32 v88, v87, 0x3e9b6dac, v171
	v_sub_f32_e32 v81, v81, v84
	v_add_f32_e32 v84, v89, v90
	v_fmaak_f32 v88, v87, v88, 0x3f2aaada
	v_sub_f32_e32 v85, v84, v89
	v_ldexp_f32 v89, v86, 1
	v_mul_f32_e32 v86, v86, v87
	v_mul_f32_e32 v86, v86, v88
	v_add_f32_e32 v87, v89, v86
	v_sub_f32_e32 v88, v87, v89
	v_ldexp_f32 v81, v81, 1
	v_sub_f32_e32 v86, v86, v88
	v_add_f32_e32 v81, v81, v86
	v_add_f32_e32 v86, v87, v81
	v_sub_f32_e32 v87, v86, v87
	v_sub_f32_e32 v81, v81, v87
	v_add_f32_e32 v87, v84, v86
	v_sub_f32_e32 v88, v87, v84
	v_sub_f32_e32 v89, v87, v88
	v_sub_f32_e32 v85, v90, v85
	v_sub_f32_e32 v84, v84, v89
	v_sub_f32_e32 v86, v86, v88
	v_add_f32_e32 v84, v86, v84
	v_add_f32_e32 v86, v85, v81
	v_sub_f32_e32 v88, v86, v85
	v_sub_f32_e32 v89, v86, v88
	v_sub_f32_e32 v85, v85, v89
	v_sub_f32_e32 v81, v81, v88
	v_add_f32_e32 v84, v86, v84
	v_add_f32_e32 v81, v81, v85
	v_add_f32_e32 v85, v87, v84
	v_sub_f32_e32 v86, v85, v87
	v_sub_f32_e32 v84, v84, v86
	v_add_f32_e32 v81, v81, v84
	v_add_f32_e32 v81, v85, v81
	v_cndmask_b32_e32 v81, v178, v81, vcc
	v_cmp_ngt_f32_e32 vcc, -1.0, v79
	s_nop 1
	v_cndmask_b32_e32 v81, v179, v81, vcc
	v_cmp_neq_f32_e32 vcc, -1.0, v79
	s_nop 1
	v_cndmask_b32_e32 v81, v180, v81, vcc
	v_cmp_lt_f32_e64 vcc, |v79|, s50
	s_nop 1
	v_cndmask_b32_e32 v79, v81, v79, vcc
	v_sub_f32_e32 v78, v78, v79
	global_store_dword v[76:77], v78, off offset:-24
	global_load_dword v79, v160, s[60:61] offset:12
	s_waitcnt vmcnt(0)
	v_fmac_f32_e32 v79, v75, v80
	v_min_f32_e32 v78, 0, v79
	v_mul_f32_e64 v79, |v79|, s46
	v_exp_f32_e32 v79, v79
	s_nop 0
	v_add_f32_e32 v81, 1.0, v79
	v_add_f32_e32 v84, -1.0, v81
	v_sub_f32_e32 v85, v84, v81
	v_add_f32_e32 v85, 1.0, v85
	v_sub_f32_e32 v84, v79, v84
	v_add_f32_e32 v86, v84, v85
	v_frexp_mant_f32_e32 v84, v81
	v_cmp_gt_f32_e32 vcc, s47, v84
	v_cvt_f64_f32_e32 v[84:85], v81
	v_frexp_exp_i32_f64_e32 v84, v[84:85]
	v_subbrev_co_u32_e32 v84, vcc, 0, v84, vcc
	v_sub_u32_e32 v85, 0, v84
	v_ldexp_f32 v81, v81, v85
	v_ldexp_f32 v85, v86, v85
	v_add_f32_e32 v86, -1.0, v81
	v_add_f32_e32 v87, 1.0, v86
	v_sub_f32_e32 v87, v81, v87
	v_add_f32_e32 v87, v85, v87
	v_add_f32_e32 v88, v86, v87
	v_sub_f32_e32 v86, v88, v86
	v_sub_f32_e32 v86, v87, v86
	v_add_f32_e32 v87, 1.0, v81
	v_add_f32_e32 v89, -1.0, v87
	v_sub_f32_e32 v81, v81, v89
	v_add_f32_e32 v81, v85, v81
	v_add_f32_e32 v85, v87, v81
	v_sub_f32_e32 v87, v85, v87
	v_sub_f32_e32 v81, v81, v87
	v_rcp_f32_e32 v87, v85
	v_cvt_f32_i32_e32 v84, v84
	v_cmp_neq_f32_e32 vcc, s49, v79
	v_mul_f32_e32 v89, v88, v87
	v_mul_f32_e32 v90, v85, v89
	v_fma_f32 v91, v89, v85, -v90
	v_fmac_f32_e32 v91, v89, v81
	v_add_f32_e32 v92, v90, v91
	v_sub_f32_e32 v93, v88, v92
	v_sub_f32_e32 v88, v88, v93
	v_sub_f32_e32 v90, v92, v90
	v_sub_f32_e32 v88, v88, v92
	v_add_f32_e32 v86, v86, v88
	v_sub_f32_e32 v88, v90, v91
	v_add_f32_e32 v86, v88, v86
	v_add_f32_e32 v88, v93, v86
	v_mul_f32_e32 v90, v87, v88
	v_mul_f32_e32 v91, v85, v90
	v_fma_f32 v85, v90, v85, -v91
	v_fmac_f32_e32 v85, v90, v81
	v_sub_f32_e32 v81, v93, v88
	v_add_f32_e32 v81, v86, v81
	v_add_f32_e32 v86, v91, v85
	v_sub_f32_e32 v92, v88, v86
	v_sub_f32_e32 v88, v88, v92
	v_sub_f32_e32 v91, v86, v91
	v_sub_f32_e32 v86, v88, v86
	v_add_f32_e32 v81, v81, v86
	v_sub_f32_e32 v85, v91, v85
	v_add_f32_e32 v81, v85, v81
	v_add_f32_e32 v85, v89, v90
	v_add_f32_e32 v81, v92, v81
	v_sub_f32_e32 v86, v85, v89
	v_mul_f32_e32 v81, v87, v81
	v_sub_f32_e32 v86, v90, v86
	v_add_f32_e32 v81, v86, v81
	v_mul_f32_e32 v89, 0x3f317218, v84
	v_add_f32_e32 v86, v85, v81
	v_fma_f32 v90, v84, s48, -v89
	v_mul_f32_e32 v87, v86, v86
	v_fmac_f32_e32 v90, 0xb102e308, v84
	v_sub_f32_e32 v84, v86, v85
	v_fmamk_f32 v88, v87, 0x3e9b6dac, v171
	v_sub_f32_e32 v81, v81, v84
	v_add_f32_e32 v84, v89, v90
	v_fmaak_f32 v88, v87, v88, 0x3f2aaada
	v_sub_f32_e32 v85, v84, v89
	v_ldexp_f32 v89, v86, 1
	v_mul_f32_e32 v86, v86, v87
	v_mul_f32_e32 v86, v86, v88
	v_add_f32_e32 v87, v89, v86
	v_sub_f32_e32 v88, v87, v89
	v_ldexp_f32 v81, v81, 1
	v_sub_f32_e32 v86, v86, v88
	v_add_f32_e32 v81, v81, v86
	v_add_f32_e32 v86, v87, v81
	v_sub_f32_e32 v87, v86, v87
	v_sub_f32_e32 v81, v81, v87
	v_add_f32_e32 v87, v84, v86
	v_sub_f32_e32 v88, v87, v84
	v_sub_f32_e32 v89, v87, v88
	v_sub_f32_e32 v85, v90, v85
	v_sub_f32_e32 v84, v84, v89
	v_sub_f32_e32 v86, v86, v88
	v_add_f32_e32 v84, v86, v84
	v_add_f32_e32 v86, v85, v81
	v_sub_f32_e32 v88, v86, v85
	v_sub_f32_e32 v89, v86, v88
	v_sub_f32_e32 v85, v85, v89
	v_sub_f32_e32 v81, v81, v88
	v_add_f32_e32 v84, v86, v84
	v_add_f32_e32 v81, v81, v85
	v_add_f32_e32 v85, v87, v84
	v_sub_f32_e32 v86, v85, v87
	v_sub_f32_e32 v84, v84, v86
	v_add_f32_e32 v81, v81, v84
	v_add_f32_e32 v81, v85, v81
	v_cndmask_b32_e32 v81, v178, v81, vcc
	v_cmp_ngt_f32_e32 vcc, -1.0, v79
	s_nop 1
	v_cndmask_b32_e32 v81, v179, v81, vcc
	v_cmp_neq_f32_e32 vcc, -1.0, v79
	s_nop 1
	v_cndmask_b32_e32 v81, v180, v81, vcc
	v_cmp_lt_f32_e64 vcc, |v79|, s50
	s_nop 1
	v_cndmask_b32_e32 v79, v81, v79, vcc
	v_sub_f32_e32 v78, v78, v79
	global_store_dword v[76:77], v78, off offset:-20
.LBB0_1309:
	s_andn2_saveexec_b64 s[2:3], s[2:3]
	s_cbranch_execz .LBB0_1311
	v_mul_f32_e32 v72, v72, v80
	v_mul_f32_e32 v73, v73, v80
	v_mul_f32_e32 v72, 0xbfb8aa3b, v72
	v_mul_f32_e32 v73, 0xbfb8aa3b, v73
	v_exp_f32_e32 v72, v72
	v_exp_f32_e32 v73, v73
	v_mul_f32_e32 v74, v74, v80
	v_mul_f32_e32 v75, v75, v80
	v_mul_f32_e32 v74, 0xbfb8aa3b, v74
	v_pk_add_f32 v[72:73], v[72:73], 1.0 op_sel_hi:[1,0]
	v_mul_f32_e32 v75, 0xbfb8aa3b, v75
	v_exp_f32_e32 v74, v74
	v_exp_f32_e32 v75, v75
	v_rcp_f32_e32 v73, v73
	v_pk_add_f32 v[74:75], v[74:75], 1.0 op_sel_hi:[1,0]
	v_rcp_f32_e32 v72, v72
	s_nop 0
	v_rcp_f32_e32 v75, v75
	s_nop 0
	v_rcp_f32_e32 v74, v74
	global_store_dwordx4 v[84:85], v[72:75], off offset:64

; DI float sigmoidf_(float x) { return 1.f / (1.f + __expf(-x)); }
; template <bool SWAP> DI void inproj_tile(const Params& p, int layer, int tm, int tn, bf16_t* smem) {
;     ...
;       for (int i = 0; i < 8; ++i) {
;         const int t = trow0 + i * 16 + l15; const float rs = rstd_from16(ssq + (size_t)t * 16, 1.f / 1024.f);
;         float* gt = (float*)(p.ws + O_GATES) + (size_t)t * 24; float* lf = (float*)(p.ws + O_LOGF) + (size_t)t * 8;
; #pragma unroll
;         for (int r = 0; r < 4; ++r) gt[quad * 4 + r] = sigmoidf_(acc[i][0][r] * rs);
;         if (quad < 2) {
; #pragma unroll
;           for (int r = 0; r < 4; ++r) gt[16 + quad * 4 + r] = sigmoidf_(acc[i][1][r] * rs);
;         } else {
; #pragma unroll
;           for (int r = 0; r < 4; ++r) { const int h = (quad - 2) * 4 + r; const float xx = acc[i][1][r] * rs + p.b_forget[layer * 8 + h]; lf[h] = fminf(xx, 0.f) - log1pf(__expf(-fabsf(xx))); }
;         }
.LrcA1_12:
	s_or_b64 exec, exec, s[98:99]
	s_waitcnt vmcnt(0)
	v_cndmask_b32_e64 v64, v249, v64, s[100:101]
	v_readlane_b32 s2, v240, 35
	v_readlane_b32 s3, v240, 36
	s_nop 1
	v_mov_b64_e32 v[66:67], s[2:3]
	v_mad_i64_i32 v[68:69], s[2:3], v80, s45, v[66:67]
	v_lshlrev_b64 v[66:67], 5, v[80:81]
	v_lshl_add_u64 v[68:69], v[68:69], 0, v[160:161]
	v_mul_f32_e32 v60, v60, v64
	v_mul_f32_e32 v61, v61, v64
	v_mul_f32_e32 v60, 0xbfb8aa3b, v60
	v_mul_f32_e32 v61, 0xbfb8aa3b, v61
	v_exp_f32_e32 v60, v60
	v_exp_f32_e32 v61, v61
	v_mul_f32_e32 v62, v62, v64
	v_mul_f32_e32 v63, v63, v64
	v_mul_f32_e32 v62, 0xbfb8aa3b, v62
	v_pk_add_f32 v[60:61], v[60:61], 1.0 op_sel_hi:[1,0]
	v_mul_f32_e32 v63, 0xbfb8aa3b, v63
	v_exp_f32_e32 v62, v62
	v_exp_f32_e32 v63, v63
	v_rcp_f32_e32 v61, v61
	v_pk_add_f32 v[62:63], v[62:63], 1.0 op_sel_hi:[1,0]
	v_rcp_f32_e32 v60, v60
	s_nop 0
	v_rcp_f32_e32 v63, v63
	s_nop 0
	v_rcp_f32_e32 v62, v62
	global_store_dwordx4 v[68:69], v[60:63], off
	s_and_saveexec_b64 s[2:3], s[4:5]
	s_xor_b64 s[2:3], exec, s[2:3]
	s_cbranch_execz .LBB0_1313
	v_readlane_b32 s52, v241, 8
	v_readlane_b32 s60, v241, 16
	v_readlane_b32 s61, v241, 17
	v_lshl_add_u64 v[60:61], s[8:9], 0, v[66:67]
	v_lshl_add_u64 v[60:61], v[60:61], 0, v[160:161]
	v_readlane_b32 s53, v241, 9
	v_readlane_b32 s54, v241, 10
	v_readlane_b32 s55, v241, 11
	global_load_dword v62, v160, s[60:61]
	v_readlane_b32 s56, v241, 12
	v_readlane_b32 s57, v241, 13
	v_readlane_b32 s58, v241, 14
	v_readlane_b32 s59, v241, 15
	v_readlane_b32 s62, v241, 18
	v_readlane_b32 s63, v241, 19
	v_readlane_b32 s64, v241, 20
	v_readlane_b32 s65, v241, 21
	v_readlane_b32 s66, v241, 22
	v_readlane_b32 s67, v241, 23
	s_waitcnt vmcnt(0)
	v_fmac_f32_e32 v62, v56, v64
	v_min_f32_e32 v65, 0, v62
	v_mul_f32_e64 v62, |v62|, s46
	v_exp_f32_e32 v68, v62
	s_nop 0
	v_add_f32_e32 v69, 1.0, v68
	v_add_f32_e32 v62, -1.0, v69
	v_sub_f32_e32 v63, v62, v69
	v_add_f32_e32 v63, 1.0, v63
	v_sub_f32_e32 v62, v68, v62
	v_add_f32_e32 v70, v62, v63
	v_frexp_mant_f32_e32 v62, v69
	v_cmp_gt_f32_e32 vcc, s47, v62
	v_cvt_f64_f32_e32 v[62:63], v69
	v_frexp_exp_i32_f64_e32 v62, v[62:63]
	v_subbrev_co_u32_e32 v62, vcc, 0, v62, vcc
	v_sub_u32_e32 v63, 0, v62
	v_ldexp_f32 v69, v69, v63
	v_ldexp_f32 v63, v70, v63
	v_add_f32_e32 v70, -1.0, v69
	v_add_f32_e32 v71, 1.0, v70
	v_sub_f32_e32 v71, v69, v71
	v_add_f32_e32 v71, v63, v71
	v_add_f32_e32 v72, v70, v71
	v_sub_f32_e32 v70, v72, v70
	v_sub_f32_e32 v70, v71, v70
	v_add_f32_e32 v71, 1.0, v69
	v_add_f32_e32 v73, -1.0, v71
	v_sub_f32_e32 v69, v69, v73
	v_add_f32_e32 v63, v63, v69
	v_add_f32_e32 v69, v71, v63
	v_sub_f32_e32 v71, v69, v71
	v_sub_f32_e32 v63, v63, v71
	v_rcp_f32_e32 v71, v69
	v_cvt_f32_i32_e32 v62, v62
	v_cmp_neq_f32_e32 vcc, s49, v68
	v_mul_f32_e32 v73, v72, v71
	v_mul_f32_e32 v74, v69, v73
	v_fma_f32 v75, v73, v69, -v74
	v_fmac_f32_e32 v75, v73, v63
	v_add_f32_e32 v76, v74, v75
	v_sub_f32_e32 v77, v72, v76
	v_sub_f32_e32 v72, v72, v77
	v_sub_f32_e32 v74, v76, v74
	v_sub_f32_e32 v72, v72, v76
	v_add_f32_e32 v70, v70, v72
	v_sub_f32_e32 v72, v74, v75
	v_add_f32_e32 v70, v72, v70
	v_add_f32_e32 v72, v77, v70
	v_mul_f32_e32 v74, v71, v72
	v_mul_f32_e32 v75, v69, v74
	v_fma_f32 v69, v74, v69, -v75
	v_fmac_f32_e32 v69, v74, v63
	v_sub_f32_e32 v63, v77, v72
	v_add_f32_e32 v63, v70, v63
	v_add_f32_e32 v70, v75, v69
	v_sub_f32_e32 v76, v72, v70
	v_sub_f32_e32 v72, v72, v76
	v_sub_f32_e32 v75, v70, v75
	v_sub_f32_e32 v70, v72, v70
	v_add_f32_e32 v63, v63, v70
	v_sub_f32_e32 v69, v75, v69
	v_add_f32_e32 v63, v69, v63
	v_add_f32_e32 v69, v73, v74
	v_add_f32_e32 v63, v76, v63
	v_sub_f32_e32 v70, v69, v73
	v_mul_f32_e32 v63, v71, v63
	v_sub_f32_e32 v70, v74, v70
	v_add_f32_e32 v63, v70, v63
	v_mul_f32_e32 v73, 0x3f317218, v62
	v_add_f32_e32 v70, v69, v63
	v_fma_f32 v74, v62, s48, -v73
	v_mul_f32_e32 v71, v70, v70
	v_fmac_f32_e32 v74, 0xb102e308, v62
	v_sub_f32_e32 v62, v70, v69
	v_fmamk_f32 v72, v71, 0x3e9b6dac, v171
	v_sub_f32_e32 v62, v63, v62
	v_add_f32_e32 v63, v73, v74
	v_fmaak_f32 v72, v71, v72, 0x3f2aaada
	v_sub_f32_e32 v69, v63, v73
	v_ldexp_f32 v73, v70, 1
	v_mul_f32_e32 v70, v70, v71
	v_mul_f32_e32 v70, v70, v72
	v_add_f32_e32 v71, v73, v70
	v_sub_f32_e32 v72, v71, v73
	v_ldexp_f32 v62, v62, 1
	v_sub_f32_e32 v70, v70, v72
	v_add_f32_e32 v62, v62, v70
	v_add_f32_e32 v70, v71, v62
	v_sub_f32_e32 v71, v70, v71
	v_sub_f32_e32 v62, v62, v71
	v_add_f32_e32 v71, v63, v70
	v_sub_f32_e32 v72, v71, v63
	v_sub_f32_e32 v73, v71, v72
	v_sub_f32_e32 v69, v74, v69
	v_sub_f32_e32 v63, v63, v73
	v_sub_f32_e32 v70, v70, v72
	v_add_f32_e32 v63, v70, v63
	v_add_f32_e32 v70, v69, v62
	v_sub_f32_e32 v72, v70, v69
	v_sub_f32_e32 v73, v70, v72
	v_sub_f32_e32 v69, v69, v73
	v_sub_f32_e32 v62, v62, v72
	v_add_f32_e32 v63, v70, v63
	v_add_f32_e32 v62, v62, v69
	v_add_f32_e32 v69, v71, v63
	v_sub_f32_e32 v70, v69, v71
	v_sub_f32_e32 v63, v63, v70
	v_add_f32_e32 v62, v62, v63
	v_add_f32_e32 v62, v69, v62
	v_cndmask_b32_e32 v62, v178, v62, vcc
	v_cmp_ngt_f32_e32 vcc, -1.0, v68
	s_nop 1
	v_cndmask_b32_e32 v62, v179, v62, vcc
	v_cmp_neq_f32_e32 vcc, -1.0, v68
	s_nop 1
	v_cndmask_b32_e32 v62, v180, v62, vcc
	v_cmp_lt_f32_e64 vcc, |v68|, s50
	s_nop 1
	v_cndmask_b32_e32 v62, v62, v68, vcc
	v_sub_f32_e32 v62, v65, v62
	global_store_dword v[60:61], v62, off offset:-32
	global_load_dword v63, v160, s[60:61] offset:4
	s_waitcnt vmcnt(0)
; template <bool SWAP> DI void inproj_tile(const Params& p, int layer, int tm, int tn, bf16_t* smem) {
;     ...
;           for (int r = 0; r < 4; ++r) { const int h = (quad - 2) * 4 + r; const float xx = acc[i][1][r] * rs + p.b_forget[layer * 8 + h]; lf[h] = fminf(xx, 0.f) - log1pf(__expf(-fabsf(xx))); }
	v_fmac_f32_e32 v63, v57, v64
	v_min_f32_e32 v62, 0, v63
	v_mul_f32_e64 v63, |v63|, s46
	v_exp_f32_e32 v63, v63
	s_nop 0
	v_add_f32_e32 v65, 1.0, v63
	v_add_f32_e32 v68, -1.0, v65
	v_sub_f32_e32 v69, v68, v65
	v_add_f32_e32 v69, 1.0, v69
	v_sub_f32_e32 v68, v63, v68
	v_add_f32_e32 v70, v68, v69
	v_frexp_mant_f32_e32 v68, v65
	v_cmp_gt_f32_e32 vcc, s47, v68
	v_cvt_f64_f32_e32 v[68:69], v65
	v_frexp_exp_i32_f64_e32 v68, v[68:69]
	v_subbrev_co_u32_e32 v68, vcc, 0, v68, vcc
	v_sub_u32_e32 v69, 0, v68
	v_ldexp_f32 v65, v65, v69
	v_ldexp_f32 v69, v70, v69
	v_add_f32_e32 v70, -1.0, v65
	v_add_f32_e32 v71, 1.0, v70
	v_sub_f32_e32 v71, v65, v71
	v_add_f32_e32 v71, v69, v71
	v_add_f32_e32 v72, v70, v71
	v_sub_f32_e32 v70, v72, v70
	v_sub_f32_e32 v70, v71, v70
	v_add_f32_e32 v71, 1.0, v65
	v_add_f32_e32 v73, -1.0, v71
	v_sub_f32_e32 v65, v65, v73
	v_add_f32_e32 v65, v69, v65
	v_add_f32_e32 v69, v71, v65
	v_sub_f32_e32 v71, v69, v71
	v_sub_f32_e32 v65, v65, v71
	v_rcp_f32_e32 v71, v69
	v_cvt_f32_i32_e32 v68, v68
	v_cmp_neq_f32_e32 vcc, s49, v63
	v_mul_f32_e32 v73, v72, v71
	v_mul_f32_e32 v74, v69, v73
	v_fma_f32 v75, v73, v69, -v74
	v_fmac_f32_e32 v75, v73, v65
	v_add_f32_e32 v76, v74, v75
	v_sub_f32_e32 v77, v72, v76
	v_sub_f32_e32 v72, v72, v77
	v_sub_f32_e32 v74, v76, v74
	v_sub_f32_e32 v72, v72, v76
	v_add_f32_e32 v70, v70, v72
	v_sub_f32_e32 v72, v74, v75
	v_add_f32_e32 v70, v72, v70
	v_add_f32_e32 v72, v77, v70
	v_mul_f32_e32 v74, v71, v72
	v_mul_f32_e32 v75, v69, v74
	v_fma_f32 v69, v74, v69, -v75
	v_fmac_f32_e32 v69, v74, v65
	v_sub_f32_e32 v65, v77, v72
	v_add_f32_e32 v65, v70, v65
	v_add_f32_e32 v70, v75, v69
	v_sub_f32_e32 v76, v72, v70
	v_sub_f32_e32 v72, v72, v76
	v_sub_f32_e32 v75, v70, v75
	v_sub_f32_e32 v70, v72, v70
	v_add_f32_e32 v65, v65, v70
	v_sub_f32_e32 v69, v75, v69
	v_add_f32_e32 v65, v69, v65
	v_add_f32_e32 v69, v73, v74
	v_add_f32_e32 v65, v76, v65
	v_sub_f32_e32 v70, v69, v73
	v_mul_f32_e32 v65, v71, v65
	v_sub_f32_e32 v70, v74, v70
	v_add_f32_e32 v65, v70, v65
	v_mul_f32_e32 v73, 0x3f317218, v68
	v_add_f32_e32 v70, v69, v65
	v_fma_f32 v74, v68, s48, -v73
	v_mul_f32_e32 v71, v70, v70
	v_fmac_f32_e32 v74, 0xb102e308, v68
	v_sub_f32_e32 v68, v70, v69
	v_fmamk_f32 v72, v71, 0x3e9b6dac, v171
	v_sub_f32_e32 v65, v65, v68
	v_add_f32_e32 v68, v73, v74
	v_fmaak_f32 v72, v71, v72, 0x3f2aaada
	v_sub_f32_e32 v69, v68, v73
	v_ldexp_f32 v73, v70, 1
	v_mul_f32_e32 v70, v70, v71
	v_mul_f32_e32 v70, v70, v72
	v_add_f32_e32 v71, v73, v70
	v_sub_f32_e32 v72, v71, v73
	v_ldexp_f32 v65, v65, 1
	v_sub_f32_e32 v70, v70, v72
	v_add_f32_e32 v65, v65, v70
	v_add_f32_e32 v70, v71, v65
	v_sub_f32_e32 v71, v70, v71
	v_sub_f32_e32 v65, v65, v71
	v_add_f32_e32 v71, v68, v70
	v_sub_f32_e32 v72, v71, v68
	v_sub_f32_e32 v73, v71, v72
	v_sub_f32_e32 v69, v74, v69
	v_sub_f32_e32 v68, v68, v73
	v_sub_f32_e32 v70, v70, v72
	v_add_f32_e32 v68, v70, v68
	v_add_f32_e32 v70, v69, v65
	v_sub_f32_e32 v72, v70, v69
	v_sub_f32_e32 v73, v70, v72
	v_sub_f32_e32 v69, v69, v73
	v_sub_f32_e32 v65, v65, v72
	v_add_f32_e32 v68, v70, v68
	v_add_f32_e32 v65, v65, v69
	v_add_f32_e32 v69, v71, v68
	v_sub_f32_e32 v70, v69, v71
	v_sub_f32_e32 v68, v68, v70
	v_add_f32_e32 v65, v65, v68
	v_add_f32_e32 v65, v69, v65
	v_cndmask_b32_e32 v65, v178, v65, vcc
	v_cmp_ngt_f32_e32 vcc, -1.0, v63
	s_nop 1
	v_cndmask_b32_e32 v65, v179, v65, vcc
	v_cmp_neq_f32_e32 vcc, -1.0, v63
	s_nop 1
	v_cndmask_b32_e32 v65, v180, v65, vcc
	v_cmp_lt_f32_e64 vcc, |v63|, s50
	s_nop 1
	v_cndmask_b32_e32 v63, v65, v63, vcc
	v_sub_f32_e32 v62, v62, v63
	global_store_dword v[60:61], v62, off offset:-28
	global_load_dword v63, v160, s[60:61] offset:8
	s_waitcnt vmcnt(0)
	v_fmac_f32_e32 v63, v58, v64
	v_min_f32_e32 v62, 0, v63
	v_mul_f32_e64 v63, |v63|, s46
	v_exp_f32_e32 v63, v63
	s_nop 0
	v_add_f32_e32 v65, 1.0, v63
	v_add_f32_e32 v68, -1.0, v65
	v_sub_f32_e32 v69, v68, v65
	v_add_f32_e32 v69, 1.0, v69
	v_sub_f32_e32 v68, v63, v68
	v_add_f32_e32 v70, v68, v69
	v_frexp_mant_f32_e32 v68, v65
	v_cmp_gt_f32_e32 vcc, s47, v68
	v_cvt_f64_f32_e32 v[68:69], v65
	v_frexp_exp_i32_f64_e32 v68, v[68:69]
	v_subbrev_co_u32_e32 v68, vcc, 0, v68, vcc
	v_sub_u32_e32 v69, 0, v68
	v_ldexp_f32 v65, v65, v69
	v_ldexp_f32 v69, v70, v69
	v_add_f32_e32 v70, -1.0, v65
	v_add_f32_e32 v71, 1.0, v70
	v_sub_f32_e32 v71, v65, v71
	v_add_f32_e32 v71, v69, v71
	v_add_f32_e32 v72, v70, v71
	v_sub_f32_e32 v70, v72, v70
	v_sub_f32_e32 v70, v71, v70
	v_add_f32_e32 v71, 1.0, v65
	v_add_f32_e32 v73, -1.0, v71
	v_sub_f32_e32 v65, v65, v73
	v_add_f32_e32 v65, v69, v65
	v_add_f32_e32 v69, v71, v65
	v_sub_f32_e32 v71, v69, v71
	v_sub_f32_e32 v65, v65, v71
	v_rcp_f32_e32 v71, v69
	v_cvt_f32_i32_e32 v68, v68
	v_cmp_neq_f32_e32 vcc, s49, v63
	v_mul_f32_e32 v73, v72, v71
	v_mul_f32_e32 v74, v69, v73
	v_fma_f32 v75, v73, v69, -v74
	v_fmac_f32_e32 v75, v73, v65
	v_add_f32_e32 v76, v74, v75
	v_sub_f32_e32 v77, v72, v76
	v_sub_f32_e32 v72, v72, v77
	v_sub_f32_e32 v74, v76, v74
	v_sub_f32_e32 v72, v72, v76
	v_add_f32_e32 v70, v70, v72
	v_sub_f32_e32 v72, v74, v75
	v_add_f32_e32 v70, v72, v70
	v_add_f32_e32 v72, v77, v70
	v_mul_f32_e32 v74, v71, v72
	v_mul_f32_e32 v75, v69, v74
	v_fma_f32 v69, v74, v69, -v75
	v_fmac_f32_e32 v69, v74, v65
	v_sub_f32_e32 v65, v77, v72
	v_add_f32_e32 v65, v70, v65
	v_add_f32_e32 v70, v75, v69
	v_sub_f32_e32 v76, v72, v70
	v_sub_f32_e32 v72, v72, v76
	v_sub_f32_e32 v75, v70, v75
	v_sub_f32_e32 v70, v72, v70
	v_add_f32_e32 v65, v65, v70
	v_sub_f32_e32 v69, v75, v69
	v_add_f32_e32 v65, v69, v65
	v_add_f32_e32 v69, v73, v74
	v_add_f32_e32 v65, v76, v65
	v_sub_f32_e32 v70, v69, v73
	v_mul_f32_e32 v65, v71, v65
	v_sub_f32_e32 v70, v74, v70
; DI float sigmoidf_(float x) { return 1.f / (1.f + __expf(-x)); }
; template <bool SWAP> DI void inproj_tile(const Params& p, int layer, int tm, int tn, bf16_t* smem) {
;     ...
;       for (int i = 0; i < 8; ++i) {
;         const int t = trow0 + i * 16 + l15; const float rs = rstd_from16(ssq + (size_t)t * 16, 1.f / 1024.f);
;         float* gt = (float*)(p.ws + O_GATES) + (size_t)t * 24; float* lf = (float*)(p.ws + O_LOGF) + (size_t)t * 8;
; #pragma unroll
;         for (int r = 0; r < 4; ++r) gt[quad * 4 + r] = sigmoidf_(acc[i][0][r] * rs);
;         if (quad < 2) {
; #pragma unroll
;           for (int r = 0; r < 4; ++r) gt[16 + quad * 4 + r] = sigmoidf_(acc[i][1][r] * rs);
;         } else {
; #pragma unroll
;           for (int r = 0; r < 4; ++r) { const int h = (quad - 2) * 4 + r; const float xx = acc[i][1][r] * rs + p.b_forget[layer * 8 + h]; lf[h] = fminf(xx, 0.f) - log1pf(__expf(-fabsf(xx))); }
;         }
	v_add_f32_e32 v65, v70, v65
	v_mul_f32_e32 v73, 0x3f317218, v68
	v_add_f32_e32 v70, v69, v65
	v_fma_f32 v74, v68, s48, -v73
	v_mul_f32_e32 v71, v70, v70
	v_fmac_f32_e32 v74, 0xb102e308, v68
	v_sub_f32_e32 v68, v70, v69
	v_fmamk_f32 v72, v71, 0x3e9b6dac, v171
	v_sub_f32_e32 v65, v65, v68
	v_add_f32_e32 v68, v73, v74
	v_fmaak_f32 v72, v71, v72, 0x3f2aaada
	v_sub_f32_e32 v69, v68, v73
	v_ldexp_f32 v73, v70, 1
	v_mul_f32_e32 v70, v70, v71
	v_mul_f32_e32 v70, v70, v72
	v_add_f32_e32 v71, v73, v70
	v_sub_f32_e32 v72, v71, v73
	v_ldexp_f32 v65, v65, 1
	v_sub_f32_e32 v70, v70, v72
	v_add_f32_e32 v65, v65, v70
	v_add_f32_e32 v70, v71, v65
	v_sub_f32_e32 v71, v70, v71
	v_sub_f32_e32 v65, v65, v71
	v_add_f32_e32 v71, v68, v70
	v_sub_f32_e32 v72, v71, v68
	v_sub_f32_e32 v73, v71, v72
	v_sub_f32_e32 v69, v74, v69
	v_sub_f32_e32 v68, v68, v73
	v_sub_f32_e32 v70, v70, v72
	v_add_f32_e32 v68, v70, v68
	v_add_f32_e32 v70, v69, v65
	v_sub_f32_e32 v72, v70, v69
	v_sub_f32_e32 v73, v70, v72
	v_sub_f32_e32 v69, v69, v73
	v_sub_f32_e32 v65, v65, v72
	v_add_f32_e32 v68, v70, v68
	v_add_f32_e32 v65, v65, v69
	v_add_f32_e32 v69, v71, v68
	v_sub_f32_e32 v70, v69, v71
	v_sub_f32_e32 v68, v68, v70
	v_add_f32_e32 v65, v65, v68
	v_add_f32_e32 v65, v69, v65
	v_cndmask_b32_e32 v65, v178, v65, vcc
	v_cmp_ngt_f32_e32 vcc, -1.0, v63
	s_nop 1
	v_cndmask_b32_e32 v65, v179, v65, vcc
	v_cmp_neq_f32_e32 vcc, -1.0, v63
	s_nop 1
	v_cndmask_b32_e32 v65, v180, v65, vcc
	v_cmp_lt_f32_e64 vcc, |v63|, s50
	s_nop 1
	v_cndmask_b32_e32 v63, v65, v63, vcc
	v_sub_f32_e32 v62, v62, v63
	global_store_dword v[60:61], v62, off offset:-24
	global_load_dword v63, v160, s[60:61] offset:12
	s_waitcnt vmcnt(0)
	v_fmac_f32_e32 v63, v59, v64
	v_min_f32_e32 v62, 0, v63
	v_mul_f32_e64 v63, |v63|, s46
	v_exp_f32_e32 v63, v63
	s_nop 0
	v_add_f32_e32 v65, 1.0, v63
	v_add_f32_e32 v68, -1.0, v65
	v_sub_f32_e32 v69, v68, v65
	v_add_f32_e32 v69, 1.0, v69
	v_sub_f32_e32 v68, v63, v68
	v_add_f32_e32 v70, v68, v69
	v_frexp_mant_f32_e32 v68, v65
	v_cmp_gt_f32_e32 vcc, s47, v68
	v_cvt_f64_f32_e32 v[68:69], v65
	v_frexp_exp_i32_f64_e32 v68, v[68:69]
	v_subbrev_co_u32_e32 v68, vcc, 0, v68, vcc
	v_sub_u32_e32 v69, 0, v68
	v_ldexp_f32 v65, v65, v69
	v_ldexp_f32 v69, v70, v69
	v_add_f32_e32 v70, -1.0, v65
	v_add_f32_e32 v71, 1.0, v70
	v_sub_f32_e32 v71, v65, v71
	v_add_f32_e32 v71, v69, v71
	v_add_f32_e32 v72, v70, v71
	v_sub_f32_e32 v70, v72, v70
	v_sub_f32_e32 v70, v71, v70
	v_add_f32_e32 v71, 1.0, v65
	v_add_f32_e32 v73, -1.0, v71
	v_sub_f32_e32 v65, v65, v73
	v_add_f32_e32 v65, v69, v65
	v_add_f32_e32 v69, v71, v65
	v_sub_f32_e32 v71, v69, v71
	v_sub_f32_e32 v65, v65, v71
	v_rcp_f32_e32 v71, v69
	v_cvt_f32_i32_e32 v68, v68
	v_cmp_neq_f32_e32 vcc, s49, v63
	v_mul_f32_e32 v73, v72, v71
	v_mul_f32_e32 v74, v69, v73
	v_fma_f32 v75, v73, v69, -v74
	v_fmac_f32_e32 v75, v73, v65
	v_add_f32_e32 v76, v74, v75
	v_sub_f32_e32 v77, v72, v76
	v_sub_f32_e32 v72, v72, v77
	v_sub_f32_e32 v74, v76, v74
	v_sub_f32_e32 v72, v72, v76
	v_add_f32_e32 v70, v70, v72
	v_sub_f32_e32 v72, v74, v75
	v_add_f32_e32 v70, v72, v70
	v_add_f32_e32 v72, v77, v70
	v_mul_f32_e32 v74, v71, v72
	v_mul_f32_e32 v75, v69, v74
	v_fma_f32 v69, v74, v69, -v75
	v_fmac_f32_e32 v69, v74, v65
	v_sub_f32_e32 v65, v77, v72
	v_add_f32_e32 v65, v70, v65
	v_add_f32_e32 v70, v75, v69
	v_sub_f32_e32 v76, v72, v70
	v_sub_f32_e32 v72, v72, v76
	v_sub_f32_e32 v75, v70, v75
	v_sub_f32_e32 v70, v72, v70
	v_add_f32_e32 v65, v65, v70
	v_sub_f32_e32 v69, v75, v69
	v_add_f32_e32 v65, v69, v65
	v_add_f32_e32 v69, v73, v74
	v_add_f32_e32 v65, v76, v65
	v_sub_f32_e32 v70, v69, v73
	v_mul_f32_e32 v65, v71, v65
	v_sub_f32_e32 v70, v74, v70
	v_add_f32_e32 v65, v70, v65
	v_mul_f32_e32 v73, 0x3f317218, v68
	v_add_f32_e32 v70, v69, v65
	v_fma_f32 v74, v68, s48, -v73
	v_mul_f32_e32 v71, v70, v70
	v_fmac_f32_e32 v74, 0xb102e308, v68
	v_sub_f32_e32 v68, v70, v69
	v_fmamk_f32 v72, v71, 0x3e9b6dac, v171
	v_sub_f32_e32 v65, v65, v68
	v_add_f32_e32 v68, v73, v74
	v_fmaak_f32 v72, v71, v72, 0x3f2aaada
	v_sub_f32_e32 v69, v68, v73
	v_ldexp_f32 v73, v70, 1
	v_mul_f32_e32 v70, v70, v71
	v_mul_f32_e32 v70, v70, v72
	v_add_f32_e32 v71, v73, v70
	v_sub_f32_e32 v72, v71, v73
	v_ldexp_f32 v65, v65, 1
	v_sub_f32_e32 v70, v70, v72
	v_add_f32_e32 v65, v65, v70
	v_add_f32_e32 v70, v71, v65
	v_sub_f32_e32 v71, v70, v71
	v_sub_f32_e32 v65, v65, v71
	v_add_f32_e32 v71, v68, v70
	v_sub_f32_e32 v72, v71, v68
	v_sub_f32_e32 v73, v71, v72
	v_sub_f32_e32 v69, v74, v69
	v_sub_f32_e32 v68, v68, v73
	v_sub_f32_e32 v70, v70, v72
	v_add_f32_e32 v68, v70, v68
	v_add_f32_e32 v70, v69, v65
	v_sub_f32_e32 v72, v70, v69
	v_sub_f32_e32 v73, v70, v72
	v_sub_f32_e32 v69, v69, v73
	v_sub_f32_e32 v65, v65, v72
	v_add_f32_e32 v68, v70, v68
	v_add_f32_e32 v65, v65, v69
	v_add_f32_e32 v69, v71, v68
	v_sub_f32_e32 v70, v69, v71
	v_sub_f32_e32 v68, v68, v70
	v_add_f32_e32 v65, v65, v68
	v_add_f32_e32 v65, v69, v65
	v_cndmask_b32_e32 v65, v178, v65, vcc
	v_cmp_ngt_f32_e32 vcc, -1.0, v63
	s_nop 1
	v_cndmask_b32_e32 v65, v179, v65, vcc
	v_cmp_neq_f32_e32 vcc, -1.0, v63
	s_nop 1
	v_cndmask_b32_e32 v65, v180, v65, vcc
	v_cmp_lt_f32_e64 vcc, |v63|, s50
	s_nop 1
	v_cndmask_b32_e32 v63, v65, v63, vcc
	v_sub_f32_e32 v62, v62, v63
	global_store_dword v[60:61], v62, off offset:-20
.LBB0_1313:
	s_andn2_saveexec_b64 s[2:3], s[2:3]
	s_cbranch_execz .LBB0_1315
	v_mul_f32_e32 v56, v56, v64
	v_mul_f32_e32 v57, v57, v64
	v_mul_f32_e32 v56, 0xbfb8aa3b, v56
	v_mul_f32_e32 v57, 0xbfb8aa3b, v57
	v_exp_f32_e32 v56, v56
	v_exp_f32_e32 v57, v57
	v_mul_f32_e32 v58, v58, v64
	v_mul_f32_e32 v59, v59, v64
	v_mul_f32_e32 v58, 0xbfb8aa3b, v58
	v_pk_add_f32 v[56:57], v[56:57], 1.0 op_sel_hi:[1,0]
	v_mul_f32_e32 v59, 0xbfb8aa3b, v59
	v_exp_f32_e32 v58, v58
	v_exp_f32_e32 v59, v59
	v_rcp_f32_e32 v57, v57
	v_pk_add_f32 v[58:59], v[58:59], 1.0 op_sel_hi:[1,0]
	v_rcp_f32_e32 v56, v56
	s_nop 0
	v_rcp_f32_e32 v59, v59
	s_nop 0
	v_rcp_f32_e32 v58, v58
	global_store_dwordx4 v[68:69], v[56:59], off offset:64

; DI float sigmoidf_(float x) { return 1.f / (1.f + __expf(-x)); }
; template <bool SWAP> DI void inproj_tile(const Params& p, int layer, int tm, int tn, bf16_t* smem) {
;     ...
;       for (int i = 0; i < 8; ++i) {
;         const int t = trow0 + i * 16 + l15; const float rs = rstd_from16(ssq + (size_t)t * 16, 1.f / 1024.f);
;         float* gt = (float*)(p.ws + O_GATES) + (size_t)t * 24; float* lf = (float*)(p.ws + O_LOGF) + (size_t)t * 8;
; #pragma unroll
;         for (int r = 0; r < 4; ++r) gt[quad * 4 + r] = sigmoidf_(acc[i][0][r] * rs);
;         if (quad < 2) {
; #pragma unroll
;           for (int r = 0; r < 4; ++r) gt[16 + quad * 4 + r] = sigmoidf_(acc[i][1][r] * rs);
;         } else {
; #pragma unroll
;           for (int r = 0; r < 4; ++r) { const int h = (quad - 2) * 4 + r; const float xx = acc[i][1][r] * rs + p.b_forget[layer * 8 + h]; lf[h] = fminf(xx, 0.f) - log1pf(__expf(-fabsf(xx))); }
;         }
.LrcA1_13:
	s_or_b64 exec, exec, s[98:99]
	s_waitcnt vmcnt(0)
	v_cndmask_b32_e64 v48, v249, v48, s[100:101]
	v_readlane_b32 s2, v240, 35
	v_readlane_b32 s3, v240, 36
	s_nop 1
	v_mov_b64_e32 v[50:51], s[2:3]
	v_mad_i64_i32 v[52:53], s[2:3], v64, s45, v[50:51]
	v_lshlrev_b64 v[50:51], 5, v[64:65]
	v_lshl_add_u64 v[52:53], v[52:53], 0, v[160:161]
	v_mul_f32_e32 v44, v44, v48
	v_mul_f32_e32 v45, v45, v48
	v_mul_f32_e32 v44, 0xbfb8aa3b, v44
	v_mul_f32_e32 v45, 0xbfb8aa3b, v45
	v_exp_f32_e32 v44, v44
	v_exp_f32_e32 v45, v45
	v_mul_f32_e32 v46, v46, v48
	v_mul_f32_e32 v47, v47, v48
	v_mul_f32_e32 v46, 0xbfb8aa3b, v46
	v_pk_add_f32 v[44:45], v[44:45], 1.0 op_sel_hi:[1,0]
	v_mul_f32_e32 v47, 0xbfb8aa3b, v47
	v_exp_f32_e32 v46, v46
	v_exp_f32_e32 v47, v47
	v_rcp_f32_e32 v45, v45
	v_pk_add_f32 v[46:47], v[46:47], 1.0 op_sel_hi:[1,0]
	v_rcp_f32_e32 v44, v44
	s_nop 0
	v_rcp_f32_e32 v47, v47
	s_nop 0
	v_rcp_f32_e32 v46, v46
	global_store_dwordx4 v[52:53], v[44:47], off
	s_and_saveexec_b64 s[2:3], s[4:5]
	s_xor_b64 s[2:3], exec, s[2:3]
	s_cbranch_execz .LBB0_1317
	v_readlane_b32 s52, v241, 8
	v_readlane_b32 s60, v241, 16
	v_readlane_b32 s61, v241, 17
	v_lshl_add_u64 v[44:45], s[8:9], 0, v[50:51]
	v_lshl_add_u64 v[44:45], v[44:45], 0, v[160:161]
	v_readlane_b32 s53, v241, 9
	v_readlane_b32 s54, v241, 10
	v_readlane_b32 s55, v241, 11
	global_load_dword v46, v160, s[60:61]
	v_readlane_b32 s56, v241, 12
	v_readlane_b32 s57, v241, 13
	v_readlane_b32 s58, v241, 14
	v_readlane_b32 s59, v241, 15
	v_readlane_b32 s62, v241, 18
	v_readlane_b32 s63, v241, 19
	v_readlane_b32 s64, v241, 20
	v_readlane_b32 s65, v241, 21
	v_readlane_b32 s66, v241, 22
	v_readlane_b32 s67, v241, 23
	s_waitcnt vmcnt(0)
	v_fmac_f32_e32 v46, v40, v48
	v_min_f32_e32 v49, 0, v46
	v_mul_f32_e64 v46, |v46|, s46
	v_exp_f32_e32 v52, v46
	s_nop 0
	v_add_f32_e32 v53, 1.0, v52
	v_add_f32_e32 v46, -1.0, v53
	v_sub_f32_e32 v47, v46, v53
	v_add_f32_e32 v47, 1.0, v47
	v_sub_f32_e32 v46, v52, v46
	v_add_f32_e32 v54, v46, v47
	v_frexp_mant_f32_e32 v46, v53
	v_cmp_gt_f32_e32 vcc, s47, v46
	v_cvt_f64_f32_e32 v[46:47], v53
	v_frexp_exp_i32_f64_e32 v46, v[46:47]
	v_subbrev_co_u32_e32 v46, vcc, 0, v46, vcc
	v_sub_u32_e32 v47, 0, v46
	v_ldexp_f32 v53, v53, v47
	v_ldexp_f32 v47, v54, v47
	v_add_f32_e32 v54, -1.0, v53
	v_add_f32_e32 v55, 1.0, v54
	v_sub_f32_e32 v55, v53, v55
	v_add_f32_e32 v55, v47, v55
	v_add_f32_e32 v56, v54, v55
	v_sub_f32_e32 v54, v56, v54
	v_sub_f32_e32 v54, v55, v54
	v_add_f32_e32 v55, 1.0, v53
	v_add_f32_e32 v57, -1.0, v55
	v_sub_f32_e32 v53, v53, v57
	v_add_f32_e32 v47, v47, v53
	v_add_f32_e32 v53, v55, v47
	v_sub_f32_e32 v55, v53, v55
	v_sub_f32_e32 v47, v47, v55
	v_rcp_f32_e32 v55, v53
	v_cvt_f32_i32_e32 v46, v46
	v_cmp_neq_f32_e32 vcc, s49, v52
	v_mul_f32_e32 v57, v56, v55
	v_mul_f32_e32 v58, v53, v57
	v_fma_f32 v59, v57, v53, -v58
	v_fmac_f32_e32 v59, v57, v47
	v_add_f32_e32 v60, v58, v59
	v_sub_f32_e32 v61, v56, v60
	v_sub_f32_e32 v56, v56, v61
	v_sub_f32_e32 v58, v60, v58
	v_sub_f32_e32 v56, v56, v60
	v_add_f32_e32 v54, v54, v56
	v_sub_f32_e32 v56, v58, v59
	v_add_f32_e32 v54, v56, v54
	v_add_f32_e32 v56, v61, v54
	v_mul_f32_e32 v58, v55, v56
	v_mul_f32_e32 v59, v53, v58
	v_fma_f32 v53, v58, v53, -v59
	v_fmac_f32_e32 v53, v58, v47
	v_sub_f32_e32 v47, v61, v56
	v_add_f32_e32 v47, v54, v47
	v_add_f32_e32 v54, v59, v53
	v_sub_f32_e32 v60, v56, v54
	v_sub_f32_e32 v56, v56, v60
	v_sub_f32_e32 v59, v54, v59
	v_sub_f32_e32 v54, v56, v54
	v_add_f32_e32 v47, v47, v54
	v_sub_f32_e32 v53, v59, v53
	v_add_f32_e32 v47, v53, v47
	v_add_f32_e32 v53, v57, v58
	v_add_f32_e32 v47, v60, v47
	v_sub_f32_e32 v54, v53, v57
	v_mul_f32_e32 v47, v55, v47
	v_sub_f32_e32 v54, v58, v54
	v_add_f32_e32 v47, v54, v47
	v_mul_f32_e32 v57, 0x3f317218, v46
	v_add_f32_e32 v54, v53, v47
	v_fma_f32 v58, v46, s48, -v57
	v_mul_f32_e32 v55, v54, v54
	v_fmac_f32_e32 v58, 0xb102e308, v46
	v_sub_f32_e32 v46, v54, v53
	v_fmamk_f32 v56, v55, 0x3e9b6dac, v171
	v_sub_f32_e32 v46, v47, v46
	v_add_f32_e32 v47, v57, v58
	v_fmaak_f32 v56, v55, v56, 0x3f2aaada
	v_sub_f32_e32 v53, v47, v57
	v_ldexp_f32 v57, v54, 1
	v_mul_f32_e32 v54, v54, v55
	v_mul_f32_e32 v54, v54, v56
	v_add_f32_e32 v55, v57, v54
	v_sub_f32_e32 v56, v55, v57
	v_ldexp_f32 v46, v46, 1
	v_sub_f32_e32 v54, v54, v56
	v_add_f32_e32 v46, v46, v54
	v_add_f32_e32 v54, v55, v46
	v_sub_f32_e32 v55, v54, v55
	v_sub_f32_e32 v46, v46, v55
	v_add_f32_e32 v55, v47, v54
	v_sub_f32_e32 v56, v55, v47
	v_sub_f32_e32 v57, v55, v56
	v_sub_f32_e32 v53, v58, v53
	v_sub_f32_e32 v47, v47, v57
	v_sub_f32_e32 v54, v54, v56
	v_add_f32_e32 v47, v54, v47
	v_add_f32_e32 v54, v53, v46
	v_sub_f32_e32 v56, v54, v53
	v_sub_f32_e32 v57, v54, v56
	v_sub_f32_e32 v53, v53, v57
	v_sub_f32_e32 v46, v46, v56
	v_add_f32_e32 v47, v54, v47
	v_add_f32_e32 v46, v46, v53
	v_add_f32_e32 v53, v55, v47
	v_sub_f32_e32 v54, v53, v55
	v_sub_f32_e32 v47, v47, v54
	v_add_f32_e32 v46, v46, v47
	v_add_f32_e32 v46, v53, v46
	v_cndmask_b32_e32 v46, v178, v46, vcc
	v_cmp_ngt_f32_e32 vcc, -1.0, v52
	s_nop 1
	v_cndmask_b32_e32 v46, v179, v46, vcc
	v_cmp_neq_f32_e32 vcc, -1.0, v52
	s_nop 1
	v_cndmask_b32_e32 v46, v180, v46, vcc
	v_cmp_lt_f32_e64 vcc, |v52|, s50
	s_nop 1
	v_cndmask_b32_e32 v46, v46, v52, vcc
	v_sub_f32_e32 v46, v49, v46
	global_store_dword v[44:45], v46, off offset:-32
	global_load_dword v47, v160, s[60:61] offset:4
	s_waitcnt vmcnt(0)
; template <bool SWAP> DI void inproj_tile(const Params& p, int layer, int tm, int tn, bf16_t* smem) {
;     ...
;           for (int r = 0; r < 4; ++r) { const int h = (quad - 2) * 4 + r; const float xx = acc[i][1][r] * rs + p.b_forget[layer * 8 + h]; lf[h] = fminf(xx, 0.f) - log1pf(__expf(-fabsf(xx))); }
	v_fmac_f32_e32 v47, v41, v48
	v_min_f32_e32 v46, 0, v47
	v_mul_f32_e64 v47, |v47|, s46
	v_exp_f32_e32 v47, v47
	s_nop 0
	v_add_f32_e32 v49, 1.0, v47
	v_add_f32_e32 v52, -1.0, v49
	v_sub_f32_e32 v53, v52, v49
	v_add_f32_e32 v53, 1.0, v53
	v_sub_f32_e32 v52, v47, v52
	v_add_f32_e32 v54, v52, v53
	v_frexp_mant_f32_e32 v52, v49
	v_cmp_gt_f32_e32 vcc, s47, v52
	v_cvt_f64_f32_e32 v[52:53], v49
	v_frexp_exp_i32_f64_e32 v52, v[52:53]
	v_subbrev_co_u32_e32 v52, vcc, 0, v52, vcc
	v_sub_u32_e32 v53, 0, v52
	v_ldexp_f32 v49, v49, v53
	v_ldexp_f32 v53, v54, v53
	v_add_f32_e32 v54, -1.0, v49
	v_add_f32_e32 v55, 1.0, v54
	v_sub_f32_e32 v55, v49, v55
	v_add_f32_e32 v55, v53, v55
	v_add_f32_e32 v56, v54, v55
	v_sub_f32_e32 v54, v56, v54
	v_sub_f32_e32 v54, v55, v54
	v_add_f32_e32 v55, 1.0, v49
	v_add_f32_e32 v57, -1.0, v55
	v_sub_f32_e32 v49, v49, v57
	v_add_f32_e32 v49, v53, v49
	v_add_f32_e32 v53, v55, v49
	v_sub_f32_e32 v55, v53, v55
	v_sub_f32_e32 v49, v49, v55
	v_rcp_f32_e32 v55, v53
	v_cvt_f32_i32_e32 v52, v52
	v_cmp_neq_f32_e32 vcc, s49, v47
	v_mul_f32_e32 v57, v56, v55
	v_mul_f32_e32 v58, v53, v57
	v_fma_f32 v59, v57, v53, -v58
	v_fmac_f32_e32 v59, v57, v49
	v_add_f32_e32 v60, v58, v59
	v_sub_f32_e32 v61, v56, v60
	v_sub_f32_e32 v56, v56, v61
	v_sub_f32_e32 v58, v60, v58
	v_sub_f32_e32 v56, v56, v60
	v_add_f32_e32 v54, v54, v56
	v_sub_f32_e32 v56, v58, v59
	v_add_f32_e32 v54, v56, v54
	v_add_f32_e32 v56, v61, v54
	v_mul_f32_e32 v58, v55, v56
	v_mul_f32_e32 v59, v53, v58
	v_fma_f32 v53, v58, v53, -v59
	v_fmac_f32_e32 v53, v58, v49
	v_sub_f32_e32 v49, v61, v56
	v_add_f32_e32 v49, v54, v49
	v_add_f32_e32 v54, v59, v53
	v_sub_f32_e32 v60, v56, v54
	v_sub_f32_e32 v56, v56, v60
	v_sub_f32_e32 v59, v54, v59
	v_sub_f32_e32 v54, v56, v54
	v_add_f32_e32 v49, v49, v54
	v_sub_f32_e32 v53, v59, v53
	v_add_f32_e32 v49, v53, v49
	v_add_f32_e32 v53, v57, v58
	v_add_f32_e32 v49, v60, v49
	v_sub_f32_e32 v54, v53, v57
	v_mul_f32_e32 v49, v55, v49
	v_sub_f32_e32 v54, v58, v54
	v_add_f32_e32 v49, v54, v49
	v_mul_f32_e32 v57, 0x3f317218, v52
	v_add_f32_e32 v54, v53, v49
	v_fma_f32 v58, v52, s48, -v57
	v_mul_f32_e32 v55, v54, v54
	v_fmac_f32_e32 v58, 0xb102e308, v52
	v_sub_f32_e32 v52, v54, v53
	v_fmamk_f32 v56, v55, 0x3e9b6dac, v171
	v_sub_f32_e32 v49, v49, v52
	v_add_f32_e32 v52, v57, v58
	v_fmaak_f32 v56, v55, v56, 0x3f2aaada
	v_sub_f32_e32 v53, v52, v57
	v_ldexp_f32 v57, v54, 1
	v_mul_f32_e32 v54, v54, v55
	v_mul_f32_e32 v54, v54, v56
	v_add_f32_e32 v55, v57, v54
	v_sub_f32_e32 v56, v55, v57
	v_ldexp_f32 v49, v49, 1
	v_sub_f32_e32 v54, v54, v56
	v_add_f32_e32 v49, v49, v54
	v_add_f32_e32 v54, v55, v49
	v_sub_f32_e32 v55, v54, v55
	v_sub_f32_e32 v49, v49, v55
	v_add_f32_e32 v55, v52, v54
	v_sub_f32_e32 v56, v55, v52
	v_sub_f32_e32 v57, v55, v56
	v_sub_f32_e32 v53, v58, v53
	v_sub_f32_e32 v52, v52, v57
	v_sub_f32_e32 v54, v54, v56
	v_add_f32_e32 v52, v54, v52
	v_add_f32_e32 v54, v53, v49
	v_sub_f32_e32 v56, v54, v53
	v_sub_f32_e32 v57, v54, v56
	v_sub_f32_e32 v53, v53, v57
	v_sub_f32_e32 v49, v49, v56
	v_add_f32_e32 v52, v54, v52
	v_add_f32_e32 v49, v49, v53
	v_add_f32_e32 v53, v55, v52
	v_sub_f32_e32 v54, v53, v55
	v_sub_f32_e32 v52, v52, v54
	v_add_f32_e32 v49, v49, v52
	v_add_f32_e32 v49, v53, v49
	v_cndmask_b32_e32 v49, v178, v49, vcc
	v_cmp_ngt_f32_e32 vcc, -1.0, v47
	s_nop 1
	v_cndmask_b32_e32 v49, v179, v49, vcc
	v_cmp_neq_f32_e32 vcc, -1.0, v47
	s_nop 1
	v_cndmask_b32_e32 v49, v180, v49, vcc
	v_cmp_lt_f32_e64 vcc, |v47|, s50
	s_nop 1
	v_cndmask_b32_e32 v47, v49, v47, vcc
	v_sub_f32_e32 v46, v46, v47
	global_store_dword v[44:45], v46, off offset:-28
	global_load_dword v47, v160, s[60:61] offset:8
	s_waitcnt vmcnt(0)
	v_fmac_f32_e32 v47, v42, v48
	v_min_f32_e32 v46, 0, v47
	v_mul_f32_e64 v47, |v47|, s46
	v_exp_f32_e32 v47, v47
	s_nop 0
	v_add_f32_e32 v49, 1.0, v47
	v_add_f32_e32 v52, -1.0, v49
	v_sub_f32_e32 v53, v52, v49
	v_add_f32_e32 v53, 1.0, v53
	v_sub_f32_e32 v52, v47, v52
	v_add_f32_e32 v54, v52, v53
	v_frexp_mant_f32_e32 v52, v49
	v_cmp_gt_f32_e32 vcc, s47, v52
	v_cvt_f64_f32_e32 v[52:53], v49
	v_frexp_exp_i32_f64_e32 v52, v[52:53]
	v_subbrev_co_u32_e32 v52, vcc, 0, v52, vcc
	v_sub_u32_e32 v53, 0, v52
	v_ldexp_f32 v49, v49, v53
	v_ldexp_f32 v53, v54, v53
	v_add_f32_e32 v54, -1.0, v49
	v_add_f32_e32 v55, 1.0, v54
	v_sub_f32_e32 v55, v49, v55
	v_add_f32_e32 v55, v53, v55
	v_add_f32_e32 v56, v54, v55
	v_sub_f32_e32 v54, v56, v54
	v_sub_f32_e32 v54, v55, v54
	v_add_f32_e32 v55, 1.0, v49
	v_add_f32_e32 v57, -1.0, v55
	v_sub_f32_e32 v49, v49, v57
	v_add_f32_e32 v49, v53, v49
	v_add_f32_e32 v53, v55, v49
	v_sub_f32_e32 v55, v53, v55
	v_sub_f32_e32 v49, v49, v55
	v_rcp_f32_e32 v55, v53
	v_cvt_f32_i32_e32 v52, v52
	v_cmp_neq_f32_e32 vcc, s49, v47
	v_mul_f32_e32 v57, v56, v55
	v_mul_f32_e32 v58, v53, v57
	v_fma_f32 v59, v57, v53, -v58
	v_fmac_f32_e32 v59, v57, v49
	v_add_f32_e32 v60, v58, v59
	v_sub_f32_e32 v61, v56, v60
	v_sub_f32_e32 v56, v56, v61
	v_sub_f32_e32 v58, v60, v58
	v_sub_f32_e32 v56, v56, v60
	v_add_f32_e32 v54, v54, v56
	v_sub_f32_e32 v56, v58, v59
	v_add_f32_e32 v54, v56, v54
	v_add_f32_e32 v56, v61, v54
	v_mul_f32_e32 v58, v55, v56
	v_mul_f32_e32 v59, v53, v58
	v_fma_f32 v53, v58, v53, -v59
	v_fmac_f32_e32 v53, v58, v49
	v_sub_f32_e32 v49, v61, v56
	v_add_f32_e32 v49, v54, v49
	v_add_f32_e32 v54, v59, v53
	v_sub_f32_e32 v60, v56, v54
	v_sub_f32_e32 v56, v56, v60
	v_sub_f32_e32 v59, v54, v59
	v_sub_f32_e32 v54, v56, v54
	v_add_f32_e32 v49, v49, v54
	v_sub_f32_e32 v53, v59, v53
	v_add_f32_e32 v49, v53, v49
	v_add_f32_e32 v53, v57, v58
	v_add_f32_e32 v49, v60, v49
	v_sub_f32_e32 v54, v53, v57
	v_mul_f32_e32 v49, v55, v49
	v_sub_f32_e32 v54, v58, v54
; DI float sigmoidf_(float x) { return 1.f / (1.f + __expf(-x)); }
; template <bool SWAP> DI void inproj_tile(const Params& p, int layer, int tm, int tn, bf16_t* smem) {
;     ...
;       for (int i = 0; i < 8; ++i) {
;         const int t = trow0 + i * 16 + l15; const float rs = rstd_from16(ssq + (size_t)t * 16, 1.f / 1024.f);
;         float* gt = (float*)(p.ws + O_GATES) + (size_t)t * 24; float* lf = (float*)(p.ws + O_LOGF) + (size_t)t * 8;
; #pragma unroll
;         for (int r = 0; r < 4; ++r) gt[quad * 4 + r] = sigmoidf_(acc[i][0][r] * rs);
;         if (quad < 2) {
; #pragma unroll
;           for (int r = 0; r < 4; ++r) gt[16 + quad * 4 + r] = sigmoidf_(acc[i][1][r] * rs);
;         } else {
; #pragma unroll
;           for (int r = 0; r < 4; ++r) { const int h = (quad - 2) * 4 + r; const float xx = acc[i][1][r] * rs + p.b_forget[layer * 8 + h]; lf[h] = fminf(xx, 0.f) - log1pf(__expf(-fabsf(xx))); }
;         }
	v_add_f32_e32 v49, v54, v49
	v_mul_f32_e32 v57, 0x3f317218, v52
	v_add_f32_e32 v54, v53, v49
	v_fma_f32 v58, v52, s48, -v57
	v_mul_f32_e32 v55, v54, v54
	v_fmac_f32_e32 v58, 0xb102e308, v52
	v_sub_f32_e32 v52, v54, v53
	v_fmamk_f32 v56, v55, 0x3e9b6dac, v171
	v_sub_f32_e32 v49, v49, v52
	v_add_f32_e32 v52, v57, v58
	v_fmaak_f32 v56, v55, v56, 0x3f2aaada
	v_sub_f32_e32 v53, v52, v57
	v_ldexp_f32 v57, v54, 1
	v_mul_f32_e32 v54, v54, v55
	v_mul_f32_e32 v54, v54, v56
	v_add_f32_e32 v55, v57, v54
	v_sub_f32_e32 v56, v55, v57
	v_ldexp_f32 v49, v49, 1
	v_sub_f32_e32 v54, v54, v56
	v_add_f32_e32 v49, v49, v54
	v_add_f32_e32 v54, v55, v49
	v_sub_f32_e32 v55, v54, v55
	v_sub_f32_e32 v49, v49, v55
	v_add_f32_e32 v55, v52, v54
	v_sub_f32_e32 v56, v55, v52
	v_sub_f32_e32 v57, v55, v56
	v_sub_f32_e32 v53, v58, v53
	v_sub_f32_e32 v52, v52, v57
	v_sub_f32_e32 v54, v54, v56
	v_add_f32_e32 v52, v54, v52
	v_add_f32_e32 v54, v53, v49
	v_sub_f32_e32 v56, v54, v53
	v_sub_f32_e32 v57, v54, v56
	v_sub_f32_e32 v53, v53, v57
	v_sub_f32_e32 v49, v49, v56
	v_add_f32_e32 v52, v54, v52
	v_add_f32_e32 v49, v49, v53
	v_add_f32_e32 v53, v55, v52
	v_sub_f32_e32 v54, v53, v55
	v_sub_f32_e32 v52, v52, v54
	v_add_f32_e32 v49, v49, v52
	v_add_f32_e32 v49, v53, v49
	v_cndmask_b32_e32 v49, v178, v49, vcc
	v_cmp_ngt_f32_e32 vcc, -1.0, v47
	s_nop 1
	v_cndmask_b32_e32 v49, v179, v49, vcc
	v_cmp_neq_f32_e32 vcc, -1.0, v47
	s_nop 1
	v_cndmask_b32_e32 v49, v180, v49, vcc
	v_cmp_lt_f32_e64 vcc, |v47|, s50
	s_nop 1
	v_cndmask_b32_e32 v47, v49, v47, vcc
	v_sub_f32_e32 v46, v46, v47
	global_store_dword v[44:45], v46, off offset:-24
	global_load_dword v47, v160, s[60:61] offset:12
	s_waitcnt vmcnt(0)
	v_fmac_f32_e32 v47, v43, v48
	v_min_f32_e32 v46, 0, v47
	v_mul_f32_e64 v47, |v47|, s46
	v_exp_f32_e32 v47, v47
	s_nop 0
	v_add_f32_e32 v49, 1.0, v47
	v_add_f32_e32 v52, -1.0, v49
	v_sub_f32_e32 v53, v52, v49
	v_add_f32_e32 v53, 1.0, v53
	v_sub_f32_e32 v52, v47, v52
	v_add_f32_e32 v54, v52, v53
	v_frexp_mant_f32_e32 v52, v49
	v_cmp_gt_f32_e32 vcc, s47, v52
	v_cvt_f64_f32_e32 v[52:53], v49
	v_frexp_exp_i32_f64_e32 v52, v[52:53]
	v_subbrev_co_u32_e32 v52, vcc, 0, v52, vcc
	v_sub_u32_e32 v53, 0, v52
	v_ldexp_f32 v49, v49, v53
	v_ldexp_f32 v53, v54, v53
	v_add_f32_e32 v54, -1.0, v49
	v_add_f32_e32 v55, 1.0, v54
	v_sub_f32_e32 v55, v49, v55
	v_add_f32_e32 v55, v53, v55
	v_add_f32_e32 v56, v54, v55
	v_sub_f32_e32 v54, v56, v54
	v_sub_f32_e32 v54, v55, v54
	v_add_f32_e32 v55, 1.0, v49
	v_add_f32_e32 v57, -1.0, v55
	v_sub_f32_e32 v49, v49, v57
	v_add_f32_e32 v49, v53, v49
	v_add_f32_e32 v53, v55, v49
	v_sub_f32_e32 v55, v53, v55
	v_sub_f32_e32 v49, v49, v55
	v_rcp_f32_e32 v55, v53
	v_cvt_f32_i32_e32 v52, v52
	v_cmp_neq_f32_e32 vcc, s49, v47
	v_mul_f32_e32 v57, v56, v55
	v_mul_f32_e32 v58, v53, v57
	v_fma_f32 v59, v57, v53, -v58
	v_fmac_f32_e32 v59, v57, v49
	v_add_f32_e32 v60, v58, v59
	v_sub_f32_e32 v61, v56, v60
	v_sub_f32_e32 v56, v56, v61
	v_sub_f32_e32 v58, v60, v58
	v_sub_f32_e32 v56, v56, v60
	v_add_f32_e32 v54, v54, v56
	v_sub_f32_e32 v56, v58, v59
	v_add_f32_e32 v54, v56, v54
	v_add_f32_e32 v56, v61, v54
	v_mul_f32_e32 v58, v55, v56
	v_mul_f32_e32 v59, v53, v58
	v_fma_f32 v53, v58, v53, -v59
	v_fmac_f32_e32 v53, v58, v49
	v_sub_f32_e32 v49, v61, v56
	v_add_f32_e32 v49, v54, v49
	v_add_f32_e32 v54, v59, v53
	v_sub_f32_e32 v60, v56, v54
	v_sub_f32_e32 v56, v56, v60
	v_sub_f32_e32 v59, v54, v59
	v_sub_f32_e32 v54, v56, v54
	v_add_f32_e32 v49, v49, v54
	v_sub_f32_e32 v53, v59, v53
	v_add_f32_e32 v49, v53, v49
	v_add_f32_e32 v53, v57, v58
	v_add_f32_e32 v49, v60, v49
	v_sub_f32_e32 v54, v53, v57
	v_mul_f32_e32 v49, v55, v49
	v_sub_f32_e32 v54, v58, v54
	v_add_f32_e32 v49, v54, v49
	v_mul_f32_e32 v57, 0x3f317218, v52
	v_add_f32_e32 v54, v53, v49
	v_fma_f32 v58, v52, s48, -v57
	v_mul_f32_e32 v55, v54, v54
	v_fmac_f32_e32 v58, 0xb102e308, v52
	v_sub_f32_e32 v52, v54, v53
	v_fmamk_f32 v56, v55, 0x3e9b6dac, v171
	v_sub_f32_e32 v49, v49, v52
	v_add_f32_e32 v52, v57, v58
	v_fmaak_f32 v56, v55, v56, 0x3f2aaada
	v_sub_f32_e32 v53, v52, v57
	v_ldexp_f32 v57, v54, 1
	v_mul_f32_e32 v54, v54, v55
	v_mul_f32_e32 v54, v54, v56
	v_add_f32_e32 v55, v57, v54
	v_sub_f32_e32 v56, v55, v57
	v_ldexp_f32 v49, v49, 1
	v_sub_f32_e32 v54, v54, v56
	v_add_f32_e32 v49, v49, v54
	v_add_f32_e32 v54, v55, v49
	v_sub_f32_e32 v55, v54, v55
	v_sub_f32_e32 v49, v49, v55
	v_add_f32_e32 v55, v52, v54
	v_sub_f32_e32 v56, v55, v52
	v_sub_f32_e32 v57, v55, v56
	v_sub_f32_e32 v53, v58, v53
	v_sub_f32_e32 v52, v52, v57
	v_sub_f32_e32 v54, v54, v56
	v_add_f32_e32 v52, v54, v52
	v_add_f32_e32 v54, v53, v49
	v_sub_f32_e32 v56, v54, v53
	v_sub_f32_e32 v57, v54, v56
	v_sub_f32_e32 v53, v53, v57
	v_sub_f32_e32 v49, v49, v56
	v_add_f32_e32 v52, v54, v52
	v_add_f32_e32 v49, v49, v53
	v_add_f32_e32 v53, v55, v52
	v_sub_f32_e32 v54, v53, v55
	v_sub_f32_e32 v52, v52, v54
	v_add_f32_e32 v49, v49, v52
	v_add_f32_e32 v49, v53, v49
	v_cndmask_b32_e32 v49, v178, v49, vcc
	v_cmp_ngt_f32_e32 vcc, -1.0, v47
	s_nop 1
	v_cndmask_b32_e32 v49, v179, v49, vcc
	v_cmp_neq_f32_e32 vcc, -1.0, v47
	s_nop 1
	v_cndmask_b32_e32 v49, v180, v49, vcc
	v_cmp_lt_f32_e64 vcc, |v47|, s50
	s_nop 1
	v_cndmask_b32_e32 v47, v49, v47, vcc
	v_sub_f32_e32 v46, v46, v47
	global_store_dword v[44:45], v46, off offset:-20
.LBB0_1317:
	s_andn2_saveexec_b64 s[2:3], s[2:3]
	s_cbranch_execz .LBB0_1319
	v_mul_f32_e32 v40, v40, v48
	v_mul_f32_e32 v41, v41, v48
	v_mul_f32_e32 v40, 0xbfb8aa3b, v40
	v_mul_f32_e32 v41, 0xbfb8aa3b, v41
	v_exp_f32_e32 v40, v40
	v_exp_f32_e32 v41, v41
	v_mul_f32_e32 v42, v42, v48
	v_mul_f32_e32 v43, v43, v48
	v_mul_f32_e32 v42, 0xbfb8aa3b, v42
	v_pk_add_f32 v[40:41], v[40:41], 1.0 op_sel_hi:[1,0]
	v_mul_f32_e32 v43, 0xbfb8aa3b, v43
	v_exp_f32_e32 v42, v42
	v_exp_f32_e32 v43, v43
	v_rcp_f32_e32 v41, v41
	v_pk_add_f32 v[42:43], v[42:43], 1.0 op_sel_hi:[1,0]
	v_rcp_f32_e32 v40, v40
	s_nop 0
	v_rcp_f32_e32 v43, v43
	s_nop 0
	v_rcp_f32_e32 v42, v42
	global_store_dwordx4 v[52:53], v[40:43], off offset:64

; DI float sigmoidf_(float x) { return 1.f / (1.f + __expf(-x)); }
; template <bool SWAP> DI void inproj_tile(const Params& p, int layer, int tm, int tn, bf16_t* smem) {
;     ...
;       for (int i = 0; i < 8; ++i) {
;         const int t = trow0 + i * 16 + l15; const float rs = rstd_from16(ssq + (size_t)t * 16, 1.f / 1024.f);
;         float* gt = (float*)(p.ws + O_GATES) + (size_t)t * 24; float* lf = (float*)(p.ws + O_LOGF) + (size_t)t * 8;
; #pragma unroll
;         for (int r = 0; r < 4; ++r) gt[quad * 4 + r] = sigmoidf_(acc[i][0][r] * rs);
;         if (quad < 2) {
; #pragma unroll
;           for (int r = 0; r < 4; ++r) gt[16 + quad * 4 + r] = sigmoidf_(acc[i][1][r] * rs);
;         } else {
; #pragma unroll
;           for (int r = 0; r < 4; ++r) { const int h = (quad - 2) * 4 + r; const float xx = acc[i][1][r] * rs + p.b_forget[layer * 8 + h]; lf[h] = fminf(xx, 0.f) - log1pf(__expf(-fabsf(xx))); }
;         }
.LrcA1_14:
	s_or_b64 exec, exec, s[98:99]
	s_waitcnt vmcnt(0)
	v_cndmask_b32_e64 v32, v249, v32, s[100:101]
	v_readlane_b32 s2, v240, 35
	v_readlane_b32 s3, v240, 36
	s_nop 1
	v_mov_b64_e32 v[34:35], s[2:3]
	v_mad_i64_i32 v[36:37], s[2:3], v48, s45, v[34:35]
	v_lshlrev_b64 v[34:35], 5, v[48:49]
	v_lshl_add_u64 v[36:37], v[36:37], 0, v[160:161]
	v_mul_f32_e32 v28, v28, v32
	v_mul_f32_e32 v29, v29, v32
	v_mul_f32_e32 v28, 0xbfb8aa3b, v28
	v_mul_f32_e32 v29, 0xbfb8aa3b, v29
	v_exp_f32_e32 v28, v28
	v_exp_f32_e32 v29, v29
	v_mul_f32_e32 v30, v30, v32
	v_mul_f32_e32 v31, v31, v32
	v_mul_f32_e32 v30, 0xbfb8aa3b, v30
	v_pk_add_f32 v[28:29], v[28:29], 1.0 op_sel_hi:[1,0]
	v_mul_f32_e32 v31, 0xbfb8aa3b, v31
	v_exp_f32_e32 v30, v30
	v_exp_f32_e32 v31, v31
	v_rcp_f32_e32 v29, v29
	v_pk_add_f32 v[30:31], v[30:31], 1.0 op_sel_hi:[1,0]
	v_rcp_f32_e32 v28, v28
	s_nop 0
	v_rcp_f32_e32 v31, v31
	s_nop 0
	v_rcp_f32_e32 v30, v30
	global_store_dwordx4 v[36:37], v[28:31], off
	s_and_saveexec_b64 s[2:3], s[4:5]
	s_xor_b64 s[2:3], exec, s[2:3]
	s_cbranch_execz .LBB0_1321
	v_readlane_b32 s52, v241, 8
	v_readlane_b32 s60, v241, 16
	v_readlane_b32 s61, v241, 17
	v_lshl_add_u64 v[28:29], s[8:9], 0, v[34:35]
	v_lshl_add_u64 v[28:29], v[28:29], 0, v[160:161]
	v_readlane_b32 s53, v241, 9
	v_readlane_b32 s54, v241, 10
	v_readlane_b32 s55, v241, 11
	global_load_dword v30, v160, s[60:61]
	v_readlane_b32 s56, v241, 12
	v_readlane_b32 s57, v241, 13
	v_readlane_b32 s58, v241, 14
	v_readlane_b32 s59, v241, 15
	v_readlane_b32 s62, v241, 18
	v_readlane_b32 s63, v241, 19
	v_readlane_b32 s64, v241, 20
	v_readlane_b32 s65, v241, 21
	v_readlane_b32 s66, v241, 22
	v_readlane_b32 s67, v241, 23
	s_waitcnt vmcnt(0)
	v_fmac_f32_e32 v30, v24, v32
	v_min_f32_e32 v33, 0, v30
	v_mul_f32_e64 v30, |v30|, s46
	v_exp_f32_e32 v36, v30
	s_nop 0
	v_add_f32_e32 v37, 1.0, v36
	v_add_f32_e32 v30, -1.0, v37
	v_sub_f32_e32 v31, v30, v37
	v_add_f32_e32 v31, 1.0, v31
	v_sub_f32_e32 v30, v36, v30
	v_add_f32_e32 v38, v30, v31
	v_frexp_mant_f32_e32 v30, v37
	v_cmp_gt_f32_e32 vcc, s47, v30
	v_cvt_f64_f32_e32 v[30:31], v37
	v_frexp_exp_i32_f64_e32 v30, v[30:31]
	v_subbrev_co_u32_e32 v30, vcc, 0, v30, vcc
	v_sub_u32_e32 v31, 0, v30
	v_ldexp_f32 v37, v37, v31
	v_ldexp_f32 v31, v38, v31
	v_add_f32_e32 v38, -1.0, v37
	v_add_f32_e32 v39, 1.0, v38
	v_sub_f32_e32 v39, v37, v39
	v_add_f32_e32 v39, v31, v39
	v_add_f32_e32 v40, v38, v39
	v_sub_f32_e32 v38, v40, v38
	v_sub_f32_e32 v38, v39, v38
	v_add_f32_e32 v39, 1.0, v37
	v_add_f32_e32 v41, -1.0, v39
	v_sub_f32_e32 v37, v37, v41
	v_add_f32_e32 v31, v31, v37
	v_add_f32_e32 v37, v39, v31
	v_sub_f32_e32 v39, v37, v39
	v_sub_f32_e32 v31, v31, v39
	v_rcp_f32_e32 v39, v37
	v_cvt_f32_i32_e32 v30, v30
	v_cmp_neq_f32_e32 vcc, s49, v36
	v_mul_f32_e32 v41, v40, v39
	v_mul_f32_e32 v42, v37, v41
	v_fma_f32 v43, v41, v37, -v42
	v_fmac_f32_e32 v43, v41, v31
	v_add_f32_e32 v44, v42, v43
	v_sub_f32_e32 v45, v40, v44
	v_sub_f32_e32 v40, v40, v45
	v_sub_f32_e32 v42, v44, v42
	v_sub_f32_e32 v40, v40, v44
	v_add_f32_e32 v38, v38, v40
	v_sub_f32_e32 v40, v42, v43
	v_add_f32_e32 v38, v40, v38
	v_add_f32_e32 v40, v45, v38
	v_mul_f32_e32 v42, v39, v40
	v_mul_f32_e32 v43, v37, v42
	v_fma_f32 v37, v42, v37, -v43
	v_fmac_f32_e32 v37, v42, v31
	v_sub_f32_e32 v31, v45, v40
	v_add_f32_e32 v31, v38, v31
	v_add_f32_e32 v38, v43, v37
	v_sub_f32_e32 v44, v40, v38
	v_sub_f32_e32 v40, v40, v44
	v_sub_f32_e32 v43, v38, v43
	v_sub_f32_e32 v38, v40, v38
	v_add_f32_e32 v31, v31, v38
	v_sub_f32_e32 v37, v43, v37
	v_add_f32_e32 v31, v37, v31
	v_add_f32_e32 v37, v41, v42
	v_add_f32_e32 v31, v44, v31
	v_sub_f32_e32 v38, v37, v41
	v_mul_f32_e32 v31, v39, v31
	v_sub_f32_e32 v38, v42, v38
	v_add_f32_e32 v31, v38, v31
	v_mul_f32_e32 v41, 0x3f317218, v30
	v_add_f32_e32 v38, v37, v31
	v_fma_f32 v42, v30, s48, -v41
	v_mul_f32_e32 v39, v38, v38
	v_fmac_f32_e32 v42, 0xb102e308, v30
	v_sub_f32_e32 v30, v38, v37
	v_fmamk_f32 v40, v39, 0x3e9b6dac, v171
	v_sub_f32_e32 v30, v31, v30
	v_add_f32_e32 v31, v41, v42
	v_fmaak_f32 v40, v39, v40, 0x3f2aaada
	v_sub_f32_e32 v37, v31, v41
	v_ldexp_f32 v41, v38, 1
	v_mul_f32_e32 v38, v38, v39
	v_mul_f32_e32 v38, v38, v40
	v_add_f32_e32 v39, v41, v38
	v_sub_f32_e32 v40, v39, v41
	v_ldexp_f32 v30, v30, 1
	v_sub_f32_e32 v38, v38, v40
	v_add_f32_e32 v30, v30, v38
	v_add_f32_e32 v38, v39, v30
	v_sub_f32_e32 v39, v38, v39
	v_sub_f32_e32 v30, v30, v39
	v_add_f32_e32 v39, v31, v38
	v_sub_f32_e32 v40, v39, v31
	v_sub_f32_e32 v41, v39, v40
	v_sub_f32_e32 v37, v42, v37
	v_sub_f32_e32 v31, v31, v41
	v_sub_f32_e32 v38, v38, v40
	v_add_f32_e32 v31, v38, v31
	v_add_f32_e32 v38, v37, v30
	v_sub_f32_e32 v40, v38, v37
	v_sub_f32_e32 v41, v38, v40
	v_sub_f32_e32 v37, v37, v41
	v_sub_f32_e32 v30, v30, v40
	v_add_f32_e32 v31, v38, v31
	v_add_f32_e32 v30, v30, v37
	v_add_f32_e32 v37, v39, v31
	v_sub_f32_e32 v38, v37, v39
	v_sub_f32_e32 v31, v31, v38
	v_add_f32_e32 v30, v30, v31
	v_add_f32_e32 v30, v37, v30
	v_cndmask_b32_e32 v30, v178, v30, vcc
	v_cmp_ngt_f32_e32 vcc, -1.0, v36
	s_nop 1
	v_cndmask_b32_e32 v30, v179, v30, vcc
	v_cmp_neq_f32_e32 vcc, -1.0, v36
	s_nop 1
	v_cndmask_b32_e32 v30, v180, v30, vcc
	v_cmp_lt_f32_e64 vcc, |v36|, s50
	s_nop 1
	v_cndmask_b32_e32 v30, v30, v36, vcc
	v_sub_f32_e32 v30, v33, v30
	global_store_dword v[28:29], v30, off offset:-32
	global_load_dword v31, v160, s[60:61] offset:4
	s_waitcnt vmcnt(0)
; template <bool SWAP> DI void inproj_tile(const Params& p, int layer, int tm, int tn, bf16_t* smem) {
;     ...
;           for (int r = 0; r < 4; ++r) { const int h = (quad - 2) * 4 + r; const float xx = acc[i][1][r] * rs + p.b_forget[layer * 8 + h]; lf[h] = fminf(xx, 0.f) - log1pf(__expf(-fabsf(xx))); }
	v_fmac_f32_e32 v31, v25, v32
	v_min_f32_e32 v30, 0, v31
	v_mul_f32_e64 v31, |v31|, s46
	v_exp_f32_e32 v31, v31
	s_nop 0
	v_add_f32_e32 v33, 1.0, v31
	v_add_f32_e32 v36, -1.0, v33
	v_sub_f32_e32 v37, v36, v33
	v_add_f32_e32 v37, 1.0, v37
	v_sub_f32_e32 v36, v31, v36
	v_add_f32_e32 v38, v36, v37
	v_frexp_mant_f32_e32 v36, v33
	v_cmp_gt_f32_e32 vcc, s47, v36
	v_cvt_f64_f32_e32 v[36:37], v33
	v_frexp_exp_i32_f64_e32 v36, v[36:37]
	v_subbrev_co_u32_e32 v36, vcc, 0, v36, vcc
	v_sub_u32_e32 v37, 0, v36
	v_ldexp_f32 v33, v33, v37
	v_ldexp_f32 v37, v38, v37
	v_add_f32_e32 v38, -1.0, v33
	v_add_f32_e32 v39, 1.0, v38
	v_sub_f32_e32 v39, v33, v39
	v_add_f32_e32 v39, v37, v39
	v_add_f32_e32 v40, v38, v39
	v_sub_f32_e32 v38, v40, v38
	v_sub_f32_e32 v38, v39, v38
	v_add_f32_e32 v39, 1.0, v33
	v_add_f32_e32 v41, -1.0, v39
	v_sub_f32_e32 v33, v33, v41
	v_add_f32_e32 v33, v37, v33
	v_add_f32_e32 v37, v39, v33
	v_sub_f32_e32 v39, v37, v39
	v_sub_f32_e32 v33, v33, v39
	v_rcp_f32_e32 v39, v37
	v_cvt_f32_i32_e32 v36, v36
	v_cmp_neq_f32_e32 vcc, s49, v31
	v_mul_f32_e32 v41, v40, v39
	v_mul_f32_e32 v42, v37, v41
	v_fma_f32 v43, v41, v37, -v42
	v_fmac_f32_e32 v43, v41, v33
	v_add_f32_e32 v44, v42, v43
	v_sub_f32_e32 v45, v40, v44
	v_sub_f32_e32 v40, v40, v45
	v_sub_f32_e32 v42, v44, v42
	v_sub_f32_e32 v40, v40, v44
	v_add_f32_e32 v38, v38, v40
	v_sub_f32_e32 v40, v42, v43
	v_add_f32_e32 v38, v40, v38
	v_add_f32_e32 v40, v45, v38
	v_mul_f32_e32 v42, v39, v40
	v_mul_f32_e32 v43, v37, v42
	v_fma_f32 v37, v42, v37, -v43
	v_fmac_f32_e32 v37, v42, v33
	v_sub_f32_e32 v33, v45, v40
	v_add_f32_e32 v33, v38, v33
	v_add_f32_e32 v38, v43, v37
	v_sub_f32_e32 v44, v40, v38
	v_sub_f32_e32 v40, v40, v44
	v_sub_f32_e32 v43, v38, v43
	v_sub_f32_e32 v38, v40, v38
	v_add_f32_e32 v33, v33, v38
	v_sub_f32_e32 v37, v43, v37
	v_add_f32_e32 v33, v37, v33
	v_add_f32_e32 v37, v41, v42
	v_add_f32_e32 v33, v44, v33
	v_sub_f32_e32 v38, v37, v41
	v_mul_f32_e32 v33, v39, v33
	v_sub_f32_e32 v38, v42, v38
	v_add_f32_e32 v33, v38, v33
	v_mul_f32_e32 v41, 0x3f317218, v36
	v_add_f32_e32 v38, v37, v33
	v_fma_f32 v42, v36, s48, -v41
	v_mul_f32_e32 v39, v38, v38
	v_fmac_f32_e32 v42, 0xb102e308, v36
	v_sub_f32_e32 v36, v38, v37
	v_fmamk_f32 v40, v39, 0x3e9b6dac, v171
	v_sub_f32_e32 v33, v33, v36
	v_add_f32_e32 v36, v41, v42
	v_fmaak_f32 v40, v39, v40, 0x3f2aaada
	v_sub_f32_e32 v37, v36, v41
	v_ldexp_f32 v41, v38, 1
	v_mul_f32_e32 v38, v38, v39
	v_mul_f32_e32 v38, v38, v40
	v_add_f32_e32 v39, v41, v38
	v_sub_f32_e32 v40, v39, v41
	v_ldexp_f32 v33, v33, 1
	v_sub_f32_e32 v38, v38, v40
	v_add_f32_e32 v33, v33, v38
	v_add_f32_e32 v38, v39, v33
	v_sub_f32_e32 v39, v38, v39
	v_sub_f32_e32 v33, v33, v39
	v_add_f32_e32 v39, v36, v38
	v_sub_f32_e32 v40, v39, v36
	v_sub_f32_e32 v41, v39, v40
	v_sub_f32_e32 v37, v42, v37
	v_sub_f32_e32 v36, v36, v41
	v_sub_f32_e32 v38, v38, v40
	v_add_f32_e32 v36, v38, v36
	v_add_f32_e32 v38, v37, v33
	v_sub_f32_e32 v40, v38, v37
	v_sub_f32_e32 v41, v38, v40
	v_sub_f32_e32 v37, v37, v41
	v_sub_f32_e32 v33, v33, v40
	v_add_f32_e32 v36, v38, v36
	v_add_f32_e32 v33, v33, v37
	v_add_f32_e32 v37, v39, v36
	v_sub_f32_e32 v38, v37, v39
	v_sub_f32_e32 v36, v36, v38
	v_add_f32_e32 v33, v33, v36
	v_add_f32_e32 v33, v37, v33
	v_cndmask_b32_e32 v33, v178, v33, vcc
	v_cmp_ngt_f32_e32 vcc, -1.0, v31
	s_nop 1
	v_cndmask_b32_e32 v33, v179, v33, vcc
	v_cmp_neq_f32_e32 vcc, -1.0, v31
	s_nop 1
	v_cndmask_b32_e32 v33, v180, v33, vcc
	v_cmp_lt_f32_e64 vcc, |v31|, s50
	s_nop 1
	v_cndmask_b32_e32 v31, v33, v31, vcc
	v_sub_f32_e32 v30, v30, v31
	global_store_dword v[28:29], v30, off offset:-28
	global_load_dword v31, v160, s[60:61] offset:8
	s_waitcnt vmcnt(0)
	v_fmac_f32_e32 v31, v26, v32
	v_min_f32_e32 v30, 0, v31
	v_mul_f32_e64 v31, |v31|, s46
	v_exp_f32_e32 v31, v31
	s_nop 0
	v_add_f32_e32 v33, 1.0, v31
	v_add_f32_e32 v36, -1.0, v33
	v_sub_f32_e32 v37, v36, v33
	v_add_f32_e32 v37, 1.0, v37
	v_sub_f32_e32 v36, v31, v36
	v_add_f32_e32 v38, v36, v37
	v_frexp_mant_f32_e32 v36, v33
	v_cmp_gt_f32_e32 vcc, s47, v36
	v_cvt_f64_f32_e32 v[36:37], v33
	v_frexp_exp_i32_f64_e32 v36, v[36:37]
	v_subbrev_co_u32_e32 v36, vcc, 0, v36, vcc
	v_sub_u32_e32 v37, 0, v36
	v_ldexp_f32 v33, v33, v37
	v_ldexp_f32 v37, v38, v37
	v_add_f32_e32 v38, -1.0, v33
	v_add_f32_e32 v39, 1.0, v38
	v_sub_f32_e32 v39, v33, v39
	v_add_f32_e32 v39, v37, v39
	v_add_f32_e32 v40, v38, v39
	v_sub_f32_e32 v38, v40, v38
	v_sub_f32_e32 v38, v39, v38
	v_add_f32_e32 v39, 1.0, v33
	v_add_f32_e32 v41, -1.0, v39
	v_sub_f32_e32 v33, v33, v41
	v_add_f32_e32 v33, v37, v33
	v_add_f32_e32 v37, v39, v33
	v_sub_f32_e32 v39, v37, v39
	v_sub_f32_e32 v33, v33, v39
	v_rcp_f32_e32 v39, v37
	v_cvt_f32_i32_e32 v36, v36
	v_cmp_neq_f32_e32 vcc, s49, v31
	v_mul_f32_e32 v41, v40, v39
	v_mul_f32_e32 v42, v37, v41
	v_fma_f32 v43, v41, v37, -v42
	v_fmac_f32_e32 v43, v41, v33
	v_add_f32_e32 v44, v42, v43
	v_sub_f32_e32 v45, v40, v44
	v_sub_f32_e32 v40, v40, v45
	v_sub_f32_e32 v42, v44, v42
	v_sub_f32_e32 v40, v40, v44
	v_add_f32_e32 v38, v38, v40
	v_sub_f32_e32 v40, v42, v43
	v_add_f32_e32 v38, v40, v38
	v_add_f32_e32 v40, v45, v38
	v_mul_f32_e32 v42, v39, v40
	v_mul_f32_e32 v43, v37, v42
	v_fma_f32 v37, v42, v37, -v43
	v_fmac_f32_e32 v37, v42, v33
	v_sub_f32_e32 v33, v45, v40
	v_add_f32_e32 v33, v38, v33
	v_add_f32_e32 v38, v43, v37
	v_sub_f32_e32 v44, v40, v38
	v_sub_f32_e32 v40, v40, v44
	v_sub_f32_e32 v43, v38, v43
	v_sub_f32_e32 v38, v40, v38
	v_add_f32_e32 v33, v33, v38
	v_sub_f32_e32 v37, v43, v37
	v_add_f32_e32 v33, v37, v33
	v_add_f32_e32 v37, v41, v42
	v_add_f32_e32 v33, v44, v33
	v_sub_f32_e32 v38, v37, v41
	v_mul_f32_e32 v33, v39, v33
	v_sub_f32_e32 v38, v42, v38
; DI float sigmoidf_(float x) { return 1.f / (1.f + __expf(-x)); }
; template <bool SWAP> DI void inproj_tile(const Params& p, int layer, int tm, int tn, bf16_t* smem) {
;     ...
;       for (int i = 0; i < 8; ++i) {
;         const int t = trow0 + i * 16 + l15; const float rs = rstd_from16(ssq + (size_t)t * 16, 1.f / 1024.f);
;         float* gt = (float*)(p.ws + O_GATES) + (size_t)t * 24; float* lf = (float*)(p.ws + O_LOGF) + (size_t)t * 8;
; #pragma unroll
;         for (int r = 0; r < 4; ++r) gt[quad * 4 + r] = sigmoidf_(acc[i][0][r] * rs);
;         if (quad < 2) {
; #pragma unroll
;           for (int r = 0; r < 4; ++r) gt[16 + quad * 4 + r] = sigmoidf_(acc[i][1][r] * rs);
;         } else {
; #pragma unroll
;           for (int r = 0; r < 4; ++r) { const int h = (quad - 2) * 4 + r; const float xx = acc[i][1][r] * rs + p.b_forget[layer * 8 + h]; lf[h] = fminf(xx, 0.f) - log1pf(__expf(-fabsf(xx))); }
;         }
	v_add_f32_e32 v33, v38, v33
	v_mul_f32_e32 v41, 0x3f317218, v36
	v_add_f32_e32 v38, v37, v33
	v_fma_f32 v42, v36, s48, -v41
	v_mul_f32_e32 v39, v38, v38
	v_fmac_f32_e32 v42, 0xb102e308, v36
	v_sub_f32_e32 v36, v38, v37
	v_fmamk_f32 v40, v39, 0x3e9b6dac, v171
	v_sub_f32_e32 v33, v33, v36
	v_add_f32_e32 v36, v41, v42
	v_fmaak_f32 v40, v39, v40, 0x3f2aaada
	v_sub_f32_e32 v37, v36, v41
	v_ldexp_f32 v41, v38, 1
	v_mul_f32_e32 v38, v38, v39
	v_mul_f32_e32 v38, v38, v40
	v_add_f32_e32 v39, v41, v38
	v_sub_f32_e32 v40, v39, v41
	v_ldexp_f32 v33, v33, 1
	v_sub_f32_e32 v38, v38, v40
	v_add_f32_e32 v33, v33, v38
	v_add_f32_e32 v38, v39, v33
	v_sub_f32_e32 v39, v38, v39
	v_sub_f32_e32 v33, v33, v39
	v_add_f32_e32 v39, v36, v38
	v_sub_f32_e32 v40, v39, v36
	v_sub_f32_e32 v41, v39, v40
	v_sub_f32_e32 v37, v42, v37
	v_sub_f32_e32 v36, v36, v41
	v_sub_f32_e32 v38, v38, v40
	v_add_f32_e32 v36, v38, v36
	v_add_f32_e32 v38, v37, v33
	v_sub_f32_e32 v40, v38, v37
	v_sub_f32_e32 v41, v38, v40
	v_sub_f32_e32 v37, v37, v41
	v_sub_f32_e32 v33, v33, v40
	v_add_f32_e32 v36, v38, v36
	v_add_f32_e32 v33, v33, v37
	v_add_f32_e32 v37, v39, v36
	v_sub_f32_e32 v38, v37, v39
	v_sub_f32_e32 v36, v36, v38
	v_add_f32_e32 v33, v33, v36
	v_add_f32_e32 v33, v37, v33
	v_cndmask_b32_e32 v33, v178, v33, vcc
	v_cmp_ngt_f32_e32 vcc, -1.0, v31
	s_nop 1
	v_cndmask_b32_e32 v33, v179, v33, vcc
	v_cmp_neq_f32_e32 vcc, -1.0, v31
	s_nop 1
	v_cndmask_b32_e32 v33, v180, v33, vcc
	v_cmp_lt_f32_e64 vcc, |v31|, s50
	s_nop 1
	v_cndmask_b32_e32 v31, v33, v31, vcc
	v_sub_f32_e32 v30, v30, v31
	global_store_dword v[28:29], v30, off offset:-24
	global_load_dword v31, v160, s[60:61] offset:12
	s_waitcnt vmcnt(0)
	v_fmac_f32_e32 v31, v27, v32
	v_min_f32_e32 v30, 0, v31
	v_mul_f32_e64 v31, |v31|, s46
	v_exp_f32_e32 v31, v31
	s_nop 0
	v_add_f32_e32 v33, 1.0, v31
	v_add_f32_e32 v36, -1.0, v33
	v_sub_f32_e32 v37, v36, v33
	v_add_f32_e32 v37, 1.0, v37
	v_sub_f32_e32 v36, v31, v36
	v_add_f32_e32 v38, v36, v37
	v_frexp_mant_f32_e32 v36, v33
	v_cmp_gt_f32_e32 vcc, s47, v36
	v_cvt_f64_f32_e32 v[36:37], v33
	v_frexp_exp_i32_f64_e32 v36, v[36:37]
	v_subbrev_co_u32_e32 v36, vcc, 0, v36, vcc
	v_sub_u32_e32 v37, 0, v36
	v_ldexp_f32 v33, v33, v37
	v_ldexp_f32 v37, v38, v37
	v_add_f32_e32 v38, -1.0, v33
	v_add_f32_e32 v39, 1.0, v38
	v_sub_f32_e32 v39, v33, v39
	v_add_f32_e32 v39, v37, v39
	v_add_f32_e32 v40, v38, v39
	v_sub_f32_e32 v38, v40, v38
	v_sub_f32_e32 v38, v39, v38
	v_add_f32_e32 v39, 1.0, v33
	v_add_f32_e32 v41, -1.0, v39
	v_sub_f32_e32 v33, v33, v41
	v_add_f32_e32 v33, v37, v33
	v_add_f32_e32 v37, v39, v33
	v_sub_f32_e32 v39, v37, v39
	v_sub_f32_e32 v33, v33, v39
	v_rcp_f32_e32 v39, v37
	v_cvt_f32_i32_e32 v36, v36
	v_cmp_neq_f32_e32 vcc, s49, v31
	v_mul_f32_e32 v41, v40, v39
	v_mul_f32_e32 v42, v37, v41
	v_fma_f32 v43, v41, v37, -v42
	v_fmac_f32_e32 v43, v41, v33
	v_add_f32_e32 v44, v42, v43
	v_sub_f32_e32 v45, v40, v44
	v_sub_f32_e32 v40, v40, v45
	v_sub_f32_e32 v42, v44, v42
	v_sub_f32_e32 v40, v40, v44
	v_add_f32_e32 v38, v38, v40
	v_sub_f32_e32 v40, v42, v43
	v_add_f32_e32 v38, v40, v38
	v_add_f32_e32 v40, v45, v38
	v_mul_f32_e32 v42, v39, v40
	v_mul_f32_e32 v43, v37, v42
	v_fma_f32 v37, v42, v37, -v43
	v_fmac_f32_e32 v37, v42, v33
	v_sub_f32_e32 v33, v45, v40
	v_add_f32_e32 v33, v38, v33
	v_add_f32_e32 v38, v43, v37
	v_sub_f32_e32 v44, v40, v38
	v_sub_f32_e32 v40, v40, v44
	v_sub_f32_e32 v43, v38, v43
	v_sub_f32_e32 v38, v40, v38
	v_add_f32_e32 v33, v33, v38
	v_sub_f32_e32 v37, v43, v37
	v_add_f32_e32 v33, v37, v33
	v_add_f32_e32 v37, v41, v42
	v_add_f32_e32 v33, v44, v33
	v_sub_f32_e32 v38, v37, v41
	v_mul_f32_e32 v33, v39, v33
	v_sub_f32_e32 v38, v42, v38
	v_add_f32_e32 v33, v38, v33
	v_mul_f32_e32 v41, 0x3f317218, v36
	v_add_f32_e32 v38, v37, v33
	v_fma_f32 v42, v36, s48, -v41
	v_mul_f32_e32 v39, v38, v38
	v_fmac_f32_e32 v42, 0xb102e308, v36
	v_sub_f32_e32 v36, v38, v37
	v_fmamk_f32 v40, v39, 0x3e9b6dac, v171
	v_sub_f32_e32 v33, v33, v36
	v_add_f32_e32 v36, v41, v42
	v_fmaak_f32 v40, v39, v40, 0x3f2aaada
	v_sub_f32_e32 v37, v36, v41
	v_ldexp_f32 v41, v38, 1
	v_mul_f32_e32 v38, v38, v39
	v_mul_f32_e32 v38, v38, v40
	v_add_f32_e32 v39, v41, v38
	v_sub_f32_e32 v40, v39, v41
	v_ldexp_f32 v33, v33, 1
	v_sub_f32_e32 v38, v38, v40
	v_add_f32_e32 v33, v33, v38
	v_add_f32_e32 v38, v39, v33
	v_sub_f32_e32 v39, v38, v39
	v_sub_f32_e32 v33, v33, v39
	v_add_f32_e32 v39, v36, v38
	v_sub_f32_e32 v40, v39, v36
	v_sub_f32_e32 v41, v39, v40
	v_sub_f32_e32 v37, v42, v37
	v_sub_f32_e32 v36, v36, v41
	v_sub_f32_e32 v38, v38, v40
	v_add_f32_e32 v36, v38, v36
	v_add_f32_e32 v38, v37, v33
	v_sub_f32_e32 v40, v38, v37
	v_sub_f32_e32 v41, v38, v40
	v_sub_f32_e32 v37, v37, v41
	v_sub_f32_e32 v33, v33, v40
	v_add_f32_e32 v36, v38, v36
	v_add_f32_e32 v33, v33, v37
	v_add_f32_e32 v37, v39, v36
	v_sub_f32_e32 v38, v37, v39
	v_sub_f32_e32 v36, v36, v38
	v_add_f32_e32 v33, v33, v36
	v_add_f32_e32 v33, v37, v33
	v_cndmask_b32_e32 v33, v178, v33, vcc
	v_cmp_ngt_f32_e32 vcc, -1.0, v31
	s_nop 1
	v_cndmask_b32_e32 v33, v179, v33, vcc
	v_cmp_neq_f32_e32 vcc, -1.0, v31
	s_nop 1
	v_cndmask_b32_e32 v33, v180, v33, vcc
	v_cmp_lt_f32_e64 vcc, |v31|, s50
	s_nop 1
	v_cndmask_b32_e32 v31, v33, v31, vcc
	v_sub_f32_e32 v30, v30, v31
	global_store_dword v[28:29], v30, off offset:-20
.LBB0_1321:
	s_andn2_saveexec_b64 s[2:3], s[2:3]
	s_cbranch_execz .LBB0_1323
	v_mul_f32_e32 v24, v24, v32
	v_mul_f32_e32 v25, v25, v32
	v_mul_f32_e32 v24, 0xbfb8aa3b, v24
	v_mul_f32_e32 v25, 0xbfb8aa3b, v25
	v_exp_f32_e32 v24, v24
	v_exp_f32_e32 v25, v25
	v_mul_f32_e32 v26, v26, v32
	v_mul_f32_e32 v27, v27, v32
	v_mul_f32_e32 v26, 0xbfb8aa3b, v26
	v_pk_add_f32 v[24:25], v[24:25], 1.0 op_sel_hi:[1,0]
	v_mul_f32_e32 v27, 0xbfb8aa3b, v27
	v_exp_f32_e32 v26, v26
	v_exp_f32_e32 v27, v27
	v_rcp_f32_e32 v25, v25
	v_pk_add_f32 v[26:27], v[26:27], 1.0 op_sel_hi:[1,0]
	v_rcp_f32_e32 v24, v24
	s_nop 0
	v_rcp_f32_e32 v27, v27
	s_nop 0
	v_rcp_f32_e32 v26, v26
	global_store_dwordx4 v[36:37], v[24:27], off offset:64

; DI float sigmoidf_(float x) { return 1.f / (1.f + __expf(-x)); }
; template <bool SWAP> DI void inproj_tile(const Params& p, int layer, int tm, int tn, bf16_t* smem) {
;     ...
;       for (int i = 0; i < 8; ++i) {
;         const int t = trow0 + i * 16 + l15; const float rs = rstd_from16(ssq + (size_t)t * 16, 1.f / 1024.f);
;         float* gt = (float*)(p.ws + O_GATES) + (size_t)t * 24; float* lf = (float*)(p.ws + O_LOGF) + (size_t)t * 8;
; #pragma unroll
;         for (int r = 0; r < 4; ++r) gt[quad * 4 + r] = sigmoidf_(acc[i][0][r] * rs);
;         if (quad < 2) {
; #pragma unroll
;           for (int r = 0; r < 4; ++r) gt[16 + quad * 4 + r] = sigmoidf_(acc[i][1][r] * rs);
;         } else {
; #pragma unroll
;           for (int r = 0; r < 4; ++r) { const int h = (quad - 2) * 4 + r; const float xx = acc[i][1][r] * rs + p.b_forget[layer * 8 + h]; lf[h] = fminf(xx, 0.f) - log1pf(__expf(-fabsf(xx))); }
;         }
.LrcA1_15:
	s_or_b64 exec, exec, s[98:99]
	s_waitcnt vmcnt(0)
	v_cndmask_b32_e64 v16, v249, v16, s[100:101]
	v_readlane_b32 s2, v240, 35
	v_readlane_b32 s3, v240, 36
	s_nop 1
	v_mov_b64_e32 v[18:19], s[2:3]
	v_mad_i64_i32 v[20:21], s[2:3], v32, s45, v[18:19]
	v_lshlrev_b64 v[18:19], 5, v[32:33]
	v_lshl_add_u64 v[20:21], v[20:21], 0, v[160:161]
	v_mul_f32_e32 v12, v12, v16
	v_mul_f32_e32 v13, v13, v16
	v_mul_f32_e32 v12, 0xbfb8aa3b, v12
	v_mul_f32_e32 v13, 0xbfb8aa3b, v13
	v_exp_f32_e32 v12, v12
	v_exp_f32_e32 v13, v13
	v_mul_f32_e32 v14, v14, v16
	v_mul_f32_e32 v15, v15, v16
	v_mul_f32_e32 v14, 0xbfb8aa3b, v14
	v_pk_add_f32 v[12:13], v[12:13], 1.0 op_sel_hi:[1,0]
	v_mul_f32_e32 v15, 0xbfb8aa3b, v15
	v_exp_f32_e32 v14, v14
	v_exp_f32_e32 v15, v15
	v_rcp_f32_e32 v13, v13
	v_pk_add_f32 v[14:15], v[14:15], 1.0 op_sel_hi:[1,0]
	v_rcp_f32_e32 v12, v12
	s_nop 0
	v_rcp_f32_e32 v15, v15
	s_nop 0
	v_rcp_f32_e32 v14, v14
	global_store_dwordx4 v[20:21], v[12:15], off
	s_and_saveexec_b64 s[2:3], s[4:5]
	s_xor_b64 s[2:3], exec, s[2:3]
	s_cbranch_execz .LBB0_1325
	v_readlane_b32 s52, v241, 8
	v_readlane_b32 s60, v241, 16
	v_readlane_b32 s61, v241, 17
	v_lshl_add_u64 v[12:13], s[8:9], 0, v[18:19]
	v_lshl_add_u64 v[12:13], v[12:13], 0, v[160:161]
	v_readlane_b32 s53, v241, 9
	v_readlane_b32 s54, v241, 10
	v_readlane_b32 s55, v241, 11
	global_load_dword v14, v160, s[60:61]
	v_readlane_b32 s56, v241, 12
	v_readlane_b32 s57, v241, 13
	v_readlane_b32 s58, v241, 14
	v_readlane_b32 s59, v241, 15
	v_readlane_b32 s62, v241, 18
	v_readlane_b32 s63, v241, 19
	v_readlane_b32 s64, v241, 20
	v_readlane_b32 s65, v241, 21
	v_readlane_b32 s66, v241, 22
	v_readlane_b32 s67, v241, 23
	s_waitcnt vmcnt(0)
	v_fmac_f32_e32 v14, v8, v16
	v_min_f32_e32 v17, 0, v14
	v_mul_f32_e64 v14, |v14|, s46
	v_exp_f32_e32 v20, v14
	s_nop 0
	v_add_f32_e32 v21, 1.0, v20
	v_add_f32_e32 v14, -1.0, v21
	v_sub_f32_e32 v15, v14, v21
	v_add_f32_e32 v15, 1.0, v15
	v_sub_f32_e32 v14, v20, v14
	v_add_f32_e32 v22, v14, v15
	v_frexp_mant_f32_e32 v14, v21
	v_cmp_gt_f32_e32 vcc, s47, v14
	v_cvt_f64_f32_e32 v[14:15], v21
	v_frexp_exp_i32_f64_e32 v14, v[14:15]
	v_subbrev_co_u32_e32 v14, vcc, 0, v14, vcc
	v_sub_u32_e32 v15, 0, v14
	v_ldexp_f32 v21, v21, v15
	v_ldexp_f32 v15, v22, v15
	v_add_f32_e32 v22, -1.0, v21
	v_add_f32_e32 v23, 1.0, v22
	v_sub_f32_e32 v23, v21, v23
	v_add_f32_e32 v23, v15, v23
	v_add_f32_e32 v24, v22, v23
	v_sub_f32_e32 v22, v24, v22
	v_sub_f32_e32 v22, v23, v22
	v_add_f32_e32 v23, 1.0, v21
	v_add_f32_e32 v25, -1.0, v23
	v_sub_f32_e32 v21, v21, v25
	v_add_f32_e32 v15, v15, v21
	v_add_f32_e32 v21, v23, v15
	v_sub_f32_e32 v23, v21, v23
	v_sub_f32_e32 v15, v15, v23
	v_rcp_f32_e32 v23, v21
	v_cvt_f32_i32_e32 v14, v14
	v_cmp_neq_f32_e32 vcc, s49, v20
	v_mul_f32_e32 v25, v24, v23
	v_mul_f32_e32 v26, v21, v25
	v_fma_f32 v27, v25, v21, -v26
	v_fmac_f32_e32 v27, v25, v15
	v_add_f32_e32 v28, v26, v27
	v_sub_f32_e32 v29, v24, v28
	v_sub_f32_e32 v24, v24, v29
	v_sub_f32_e32 v26, v28, v26
	v_sub_f32_e32 v24, v24, v28
	v_add_f32_e32 v22, v22, v24
	v_sub_f32_e32 v24, v26, v27
	v_add_f32_e32 v22, v24, v22
	v_add_f32_e32 v24, v29, v22
	v_mul_f32_e32 v26, v23, v24
	v_mul_f32_e32 v27, v21, v26
	v_fma_f32 v21, v26, v21, -v27
	v_fmac_f32_e32 v21, v26, v15
	v_sub_f32_e32 v15, v29, v24
	v_add_f32_e32 v15, v22, v15
	v_add_f32_e32 v22, v27, v21
	v_sub_f32_e32 v28, v24, v22
	v_sub_f32_e32 v24, v24, v28
	v_sub_f32_e32 v27, v22, v27
	v_sub_f32_e32 v22, v24, v22
	v_add_f32_e32 v15, v15, v22
	v_sub_f32_e32 v21, v27, v21
	v_add_f32_e32 v15, v21, v15
	v_add_f32_e32 v21, v25, v26
	v_add_f32_e32 v15, v28, v15
	v_sub_f32_e32 v22, v21, v25
	v_mul_f32_e32 v15, v23, v15
	v_sub_f32_e32 v22, v26, v22
	v_add_f32_e32 v15, v22, v15
	v_mul_f32_e32 v25, 0x3f317218, v14
	v_add_f32_e32 v22, v21, v15
	v_fma_f32 v26, v14, s48, -v25
	v_mul_f32_e32 v23, v22, v22
	v_fmac_f32_e32 v26, 0xb102e308, v14
	v_sub_f32_e32 v14, v22, v21
	v_fmamk_f32 v24, v23, 0x3e9b6dac, v171
	v_sub_f32_e32 v14, v15, v14
	v_add_f32_e32 v15, v25, v26
	v_fmaak_f32 v24, v23, v24, 0x3f2aaada
	v_sub_f32_e32 v21, v15, v25
	v_ldexp_f32 v25, v22, 1
	v_mul_f32_e32 v22, v22, v23
	v_mul_f32_e32 v22, v22, v24
	v_add_f32_e32 v23, v25, v22
	v_sub_f32_e32 v24, v23, v25
	v_ldexp_f32 v14, v14, 1
	v_sub_f32_e32 v22, v22, v24
	v_add_f32_e32 v14, v14, v22
	v_add_f32_e32 v22, v23, v14
	v_sub_f32_e32 v23, v22, v23
	v_sub_f32_e32 v14, v14, v23
	v_add_f32_e32 v23, v15, v22
	v_sub_f32_e32 v24, v23, v15
	v_sub_f32_e32 v25, v23, v24
	v_sub_f32_e32 v21, v26, v21
	v_sub_f32_e32 v15, v15, v25
	v_sub_f32_e32 v22, v22, v24
	v_add_f32_e32 v15, v22, v15
	v_add_f32_e32 v22, v21, v14
	v_sub_f32_e32 v24, v22, v21
	v_sub_f32_e32 v25, v22, v24
	v_sub_f32_e32 v21, v21, v25
	v_sub_f32_e32 v14, v14, v24
	v_add_f32_e32 v15, v22, v15
	v_add_f32_e32 v14, v14, v21
	v_add_f32_e32 v21, v23, v15
	v_sub_f32_e32 v22, v21, v23
	v_sub_f32_e32 v15, v15, v22
	v_add_f32_e32 v14, v14, v15
	v_add_f32_e32 v14, v21, v14
	v_cndmask_b32_e32 v14, v178, v14, vcc
	v_cmp_ngt_f32_e32 vcc, -1.0, v20
	s_nop 1
	v_cndmask_b32_e32 v14, v179, v14, vcc
	v_cmp_neq_f32_e32 vcc, -1.0, v20
	s_nop 1
	v_cndmask_b32_e32 v14, v180, v14, vcc
	v_cmp_lt_f32_e64 vcc, |v20|, s50
	s_nop 1
	v_cndmask_b32_e32 v14, v14, v20, vcc
	v_sub_f32_e32 v14, v17, v14
	global_store_dword v[12:13], v14, off offset:-32
	global_load_dword v15, v160, s[60:61] offset:4
	s_waitcnt vmcnt(0)
; template <bool SWAP> DI void inproj_tile(const Params& p, int layer, int tm, int tn, bf16_t* smem) {
;     ...
;           for (int r = 0; r < 4; ++r) { const int h = (quad - 2) * 4 + r; const float xx = acc[i][1][r] * rs + p.b_forget[layer * 8 + h]; lf[h] = fminf(xx, 0.f) - log1pf(__expf(-fabsf(xx))); }
	v_fmac_f32_e32 v15, v9, v16
	v_min_f32_e32 v14, 0, v15
	v_mul_f32_e64 v15, |v15|, s46
	v_exp_f32_e32 v15, v15
	s_nop 0
	v_add_f32_e32 v17, 1.0, v15
	v_add_f32_e32 v20, -1.0, v17
	v_sub_f32_e32 v21, v20, v17
	v_add_f32_e32 v21, 1.0, v21
	v_sub_f32_e32 v20, v15, v20
	v_add_f32_e32 v22, v20, v21
	v_frexp_mant_f32_e32 v20, v17
	v_cmp_gt_f32_e32 vcc, s47, v20
	v_cvt_f64_f32_e32 v[20:21], v17
	v_frexp_exp_i32_f64_e32 v20, v[20:21]
	v_subbrev_co_u32_e32 v20, vcc, 0, v20, vcc
	v_sub_u32_e32 v21, 0, v20
	v_ldexp_f32 v17, v17, v21
	v_ldexp_f32 v21, v22, v21
	v_add_f32_e32 v22, -1.0, v17
	v_add_f32_e32 v23, 1.0, v22
	v_sub_f32_e32 v23, v17, v23
	v_add_f32_e32 v23, v21, v23
	v_add_f32_e32 v24, v22, v23
	v_sub_f32_e32 v22, v24, v22
	v_sub_f32_e32 v22, v23, v22
	v_add_f32_e32 v23, 1.0, v17
	v_add_f32_e32 v25, -1.0, v23
	v_sub_f32_e32 v17, v17, v25
	v_add_f32_e32 v17, v21, v17
	v_add_f32_e32 v21, v23, v17
	v_sub_f32_e32 v23, v21, v23
	v_sub_f32_e32 v17, v17, v23
	v_rcp_f32_e32 v23, v21
	v_cvt_f32_i32_e32 v20, v20
	v_cmp_neq_f32_e32 vcc, s49, v15
	v_mul_f32_e32 v25, v24, v23
	v_mul_f32_e32 v26, v21, v25
	v_fma_f32 v27, v25, v21, -v26
	v_fmac_f32_e32 v27, v25, v17
	v_add_f32_e32 v28, v26, v27
	v_sub_f32_e32 v29, v24, v28
	v_sub_f32_e32 v24, v24, v29
	v_sub_f32_e32 v26, v28, v26
	v_sub_f32_e32 v24, v24, v28
	v_add_f32_e32 v22, v22, v24
	v_sub_f32_e32 v24, v26, v27
	v_add_f32_e32 v22, v24, v22
	v_add_f32_e32 v24, v29, v22
	v_mul_f32_e32 v26, v23, v24
	v_mul_f32_e32 v27, v21, v26
	v_fma_f32 v21, v26, v21, -v27
	v_fmac_f32_e32 v21, v26, v17
	v_sub_f32_e32 v17, v29, v24
	v_add_f32_e32 v17, v22, v17
	v_add_f32_e32 v22, v27, v21
	v_sub_f32_e32 v28, v24, v22
	v_sub_f32_e32 v24, v24, v28
	v_sub_f32_e32 v27, v22, v27
	v_sub_f32_e32 v22, v24, v22
	v_add_f32_e32 v17, v17, v22
	v_sub_f32_e32 v21, v27, v21
	v_add_f32_e32 v17, v21, v17
	v_add_f32_e32 v21, v25, v26
	v_add_f32_e32 v17, v28, v17
	v_sub_f32_e32 v22, v21, v25
	v_mul_f32_e32 v17, v23, v17
	v_sub_f32_e32 v22, v26, v22
	v_add_f32_e32 v17, v22, v17
	v_mul_f32_e32 v25, 0x3f317218, v20
	v_add_f32_e32 v22, v21, v17
	v_fma_f32 v26, v20, s48, -v25
	v_mul_f32_e32 v23, v22, v22
	v_fmac_f32_e32 v26, 0xb102e308, v20
	v_sub_f32_e32 v20, v22, v21
	v_fmamk_f32 v24, v23, 0x3e9b6dac, v171
	v_sub_f32_e32 v17, v17, v20
	v_add_f32_e32 v20, v25, v26
	v_fmaak_f32 v24, v23, v24, 0x3f2aaada
	v_sub_f32_e32 v21, v20, v25
	v_ldexp_f32 v25, v22, 1
	v_mul_f32_e32 v22, v22, v23
	v_mul_f32_e32 v22, v22, v24
	v_add_f32_e32 v23, v25, v22
	v_sub_f32_e32 v24, v23, v25
	v_ldexp_f32 v17, v17, 1
	v_sub_f32_e32 v22, v22, v24
	v_add_f32_e32 v17, v17, v22
	v_add_f32_e32 v22, v23, v17
	v_sub_f32_e32 v23, v22, v23
	v_sub_f32_e32 v17, v17, v23
	v_add_f32_e32 v23, v20, v22
	v_sub_f32_e32 v24, v23, v20
	v_sub_f32_e32 v25, v23, v24
	v_sub_f32_e32 v21, v26, v21
	v_sub_f32_e32 v20, v20, v25
	v_sub_f32_e32 v22, v22, v24
	v_add_f32_e32 v20, v22, v20
	v_add_f32_e32 v22, v21, v17
	v_sub_f32_e32 v24, v22, v21
	v_sub_f32_e32 v25, v22, v24
	v_sub_f32_e32 v21, v21, v25
	v_sub_f32_e32 v17, v17, v24
	v_add_f32_e32 v20, v22, v20
	v_add_f32_e32 v17, v17, v21
	v_add_f32_e32 v21, v23, v20
	v_sub_f32_e32 v22, v21, v23
	v_sub_f32_e32 v20, v20, v22
	v_add_f32_e32 v17, v17, v20
	v_add_f32_e32 v17, v21, v17
	v_cndmask_b32_e32 v17, v178, v17, vcc
	v_cmp_ngt_f32_e32 vcc, -1.0, v15
	s_nop 1
	v_cndmask_b32_e32 v17, v179, v17, vcc
	v_cmp_neq_f32_e32 vcc, -1.0, v15
	s_nop 1
	v_cndmask_b32_e32 v17, v180, v17, vcc
	v_cmp_lt_f32_e64 vcc, |v15|, s50
	s_nop 1
	v_cndmask_b32_e32 v15, v17, v15, vcc
	v_sub_f32_e32 v14, v14, v15
	global_store_dword v[12:13], v14, off offset:-28
	global_load_dword v15, v160, s[60:61] offset:8
	s_waitcnt vmcnt(0)
	v_fmac_f32_e32 v15, v10, v16
	v_min_f32_e32 v14, 0, v15
	v_mul_f32_e64 v15, |v15|, s46
	v_exp_f32_e32 v15, v15
	s_nop 0
	v_add_f32_e32 v17, 1.0, v15
	v_add_f32_e32 v20, -1.0, v17
	v_sub_f32_e32 v21, v20, v17
	v_add_f32_e32 v21, 1.0, v21
	v_sub_f32_e32 v20, v15, v20
	v_add_f32_e32 v22, v20, v21
	v_frexp_mant_f32_e32 v20, v17
	v_cmp_gt_f32_e32 vcc, s47, v20
	v_cvt_f64_f32_e32 v[20:21], v17
	v_frexp_exp_i32_f64_e32 v20, v[20:21]
	v_subbrev_co_u32_e32 v20, vcc, 0, v20, vcc
	v_sub_u32_e32 v21, 0, v20
	v_ldexp_f32 v17, v17, v21
	v_ldexp_f32 v21, v22, v21
	v_add_f32_e32 v22, -1.0, v17
	v_add_f32_e32 v23, 1.0, v22
	v_sub_f32_e32 v23, v17, v23
	v_add_f32_e32 v23, v21, v23
	v_add_f32_e32 v24, v22, v23
	v_sub_f32_e32 v22, v24, v22
	v_sub_f32_e32 v22, v23, v22
	v_add_f32_e32 v23, 1.0, v17
	v_add_f32_e32 v25, -1.0, v23
	v_sub_f32_e32 v17, v17, v25
	v_add_f32_e32 v17, v21, v17
	v_add_f32_e32 v21, v23, v17
	v_sub_f32_e32 v23, v21, v23
	v_sub_f32_e32 v17, v17, v23
	v_rcp_f32_e32 v23, v21
	v_cvt_f32_i32_e32 v20, v20
	v_cmp_neq_f32_e32 vcc, s49, v15
	v_mul_f32_e32 v25, v24, v23
	v_mul_f32_e32 v26, v21, v25
	v_fma_f32 v27, v25, v21, -v26
	v_fmac_f32_e32 v27, v25, v17
	v_add_f32_e32 v28, v26, v27
	v_sub_f32_e32 v29, v24, v28
	v_sub_f32_e32 v24, v24, v29
	v_sub_f32_e32 v26, v28, v26
	v_sub_f32_e32 v24, v24, v28
	v_add_f32_e32 v22, v22, v24
	v_sub_f32_e32 v24, v26, v27
	v_add_f32_e32 v22, v24, v22
	v_add_f32_e32 v24, v29, v22
	v_mul_f32_e32 v26, v23, v24
	v_mul_f32_e32 v27, v21, v26
	v_fma_f32 v21, v26, v21, -v27
	v_fmac_f32_e32 v21, v26, v17
	v_sub_f32_e32 v17, v29, v24
	v_add_f32_e32 v17, v22, v17
	v_add_f32_e32 v22, v27, v21
	v_sub_f32_e32 v28, v24, v22
	v_sub_f32_e32 v24, v24, v28
	v_sub_f32_e32 v27, v22, v27
	v_sub_f32_e32 v22, v24, v22
	v_add_f32_e32 v17, v17, v22
	v_sub_f32_e32 v21, v27, v21
	v_add_f32_e32 v17, v21, v17
	v_add_f32_e32 v21, v25, v26
	v_add_f32_e32 v17, v28, v17
	v_sub_f32_e32 v22, v21, v25
	v_mul_f32_e32 v17, v23, v17
	v_sub_f32_e32 v22, v26, v22
; DI float sigmoidf_(float x) { return 1.f / (1.f + __expf(-x)); }
; template <bool SWAP> DI void inproj_tile(const Params& p, int layer, int tm, int tn, bf16_t* smem) {
;     ...
;       for (int i = 0; i < 8; ++i) {
;         const int t = trow0 + i * 16 + l15; const float rs = rstd_from16(ssq + (size_t)t * 16, 1.f / 1024.f);
;         float* gt = (float*)(p.ws + O_GATES) + (size_t)t * 24; float* lf = (float*)(p.ws + O_LOGF) + (size_t)t * 8;
; #pragma unroll
;         for (int r = 0; r < 4; ++r) gt[quad * 4 + r] = sigmoidf_(acc[i][0][r] * rs);
;         if (quad < 2) {
; #pragma unroll
;           for (int r = 0; r < 4; ++r) gt[16 + quad * 4 + r] = sigmoidf_(acc[i][1][r] * rs);
;         } else {
; #pragma unroll
;           for (int r = 0; r < 4; ++r) { const int h = (quad - 2) * 4 + r; const float xx = acc[i][1][r] * rs + p.b_forget[layer * 8 + h]; lf[h] = fminf(xx, 0.f) - log1pf(__expf(-fabsf(xx))); }
;         }
	v_add_f32_e32 v17, v22, v17
	v_mul_f32_e32 v25, 0x3f317218, v20
	v_add_f32_e32 v22, v21, v17
	v_fma_f32 v26, v20, s48, -v25
	v_mul_f32_e32 v23, v22, v22
	v_fmac_f32_e32 v26, 0xb102e308, v20
	v_sub_f32_e32 v20, v22, v21
	v_fmamk_f32 v24, v23, 0x3e9b6dac, v171
	v_sub_f32_e32 v17, v17, v20
	v_add_f32_e32 v20, v25, v26
	v_fmaak_f32 v24, v23, v24, 0x3f2aaada
	v_sub_f32_e32 v21, v20, v25
	v_ldexp_f32 v25, v22, 1
	v_mul_f32_e32 v22, v22, v23
	v_mul_f32_e32 v22, v22, v24
	v_add_f32_e32 v23, v25, v22
	v_sub_f32_e32 v24, v23, v25
	v_ldexp_f32 v17, v17, 1
	v_sub_f32_e32 v22, v22, v24
	v_add_f32_e32 v17, v17, v22
	v_add_f32_e32 v22, v23, v17
	v_sub_f32_e32 v23, v22, v23
	v_sub_f32_e32 v17, v17, v23
	v_add_f32_e32 v23, v20, v22
	v_sub_f32_e32 v24, v23, v20
	v_sub_f32_e32 v25, v23, v24
	v_sub_f32_e32 v21, v26, v21
	v_sub_f32_e32 v20, v20, v25
	v_sub_f32_e32 v22, v22, v24
	v_add_f32_e32 v20, v22, v20
	v_add_f32_e32 v22, v21, v17
	v_sub_f32_e32 v24, v22, v21
	v_sub_f32_e32 v25, v22, v24
	v_sub_f32_e32 v21, v21, v25
	v_sub_f32_e32 v17, v17, v24
	v_add_f32_e32 v20, v22, v20
	v_add_f32_e32 v17, v17, v21
	v_add_f32_e32 v21, v23, v20
	v_sub_f32_e32 v22, v21, v23
	v_sub_f32_e32 v20, v20, v22
	v_add_f32_e32 v17, v17, v20
	v_add_f32_e32 v17, v21, v17
	v_cndmask_b32_e32 v17, v178, v17, vcc
	v_cmp_ngt_f32_e32 vcc, -1.0, v15
	s_nop 1
	v_cndmask_b32_e32 v17, v179, v17, vcc
	v_cmp_neq_f32_e32 vcc, -1.0, v15
	s_nop 1
	v_cndmask_b32_e32 v17, v180, v17, vcc
	v_cmp_lt_f32_e64 vcc, |v15|, s50
	s_nop 1
	v_cndmask_b32_e32 v15, v17, v15, vcc
	v_sub_f32_e32 v14, v14, v15
	global_store_dword v[12:13], v14, off offset:-24
	global_load_dword v15, v160, s[60:61] offset:12
	s_waitcnt vmcnt(0)
	v_fmac_f32_e32 v15, v11, v16
	v_min_f32_e32 v14, 0, v15
	v_mul_f32_e64 v15, |v15|, s46
	v_exp_f32_e32 v15, v15
	s_nop 0
	v_add_f32_e32 v17, 1.0, v15
	v_add_f32_e32 v20, -1.0, v17
	v_sub_f32_e32 v21, v20, v17
	v_add_f32_e32 v21, 1.0, v21
	v_sub_f32_e32 v20, v15, v20
	v_add_f32_e32 v22, v20, v21
	v_frexp_mant_f32_e32 v20, v17
	v_cmp_gt_f32_e32 vcc, s47, v20
	v_cvt_f64_f32_e32 v[20:21], v17
	v_frexp_exp_i32_f64_e32 v20, v[20:21]
	v_subbrev_co_u32_e32 v20, vcc, 0, v20, vcc
	v_sub_u32_e32 v21, 0, v20
	v_ldexp_f32 v17, v17, v21
	v_ldexp_f32 v21, v22, v21
	v_add_f32_e32 v22, -1.0, v17
	v_add_f32_e32 v23, 1.0, v22
	v_sub_f32_e32 v23, v17, v23
	v_add_f32_e32 v23, v21, v23
	v_add_f32_e32 v24, v22, v23
	v_sub_f32_e32 v22, v24, v22
	v_sub_f32_e32 v22, v23, v22
	v_add_f32_e32 v23, 1.0, v17
	v_add_f32_e32 v25, -1.0, v23
	v_sub_f32_e32 v17, v17, v25
	v_add_f32_e32 v17, v21, v17
	v_add_f32_e32 v21, v23, v17
	v_sub_f32_e32 v23, v21, v23
	v_sub_f32_e32 v17, v17, v23
	v_rcp_f32_e32 v23, v21
	v_cvt_f32_i32_e32 v20, v20
	v_cmp_neq_f32_e32 vcc, s49, v15
	v_mul_f32_e32 v25, v24, v23
	v_mul_f32_e32 v26, v21, v25
	v_fma_f32 v27, v25, v21, -v26
	v_fmac_f32_e32 v27, v25, v17
	v_add_f32_e32 v28, v26, v27
	v_sub_f32_e32 v29, v24, v28
	v_sub_f32_e32 v24, v24, v29
	v_sub_f32_e32 v26, v28, v26
	v_sub_f32_e32 v24, v24, v28
	v_add_f32_e32 v22, v22, v24
	v_sub_f32_e32 v24, v26, v27
	v_add_f32_e32 v22, v24, v22
	v_add_f32_e32 v24, v29, v22
	v_mul_f32_e32 v26, v23, v24
	v_mul_f32_e32 v27, v21, v26
	v_fma_f32 v21, v26, v21, -v27
	v_fmac_f32_e32 v21, v26, v17
	v_sub_f32_e32 v17, v29, v24
	v_add_f32_e32 v17, v22, v17
	v_add_f32_e32 v22, v27, v21
	v_sub_f32_e32 v28, v24, v22
	v_sub_f32_e32 v24, v24, v28
	v_sub_f32_e32 v27, v22, v27
	v_sub_f32_e32 v22, v24, v22
	v_add_f32_e32 v17, v17, v22
	v_sub_f32_e32 v21, v27, v21
	v_add_f32_e32 v17, v21, v17
	v_add_f32_e32 v21, v25, v26
	v_add_f32_e32 v17, v28, v17
	v_sub_f32_e32 v22, v21, v25
	v_mul_f32_e32 v17, v23, v17
	v_sub_f32_e32 v22, v26, v22
	v_add_f32_e32 v17, v22, v17
	v_mul_f32_e32 v25, 0x3f317218, v20
	v_add_f32_e32 v22, v21, v17
	v_fma_f32 v26, v20, s48, -v25
	v_mul_f32_e32 v23, v22, v22
	v_fmac_f32_e32 v26, 0xb102e308, v20
	v_sub_f32_e32 v20, v22, v21
	v_fmamk_f32 v24, v23, 0x3e9b6dac, v171
	v_sub_f32_e32 v17, v17, v20
	v_add_f32_e32 v20, v25, v26
	v_fmaak_f32 v24, v23, v24, 0x3f2aaada
	v_sub_f32_e32 v21, v20, v25
	v_ldexp_f32 v25, v22, 1
	v_mul_f32_e32 v22, v22, v23
	v_mul_f32_e32 v22, v22, v24
	v_add_f32_e32 v23, v25, v22
	v_sub_f32_e32 v24, v23, v25
	v_ldexp_f32 v17, v17, 1
	v_sub_f32_e32 v22, v22, v24
	v_add_f32_e32 v17, v17, v22
	v_add_f32_e32 v22, v23, v17
	v_sub_f32_e32 v23, v22, v23
	v_sub_f32_e32 v17, v17, v23
	v_add_f32_e32 v23, v20, v22
	v_sub_f32_e32 v24, v23, v20
	v_sub_f32_e32 v25, v23, v24
	v_sub_f32_e32 v21, v26, v21
	v_sub_f32_e32 v20, v20, v25
	v_sub_f32_e32 v22, v22, v24
	v_add_f32_e32 v20, v22, v20
	v_add_f32_e32 v22, v21, v17
	v_sub_f32_e32 v24, v22, v21
	v_sub_f32_e32 v25, v22, v24
	v_sub_f32_e32 v21, v21, v25
	v_sub_f32_e32 v17, v17, v24
	v_add_f32_e32 v20, v22, v20
	v_add_f32_e32 v17, v17, v21
	v_add_f32_e32 v21, v23, v20
	v_sub_f32_e32 v22, v21, v23
	v_sub_f32_e32 v20, v20, v22
	v_add_f32_e32 v17, v17, v20
	v_add_f32_e32 v17, v21, v17
	v_cndmask_b32_e32 v17, v178, v17, vcc
	v_cmp_ngt_f32_e32 vcc, -1.0, v15
	s_nop 1
	v_cndmask_b32_e32 v17, v179, v17, vcc
	v_cmp_neq_f32_e32 vcc, -1.0, v15
	s_nop 1
	v_cndmask_b32_e32 v17, v180, v17, vcc
	v_cmp_lt_f32_e64 vcc, |v15|, s50
	s_nop 1
	v_cndmask_b32_e32 v15, v17, v15, vcc
	v_sub_f32_e32 v14, v14, v15
	global_store_dword v[12:13], v14, off offset:-20
.LBB0_1325:
	s_andn2_saveexec_b64 s[2:3], s[2:3]
	s_cbranch_execz .LBB0_1327
	v_mul_f32_e32 v8, v8, v16
	v_mul_f32_e32 v9, v9, v16
	v_mul_f32_e32 v8, 0xbfb8aa3b, v8
	v_mul_f32_e32 v9, 0xbfb8aa3b, v9
	v_exp_f32_e32 v8, v8
	v_exp_f32_e32 v9, v9
	v_mul_f32_e32 v10, v10, v16
	v_mul_f32_e32 v11, v11, v16
	v_mul_f32_e32 v10, 0xbfb8aa3b, v10
	v_pk_add_f32 v[8:9], v[8:9], 1.0 op_sel_hi:[1,0]
	v_mul_f32_e32 v11, 0xbfb8aa3b, v11
	v_exp_f32_e32 v10, v10
	v_exp_f32_e32 v11, v11
	v_rcp_f32_e32 v9, v9
	v_pk_add_f32 v[10:11], v[10:11], 1.0 op_sel_hi:[1,0]
	v_rcp_f32_e32 v8, v8
	s_nop 0
	v_rcp_f32_e32 v11, v11
	s_nop 0
	v_rcp_f32_e32 v10, v10
	global_store_dwordx4 v[20:21], v[8:11], off offset:64

; DI unsigned pk2(float lo, float hi) { f32x2 v = {lo, hi}; return __builtin_bit_cast(unsigned, __builtin_convertvector(v, bfx2)); }
; DI float gelu_tanh(float x) { const float u = 0.7978845608028654f * (x + 0.044715f * x * x * x); return x / (1.f + __expf(-2.f * u)); }
; DI void compress_item(const Params& p, int layer, int item, bf16_t* smem) {
;     ...
; #pragma unroll
;   for (int j = 0; j < 4; ++j) {
;     asm volatile("" ::: "memory");
;     f32x4 bv = {0.f, 0.f, 0.f, 0.f};
;     for (int pc = 0; pc < 16; ++pc) bv += *(const f32x4*)(b1 + pc * 256 + wn * 64 + j * 16 + quad * 4);
; #pragma unroll
;     for (int i = 0; i < 4; ++i) {
;       const int row = wm * 64 + i * 16 + l15, col = wn * 64 + j * 16 + quad * 4;
;       *(u32x2*)(H + row * LDH + col) = (u32x2){pk2(gelu_tanh(acc[i][j][0] + bv[0]), gelu_tanh(acc[i][j][1] + bv[1])), pk2(gelu_tanh(acc[i][j][2] + bv[2]), gelu_tanh(acc[i][j][3] + bv[3]))};
.Lcp1_exit:
	v_mfma_f32_16x16x32_bf16 v[52:55], v[140:143], v[132:135], v[52:55]
	v_mfma_f32_16x16x32_bf16 v[48:51], v[140:143], v[136:139], v[48:51]
	v_mfma_f32_16x16x32_bf16 v[36:39], v[148:151], v[132:135], v[36:39]
	v_mfma_f32_16x16x32_bf16 v[32:35], v[148:151], v[136:139], v[32:35]
	v_mfma_f32_16x16x32_bf16 v[20:23], v[152:155], v[132:135], v[20:23]
	v_mfma_f32_16x16x32_bf16 v[16:19], v[152:155], v[136:139], v[16:19]
	v_mfma_f32_16x16x32_bf16 v[4:7], v[242:245], v[132:135], v[4:7]
	v_mfma_f32_16x16x32_bf16 v[0:3], v[242:245], v[136:139], v[0:3]
	s_nop 7
	s_waitcnt vmcnt(1)
	v_mov_b32_e32 v78, v220
	v_mov_b32_e32 v81, v220
	s_lshl_b32 s0, s13, 14
	v_ashrrev_i32_e32 v80, 6, v81
	v_readlane_b32 s8, v241, 0
	v_and_b32_e32 v142, 3, v80
	v_readlane_b32 s9, v241, 1
	s_add_u32 s0, s8, s0
	v_bfe_u32 v79, v78, 4, 2
	s_addc_u32 s1, s9, 0
	v_lshlrev_b32_e32 v64, 8, v142
	v_mov_b32_e32 v65, 0
	v_lshl_add_u64 v[66:67], s[0:1], 0, v[64:65]
	v_lshlrev_b32_e32 v64, 4, v79
	v_lshl_add_u64 v[72:73], v[66:67], 0, v[64:65]
	s_mov_b64 s[0:1], 0x4b4c000
	v_lshl_add_u64 v[70:71], v[72:73], 0, s[0:1]
	s_mov_b32 s0, 0x4b4d000
	v_add_co_u32_e32 v66, vcc, s0, v72
	s_mov_b32 s1, 0x4b4f000
	s_nop 0
	v_addc_co_u32_e32 v67, vcc, 0, v73, vcc
	global_load_dwordx4 v[74:77], v[66:67], off offset:-4096
	global_load_dwordx4 v[82:85], v[70:71], off offset:1024
	global_load_dwordx4 v[86:89], v[70:71], off offset:2048
	global_load_dwordx4 v[90:93], v[70:71], off offset:3072
	global_load_dwordx4 v[94:97], v[66:67], off
	global_load_dwordx4 v[98:101], v[66:67], off offset:1024
	global_load_dwordx4 v[102:105], v[66:67], off offset:2048
	v_add_co_u32_e32 v68, vcc, s1, v72
	s_mov_b32 s0, 0x4b4e000
	s_nop 0
	v_addc_co_u32_e32 v69, vcc, 0, v73, vcc
	global_load_dwordx4 v[106:109], v[66:67], off offset:3072
	global_load_dwordx4 v[110:113], v[68:69], off offset:-4096
	v_add_co_u32_e32 v72, vcc, s0, v72
	s_mov_b32 s0, 0xfffffc0
	s_nop 0
	v_addc_co_u32_e32 v73, vcc, 0, v73, vcc
	global_load_dwordx4 v[114:117], v[72:73], off offset:1024
	global_load_dwordx4 v[118:121], v[72:73], off offset:2048
	global_load_dwordx4 v[122:125], v[72:73], off offset:3072
	global_load_dwordx4 v[126:129], v[68:69], off
	global_load_dwordx4 v[130:133], v[68:69], off offset:1024
	global_load_dwordx4 v[134:137], v[68:69], off offset:2048
	global_load_dwordx4 v[138:141], v[68:69], off offset:3072
	v_and_b32_e32 v78, 15, v78
	v_lshrrev_b32_e32 v81, 2, v81
	v_and_or_b32 v81, v81, s0, v78
	v_lshlrev_b32_e32 v143, 3, v79
	v_lshl_or_b32 v142, v142, 7, v143
	s_and_b64 s[6:7], s[4:5], exec
	s_waitcnt vmcnt(15)
	v_pk_add_f32 v[76:77], v[76:77], 0 op_sel_hi:[1,0]
	v_pk_add_f32 v[74:75], v[74:75], 0 op_sel_hi:[1,0]
	s_waitcnt vmcnt(14)
	v_pk_add_f32 v[76:77], v[76:77], v[84:85]
	v_pk_add_f32 v[74:75], v[74:75], v[82:83]
	s_waitcnt vmcnt(13)
	v_pk_add_f32 v[76:77], v[76:77], v[88:89]
	v_pk_add_f32 v[74:75], v[74:75], v[86:87]
	s_waitcnt vmcnt(12)
	v_pk_add_f32 v[76:77], v[76:77], v[92:93]
	v_pk_add_f32 v[74:75], v[74:75], v[90:91]
	s_waitcnt vmcnt(11)
	v_pk_add_f32 v[76:77], v[76:77], v[96:97]
	v_pk_add_f32 v[74:75], v[74:75], v[94:95]
	s_waitcnt vmcnt(10)
	v_pk_add_f32 v[76:77], v[76:77], v[100:101]
	v_pk_add_f32 v[74:75], v[74:75], v[98:99]
	s_waitcnt vmcnt(9)
	v_pk_add_f32 v[76:77], v[76:77], v[104:105]
	v_pk_add_f32 v[74:75], v[74:75], v[102:103]
	s_waitcnt vmcnt(8)
	v_pk_add_f32 v[76:77], v[76:77], v[108:109]
	v_pk_add_f32 v[74:75], v[74:75], v[106:107]
	s_waitcnt vmcnt(7)
	v_pk_add_f32 v[76:77], v[76:77], v[112:113]
	v_pk_add_f32 v[74:75], v[74:75], v[110:111]
	s_waitcnt vmcnt(6)
	v_pk_add_f32 v[76:77], v[76:77], v[116:117]
	v_pk_add_f32 v[74:75], v[74:75], v[114:115]
	s_waitcnt vmcnt(5)
	v_pk_add_f32 v[76:77], v[76:77], v[120:121]
	v_pk_add_f32 v[74:75], v[74:75], v[118:119]
	s_waitcnt vmcnt(4)
	v_pk_add_f32 v[76:77], v[76:77], v[124:125]
	v_pk_add_f32 v[74:75], v[74:75], v[122:123]
	s_waitcnt vmcnt(3)
	v_pk_add_f32 v[76:77], v[76:77], v[128:129]
	v_pk_add_f32 v[74:75], v[74:75], v[126:127]
	s_waitcnt vmcnt(2)
	v_pk_add_f32 v[76:77], v[76:77], v[132:133]
	v_pk_add_f32 v[74:75], v[74:75], v[130:131]
	s_waitcnt vmcnt(1)
	v_pk_add_f32 v[76:77], v[76:77], v[136:137]
	v_pk_add_f32 v[82:83], v[74:75], v[134:135]
	s_waitcnt vmcnt(0)
	v_pk_add_f32 v[74:75], v[76:77], v[140:141]
	v_pk_add_f32 v[76:77], v[82:83], v[138:139]
	v_pk_add_f32 v[62:63], v[62:63], v[74:75]
	v_pk_add_f32 v[60:61], v[60:61], v[76:77]
	v_mul_f32_e32 v84, 0x3d372713, v62
	v_mul_f32_e32 v82, 0x3d372713, v60
	v_mul_f32_e32 v83, 0x3d372713, v61
	v_mul_f32_e32 v82, v60, v82
	v_mul_f32_e32 v83, v61, v83
	v_fma_f32 v82, v60, v82, v60
	v_fma_f32 v83, v61, v83, v61
	v_mul_f32_e32 v82, 0x3f4c422a, v82
	v_mul_f32_e32 v83, 0x3f4c422a, v83
	v_mul_f32_e32 v82, -2.0, v82
	v_mul_f32_e32 v83, -2.0, v83
	v_mul_f32_e32 v82, 0x3fb8aa3b, v82
	v_mul_f32_e32 v83, 0x3fb8aa3b, v83
	v_exp_f32_e32 v82, v82
	v_exp_f32_e32 v83, v83
	v_mul_f32_e32 v84, v62, v84
	v_pk_add_f32 v[58:59], v[58:59], v[74:75]
	v_pk_add_f32 v[52:53], v[52:53], v[76:77]
	v_pk_add_f32 v[82:83], v[82:83], 1.0 op_sel_hi:[1,0]
	v_pk_add_f32 v[54:55], v[54:55], v[74:75]
	v_div_scale_f32 v87, s[0:1], v82, v82, v60
	v_rcp_f32_e32 v85, v83
	s_nop 0
	v_mul_f32_e32 v61, v61, v85
	v_fma_f32 v83, v62, v84, v62
	v_mul_f32_e32 v83, 0x3f4c422a, v83
	v_mul_f32_e32 v83, -2.0, v83
	v_mul_f32_e32 v83, 0x3fb8aa3b, v83
	v_exp_f32_e32 v84, v83
	v_mul_f32_e32 v83, 0x3d372713, v63
	v_mul_f32_e32 v83, v63, v83
	v_fma_f32 v83, v63, v83, v63
	v_rcp_f32_e32 v89, v87
	v_mul_f32_e32 v83, 0x3f4c422a, v83
	v_mul_f32_e32 v83, -2.0, v83
	v_mul_f32_e32 v83, 0x3fb8aa3b, v83
	v_exp_f32_e32 v85, v83
	v_fma_f32 v92, -v87, v89, 1.0
; DI unsigned pk2(float lo, float hi) { f32x2 v = {lo, hi}; return __builtin_bit_cast(unsigned, __builtin_convertvector(v, bfx2)); }
; DI float gelu_tanh(float x) { const float u = 0.7978845608028654f * (x + 0.044715f * x * x * x); return x / (1.f + __expf(-2.f * u)); }
; DI void compress_item(const Params& p, int layer, int item, bf16_t* smem) {
;     ...
; #pragma unroll
;   for (int j = 0; j < 4; ++j) {
;     asm volatile("" ::: "memory");
;     f32x4 bv = {0.f, 0.f, 0.f, 0.f};
;     for (int pc = 0; pc < 16; ++pc) bv += *(const f32x4*)(b1 + pc * 256 + wn * 64 + j * 16 + quad * 4);
; #pragma unroll
;     for (int i = 0; i < 4; ++i) {
;       const int row = wm * 64 + i * 16 + l15, col = wn * 64 + j * 16 + quad * 4;
;       *(u32x2*)(H + row * LDH + col) = (u32x2){pk2(gelu_tanh(acc[i][j][0] + bv[0]), gelu_tanh(acc[i][j][1] + bv[1])), pk2(gelu_tanh(acc[i][j][2] + bv[2]), gelu_tanh(acc[i][j][3] + bv[3]))};
;     }
;   }
	v_div_scale_f32 v90, s[0:1], v60, v82, v60
	v_fmac_f32_e32 v89, v92, v89
	v_mul_f32_e32 v92, v90, v89
	v_fma_f32 v83, -v87, v92, v90
	v_pk_add_f32 v[84:85], v[84:85], 1.0 op_sel_hi:[1,0]
	v_fmac_f32_e32 v92, v83, v89
	v_fma_f32 v83, -v87, v92, v90
	s_mov_b64 vcc, s[0:1]
	v_div_fmas_f32 v83, v83, v89, v92
	v_div_fixup_f32 v60, v83, v82, v60
	v_cvt_pk_bf16_f32 v60, v60, v61
	v_rcp_f32_e32 v61, v85
	s_nop 0
	v_mul_f32_e32 v61, v63, v61
	s_movk_i32 s0, 0x210
	v_pk_add_f32 v[82:83], v[56:57], v[76:77]
	v_rcp_f32_e32 v63, v84
	s_nop 0
	v_mul_f32_e32 v62, v62, v63
	v_mul_f32_e32 v56, 0x3d372713, v82
	v_mul_f32_e32 v57, 0x3d372713, v83
	v_mul_f32_e32 v56, v82, v56
	v_mul_f32_e32 v57, v83, v57
	v_fma_f32 v56, v82, v56, v82
	v_fma_f32 v57, v83, v57, v83
	v_mul_f32_e32 v56, 0x3f4c422a, v56
	v_mul_f32_e32 v57, 0x3f4c422a, v57
	v_mul_f32_e32 v56, -2.0, v56
	v_mul_f32_e32 v57, -2.0, v57
	v_mul_f32_e32 v56, 0x3fb8aa3b, v56
	v_mul_f32_e32 v57, 0x3fb8aa3b, v57
	v_exp_f32_e32 v56, v56
	v_exp_f32_e32 v57, v57
	v_cvt_pk_bf16_f32 v61, v62, v61
	v_pk_add_f32 v[48:49], v[48:49], v[76:77]
	v_pk_add_f32 v[50:51], v[50:51], v[74:75]
	v_pk_add_f32 v[62:63], v[56:57], 1.0 op_sel_hi:[1,0]
	v_mad_u64_u32 v[56:57], s[6:7], v81, s0, v[142:143]
	ds_write_b64 v56, v[60:61]
	v_mul_f32_e32 v61, 0x3d372713, v59
	v_mul_f32_e32 v61, v59, v61
	v_mul_f32_e32 v60, 0x3d372713, v58
	v_mul_f32_e32 v60, v58, v60
	v_fma_f32 v60, v58, v60, v58
	v_fma_f32 v61, v59, v61, v59
	v_mul_f32_e32 v60, 0x3f4c422a, v60
	v_mul_f32_e32 v61, 0x3f4c422a, v61
	v_mul_f32_e32 v60, -2.0, v60
	v_mul_f32_e32 v61, -2.0, v61
	v_mul_f32_e32 v60, 0x3fb8aa3b, v60
	v_mul_f32_e32 v61, 0x3fb8aa3b, v61
	v_exp_f32_e32 v60, v60
	v_exp_f32_e32 v61, v61
	v_rcp_f32_e32 v57, v63
	s_nop 0
	v_mul_f32_e32 v57, v83, v57
	v_pk_add_f32 v[60:61], v[60:61], 1.0 op_sel_hi:[1,0]
	v_rcp_f32_e32 v63, v62
	s_nop 0
	v_mul_f32_e32 v62, v82, v63
	v_cvt_pk_bf16_f32 v62, v62, v57
	v_rcp_f32_e32 v57, v61
	s_nop 0
	v_mul_f32_e32 v57, v59, v57
	s_mov_b32 s1, 0xf00000
	v_mul_f32_e32 v63, 0x3d372713, v52
	v_mul_f32_e32 v63, v52, v63
	v_fma_f32 v63, v52, v63, v52
	v_mul_f32_e32 v63, 0x3f4c422a, v63
	v_mul_f32_e32 v63, -2.0, v63
	v_mul_f32_e32 v63, 0x3fb8aa3b, v63
	v_exp_f32_e32 v82, v63
	v_mul_f32_e32 v63, 0x3d372713, v53
	v_mul_f32_e32 v63, v53, v63
	v_fma_f32 v63, v53, v63, v53
	v_mul_f32_e32 v63, 0x3f4c422a, v63
	v_mul_f32_e32 v63, -2.0, v63
	v_mul_f32_e32 v63, 0x3fb8aa3b, v63
	v_exp_f32_e32 v83, v63
	v_rcp_f32_e32 v59, v60
	s_nop 0
	v_mul_f32_e32 v60, v58, v59
	v_pk_add_f32 v[58:59], v[82:83], 1.0 op_sel_hi:[1,0]
	v_cvt_pk_bf16_f32 v63, v60, v57
	ds_write_b64 v56, v[62:63] offset:8448
	s_cselect_b32 s1, s1, 0xf08000
	v_mul_f32_e32 v60, 0x3d372713, v54
	v_mul_f32_e32 v61, 0x3d372713, v55
	v_mul_f32_e32 v60, v54, v60
	v_mul_f32_e32 v61, v55, v61
	v_fma_f32 v60, v54, v60, v54
	v_fma_f32 v61, v55, v61, v55
	v_mul_f32_e32 v60, 0x3f4c422a, v60
	v_mul_f32_e32 v61, 0x3f4c422a, v61
	v_mul_f32_e32 v60, -2.0, v60
	v_mul_f32_e32 v61, -2.0, v61
	v_mul_f32_e32 v60, 0x3fb8aa3b, v60
	v_mul_f32_e32 v61, 0x3fb8aa3b, v61
	v_rcp_f32_e32 v57, v59
	s_nop 0
	v_mul_f32_e32 v53, v53, v57
	v_exp_f32_e32 v60, v60
	v_exp_f32_e32 v61, v61
	s_nop 0
	v_pk_add_f32 v[60:61], v[60:61], 1.0 op_sel_hi:[1,0]
	v_rcp_f32_e32 v57, v58
	s_nop 0
	v_mul_f32_e32 v52, v52, v57
	v_cvt_pk_bf16_f32 v52, v52, v53
	v_rcp_f32_e32 v53, v61
	s_nop 0
	v_mul_f32_e32 v53, v55, v53
	v_mul_f32_e32 v58, 0x3d372713, v48
	v_mul_f32_e32 v59, 0x3d372713, v49
	v_mul_f32_e32 v58, v48, v58
	v_mul_f32_e32 v59, v49, v59
	v_fma_f32 v58, v48, v58, v48
	v_fma_f32 v59, v49, v59, v49
	v_mul_f32_e32 v58, 0x3f4c422a, v58
	v_mul_f32_e32 v59, 0x3f4c422a, v59
	v_mul_f32_e32 v58, -2.0, v58
	v_mul_f32_e32 v59, -2.0, v59
	v_mul_f32_e32 v58, 0x3fb8aa3b, v58
	v_mul_f32_e32 v59, 0x3fb8aa3b, v59
	v_exp_f32_e32 v58, v58
	v_exp_f32_e32 v59, v59
	v_rcp_f32_e32 v55, v60
	s_nop 0
	v_mul_f32_e32 v57, v54, v55
	v_cvt_pk_bf16_f32 v53, v57, v53
	v_pk_add_f32 v[54:55], v[58:59], 1.0 op_sel_hi:[1,0]
	ds_write_b64 v56, v[52:53] offset:16896
	s_nop 0
	v_rcp_f32_e32 v52, v55
	s_nop 0
	v_mul_f32_e32 v49, v49, v52
	v_mul_f32_e32 v53, 0x3d372713, v51
	v_mul_f32_e32 v52, 0x3d372713, v50
	v_mul_f32_e32 v52, v50, v52
	v_mul_f32_e32 v53, v51, v53
	v_fma_f32 v52, v50, v52, v50
	v_fma_f32 v53, v51, v53, v51
	v_mul_f32_e32 v52, 0x3f4c422a, v52
	v_mul_f32_e32 v53, 0x3f4c422a, v53
	v_mul_f32_e32 v52, -2.0, v52
	v_mul_f32_e32 v53, -2.0, v53
	v_mul_f32_e32 v52, 0x3fb8aa3b, v52
	v_mul_f32_e32 v53, 0x3fb8aa3b, v53
	v_exp_f32_e32 v52, v52
	v_exp_f32_e32 v53, v53
	s_nop 0
	v_pk_add_f32 v[52:53], v[52:53], 1.0 op_sel_hi:[1,0]
	v_rcp_f32_e32 v55, v54
	s_nop 0
	v_mul_f32_e32 v48, v48, v55
	v_cvt_pk_bf16_f32 v48, v48, v49
	v_rcp_f32_e32 v49, v53
	s_nop 0
	v_mul_f32_e32 v49, v51, v49
	v_rcp_f32_e32 v51, v52
	s_nop 0
	v_mul_f32_e32 v50, v50, v51
	v_cvt_pk_bf16_f32 v49, v50, v49
	ds_write_b64 v56, v[48:49] offset:25344
	global_load_dwordx4 v[48:51], v[70:71], off offset:64
	global_load_dwordx4 v[52:55], v[70:71], off offset:1088
	global_load_dwordx4 v[58:61], v[70:71], off offset:2112
	global_load_dwordx4 v[74:77], v[70:71], off offset:3136
	global_load_dwordx4 v[82:85], v[66:67], off offset:64
	global_load_dwordx4 v[86:89], v[66:67], off offset:1088
	global_load_dwordx4 v[90:93], v[66:67], off offset:2112
	global_load_dwordx4 v[94:97], v[66:67], off offset:3136
	global_load_dwordx4 v[98:101], v[72:73], off offset:64
	global_load_dwordx4 v[102:105], v[72:73], off offset:1088
	global_load_dwordx4 v[106:109], v[72:73], off offset:2112
	global_load_dwordx4 v[110:113], v[72:73], off offset:3136
	global_load_dwordx4 v[114:117], v[68:69], off offset:64
	global_load_dwordx4 v[118:121], v[68:69], off offset:1088
	global_load_dwordx4 v[122:125], v[68:69], off offset:2112
	global_load_dwordx4 v[126:129], v[68:69], off offset:3136
	s_waitcnt vmcnt(15)
; DI unsigned pk2(float lo, float hi) { f32x2 v = {lo, hi}; return __builtin_bit_cast(unsigned, __builtin_convertvector(v, bfx2)); }
; DI float gelu_tanh(float x) { const float u = 0.7978845608028654f * (x + 0.044715f * x * x * x); return x / (1.f + __expf(-2.f * u)); }
; DI void compress_item(const Params& p, int layer, int item, bf16_t* smem) {
;     ...
; #pragma unroll
;   for (int j = 0; j < 4; ++j) {
;     asm volatile("" ::: "memory");
;     f32x4 bv = {0.f, 0.f, 0.f, 0.f};
;     for (int pc = 0; pc < 16; ++pc) bv += *(const f32x4*)(b1 + pc * 256 + wn * 64 + j * 16 + quad * 4);
; #pragma unroll
;     for (int i = 0; i < 4; ++i) {
;       const int row = wm * 64 + i * 16 + l15, col = wn * 64 + j * 16 + quad * 4;
;       *(u32x2*)(H + row * LDH + col) = (u32x2){pk2(gelu_tanh(acc[i][j][0] + bv[0]), gelu_tanh(acc[i][j][1] + bv[1])), pk2(gelu_tanh(acc[i][j][2] + bv[2]), gelu_tanh(acc[i][j][3] + bv[3]))};
;     }
;   }
	v_pk_add_f32 v[48:49], v[48:49], 0 op_sel_hi:[1,0]
	s_waitcnt vmcnt(14)
	v_pk_add_f32 v[48:49], v[48:49], v[52:53]
	v_pk_add_f32 v[50:51], v[50:51], 0 op_sel_hi:[1,0]
	s_waitcnt vmcnt(13)
	v_pk_add_f32 v[48:49], v[48:49], v[58:59]
	v_pk_add_f32 v[50:51], v[50:51], v[54:55]
	s_waitcnt vmcnt(12)
	v_pk_add_f32 v[48:49], v[48:49], v[74:75]
	v_pk_add_f32 v[50:51], v[50:51], v[60:61]
	s_waitcnt vmcnt(11)
	v_pk_add_f32 v[48:49], v[48:49], v[82:83]
	v_pk_add_f32 v[50:51], v[50:51], v[76:77]
	s_waitcnt vmcnt(10)
	v_pk_add_f32 v[48:49], v[48:49], v[86:87]
	v_pk_add_f32 v[50:51], v[50:51], v[84:85]
	s_waitcnt vmcnt(9)
	v_pk_add_f32 v[48:49], v[48:49], v[90:91]
	v_pk_add_f32 v[50:51], v[50:51], v[88:89]
	s_waitcnt vmcnt(8)
	v_pk_add_f32 v[48:49], v[48:49], v[94:95]
	v_pk_add_f32 v[50:51], v[50:51], v[92:93]
	s_waitcnt vmcnt(7)
	v_pk_add_f32 v[48:49], v[48:49], v[98:99]
	v_pk_add_f32 v[50:51], v[50:51], v[96:97]
	s_waitcnt vmcnt(6)
	v_pk_add_f32 v[48:49], v[48:49], v[102:103]
	v_pk_add_f32 v[50:51], v[50:51], v[100:101]
	s_waitcnt vmcnt(5)
	v_pk_add_f32 v[48:49], v[48:49], v[106:107]
	v_pk_add_f32 v[50:51], v[50:51], v[104:105]
	s_waitcnt vmcnt(4)
	v_pk_add_f32 v[48:49], v[48:49], v[110:111]
	v_pk_add_f32 v[50:51], v[50:51], v[108:109]
	s_waitcnt vmcnt(3)
	v_pk_add_f32 v[48:49], v[48:49], v[114:115]
	v_pk_add_f32 v[50:51], v[50:51], v[112:113]
	s_waitcnt vmcnt(2)
	v_pk_add_f32 v[48:49], v[48:49], v[118:119]
	v_pk_add_f32 v[50:51], v[50:51], v[116:117]
	s_waitcnt vmcnt(1)
	v_pk_add_f32 v[48:49], v[48:49], v[122:123]
	v_pk_add_f32 v[50:51], v[50:51], v[120:121]
	s_waitcnt vmcnt(0)
	v_pk_add_f32 v[48:49], v[48:49], v[126:127]
	s_nop 0
	v_pk_add_f32 v[52:53], v[44:45], v[48:49]
	v_pk_add_f32 v[40:41], v[40:41], v[48:49]
	v_mul_f32_e32 v44, 0x3d372713, v52
	v_mul_f32_e32 v45, 0x3d372713, v53
	v_mul_f32_e32 v44, v52, v44
	v_mul_f32_e32 v45, v53, v45
	v_fma_f32 v44, v52, v44, v52
	v_fma_f32 v45, v53, v45, v53
	v_mul_f32_e32 v44, 0x3f4c422a, v44
	v_mul_f32_e32 v45, 0x3f4c422a, v45
	v_mul_f32_e32 v44, -2.0, v44
	v_mul_f32_e32 v45, -2.0, v45
	v_mul_f32_e32 v44, 0x3fb8aa3b, v44
	v_mul_f32_e32 v45, 0x3fb8aa3b, v45
	v_exp_f32_e32 v44, v44
	v_exp_f32_e32 v45, v45
	v_pk_add_f32 v[36:37], v[36:37], v[48:49]
	v_pk_add_f32 v[32:33], v[32:33], v[48:49]
	v_pk_add_f32 v[54:55], v[44:45], 1.0 op_sel_hi:[1,0]
	s_nop 0
	v_pk_add_f32 v[44:45], v[50:51], v[124:125]
	v_pk_add_f32 v[44:45], v[44:45], v[128:129]
	v_pk_add_f32 v[46:47], v[46:47], v[44:45]
	v_rcp_f32_e32 v50, v55
	s_nop 0
	v_mul_f32_e32 v53, v53, v50
	v_mul_f32_e32 v50, 0x3d372713, v46
	v_mul_f32_e32 v51, 0x3d372713, v47
	v_mul_f32_e32 v50, v46, v50
	v_mul_f32_e32 v51, v47, v51
	v_fma_f32 v50, v46, v50, v46
	v_fma_f32 v51, v47, v51, v47
	v_mul_f32_e32 v50, 0x3f4c422a, v50
	v_mul_f32_e32 v51, 0x3f4c422a, v51
	v_mul_f32_e32 v50, -2.0, v50
	v_mul_f32_e32 v51, -2.0, v51
	v_mul_f32_e32 v50, 0x3fb8aa3b, v50
	v_mul_f32_e32 v51, 0x3fb8aa3b, v51
	v_exp_f32_e32 v50, v50
	v_exp_f32_e32 v51, v51
	s_nop 0
	v_pk_add_f32 v[50:51], v[50:51], 1.0 op_sel_hi:[1,0]
	v_rcp_f32_e32 v55, v54
	s_nop 0
	v_mul_f32_e32 v52, v52, v55
	v_cvt_pk_bf16_f32 v52, v52, v53
	v_rcp_f32_e32 v53, v51
	s_nop 0
	v_mul_f32_e32 v51, v47, v53
	v_pk_add_f32 v[42:43], v[42:43], v[44:45]
	v_mul_f32_e32 v54, 0x3d372713, v40
	v_mul_f32_e32 v55, 0x3d372713, v41
	v_mul_f32_e32 v54, v40, v54
	v_mul_f32_e32 v55, v41, v55
	v_fma_f32 v54, v40, v54, v40
	v_fma_f32 v55, v41, v55, v41
	v_mul_f32_e32 v54, 0x3f4c422a, v54
	v_mul_f32_e32 v55, 0x3f4c422a, v55
	v_mul_f32_e32 v54, -2.0, v54
	v_mul_f32_e32 v55, -2.0, v55
	v_mul_f32_e32 v54, 0x3fb8aa3b, v54
	v_mul_f32_e32 v55, 0x3fb8aa3b, v55
	v_exp_f32_e32 v54, v54
	v_exp_f32_e32 v55, v55
	v_rcp_f32_e32 v47, v50
	s_nop 0
	v_mul_f32_e32 v50, v46, v47
	v_cvt_pk_bf16_f32 v53, v50, v51
	v_pk_add_f32 v[46:47], v[54:55], 1.0 op_sel_hi:[1,0]
	ds_write_b64 v56, v[52:53] offset:32
	v_pk_add_f32 v[38:39], v[38:39], v[44:45]
	v_pk_add_f32 v[34:35], v[34:35], v[44:45]
	v_rcp_f32_e32 v50, v47
	s_nop 0
	v_mul_f32_e32 v41, v41, v50
	v_mul_f32_e32 v50, 0x3d372713, v42
	v_mul_f32_e32 v51, 0x3d372713, v43
	v_mul_f32_e32 v50, v42, v50
	v_mul_f32_e32 v51, v43, v51
	v_fma_f32 v50, v42, v50, v42
	v_fma_f32 v51, v43, v51, v43
	v_mul_f32_e32 v50, 0x3f4c422a, v50
	v_mul_f32_e32 v51, 0x3f4c422a, v51
	v_mul_f32_e32 v50, -2.0, v50
	v_mul_f32_e32 v51, -2.0, v51
	v_mul_f32_e32 v50, 0x3fb8aa3b, v50
	v_mul_f32_e32 v51, 0x3fb8aa3b, v51
	v_exp_f32_e32 v50, v50
	v_exp_f32_e32 v51, v51
	s_nop 0
	v_pk_add_f32 v[50:51], v[50:51], 1.0 op_sel_hi:[1,0]
	v_rcp_f32_e32 v47, v46
	s_nop 0
	v_mul_f32_e32 v40, v40, v47
	v_cvt_pk_bf16_f32 v40, v40, v41
	v_rcp_f32_e32 v41, v51
	s_nop 0
	v_mul_f32_e32 v41, v43, v41
	v_mul_f32_e32 v46, 0x3d372713, v36
	v_mul_f32_e32 v47, 0x3d372713, v37
	v_mul_f32_e32 v46, v36, v46
	v_mul_f32_e32 v47, v37, v47
	v_fma_f32 v46, v36, v46, v36
	v_fma_f32 v47, v37, v47, v37
	v_mul_f32_e32 v46, 0x3f4c422a, v46
	v_mul_f32_e32 v47, 0x3f4c422a, v47
	v_mul_f32_e32 v46, -2.0, v46
	v_mul_f32_e32 v47, -2.0, v47
	v_mul_f32_e32 v46, 0x3fb8aa3b, v46
	v_mul_f32_e32 v47, 0x3fb8aa3b, v47
	v_exp_f32_e32 v46, v46
	v_exp_f32_e32 v47, v47
	v_rcp_f32_e32 v43, v50
	s_nop 0
	v_mul_f32_e32 v50, v42, v43
	v_cvt_pk_bf16_f32 v41, v50, v41
	v_pk_add_f32 v[42:43], v[46:47], 1.0 op_sel_hi:[1,0]
	ds_write_b64 v56, v[40:41] offset:8480
	s_nop 0
	v_rcp_f32_e32 v40, v43
	s_nop 0
	v_mul_f32_e32 v37, v37, v40
	v_mul_f32_e32 v41, 0x3d372713, v39
	v_mul_f32_e32 v40, 0x3d372713, v38
	v_mul_f32_e32 v40, v38, v40
	v_mul_f32_e32 v41, v39, v41
	v_fma_f32 v40, v38, v40, v38
	v_fma_f32 v41, v39, v41, v39
	v_mul_f32_e32 v40, 0x3f4c422a, v40
	v_mul_f32_e32 v41, 0x3f4c422a, v41
; DI unsigned pk2(float lo, float hi) { f32x2 v = {lo, hi}; return __builtin_bit_cast(unsigned, __builtin_convertvector(v, bfx2)); }
; DI float gelu_tanh(float x) { const float u = 0.7978845608028654f * (x + 0.044715f * x * x * x); return x / (1.f + __expf(-2.f * u)); }
; DI void compress_item(const Params& p, int layer, int item, bf16_t* smem) {
;     ...
; #pragma unroll
;   for (int j = 0; j < 4; ++j) {
;     asm volatile("" ::: "memory");
;     f32x4 bv = {0.f, 0.f, 0.f, 0.f};
;     for (int pc = 0; pc < 16; ++pc) bv += *(const f32x4*)(b1 + pc * 256 + wn * 64 + j * 16 + quad * 4);
; #pragma unroll
;     for (int i = 0; i < 4; ++i) {
;       const int row = wm * 64 + i * 16 + l15, col = wn * 64 + j * 16 + quad * 4;
;       *(u32x2*)(H + row * LDH + col) = (u32x2){pk2(gelu_tanh(acc[i][j][0] + bv[0]), gelu_tanh(acc[i][j][1] + bv[1])), pk2(gelu_tanh(acc[i][j][2] + bv[2]), gelu_tanh(acc[i][j][3] + bv[3]))};
;     }
;   }
	v_mul_f32_e32 v40, -2.0, v40
	v_mul_f32_e32 v41, -2.0, v41
	v_mul_f32_e32 v40, 0x3fb8aa3b, v40
	v_mul_f32_e32 v41, 0x3fb8aa3b, v41
	v_exp_f32_e32 v40, v40
	v_exp_f32_e32 v41, v41
	s_nop 0
	v_pk_add_f32 v[40:41], v[40:41], 1.0 op_sel_hi:[1,0]
	v_rcp_f32_e32 v43, v42
	s_nop 0
	v_mul_f32_e32 v36, v36, v43
	v_cvt_pk_bf16_f32 v36, v36, v37
	v_rcp_f32_e32 v37, v41
	s_nop 0
	v_mul_f32_e32 v37, v39, v37
	v_mul_f32_e32 v42, 0x3d372713, v32
	v_mul_f32_e32 v43, 0x3d372713, v33
	v_mul_f32_e32 v42, v32, v42
	v_mul_f32_e32 v43, v33, v43
	v_fma_f32 v42, v32, v42, v32
	v_fma_f32 v43, v33, v43, v33
	v_mul_f32_e32 v42, 0x3f4c422a, v42
	v_mul_f32_e32 v43, 0x3f4c422a, v43
	v_mul_f32_e32 v42, -2.0, v42
	v_mul_f32_e32 v43, -2.0, v43
	v_mul_f32_e32 v42, 0x3fb8aa3b, v42
	v_mul_f32_e32 v43, 0x3fb8aa3b, v43
	v_exp_f32_e32 v42, v42
	v_exp_f32_e32 v43, v43
	v_rcp_f32_e32 v39, v40
	s_nop 0
	v_mul_f32_e32 v40, v38, v39
	v_cvt_pk_bf16_f32 v37, v40, v37
	v_pk_add_f32 v[38:39], v[42:43], 1.0 op_sel_hi:[1,0]
	ds_write_b64 v56, v[36:37] offset:16928
	s_nop 0
	v_rcp_f32_e32 v36, v39
	s_nop 0
	v_mul_f32_e32 v33, v33, v36
	v_mul_f32_e32 v37, 0x3d372713, v35
	v_mul_f32_e32 v36, 0x3d372713, v34
	v_mul_f32_e32 v36, v34, v36
	v_mul_f32_e32 v37, v35, v37
	v_fma_f32 v36, v34, v36, v34
	v_fma_f32 v37, v35, v37, v35
	v_mul_f32_e32 v36, 0x3f4c422a, v36
	v_mul_f32_e32 v37, 0x3f4c422a, v37
	v_mul_f32_e32 v36, -2.0, v36
	v_mul_f32_e32 v37, -2.0, v37
	v_mul_f32_e32 v36, 0x3fb8aa3b, v36
	v_mul_f32_e32 v37, 0x3fb8aa3b, v37
	v_exp_f32_e32 v36, v36
	v_exp_f32_e32 v37, v37
	s_nop 0
	v_pk_add_f32 v[36:37], v[36:37], 1.0 op_sel_hi:[1,0]
	v_rcp_f32_e32 v39, v38
	s_nop 0
	v_mul_f32_e32 v32, v32, v39
	v_cvt_pk_bf16_f32 v32, v32, v33
	v_rcp_f32_e32 v33, v37
	s_nop 0
	v_mul_f32_e32 v33, v35, v33
	v_rcp_f32_e32 v35, v36
	s_nop 0
	v_mul_f32_e32 v34, v34, v35
	v_cvt_pk_bf16_f32 v33, v34, v33
	ds_write_b64 v56, v[32:33] offset:25376
	global_load_dwordx4 v[32:35], v[70:71], off offset:128
	global_load_dwordx4 v[36:39], v[70:71], off offset:1152
	global_load_dwordx4 v[40:43], v[70:71], off offset:2176
	global_load_dwordx4 v[44:47], v[70:71], off offset:3200
	global_load_dwordx4 v[48:51], v[66:67], off offset:128
	global_load_dwordx4 v[52:55], v[66:67], off offset:1152
	global_load_dwordx4 v[58:61], v[66:67], off offset:2176
	global_load_dwordx4 v[74:77], v[66:67], off offset:3200
	global_load_dwordx4 v[82:85], v[72:73], off offset:128
	global_load_dwordx4 v[86:89], v[72:73], off offset:1152
	global_load_dwordx4 v[90:93], v[72:73], off offset:2176
	global_load_dwordx4 v[94:97], v[72:73], off offset:3200
	global_load_dwordx4 v[98:101], v[68:69], off offset:128
	global_load_dwordx4 v[102:105], v[68:69], off offset:1152
	global_load_dwordx4 v[106:109], v[68:69], off offset:2176
	global_load_dwordx4 v[110:113], v[68:69], off offset:3200
	s_waitcnt vmcnt(15)
	v_pk_add_f32 v[32:33], v[32:33], 0 op_sel_hi:[1,0]
	s_waitcnt vmcnt(14)
	v_pk_add_f32 v[32:33], v[32:33], v[36:37]
	v_pk_add_f32 v[34:35], v[34:35], 0 op_sel_hi:[1,0]
	s_waitcnt vmcnt(13)
	v_pk_add_f32 v[32:33], v[32:33], v[40:41]
	v_pk_add_f32 v[34:35], v[34:35], v[38:39]
	s_waitcnt vmcnt(12)
	v_pk_add_f32 v[32:33], v[32:33], v[44:45]
	v_pk_add_f32 v[34:35], v[34:35], v[42:43]
	s_waitcnt vmcnt(11)
	v_pk_add_f32 v[32:33], v[32:33], v[48:49]
	v_pk_add_f32 v[34:35], v[34:35], v[46:47]
	s_waitcnt vmcnt(10)
	v_pk_add_f32 v[32:33], v[32:33], v[52:53]
	v_pk_add_f32 v[34:35], v[34:35], v[50:51]
	s_waitcnt vmcnt(9)
	v_pk_add_f32 v[32:33], v[32:33], v[58:59]
	v_pk_add_f32 v[34:35], v[34:35], v[54:55]
	s_waitcnt vmcnt(8)
	v_pk_add_f32 v[32:33], v[32:33], v[74:75]
	v_pk_add_f32 v[34:35], v[34:35], v[60:61]
	s_waitcnt vmcnt(7)
	v_pk_add_f32 v[32:33], v[32:33], v[82:83]
	v_pk_add_f32 v[34:35], v[34:35], v[76:77]
	s_waitcnt vmcnt(6)
	v_pk_add_f32 v[32:33], v[32:33], v[86:87]
	v_pk_add_f32 v[34:35], v[34:35], v[84:85]
	s_waitcnt vmcnt(5)
	v_pk_add_f32 v[32:33], v[32:33], v[90:91]
	v_pk_add_f32 v[34:35], v[34:35], v[88:89]
	s_waitcnt vmcnt(4)
	v_pk_add_f32 v[32:33], v[32:33], v[94:95]
	v_pk_add_f32 v[34:35], v[34:35], v[92:93]
	s_waitcnt vmcnt(3)
	v_pk_add_f32 v[32:33], v[32:33], v[98:99]
	v_pk_add_f32 v[34:35], v[34:35], v[96:97]
	s_waitcnt vmcnt(2)
	v_pk_add_f32 v[32:33], v[32:33], v[102:103]
	v_pk_add_f32 v[34:35], v[34:35], v[100:101]
	s_waitcnt vmcnt(1)
	v_pk_add_f32 v[32:33], v[32:33], v[106:107]
	v_pk_add_f32 v[34:35], v[34:35], v[104:105]
	s_waitcnt vmcnt(0)
; DI unsigned pk2(float lo, float hi) { f32x2 v = {lo, hi}; return __builtin_bit_cast(unsigned, __builtin_convertvector(v, bfx2)); }
; DI float gelu_tanh(float x) { const float u = 0.7978845608028654f * (x + 0.044715f * x * x * x); return x / (1.f + __expf(-2.f * u)); }
; DI void compress_item(const Params& p, int layer, int item, bf16_t* smem) {
;     ...
; #pragma unroll
;   for (int j = 0; j < 4; ++j) {
;     asm volatile("" ::: "memory");
;     f32x4 bv = {0.f, 0.f, 0.f, 0.f};
;     for (int pc = 0; pc < 16; ++pc) bv += *(const f32x4*)(b1 + pc * 256 + wn * 64 + j * 16 + quad * 4);
; #pragma unroll
;     for (int i = 0; i < 4; ++i) {
;       const int row = wm * 64 + i * 16 + l15, col = wn * 64 + j * 16 + quad * 4;
;       *(u32x2*)(H + row * LDH + col) = (u32x2){pk2(gelu_tanh(acc[i][j][0] + bv[0]), gelu_tanh(acc[i][j][1] + bv[1])), pk2(gelu_tanh(acc[i][j][2] + bv[2]), gelu_tanh(acc[i][j][3] + bv[3]))};
;     }
;   }
	v_pk_add_f32 v[32:33], v[32:33], v[110:111]
	s_nop 0
	v_pk_add_f32 v[36:37], v[28:29], v[32:33]
	v_pk_add_f32 v[24:25], v[24:25], v[32:33]
	v_mul_f32_e32 v28, 0x3d372713, v36
	v_mul_f32_e32 v29, 0x3d372713, v37
	v_mul_f32_e32 v28, v36, v28
	v_mul_f32_e32 v29, v37, v29
	v_fma_f32 v28, v36, v28, v36
	v_fma_f32 v29, v37, v29, v37
	v_mul_f32_e32 v28, 0x3f4c422a, v28
	v_mul_f32_e32 v29, 0x3f4c422a, v29
	v_mul_f32_e32 v28, -2.0, v28
	v_mul_f32_e32 v29, -2.0, v29
	v_mul_f32_e32 v28, 0x3fb8aa3b, v28
	v_mul_f32_e32 v29, 0x3fb8aa3b, v29
	v_exp_f32_e32 v28, v28
	v_exp_f32_e32 v29, v29
	v_pk_add_f32 v[20:21], v[20:21], v[32:33]
	v_pk_add_f32 v[16:17], v[16:17], v[32:33]
	v_pk_add_f32 v[38:39], v[28:29], 1.0 op_sel_hi:[1,0]
	s_nop 0
	v_pk_add_f32 v[28:29], v[34:35], v[108:109]
	v_pk_add_f32 v[28:29], v[28:29], v[112:113]
	v_pk_add_f32 v[30:31], v[30:31], v[28:29]
	v_rcp_f32_e32 v34, v39
	s_nop 0
	v_mul_f32_e32 v37, v37, v34
	v_mul_f32_e32 v34, 0x3d372713, v30
	v_mul_f32_e32 v35, 0x3d372713, v31
	v_mul_f32_e32 v34, v30, v34
	v_mul_f32_e32 v35, v31, v35
	v_fma_f32 v34, v30, v34, v30
	v_fma_f32 v35, v31, v35, v31
	v_mul_f32_e32 v34, 0x3f4c422a, v34
	v_mul_f32_e32 v35, 0x3f4c422a, v35
	v_mul_f32_e32 v34, -2.0, v34
	v_mul_f32_e32 v35, -2.0, v35
	v_mul_f32_e32 v34, 0x3fb8aa3b, v34
	v_mul_f32_e32 v35, 0x3fb8aa3b, v35
	v_exp_f32_e32 v34, v34
	v_exp_f32_e32 v35, v35
	s_nop 0
	v_pk_add_f32 v[34:35], v[34:35], 1.0 op_sel_hi:[1,0]
	v_rcp_f32_e32 v39, v38
	s_nop 0
	v_mul_f32_e32 v36, v36, v39
	v_cvt_pk_bf16_f32 v36, v36, v37
	v_rcp_f32_e32 v37, v35
	s_nop 0
	v_mul_f32_e32 v35, v31, v37
	v_pk_add_f32 v[26:27], v[26:27], v[28:29]
	v_mul_f32_e32 v38, 0x3d372713, v24
	v_mul_f32_e32 v39, 0x3d372713, v25
	v_mul_f32_e32 v38, v24, v38
	v_mul_f32_e32 v39, v25, v39
	v_fma_f32 v38, v24, v38, v24
	v_fma_f32 v39, v25, v39, v25
	v_mul_f32_e32 v38, 0x3f4c422a, v38
	v_mul_f32_e32 v39, 0x3f4c422a, v39
	v_mul_f32_e32 v38, -2.0, v38
	v_mul_f32_e32 v39, -2.0, v39
	v_mul_f32_e32 v38, 0x3fb8aa3b, v38
	v_mul_f32_e32 v39, 0x3fb8aa3b, v39
	v_exp_f32_e32 v38, v38
	v_exp_f32_e32 v39, v39
	v_rcp_f32_e32 v31, v34
	s_nop 0
	v_mul_f32_e32 v34, v30, v31
	v_cvt_pk_bf16_f32 v37, v34, v35
	v_pk_add_f32 v[30:31], v[38:39], 1.0 op_sel_hi:[1,0]
	ds_write_b64 v56, v[36:37] offset:64
	v_pk_add_f32 v[22:23], v[22:23], v[28:29]
	v_pk_add_f32 v[18:19], v[18:19], v[28:29]
	v_rcp_f32_e32 v34, v31
	s_nop 0
	v_mul_f32_e32 v25, v25, v34
	v_mul_f32_e32 v34, 0x3d372713, v26
	v_mul_f32_e32 v35, 0x3d372713, v27
	v_mul_f32_e32 v34, v26, v34
	v_mul_f32_e32 v35, v27, v35
	v_fma_f32 v34, v26, v34, v26
	v_fma_f32 v35, v27, v35, v27
	v_mul_f32_e32 v34, 0x3f4c422a, v34
	v_mul_f32_e32 v35, 0x3f4c422a, v35
	v_mul_f32_e32 v34, -2.0, v34
	v_mul_f32_e32 v35, -2.0, v35
	v_mul_f32_e32 v34, 0x3fb8aa3b, v34
	v_mul_f32_e32 v35, 0x3fb8aa3b, v35
	v_exp_f32_e32 v34, v34
	v_exp_f32_e32 v35, v35
	s_nop 0
	v_pk_add_f32 v[34:35], v[34:35], 1.0 op_sel_hi:[1,0]
	v_rcp_f32_e32 v31, v30
	s_nop 0
	v_mul_f32_e32 v24, v24, v31
	v_cvt_pk_bf16_f32 v24, v24, v25
	v_rcp_f32_e32 v25, v35
	s_nop 0
	v_mul_f32_e32 v25, v27, v25
	v_mul_f32_e32 v30, 0x3d372713, v20
	v_mul_f32_e32 v31, 0x3d372713, v21
	v_mul_f32_e32 v30, v20, v30
	v_mul_f32_e32 v31, v21, v31
	v_fma_f32 v30, v20, v30, v20
	v_fma_f32 v31, v21, v31, v21
	v_mul_f32_e32 v30, 0x3f4c422a, v30
	v_mul_f32_e32 v31, 0x3f4c422a, v31
	v_mul_f32_e32 v30, -2.0, v30
	v_mul_f32_e32 v31, -2.0, v31
	v_mul_f32_e32 v30, 0x3fb8aa3b, v30
	v_mul_f32_e32 v31, 0x3fb8aa3b, v31
	v_exp_f32_e32 v30, v30
	v_exp_f32_e32 v31, v31
	v_rcp_f32_e32 v27, v34
	s_nop 0
	v_mul_f32_e32 v34, v26, v27
	v_cvt_pk_bf16_f32 v25, v34, v25
	v_pk_add_f32 v[26:27], v[30:31], 1.0 op_sel_hi:[1,0]
	ds_write_b64 v56, v[24:25] offset:8512
	s_nop 0
	v_rcp_f32_e32 v24, v27
	s_nop 0
	v_mul_f32_e32 v21, v21, v24
	v_mul_f32_e32 v25, 0x3d372713, v23
	v_mul_f32_e32 v24, 0x3d372713, v22
	v_mul_f32_e32 v24, v22, v24
	v_mul_f32_e32 v25, v23, v25
	v_fma_f32 v24, v22, v24, v22
	v_fma_f32 v25, v23, v25, v23
	v_mul_f32_e32 v24, 0x3f4c422a, v24
	v_mul_f32_e32 v25, 0x3f4c422a, v25
	v_mul_f32_e32 v24, -2.0, v24
	v_mul_f32_e32 v25, -2.0, v25
	v_mul_f32_e32 v24, 0x3fb8aa3b, v24
	v_mul_f32_e32 v25, 0x3fb8aa3b, v25
	v_exp_f32_e32 v24, v24
	v_exp_f32_e32 v25, v25
	s_nop 0
	v_pk_add_f32 v[24:25], v[24:25], 1.0 op_sel_hi:[1,0]
	v_rcp_f32_e32 v27, v26
	s_nop 0
	v_mul_f32_e32 v20, v20, v27
	v_cvt_pk_bf16_f32 v20, v20, v21
	v_rcp_f32_e32 v21, v25
	s_nop 0
	v_mul_f32_e32 v21, v23, v21
	v_mul_f32_e32 v26, 0x3d372713, v16
	v_mul_f32_e32 v27, 0x3d372713, v17
	v_mul_f32_e32 v26, v16, v26
	v_mul_f32_e32 v27, v17, v27
	v_fma_f32 v26, v16, v26, v16
	v_fma_f32 v27, v17, v27, v17
	v_mul_f32_e32 v26, 0x3f4c422a, v26
	v_mul_f32_e32 v27, 0x3f4c422a, v27
	v_mul_f32_e32 v26, -2.0, v26
	v_mul_f32_e32 v27, -2.0, v27
	v_mul_f32_e32 v26, 0x3fb8aa3b, v26
	v_mul_f32_e32 v27, 0x3fb8aa3b, v27
	v_exp_f32_e32 v26, v26
	v_exp_f32_e32 v27, v27
	v_rcp_f32_e32 v23, v24
	s_nop 0
	v_mul_f32_e32 v24, v22, v23
	v_cvt_pk_bf16_f32 v21, v24, v21
	v_pk_add_f32 v[22:23], v[26:27], 1.0 op_sel_hi:[1,0]
	ds_write_b64 v56, v[20:21] offset:16960
	s_nop 0
	v_rcp_f32_e32 v20, v23
	s_nop 0
	v_mul_f32_e32 v17, v17, v20
	v_mul_f32_e32 v21, 0x3d372713, v19
	v_mul_f32_e32 v20, 0x3d372713, v18
	v_mul_f32_e32 v20, v18, v20
	v_mul_f32_e32 v21, v19, v21
	v_fma_f32 v20, v18, v20, v18
	v_fma_f32 v21, v19, v21, v19
	v_mul_f32_e32 v20, 0x3f4c422a, v20
	v_mul_f32_e32 v21, 0x3f4c422a, v21
	v_mul_f32_e32 v20, -2.0, v20
	v_mul_f32_e32 v21, -2.0, v21
	v_mul_f32_e32 v20, 0x3fb8aa3b, v20
	v_mul_f32_e32 v21, 0x3fb8aa3b, v21
	v_exp_f32_e32 v20, v20
	v_exp_f32_e32 v21, v21
	s_nop 0
	v_pk_add_f32 v[20:21], v[20:21], 1.0 op_sel_hi:[1,0]
	v_rcp_f32_e32 v23, v22
	s_nop 0
	v_mul_f32_e32 v16, v16, v23
	v_cvt_pk_bf16_f32 v16, v16, v17
	v_rcp_f32_e32 v17, v21
	s_nop 0
	v_mul_f32_e32 v17, v19, v17
	v_rcp_f32_e32 v19, v20
	s_nop 0
	v_mul_f32_e32 v18, v18, v19
	v_cvt_pk_bf16_f32 v17, v18, v17
	ds_write_b64 v56, v[16:17] offset:25408
	global_load_dwordx4 v[16:19], v[70:71], off offset:192
	global_load_dwordx4 v[20:23], v[70:71], off offset:1216
	global_load_dwordx4 v[24:27], v[70:71], off offset:2240
	global_load_dwordx4 v[28:31], v[70:71], off offset:3264
	global_load_dwordx4 v[32:35], v[66:67], off offset:192
	global_load_dwordx4 v[36:39], v[66:67], off offset:1216
	global_load_dwordx4 v[40:43], v[66:67], off offset:2240
	global_load_dwordx4 v[44:47], v[66:67], off offset:3264
	global_load_dwordx4 v[48:51], v[72:73], off offset:192
	global_load_dwordx4 v[52:55], v[72:73], off offset:1216
	global_load_dwordx4 v[58:61], v[72:73], off offset:2240
	s_nop 0
	global_load_dwordx4 v[70:73], v[72:73], off offset:3264
	s_nop 0
	global_load_dwordx4 v[74:77], v[68:69], off offset:192
	global_load_dwordx4 v[82:85], v[68:69], off offset:1216
	global_load_dwordx4 v[86:89], v[68:69], off offset:2240
	s_nop 0
	global_load_dwordx4 v[66:69], v[68:69], off offset:3264
	s_waitcnt vmcnt(15)
; DI unsigned pk2(float lo, float hi) { f32x2 v = {lo, hi}; return __builtin_bit_cast(unsigned, __builtin_convertvector(v, bfx2)); }
; DI float gelu_tanh(float x) { const float u = 0.7978845608028654f * (x + 0.044715f * x * x * x); return x / (1.f + __expf(-2.f * u)); }
; DI void compress_item(const Params& p, int layer, int item, bf16_t* smem) {
;     ...
; #pragma unroll
;   for (int j = 0; j < 4; ++j) {
;     asm volatile("" ::: "memory");
;     f32x4 bv = {0.f, 0.f, 0.f, 0.f};
;     for (int pc = 0; pc < 16; ++pc) bv += *(const f32x4*)(b1 + pc * 256 + wn * 64 + j * 16 + quad * 4);
; #pragma unroll
;     for (int i = 0; i < 4; ++i) {
;       const int row = wm * 64 + i * 16 + l15, col = wn * 64 + j * 16 + quad * 4;
;       *(u32x2*)(H + row * LDH + col) = (u32x2){pk2(gelu_tanh(acc[i][j][0] + bv[0]), gelu_tanh(acc[i][j][1] + bv[1])), pk2(gelu_tanh(acc[i][j][2] + bv[2]), gelu_tanh(acc[i][j][3] + bv[3]))};
;     }
;   }
	v_pk_add_f32 v[16:17], v[16:17], 0 op_sel_hi:[1,0]
	s_waitcnt vmcnt(14)
	v_pk_add_f32 v[16:17], v[16:17], v[20:21]
	v_pk_add_f32 v[18:19], v[18:19], 0 op_sel_hi:[1,0]
	s_waitcnt vmcnt(13)
	v_pk_add_f32 v[16:17], v[16:17], v[24:25]
	v_pk_add_f32 v[18:19], v[18:19], v[22:23]
	s_waitcnt vmcnt(12)
	v_pk_add_f32 v[16:17], v[16:17], v[28:29]
	v_pk_add_f32 v[18:19], v[18:19], v[26:27]
	s_waitcnt vmcnt(11)
	v_pk_add_f32 v[16:17], v[16:17], v[32:33]
	v_pk_add_f32 v[18:19], v[18:19], v[30:31]
	s_waitcnt vmcnt(10)
	v_pk_add_f32 v[16:17], v[16:17], v[36:37]
	v_pk_add_f32 v[18:19], v[18:19], v[34:35]
	s_waitcnt vmcnt(9)
	v_pk_add_f32 v[16:17], v[16:17], v[40:41]
	v_pk_add_f32 v[18:19], v[18:19], v[38:39]
	s_waitcnt vmcnt(8)
	v_pk_add_f32 v[16:17], v[16:17], v[44:45]
	v_pk_add_f32 v[18:19], v[18:19], v[42:43]
	s_waitcnt vmcnt(7)
	v_pk_add_f32 v[16:17], v[16:17], v[48:49]
	v_pk_add_f32 v[18:19], v[18:19], v[46:47]
	s_waitcnt vmcnt(6)
	v_pk_add_f32 v[16:17], v[16:17], v[52:53]
	v_pk_add_f32 v[18:19], v[18:19], v[50:51]
	s_waitcnt vmcnt(5)
	v_pk_add_f32 v[16:17], v[16:17], v[58:59]
	v_pk_add_f32 v[18:19], v[18:19], v[54:55]
	s_waitcnt vmcnt(4)
	v_pk_add_f32 v[16:17], v[16:17], v[70:71]
	v_pk_add_f32 v[18:19], v[18:19], v[60:61]
	s_waitcnt vmcnt(3)
	v_pk_add_f32 v[16:17], v[16:17], v[74:75]
	v_pk_add_f32 v[18:19], v[18:19], v[72:73]
	s_waitcnt vmcnt(2)
	v_pk_add_f32 v[16:17], v[16:17], v[82:83]
	v_pk_add_f32 v[18:19], v[18:19], v[76:77]
	s_waitcnt vmcnt(1)
	v_pk_add_f32 v[16:17], v[16:17], v[86:87]
	v_pk_add_f32 v[18:19], v[18:19], v[84:85]
	s_waitcnt vmcnt(0)
	v_pk_add_f32 v[16:17], v[16:17], v[66:67]
	v_lshlrev_b32_e32 v48, 4, v80
	v_pk_add_f32 v[20:21], v[12:13], v[16:17]
	v_pk_add_f32 v[8:9], v[8:9], v[16:17]
	v_mul_f32_e32 v12, 0x3d372713, v20
	v_mul_f32_e32 v13, 0x3d372713, v21
	v_mul_f32_e32 v12, v20, v12
	v_mul_f32_e32 v13, v21, v13
	v_fma_f32 v12, v20, v12, v20
	v_fma_f32 v13, v21, v13, v21
	v_mul_f32_e32 v12, 0x3f4c422a, v12
	v_mul_f32_e32 v13, 0x3f4c422a, v13
	v_mul_f32_e32 v12, -2.0, v12
	v_mul_f32_e32 v13, -2.0, v13
	v_mul_f32_e32 v12, 0x3fb8aa3b, v12
	v_mul_f32_e32 v13, 0x3fb8aa3b, v13
	v_exp_f32_e32 v12, v12
	v_exp_f32_e32 v13, v13
	v_pk_add_f32 v[4:5], v[4:5], v[16:17]
	v_pk_add_f32 v[0:1], v[0:1], v[16:17]
	v_mov_b32_e32 v43, v65
	v_pk_add_f32 v[22:23], v[12:13], 1.0 op_sel_hi:[1,0]
	v_pk_add_f32 v[12:13], v[18:19], v[88:89]
	v_pk_add_f32 v[12:13], v[12:13], v[68:69]
	v_mov_b32_e32 v45, v65
	v_pk_add_f32 v[14:15], v[14:15], v[12:13]
	v_rcp_f32_e32 v18, v23
	s_nop 0
	v_mul_f32_e32 v21, v21, v18
	v_mul_f32_e32 v19, 0x3d372713, v15
	v_mul_f32_e32 v18, 0x3d372713, v14
	v_mul_f32_e32 v18, v14, v18
	v_mul_f32_e32 v19, v15, v19
	v_fma_f32 v18, v14, v18, v14
	v_fma_f32 v19, v15, v19, v15
	v_mul_f32_e32 v18, 0x3f4c422a, v18
	v_mul_f32_e32 v19, 0x3f4c422a, v19
	v_mul_f32_e32 v18, -2.0, v18
	v_mul_f32_e32 v19, -2.0, v19
	v_mul_f32_e32 v18, 0x3fb8aa3b, v18
	v_mul_f32_e32 v19, 0x3fb8aa3b, v19
	v_exp_f32_e32 v18, v18
	v_exp_f32_e32 v19, v19
	s_nop 0
	v_pk_add_f32 v[18:19], v[18:19], 1.0 op_sel_hi:[1,0]
	v_rcp_f32_e32 v23, v22
	s_nop 0
	v_mul_f32_e32 v20, v20, v23
	v_cvt_pk_bf16_f32 v20, v20, v21
	v_rcp_f32_e32 v21, v19
	s_nop 0
	v_mul_f32_e32 v19, v15, v21
	v_pk_add_f32 v[10:11], v[10:11], v[12:13]
	v_mul_f32_e32 v22, 0x3d372713, v8
	v_mul_f32_e32 v23, 0x3d372713, v9
	v_mul_f32_e32 v22, v8, v22
	v_mul_f32_e32 v23, v9, v23
	v_fma_f32 v22, v8, v22, v8
	v_fma_f32 v23, v9, v23, v9
	v_mul_f32_e32 v22, 0x3f4c422a, v22
	v_mul_f32_e32 v23, 0x3f4c422a, v23
	v_mul_f32_e32 v22, -2.0, v22
	v_mul_f32_e32 v23, -2.0, v23
	v_mul_f32_e32 v22, 0x3fb8aa3b, v22
	v_mul_f32_e32 v23, 0x3fb8aa3b, v23
	v_exp_f32_e32 v22, v22
	v_exp_f32_e32 v23, v23
	v_rcp_f32_e32 v15, v18
	s_nop 0
	v_mul_f32_e32 v18, v14, v15
	v_cvt_pk_bf16_f32 v21, v18, v19
	v_pk_add_f32 v[14:15], v[22:23], 1.0 op_sel_hi:[1,0]
	ds_write_b64 v56, v[20:21] offset:96
	v_pk_add_f32 v[6:7], v[6:7], v[12:13]
	v_pk_add_f32 v[2:3], v[2:3], v[12:13]
	v_rcp_f32_e32 v18, v15
	s_nop 0
	v_mul_f32_e32 v9, v9, v18
	v_mul_f32_e32 v18, 0x3d372713, v10
	v_mul_f32_e32 v19, 0x3d372713, v11
	v_mul_f32_e32 v18, v10, v18
	v_mul_f32_e32 v19, v11, v19
	v_fma_f32 v18, v10, v18, v10
	v_fma_f32 v19, v11, v19, v11
	v_mul_f32_e32 v18, 0x3f4c422a, v18
	v_mul_f32_e32 v19, 0x3f4c422a, v19
	v_mul_f32_e32 v18, -2.0, v18
	v_mul_f32_e32 v19, -2.0, v19
	v_mul_f32_e32 v18, 0x3fb8aa3b, v18
	v_mul_f32_e32 v19, 0x3fb8aa3b, v19
	v_exp_f32_e32 v18, v18
	v_exp_f32_e32 v19, v19
	s_nop 0
	v_pk_add_f32 v[18:19], v[18:19], 1.0 op_sel_hi:[1,0]
	v_rcp_f32_e32 v15, v14
	s_nop 0
	v_mul_f32_e32 v8, v8, v15
	v_cvt_pk_bf16_f32 v8, v8, v9
	v_rcp_f32_e32 v9, v19
	s_nop 0
	v_mul_f32_e32 v9, v11, v9
	v_mul_f32_e32 v14, 0x3d372713, v4
	v_mul_f32_e32 v15, 0x3d372713, v5
	v_mul_f32_e32 v14, v4, v14
	v_mul_f32_e32 v15, v5, v15
	v_fma_f32 v14, v4, v14, v4
	v_fma_f32 v15, v5, v15, v5
	v_mul_f32_e32 v14, 0x3f4c422a, v14
	v_mul_f32_e32 v15, 0x3f4c422a, v15
	v_mul_f32_e32 v14, -2.0, v14
	v_mul_f32_e32 v15, -2.0, v15
	v_mul_f32_e32 v14, 0x3fb8aa3b, v14
	v_mul_f32_e32 v15, 0x3fb8aa3b, v15
	v_exp_f32_e32 v14, v14
	v_exp_f32_e32 v15, v15
	v_rcp_f32_e32 v11, v18
	s_nop 0
	v_mul_f32_e32 v18, v10, v11
	v_cvt_pk_bf16_f32 v9, v18, v9
	v_pk_add_f32 v[10:11], v[14:15], 1.0 op_sel_hi:[1,0]
	ds_write_b64 v56, v[8:9] offset:8544
	s_nop 0
	v_rcp_f32_e32 v8, v11
	s_nop 0
	v_mul_f32_e32 v5, v5, v8
	v_mul_f32_e32 v9, 0x3d372713, v7
	v_mul_f32_e32 v8, 0x3d372713, v6
	v_mul_f32_e32 v8, v6, v8
	v_mul_f32_e32 v9, v7, v9
	v_fma_f32 v8, v6, v8, v6
	v_fma_f32 v9, v7, v9, v7
	v_mul_f32_e32 v8, 0x3f4c422a, v8
	v_mul_f32_e32 v9, 0x3f4c422a, v9
	v_mul_f32_e32 v8, -2.0, v8
	v_mul_f32_e32 v9, -2.0, v9
; DI unsigned pk2(float lo, float hi) { f32x2 v = {lo, hi}; return __builtin_bit_cast(unsigned, __builtin_convertvector(v, bfx2)); }
; DI float gelu_tanh(float x) { const float u = 0.7978845608028654f * (x + 0.044715f * x * x * x); return x / (1.f + __expf(-2.f * u)); }
; DI f32x4 mfma16(bf16x8 a, bf16x8 b, f32x4 c) { return __builtin_amdgcn_mfma_f32_16x16x32_bf16(a, b, c, 0, 0, 0); }
; DI void compress_item(const Params& p, int layer, int item, bf16_t* smem) {
;     ...
; #pragma unroll
;   for (int j = 0; j < 4; ++j) {
;     asm volatile("" ::: "memory");
;     f32x4 bv = {0.f, 0.f, 0.f, 0.f};
;     for (int pc = 0; pc < 16; ++pc) bv += *(const f32x4*)(b1 + pc * 256 + wn * 64 + j * 16 + quad * 4);
; #pragma unroll
;     for (int i = 0; i < 4; ++i) {
;       const int row = wm * 64 + i * 16 + l15, col = wn * 64 + j * 16 + quad * 4;
;       *(u32x2*)(H + row * LDH + col) = (u32x2){pk2(gelu_tanh(acc[i][j][0] + bv[0]), gelu_tanh(acc[i][j][1] + bv[1])), pk2(gelu_tanh(acc[i][j][2] + bv[2]), gelu_tanh(acc[i][j][3] + bv[3]))};
;     }
;   }
;   __syncthreads();
;   f32x4 a2[4];
; #pragma unroll
;   for (int j = 0; j < 4; ++j) a2[j] = (f32x4){0.f, 0.f, 0.f, 0.f};
;   const bf16_t* w2 = wl + (kv ? W_2V : W_2K);
; #pragma unroll
;   for (int ks = 0; ks < 8; ++ks) {
;     const bf16x8 a = *(const bf16x8*)(H + (wid * 16 + l15) * LDH + ks * 32 + quad * 8);
; #pragma unroll
;     for (int j = 0; j < 4; ++j) a2[j] = mfma16(a, *(const bf16x8*)(w2 + (size_t)(j * 16 + l15) * 256 + ks * 32 + quad * 8), a2[j]);
;   }
	v_mul_f32_e32 v8, 0x3fb8aa3b, v8
	v_mul_f32_e32 v9, 0x3fb8aa3b, v9
	v_exp_f32_e32 v8, v8
	v_exp_f32_e32 v9, v9
	s_nop 0
	v_pk_add_f32 v[8:9], v[8:9], 1.0 op_sel_hi:[1,0]
	v_rcp_f32_e32 v11, v10
	s_nop 0
	v_mul_f32_e32 v4, v4, v11
	v_cvt_pk_bf16_f32 v4, v4, v5
	v_rcp_f32_e32 v5, v9
	s_nop 0
	v_mul_f32_e32 v5, v7, v5
	v_mul_f32_e32 v10, 0x3d372713, v0
	v_mul_f32_e32 v11, 0x3d372713, v1
	v_mul_f32_e32 v10, v0, v10
	v_mul_f32_e32 v11, v1, v11
	v_fma_f32 v10, v0, v10, v0
	v_fma_f32 v11, v1, v11, v1
	v_mul_f32_e32 v10, 0x3f4c422a, v10
	v_mul_f32_e32 v11, 0x3f4c422a, v11
	v_mul_f32_e32 v10, -2.0, v10
	v_mul_f32_e32 v11, -2.0, v11
	v_mul_f32_e32 v10, 0x3fb8aa3b, v10
	v_mul_f32_e32 v11, 0x3fb8aa3b, v11
	v_exp_f32_e32 v10, v10
	v_exp_f32_e32 v11, v11
	v_rcp_f32_e32 v7, v8
	s_nop 0
	v_mul_f32_e32 v8, v6, v7
	v_cvt_pk_bf16_f32 v5, v8, v5
	v_pk_add_f32 v[6:7], v[10:11], 1.0 op_sel_hi:[1,0]
	ds_write_b64 v56, v[4:5] offset:16992
	s_nop 0
	v_rcp_f32_e32 v4, v7
	s_nop 0
	v_mul_f32_e32 v1, v1, v4
	v_mul_f32_e32 v5, 0x3d372713, v3
	v_mul_f32_e32 v4, 0x3d372713, v2
	v_mul_f32_e32 v4, v2, v4
	v_mul_f32_e32 v5, v3, v5
	v_fma_f32 v4, v2, v4, v2
	v_fma_f32 v5, v3, v5, v3
	v_mul_f32_e32 v4, 0x3f4c422a, v4
	v_mul_f32_e32 v5, 0x3f4c422a, v5
	v_mul_f32_e32 v4, -2.0, v4
	v_mul_f32_e32 v5, -2.0, v5
	v_mul_f32_e32 v4, 0x3fb8aa3b, v4
	v_mul_f32_e32 v5, 0x3fb8aa3b, v5
	v_exp_f32_e32 v4, v4
	v_exp_f32_e32 v5, v5
	s_nop 0
	v_pk_add_f32 v[4:5], v[4:5], 1.0 op_sel_hi:[1,0]
	v_rcp_f32_e32 v7, v6
	s_nop 0
	v_mul_f32_e32 v0, v0, v7
	v_cvt_pk_bf16_f32 v0, v0, v1
	v_rcp_f32_e32 v1, v5
	s_nop 0
	v_mul_f32_e32 v1, v3, v1
	s_add_u32 s6, s11, s1
	v_rcp_f32_e32 v3, v4
	s_nop 0
	v_mul_f32_e32 v2, v2, v3
	v_cvt_pk_bf16_f32 v1, v2, v1
	ds_write_b64 v56, v[0:1] offset:25440
	s_addc_u32 s7, s12, 0
	v_or_b32_e32 v0, v48, v78
	v_mad_u64_u32 v[36:37], s[0:1], v0, s0, v[64:65]
	v_lshl_add_u64 v[38:39], s[6:7], 0, v[64:65]
	v_lshlrev_b32_e32 v64, 9, v78
	v_lshl_add_u64 v[40:41], v[38:39], 0, v[64:65]
	s_waitcnt lgkmcnt(0)
	s_barrier
	global_load_dwordx4 v[0:3], v[40:41], off
	v_or_b32_e32 v42, 0x2000, v64
	v_lshl_add_u64 v[4:5], v[38:39], 0, v[42:43]
	global_load_dwordx4 v[4:7], v[4:5], off
	ds_read_b128 v[8:11], v36
	ds_read_b128 v[12:15], v36 offset:64
	global_load_dwordx4 v[16:19], v[40:41], off offset:64
	v_or_b32_e32 v44, 0x4000, v64
	s_waitcnt vmcnt(2) lgkmcnt(1)
	v_mfma_f32_16x16x32_bf16 v[0:3], v[8:11], v[0:3], 0
	v_lshl_add_u64 v[20:21], v[38:39], 0, v[44:45]
	v_or_b32_e32 v64, 0x6000, v64
	global_load_dwordx4 v[20:23], v[20:21], off
	v_lshl_add_u64 v[24:25], v[38:39], 0, v[64:65]
	v_lshl_add_u64 v[32:33], v[38:39], 0, 64
	global_load_dwordx4 v[24:27], v[24:25], off
	v_lshl_add_u64 v[28:29], v[32:33], 0, v[42:43]
	global_load_dwordx4 v[28:31], v[28:29], off
	s_waitcnt vmcnt(3) lgkmcnt(0)
	v_mfma_f32_16x16x32_bf16 v[0:3], v[12:15], v[16:19], v[0:3]
	v_lshl_add_u64 v[16:17], v[32:33], 0, v[44:45]
	global_load_dwordx4 v[16:19], v[16:17], off
	s_mov_b64 s[0:1], 0x80
	v_mfma_f32_16x16x32_bf16 v[4:7], v[8:11], v[4:7], 0
	v_lshl_add_u64 v[46:47], v[38:39], 0, s[0:1]
	s_mov_b64 s[0:1], 0xc0
	s_add_u32 s6, s8, 0x1e454000
	s_waitcnt vmcnt(3)
	v_mfma_f32_16x16x32_bf16 v[20:23], v[8:11], v[20:23], 0
	s_addc_u32 s7, s9, 0
	s_add_u32 s8, s8, 0x1e4d4000
	s_addc_u32 s9, s9, 0
	s_waitcnt vmcnt(2)
	v_mfma_f32_16x16x32_bf16 v[8:11], v[8:11], v[24:27], 0
	v_lshl_add_u64 v[24:25], v[32:33], 0, v[64:65]
	s_waitcnt vmcnt(1)
	v_mfma_f32_16x16x32_bf16 v[4:7], v[12:15], v[28:31], v[4:7]
	global_load_dwordx4 v[24:27], v[24:25], off
	s_nop 0
	global_load_dwordx4 v[28:31], v[40:41], off offset:128
	s_waitcnt vmcnt(2)
	v_mfma_f32_16x16x32_bf16 v[16:19], v[12:15], v[16:19], v[20:23]
	s_nop 2
	v_lshl_add_u64 v[20:21], v[46:47], 0, v[42:43]
	global_load_dwordx4 v[20:23], v[20:21], off
	s_waitcnt vmcnt(2)
	v_mfma_f32_16x16x32_bf16 v[8:11], v[12:15], v[24:27], v[8:11]
	ds_read_b128 v[12:15], v36 offset:128
	ds_read_b128 v[24:27], v36 offset:192
	global_load_dwordx4 v[32:35], v[40:41], off offset:192
	s_waitcnt vmcnt(2) lgkmcnt(1)
	v_mfma_f32_16x16x32_bf16 v[0:3], v[12:15], v[28:31], v[0:3]
	v_lshl_add_u64 v[28:29], v[46:47], 0, v[44:45]
	global_load_dwordx4 v[28:31], v[28:29], off
	s_waitcnt vmcnt(2)
	v_mfma_f32_16x16x32_bf16 v[4:7], v[12:15], v[20:23], v[4:7]
	v_lshl_add_u64 v[20:21], v[46:47], 0, v[64:65]
	global_load_dwordx4 v[20:23], v[20:21], off
	v_lshl_add_u64 v[46:47], v[38:39], 0, s[0:1]
	s_waitcnt vmcnt(1)
	v_mfma_f32_16x16x32_bf16 v[16:19], v[12:15], v[28:31], v[16:19]
	v_lshl_add_u64 v[28:29], v[46:47], 0, v[42:43]
	global_load_dwordx4 v[28:31], v[28:29], off
	s_mov_b64 s[0:1], 0x100
	s_waitcnt vmcnt(1)
; DI bf16_t f2bf(float x) { return (bf16_t)(pk2(x, 0.f) & 0xffffu); }
; DI f32x4 mfma16(bf16x8 a, bf16x8 b, f32x4 c) { return __builtin_amdgcn_mfma_f32_16x16x32_bf16(a, b, c, 0, 0, 0); }
; DI void compress_item(const Params& p, int layer, int item, bf16_t* smem) {
;     ...
; #pragma unroll
;   for (int ks = 0; ks < 8; ++ks) {
;     const bf16x8 a = *(const bf16x8*)(H + (wid * 16 + l15) * LDH + ks * 32 + quad * 8);
; #pragma unroll
;     for (int j = 0; j < 4; ++j) a2[j] = mfma16(a, *(const bf16x8*)(w2 + (size_t)(j * 16 + l15) * 256 + ks * 32 + quad * 8), a2[j]);
;   }
;   bf16_t* kc = (bf16_t*)(p.ws + O_KC); bf16_t* vct = (bf16_t*)(p.ws + O_VCT);
; #pragma unroll
;   for (int r = 0; r < 4; ++r) {
;     const int R = tm * 128 + wid * 16 + quad * 4 + r;
;     if (R < 4080) {
;       const int b = R / 510, rem = R - b * 510, n = rem >> 1, g = rem & 1;
; #pragma unroll
;       for (int j = 0; j < 4; ++j) {
;         const int d = j * 16 + l15; const bf16_t v = f2bf(a2[j][r]);
;         if (kv == 0) kc[((size_t)(b * 2 + g) * 256 + n) * 64 + d] = v; else vct[((size_t)(b * 2 + g) * 64 + d) * 256 + n] = v;
;       }
;     }
	v_mfma_f32_16x16x32_bf16 v[8:11], v[12:15], v[20:23], v[8:11]
	v_lshl_add_u64 v[12:13], v[46:47], 0, v[44:45]
	global_load_dwordx4 v[12:15], v[12:13], off
	v_lshl_add_u64 v[20:21], v[46:47], 0, v[64:65]
	global_load_dwordx4 v[20:23], v[20:21], off
	v_lshl_add_u64 v[46:47], v[38:39], 0, s[0:1]
	s_waitcnt vmcnt(1) lgkmcnt(0)
	v_mfma_f32_16x16x32_bf16 v[12:15], v[24:27], v[12:15], v[16:19]
	s_nop 2
	v_lshl_add_u64 v[16:17], v[46:47], 0, v[42:43]
	global_load_dwordx4 v[16:19], v[16:17], off
	s_mov_b64 s[0:1], 0x140
	v_mfma_f32_16x16x32_bf16 v[4:7], v[24:27], v[28:31], v[4:7]
	global_load_dwordx4 v[28:31], v[40:41], off offset:256
	v_mfma_f32_16x16x32_bf16 v[0:3], v[24:27], v[32:35], v[0:3]
	s_waitcnt vmcnt(2)
	v_mfma_f32_16x16x32_bf16 v[8:11], v[24:27], v[20:23], v[8:11]
	ds_read_b128 v[20:23], v36 offset:256
	ds_read_b128 v[24:27], v36 offset:320
	global_load_dwordx4 v[32:35], v[40:41], off offset:320
	s_waitcnt vmcnt(1) lgkmcnt(1)
	v_mfma_f32_16x16x32_bf16 v[0:3], v[20:23], v[28:31], v[0:3]
	v_lshl_add_u64 v[28:29], v[46:47], 0, v[44:45]
	global_load_dwordx4 v[28:31], v[28:29], off
	v_mfma_f32_16x16x32_bf16 v[4:7], v[20:23], v[16:19], v[4:7]
	v_lshl_add_u64 v[16:17], v[46:47], 0, v[64:65]
	global_load_dwordx4 v[16:19], v[16:17], off
	v_lshl_add_u64 v[46:47], v[38:39], 0, s[0:1]
	s_waitcnt vmcnt(0)
	v_mfma_f32_16x16x32_bf16 v[8:11], v[20:23], v[16:19], v[8:11]
	v_lshl_add_u64 v[16:17], v[46:47], 0, v[44:45]
	global_load_dwordx4 v[16:19], v[16:17], off
	s_mov_b64 s[0:1], 0x180
	v_mfma_f32_16x16x32_bf16 v[12:15], v[20:23], v[28:31], v[12:15]
	v_lshl_add_u64 v[28:29], v[46:47], 0, v[42:43]
	global_load_dwordx4 v[28:31], v[28:29], off
	v_lshl_add_u64 v[20:21], v[46:47], 0, v[64:65]
	global_load_dwordx4 v[20:23], v[20:21], off
	s_waitcnt vmcnt(2) lgkmcnt(0)
	v_mfma_f32_16x16x32_bf16 v[12:15], v[24:27], v[16:19], v[12:15]
	global_load_dwordx4 v[16:19], v[40:41], off offset:384
	v_lshl_add_u64 v[46:47], v[38:39], 0, s[0:1]
	s_mov_b64 s[0:1], 0x1c0
	s_waitcnt vmcnt(2)
	v_mfma_f32_16x16x32_bf16 v[4:7], v[24:27], v[28:31], v[4:7]
	ds_read_b128 v[28:31], v36 offset:384
	v_mfma_f32_16x16x32_bf16 v[0:3], v[24:27], v[32:35], v[0:3]
	global_load_dwordx4 v[32:35], v[40:41], off offset:448
	s_waitcnt vmcnt(2)
	v_mfma_f32_16x16x32_bf16 v[8:11], v[24:27], v[20:23], v[8:11]
	ds_read_b128 v[24:27], v36 offset:448
	v_lshl_add_u64 v[20:21], v[46:47], 0, v[42:43]
	global_load_dwordx4 v[20:23], v[20:21], off
	s_waitcnt vmcnt(2) lgkmcnt(1)
	v_mfma_f32_16x16x32_bf16 v[0:3], v[28:31], v[16:19], v[0:3]
	v_lshl_add_u64 v[16:17], v[46:47], 0, v[44:45]
	global_load_dwordx4 v[16:19], v[16:17], off
	v_lshl_add_u64 v[40:41], v[38:39], 0, s[0:1]
	s_waitcnt vmcnt(0)
	v_mfma_f32_16x16x32_bf16 v[16:19], v[28:31], v[16:19], v[12:15]
	s_nop 2
	v_lshl_add_u64 v[12:13], v[40:41], 0, v[42:43]
	global_load_dwordx4 v[36:39], v[12:13], off
	s_movk_i32 s0, 0xff0
	v_mfma_f32_16x16x32_bf16 v[4:7], v[28:31], v[20:23], v[4:7]
	v_lshl_add_u64 v[20:21], v[46:47], 0, v[64:65]
	global_load_dwordx4 v[20:23], v[20:21], off
	s_waitcnt vmcnt(0)
	v_mfma_f32_16x16x32_bf16 v[28:31], v[28:31], v[20:23], v[8:11]
	v_lshlrev_b32_e32 v22, 8, v78
	s_waitcnt lgkmcnt(0)
	v_mfma_f32_16x16x32_bf16 v[12:15], v[24:27], v[32:35], v[0:3]
	s_nop 2
	v_lshl_add_u64 v[0:1], v[40:41], 0, v[44:45]
	v_mfma_f32_16x16x32_bf16 v[8:11], v[24:27], v[36:39], v[4:7]
	global_load_dwordx4 v[0:3], v[0:1], off
	s_nop 1
	v_lshl_add_u64 v[4:5], v[40:41], 0, v[64:65]
	global_load_dwordx4 v[32:35], v[4:5], off
	s_waitcnt vmcnt(1)
	v_mfma_f32_16x16x32_bf16 v[4:7], v[24:27], v[0:3], v[16:19]
	s_nop 2
	v_add_u32_e32 v16, s10, v48
	v_lshl_or_b32 v23, v79, 2, v16
	v_cmp_gt_i32_e32 vcc, s0, v23
	s_waitcnt vmcnt(0)
	v_mfma_f32_16x16x32_bf16 v[0:3], v[24:27], v[32:35], v[28:31]
	s_and_saveexec_b64 s[0:1], vcc
	s_cbranch_execz .LBB0_1446
	s_mov_b32 s10, 0x80808081
	v_mul_hi_i32 v16, v23, s10
	v_add_u32_e32 v16, v16, v23
	v_lshrrev_b32_e32 v17, 31, v16
	v_ashrrev_i32_e32 v16, 8, v16
	v_add_u32_e32 v16, v16, v17
	s_movk_i32 s10, 0xfe02
	v_mad_i32_i24 v17, v16, s10, v23
	v_lshlrev_b32_e32 v16, 1, v16
	v_ashrrev_i32_e32 v18, 1, v17
	v_ashrrev_i32_e32 v17, 31, v16
	v_ashrrev_i32_e32 v19, 31, v18
	v_lshlrev_b64 v[20:21], 15, v[16:17]
	v_cvt_pk_bf16_f32 v12, v12, s0
	s_and_b64 vcc, exec, s[2:3]
	s_cbranch_vccz .LBB0_1443
	v_lshl_add_u64 v[16:17], s[8:9], 0, v[20:21]
	v_lshl_add_u64 v[16:17], v[18:19], 1, v[16:17]
	v_lshlrev_b32_e32 v24, 1, v22
	v_mov_b32_e32 v25, 0
	v_lshl_add_u64 v[24:25], v[16:17], 0, v[24:25]
	global_store_short v[24:25], v12, off
	s_cbranch_execz .LBB0_1444
	s_branch .LBB0_1445

; DI unsigned pk2(float lo, float hi) { f32x2 v = {lo, hi}; return __builtin_bit_cast(unsigned, __builtin_convertvector(v, bfx2)); }
; DI float ex2(float x) { return __builtin_amdgcn_exp2f(x); }
; DI f32x4 mfma16(bf16x8 a, bf16x8 b, f32x4 c) { return __builtin_amdgcn_mfma_f32_16x16x32_bf16(a, b, c, 0, 0, 0); }
; DI void cmp_item(const Params& p, int item, unsigned char* smem_) {
;     ...
;     sum += __shfl_xor(sum, 16); sum += __shfl_xor(sum, 32);
;     const float inv = 1.f / fmaxf(sum, 1e-30f);
;     f32x4 oacc[4];
; #pragma unroll
;     for (int j = 0; j < 4; ++j) oacc[j] = (f32x4){0.f, 0.f, 0.f, 0.f};
; #pragma unroll
;     for (int c = 0; c < 8; ++c) {
;       asm volatile("" ::: "memory");
;       if (2 * c < nsub) {
;         f32x4 pa = score(2 * c), pb = {-INFINITY, -INFINITY, -INFINITY, -INFINITY};
;         if (2 * c + 1 < nsub) pb = score(2 * c + 1);
; #pragma unroll
;         for (int r = 0; r < 4; ++r) { pa[r] = ex2(pa[r] - mx) * inv; pb[r] = ex2(pb[r] - mx) * inv; }
;         impa[2 * c] += pa[0] + pa[1] + pa[2] + 0.5f * pa[3]; p3a[2 * c] += pa[3];
;         impa[2 * c + 1] += pb[0] + pb[1] + pb[2] + 0.5f * pb[3]; p3a[2 * c + 1] += pb[3];
;         const u32x4 pw = {pk2(pa[0], pa[1]), pk2(pa[2], pa[3]), pk2(pb[0], pb[1]), pk2(pb[2], pb[3])};
;         const bf16x8 pf = __builtin_bit_cast(bf16x8, pw);
; #pragma unroll
;         for (int j = 0; j < 4; ++j) {
;           const bf16_t* vr = vcs + (j * 16 + l15) * VC_LD + c * 32 + quad * 4;
;           const u32x2 lo = *(const u32x2*)vr, hi = *(const u32x2*)(vr + 16);
;           const u32x4 vw = {lo[0], lo[1], hi[0], hi[1]};
;           oacc[j] = mfma16(__builtin_bit_cast(bf16x8, vw), pf, oacc[j]);
;         }
.LBB0_1536:
	s_waitcnt lgkmcnt(0)
	v_add_f32_e32 v12, v12, v13
	v_max_f32_e32 v12, 0xda24260, v12
	v_cndmask_b32_e64 v8, v8, v84, s[4:5]
	v_sub_f32_e32 v8, v8, v28
	v_rcp_f32_e32 v82, v12
	v_cndmask_b32_e64 v9, v9, v84, s[6:7]
	v_exp_f32_e32 v12, v8
	v_sub_f32_e32 v8, v14, v28
	v_exp_f32_e32 v14, v8
	v_sub_f32_e32 v8, v9, v28
	v_cndmask_b32_e64 v10, v10, v84, s[8:9]
	v_exp_f32_e32 v13, v8
	v_sub_f32_e32 v8, v15, v28
	v_exp_f32_e32 v15, v8
	v_sub_f32_e32 v8, v10, v28
	v_exp_f32_e32 v18, v8
	v_sub_f32_e32 v8, v17, v28
	v_exp_f32_e32 v19, v8
	v_cndmask_b32_e64 v11, v11, v84, s[10:11]
	v_sub_f32_e32 v8, v11, v28
	v_mov_b32_e32 v83, v82
	v_exp_f32_e32 v106, v8
	v_sub_f32_e32 v8, v16, v28
	v_exp_f32_e32 v107, v8
	ds_read2_b64 v[8:11], v102 offset1:4
	v_pk_mul_f32 v[76:77], v[82:83], v[12:13] op_sel_hi:[0,1]
	v_pk_mul_f32 v[78:79], v[82:83], v[14:15] op_sel_hi:[0,1]
	v_pk_mul_f32 v[80:81], v[82:83], v[18:19] op_sel_hi:[0,1]
	ds_read2_b64 v[12:15], v103 offset1:4
	ds_read2_b64 v[16:19], v104 offset0:64 offset1:68
	ds_read2_b64 v[24:27], v105 offset0:96 offset1:100
	v_pk_mul_f32 v[74:75], v[82:83], v[106:107] op_sel_hi:[0,1]
	v_cvt_pk_bf16_f32 v20, v76, v77
	v_cvt_pk_bf16_f32 v21, v80, v74
	v_cvt_pk_bf16_f32 v22, v78, v79
	v_cvt_pk_bf16_f32 v23, v81, v75
	v_pk_fma_f32 v[38:39], v[82:83], v[106:107], v[38:39] op_sel_hi:[0,1,1]
	s_andn2_b64 vcc, exec, s[2:3]
	s_waitcnt lgkmcnt(3)
	v_mfma_f32_16x16x32_bf16 v[8:11], v[8:11], v[20:23], 0
	s_waitcnt lgkmcnt(2)
	v_mfma_f32_16x16x32_bf16 v[12:15], v[12:15], v[20:23], 0
	s_waitcnt lgkmcnt(1)
	v_mfma_f32_16x16x32_bf16 v[16:19], v[16:19], v[20:23], 0
	s_waitcnt lgkmcnt(0)
	v_mfma_f32_16x16x32_bf16 v[20:23], v[24:27], v[20:23], 0
	s_cbranch_vccnz .LBB0_1540
	ds_read_b128 v[24:27], v99 offset:4608
	ds_read_b128 v[106:109], v99 offset:4672
	s_andn2_b64 vcc, exec, s[0:1]
	s_waitcnt lgkmcnt(1)
	v_mfma_f32_16x16x32_bf16 v[24:27], v[24:27], v[4:7], 0
	s_waitcnt lgkmcnt(0)
	v_mfma_f32_16x16x32_bf16 v[24:27], v[106:109], v[0:3], v[24:27]
	v_mov_b32_e32 v106, 0xff800000
	v_mov_b32_e32 v108, 0xff800000
	v_mov_b32_e32 v109, 0xff800000
	v_mov_b32_e32 v107, 0xff800000
	s_cbranch_vccnz .LBB0_1539
	ds_read_b128 v[106:109], v99 offset:6912
	ds_read_b128 v[110:113], v99 offset:6976
	v_readlane_b32 vcc_lo, v241, 56
	v_readlane_b32 vcc_hi, v241, 57
	s_waitcnt lgkmcnt(1)
	v_mfma_f32_16x16x32_bf16 v[106:109], v[106:109], v[4:7], 0
	s_waitcnt lgkmcnt(0)
	v_mfma_f32_16x16x32_bf16 v[108:111], v[110:113], v[0:3], v[106:109]
	s_nop 7
	v_cndmask_b32_e32 v106, v108, v84, vcc
	v_readlane_b32 vcc_lo, v241, 44
	v_readlane_b32 vcc_hi, v241, 45
	s_nop 1
	v_cndmask_b32_e32 v108, v109, v84, vcc
	v_readlane_b32 vcc_lo, v241, 46
	v_readlane_b32 vcc_hi, v241, 47
	s_nop 1
	v_cndmask_b32_e32 v109, v110, v84, vcc
	v_readlane_b32 vcc_lo, v241, 48
	v_readlane_b32 vcc_hi, v241, 49
	s_nop 1
	v_cndmask_b32_e32 v107, v111, v84, vcc

; DI int TIDX() { int t = (int)threadIdx.x; asm volatile("" : "+v"(t)); return t; }
; DI float sigmoidf_(float x) { return 1.f / (1.f + __expf(-x)); }
; DI void merge_tile(const Params& p, int layer, int tm, int tn, bf16_t* smem) {
;     ...
;     if ((sg & 1) == 0) {
;       const int t2 = TIDX(), row0 = tm * 256 + ((t2 >> 8) & 1) * 128 + (t2 & 15);
; #pragma unroll
;       for (int i = 0; i < 8; ++i) {
;         asm volatile("" ::: "memory");
;         const float rs = rstd_from16((const float*)(p.ws + O_SSQ) + (size_t)(row0 + i * 16) * 16, 1.f / 1024.f);
; #pragma unroll
;         for (int j = 0; j < 2; ++j) {
;           unsigned w = 0;
; #pragma unroll
;           for (int r = 0; r < 4; ++r) w |= (unsigned)__float2int_rn(sigmoidf_(acc[i][j][r] * rs) * 255.f) << (8 * r);
;           gsp[(i * 2 + j) * NTHR] = w;
;         }
;       }
.LrcE1_0:
	s_or_b64 exec, exec, s[98:99]
	s_waitcnt vmcnt(0)
	v_cndmask_b32_e64 v153, v249, v153, s[100:101]
	v_mul_f32_e32 v148, v148, v153
	v_mul_f32_e32 v149, v149, v153
	v_mul_f32_e32 v148, 0xbfb8aa3b, v148
	v_mul_f32_e32 v150, v150, v153
	v_mul_f32_e32 v149, 0xbfb8aa3b, v149
	v_exp_f32_e32 v148, v148
	v_mul_f32_e32 v151, v151, v153
	v_mul_f32_e32 v150, 0xbfb8aa3b, v150
	v_exp_f32_e32 v149, v149
	v_mul_f32_e32 v151, 0xbfb8aa3b, v151
	v_exp_f32_e32 v150, v150
	v_exp_f32_e32 v151, v151
	v_add_f32_e32 v148, 1.0, v148
	v_add_f32_e32 v149, 1.0, v149
	v_add_f32_e32 v150, 1.0, v150
	v_div_scale_f32 v156, s[0:1], v149, v149, 1.0
	v_add_f32_e32 v151, 1.0, v151
	v_div_scale_f32 v158, s[2:3], v150, v150, 1.0
	v_rcp_f32_e32 v164, v156
	v_mul_f32_e32 v144, v144, v153
	v_div_scale_f32 v160, s[4:5], v151, v151, 1.0
	v_rcp_f32_e32 v165, v158
	v_mul_f32_e32 v144, 0xbfb8aa3b, v144
	v_rcp_f32_e32 v166, v160
	v_exp_f32_e32 v144, v144
	v_fma_f32 v169, -v156, v164, 1.0
	v_div_scale_f32 v157, s[0:1], 1.0, v149, 1.0
	v_fma_f32 v170, -v158, v165, 1.0
	v_fmac_f32_e32 v164, v169, v164
	v_div_scale_f32 v159, s[2:3], 1.0, v150, 1.0
	v_fma_f32 v171, -v160, v166, 1.0
	v_fmac_f32_e32 v165, v170, v165
	v_mul_f32_e32 v169, v157, v164
	v_add_f32_e32 v144, 1.0, v144
	v_div_scale_f32 v161, s[4:5], 1.0, v151, 1.0
	v_fmac_f32_e32 v166, v171, v166
	v_mul_f32_e32 v170, v159, v165
	v_fma_f32 v173, -v156, v169, v157
	v_mul_f32_e32 v171, v161, v166
	v_fma_f32 v174, -v158, v170, v159
	v_fmac_f32_e32 v169, v173, v164
	v_fma_f32 v175, -v160, v171, v161
	v_fmac_f32_e32 v170, v174, v165
	v_fma_f32 v155, -v156, v169, v157
	s_mov_b64 vcc, s[0:1]
	v_fmac_f32_e32 v171, v175, v166
	v_fma_f32 v156, -v158, v170, v159
	v_rcp_f32_e32 v148, v148
	v_div_fmas_f32 v154, v155, v164, v169
	s_mov_b64 vcc, s[2:3]
	v_fma_f32 v157, -v160, v171, v161
	v_div_fixup_f32 v149, v154, v149, 1.0
	v_div_fmas_f32 v154, v156, v165, v170
	s_mov_b64 vcc, s[4:5]
	v_div_fixup_f32 v150, v154, v150, 1.0
	v_div_fmas_f32 v154, v157, v166, v171
	v_div_fixup_f32 v151, v154, v151, 1.0
	v_mul_f32_e32 v145, v145, v153
	v_mul_f32_e32 v145, 0xbfb8aa3b, v145
	v_exp_f32_e32 v145, v145
	s_nop 0
	v_add_f32_e32 v145, 1.0, v145
	v_rcp_f32_e32 v144, v144
	v_mul_f32_e32 v146, v146, v153
	v_mul_f32_e32 v146, 0xbfb8aa3b, v146
	v_exp_f32_e32 v146, v146
	s_nop 0
	v_add_f32_e32 v146, 1.0, v146
	v_rcp_f32_e32 v145, v145
	v_mul_f32_e32 v147, v147, v153
	v_mul_f32_e32 v147, 0xbfb8aa3b, v147
	v_exp_f32_e32 v147, v147
	s_nop 0
	v_add_f32_e32 v147, 1.0, v147
	v_rcp_f32_e32 v146, v146
	v_mul_f32_e32 v148, 0x437f0000, v148
	v_mul_f32_e32 v149, 0x437f0000, v149
	v_mul_f32_e32 v144, 0x437f0000, v144
	v_mul_f32_e32 v145, 0x437f0000, v145
	v_rcp_f32_e32 v147, v147
	v_rndne_f32_e32 v148, v148
	v_rndne_f32_e32 v149, v149
	v_mul_f32_e32 v150, 0x437f0000, v150
	v_mul_f32_e32 v151, 0x437f0000, v151
	v_rndne_f32_e32 v144, v144
	v_rndne_f32_e32 v145, v145
	v_mul_f32_e32 v146, 0x437f0000, v146
	v_mul_f32_e32 v147, 0x437f0000, v147
	v_cvt_i32_f32_e32 v148, v148
	v_cvt_i32_f32_e32 v149, v149
	v_rndne_f32_e32 v150, v150
	v_rndne_f32_e32 v151, v151
	v_cvt_i32_f32_e32 v144, v144
	v_cvt_i32_f32_e32 v145, v145
	v_rndne_f32_e32 v146, v146
	v_rndne_f32_e32 v147, v147
	v_cvt_i32_f32_sdwa v150, v150 dst_sel:WORD_1 dst_unused:UNUSED_PAD src0_sel:DWORD
	v_cvt_i32_f32_sdwa v151, v151 dst_sel:BYTE_3 dst_unused:UNUSED_PAD src0_sel:DWORD
	v_cvt_i32_f32_sdwa v146, v146 dst_sel:WORD_1 dst_unused:UNUSED_PAD src0_sel:DWORD
	v_cvt_i32_f32_sdwa v147, v147 dst_sel:BYTE_3 dst_unused:UNUSED_PAD src0_sel:DWORD
	v_lshl_or_b32 v148, v149, 8, v148
	v_lshl_or_b32 v144, v145, 8, v144
	v_or3_b32 v148, v148, v150, v151
	v_or3_b32 v144, v144, v146, v147
	ds_write2st64_b32 v228, v148, v144 offset1:8
	v_or_b32_e32 v144, 16, v152
	v_ashrrev_i32_e32 v145, 31, v144
	v_lshlrev_b64 v[144:145], 6, v[144:145]
	v_lshl_add_u64 v[158:159], s[6:7], 0, v[144:145]
	v_bfe_u32 v244, v158, 6, 8
	v_lshlrev_b32_e32 v244, 3, v244
	v_add_u32_e32 v244, 0x24010, v244
	v_or_b32_e32 v246, 3, v158
	ds_read_b64 v[248:249], v244
	s_waitcnt lgkmcnt(0)
	v_cmp_ne_u32_e64 s[100:101], v248, v246
	s_nop 1
	s_and_saveexec_b64 s[98:99], s[100:101]
	s_cbranch_execz .LrcE1_1
	global_load_dwordx4 v[144:147], v[158:159], off
	global_load_dwordx4 v[148:151], v[158:159], off offset:16
	global_load_dwordx4 v[154:157], v[158:159], off offset:32
	s_nop 0
	global_load_dwordx4 v[158:161], v[158:159], off offset:48
	s_waitcnt vmcnt(3)
	v_mov_b32_e32 v162, v145
	v_mov_b32_e32 v163, v146
	v_mov_b32_e32 v145, v147
	s_waitcnt vmcnt(2)
	v_mov_b32_e32 v146, v149
	v_mov_b32_e32 v147, v150
	v_mov_b32_e32 v149, v151
	v_pk_add_f32 v[144:145], v[162:163], v[144:145]
	v_pk_add_f32 v[146:147], v[146:147], v[148:149]
	v_pk_add_f32 v[144:145], v[144:145], v[144:145] op_sel:[0,1] op_sel_hi:[1,0]
	v_pk_add_f32 v[146:147], v[146:147], v[146:147] op_sel:[0,1] op_sel_hi:[1,0]
	s_waitcnt vmcnt(1)
	v_add_f32_e32 v148, v154, v155
	v_add_f32_e32 v150, v156, v157
	s_waitcnt vmcnt(0)
	v_mov_b32_e32 v145, v158
	v_mov_b32_e32 v147, v159
	v_mov_b32_e32 v149, v160
	v_mov_b32_e32 v151, v161
	v_pk_add_f32 v[144:145], v[144:145], v[146:147]
	v_pk_add_f32 v[146:147], v[148:149], v[150:151]
	v_pk_add_f32 v[144:145], v[144:145], v[146:147]
	v_add_f32_e32 v144, v144, v145
	v_fmamk_f32 v144, v144, 0x3a800000, v225
	v_mul_f32_e32 v145, 0x4b800000, v144
	v_cmp_gt_f32_e32 vcc, s45, v144
	v_cndmask_b32_e32 v144, v144, v145, vcc
	v_rsq_f32_e32 v144, v144
	s_nop 0
	v_mul_f32_e32 v145, 0x45800000, v144
	v_cndmask_b32_e32 v144, v144, v145, vcc
	s_nop 0
	v_mov_b32_e32 v247, v144
	ds_write_b64 v244, v[246:247]
; DI int TIDX() { int t = (int)threadIdx.x; asm volatile("" : "+v"(t)); return t; }
; DI float sigmoidf_(float x) { return 1.f / (1.f + __expf(-x)); }
; DI void merge_tile(const Params& p, int layer, int tm, int tn, bf16_t* smem) {
;     ...
;     if ((sg & 1) == 0) {
;       const int t2 = TIDX(), row0 = tm * 256 + ((t2 >> 8) & 1) * 128 + (t2 & 15);
; #pragma unroll
;       for (int i = 0; i < 8; ++i) {
;         asm volatile("" ::: "memory");
;         const float rs = rstd_from16((const float*)(p.ws + O_SSQ) + (size_t)(row0 + i * 16) * 16, 1.f / 1024.f);
; #pragma unroll
;         for (int j = 0; j < 2; ++j) {
;           unsigned w = 0;
; #pragma unroll
;           for (int r = 0; r < 4; ++r) w |= (unsigned)__float2int_rn(sigmoidf_(acc[i][j][r] * rs) * 255.f) << (8 * r);
;           gsp[(i * 2 + j) * NTHR] = w;
;         }
;       }
.LrcE1_1:
	s_or_b64 exec, exec, s[98:99]
	s_waitcnt vmcnt(0)
	v_cndmask_b32_e64 v144, v249, v144, s[100:101]
	v_mov_b64_e32 v[174:175], v[66:67]
	v_mov_b64_e32 v[170:171], v[70:71]
	v_mov_b64_e32 v[166:167], v[74:75]
	v_mov_b64_e32 v[172:173], v[64:65]
	v_mov_b64_e32 v[168:169], v[68:69]
	v_mov_b64_e32 v[164:165], v[72:73]
	v_mov_b64_e32 v[162:163], v[78:79]
	v_mov_b64_e32 v[158:159], v[82:83]
	v_mov_b64_e32 v[160:161], v[76:77]
	v_mov_b64_e32 v[156:157], v[80:81]
	v_mul_f32_e32 v140, v140, v144
	v_mul_f32_e32 v140, 0xbfb8aa3b, v140
	v_exp_f32_e32 v140, v140
	v_mul_f32_e32 v141, v141, v144
	v_mul_f32_e32 v141, 0xbfb8aa3b, v141
	v_exp_f32_e32 v141, v141
	v_add_f32_e32 v140, 1.0, v140
	v_add_f32_e32 v141, 1.0, v141
	v_mul_f32_e32 v142, v142, v144
	v_mul_f32_e32 v142, 0xbfb8aa3b, v142
	v_rcp_f32_e32 v140, v140
	v_exp_f32_e32 v142, v142
	v_mul_f32_e32 v143, v143, v144
	v_mul_f32_e32 v143, 0xbfb8aa3b, v143
	v_add_f32_e32 v142, 1.0, v142
	v_rcp_f32_e32 v141, v141
	v_exp_f32_e32 v143, v143
	v_mul_f32_e32 v136, v136, v144
	v_mul_f32_e32 v136, 0xbfb8aa3b, v136
	v_add_f32_e32 v143, 1.0, v143
	v_rcp_f32_e32 v142, v142
	v_exp_f32_e32 v136, v136
	v_mul_f32_e32 v137, v137, v144
	v_mul_f32_e32 v137, 0xbfb8aa3b, v137
	v_add_f32_e32 v136, 1.0, v136
	v_rcp_f32_e32 v143, v143
	v_exp_f32_e32 v137, v137
	v_mul_f32_e32 v138, v138, v144
	v_mul_f32_e32 v138, 0xbfb8aa3b, v138
	v_add_f32_e32 v137, 1.0, v137
	v_rcp_f32_e32 v136, v136
	v_exp_f32_e32 v138, v138
	v_mul_f32_e32 v139, v139, v144
	v_mul_f32_e32 v139, 0xbfb8aa3b, v139
	v_add_f32_e32 v138, 1.0, v138
	v_rcp_f32_e32 v137, v137
	v_exp_f32_e32 v139, v139
	v_mul_f32_e32 v140, 0x437f0000, v140
	v_mul_f32_e32 v141, 0x437f0000, v141
	v_add_f32_e32 v139, 1.0, v139
	v_rcp_f32_e32 v138, v138
	v_mul_f32_e32 v136, 0x437f0000, v136
	v_mul_f32_e32 v137, 0x437f0000, v137
	v_rndne_f32_e32 v140, v140
	v_rcp_f32_e32 v139, v139
	v_rndne_f32_e32 v141, v141
	v_mul_f32_e32 v142, 0x437f0000, v142
	v_mul_f32_e32 v143, 0x437f0000, v143
	v_rndne_f32_e32 v136, v136
	v_rndne_f32_e32 v137, v137
	v_mul_f32_e32 v138, 0x437f0000, v138
	v_mul_f32_e32 v139, 0x437f0000, v139
	v_cvt_i32_f32_e32 v140, v140
	v_cvt_i32_f32_e32 v141, v141
	v_rndne_f32_e32 v142, v142
	v_rndne_f32_e32 v143, v143
	v_cvt_i32_f32_e32 v136, v136
	v_cvt_i32_f32_e32 v137, v137
	v_rndne_f32_e32 v138, v138
	v_rndne_f32_e32 v139, v139
	v_cvt_i32_f32_sdwa v142, v142 dst_sel:WORD_1 dst_unused:UNUSED_PAD src0_sel:DWORD
	v_cvt_i32_f32_sdwa v143, v143 dst_sel:BYTE_3 dst_unused:UNUSED_PAD src0_sel:DWORD
	v_cvt_i32_f32_sdwa v138, v138 dst_sel:WORD_1 dst_unused:UNUSED_PAD src0_sel:DWORD
	v_cvt_i32_f32_sdwa v139, v139 dst_sel:BYTE_3 dst_unused:UNUSED_PAD src0_sel:DWORD
	v_lshl_or_b32 v140, v141, 8, v140
	v_lshl_or_b32 v136, v137, 8, v136
	v_or3_b32 v140, v140, v142, v143
	v_or3_b32 v136, v136, v138, v139
	ds_write2st64_b32 v228, v140, v136 offset0:16 offset1:24
	v_or_b32_e32 v136, 32, v152
	v_ashrrev_i32_e32 v137, 31, v136
	v_lshlrev_b64 v[136:137], 6, v[136:137]
	v_lshl_add_u64 v[148:149], s[6:7], 0, v[136:137]
	v_bfe_u32 v244, v148, 6, 8
	v_lshlrev_b32_e32 v244, 3, v244
	v_add_u32_e32 v244, 0x24010, v244
	v_or_b32_e32 v246, 3, v148
	ds_read_b64 v[248:249], v244
	s_waitcnt lgkmcnt(0)
	v_cmp_ne_u32_e64 s[100:101], v248, v246
	s_nop 1
	s_and_saveexec_b64 s[98:99], s[100:101]
	s_cbranch_execz .LrcE1_2
	global_load_dwordx4 v[136:139], v[148:149], off
	global_load_dwordx4 v[140:143], v[148:149], off offset:16
	global_load_dwordx4 v[144:147], v[148:149], off offset:32
	s_nop 0
	global_load_dwordx4 v[148:151], v[148:149], off offset:48
	s_waitcnt vmcnt(3)
	v_mov_b32_e32 v154, v137
	v_mov_b32_e32 v155, v138
	v_mov_b32_e32 v137, v139
	s_waitcnt vmcnt(2)
	v_mov_b32_e32 v138, v141
	v_mov_b32_e32 v139, v142
	v_mov_b32_e32 v141, v143
	v_pk_add_f32 v[136:137], v[154:155], v[136:137]
	v_pk_add_f32 v[138:139], v[138:139], v[140:141]
	v_pk_add_f32 v[136:137], v[136:137], v[136:137] op_sel:[0,1] op_sel_hi:[1,0]
	v_pk_add_f32 v[138:139], v[138:139], v[138:139] op_sel:[0,1] op_sel_hi:[1,0]
	s_waitcnt vmcnt(1)
	v_add_f32_e32 v140, v144, v145
	v_add_f32_e32 v142, v146, v147
	s_waitcnt vmcnt(0)
	v_mov_b32_e32 v137, v148
	v_mov_b32_e32 v139, v149
	v_mov_b32_e32 v141, v150
	v_mov_b32_e32 v143, v151
	v_pk_add_f32 v[136:137], v[136:137], v[138:139]
	v_pk_add_f32 v[138:139], v[140:141], v[142:143]
	s_nop 0
	v_pk_add_f32 v[136:137], v[136:137], v[138:139]
	s_nop 0
	v_add_f32_e32 v136, v136, v137
	v_fmamk_f32 v136, v136, 0x3a800000, v225
	v_mul_f32_e32 v137, 0x4b800000, v136
	v_cmp_gt_f32_e32 vcc, s45, v136
	s_nop 1
	v_cndmask_b32_e32 v136, v136, v137, vcc
	v_rsq_f32_e32 v136, v136
	s_nop 0
	v_mul_f32_e32 v137, 0x45800000, v136
	v_cndmask_b32_e32 v136, v136, v137, vcc
	s_nop 0
	v_mov_b32_e32 v247, v136
	ds_write_b64 v244, v[246:247]
; DI int TIDX() { int t = (int)threadIdx.x; asm volatile("" : "+v"(t)); return t; }
; DI float sigmoidf_(float x) { return 1.f / (1.f + __expf(-x)); }
; DI void merge_tile(const Params& p, int layer, int tm, int tn, bf16_t* smem) {
;     ...
;     if ((sg & 1) == 0) {
;       const int t2 = TIDX(), row0 = tm * 256 + ((t2 >> 8) & 1) * 128 + (t2 & 15);
; #pragma unroll
;       for (int i = 0; i < 8; ++i) {
;         asm volatile("" ::: "memory");
;         const float rs = rstd_from16((const float*)(p.ws + O_SSQ) + (size_t)(row0 + i * 16) * 16, 1.f / 1024.f);
; #pragma unroll
;         for (int j = 0; j < 2; ++j) {
;           unsigned w = 0;
; #pragma unroll
;           for (int r = 0; r < 4; ++r) w |= (unsigned)__float2int_rn(sigmoidf_(acc[i][j][r] * rs) * 255.f) << (8 * r);
;           gsp[(i * 2 + j) * NTHR] = w;
;         }
;       }
.LrcE1_2:
	s_or_b64 exec, exec, s[98:99]
	s_waitcnt vmcnt(0)
	v_cndmask_b32_e64 v136, v249, v136, s[100:101]
	v_mul_f32_e32 v132, v132, v136
	v_mul_f32_e32 v132, 0xbfb8aa3b, v132
	v_exp_f32_e32 v132, v132
	v_mul_f32_e32 v133, v133, v136
	v_mul_f32_e32 v133, 0xbfb8aa3b, v133
	v_exp_f32_e32 v133, v133
	v_add_f32_e32 v132, 1.0, v132
	v_add_f32_e32 v133, 1.0, v133
	v_mul_f32_e32 v134, v134, v136
	v_mul_f32_e32 v134, 0xbfb8aa3b, v134
	v_rcp_f32_e32 v132, v132
	v_exp_f32_e32 v134, v134
	v_mul_f32_e32 v135, v135, v136
	v_mul_f32_e32 v135, 0xbfb8aa3b, v135
	v_add_f32_e32 v134, 1.0, v134
	v_rcp_f32_e32 v133, v133
	v_exp_f32_e32 v135, v135
	v_mul_f32_e32 v128, v128, v136
	v_mul_f32_e32 v128, 0xbfb8aa3b, v128
	v_add_f32_e32 v135, 1.0, v135
	v_rcp_f32_e32 v134, v134
	v_exp_f32_e32 v128, v128
	v_mul_f32_e32 v129, v129, v136
	v_mul_f32_e32 v129, 0xbfb8aa3b, v129
	v_add_f32_e32 v128, 1.0, v128
	v_rcp_f32_e32 v135, v135
	v_exp_f32_e32 v129, v129
	v_mul_f32_e32 v130, v130, v136
	v_mul_f32_e32 v130, 0xbfb8aa3b, v130
	v_add_f32_e32 v129, 1.0, v129
	v_rcp_f32_e32 v128, v128
	v_exp_f32_e32 v130, v130
	v_mul_f32_e32 v131, v131, v136
	v_mul_f32_e32 v131, 0xbfb8aa3b, v131
	v_add_f32_e32 v130, 1.0, v130
	v_rcp_f32_e32 v129, v129
	v_exp_f32_e32 v131, v131
	v_mul_f32_e32 v132, 0x437f0000, v132
	v_mul_f32_e32 v133, 0x437f0000, v133
	v_add_f32_e32 v131, 1.0, v131
	v_rcp_f32_e32 v130, v130
	v_mul_f32_e32 v128, 0x437f0000, v128
	v_mul_f32_e32 v129, 0x437f0000, v129
	v_rndne_f32_e32 v132, v132
	v_rcp_f32_e32 v131, v131
	v_rndne_f32_e32 v133, v133
	v_mul_f32_e32 v134, 0x437f0000, v134
	v_mul_f32_e32 v135, 0x437f0000, v135
	v_rndne_f32_e32 v128, v128
	v_rndne_f32_e32 v129, v129
	v_mul_f32_e32 v130, 0x437f0000, v130
	v_mul_f32_e32 v131, 0x437f0000, v131
	v_cvt_i32_f32_e32 v132, v132
	v_cvt_i32_f32_e32 v133, v133
	v_rndne_f32_e32 v134, v134
	v_rndne_f32_e32 v135, v135
	v_cvt_i32_f32_e32 v128, v128
	v_cvt_i32_f32_e32 v129, v129
	v_rndne_f32_e32 v130, v130
	v_rndne_f32_e32 v131, v131
	v_cvt_i32_f32_sdwa v134, v134 dst_sel:WORD_1 dst_unused:UNUSED_PAD src0_sel:DWORD
	v_cvt_i32_f32_sdwa v135, v135 dst_sel:BYTE_3 dst_unused:UNUSED_PAD src0_sel:DWORD
	v_cvt_i32_f32_sdwa v130, v130 dst_sel:WORD_1 dst_unused:UNUSED_PAD src0_sel:DWORD
	v_cvt_i32_f32_sdwa v131, v131 dst_sel:BYTE_3 dst_unused:UNUSED_PAD src0_sel:DWORD
	v_lshl_or_b32 v132, v133, 8, v132
	v_lshl_or_b32 v128, v129, 8, v128
	v_or3_b32 v132, v132, v134, v135
	v_or3_b32 v128, v128, v130, v131
	ds_write2st64_b32 v228, v132, v128 offset0:32 offset1:40
	v_or_b32_e32 v128, 48, v152
	v_ashrrev_i32_e32 v129, 31, v128
	v_lshlrev_b64 v[128:129], 6, v[128:129]
	v_lshl_add_u64 v[140:141], s[6:7], 0, v[128:129]
	v_bfe_u32 v244, v140, 6, 8
	v_lshlrev_b32_e32 v244, 3, v244
	v_add_u32_e32 v244, 0x24010, v244
	v_or_b32_e32 v246, 3, v140
	ds_read_b64 v[248:249], v244
	s_waitcnt lgkmcnt(0)
	v_cmp_ne_u32_e64 s[100:101], v248, v246
	s_nop 1
	s_and_saveexec_b64 s[98:99], s[100:101]
	s_cbranch_execz .LrcE1_3
	global_load_dwordx4 v[128:131], v[140:141], off
	global_load_dwordx4 v[132:135], v[140:141], off offset:16
	global_load_dwordx4 v[136:139], v[140:141], off offset:32
	s_nop 0
	global_load_dwordx4 v[140:143], v[140:141], off offset:48
	s_waitcnt vmcnt(3)
	v_mov_b32_e32 v144, v129
	v_mov_b32_e32 v145, v130
	v_mov_b32_e32 v129, v131
	s_waitcnt vmcnt(2)
	v_mov_b32_e32 v130, v133
	v_mov_b32_e32 v131, v134
	v_mov_b32_e32 v133, v135
	v_pk_add_f32 v[128:129], v[144:145], v[128:129]
	v_pk_add_f32 v[130:131], v[130:131], v[132:133]
	v_pk_add_f32 v[128:129], v[128:129], v[128:129] op_sel:[0,1] op_sel_hi:[1,0]
	v_pk_add_f32 v[130:131], v[130:131], v[130:131] op_sel:[0,1] op_sel_hi:[1,0]
	s_waitcnt vmcnt(1)
	v_add_f32_e32 v132, v136, v137
	v_add_f32_e32 v134, v138, v139
	s_waitcnt vmcnt(0)
	v_mov_b32_e32 v129, v140
	v_mov_b32_e32 v131, v141
	v_mov_b32_e32 v133, v142
	v_mov_b32_e32 v135, v143
	v_pk_add_f32 v[128:129], v[128:129], v[130:131]
	v_pk_add_f32 v[130:131], v[132:133], v[134:135]
	s_nop 0
	v_pk_add_f32 v[128:129], v[128:129], v[130:131]
	s_nop 0
	v_add_f32_e32 v128, v128, v129
	v_fmamk_f32 v128, v128, 0x3a800000, v225
	v_mul_f32_e32 v129, 0x4b800000, v128
	v_cmp_gt_f32_e32 vcc, s45, v128
	s_nop 1
	v_cndmask_b32_e32 v128, v128, v129, vcc
	v_rsq_f32_e32 v128, v128
	s_nop 0
	v_mul_f32_e32 v129, 0x45800000, v128
	v_cndmask_b32_e32 v128, v128, v129, vcc
	s_nop 0
	v_mov_b32_e32 v247, v128
	ds_write_b64 v244, v[246:247]
; DI int TIDX() { int t = (int)threadIdx.x; asm volatile("" : "+v"(t)); return t; }
; DI float sigmoidf_(float x) { return 1.f / (1.f + __expf(-x)); }
; DI void merge_tile(const Params& p, int layer, int tm, int tn, bf16_t* smem) {
;     ...
;     if ((sg & 1) == 0) {
;       const int t2 = TIDX(), row0 = tm * 256 + ((t2 >> 8) & 1) * 128 + (t2 & 15);
; #pragma unroll
;       for (int i = 0; i < 8; ++i) {
;         asm volatile("" ::: "memory");
;         const float rs = rstd_from16((const float*)(p.ws + O_SSQ) + (size_t)(row0 + i * 16) * 16, 1.f / 1024.f);
; #pragma unroll
;         for (int j = 0; j < 2; ++j) {
;           unsigned w = 0;
; #pragma unroll
;           for (int r = 0; r < 4; ++r) w |= (unsigned)__float2int_rn(sigmoidf_(acc[i][j][r] * rs) * 255.f) << (8 * r);
;           gsp[(i * 2 + j) * NTHR] = w;
;         }
;       }
.LrcE1_3:
	s_or_b64 exec, exec, s[98:99]
	s_waitcnt vmcnt(0)
	v_cndmask_b32_e64 v128, v249, v128, s[100:101]
	v_mul_f32_e32 v124, v124, v128
	v_mul_f32_e32 v124, 0xbfb8aa3b, v124
	v_exp_f32_e32 v124, v124
	v_mul_f32_e32 v125, v125, v128
	v_mul_f32_e32 v125, 0xbfb8aa3b, v125
	v_exp_f32_e32 v125, v125
	v_add_f32_e32 v124, 1.0, v124
	v_add_f32_e32 v125, 1.0, v125
	v_mul_f32_e32 v126, v126, v128
	v_mul_f32_e32 v126, 0xbfb8aa3b, v126
	v_rcp_f32_e32 v124, v124
	v_exp_f32_e32 v126, v126
	v_mul_f32_e32 v127, v127, v128
	v_mul_f32_e32 v127, 0xbfb8aa3b, v127
	v_add_f32_e32 v126, 1.0, v126
	v_rcp_f32_e32 v125, v125
	v_exp_f32_e32 v127, v127
	v_mul_f32_e32 v120, v120, v128
	v_mul_f32_e32 v120, 0xbfb8aa3b, v120
	v_add_f32_e32 v127, 1.0, v127
	v_rcp_f32_e32 v126, v126
	v_exp_f32_e32 v120, v120
	v_mul_f32_e32 v121, v121, v128
	v_mul_f32_e32 v121, 0xbfb8aa3b, v121
	v_add_f32_e32 v120, 1.0, v120
	v_rcp_f32_e32 v127, v127
	v_exp_f32_e32 v121, v121
	v_mul_f32_e32 v122, v122, v128
	v_mul_f32_e32 v122, 0xbfb8aa3b, v122
	v_add_f32_e32 v121, 1.0, v121
	v_rcp_f32_e32 v120, v120
	v_exp_f32_e32 v122, v122
	v_mul_f32_e32 v123, v123, v128
	v_mul_f32_e32 v123, 0xbfb8aa3b, v123
	v_add_f32_e32 v122, 1.0, v122
	v_rcp_f32_e32 v121, v121
	v_exp_f32_e32 v123, v123
	v_mul_f32_e32 v124, 0x437f0000, v124
	v_mul_f32_e32 v125, 0x437f0000, v125
	v_add_f32_e32 v123, 1.0, v123
	v_rcp_f32_e32 v122, v122
	v_mul_f32_e32 v120, 0x437f0000, v120
	v_mul_f32_e32 v121, 0x437f0000, v121
	v_rndne_f32_e32 v124, v124
	v_rcp_f32_e32 v123, v123
	v_rndne_f32_e32 v125, v125
	v_mul_f32_e32 v126, 0x437f0000, v126
	v_mul_f32_e32 v127, 0x437f0000, v127
	v_rndne_f32_e32 v120, v120
	v_rndne_f32_e32 v121, v121
	v_mul_f32_e32 v122, 0x437f0000, v122
	v_mul_f32_e32 v123, 0x437f0000, v123
	v_cvt_i32_f32_e32 v124, v124
	v_cvt_i32_f32_e32 v125, v125
	v_rndne_f32_e32 v126, v126
	v_rndne_f32_e32 v127, v127
	v_cvt_i32_f32_e32 v120, v120
	v_cvt_i32_f32_e32 v121, v121
	v_rndne_f32_e32 v122, v122
	v_rndne_f32_e32 v123, v123
	v_cvt_i32_f32_sdwa v126, v126 dst_sel:WORD_1 dst_unused:UNUSED_PAD src0_sel:DWORD
	v_cvt_i32_f32_sdwa v127, v127 dst_sel:BYTE_3 dst_unused:UNUSED_PAD src0_sel:DWORD
	v_cvt_i32_f32_sdwa v122, v122 dst_sel:WORD_1 dst_unused:UNUSED_PAD src0_sel:DWORD
	v_cvt_i32_f32_sdwa v123, v123 dst_sel:BYTE_3 dst_unused:UNUSED_PAD src0_sel:DWORD
	v_lshl_or_b32 v124, v125, 8, v124
	v_lshl_or_b32 v120, v121, 8, v120
	v_or3_b32 v124, v124, v126, v127
	v_or3_b32 v120, v120, v122, v123
	ds_write2st64_b32 v228, v124, v120 offset0:48 offset1:56
	v_or_b32_e32 v120, 64, v152
	v_ashrrev_i32_e32 v121, 31, v120
	v_lshlrev_b64 v[120:121], 6, v[120:121]
	v_lshl_add_u64 v[132:133], s[6:7], 0, v[120:121]
	v_bfe_u32 v244, v132, 6, 8
	v_lshlrev_b32_e32 v244, 3, v244
	v_add_u32_e32 v244, 0x24010, v244
	v_or_b32_e32 v246, 3, v132
	ds_read_b64 v[248:249], v244
	s_waitcnt lgkmcnt(0)
	v_cmp_ne_u32_e64 s[100:101], v248, v246
	s_nop 1
	s_and_saveexec_b64 s[98:99], s[100:101]
	s_cbranch_execz .LrcE1_4
	global_load_dwordx4 v[120:123], v[132:133], off
	global_load_dwordx4 v[124:127], v[132:133], off offset:16
	global_load_dwordx4 v[128:131], v[132:133], off offset:32
	s_nop 0
	global_load_dwordx4 v[132:135], v[132:133], off offset:48
	s_waitcnt vmcnt(3)
	v_mov_b32_e32 v136, v121
	v_mov_b32_e32 v137, v122
	v_mov_b32_e32 v121, v123
	s_waitcnt vmcnt(2)
	v_mov_b32_e32 v122, v125
	v_mov_b32_e32 v123, v126
	v_mov_b32_e32 v125, v127
	v_pk_add_f32 v[120:121], v[136:137], v[120:121]
	v_pk_add_f32 v[122:123], v[122:123], v[124:125]
	v_pk_add_f32 v[120:121], v[120:121], v[120:121] op_sel:[0,1] op_sel_hi:[1,0]
	v_pk_add_f32 v[122:123], v[122:123], v[122:123] op_sel:[0,1] op_sel_hi:[1,0]
	s_waitcnt vmcnt(1)
	v_add_f32_e32 v124, v128, v129
	v_add_f32_e32 v126, v130, v131
	s_waitcnt vmcnt(0)
	v_mov_b32_e32 v121, v132
	v_mov_b32_e32 v123, v133
	v_mov_b32_e32 v125, v134
	v_mov_b32_e32 v127, v135
	v_pk_add_f32 v[120:121], v[120:121], v[122:123]
	v_pk_add_f32 v[122:123], v[124:125], v[126:127]
	s_nop 0
	v_pk_add_f32 v[120:121], v[120:121], v[122:123]
	s_nop 0
	v_add_f32_e32 v120, v120, v121
	v_fmamk_f32 v120, v120, 0x3a800000, v225
	v_mul_f32_e32 v121, 0x4b800000, v120
	v_cmp_gt_f32_e32 vcc, s45, v120
	s_nop 1
	v_cndmask_b32_e32 v120, v120, v121, vcc
	v_rsq_f32_e32 v120, v120
	s_nop 0
	v_mul_f32_e32 v121, 0x45800000, v120
	v_cndmask_b32_e32 v120, v120, v121, vcc
	s_nop 0
	v_mov_b32_e32 v247, v120
	ds_write_b64 v244, v[246:247]
; DI int TIDX() { int t = (int)threadIdx.x; asm volatile("" : "+v"(t)); return t; }
; DI float sigmoidf_(float x) { return 1.f / (1.f + __expf(-x)); }
; DI void merge_tile(const Params& p, int layer, int tm, int tn, bf16_t* smem) {
;     ...
;     if ((sg & 1) == 0) {
;       const int t2 = TIDX(), row0 = tm * 256 + ((t2 >> 8) & 1) * 128 + (t2 & 15);
; #pragma unroll
;       for (int i = 0; i < 8; ++i) {
;         asm volatile("" ::: "memory");
;         const float rs = rstd_from16((const float*)(p.ws + O_SSQ) + (size_t)(row0 + i * 16) * 16, 1.f / 1024.f);
; #pragma unroll
;         for (int j = 0; j < 2; ++j) {
;           unsigned w = 0;
; #pragma unroll
;           for (int r = 0; r < 4; ++r) w |= (unsigned)__float2int_rn(sigmoidf_(acc[i][j][r] * rs) * 255.f) << (8 * r);
;           gsp[(i * 2 + j) * NTHR] = w;
;         }
;       }
.LrcE1_4:
	s_or_b64 exec, exec, s[98:99]
	s_waitcnt vmcnt(0)
	v_cndmask_b32_e64 v120, v249, v120, s[100:101]
	v_mul_f32_e32 v116, v116, v120
	v_mul_f32_e32 v116, 0xbfb8aa3b, v116
	v_exp_f32_e32 v116, v116
	v_mul_f32_e32 v117, v117, v120
	v_mul_f32_e32 v117, 0xbfb8aa3b, v117
	v_exp_f32_e32 v117, v117
	v_add_f32_e32 v116, 1.0, v116
	v_add_f32_e32 v117, 1.0, v117
	v_mul_f32_e32 v118, v118, v120
	v_mul_f32_e32 v118, 0xbfb8aa3b, v118
	v_rcp_f32_e32 v116, v116
	v_exp_f32_e32 v118, v118
	v_mul_f32_e32 v119, v119, v120
	v_mul_f32_e32 v119, 0xbfb8aa3b, v119
	v_add_f32_e32 v118, 1.0, v118
	v_rcp_f32_e32 v117, v117
	v_exp_f32_e32 v119, v119
	v_mul_f32_e32 v112, v112, v120
	v_mul_f32_e32 v112, 0xbfb8aa3b, v112
	v_add_f32_e32 v119, 1.0, v119
	v_rcp_f32_e32 v118, v118
	v_exp_f32_e32 v112, v112
	v_mul_f32_e32 v113, v113, v120
	v_mul_f32_e32 v113, 0xbfb8aa3b, v113
	v_add_f32_e32 v112, 1.0, v112
	v_rcp_f32_e32 v119, v119
	v_exp_f32_e32 v113, v113
	v_mul_f32_e32 v114, v114, v120
	v_mul_f32_e32 v114, 0xbfb8aa3b, v114
	v_add_f32_e32 v113, 1.0, v113
	v_rcp_f32_e32 v112, v112
	v_exp_f32_e32 v114, v114
	v_mul_f32_e32 v115, v115, v120
	v_mul_f32_e32 v115, 0xbfb8aa3b, v115
	v_add_f32_e32 v114, 1.0, v114
	v_rcp_f32_e32 v113, v113
	v_exp_f32_e32 v115, v115
	v_mul_f32_e32 v116, 0x437f0000, v116
	v_mul_f32_e32 v117, 0x437f0000, v117
	v_add_f32_e32 v115, 1.0, v115
	v_rcp_f32_e32 v114, v114
	v_mul_f32_e32 v112, 0x437f0000, v112
	v_mul_f32_e32 v113, 0x437f0000, v113
	v_rndne_f32_e32 v116, v116
	v_rcp_f32_e32 v115, v115
	v_rndne_f32_e32 v117, v117
	v_mul_f32_e32 v118, 0x437f0000, v118
	v_mul_f32_e32 v119, 0x437f0000, v119
	v_rndne_f32_e32 v112, v112
	v_rndne_f32_e32 v113, v113
	v_mul_f32_e32 v114, 0x437f0000, v114
	v_mul_f32_e32 v115, 0x437f0000, v115
	v_cvt_i32_f32_e32 v116, v116
	v_cvt_i32_f32_e32 v117, v117
	v_rndne_f32_e32 v118, v118
	v_rndne_f32_e32 v119, v119
	v_cvt_i32_f32_e32 v112, v112
	v_cvt_i32_f32_e32 v113, v113
	v_rndne_f32_e32 v114, v114
	v_rndne_f32_e32 v115, v115
	v_cvt_i32_f32_sdwa v118, v118 dst_sel:WORD_1 dst_unused:UNUSED_PAD src0_sel:DWORD
	v_cvt_i32_f32_sdwa v119, v119 dst_sel:BYTE_3 dst_unused:UNUSED_PAD src0_sel:DWORD
	v_cvt_i32_f32_sdwa v114, v114 dst_sel:WORD_1 dst_unused:UNUSED_PAD src0_sel:DWORD
	v_cvt_i32_f32_sdwa v115, v115 dst_sel:BYTE_3 dst_unused:UNUSED_PAD src0_sel:DWORD
	v_lshl_or_b32 v116, v117, 8, v116
	v_lshl_or_b32 v112, v113, 8, v112
	v_or3_b32 v116, v116, v118, v119
	v_or3_b32 v112, v112, v114, v115
	ds_write2st64_b32 v228, v116, v112 offset0:64 offset1:72
	v_or_b32_e32 v112, 0x50, v152
	v_ashrrev_i32_e32 v113, 31, v112
	v_lshlrev_b64 v[112:113], 6, v[112:113]
	v_lshl_add_u64 v[124:125], s[6:7], 0, v[112:113]
	v_bfe_u32 v244, v124, 6, 8
	v_lshlrev_b32_e32 v244, 3, v244
	v_add_u32_e32 v244, 0x24010, v244
	v_or_b32_e32 v246, 3, v124
	ds_read_b64 v[248:249], v244
	s_waitcnt lgkmcnt(0)
	v_cmp_ne_u32_e64 s[100:101], v248, v246
	s_nop 1
	s_and_saveexec_b64 s[98:99], s[100:101]
	s_cbranch_execz .LrcE1_5
	global_load_dwordx4 v[112:115], v[124:125], off
	global_load_dwordx4 v[116:119], v[124:125], off offset:16
	global_load_dwordx4 v[120:123], v[124:125], off offset:32
	s_nop 0
	global_load_dwordx4 v[124:127], v[124:125], off offset:48
	s_waitcnt vmcnt(3)
	v_mov_b32_e32 v128, v113
	v_mov_b32_e32 v129, v114
	v_mov_b32_e32 v113, v115
	s_waitcnt vmcnt(2)
	v_mov_b32_e32 v114, v117
	v_mov_b32_e32 v115, v118
	v_mov_b32_e32 v117, v119
	v_pk_add_f32 v[112:113], v[128:129], v[112:113]
	v_pk_add_f32 v[114:115], v[114:115], v[116:117]
	v_pk_add_f32 v[112:113], v[112:113], v[112:113] op_sel:[0,1] op_sel_hi:[1,0]
	v_pk_add_f32 v[114:115], v[114:115], v[114:115] op_sel:[0,1] op_sel_hi:[1,0]
	s_waitcnt vmcnt(1)
	v_add_f32_e32 v116, v120, v121
	v_add_f32_e32 v118, v122, v123
	s_waitcnt vmcnt(0)
	v_mov_b32_e32 v113, v124
	v_mov_b32_e32 v115, v125
	v_mov_b32_e32 v117, v126
	v_mov_b32_e32 v119, v127
	v_pk_add_f32 v[112:113], v[112:113], v[114:115]
	v_pk_add_f32 v[114:115], v[116:117], v[118:119]
	s_nop 0
	v_pk_add_f32 v[112:113], v[112:113], v[114:115]
	s_nop 0
	v_add_f32_e32 v112, v112, v113
	v_fmamk_f32 v112, v112, 0x3a800000, v225
	v_mul_f32_e32 v113, 0x4b800000, v112
	v_cmp_gt_f32_e32 vcc, s45, v112
	s_nop 1
	v_cndmask_b32_e32 v112, v112, v113, vcc
	v_rsq_f32_e32 v112, v112
	s_nop 0
	v_mul_f32_e32 v113, 0x45800000, v112
	v_cndmask_b32_e32 v112, v112, v113, vcc
	s_nop 0
	v_mov_b32_e32 v247, v112
	ds_write_b64 v244, v[246:247]
; DI int TIDX() { int t = (int)threadIdx.x; asm volatile("" : "+v"(t)); return t; }
; DI float sigmoidf_(float x) { return 1.f / (1.f + __expf(-x)); }
; DI void merge_tile(const Params& p, int layer, int tm, int tn, bf16_t* smem) {
;     ...
;     if ((sg & 1) == 0) {
;       const int t2 = TIDX(), row0 = tm * 256 + ((t2 >> 8) & 1) * 128 + (t2 & 15);
; #pragma unroll
;       for (int i = 0; i < 8; ++i) {
;         asm volatile("" ::: "memory");
;         const float rs = rstd_from16((const float*)(p.ws + O_SSQ) + (size_t)(row0 + i * 16) * 16, 1.f / 1024.f);
; #pragma unroll
;         for (int j = 0; j < 2; ++j) {
;           unsigned w = 0;
; #pragma unroll
;           for (int r = 0; r < 4; ++r) w |= (unsigned)__float2int_rn(sigmoidf_(acc[i][j][r] * rs) * 255.f) << (8 * r);
;           gsp[(i * 2 + j) * NTHR] = w;
;         }
;       }
.LrcE1_5:
	s_or_b64 exec, exec, s[98:99]
	s_waitcnt vmcnt(0)
	v_cndmask_b32_e64 v112, v249, v112, s[100:101]
	v_mul_f32_e32 v108, v108, v112
	v_mul_f32_e32 v108, 0xbfb8aa3b, v108
	v_exp_f32_e32 v108, v108
	v_mul_f32_e32 v109, v109, v112
	v_mul_f32_e32 v109, 0xbfb8aa3b, v109
	v_exp_f32_e32 v109, v109
	v_add_f32_e32 v108, 1.0, v108
	v_add_f32_e32 v109, 1.0, v109
	v_mul_f32_e32 v110, v110, v112
	v_mul_f32_e32 v110, 0xbfb8aa3b, v110
	v_rcp_f32_e32 v108, v108
	v_exp_f32_e32 v110, v110
	v_mul_f32_e32 v111, v111, v112
	v_mul_f32_e32 v111, 0xbfb8aa3b, v111
	v_add_f32_e32 v110, 1.0, v110
	v_rcp_f32_e32 v109, v109
	v_exp_f32_e32 v111, v111
	v_mul_f32_e32 v104, v104, v112
	v_mul_f32_e32 v104, 0xbfb8aa3b, v104
	v_add_f32_e32 v111, 1.0, v111
	v_rcp_f32_e32 v110, v110
	v_exp_f32_e32 v104, v104
	v_mul_f32_e32 v105, v105, v112
	v_mul_f32_e32 v105, 0xbfb8aa3b, v105
	v_add_f32_e32 v104, 1.0, v104
	v_rcp_f32_e32 v111, v111
	v_exp_f32_e32 v105, v105
	v_mul_f32_e32 v106, v106, v112
	v_mul_f32_e32 v106, 0xbfb8aa3b, v106
	v_add_f32_e32 v105, 1.0, v105
	v_rcp_f32_e32 v104, v104
	v_exp_f32_e32 v106, v106
	v_mul_f32_e32 v107, v107, v112
	v_mul_f32_e32 v107, 0xbfb8aa3b, v107
	v_add_f32_e32 v106, 1.0, v106
	v_rcp_f32_e32 v105, v105
	v_exp_f32_e32 v107, v107
	v_mul_f32_e32 v108, 0x437f0000, v108
	v_mul_f32_e32 v109, 0x437f0000, v109
	v_add_f32_e32 v107, 1.0, v107
	v_rcp_f32_e32 v106, v106
	v_mul_f32_e32 v104, 0x437f0000, v104
	v_mul_f32_e32 v105, 0x437f0000, v105
	v_rndne_f32_e32 v108, v108
	v_rcp_f32_e32 v107, v107
	v_rndne_f32_e32 v109, v109
	v_mul_f32_e32 v110, 0x437f0000, v110
	v_mul_f32_e32 v111, 0x437f0000, v111
	v_rndne_f32_e32 v104, v104
	v_rndne_f32_e32 v105, v105
	v_mul_f32_e32 v106, 0x437f0000, v106
	v_mul_f32_e32 v107, 0x437f0000, v107
	v_cvt_i32_f32_e32 v108, v108
	v_cvt_i32_f32_e32 v109, v109
	v_rndne_f32_e32 v110, v110
	v_rndne_f32_e32 v111, v111
	v_cvt_i32_f32_e32 v104, v104
	v_cvt_i32_f32_e32 v105, v105
	v_rndne_f32_e32 v106, v106
	v_rndne_f32_e32 v107, v107
	v_cvt_i32_f32_sdwa v110, v110 dst_sel:WORD_1 dst_unused:UNUSED_PAD src0_sel:DWORD
	v_cvt_i32_f32_sdwa v111, v111 dst_sel:BYTE_3 dst_unused:UNUSED_PAD src0_sel:DWORD
	v_cvt_i32_f32_sdwa v106, v106 dst_sel:WORD_1 dst_unused:UNUSED_PAD src0_sel:DWORD
	v_cvt_i32_f32_sdwa v107, v107 dst_sel:BYTE_3 dst_unused:UNUSED_PAD src0_sel:DWORD
	v_lshl_or_b32 v108, v109, 8, v108
	v_lshl_or_b32 v104, v105, 8, v104
	v_or3_b32 v108, v108, v110, v111
	v_or3_b32 v104, v104, v106, v107
	ds_write2st64_b32 v228, v108, v104 offset0:80 offset1:88
	v_or_b32_e32 v104, 0x60, v152
	v_ashrrev_i32_e32 v105, 31, v104
	v_lshlrev_b64 v[104:105], 6, v[104:105]
	v_lshl_add_u64 v[116:117], s[6:7], 0, v[104:105]
	v_bfe_u32 v244, v116, 6, 8
	v_lshlrev_b32_e32 v244, 3, v244
	v_add_u32_e32 v244, 0x24010, v244
	v_or_b32_e32 v246, 3, v116
	ds_read_b64 v[248:249], v244
	s_waitcnt lgkmcnt(0)
	v_cmp_ne_u32_e64 s[100:101], v248, v246
	s_nop 1
	s_and_saveexec_b64 s[98:99], s[100:101]
	s_cbranch_execz .LrcE1_6
	global_load_dwordx4 v[104:107], v[116:117], off
	global_load_dwordx4 v[108:111], v[116:117], off offset:16
	global_load_dwordx4 v[112:115], v[116:117], off offset:32
	s_nop 0
	global_load_dwordx4 v[116:119], v[116:117], off offset:48
	s_waitcnt vmcnt(3)
	v_mov_b32_e32 v120, v105
	v_mov_b32_e32 v121, v106
	v_mov_b32_e32 v105, v107
	s_waitcnt vmcnt(2)
	v_mov_b32_e32 v106, v109
	v_mov_b32_e32 v107, v110
	v_mov_b32_e32 v109, v111
	v_pk_add_f32 v[104:105], v[120:121], v[104:105]
	v_pk_add_f32 v[106:107], v[106:107], v[108:109]
	v_pk_add_f32 v[104:105], v[104:105], v[104:105] op_sel:[0,1] op_sel_hi:[1,0]
	v_pk_add_f32 v[106:107], v[106:107], v[106:107] op_sel:[0,1] op_sel_hi:[1,0]
	s_waitcnt vmcnt(1)
	v_add_f32_e32 v108, v112, v113
	v_add_f32_e32 v110, v114, v115
	s_waitcnt vmcnt(0)
	v_mov_b32_e32 v105, v116
	v_mov_b32_e32 v107, v117
	v_mov_b32_e32 v109, v118
	v_mov_b32_e32 v111, v119
	v_pk_add_f32 v[104:105], v[104:105], v[106:107]
	v_pk_add_f32 v[106:107], v[108:109], v[110:111]
	s_nop 0
	v_pk_add_f32 v[104:105], v[104:105], v[106:107]
	s_nop 0
	v_add_f32_e32 v104, v104, v105
	v_fmamk_f32 v104, v104, 0x3a800000, v225
	v_mul_f32_e32 v105, 0x4b800000, v104
	v_cmp_gt_f32_e32 vcc, s45, v104
	s_nop 1
	v_cndmask_b32_e32 v104, v104, v105, vcc
	v_rsq_f32_e32 v104, v104
	s_nop 0
	v_mul_f32_e32 v105, 0x45800000, v104
	v_cndmask_b32_e32 v104, v104, v105, vcc
	s_nop 0
	v_mov_b32_e32 v247, v104
	ds_write_b64 v244, v[246:247]
; DI int TIDX() { int t = (int)threadIdx.x; asm volatile("" : "+v"(t)); return t; }
; DI float sigmoidf_(float x) { return 1.f / (1.f + __expf(-x)); }
; DI void merge_tile(const Params& p, int layer, int tm, int tn, bf16_t* smem) {
;     ...
;   for (int sg = 0; sg < 6; ++sg) {
;     ...
;     if ((sg & 1) == 0) {
;       const int t2 = TIDX(), row0 = tm * 256 + ((t2 >> 8) & 1) * 128 + (t2 & 15);
; #pragma unroll
;       for (int i = 0; i < 8; ++i) {
;         asm volatile("" ::: "memory");
;         const float rs = rstd_from16((const float*)(p.ws + O_SSQ) + (size_t)(row0 + i * 16) * 16, 1.f / 1024.f);
; #pragma unroll
;         for (int j = 0; j < 2; ++j) {
;           unsigned w = 0;
; #pragma unroll
;           for (int r = 0; r < 4; ++r) w |= (unsigned)__float2int_rn(sigmoidf_(acc[i][j][r] * rs) * 255.f) << (8 * r);
;           gsp[(i * 2 + j) * NTHR] = w;
;         }
;       }
.LrcE1_6:
	s_or_b64 exec, exec, s[98:99]
	s_waitcnt vmcnt(0)
	v_cndmask_b32_e64 v104, v249, v104, s[100:101]
	v_mul_f32_e32 v100, v100, v104
	v_mul_f32_e32 v100, 0xbfb8aa3b, v100
	v_exp_f32_e32 v100, v100
	v_mul_f32_e32 v101, v101, v104
	v_mul_f32_e32 v101, 0xbfb8aa3b, v101
	v_exp_f32_e32 v101, v101
	v_add_f32_e32 v100, 1.0, v100
	v_add_f32_e32 v101, 1.0, v101
	v_mul_f32_e32 v102, v102, v104
	v_mul_f32_e32 v102, 0xbfb8aa3b, v102
	v_rcp_f32_e32 v100, v100
	v_exp_f32_e32 v102, v102
	v_mul_f32_e32 v103, v103, v104
	v_mul_f32_e32 v103, 0xbfb8aa3b, v103
	v_add_f32_e32 v102, 1.0, v102
	v_rcp_f32_e32 v101, v101
	v_exp_f32_e32 v103, v103
	v_mul_f32_e32 v96, v96, v104
	v_mul_f32_e32 v96, 0xbfb8aa3b, v96
	v_add_f32_e32 v103, 1.0, v103
	v_rcp_f32_e32 v102, v102
	v_exp_f32_e32 v96, v96
	v_mul_f32_e32 v97, v97, v104
	v_mul_f32_e32 v97, 0xbfb8aa3b, v97
	v_add_f32_e32 v96, 1.0, v96
	v_rcp_f32_e32 v103, v103
	v_exp_f32_e32 v97, v97
	v_mul_f32_e32 v98, v98, v104
	v_mul_f32_e32 v98, 0xbfb8aa3b, v98
	v_add_f32_e32 v97, 1.0, v97
	v_rcp_f32_e32 v96, v96
	v_exp_f32_e32 v98, v98
	v_mul_f32_e32 v99, v99, v104
	v_mul_f32_e32 v99, 0xbfb8aa3b, v99
	v_add_f32_e32 v98, 1.0, v98
	v_rcp_f32_e32 v97, v97
	v_exp_f32_e32 v99, v99
	v_mul_f32_e32 v100, 0x437f0000, v100
	v_mul_f32_e32 v101, 0x437f0000, v101
	v_add_f32_e32 v99, 1.0, v99
	v_rcp_f32_e32 v98, v98
	v_mul_f32_e32 v96, 0x437f0000, v96
	v_mul_f32_e32 v97, 0x437f0000, v97
	v_rndne_f32_e32 v100, v100
	v_rcp_f32_e32 v99, v99
	v_rndne_f32_e32 v101, v101
	v_mul_f32_e32 v102, 0x437f0000, v102
	v_mul_f32_e32 v103, 0x437f0000, v103
	v_rndne_f32_e32 v96, v96
	v_rndne_f32_e32 v97, v97
	v_mul_f32_e32 v98, 0x437f0000, v98
	v_mul_f32_e32 v99, 0x437f0000, v99
	v_cvt_i32_f32_e32 v100, v100
	v_cvt_i32_f32_e32 v101, v101
	v_rndne_f32_e32 v102, v102
	v_rndne_f32_e32 v103, v103
	v_cvt_i32_f32_e32 v96, v96
	v_cvt_i32_f32_e32 v97, v97
	v_rndne_f32_e32 v98, v98
	v_rndne_f32_e32 v99, v99
	v_cvt_i32_f32_sdwa v102, v102 dst_sel:WORD_1 dst_unused:UNUSED_PAD src0_sel:DWORD
	v_cvt_i32_f32_sdwa v103, v103 dst_sel:BYTE_3 dst_unused:UNUSED_PAD src0_sel:DWORD
	v_cvt_i32_f32_sdwa v98, v98 dst_sel:WORD_1 dst_unused:UNUSED_PAD src0_sel:DWORD
	v_cvt_i32_f32_sdwa v99, v99 dst_sel:BYTE_3 dst_unused:UNUSED_PAD src0_sel:DWORD
	v_lshl_or_b32 v100, v101, 8, v100
	v_lshl_or_b32 v96, v97, 8, v96
	v_or3_b32 v100, v100, v102, v103
	v_or3_b32 v96, v96, v98, v99
	ds_write2st64_b32 v228, v100, v96 offset0:96 offset1:104
	v_or_b32_e32 v96, 0x70, v152
	v_ashrrev_i32_e32 v97, 31, v96
	v_lshlrev_b64 v[96:97], 6, v[96:97]
	v_lshl_add_u64 v[108:109], s[6:7], 0, v[96:97]
	v_mov_b64_e32 v[154:155], v[86:87]
	v_mov_b64_e32 v[152:153], v[84:85]
	v_bfe_u32 v244, v108, 6, 8
	v_lshlrev_b32_e32 v244, 3, v244
	v_add_u32_e32 v244, 0x24010, v244
	v_or_b32_e32 v246, 3, v108
	ds_read_b64 v[248:249], v244
	s_waitcnt lgkmcnt(0)
	v_cmp_ne_u32_e64 s[100:101], v248, v246
	s_nop 1
	s_and_saveexec_b64 s[98:99], s[100:101]
	s_cbranch_execz .LrcE1_7
	global_load_dwordx4 v[96:99], v[108:109], off
	global_load_dwordx4 v[100:103], v[108:109], off offset:16
	global_load_dwordx4 v[104:107], v[108:109], off offset:32
	s_nop 0
	global_load_dwordx4 v[108:111], v[108:109], off offset:48
	s_waitcnt vmcnt(3)
	v_mov_b32_e32 v112, v97
	v_mov_b32_e32 v113, v98
	v_mov_b32_e32 v97, v99
	s_waitcnt vmcnt(2)
	v_mov_b32_e32 v98, v101
	v_mov_b32_e32 v99, v102
	v_mov_b32_e32 v101, v103
	v_pk_add_f32 v[96:97], v[112:113], v[96:97]
	v_pk_add_f32 v[98:99], v[98:99], v[100:101]
	v_pk_add_f32 v[96:97], v[96:97], v[96:97] op_sel:[0,1] op_sel_hi:[1,0]
	v_pk_add_f32 v[98:99], v[98:99], v[98:99] op_sel:[0,1] op_sel_hi:[1,0]
	s_waitcnt vmcnt(1)
	v_add_f32_e32 v100, v104, v105
	v_add_f32_e32 v102, v106, v107
	s_waitcnt vmcnt(0)
	v_mov_b32_e32 v97, v108
	v_mov_b32_e32 v99, v109
	v_mov_b32_e32 v101, v110
	v_mov_b32_e32 v103, v111
	v_pk_add_f32 v[96:97], v[96:97], v[98:99]
	v_pk_add_f32 v[98:99], v[100:101], v[102:103]
	s_nop 0
	v_pk_add_f32 v[96:97], v[96:97], v[98:99]
	s_nop 0
	v_add_f32_e32 v96, v96, v97
	v_fmamk_f32 v96, v96, 0x3a800000, v225
	v_mul_f32_e32 v97, 0x4b800000, v96
	v_cmp_gt_f32_e32 vcc, s45, v96
	s_nop 1
	v_cndmask_b32_e32 v96, v96, v97, vcc
	v_rsq_f32_e32 v96, v96
	s_nop 0
	v_mul_f32_e32 v97, 0x45800000, v96
	v_cndmask_b32_e32 v96, v96, v97, vcc
	s_nop 0
	v_mov_b32_e32 v247, v96
	ds_write_b64 v244, v[246:247]
.LrcE1_7:
	s_or_b64 exec, exec, s[98:99]
	s_waitcnt vmcnt(0)
	v_cndmask_b32_e64 v96, v249, v96, s[100:101]
	v_mul_f32_e32 v92, v92, v96
	v_mul_f32_e32 v92, 0xbfb8aa3b, v92
	v_exp_f32_e32 v92, v92
	v_mul_f32_e32 v93, v93, v96
	v_mul_f32_e32 v93, 0xbfb8aa3b, v93
	v_exp_f32_e32 v93, v93
	v_add_f32_e32 v92, 1.0, v92
	v_add_f32_e32 v93, 1.0, v93
	v_mul_f32_e32 v94, v94, v96
	v_mul_f32_e32 v94, 0xbfb8aa3b, v94
	v_rcp_f32_e32 v92, v92
	v_exp_f32_e32 v94, v94
	v_mul_f32_e32 v95, v95, v96
	v_mul_f32_e32 v95, 0xbfb8aa3b, v95
	v_add_f32_e32 v94, 1.0, v94
	v_rcp_f32_e32 v93, v93
	v_exp_f32_e32 v95, v95
	v_mul_f32_e32 v88, v88, v96
	v_mul_f32_e32 v88, 0xbfb8aa3b, v88
	v_add_f32_e32 v95, 1.0, v95
	v_rcp_f32_e32 v94, v94
	v_exp_f32_e32 v88, v88
	v_mul_f32_e32 v89, v89, v96
	v_mul_f32_e32 v89, 0xbfb8aa3b, v89
	v_add_f32_e32 v88, 1.0, v88
	v_rcp_f32_e32 v95, v95
	v_exp_f32_e32 v89, v89
	v_mul_f32_e32 v90, v90, v96
	v_mul_f32_e32 v90, 0xbfb8aa3b, v90
	v_add_f32_e32 v89, 1.0, v89
	v_rcp_f32_e32 v88, v88
	v_exp_f32_e32 v90, v90
	v_mul_f32_e32 v91, v91, v96
	v_mul_f32_e32 v91, 0xbfb8aa3b, v91
	v_add_f32_e32 v90, 1.0, v90
	v_rcp_f32_e32 v89, v89
	v_exp_f32_e32 v91, v91
	v_mul_f32_e32 v92, 0x437f0000, v92
	v_mul_f32_e32 v93, 0x437f0000, v93
	v_add_f32_e32 v91, 1.0, v91
	v_rcp_f32_e32 v90, v90
	v_mul_f32_e32 v88, 0x437f0000, v88
	v_mul_f32_e32 v89, 0x437f0000, v89
	v_rndne_f32_e32 v92, v92
	v_rcp_f32_e32 v91, v91
	v_rndne_f32_e32 v93, v93
	v_mul_f32_e32 v94, 0x437f0000, v94
	v_mul_f32_e32 v95, 0x437f0000, v95
	v_rndne_f32_e32 v88, v88
	v_rndne_f32_e32 v89, v89
	v_mul_f32_e32 v90, 0x437f0000, v90
	v_mul_f32_e32 v91, 0x437f0000, v91
	v_cvt_i32_f32_e32 v92, v92
	v_cvt_i32_f32_e32 v93, v93
	v_rndne_f32_e32 v94, v94
	v_rndne_f32_e32 v95, v95
	v_cvt_i32_f32_e32 v88, v88
	v_cvt_i32_f32_e32 v89, v89
	v_rndne_f32_e32 v90, v90
	v_rndne_f32_e32 v91, v91
	v_cvt_i32_f32_sdwa v94, v94 dst_sel:WORD_1 dst_unused:UNUSED_PAD src0_sel:DWORD
	v_cvt_i32_f32_sdwa v95, v95 dst_sel:BYTE_3 dst_unused:UNUSED_PAD src0_sel:DWORD
	v_cvt_i32_f32_sdwa v90, v90 dst_sel:WORD_1 dst_unused:UNUSED_PAD src0_sel:DWORD
	v_cvt_i32_f32_sdwa v91, v91 dst_sel:BYTE_3 dst_unused:UNUSED_PAD src0_sel:DWORD
	v_lshl_or_b32 v92, v93, 8, v92
	v_lshl_or_b32 v88, v89, 8, v88
	v_or3_b32 v92, v92, v94, v95
	v_or3_b32 v88, v88, v90, v91
	ds_write2st64_b32 v228, v92, v88 offset0:112 offset1:120
	s_add_i32 s51, s51, 1
	s_cmp_lg_u32 s51, 6
	s_cbranch_scc0 .LBB0_1867

; DI unsigned pk2(float lo, float hi) { f32x2 v = {lo, hi}; return __builtin_bit_cast(unsigned, __builtin_convertvector(v, bfx2)); }
; DI float bf2f(bf16_t h) { return __uint_as_float(((unsigned)h) << 16); }
; DI float sigmoidf_(float x) { return 1.f / (1.f + __expf(-x)); }
; DI void ffnup_tile(const Params& p, int layer, int b, int mt, int tn, bf16_t* smem) {
;     ...
;       const int row = it * 32 + (tid >> 4), s = s0 + row;
;       if (row >= 2 && s < S_) {
;         const u32x4 u0 = *(const u32x4*)(U + (row - 2) * LDU + cc * 8), u1 = *(const u32x4*)(U + (row - 1) * LDU + cc * 8), u2 = *(const u32x4*)(U + row * LDU + cc * 8), vv = *(const u32x4*)(V + row * LDU + cc * 8);
;         unsigned o[4];
; #pragma unroll
;         for (int e = 0; e < 4; ++e) {
;           float r2[2];
; #pragma unroll
;           for (int h = 0; h < 2; ++h) {
;             const int k = 2 * e + h;
;             const float a0 = bf2f((bf16_t)(h ? u0[e] >> 16 : u0[e] & 0xffffu)), a1 = bf2f((bf16_t)(h ? u1[e] >> 16 : u1[e] & 0xffffu)), a2 = bf2f((bf16_t)(h ? u2[e] >> 16 : u2[e] & 0xffffu)), vx = bf2f((bf16_t)(h ? vv[e] >> 16 : vv[e] & 0xffffu));
;             const float uc = w0[k] * a0 + w1[k] * a1 + w2[k] * a2 + cb[k];
;             r2[h] = uc * sigmoidf_(uc) * vx;
;           }
;           o[e] = pk2(r2[0], r2[1]);
;         }
;         __builtin_nontemporal_store((u32x4){o[0], o[1], o[2], o[3]}, (u32x4*)(act + ((size_t)b * S_ + s) * DFF_ + cg0));
.LBB0_2102:
	v_add_u32_e32 v40, s4, v38
	v_add_u32_e32 v39, s4, v36
	v_add_u32_e32 v34, -2, v40
	v_cmp_lt_i32_e32 vcc, 1, v39
	v_cmp_gt_i32_e64 s[0:1], s28, v34
	s_and_b64 s[16:17], vcc, s[0:1]
	s_and_saveexec_b64 s[0:1], s[16:17]
	s_cbranch_execz .LBB0_2104
	v_add_u32_e32 v41, 0xfffecbe0, v37
	ds_read_b128 v[42:45], v41
	v_add_u32_e32 v41, 0xfffeccf0, v37
	v_add_u32_e32 v35, 0xfffece00, v37
	ds_read_b128 v[46:49], v41
	ds_read_b128 v[50:53], v35
	v_add_u32_e32 v35, 0xffffde00, v37
	s_waitcnt lgkmcnt(2)
	v_lshlrev_b32_e32 v58, 16, v42
	v_and_b32_e32 v59, 0xffff0000, v42
	s_waitcnt lgkmcnt(1)
	v_lshlrev_b32_e32 v60, 16, v46
	v_and_b32_e32 v61, 0xffff0000, v46
	v_pk_mul_f32 v[60:61], v[8:9], v[60:61]
	s_waitcnt lgkmcnt(0)
	v_lshlrev_b32_e32 v62, 16, v50
	v_and_b32_e32 v63, 0xffff0000, v50
	v_pk_fma_f32 v[58:59], v[4:5], v[58:59], v[60:61]
	ds_read_b128 v[54:57], v35
	v_pk_fma_f32 v[58:59], v[12:13], v[62:63], v[58:59]
	v_lshlrev_b32_e32 v64, 16, v52
	v_pk_add_f32 v[58:59], v[28:29], v[58:59]
	v_and_b32_e32 v65, 0xffff0000, v52
	v_mul_f32_e32 v35, 0xbfb8aa3b, v58
	v_exp_f32_e32 v60, v35
	v_mul_f32_e32 v35, 0xbfb8aa3b, v59
	v_exp_f32_e32 v61, v35
	s_waitcnt lgkmcnt(0)
	v_lshlrev_b32_e32 v62, 16, v54
	v_and_b32_e32 v63, 0xffff0000, v54
	v_pk_add_f32 v[60:61], v[60:61], 1.0 op_sel_hi:[1,0]
	s_nop 0
	s_nop 0
	v_rcp_f32_e32 v61, v61
	v_lshlrev_b32_e32 v46, 16, v47
	v_and_b32_e32 v47, 0xffff0000, v47
	v_lshlrev_b32_e32 v42, 16, v43
	v_and_b32_e32 v43, 0xffff0000, v43
	v_pk_mul_f32 v[46:47], v[10:11], v[46:47]
	v_lshlrev_b32_e32 v50, 16, v51
	v_and_b32_e32 v51, 0xffff0000, v51
	v_pk_fma_f32 v[42:43], v[6:7], v[42:43], v[46:47]
	v_rcp_f32_e32 v60, v60
	v_pk_fma_f32 v[42:43], v[14:15], v[50:51], v[42:43]
	v_pk_mul_f32 v[50:51], v[58:59], v[60:61]
	v_pk_add_f32 v[46:47], v[30:31], v[42:43]
	v_pk_mul_f32 v[50:51], v[50:51], v[62:63]
	v_mul_f32_e32 v41, 0xbfb8aa3b, v46
	v_exp_f32_e32 v42, v41
	v_mul_f32_e32 v41, 0xbfb8aa3b, v47
	v_exp_f32_e32 v43, v41
	v_lshlrev_b32_e32 v62, 16, v48
	v_and_b32_e32 v63, 0xffff0000, v48
	v_and_b32_e32 v61, 0xffff0000, v44
	v_pk_add_f32 v[58:59], v[42:43], 1.0 op_sel_hi:[1,0]
	v_cvt_pk_bf16_f32 v42, v50, v51
	v_lshlrev_b32_e32 v50, 16, v55
	v_and_b32_e32 v51, 0xffff0000, v55
	v_pk_mul_f32 v[62:63], v[16:17], v[62:63]
	v_rcp_f32_e32 v55, v59
	v_lshlrev_b32_e32 v60, 16, v44
	v_pk_fma_f32 v[60:61], v[0:1], v[60:61], v[62:63]
	v_rcp_f32_e32 v54, v58
	v_pk_fma_f32 v[60:61], v[20:21], v[64:65], v[60:61]
	v_pk_mul_f32 v[46:47], v[46:47], v[54:55]
	v_pk_add_f32 v[60:61], v[24:25], v[60:61]
	v_pk_mul_f32 v[46:47], v[46:47], v[50:51]
	v_mul_f32_e32 v41, 0xbfb8aa3b, v60
	v_exp_f32_e32 v62, v41
	v_mul_f32_e32 v41, 0xbfb8aa3b, v61
	v_exp_f32_e32 v63, v41
	v_cvt_pk_bf16_f32 v43, v46, v47
	v_lshlrev_b32_e32 v46, 16, v56
	v_and_b32_e32 v47, 0xffff0000, v56
	v_pk_add_f32 v[50:51], v[62:63], 1.0 op_sel_hi:[1,0]
	s_nop 0
	s_nop 0
	v_rcp_f32_e32 v51, v51
	v_lshlrev_b32_e32 v48, 16, v49
	v_and_b32_e32 v49, 0xffff0000, v49
	v_lshlrev_b32_e32 v44, 16, v45
	v_and_b32_e32 v45, 0xffff0000, v45
	v_pk_mul_f32 v[48:49], v[18:19], v[48:49]
	v_lshlrev_b32_e32 v52, 16, v53
	v_and_b32_e32 v53, 0xffff0000, v53
	v_pk_fma_f32 v[44:45], v[2:3], v[44:45], v[48:49]
	v_rcp_f32_e32 v50, v50
	v_pk_fma_f32 v[44:45], v[22:23], v[52:53], v[44:45]
	v_pk_mul_f32 v[50:51], v[60:61], v[50:51]
	v_pk_add_f32 v[48:49], v[26:27], v[44:45]
	v_pk_mul_f32 v[46:47], v[50:51], v[46:47]
	v_mul_f32_e32 v41, 0xbfb8aa3b, v48
	v_exp_f32_e32 v44, v41
	v_mul_f32_e32 v41, 0xbfb8aa3b, v49
	v_exp_f32_e32 v45, v41
	s_nop 0
	v_pk_add_f32 v[50:51], v[44:45], 1.0 op_sel_hi:[1,0]
	s_nop 0
	v_cvt_pk_bf16_f32 v44, v46, v47
	v_lshlrev_b32_e32 v46, 16, v57
	v_and_b32_e32 v47, 0xffff0000, v57
	v_rcp_f32_e32 v51, v51
	v_rcp_f32_e32 v50, v50
	s_nop 0
	v_pk_mul_f32 v[48:49], v[48:49], v[50:51]
	v_ashrrev_i32_e32 v35, 31, v34
	v_pk_mul_f32 v[46:47], v[48:49], v[46:47]
	v_lshl_add_u64 v[34:35], s[2:3], 0, v[34:35]
	v_cvt_pk_bf16_f32 v45, v46, v47
	v_mad_u64_u32 v[46:47], s[16:17], v34, s39, v[32:33]
	v_mad_i32_i24 v47, v35, s39, v47
	global_store_dwordx4 v[46:47], v[42:45], off nt
; DI unsigned pk2(float lo, float hi) { f32x2 v = {lo, hi}; return __builtin_bit_cast(unsigned, __builtin_convertvector(v, bfx2)); }
; DI float bf2f(bf16_t h) { return __uint_as_float(((unsigned)h) << 16); }
; DI float sigmoidf_(float x) { return 1.f / (1.f + __expf(-x)); }
; DI void ffnup_tile(const Params& p, int layer, int b, int mt, int tn, bf16_t* smem) {
;     ...
;       const int row = it * 32 + (tid >> 4), s = s0 + row;
;       if (row >= 2 && s < S_) {
;         const u32x4 u0 = *(const u32x4*)(U + (row - 2) * LDU + cc * 8), u1 = *(const u32x4*)(U + (row - 1) * LDU + cc * 8), u2 = *(const u32x4*)(U + row * LDU + cc * 8), vv = *(const u32x4*)(V + row * LDU + cc * 8);
;         unsigned o[4];
; #pragma unroll
;         for (int e = 0; e < 4; ++e) {
;           float r2[2];
; #pragma unroll
;           for (int h = 0; h < 2; ++h) {
;             const int k = 2 * e + h;
;             const float a0 = bf2f((bf16_t)(h ? u0[e] >> 16 : u0[e] & 0xffffu)), a1 = bf2f((bf16_t)(h ? u1[e] >> 16 : u1[e] & 0xffffu)), a2 = bf2f((bf16_t)(h ? u2[e] >> 16 : u2[e] & 0xffffu)), vx = bf2f((bf16_t)(h ? vv[e] >> 16 : vv[e] & 0xffffu));
;             const float uc = w0[k] * a0 + w1[k] * a1 + w2[k] * a2 + cb[k];
;             r2[h] = uc * sigmoidf_(uc) * vx;
;           }
;           o[e] = pk2(r2[0], r2[1]);
;         }
;         __builtin_nontemporal_store((u32x4){o[0], o[1], o[2], o[3]}, (u32x4*)(act + ((size_t)b * S_ + s) * DFF_ + cg0));
.LBB0_2104:
	s_or_b64 exec, exec, s[0:1]
	v_add_u32_e32 v35, 32, v39
	v_add_u32_e32 v34, 30, v40
	v_cmp_lt_i32_e32 vcc, 1, v35
	v_cmp_gt_i32_e64 s[0:1], s28, v34
	s_and_b64 s[16:17], vcc, s[0:1]
	s_and_saveexec_b64 s[0:1], s[16:17]
	s_cbranch_execz .LBB0_2101
	v_add_u32_e32 v39, 0xfffeede0, v37
	ds_read_b128 v[40:43], v39
	v_add_u32_e32 v39, 0xfffeeef0, v37
	v_add_u32_e32 v35, 0xfffef000, v37
	ds_read_b128 v[44:47], v39
	ds_read_b128 v[48:51], v35
	ds_read_b128 v[52:55], v37
	s_waitcnt lgkmcnt(3)
	v_lshlrev_b32_e32 v56, 16, v40
	s_waitcnt lgkmcnt(2)
	v_lshlrev_b32_e32 v58, 16, v44
	v_and_b32_e32 v59, 0xffff0000, v44
	v_and_b32_e32 v57, 0xffff0000, v40
	v_pk_mul_f32 v[58:59], v[8:9], v[58:59]
	s_waitcnt lgkmcnt(1)
	v_lshlrev_b32_e32 v60, 16, v48
	v_and_b32_e32 v61, 0xffff0000, v48
	v_pk_fma_f32 v[56:57], v[4:5], v[56:57], v[58:59]
	v_lshlrev_b32_e32 v62, 16, v50
	v_pk_fma_f32 v[56:57], v[12:13], v[60:61], v[56:57]
	s_waitcnt lgkmcnt(0)
	v_lshlrev_b32_e32 v60, 16, v52
	v_pk_add_f32 v[56:57], v[28:29], v[56:57]
	v_and_b32_e32 v61, 0xffff0000, v52
	v_mul_f32_e32 v35, 0xbfb8aa3b, v56
	v_exp_f32_e32 v58, v35
	v_mul_f32_e32 v35, 0xbfb8aa3b, v57
	v_exp_f32_e32 v59, v35
	v_and_b32_e32 v63, 0xffff0000, v50
	v_pk_add_f32 v[58:59], v[58:59], 1.0 op_sel_hi:[1,0]
	s_nop 0
	s_nop 0
	v_rcp_f32_e32 v59, v59
	v_lshlrev_b32_e32 v44, 16, v45
	v_and_b32_e32 v45, 0xffff0000, v45
	v_lshlrev_b32_e32 v40, 16, v41
	v_and_b32_e32 v41, 0xffff0000, v41
	v_pk_mul_f32 v[44:45], v[10:11], v[44:45]
	v_lshlrev_b32_e32 v48, 16, v49
	v_and_b32_e32 v49, 0xffff0000, v49
	v_pk_fma_f32 v[40:41], v[6:7], v[40:41], v[44:45]
	v_rcp_f32_e32 v58, v58
	v_pk_fma_f32 v[40:41], v[14:15], v[48:49], v[40:41]
	v_pk_mul_f32 v[48:49], v[56:57], v[58:59]
	v_pk_add_f32 v[44:45], v[30:31], v[40:41]
	v_pk_mul_f32 v[48:49], v[48:49], v[60:61]
	v_mul_f32_e32 v39, 0xbfb8aa3b, v44
	v_exp_f32_e32 v40, v39
	v_mul_f32_e32 v39, 0xbfb8aa3b, v45
	v_exp_f32_e32 v41, v39
	v_lshlrev_b32_e32 v60, 16, v46
	v_and_b32_e32 v61, 0xffff0000, v46
	v_and_b32_e32 v59, 0xffff0000, v42
	v_pk_add_f32 v[56:57], v[40:41], 1.0 op_sel_hi:[1,0]
	v_cvt_pk_bf16_f32 v40, v48, v49
	v_lshlrev_b32_e32 v48, 16, v53
	v_and_b32_e32 v49, 0xffff0000, v53
	v_pk_mul_f32 v[60:61], v[16:17], v[60:61]
	v_rcp_f32_e32 v53, v57
	v_lshlrev_b32_e32 v58, 16, v42
	v_pk_fma_f32 v[58:59], v[0:1], v[58:59], v[60:61]
	v_rcp_f32_e32 v52, v56
	v_pk_fma_f32 v[58:59], v[20:21], v[62:63], v[58:59]
	v_pk_mul_f32 v[44:45], v[44:45], v[52:53]
	v_pk_add_f32 v[58:59], v[24:25], v[58:59]
	v_pk_mul_f32 v[44:45], v[44:45], v[48:49]
	v_mul_f32_e32 v39, 0xbfb8aa3b, v58
	v_exp_f32_e32 v60, v39
	v_mul_f32_e32 v39, 0xbfb8aa3b, v59
	v_exp_f32_e32 v61, v39
	v_cvt_pk_bf16_f32 v41, v44, v45
	v_lshlrev_b32_e32 v44, 16, v54
	v_and_b32_e32 v45, 0xffff0000, v54
	v_pk_add_f32 v[48:49], v[60:61], 1.0 op_sel_hi:[1,0]
	s_nop 0
	s_nop 0
	v_rcp_f32_e32 v49, v49
	v_lshlrev_b32_e32 v46, 16, v47
	v_and_b32_e32 v47, 0xffff0000, v47
	v_lshlrev_b32_e32 v42, 16, v43
	v_and_b32_e32 v43, 0xffff0000, v43
	v_pk_mul_f32 v[46:47], v[18:19], v[46:47]
	v_lshlrev_b32_e32 v50, 16, v51
	v_and_b32_e32 v51, 0xffff0000, v51
	v_pk_fma_f32 v[42:43], v[2:3], v[42:43], v[46:47]
	v_rcp_f32_e32 v48, v48
	v_pk_fma_f32 v[42:43], v[22:23], v[50:51], v[42:43]
	v_pk_mul_f32 v[48:49], v[58:59], v[48:49]
	v_pk_add_f32 v[46:47], v[26:27], v[42:43]
	v_pk_mul_f32 v[44:45], v[48:49], v[44:45]
	v_mul_f32_e32 v39, 0xbfb8aa3b, v46
	v_exp_f32_e32 v42, v39
	v_mul_f32_e32 v39, 0xbfb8aa3b, v47
	v_exp_f32_e32 v43, v39
	s_nop 0
	v_pk_add_f32 v[48:49], v[42:43], 1.0 op_sel_hi:[1,0]
	s_nop 0
	v_cvt_pk_bf16_f32 v42, v44, v45
	v_lshlrev_b32_e32 v44, 16, v55
	v_and_b32_e32 v45, 0xffff0000, v55
	v_rcp_f32_e32 v49, v49
	v_rcp_f32_e32 v48, v48
	s_nop 0
	v_pk_mul_f32 v[46:47], v[46:47], v[48:49]
	v_ashrrev_i32_e32 v35, 31, v34
	v_pk_mul_f32 v[44:45], v[46:47], v[44:45]
	v_lshl_add_u64 v[34:35], s[2:3], 0, v[34:35]
	v_cvt_pk_bf16_f32 v43, v44, v45
	v_mad_u64_u32 v[44:45], s[16:17], v34, s39, v[32:33]
	v_mad_i32_i24 v45, v35, s39, v45
	global_store_dwordx4 v[44:45], v[40:43], off nt
	s_branch .LBB0_2101
